# all flat_load/store/atomic converted to global_* (pointers are global memory); on top of rcp divisions
# speedup vs baseline: 1.0390x; 1.0057x over previous
.LBB0_132:
	s_add_u32 s2, s6, 0xfffc0080
	s_addc_u32 s3, s7, -1
	s_add_i32 s23, 0, 0x10000
	v_add_u32_e32 v150, s23, v157
	ds_read_b128 v[138:141], v150
	ds_read_b128 v[142:145], v150 offset:1024
	ds_read_b128 v[146:149], v150 offset:2048
	ds_read_b128 v[150:153], v150 offset:3072
	s_cmp_eq_u32 s22, 12
	s_cselect_b32 s21, s15, s3
	s_cselect_b32 s20, s37, s2
	s_cselect_b32 s3, s13, s40
	s_cselect_b32 s2, s38, s39
	v_lshl_add_u64 v[154:155], s[6:7], 0, v[136:137]
	s_add_i32 m0, s26, 0xc000
	ds_read_b128 v[160:163], v159
	ds_read_b128 v[164:167], v159 offset:1024
	ds_read_b128 v[168:171], v159 offset:2048
	ds_read_b128 v[172:175], v159 offset:3072
	ds_read_b128 v[176:179], v159 offset:4096
	ds_read_b128 v[180:183], v159 offset:5120
	ds_read_b128 v[184:187], v159 offset:6144
	ds_read_b128 v[188:191], v159 offset:7168
	global_load_lds_dwordx4 v[154:155], off
	v_lshl_add_u64 v[154:155], s[6:7], 0, v[134:135]
	s_add_i32 m0, s26, 0xe000
	s_nop 0
	global_load_lds_dwordx4 v[154:155], off
	s_waitcnt lgkmcnt(8)
	s_barrier
	s_waitcnt lgkmcnt(0)
	s_setprio 1
	s_waitcnt lgkmcnt(0)
	v_mfma_f32_16x16x32_bf16 v[112:115], v[138:141], v[160:163], v[112:115]
	v_mfma_f32_16x16x32_bf16 v[116:119], v[146:149], v[160:163], v[116:119]
	v_mfma_f32_16x16x32_bf16 v[96:99], v[138:141], v[168:171], v[96:99]
	v_mfma_f32_16x16x32_bf16 v[100:103], v[146:149], v[168:171], v[100:103]
	v_mfma_f32_16x16x32_bf16 v[80:83], v[138:141], v[176:179], v[80:83]
	v_mfma_f32_16x16x32_bf16 v[84:87], v[146:149], v[176:179], v[84:87]
	v_mfma_f32_16x16x32_bf16 v[48:51], v[138:141], v[184:187], v[48:51]
	v_mfma_f32_16x16x32_bf16 v[56:59], v[146:149], v[184:187], v[56:59]
	v_mfma_f32_16x16x32_bf16 v[112:115], v[142:145], v[164:167], v[112:115]
	v_mfma_f32_16x16x32_bf16 v[116:119], v[150:153], v[164:167], v[116:119]
	v_mfma_f32_16x16x32_bf16 v[96:99], v[142:145], v[172:175], v[96:99]
	v_mfma_f32_16x16x32_bf16 v[100:103], v[150:153], v[172:175], v[100:103]
	v_mfma_f32_16x16x32_bf16 v[80:83], v[142:145], v[180:183], v[80:83]
	v_mfma_f32_16x16x32_bf16 v[84:87], v[150:153], v[180:183], v[84:87]
	v_mfma_f32_16x16x32_bf16 v[48:51], v[142:145], v[188:191], v[48:51]
	v_mfma_f32_16x16x32_bf16 v[56:59], v[150:153], v[188:191], v[56:59]
	s_setprio 0
	s_barrier
	s_add_i32 s41, 0, 0x14000
	v_add_u32_e32 v154, s41, v157
	s_add_i32 s23, s23, s25
	ds_read_b128 v[206:209], v154
	ds_read_b128 v[210:213], v154 offset:1024
	ds_read_b128 v[214:217], v154 offset:2048
	ds_read_b128 v[218:221], v154 offset:3072
	v_lshl_add_u64 v[154:155], s[2:3], 0, v[194:195]
	s_mov_b32 m0, s23
	v_lshl_add_u64 v[222:223], s[2:3], 0, v[128:129]
	global_load_lds_dwordx4 v[154:155], off
	s_add_i32 m0, s23, 0x2000
	s_nop 0
	global_load_lds_dwordx4 v[222:223], off
	s_barrier
	s_waitcnt lgkmcnt(0)
	s_setprio 1
	s_waitcnt lgkmcnt(0)
	v_mfma_f32_16x16x32_bf16 v[120:123], v[206:209], v[160:163], v[120:123]
	v_mfma_f32_16x16x32_bf16 v[124:127], v[214:217], v[160:163], v[124:127]
	v_mfma_f32_16x16x32_bf16 v[104:107], v[206:209], v[168:171], v[104:107]
	v_mfma_f32_16x16x32_bf16 v[108:111], v[214:217], v[168:171], v[108:111]
	v_mfma_f32_16x16x32_bf16 v[88:91], v[206:209], v[176:179], v[88:91]
	v_mfma_f32_16x16x32_bf16 v[92:95], v[214:217], v[176:179], v[92:95]
	v_mfma_f32_16x16x32_bf16 v[64:67], v[206:209], v[184:187], v[64:67]
	v_mfma_f32_16x16x32_bf16 v[72:75], v[214:217], v[184:187], v[72:75]
	v_mfma_f32_16x16x32_bf16 v[120:123], v[210:213], v[164:167], v[120:123]
	v_mfma_f32_16x16x32_bf16 v[124:127], v[218:221], v[164:167], v[124:127]
	v_mfma_f32_16x16x32_bf16 v[104:107], v[210:213], v[172:175], v[104:107]
	v_mfma_f32_16x16x32_bf16 v[108:111], v[218:221], v[172:175], v[108:111]
	v_mfma_f32_16x16x32_bf16 v[88:91], v[210:213], v[180:183], v[88:91]
	v_mfma_f32_16x16x32_bf16 v[92:95], v[218:221], v[180:183], v[92:95]
	v_mfma_f32_16x16x32_bf16 v[64:67], v[210:213], v[188:191], v[64:67]
	v_mfma_f32_16x16x32_bf16 v[72:75], v[218:221], v[188:191], v[72:75]
	s_setprio 0
	s_mov_b32 m0, s26
	v_lshl_add_u64 v[224:225], s[20:21], 0, v[132:133]
	s_barrier
	ds_read_b128 v[160:163], v159 offset:16384
	ds_read_b128 v[164:167], v159 offset:17408
	ds_read_b128 v[168:171], v159 offset:18432
	ds_read_b128 v[172:175], v159 offset:19456
	ds_read_b128 v[176:179], v159 offset:20480
	ds_read_b128 v[180:183], v159 offset:21504
	ds_read_b128 v[184:187], v159 offset:22528
	ds_read_b128 v[188:191], v159 offset:23552
	global_load_lds_dwordx4 v[224:225], off
	v_lshl_add_u64 v[226:227], s[20:21], 0, v[130:131]
	s_mov_b32 m0, s27
	s_nop 0
	global_load_lds_dwordx4 v[226:227], off
	s_barrier
	s_waitcnt lgkmcnt(0)
	s_setprio 1
	s_waitcnt lgkmcnt(0)
	v_mfma_f32_16x16x32_bf16 v[52:55], v[138:141], v[160:163], v[52:55]
	v_mfma_f32_16x16x32_bf16 v[60:63], v[146:149], v[160:163], v[60:63]
	v_mfma_f32_16x16x32_bf16 v[32:35], v[138:141], v[168:171], v[32:35]
	v_mfma_f32_16x16x32_bf16 v[36:39], v[146:149], v[168:171], v[36:39]
	v_mfma_f32_16x16x32_bf16 v[16:19], v[138:141], v[176:179], v[16:19]
	v_mfma_f32_16x16x32_bf16 v[20:23], v[146:149], v[176:179], v[20:23]
	v_mfma_f32_16x16x32_bf16 v[0:3], v[138:141], v[184:187], v[0:3]
	v_mfma_f32_16x16x32_bf16 v[4:7], v[146:149], v[184:187], v[4:7]
	v_mfma_f32_16x16x32_bf16 v[52:55], v[142:145], v[164:167], v[52:55]
	v_mfma_f32_16x16x32_bf16 v[60:63], v[150:153], v[164:167], v[60:63]
	v_mfma_f32_16x16x32_bf16 v[32:35], v[142:145], v[172:175], v[32:35]
	v_mfma_f32_16x16x32_bf16 v[36:39], v[150:153], v[172:175], v[36:39]
	v_mfma_f32_16x16x32_bf16 v[16:19], v[142:145], v[180:183], v[16:19]
	v_mfma_f32_16x16x32_bf16 v[20:23], v[150:153], v[180:183], v[20:23]
	v_mfma_f32_16x16x32_bf16 v[0:3], v[142:145], v[188:191], v[0:3]
	v_mfma_f32_16x16x32_bf16 v[4:7], v[150:153], v[188:191], v[4:7]
	s_setprio 0
	s_barrier
	s_add_u32 s56, s2, 0x40000
	s_addc_u32 s57, s3, 0
	s_add_i32 s23, s41, s25
	v_lshl_add_u64 v[138:139], s[56:57], 0, v[194:195]
	s_mov_b32 m0, s23
	s_nop 0
	global_load_lds_dwordx4 v[138:139], off
	v_lshl_add_u64 v[138:139], s[56:57], 0, v[128:129]
	s_add_i32 m0, s23, 0x2000
	s_nop 0
	global_load_lds_dwordx4 v[138:139], off
	s_waitcnt vmcnt(6)
	s_barrier
	s_setprio 1
	v_mfma_f32_16x16x32_bf16 v[68:71], v[206:209], v[160:163], v[68:71]
	v_mfma_f32_16x16x32_bf16 v[76:79], v[214:217], v[160:163], v[76:79]
	v_mfma_f32_16x16x32_bf16 v[40:43], v[206:209], v[168:171], v[40:43]
	v_mfma_f32_16x16x32_bf16 v[44:47], v[214:217], v[168:171], v[44:47]
	v_mfma_f32_16x16x32_bf16 v[24:27], v[206:209], v[176:179], v[24:27]
	v_mfma_f32_16x16x32_bf16 v[28:31], v[214:217], v[176:179], v[28:31]
	v_mfma_f32_16x16x32_bf16 v[8:11], v[206:209], v[184:187], v[8:11]
	v_mfma_f32_16x16x32_bf16 v[12:15], v[214:217], v[184:187], v[12:15]
	v_mfma_f32_16x16x32_bf16 v[68:71], v[210:213], v[164:167], v[68:71]
	v_mfma_f32_16x16x32_bf16 v[76:79], v[218:221], v[164:167], v[76:79]
	v_mfma_f32_16x16x32_bf16 v[40:43], v[210:213], v[172:175], v[40:43]
	v_mfma_f32_16x16x32_bf16 v[44:47], v[218:221], v[172:175], v[44:47]
	v_mfma_f32_16x16x32_bf16 v[24:27], v[210:213], v[180:183], v[24:27]
	v_mfma_f32_16x16x32_bf16 v[28:31], v[218:221], v[180:183], v[28:31]
	v_mfma_f32_16x16x32_bf16 v[8:11], v[210:213], v[188:191], v[8:11]
	v_mfma_f32_16x16x32_bf16 v[12:15], v[218:221], v[188:191], v[12:15]
	s_setprio 0
	s_add_i32 s23, 0, 0x18000
	v_add_u32_e32 v150, s23, v157
	s_barrier
	ds_read_b128 v[138:141], v150
	ds_read_b128 v[142:145], v150 offset:1024
	ds_read_b128 v[146:149], v150 offset:2048
	ds_read_b128 v[150:153], v150 offset:3072
	s_add_u32 s20, s20, 0x40000
	s_addc_u32 s21, s21, 0
	s_mov_b32 m0, s28
	v_lshl_add_u64 v[206:207], s[20:21], 0, v[132:133]
	ds_read_b128 v[160:163], v159 offset:32768
	ds_read_b128 v[164:167], v159 offset:33792
	ds_read_b128 v[168:171], v159 offset:34816
	ds_read_b128 v[172:175], v159 offset:35840
	ds_read_b128 v[176:179], v159 offset:36864
	ds_read_b128 v[180:183], v159 offset:37888
	ds_read_b128 v[184:187], v159 offset:38912
	ds_read_b128 v[188:191], v159 offset:39936
	global_load_lds_dwordx4 v[206:207], off
	v_lshl_add_u64 v[206:207], s[20:21], 0, v[130:131]
	s_mov_b32 m0, s29
	s_nop 0
	global_load_lds_dwordx4 v[206:207], off
	s_waitcnt lgkmcnt(8)
	s_barrier
	s_waitcnt lgkmcnt(0)
	s_setprio 1
	s_waitcnt lgkmcnt(0)
	v_mfma_f32_16x16x32_bf16 v[112:115], v[138:141], v[160:163], v[112:115]
	v_mfma_f32_16x16x32_bf16 v[116:119], v[146:149], v[160:163], v[116:119]
	v_mfma_f32_16x16x32_bf16 v[96:99], v[138:141], v[168:171], v[96:99]
	v_mfma_f32_16x16x32_bf16 v[100:103], v[146:149], v[168:171], v[100:103]
	v_mfma_f32_16x16x32_bf16 v[80:83], v[138:141], v[176:179], v[80:83]
	v_mfma_f32_16x16x32_bf16 v[84:87], v[146:149], v[176:179], v[84:87]
	v_mfma_f32_16x16x32_bf16 v[48:51], v[138:141], v[184:187], v[48:51]
	v_mfma_f32_16x16x32_bf16 v[56:59], v[146:149], v[184:187], v[56:59]
	v_mfma_f32_16x16x32_bf16 v[112:115], v[142:145], v[164:167], v[112:115]
	v_mfma_f32_16x16x32_bf16 v[116:119], v[150:153], v[164:167], v[116:119]
	v_mfma_f32_16x16x32_bf16 v[96:99], v[142:145], v[172:175], v[96:99]
	v_mfma_f32_16x16x32_bf16 v[100:103], v[150:153], v[172:175], v[100:103]
	v_mfma_f32_16x16x32_bf16 v[80:83], v[142:145], v[180:183], v[80:83]
	v_mfma_f32_16x16x32_bf16 v[84:87], v[150:153], v[180:183], v[84:87]
	v_mfma_f32_16x16x32_bf16 v[48:51], v[142:145], v[188:191], v[48:51]
	v_mfma_f32_16x16x32_bf16 v[56:59], v[150:153], v[188:191], v[56:59]
	s_setprio 0
	s_barrier
	s_add_i32 s20, 0, 0x1c000
	s_add_i32 s21, s23, s25
	v_add_u32_e32 v193, s20, v157
	v_lshl_add_u64 v[154:155], v[154:155], 0, s[70:71]
	s_mov_b32 m0, s21
	ds_read_b128 v[206:209], v193
	ds_read_b128 v[210:213], v193 offset:1024
	ds_read_b128 v[214:217], v193 offset:2048
	ds_read_b128 v[218:221], v193 offset:3072
	global_load_lds_dwordx4 v[154:155], off
	v_lshl_add_u64 v[154:155], v[222:223], 0, s[70:71]
	s_add_i32 m0, s21, 0x2000
	s_nop 0
	global_load_lds_dwordx4 v[154:155], off
	s_barrier
	s_waitcnt lgkmcnt(0)
	s_setprio 1
	s_waitcnt lgkmcnt(0)
	v_mfma_f32_16x16x32_bf16 v[120:123], v[206:209], v[160:163], v[120:123]
	v_mfma_f32_16x16x32_bf16 v[124:127], v[214:217], v[160:163], v[124:127]
	v_mfma_f32_16x16x32_bf16 v[104:107], v[206:209], v[168:171], v[104:107]
	v_mfma_f32_16x16x32_bf16 v[108:111], v[214:217], v[168:171], v[108:111]
	v_mfma_f32_16x16x32_bf16 v[88:91], v[206:209], v[176:179], v[88:91]
	v_mfma_f32_16x16x32_bf16 v[92:95], v[214:217], v[176:179], v[92:95]
	v_mfma_f32_16x16x32_bf16 v[64:67], v[206:209], v[184:187], v[64:67]
	v_mfma_f32_16x16x32_bf16 v[72:75], v[214:217], v[184:187], v[72:75]
	v_mfma_f32_16x16x32_bf16 v[120:123], v[210:213], v[164:167], v[120:123]
	v_mfma_f32_16x16x32_bf16 v[124:127], v[218:221], v[164:167], v[124:127]
	v_mfma_f32_16x16x32_bf16 v[104:107], v[210:213], v[172:175], v[104:107]
	v_mfma_f32_16x16x32_bf16 v[108:111], v[218:221], v[172:175], v[108:111]
	v_mfma_f32_16x16x32_bf16 v[88:91], v[210:213], v[180:183], v[88:91]
	v_mfma_f32_16x16x32_bf16 v[92:95], v[218:221], v[180:183], v[92:95]
	v_mfma_f32_16x16x32_bf16 v[64:67], v[210:213], v[188:191], v[64:67]
	v_mfma_f32_16x16x32_bf16 v[72:75], v[218:221], v[188:191], v[72:75]
	s_setprio 0
	s_mov_b32 m0, s30
	v_lshl_add_u64 v[154:155], v[224:225], 0, s[70:71]
	s_barrier
	ds_read_b128 v[160:163], v159 offset:49152
	ds_read_b128 v[164:167], v159 offset:50176
	ds_read_b128 v[168:171], v159 offset:51200
	ds_read_b128 v[172:175], v159 offset:52224
	ds_read_b128 v[176:179], v159 offset:53248
	ds_read_b128 v[180:183], v159 offset:54272
	ds_read_b128 v[184:187], v159 offset:55296
	ds_read_b128 v[188:191], v159 offset:56320
	global_load_lds_dwordx4 v[154:155], off
	v_lshl_add_u64 v[154:155], v[226:227], 0, s[70:71]
	s_mov_b32 m0, s31
	s_nop 0
	global_load_lds_dwordx4 v[154:155], off
	s_barrier
	s_waitcnt lgkmcnt(0)
	s_setprio 1
	s_waitcnt lgkmcnt(0)
	v_mfma_f32_16x16x32_bf16 v[52:55], v[138:141], v[160:163], v[52:55]
	v_mfma_f32_16x16x32_bf16 v[60:63], v[146:149], v[160:163], v[60:63]
	v_mfma_f32_16x16x32_bf16 v[32:35], v[138:141], v[168:171], v[32:35]
	v_mfma_f32_16x16x32_bf16 v[36:39], v[146:149], v[168:171], v[36:39]
	v_mfma_f32_16x16x32_bf16 v[16:19], v[138:141], v[176:179], v[16:19]
	v_mfma_f32_16x16x32_bf16 v[20:23], v[146:149], v[176:179], v[20:23]
	v_mfma_f32_16x16x32_bf16 v[0:3], v[138:141], v[184:187], v[0:3]
	v_mfma_f32_16x16x32_bf16 v[4:7], v[146:149], v[184:187], v[4:7]
	v_mfma_f32_16x16x32_bf16 v[52:55], v[142:145], v[164:167], v[52:55]
	v_mfma_f32_16x16x32_bf16 v[60:63], v[150:153], v[164:167], v[60:63]
	v_mfma_f32_16x16x32_bf16 v[32:35], v[142:145], v[172:175], v[32:35]
	v_mfma_f32_16x16x32_bf16 v[36:39], v[150:153], v[172:175], v[36:39]
	v_mfma_f32_16x16x32_bf16 v[16:19], v[142:145], v[180:183], v[16:19]
	v_mfma_f32_16x16x32_bf16 v[20:23], v[150:153], v[180:183], v[20:23]
	v_mfma_f32_16x16x32_bf16 v[0:3], v[142:145], v[188:191], v[0:3]
	v_mfma_f32_16x16x32_bf16 v[4:7], v[150:153], v[188:191], v[4:7]
	s_setprio 0
	s_barrier
	s_add_u32 s2, s2, 0x40080
	s_addc_u32 s3, s3, 0
	s_add_i32 s20, s20, s25
	v_lshl_add_u64 v[138:139], s[2:3], 0, v[194:195]
	s_mov_b32 m0, s20
	s_nop 0
	global_load_lds_dwordx4 v[138:139], off
	v_lshl_add_u64 v[138:139], s[2:3], 0, v[128:129]
	s_add_i32 m0, s20, 0x2000
	s_nop 0
	global_load_lds_dwordx4 v[138:139], off
	s_waitcnt vmcnt(6)
	s_barrier
	s_setprio 1
	v_mfma_f32_16x16x32_bf16 v[68:71], v[206:209], v[160:163], v[68:71]
	v_mfma_f32_16x16x32_bf16 v[76:79], v[214:217], v[160:163], v[76:79]
	v_mfma_f32_16x16x32_bf16 v[40:43], v[206:209], v[168:171], v[40:43]
	v_mfma_f32_16x16x32_bf16 v[44:47], v[214:217], v[168:171], v[44:47]
	v_mfma_f32_16x16x32_bf16 v[24:27], v[206:209], v[176:179], v[24:27]
	v_mfma_f32_16x16x32_bf16 v[28:31], v[214:217], v[176:179], v[28:31]
	v_mfma_f32_16x16x32_bf16 v[8:11], v[206:209], v[184:187], v[8:11]
	v_mfma_f32_16x16x32_bf16 v[12:15], v[214:217], v[184:187], v[12:15]
	v_mfma_f32_16x16x32_bf16 v[68:71], v[210:213], v[164:167], v[68:71]
	v_mfma_f32_16x16x32_bf16 v[76:79], v[218:221], v[164:167], v[76:79]
	v_mfma_f32_16x16x32_bf16 v[40:43], v[210:213], v[172:175], v[40:43]
	v_mfma_f32_16x16x32_bf16 v[44:47], v[218:221], v[172:175], v[44:47]
	v_mfma_f32_16x16x32_bf16 v[24:27], v[210:213], v[180:183], v[24:27]
	v_mfma_f32_16x16x32_bf16 v[28:31], v[218:221], v[180:183], v[28:31]
	v_mfma_f32_16x16x32_bf16 v[8:11], v[210:213], v[188:191], v[8:11]
	v_mfma_f32_16x16x32_bf16 v[12:15], v[218:221], v[188:191], v[12:15]
	s_setprio 0
	s_add_i32 s22, s22, 2
	s_add_u32 s39, s39, 0x100
	s_addc_u32 s40, s40, 0
	s_add_u32 s6, s6, 0x100
	s_addc_u32 s7, s7, 0
	s_cmp_gt_u32 s22, 13
	s_barrier
	s_cbranch_scc0 .LBB0_132
	v_lshl_add_u32 v140, s36, 8, v156
	v_ashrrev_i32_e32 v141, 31, v140
	v_lshl_add_u64 v[138:139], v[140:141], 3, s[10:11]
	global_load_dwordx2 v[142:143], v[138:139], off
	global_load_dwordx2 v[160:161], v[138:139], off offset:128
	global_load_dwordx2 v[154:155], v[138:139], off offset:256
	global_load_dwordx2 v[152:153], v[138:139], off offset:384
	s_mov_b32 s20, 0x800000
	global_load_dwordx2 v[150:151], v[138:139], off offset:1024
	global_load_dwordx2 v[148:149], v[138:139], off offset:1152
	global_load_dwordx2 v[146:147], v[138:139], off offset:1280
	s_nop 0
	global_load_dwordx2 v[138:139], v[138:139], off offset:1408
	v_lshl_or_b32 v144, s35, 8, v158
	v_ashrrev_i32_e32 v145, 31, v144
	v_lshlrev_b64 v[144:145], 1, v[144:145]
	v_add_u32_e32 v141, 0x80, v140
	v_readlane_b32 s38, v255, 9
	v_readlane_b32 s39, v255, 10
	s_waitcnt vmcnt(0) lgkmcnt(0)
	v_ffbh_u32_e32 v162, v143
	v_min_u32_e32 v162, 32, v162
	v_lshlrev_b64 v[142:143], v162, v[142:143]
	v_min_u32_e32 v142, 1, v142
	v_or_b32_e32 v142, v143, v142
	v_cvt_f32_u32_e32 v142, v142
	v_sub_u32_e32 v143, 32, v162
	v_ldexp_f32 v142, v142, v143
	v_fmamk_f32 v142, v142, 0x2e800000, v236
	v_cmp_gt_f32_e32 vcc, s20, v142
	v_mul_f32_e32 v143, 0x4b800000, v142
	s_nop 0
	v_cndmask_b32_e32 v142, v142, v143, vcc
	v_rsq_f32_e32 v142, v142
	s_nop 0
	v_mul_f32_e32 v143, 0x45800000, v142
	v_cndmask_b32_e32 v162, v142, v143, vcc
	v_mov_b64_e32 v[142:143], s[8:9]
	v_mad_i64_i32 v[164:165], s[2:3], v140, s86, v[142:143]
	v_pk_mul_f32 v[114:115], v[114:115], v[162:163] op_sel_hi:[1,0]
	v_pk_mul_f32 v[112:113], v[112:113], v[162:163] op_sel_hi:[1,0]
	v_pk_mul_f32 v[118:119], v[118:119], v[162:163] op_sel_hi:[1,0]
	v_pk_mul_f32 v[116:117], v[116:117], v[162:163] op_sel_hi:[1,0]
	v_lshl_add_u64 v[164:165], v[164:165], 0, v[144:145]
	v_cvt_pk_bf16_f32 v112, v112, v113
	v_cvt_pk_bf16_f32 v113, v114, v115
	v_cvt_pk_bf16_f32 v114, v116, v117
	v_cvt_pk_bf16_f32 v115, v118, v119
	global_store_dwordx4 v[164:165], v[112:115], off
	v_pk_mul_f32 v[116:117], v[126:127], v[162:163] op_sel_hi:[1,0]
	v_pk_mul_f32 v[118:119], v[124:125], v[162:163] op_sel_hi:[1,0]
	v_pk_mul_f32 v[114:115], v[122:123], v[162:163] op_sel_hi:[1,0]
	v_pk_mul_f32 v[112:113], v[120:121], v[162:163] op_sel_hi:[1,0]
	s_nop 0
	v_cvt_pk_bf16_f32 v112, v112, v113
	v_cvt_pk_bf16_f32 v113, v114, v115
	v_cvt_pk_bf16_f32 v114, v118, v119
	v_cvt_pk_bf16_f32 v115, v116, v117
	global_store_dwordx4 v[164:165], v[112:115], off offset:256
	s_nop 1
	v_ffbh_u32_e32 v112, v161
	v_min_u32_e32 v115, 32, v112
	v_lshlrev_b64 v[112:113], v115, v[160:161]
	v_min_u32_e32 v112, 1, v112
	v_or_b32_e32 v112, v113, v112
	v_cvt_f32_u32_e32 v112, v112
	v_sub_u32_e32 v113, 32, v115
	v_or_b32_e32 v114, 16, v140
	v_mad_i64_i32 v[114:115], s[2:3], v114, s86, v[142:143]
	v_ldexp_f32 v112, v112, v113
	v_fmamk_f32 v112, v112, 0x2e800000, v236
	v_cmp_gt_f32_e32 vcc, s20, v112
	v_mul_f32_e32 v113, 0x4b800000, v112
	v_lshl_add_u64 v[114:115], v[114:115], 0, v[144:145]
	v_cndmask_b32_e32 v112, v112, v113, vcc
	v_rsq_f32_e32 v112, v112
	s_nop 0
	v_mul_f32_e32 v113, 0x45800000, v112
	v_cndmask_b32_e32 v112, v112, v113, vcc
	v_pk_mul_f32 v[98:99], v[98:99], v[112:113] op_sel_hi:[1,0]
	v_pk_mul_f32 v[96:97], v[96:97], v[112:113] op_sel_hi:[1,0]
	v_pk_mul_f32 v[102:103], v[102:103], v[112:113] op_sel_hi:[1,0]
	v_pk_mul_f32 v[100:101], v[100:101], v[112:113] op_sel_hi:[1,0]
	v_cvt_pk_bf16_f32 v96, v96, v97
	v_cvt_pk_bf16_f32 v97, v98, v99
	v_cvt_pk_bf16_f32 v98, v100, v101
	v_cvt_pk_bf16_f32 v99, v102, v103
	global_store_dwordx4 v[114:115], v[96:99], off
	v_pk_mul_f32 v[100:101], v[110:111], v[112:113] op_sel_hi:[1,0]
	v_pk_mul_f32 v[102:103], v[108:109], v[112:113] op_sel_hi:[1,0]
	v_pk_mul_f32 v[98:99], v[106:107], v[112:113] op_sel_hi:[1,0]
	v_pk_mul_f32 v[96:97], v[104:105], v[112:113] op_sel_hi:[1,0]
	s_nop 0
	v_cvt_pk_bf16_f32 v96, v96, v97
	v_cvt_pk_bf16_f32 v97, v98, v99
	v_cvt_pk_bf16_f32 v98, v102, v103
	v_cvt_pk_bf16_f32 v99, v100, v101
	global_store_dwordx4 v[114:115], v[96:99], off offset:256
	s_nop 1
	v_ffbh_u32_e32 v96, v155
	v_min_u32_e32 v99, 32, v96
	v_lshlrev_b64 v[96:97], v99, v[154:155]
	v_min_u32_e32 v96, 1, v96
	v_or_b32_e32 v96, v97, v96
	v_cvt_f32_u32_e32 v96, v96
	v_sub_u32_e32 v97, 32, v99
	v_or_b32_e32 v98, 32, v140
	v_mad_i64_i32 v[98:99], s[2:3], v98, s86, v[142:143]
	v_ldexp_f32 v96, v96, v97
	v_fmamk_f32 v96, v96, 0x2e800000, v236
	v_cmp_gt_f32_e32 vcc, s20, v96
	v_mul_f32_e32 v97, 0x4b800000, v96
	v_lshl_add_u64 v[98:99], v[98:99], 0, v[144:145]
	v_cndmask_b32_e32 v96, v96, v97, vcc
	v_rsq_f32_e32 v96, v96
	s_nop 0
	v_mul_f32_e32 v97, 0x45800000, v96
	v_cndmask_b32_e32 v96, v96, v97, vcc
	v_pk_mul_f32 v[82:83], v[82:83], v[96:97] op_sel_hi:[1,0]
	v_pk_mul_f32 v[80:81], v[80:81], v[96:97] op_sel_hi:[1,0]
	v_pk_mul_f32 v[86:87], v[86:87], v[96:97] op_sel_hi:[1,0]
	v_pk_mul_f32 v[84:85], v[84:85], v[96:97] op_sel_hi:[1,0]
	v_cvt_pk_bf16_f32 v80, v80, v81
	v_cvt_pk_bf16_f32 v81, v82, v83
	v_cvt_pk_bf16_f32 v82, v84, v85
	v_cvt_pk_bf16_f32 v83, v86, v87
	global_store_dwordx4 v[98:99], v[80:83], off
	v_pk_mul_f32 v[84:85], v[94:95], v[96:97] op_sel_hi:[1,0]
	v_pk_mul_f32 v[86:87], v[92:93], v[96:97] op_sel_hi:[1,0]
	v_pk_mul_f32 v[82:83], v[90:91], v[96:97] op_sel_hi:[1,0]
	v_pk_mul_f32 v[80:81], v[88:89], v[96:97] op_sel_hi:[1,0]
	s_nop 0
	v_cvt_pk_bf16_f32 v80, v80, v81
	v_cvt_pk_bf16_f32 v81, v82, v83
	v_cvt_pk_bf16_f32 v82, v86, v87
	v_cvt_pk_bf16_f32 v83, v84, v85
	global_store_dwordx4 v[98:99], v[80:83], off offset:256
	s_nop 1
	v_ffbh_u32_e32 v80, v153
	v_min_u32_e32 v83, 32, v80
	v_lshlrev_b64 v[80:81], v83, v[152:153]
	v_min_u32_e32 v80, 1, v80
	v_or_b32_e32 v80, v81, v80
	v_cvt_f32_u32_e32 v80, v80
	v_sub_u32_e32 v81, 32, v83
	v_or_b32_e32 v82, 48, v140
	v_mad_i64_i32 v[82:83], s[2:3], v82, s86, v[142:143]
	v_ldexp_f32 v80, v80, v81
	v_fmamk_f32 v80, v80, 0x2e800000, v236
	v_cmp_gt_f32_e32 vcc, s20, v80
	v_mul_f32_e32 v81, 0x4b800000, v80
	v_lshl_add_u64 v[82:83], v[82:83], 0, v[144:145]
	v_cndmask_b32_e32 v80, v80, v81, vcc
	v_rsq_f32_e32 v80, v80
	s_nop 0
	v_mul_f32_e32 v81, 0x45800000, v80
	v_cndmask_b32_e32 v80, v80, v81, vcc
	v_pk_mul_f32 v[50:51], v[50:51], v[80:81] op_sel_hi:[1,0]
	v_pk_mul_f32 v[48:49], v[48:49], v[80:81] op_sel_hi:[1,0]
	v_pk_mul_f32 v[58:59], v[58:59], v[80:81] op_sel_hi:[1,0]
	v_pk_mul_f32 v[56:57], v[56:57], v[80:81] op_sel_hi:[1,0]
	v_cvt_pk_bf16_f32 v48, v48, v49
	v_cvt_pk_bf16_f32 v49, v50, v51
	v_cvt_pk_bf16_f32 v50, v56, v57
	v_cvt_pk_bf16_f32 v51, v58, v59
	global_store_dwordx4 v[82:83], v[48:51], off
	v_pk_mul_f32 v[56:57], v[74:75], v[80:81] op_sel_hi:[1,0]
	v_pk_mul_f32 v[58:59], v[72:73], v[80:81] op_sel_hi:[1,0]
	v_pk_mul_f32 v[50:51], v[66:67], v[80:81] op_sel_hi:[1,0]
	v_pk_mul_f32 v[48:49], v[64:65], v[80:81] op_sel_hi:[1,0]
	s_nop 0
	v_cvt_pk_bf16_f32 v48, v48, v49
	v_cvt_pk_bf16_f32 v49, v50, v51
	v_cvt_pk_bf16_f32 v50, v58, v59
	v_cvt_pk_bf16_f32 v51, v56, v57
	global_store_dwordx4 v[82:83], v[48:51], off offset:256
	s_nop 1
	v_ffbh_u32_e32 v48, v151
	v_min_u32_e32 v50, 32, v48
	v_lshlrev_b64 v[48:49], v50, v[150:151]
	v_min_u32_e32 v48, 1, v48
	v_or_b32_e32 v48, v49, v48
	v_cvt_f32_u32_e32 v48, v48
	v_sub_u32_e32 v49, 32, v50
	v_ldexp_f32 v48, v48, v49
	v_fmamk_f32 v48, v48, 0x2e800000, v236
	v_cmp_gt_f32_e32 vcc, s20, v48
	v_mul_f32_e32 v49, 0x4b800000, v48
	s_nop 0
	v_cndmask_b32_e32 v48, v48, v49, vcc
	v_rsq_f32_e32 v48, v48
	s_nop 0
	v_mul_f32_e32 v49, 0x45800000, v48
	v_cndmask_b32_e32 v56, v48, v49, vcc
	v_mad_i64_i32 v[48:49], s[2:3], v141, s86, v[142:143]
	v_lshl_add_u64 v[58:59], v[48:49], 0, v[144:145]
	v_pk_mul_f32 v[50:51], v[54:55], v[56:57] op_sel_hi:[1,0]
	v_pk_mul_f32 v[48:49], v[52:53], v[56:57] op_sel_hi:[1,0]
	v_pk_mul_f32 v[52:53], v[62:63], v[56:57] op_sel_hi:[1,0]
	v_pk_mul_f32 v[54:55], v[60:61], v[56:57] op_sel_hi:[1,0]
	v_cvt_pk_bf16_f32 v48, v48, v49
	v_cvt_pk_bf16_f32 v49, v50, v51
	v_cvt_pk_bf16_f32 v50, v54, v55
	v_cvt_pk_bf16_f32 v51, v52, v53
	global_store_dwordx4 v[58:59], v[48:51], off
	v_pk_mul_f32 v[52:53], v[78:79], v[56:57] op_sel_hi:[1,0]
	v_pk_mul_f32 v[54:55], v[76:77], v[56:57] op_sel_hi:[1,0]
	v_pk_mul_f32 v[50:51], v[70:71], v[56:57] op_sel_hi:[1,0]
	v_pk_mul_f32 v[48:49], v[68:69], v[56:57] op_sel_hi:[1,0]
	s_nop 0
	v_cvt_pk_bf16_f32 v48, v48, v49
	v_cvt_pk_bf16_f32 v49, v50, v51
	v_cvt_pk_bf16_f32 v50, v54, v55
	v_cvt_pk_bf16_f32 v51, v52, v53
	global_store_dwordx4 v[58:59], v[48:51], off offset:256
	s_nop 1
	v_ffbh_u32_e32 v48, v149
	v_min_u32_e32 v51, 32, v48
	v_lshlrev_b64 v[48:49], v51, v[148:149]
	v_min_u32_e32 v48, 1, v48
	v_or_b32_e32 v48, v49, v48
	v_cvt_f32_u32_e32 v48, v48
	v_sub_u32_e32 v49, 32, v51
	v_add_u32_e32 v50, 0x90, v140
	v_mad_i64_i32 v[50:51], s[2:3], v50, s86, v[142:143]
	v_ldexp_f32 v48, v48, v49
	v_fmamk_f32 v48, v48, 0x2e800000, v236
	v_cmp_gt_f32_e32 vcc, s20, v48
	v_mul_f32_e32 v49, 0x4b800000, v48
	v_lshl_add_u64 v[50:51], v[50:51], 0, v[144:145]
	v_cndmask_b32_e32 v48, v48, v49, vcc
	v_rsq_f32_e32 v48, v48
	s_nop 0
	v_mul_f32_e32 v49, 0x45800000, v48
	v_cndmask_b32_e32 v48, v48, v49, vcc
	v_pk_mul_f32 v[34:35], v[34:35], v[48:49] op_sel_hi:[1,0]
	v_pk_mul_f32 v[32:33], v[32:33], v[48:49] op_sel_hi:[1,0]
	v_pk_mul_f32 v[38:39], v[38:39], v[48:49] op_sel_hi:[1,0]
	v_pk_mul_f32 v[36:37], v[36:37], v[48:49] op_sel_hi:[1,0]
	v_cvt_pk_bf16_f32 v32, v32, v33
	v_cvt_pk_bf16_f32 v33, v34, v35
	v_cvt_pk_bf16_f32 v34, v36, v37
	v_cvt_pk_bf16_f32 v35, v38, v39
	global_store_dwordx4 v[50:51], v[32:35], off
	v_pk_mul_f32 v[36:37], v[46:47], v[48:49] op_sel_hi:[1,0]
	v_pk_mul_f32 v[38:39], v[44:45], v[48:49] op_sel_hi:[1,0]
	v_pk_mul_f32 v[34:35], v[42:43], v[48:49] op_sel_hi:[1,0]
	v_pk_mul_f32 v[32:33], v[40:41], v[48:49] op_sel_hi:[1,0]
	s_nop 0
	v_cvt_pk_bf16_f32 v32, v32, v33
	v_cvt_pk_bf16_f32 v33, v34, v35
	v_cvt_pk_bf16_f32 v34, v38, v39
	v_cvt_pk_bf16_f32 v35, v36, v37
	global_store_dwordx4 v[50:51], v[32:35], off offset:256
	s_nop 1
	v_ffbh_u32_e32 v32, v147
	v_min_u32_e32 v35, 32, v32
	v_lshlrev_b64 v[32:33], v35, v[146:147]
	v_min_u32_e32 v32, 1, v32
	v_or_b32_e32 v32, v33, v32
	v_cvt_f32_u32_e32 v32, v32
	v_sub_u32_e32 v33, 32, v35
	v_add_u32_e32 v34, 0xa0, v140
	v_mad_i64_i32 v[34:35], s[2:3], v34, s86, v[142:143]
	v_ldexp_f32 v32, v32, v33
	v_fmamk_f32 v32, v32, 0x2e800000, v236
	v_cmp_gt_f32_e32 vcc, s20, v32
	v_mul_f32_e32 v33, 0x4b800000, v32
	v_lshl_add_u64 v[34:35], v[34:35], 0, v[144:145]
	v_cndmask_b32_e32 v32, v32, v33, vcc
	v_rsq_f32_e32 v32, v32
	s_nop 0
	v_mul_f32_e32 v33, 0x45800000, v32
	v_cndmask_b32_e32 v32, v32, v33, vcc
	v_pk_mul_f32 v[18:19], v[18:19], v[32:33] op_sel_hi:[1,0]
	v_pk_mul_f32 v[16:17], v[16:17], v[32:33] op_sel_hi:[1,0]
	v_pk_mul_f32 v[22:23], v[22:23], v[32:33] op_sel_hi:[1,0]
	v_pk_mul_f32 v[20:21], v[20:21], v[32:33] op_sel_hi:[1,0]
	v_cvt_pk_bf16_f32 v16, v16, v17
	v_cvt_pk_bf16_f32 v17, v18, v19
	v_cvt_pk_bf16_f32 v18, v20, v21
	v_cvt_pk_bf16_f32 v19, v22, v23
	global_store_dwordx4 v[34:35], v[16:19], off
	v_pk_mul_f32 v[20:21], v[30:31], v[32:33] op_sel_hi:[1,0]
	v_pk_mul_f32 v[22:23], v[28:29], v[32:33] op_sel_hi:[1,0]
	v_pk_mul_f32 v[18:19], v[26:27], v[32:33] op_sel_hi:[1,0]
	v_pk_mul_f32 v[16:17], v[24:25], v[32:33] op_sel_hi:[1,0]
	s_nop 0
	v_cvt_pk_bf16_f32 v16, v16, v17
	v_cvt_pk_bf16_f32 v17, v18, v19
	v_cvt_pk_bf16_f32 v18, v22, v23
	v_cvt_pk_bf16_f32 v19, v20, v21
	global_store_dwordx4 v[34:35], v[16:19], off offset:256
	s_nop 1
	v_ffbh_u32_e32 v16, v139
	v_min_u32_e32 v19, 32, v16
	v_lshlrev_b64 v[16:17], v19, v[138:139]
	v_min_u32_e32 v16, 1, v16
	v_or_b32_e32 v16, v17, v16
	v_cvt_f32_u32_e32 v16, v16
	v_sub_u32_e32 v17, 32, v19
	v_add_u32_e32 v18, 0xb0, v140
	v_mad_i64_i32 v[18:19], s[2:3], v18, s86, v[142:143]
	v_ldexp_f32 v16, v16, v17
	v_fmamk_f32 v16, v16, 0x2e800000, v236
	v_cmp_gt_f32_e32 vcc, s20, v16
	v_mul_f32_e32 v17, 0x4b800000, v16
	v_lshl_add_u64 v[18:19], v[18:19], 0, v[144:145]
	v_cndmask_b32_e32 v16, v16, v17, vcc
	v_rsq_f32_e32 v16, v16
	s_mov_b64 s[2:3], -1
	v_mul_f32_e32 v17, 0x45800000, v16
	v_cndmask_b32_e32 v16, v16, v17, vcc
	v_pk_mul_f32 v[2:3], v[2:3], v[16:17] op_sel_hi:[1,0]
	v_pk_mul_f32 v[0:1], v[0:1], v[16:17] op_sel_hi:[1,0]
	v_pk_mul_f32 v[6:7], v[6:7], v[16:17] op_sel_hi:[1,0]
	v_pk_mul_f32 v[4:5], v[4:5], v[16:17] op_sel_hi:[1,0]
	v_cvt_pk_bf16_f32 v0, v0, v1
	v_cvt_pk_bf16_f32 v1, v2, v3
	v_cvt_pk_bf16_f32 v2, v4, v5
	v_cvt_pk_bf16_f32 v3, v6, v7
	global_store_dwordx4 v[18:19], v[0:3], off
	v_pk_mul_f32 v[4:5], v[14:15], v[16:17] op_sel_hi:[1,0]
	v_pk_mul_f32 v[6:7], v[12:13], v[16:17] op_sel_hi:[1,0]
	v_pk_mul_f32 v[2:3], v[10:11], v[16:17] op_sel_hi:[1,0]
	v_pk_mul_f32 v[0:1], v[8:9], v[16:17] op_sel_hi:[1,0]
	s_andn2_b64 vcc, exec, s[4:5]
	v_cvt_pk_bf16_f32 v0, v0, v1
	v_cvt_pk_bf16_f32 v1, v2, v3
	v_cvt_pk_bf16_f32 v2, v6, v7
	v_cvt_pk_bf16_f32 v3, v4, v5
	global_store_dwordx4 v[18:19], v[0:3], off offset:256
	s_cbranch_vccnz .LBB0_128
	v_mov_b32_e32 v112, v192
	v_mov_b32_e32 v116, v192
	v_mov_b32_e32 v96, v192
	v_mov_b32_e32 v100, v192
	v_mov_b32_e32 v80, v192
	v_mov_b32_e32 v84, v192
	v_mov_b32_e32 v48, v192
	v_mov_b32_e32 v56, v192
	v_mov_b32_e32 v120, v192
	v_mov_b32_e32 v124, v192
	v_mov_b32_e32 v104, v192
	v_mov_b32_e32 v108, v192
	v_mov_b32_e32 v88, v192
	v_mov_b32_e32 v92, v192
	v_mov_b32_e32 v64, v192
	v_mov_b32_e32 v72, v192
	v_mov_b32_e32 v52, v192
	v_mov_b32_e32 v60, v192
	v_mov_b32_e32 v32, v192
	v_mov_b32_e32 v36, v192
	v_mov_b32_e32 v16, v192
	v_mov_b32_e32 v20, v192
	v_mov_b32_e32 v0, v192
	v_mov_b32_e32 v4, v192
	v_mov_b32_e32 v68, v192
	v_mov_b32_e32 v76, v192
	v_mov_b32_e32 v40, v192
	v_mov_b32_e32 v44, v192
	v_mov_b32_e32 v24, v192
	v_mov_b32_e32 v28, v192
	v_mov_b32_e32 v8, v192
	v_mov_b32_e32 v12, v195
	s_nop 0
	v_mov_b32_e32 v113, v112
	v_mov_b32_e32 v114, v112
	v_mov_b32_e32 v115, v112
	v_mov_b32_e32 v117, v116
	v_mov_b32_e32 v118, v116
	v_mov_b32_e32 v119, v116
	v_mov_b32_e32 v97, v96
	v_mov_b32_e32 v98, v96
	v_mov_b32_e32 v99, v96
	v_mov_b32_e32 v101, v100
	v_mov_b32_e32 v102, v100
	v_mov_b32_e32 v103, v100
	v_mov_b32_e32 v81, v80
	v_mov_b32_e32 v82, v80
	v_mov_b32_e32 v83, v80
	v_mov_b32_e32 v85, v84
	v_mov_b32_e32 v86, v84
	v_mov_b32_e32 v87, v84
	s_nop 0
	v_mov_b32_e32 v49, v48
	v_mov_b32_e32 v50, v48
	v_mov_b32_e32 v51, v48
	v_mov_b32_e32 v57, v56
	v_mov_b32_e32 v58, v56
	v_mov_b32_e32 v59, v56
	v_mov_b32_e32 v121, v120
	v_mov_b32_e32 v122, v120
	v_mov_b32_e32 v123, v120
	v_mov_b32_e32 v125, v124
	v_mov_b32_e32 v126, v124
	v_mov_b32_e32 v127, v124
	v_mov_b32_e32 v105, v104
	v_mov_b32_e32 v106, v104
	v_mov_b32_e32 v107, v104
	v_mov_b32_e32 v109, v108
	v_mov_b32_e32 v110, v108
	v_mov_b32_e32 v111, v108
	s_nop 0
	v_mov_b32_e32 v89, v88
	v_mov_b32_e32 v90, v88
	v_mov_b32_e32 v91, v88
	v_mov_b32_e32 v93, v92
	v_mov_b32_e32 v94, v92
	v_mov_b32_e32 v95, v92
	v_mov_b32_e32 v65, v64
	v_mov_b32_e32 v66, v64
	v_mov_b32_e32 v67, v64
	v_mov_b32_e32 v73, v72
	v_mov_b32_e32 v74, v72
	v_mov_b32_e32 v75, v72
	v_mov_b32_e32 v53, v52
	v_mov_b32_e32 v54, v52
	v_mov_b32_e32 v55, v52
	v_mov_b32_e32 v61, v60
	v_mov_b32_e32 v62, v60
	v_mov_b32_e32 v63, v60
	s_nop 0
	v_mov_b32_e32 v33, v32
	v_mov_b32_e32 v34, v32
	v_mov_b32_e32 v35, v32
	v_mov_b32_e32 v37, v36
	v_mov_b32_e32 v38, v36
	v_mov_b32_e32 v39, v36
	v_mov_b32_e32 v17, v16
	v_mov_b32_e32 v18, v16
	v_mov_b32_e32 v19, v16
	v_mov_b32_e32 v21, v20
	v_mov_b32_e32 v22, v20
	v_mov_b32_e32 v23, v20
	v_mov_b32_e32 v1, v0
	v_mov_b32_e32 v2, v0
	v_mov_b32_e32 v3, v0
	v_mov_b32_e32 v5, v4
	v_mov_b32_e32 v6, v4
	v_mov_b32_e32 v7, v4
	s_nop 0
	v_mov_b32_e32 v69, v68
	v_mov_b32_e32 v70, v68
	v_mov_b32_e32 v71, v68
	v_mov_b32_e32 v77, v76
	v_mov_b32_e32 v78, v76
	v_mov_b32_e32 v79, v76
	v_mov_b32_e32 v41, v40
	v_mov_b32_e32 v42, v40
	v_mov_b32_e32 v43, v40
	v_mov_b32_e32 v45, v44
	v_mov_b32_e32 v46, v44
	v_mov_b32_e32 v47, v44
	v_mov_b32_e32 v25, v24
	v_mov_b32_e32 v26, v24
	v_mov_b32_e32 v27, v24
	v_mov_b32_e32 v29, v28
	v_mov_b32_e32 v30, v28
	v_mov_b32_e32 v31, v28
	s_mov_b64 s[2:3], 0
	v_mov_b32_e32 v9, v8
	v_mov_b32_e32 v10, v8
	v_mov_b32_e32 v11, v8
	v_mov_b32_e32 v13, v12
	v_mov_b32_e32 v14, v12
	v_mov_b32_e32 v15, v12
	s_branch .LBB0_128

.LBB0_141:
	s_and_b32 s11, s7, 0x70
	s_and_b32 s10, s3, 0xffffffe0
	v_or_b32_e32 v5, s11, v14
	v_or_b32_e32 v8, s10, v14
	v_lshlrev_b32_e32 v194, 11, v5
	v_ashrrev_i32_e32 v9, 31, v8
	v_or_b32_e32 v16, 16, v8
	v_lshl_add_u64 v[6:7], v[0:1], 0, v[194:195]
	v_lshlrev_b64 v[8:9], 11, v[8:9]
	v_ashrrev_i32_e32 v17, 31, v16
	v_lshl_add_u64 v[10:11], v[2:3], 0, v[8:9]
	v_lshlrev_b64 v[8:9], 11, v[16:17]
	global_load_dwordx4 v[16:19], v[6:7], off
	global_load_dwordx4 v[20:23], v[6:7], off offset:64
	global_load_dwordx4 v[24:27], v[10:11], off
	v_lshl_add_u64 v[8:9], v[2:3], 0, v[8:9]
	global_load_dwordx4 v[28:31], v[10:11], off offset:64
	global_load_dwordx4 v[32:35], v[8:9], off
	global_load_dwordx4 v[36:39], v[8:9], off offset:64
	v_or_b32_e32 v15, 0x4000, v5
	v_lshlrev_b32_e32 v194, 3, v15
	v_lshl_add_u64 v[92:93], s[4:5], 0, v[194:195]
	s_ashr_i32 s11, s10, 31
	v_mov_b32_e32 v5, v195
	s_add_i32 s2, s2, s80
	s_add_i32 s3, s3, s76
	s_add_i32 s7, s7, s64
	s_cmpk_gt_i32 s2, 0x25f
	s_waitcnt vmcnt(0) lgkmcnt(0)
	v_mfma_f32_16x16x32_bf16 v[24:27], v[24:27], v[16:19], 0
	v_mfma_f32_16x16x32_bf16 v[16:19], v[32:35], v[16:19], 0
	global_load_dwordx4 v[32:35], v[6:7], off offset:128
	global_load_dwordx4 v[40:43], v[6:7], off offset:192
	global_load_dwordx4 v[44:47], v[6:7], off offset:256
	v_mfma_f32_16x16x32_bf16 v[24:27], v[28:31], v[20:23], v[24:27]
	global_load_dwordx4 v[28:31], v[10:11], off offset:128
	global_load_dwordx4 v[48:51], v[10:11], off offset:192
	v_mfma_f32_16x16x32_bf16 v[16:19], v[36:39], v[20:23], v[16:19]
	global_load_dwordx4 v[20:23], v[8:9], off offset:128
	s_waitcnt vmcnt(0) lgkmcnt(0)
	v_mfma_f32_16x16x32_bf16 v[24:27], v[28:31], v[32:35], v[24:27]
	global_load_dwordx4 v[28:31], v[8:9], off offset:192
	v_mfma_f32_16x16x32_bf16 v[16:19], v[20:23], v[32:35], v[16:19]
	global_load_dwordx4 v[20:23], v[6:7], off offset:320
	global_load_dwordx4 v[32:35], v[6:7], off offset:384
	global_load_dwordx4 v[36:39], v[6:7], off offset:448
	v_mfma_f32_16x16x32_bf16 v[24:27], v[48:51], v[40:43], v[24:27]
	global_load_dwordx4 v[48:51], v[10:11], off offset:256
	global_load_dwordx4 v[52:55], v[10:11], off offset:320
	s_waitcnt vmcnt(0) lgkmcnt(0)
	v_mfma_f32_16x16x32_bf16 v[16:19], v[28:31], v[40:43], v[16:19]
	global_load_dwordx4 v[28:31], v[8:9], off offset:256
	global_load_dwordx4 v[40:43], v[8:9], off offset:320
	v_mfma_f32_16x16x32_bf16 v[24:27], v[48:51], v[44:47], v[24:27]
	v_mfma_f32_16x16x32_bf16 v[24:27], v[52:55], v[20:23], v[24:27]
	s_waitcnt vmcnt(0) lgkmcnt(0)
	v_mfma_f32_16x16x32_bf16 v[16:19], v[28:31], v[44:47], v[16:19]
	global_load_dwordx4 v[28:31], v[6:7], off offset:512
	global_load_dwordx4 v[44:47], v[6:7], off offset:576
	global_load_dwordx4 v[48:51], v[6:7], off offset:640
	global_load_dwordx4 v[52:55], v[10:11], off offset:384
	global_load_dwordx4 v[56:59], v[10:11], off offset:448
	v_mfma_f32_16x16x32_bf16 v[16:19], v[40:43], v[20:23], v[16:19]
	global_load_dwordx4 v[20:23], v[8:9], off offset:384
	global_load_dwordx4 v[40:43], v[8:9], off offset:448
	s_waitcnt vmcnt(0) lgkmcnt(0)
	v_mfma_f32_16x16x32_bf16 v[24:27], v[52:55], v[32:35], v[24:27]
	v_mfma_f32_16x16x32_bf16 v[16:19], v[20:23], v[32:35], v[16:19]
	global_load_dwordx4 v[20:23], v[6:7], off offset:704
	global_load_dwordx4 v[32:35], v[6:7], off offset:768
	global_load_dwordx4 v[52:55], v[6:7], off offset:832
	v_mfma_f32_16x16x32_bf16 v[24:27], v[56:59], v[36:39], v[24:27]
	global_load_dwordx4 v[56:59], v[10:11], off offset:512
	global_load_dwordx4 v[60:63], v[10:11], off offset:576
	v_mfma_f32_16x16x32_bf16 v[16:19], v[40:43], v[36:39], v[16:19]
	global_load_dwordx4 v[36:39], v[8:9], off offset:512
	global_load_dwordx4 v[40:43], v[8:9], off offset:576
	s_waitcnt vmcnt(0) lgkmcnt(0)
	v_mfma_f32_16x16x32_bf16 v[24:27], v[56:59], v[28:31], v[24:27]
	v_mfma_f32_16x16x32_bf16 v[16:19], v[36:39], v[28:31], v[16:19]
	global_load_dwordx4 v[28:31], v[6:7], off offset:896
	global_load_dwordx4 v[36:39], v[6:7], off offset:960
	global_load_dwordx4 v[56:59], v[6:7], off offset:1024
	v_mfma_f32_16x16x32_bf16 v[24:27], v[60:63], v[44:47], v[24:27]
	global_load_dwordx4 v[60:63], v[10:11], off offset:640
	global_load_dwordx4 v[64:67], v[10:11], off offset:704
	v_mfma_f32_16x16x32_bf16 v[16:19], v[40:43], v[44:47], v[16:19]
	global_load_dwordx4 v[40:43], v[8:9], off offset:640
	global_load_dwordx4 v[44:47], v[8:9], off offset:704
	s_waitcnt vmcnt(0) lgkmcnt(0)
	v_mfma_f32_16x16x32_bf16 v[24:27], v[60:63], v[48:51], v[24:27]
	v_mfma_f32_16x16x32_bf16 v[16:19], v[40:43], v[48:51], v[16:19]
	global_load_dwordx4 v[40:43], v[6:7], off offset:1088
	global_load_dwordx4 v[48:51], v[6:7], off offset:1152
	global_load_dwordx4 v[60:63], v[6:7], off offset:1216
	v_mfma_f32_16x16x32_bf16 v[24:27], v[64:67], v[20:23], v[24:27]
	global_load_dwordx4 v[64:67], v[10:11], off offset:768
	global_load_dwordx4 v[68:71], v[10:11], off offset:832
	v_mfma_f32_16x16x32_bf16 v[16:19], v[44:47], v[20:23], v[16:19]
	global_load_dwordx4 v[20:23], v[8:9], off offset:768
	global_load_dwordx4 v[44:47], v[8:9], off offset:832
	s_waitcnt vmcnt(0) lgkmcnt(0)
	v_mfma_f32_16x16x32_bf16 v[24:27], v[64:67], v[32:35], v[24:27]
	v_mfma_f32_16x16x32_bf16 v[16:19], v[20:23], v[32:35], v[16:19]
	global_load_dwordx4 v[20:23], v[6:7], off offset:1280
	global_load_dwordx4 v[32:35], v[6:7], off offset:1344
	global_load_dwordx4 v[64:67], v[6:7], off offset:1408
	v_mfma_f32_16x16x32_bf16 v[24:27], v[68:71], v[52:55], v[24:27]
	global_load_dwordx4 v[68:71], v[10:11], off offset:896
	global_load_dwordx4 v[72:75], v[10:11], off offset:960
	v_mfma_f32_16x16x32_bf16 v[16:19], v[44:47], v[52:55], v[16:19]
	global_load_dwordx4 v[44:47], v[8:9], off offset:896
	global_load_dwordx4 v[52:55], v[8:9], off offset:960
	s_waitcnt vmcnt(0) lgkmcnt(0)
	v_mfma_f32_16x16x32_bf16 v[24:27], v[68:71], v[28:31], v[24:27]
	v_mfma_f32_16x16x32_bf16 v[16:19], v[44:47], v[28:31], v[16:19]
	global_load_dwordx4 v[28:31], v[6:7], off offset:1472
	global_load_dwordx4 v[44:47], v[6:7], off offset:1536
	global_load_dwordx4 v[68:71], v[6:7], off offset:1600
	v_mfma_f32_16x16x32_bf16 v[24:27], v[72:75], v[36:39], v[24:27]
	global_load_dwordx4 v[72:75], v[10:11], off offset:1024
	global_load_dwordx4 v[76:79], v[10:11], off offset:1088
	v_mfma_f32_16x16x32_bf16 v[16:19], v[52:55], v[36:39], v[16:19]
	global_load_dwordx4 v[36:39], v[8:9], off offset:1024
	global_load_dwordx4 v[52:55], v[8:9], off offset:1088
	s_waitcnt vmcnt(0) lgkmcnt(0)
	v_mfma_f32_16x16x32_bf16 v[24:27], v[72:75], v[56:59], v[24:27]
	v_mfma_f32_16x16x32_bf16 v[16:19], v[36:39], v[56:59], v[16:19]
	global_load_dwordx4 v[36:39], v[6:7], off offset:1664
	global_load_dwordx4 v[56:59], v[6:7], off offset:1728
	global_load_dwordx4 v[72:75], v[6:7], off offset:1792
	v_mfma_f32_16x16x32_bf16 v[24:27], v[76:79], v[40:43], v[24:27]
	global_load_dwordx4 v[76:79], v[10:11], off offset:1152
	global_load_dwordx4 v[80:83], v[10:11], off offset:1216
	v_mfma_f32_16x16x32_bf16 v[16:19], v[52:55], v[40:43], v[16:19]
	global_load_dwordx4 v[40:43], v[8:9], off offset:1152
	global_load_dwordx4 v[52:55], v[8:9], off offset:1216
	s_waitcnt vmcnt(0) lgkmcnt(0)
	v_mfma_f32_16x16x32_bf16 v[24:27], v[76:79], v[48:51], v[24:27]
	v_mfma_f32_16x16x32_bf16 v[16:19], v[40:43], v[48:51], v[16:19]
	global_load_dwordx4 v[40:43], v[6:7], off offset:1856
	global_load_dwordx4 v[48:51], v[6:7], off offset:1920
	v_mfma_f32_16x16x32_bf16 v[24:27], v[80:83], v[60:63], v[24:27]
	global_load_dwordx4 v[76:79], v[10:11], off offset:1280
	global_load_dwordx4 v[80:83], v[10:11], off offset:1344
	v_mfma_f32_16x16x32_bf16 v[16:19], v[52:55], v[60:63], v[16:19]
	global_load_dwordx4 v[52:55], v[8:9], off offset:1280
	global_load_dwordx4 v[60:63], v[8:9], off offset:1344
	s_waitcnt vmcnt(0) lgkmcnt(0)
	v_mfma_f32_16x16x32_bf16 v[24:27], v[76:79], v[20:23], v[24:27]
	v_mfma_f32_16x16x32_bf16 v[16:19], v[52:55], v[20:23], v[16:19]
	global_load_dwordx4 v[20:23], v[10:11], off offset:1408
	global_load_dwordx4 v[52:55], v[10:11], off offset:1472
	v_mfma_f32_16x16x32_bf16 v[24:27], v[80:83], v[32:35], v[24:27]
	global_load_dwordx4 v[76:79], v[10:11], off offset:1536
	global_load_dwordx4 v[80:83], v[10:11], off offset:1600
	global_load_dwordx4 v[84:87], v[10:11], off offset:1664
	v_mfma_f32_16x16x32_bf16 v[16:19], v[60:63], v[32:35], v[16:19]
	global_load_dwordx4 v[32:35], v[8:9], off offset:1408
	s_waitcnt vmcnt(0) lgkmcnt(0)
	v_mfma_f32_16x16x32_bf16 v[20:23], v[20:23], v[64:67], v[24:27]
	s_nop 2
	global_load_dwordx4 v[24:27], v[8:9], off offset:1472
	v_mfma_f32_16x16x32_bf16 v[16:19], v[32:35], v[64:67], v[16:19]
	global_load_dwordx4 v[32:35], v[10:11], off offset:1728
	global_load_dwordx4 v[60:63], v[10:11], off offset:1792
	global_load_dwordx4 v[64:67], v[10:11], off offset:1856
	v_mfma_f32_16x16x32_bf16 v[20:23], v[52:55], v[28:31], v[20:23]
	global_load_dwordx4 v[52:55], v[10:11], off offset:1920
	global_load_dwordx4 v[88:91], v[10:11], off offset:1984
	s_nop 0
	global_load_dwordx2 v[92:93], v[92:93], off
	v_mfma_f32_16x16x32_bf16 v[20:23], v[76:79], v[44:47], v[20:23]
	v_mfma_f32_16x16x32_bf16 v[20:23], v[80:83], v[68:71], v[20:23]
	v_mfma_f32_16x16x32_bf16 v[20:23], v[84:87], v[36:39], v[20:23]
	s_waitcnt vmcnt(0) lgkmcnt(0)
	v_mfma_f32_16x16x32_bf16 v[16:19], v[24:27], v[28:31], v[16:19]
	global_load_dwordx4 v[24:27], v[8:9], off offset:1536
	global_load_dwordx4 v[28:31], v[8:9], off offset:1600
	v_mfma_f32_16x16x32_bf16 v[20:23], v[32:35], v[56:59], v[20:23]
	v_mfma_f32_16x16x32_bf16 v[20:23], v[60:63], v[72:75], v[20:23]
	v_mfma_f32_16x16x32_bf16 v[20:23], v[64:67], v[40:43], v[20:23]
	v_mfma_f32_16x16x32_bf16 v[20:23], v[52:55], v[48:51], v[20:23]
	s_waitcnt vmcnt(0) lgkmcnt(0)
	v_mfma_f32_16x16x32_bf16 v[16:19], v[24:27], v[44:47], v[16:19]
	global_load_dwordx4 v[24:27], v[8:9], off offset:1664
	global_load_dwordx4 v[44:47], v[8:9], off offset:1728
	v_mfma_f32_16x16x32_bf16 v[16:19], v[28:31], v[68:71], v[16:19]
	global_load_dwordx4 v[28:31], v[8:9], off offset:1792
	global_load_dwordx4 v[68:71], v[8:9], off offset:1856
	s_waitcnt vmcnt(0) lgkmcnt(0)
	v_mfma_f32_16x16x32_bf16 v[16:19], v[24:27], v[36:39], v[16:19]
	global_load_dwordx4 v[24:27], v[8:9], off offset:1920
	s_nop 0
	global_load_dwordx4 v[8:11], v[8:9], off offset:1984
	s_nop 0
	global_load_dwordx4 v[32:35], v[6:7], off offset:1984
	v_mfma_f32_16x16x32_bf16 v[16:19], v[44:47], v[56:59], v[16:19]
	v_mul_u32_u24_e32 v6, 0xa00, v15
	v_lshlrev_b32_e32 v194, 1, v6
	v_lshl_add_u64 v[6:7], s[0:1], 0, v[194:195]
	v_lshl_add_u64 v[6:7], s[10:11], 1, v[6:7]
	v_mfma_f32_16x16x32_bf16 v[16:19], v[28:31], v[72:75], v[16:19]
	v_lshl_add_u64 v[28:29], v[6:7], 0, v[4:5]
	v_ffbh_u32_e32 v5, v93
	v_min_u32_e32 v5, 32, v5
	v_lshlrev_b64 v[6:7], v5, v[92:93]
	v_min_u32_e32 v6, 1, v6
	v_or_b32_e32 v6, v7, v6
	v_cvt_f32_u32_e32 v6, v6
	v_sub_u32_e32 v5, 32, v5
	v_mfma_f32_16x16x32_bf16 v[16:19], v[68:71], v[40:43], v[16:19]
	v_ldexp_f32 v5, v6, v5
	v_fmamk_f32 v5, v5, 0x2e800000, v236
	v_mul_f32_e32 v6, 0x4b800000, v5
	v_cmp_gt_f32_e32 vcc, s20, v5
	s_waitcnt vmcnt(0) lgkmcnt(0)
	v_mfma_f32_16x16x32_bf16 v[16:19], v[24:27], v[48:51], v[16:19]
	v_cndmask_b32_e32 v5, v5, v6, vcc
	v_rsq_f32_e32 v5, v5
	v_mfma_f32_16x16x32_bf16 v[20:23], v[88:91], v[32:35], v[20:23]
	v_mul_f32_e32 v6, 0x45800000, v5
	v_cndmask_b32_e32 v24, v5, v6, vcc
	v_mfma_f32_16x16x32_bf16 v[6:9], v[8:11], v[32:35], v[16:19]
	s_nop 4
	v_mul_f32_e64 v10, v22, v24
	v_mul_f32_e64 v11, v23, v24
	v_pk_mul_f32 v[16:17], v[20:21], v[24:25] op_sel_hi:[1,0]
	v_pk_mul_f32 v[8:9], v[8:9], v[24:25] op_sel_hi:[1,0]
	v_pk_mul_f32 v[6:7], v[6:7], v[24:25] op_sel_hi:[1,0]
	v_cvt_pk_bf16_f32 v16, v16, v17
	v_cvt_pk_bf16_f32 v17, v10, v11
	v_cvt_pk_bf16_f32 v6, v6, v7
	v_cvt_pk_bf16_f32 v7, v8, v9
	global_store_dwordx2 v[28:29], v[16:17], off
	global_store_dwordx2 v[28:29], v[6:7], off offset:32
	s_cbranch_scc0 .LBB0_141

.LBB0_147:
	s_and_b32 s7, s6, 0x70
	s_and_b32 s8, s3, 0xffffffe0
	v_or_b32_e32 v5, s7, v13
	v_or_b32_e32 v8, s8, v13
	v_lshlrev_b32_e32 v194, 11, v5
	v_ashrrev_i32_e32 v9, 31, v8
	v_or_b32_e32 v14, 16, v8
	v_lshl_add_u64 v[6:7], v[0:1], 0, v[194:195]
	v_lshlrev_b64 v[8:9], 11, v[8:9]
	v_ashrrev_i32_e32 v15, 31, v14
	v_lshl_add_u64 v[10:11], v[2:3], 0, v[8:9]
	v_lshlrev_b64 v[8:9], 11, v[14:15]
	global_load_dwordx4 v[14:17], v[6:7], off
	global_load_dwordx4 v[18:21], v[6:7], off offset:64
	global_load_dwordx4 v[22:25], v[10:11], off
	v_lshl_add_u64 v[8:9], v[2:3], 0, v[8:9]
	global_load_dwordx4 v[26:29], v[10:11], off offset:64
	global_load_dwordx4 v[30:33], v[8:9], off
	global_load_dwordx4 v[34:37], v[8:9], off offset:64
	v_or_b32_e32 v12, 0x4000, v5
	v_lshlrev_b32_e32 v194, 3, v12
	v_lshl_add_u64 v[90:91], s[4:5], 0, v[194:195]
	s_ashr_i32 s9, s8, 31
	v_mov_b32_e32 v5, v195
	s_add_i32 s2, s2, s42
	s_add_i32 s3, s3, s12
	s_add_i32 s6, s6, s10
	s_cmpk_gt_i32 s2, 0x25f
	s_waitcnt vmcnt(0) lgkmcnt(0)
	v_mfma_f32_16x16x32_bf16 v[22:25], v[22:25], v[14:17], 0
	v_mfma_f32_16x16x32_bf16 v[14:17], v[30:33], v[14:17], 0
	global_load_dwordx4 v[30:33], v[6:7], off offset:128
	global_load_dwordx4 v[38:41], v[6:7], off offset:192
	global_load_dwordx4 v[42:45], v[6:7], off offset:256
	v_mfma_f32_16x16x32_bf16 v[22:25], v[26:29], v[18:21], v[22:25]
	global_load_dwordx4 v[26:29], v[10:11], off offset:128
	global_load_dwordx4 v[46:49], v[10:11], off offset:192
	v_mfma_f32_16x16x32_bf16 v[14:17], v[34:37], v[18:21], v[14:17]
	global_load_dwordx4 v[18:21], v[8:9], off offset:128
	s_waitcnt vmcnt(0) lgkmcnt(0)
	v_mfma_f32_16x16x32_bf16 v[22:25], v[26:29], v[30:33], v[22:25]
	global_load_dwordx4 v[26:29], v[8:9], off offset:192
	v_mfma_f32_16x16x32_bf16 v[14:17], v[18:21], v[30:33], v[14:17]
	global_load_dwordx4 v[18:21], v[6:7], off offset:320
	global_load_dwordx4 v[30:33], v[6:7], off offset:384
	global_load_dwordx4 v[34:37], v[6:7], off offset:448
	v_mfma_f32_16x16x32_bf16 v[22:25], v[46:49], v[38:41], v[22:25]
	global_load_dwordx4 v[46:49], v[10:11], off offset:256
	global_load_dwordx4 v[50:53], v[10:11], off offset:320
	s_waitcnt vmcnt(0) lgkmcnt(0)
	v_mfma_f32_16x16x32_bf16 v[14:17], v[26:29], v[38:41], v[14:17]
	global_load_dwordx4 v[26:29], v[8:9], off offset:256
	global_load_dwordx4 v[38:41], v[8:9], off offset:320
	v_mfma_f32_16x16x32_bf16 v[22:25], v[46:49], v[42:45], v[22:25]
	v_mfma_f32_16x16x32_bf16 v[22:25], v[50:53], v[18:21], v[22:25]
	s_waitcnt vmcnt(0) lgkmcnt(0)
	v_mfma_f32_16x16x32_bf16 v[14:17], v[26:29], v[42:45], v[14:17]
	global_load_dwordx4 v[26:29], v[6:7], off offset:512
	global_load_dwordx4 v[42:45], v[6:7], off offset:576
	global_load_dwordx4 v[46:49], v[6:7], off offset:640
	global_load_dwordx4 v[50:53], v[10:11], off offset:384
	global_load_dwordx4 v[54:57], v[10:11], off offset:448
	v_mfma_f32_16x16x32_bf16 v[14:17], v[38:41], v[18:21], v[14:17]
	global_load_dwordx4 v[18:21], v[8:9], off offset:384
	global_load_dwordx4 v[38:41], v[8:9], off offset:448
	s_waitcnt vmcnt(0) lgkmcnt(0)
	v_mfma_f32_16x16x32_bf16 v[22:25], v[50:53], v[30:33], v[22:25]
	v_mfma_f32_16x16x32_bf16 v[14:17], v[18:21], v[30:33], v[14:17]
	global_load_dwordx4 v[18:21], v[6:7], off offset:704
	global_load_dwordx4 v[30:33], v[6:7], off offset:768
	global_load_dwordx4 v[50:53], v[6:7], off offset:832
	v_mfma_f32_16x16x32_bf16 v[22:25], v[54:57], v[34:37], v[22:25]
	global_load_dwordx4 v[54:57], v[10:11], off offset:512
	global_load_dwordx4 v[58:61], v[10:11], off offset:576
	v_mfma_f32_16x16x32_bf16 v[14:17], v[38:41], v[34:37], v[14:17]
	global_load_dwordx4 v[34:37], v[8:9], off offset:512
	global_load_dwordx4 v[38:41], v[8:9], off offset:576
	s_waitcnt vmcnt(0) lgkmcnt(0)
	v_mfma_f32_16x16x32_bf16 v[22:25], v[54:57], v[26:29], v[22:25]
	v_mfma_f32_16x16x32_bf16 v[14:17], v[34:37], v[26:29], v[14:17]
	global_load_dwordx4 v[26:29], v[6:7], off offset:896
	global_load_dwordx4 v[34:37], v[6:7], off offset:960
	global_load_dwordx4 v[54:57], v[6:7], off offset:1024
	v_mfma_f32_16x16x32_bf16 v[22:25], v[58:61], v[42:45], v[22:25]
	global_load_dwordx4 v[58:61], v[10:11], off offset:640
	global_load_dwordx4 v[62:65], v[10:11], off offset:704
	v_mfma_f32_16x16x32_bf16 v[14:17], v[38:41], v[42:45], v[14:17]
	global_load_dwordx4 v[38:41], v[8:9], off offset:640
	global_load_dwordx4 v[42:45], v[8:9], off offset:704
	s_waitcnt vmcnt(0) lgkmcnt(0)
	v_mfma_f32_16x16x32_bf16 v[22:25], v[58:61], v[46:49], v[22:25]
	v_mfma_f32_16x16x32_bf16 v[14:17], v[38:41], v[46:49], v[14:17]
	global_load_dwordx4 v[38:41], v[6:7], off offset:1088
	global_load_dwordx4 v[46:49], v[6:7], off offset:1152
	global_load_dwordx4 v[58:61], v[6:7], off offset:1216
	v_mfma_f32_16x16x32_bf16 v[22:25], v[62:65], v[18:21], v[22:25]
	global_load_dwordx4 v[62:65], v[10:11], off offset:768
	global_load_dwordx4 v[66:69], v[10:11], off offset:832
	v_mfma_f32_16x16x32_bf16 v[14:17], v[42:45], v[18:21], v[14:17]
	global_load_dwordx4 v[18:21], v[8:9], off offset:768
	global_load_dwordx4 v[42:45], v[8:9], off offset:832
	s_waitcnt vmcnt(0) lgkmcnt(0)
	v_mfma_f32_16x16x32_bf16 v[22:25], v[62:65], v[30:33], v[22:25]
	v_mfma_f32_16x16x32_bf16 v[14:17], v[18:21], v[30:33], v[14:17]
	global_load_dwordx4 v[18:21], v[6:7], off offset:1280
	global_load_dwordx4 v[30:33], v[6:7], off offset:1344
	global_load_dwordx4 v[62:65], v[6:7], off offset:1408
	v_mfma_f32_16x16x32_bf16 v[22:25], v[66:69], v[50:53], v[22:25]
	global_load_dwordx4 v[66:69], v[10:11], off offset:896
	global_load_dwordx4 v[70:73], v[10:11], off offset:960
	v_mfma_f32_16x16x32_bf16 v[14:17], v[42:45], v[50:53], v[14:17]
	global_load_dwordx4 v[42:45], v[8:9], off offset:896
	global_load_dwordx4 v[50:53], v[8:9], off offset:960
	s_waitcnt vmcnt(0) lgkmcnt(0)
	v_mfma_f32_16x16x32_bf16 v[22:25], v[66:69], v[26:29], v[22:25]
	v_mfma_f32_16x16x32_bf16 v[14:17], v[42:45], v[26:29], v[14:17]
	global_load_dwordx4 v[26:29], v[6:7], off offset:1472
	global_load_dwordx4 v[42:45], v[6:7], off offset:1536
	global_load_dwordx4 v[66:69], v[6:7], off offset:1600
	v_mfma_f32_16x16x32_bf16 v[22:25], v[70:73], v[34:37], v[22:25]
	global_load_dwordx4 v[70:73], v[10:11], off offset:1024
	global_load_dwordx4 v[74:77], v[10:11], off offset:1088
	v_mfma_f32_16x16x32_bf16 v[14:17], v[50:53], v[34:37], v[14:17]
	global_load_dwordx4 v[34:37], v[8:9], off offset:1024
	global_load_dwordx4 v[50:53], v[8:9], off offset:1088
	s_waitcnt vmcnt(0) lgkmcnt(0)
	v_mfma_f32_16x16x32_bf16 v[22:25], v[70:73], v[54:57], v[22:25]
	v_mfma_f32_16x16x32_bf16 v[14:17], v[34:37], v[54:57], v[14:17]
	global_load_dwordx4 v[34:37], v[6:7], off offset:1664
	global_load_dwordx4 v[54:57], v[6:7], off offset:1728
	global_load_dwordx4 v[70:73], v[6:7], off offset:1792
	v_mfma_f32_16x16x32_bf16 v[22:25], v[74:77], v[38:41], v[22:25]
	global_load_dwordx4 v[74:77], v[10:11], off offset:1152
	global_load_dwordx4 v[78:81], v[10:11], off offset:1216
	v_mfma_f32_16x16x32_bf16 v[14:17], v[50:53], v[38:41], v[14:17]
	global_load_dwordx4 v[38:41], v[8:9], off offset:1152
	global_load_dwordx4 v[50:53], v[8:9], off offset:1216
	s_waitcnt vmcnt(0) lgkmcnt(0)
	v_mfma_f32_16x16x32_bf16 v[22:25], v[74:77], v[46:49], v[22:25]
	v_mfma_f32_16x16x32_bf16 v[14:17], v[38:41], v[46:49], v[14:17]
	global_load_dwordx4 v[38:41], v[6:7], off offset:1856
	global_load_dwordx4 v[46:49], v[6:7], off offset:1920
	v_mfma_f32_16x16x32_bf16 v[22:25], v[78:81], v[58:61], v[22:25]
	global_load_dwordx4 v[74:77], v[10:11], off offset:1280
	global_load_dwordx4 v[78:81], v[10:11], off offset:1344
	v_mfma_f32_16x16x32_bf16 v[14:17], v[50:53], v[58:61], v[14:17]
	global_load_dwordx4 v[50:53], v[8:9], off offset:1280
	global_load_dwordx4 v[58:61], v[8:9], off offset:1344
	s_waitcnt vmcnt(0) lgkmcnt(0)
	v_mfma_f32_16x16x32_bf16 v[22:25], v[74:77], v[18:21], v[22:25]
	v_mfma_f32_16x16x32_bf16 v[14:17], v[50:53], v[18:21], v[14:17]
	global_load_dwordx4 v[18:21], v[10:11], off offset:1408
	global_load_dwordx4 v[50:53], v[10:11], off offset:1472
	v_mfma_f32_16x16x32_bf16 v[22:25], v[78:81], v[30:33], v[22:25]
	global_load_dwordx4 v[74:77], v[10:11], off offset:1536
	global_load_dwordx4 v[78:81], v[10:11], off offset:1600
	global_load_dwordx4 v[82:85], v[10:11], off offset:1664
	v_mfma_f32_16x16x32_bf16 v[14:17], v[58:61], v[30:33], v[14:17]
	global_load_dwordx4 v[30:33], v[8:9], off offset:1408
	s_waitcnt vmcnt(0) lgkmcnt(0)
	v_mfma_f32_16x16x32_bf16 v[18:21], v[18:21], v[62:65], v[22:25]
	s_nop 2
	global_load_dwordx4 v[22:25], v[8:9], off offset:1472
	v_mfma_f32_16x16x32_bf16 v[14:17], v[30:33], v[62:65], v[14:17]
	global_load_dwordx4 v[30:33], v[10:11], off offset:1728
	global_load_dwordx4 v[58:61], v[10:11], off offset:1792
	global_load_dwordx4 v[62:65], v[10:11], off offset:1856
	v_mfma_f32_16x16x32_bf16 v[18:21], v[50:53], v[26:29], v[18:21]
	global_load_dwordx4 v[50:53], v[10:11], off offset:1920
	global_load_dwordx4 v[86:89], v[10:11], off offset:1984
	s_nop 0
	global_load_dwordx2 v[90:91], v[90:91], off
	v_mfma_f32_16x16x32_bf16 v[18:21], v[74:77], v[42:45], v[18:21]
	v_mfma_f32_16x16x32_bf16 v[18:21], v[78:81], v[66:69], v[18:21]
	v_mfma_f32_16x16x32_bf16 v[18:21], v[82:85], v[34:37], v[18:21]
	s_waitcnt vmcnt(0) lgkmcnt(0)
	v_mfma_f32_16x16x32_bf16 v[14:17], v[22:25], v[26:29], v[14:17]
	global_load_dwordx4 v[22:25], v[8:9], off offset:1536
	global_load_dwordx4 v[26:29], v[8:9], off offset:1600
	v_mfma_f32_16x16x32_bf16 v[18:21], v[30:33], v[54:57], v[18:21]
	v_mfma_f32_16x16x32_bf16 v[18:21], v[58:61], v[70:73], v[18:21]
	v_mfma_f32_16x16x32_bf16 v[18:21], v[62:65], v[38:41], v[18:21]
	v_mfma_f32_16x16x32_bf16 v[18:21], v[50:53], v[46:49], v[18:21]
	s_waitcnt vmcnt(0) lgkmcnt(0)
	v_mfma_f32_16x16x32_bf16 v[14:17], v[22:25], v[42:45], v[14:17]
	global_load_dwordx4 v[22:25], v[8:9], off offset:1664
	global_load_dwordx4 v[42:45], v[8:9], off offset:1728
	v_mfma_f32_16x16x32_bf16 v[14:17], v[26:29], v[66:69], v[14:17]
	global_load_dwordx4 v[26:29], v[8:9], off offset:1792
	global_load_dwordx4 v[66:69], v[8:9], off offset:1856
	s_waitcnt vmcnt(0) lgkmcnt(0)
	v_mfma_f32_16x16x32_bf16 v[14:17], v[22:25], v[34:37], v[14:17]
	global_load_dwordx4 v[22:25], v[8:9], off offset:1920
	s_nop 0
	global_load_dwordx4 v[8:11], v[8:9], off offset:1984
	s_nop 0
	global_load_dwordx4 v[30:33], v[6:7], off offset:1984
	v_mfma_f32_16x16x32_bf16 v[14:17], v[42:45], v[54:57], v[14:17]
	v_mul_u32_u24_e32 v6, 0xa00, v12
	v_lshlrev_b32_e32 v194, 1, v6
	v_lshl_add_u64 v[6:7], s[0:1], 0, v[194:195]
	v_lshl_add_u64 v[6:7], s[8:9], 1, v[6:7]
	v_mfma_f32_16x16x32_bf16 v[14:17], v[26:29], v[70:73], v[14:17]
	v_lshl_add_u64 v[26:27], v[6:7], 0, v[4:5]
	v_ffbh_u32_e32 v5, v91
	v_min_u32_e32 v5, 32, v5
	v_lshlrev_b64 v[6:7], v5, v[90:91]
	v_min_u32_e32 v6, 1, v6
	v_or_b32_e32 v6, v7, v6
	v_cvt_f32_u32_e32 v6, v6
	v_sub_u32_e32 v5, 32, v5
	v_mfma_f32_16x16x32_bf16 v[14:17], v[66:69], v[38:41], v[14:17]
	v_ldexp_f32 v5, v6, v5
	v_fmamk_f32 v5, v5, 0x2e800000, v236
	v_mul_f32_e32 v6, 0x4b800000, v5
	v_cmp_gt_f32_e32 vcc, s20, v5
	s_waitcnt vmcnt(0) lgkmcnt(0)
	v_mfma_f32_16x16x32_bf16 v[14:17], v[22:25], v[46:49], v[14:17]
	v_cndmask_b32_e32 v5, v5, v6, vcc
	v_rsq_f32_e32 v5, v5
	v_mfma_f32_16x16x32_bf16 v[18:21], v[86:89], v[30:33], v[18:21]
	v_mul_f32_e32 v6, 0x45800000, v5
	v_cndmask_b32_e32 v12, v5, v6, vcc
	v_mfma_f32_16x16x32_bf16 v[6:9], v[8:11], v[30:33], v[14:17]
	s_nop 4
	v_mul_f32_e64 v10, v20, v12
	v_mul_f32_e64 v11, v21, v12
	v_pk_mul_f32 v[14:15], v[18:19], v[12:13] op_sel_hi:[1,0]
	v_pk_mul_f32 v[8:9], v[8:9], v[12:13] op_sel_hi:[1,0]
	v_pk_mul_f32 v[6:7], v[6:7], v[12:13] op_sel_hi:[1,0]
	v_cvt_pk_bf16_f32 v14, v14, v15
	v_cvt_pk_bf16_f32 v15, v10, v11
	v_cvt_pk_bf16_f32 v6, v6, v7
	v_cvt_pk_bf16_f32 v7, v8, v9
	global_store_dwordx2 v[26:27], v[14:15], off
	global_store_dwordx2 v[26:27], v[6:7], off offset:32
	s_cbranch_scc0 .LBB0_147

.LBB0_167:
	ds_read2_b32 v[24:25], v23 offset1:65
	ds_read2_b32 v[26:27], v23 offset0:130 offset1:195
	v_add_u32_e32 v17, 0x400, v23
	ds_read2_b32 v[28:29], v17 offset0:4 offset1:69
	ds_read2_b32 v[30:31], v17 offset0:134 offset1:199
	s_add_i32 s39, s39, s41
	s_waitcnt lgkmcnt(3)
	v_cvt_pk_bf16_f32 v24, v24, v25
	s_waitcnt lgkmcnt(2)
	v_cvt_pk_bf16_f32 v25, v26, v27
	s_waitcnt lgkmcnt(1)
	v_cvt_pk_bf16_f32 v26, v28, v29
	v_lshl_add_u64 v[28:29], s[0:1], 0, v[14:15]
	v_mov_b32_e32 v17, v195
	s_add_i32 s34, s34, s41
	s_add_i32 s35, s35, s36
	s_add_i32 s37, s37, s38
	s_waitcnt lgkmcnt(0)
	v_cvt_pk_bf16_f32 v27, v30, v31
	v_lshl_add_u64 v[28:29], v[28:29], 0, v[16:17]
	s_cmpk_lt_i32 s39, 0x5d8
	s_mov_b64 s[0:1], s[2:3]
	global_store_dwordx4 v[28:29], v[24:27], off
	s_waitcnt lgkmcnt(0)
	s_barrier
	s_cbranch_scc0 .LBB0_178

.LBB0_181:
	v_ashrrev_i32_e32 v23, 31, v2
	v_mov_b32_e32 v22, v2
	v_lshl_add_u64 v[22:23], v[22:23], 1, s[10:11]
	v_ashrrev_i32_e32 v17, 31, v3
	v_mov_b32_e32 v16, v3
	v_add_co_u32_e32 v22, vcc, s22, v22
	v_lshl_add_u64 v[16:17], v[16:17], 1, s[10:11]
	s_nop 0
	v_addc_co_u32_e32 v23, vcc, 0, v23, vcc
	v_ashrrev_i32_e32 v15, 31, v4
	v_mov_b32_e32 v14, v4
	v_add_co_u32_e32 v16, vcc, s22, v16
	v_lshl_add_u64 v[14:15], v[14:15], 1, s[10:11]
	s_nop 0
	v_addc_co_u32_e32 v17, vcc, 0, v17, vcc
	v_ashrrev_i32_e32 v13, 31, v5
	v_mov_b32_e32 v12, v5
	v_add_co_u32_e32 v14, vcc, s22, v14
	v_lshl_add_u64 v[12:13], v[12:13], 1, s[10:11]
	s_nop 0
	v_addc_co_u32_e32 v15, vcc, 0, v15, vcc
	v_add_co_u32_e32 v12, vcc, s22, v12
	v_add_u32_e32 v11, -4, v11
	s_nop 0
	v_addc_co_u32_e32 v13, vcc, 0, v13, vcc
	v_cmp_eq_u32_e32 vcc, 0, v11
	v_add_u32_e32 v5, s14, v5
	v_add_u32_e32 v4, s13, v4
	v_add_u32_e32 v3, s7, v3
	v_add_u32_e32 v2, s6, v2
	s_or_b64 s[4:5], vcc, s[4:5]
	global_store_short v[22:23], v195, off
	global_store_short v[16:17], v195, off
	global_store_short v[14:15], v195, off
	global_store_short v[12:13], v195, off
	s_andn2_b64 exec, exec, s[4:5]
	s_cbranch_execnz .LBB0_181
	s_or_b64 exec, exec, s[4:5]
	v_mad_u64_u32 v[2:3], s[4:5], v7, s12, v[0:1]
	v_cmp_ne_u32_e32 vcc, v6, v7
	s_orn2_b64 s[4:5], vcc, exec

.LBB0_185:
	v_add_u32_e32 v2, s12, v2
	v_cmp_lt_i32_e32 vcc, s6, v2
	global_store_short v[4:5], v195, off
	s_or_b64 s[4:5], vcc, s[4:5]
	v_lshl_add_u64 v[4:5], v[4:5], 0, s[2:3]
	s_andn2_b64 exec, exec, s[4:5]
	s_cbranch_execnz .LBB0_185

.LBB0_189:
	v_ashrrev_i32_e32 v12, 7, v4
	v_ashrrev_i32_e32 v14, 7, v5
	v_ashrrev_i32_e32 v13, 31, v12
	v_ashrrev_i32_e32 v15, 31, v14
	v_lshl_add_u64 v[12:13], v[12:13], 2, v[2:3]
	v_lshl_add_u64 v[14:15], v[14:15], 2, v[2:3]
	global_load_dword v1, v[12:13], off
	global_load_dword v7, v[14:15], off
	v_add_u32_e32 v6, -2, v6
	v_ashrrev_i32_e32 v15, 31, v4
	v_mov_b32_e32 v14, v4
	v_cmp_eq_u32_e64 s[0:1], 0, v6
	v_ashrrev_i32_e32 v13, 31, v5
	v_mov_b32_e32 v12, v5
	v_lshl_add_u64 v[14:15], v[14:15], 1, s[6:7]
	v_add_u32_e32 v5, s14, v5
	v_add_u32_e32 v4, s13, v4
	s_or_b64 s[10:11], s[0:1], s[10:11]
	v_lshl_add_u64 v[12:13], v[12:13], 1, s[6:7]
	s_waitcnt vmcnt(0)
	v_cvt_pk_bf16_f32 v1, v1, v7
	global_store_short v[14:15], v1, off
	global_store_short_d16_hi v[12:13], v1, off
	s_andn2_b64 exec, exec, s[10:11]
	s_cbranch_execnz .LBB0_189
	s_or_b64 exec, exec, s[10:11]
	v_mad_u64_u32 v[4:5], s[0:1], v11, s12, v[0:1]
	v_cmp_ne_u32_e64 s[0:1], v10, v11
	s_and_b64 s[6:7], s[0:1], exec

.LBB0_195:
	v_ashrrev_i32_e32 v10, 7, v4
	v_ashrrev_i32_e32 v11, 31, v10
	v_lshl_add_u64 v[10:11], v[10:11], 2, v[2:3]
	global_load_dword v1, v[10:11], off
	v_add_u32_e32 v4, s12, v4
	v_cmp_lt_i32_e32 vcc, s62, v4
	s_or_b64 s[4:5], vcc, s[4:5]
	s_waitcnt vmcnt(0)
	v_cvt_pk_bf16_f32 v1, v1, s0
	global_store_short v[6:7], v1, off
	v_lshl_add_u64 v[6:7], v[6:7], 0, s[0:1]
	s_andn2_b64 exec, exec, s[4:5]
	s_cbranch_execnz .LBB0_195

.LBB0_198:
	s_or_b64 exec, exec, s[10:11]
	v_add_u32_e32 v0, s12, v0
	s_mov_b32 s10, 0xffff
	v_cmp_lt_i32_e32 vcc, s10, v0
	global_store_short v[2:3], v1, off
	v_lshl_add_u64 v[2:3], v[2:3], 0, s[2:3]
	s_or_b64 s[6:7], vcc, s[6:7]
	v_lshl_add_u64 v[4:5], v[4:5], 0, s[4:5]
	s_andn2_b64 exec, exec, s[6:7]
	s_cbranch_execz .LBB0_201

.LBB0_221:
	ds_read2_b32 v[24:25], v22 offset1:65
	ds_read2_b32 v[26:27], v22 offset0:130 offset1:195
	v_add_u32_e32 v17, 0x400, v22
	ds_read2_b32 v[28:29], v17 offset0:4 offset1:69
	ds_read2_b32 v[30:31], v17 offset0:134 offset1:199
	s_add_i32 s39, s39, s40
	s_waitcnt lgkmcnt(3)
	v_cvt_pk_bf16_f32 v24, v24, v25
	s_waitcnt lgkmcnt(2)
	v_cvt_pk_bf16_f32 v25, v26, v27
	s_waitcnt lgkmcnt(1)
	v_cvt_pk_bf16_f32 v26, v28, v29
	v_lshl_add_u64 v[28:29], s[0:1], 0, v[14:15]
	v_mov_b32_e32 v17, v195
	s_add_i32 s34, s34, s40
	s_add_i32 s35, s35, s36
	s_add_i32 s37, s37, s38
	s_waitcnt lgkmcnt(0)
	v_cvt_pk_bf16_f32 v27, v30, v31
	v_lshl_add_u64 v[28:29], v[28:29], 0, v[16:17]
	s_cmpk_lt_i32 s39, 0x5d8
	s_mov_b64 s[0:1], s[2:3]
	global_store_dwordx4 v[28:29], v[24:27], off
	s_waitcnt lgkmcnt(0)
	s_barrier
	s_cbranch_scc0 .LBB0_232

.LBB0_235:
	v_ashrrev_i32_e32 v21, 31, v2
	v_mov_b32_e32 v20, v2
	v_lshl_add_u64 v[20:21], v[20:21], 1, s[10:11]
	v_ashrrev_i32_e32 v17, 31, v3
	v_mov_b32_e32 v16, v3
	v_add_co_u32_e32 v20, vcc, s22, v20
	v_lshl_add_u64 v[16:17], v[16:17], 1, s[10:11]
	s_nop 0
	v_addc_co_u32_e32 v21, vcc, 0, v21, vcc
	v_ashrrev_i32_e32 v15, 31, v4
	v_mov_b32_e32 v14, v4
	v_add_co_u32_e32 v16, vcc, s22, v16
	v_lshl_add_u64 v[14:15], v[14:15], 1, s[10:11]
	s_nop 0
	v_addc_co_u32_e32 v17, vcc, 0, v17, vcc
	v_ashrrev_i32_e32 v13, 31, v5
	v_mov_b32_e32 v12, v5
	v_add_co_u32_e32 v14, vcc, s22, v14
	v_lshl_add_u64 v[12:13], v[12:13], 1, s[10:11]
	s_nop 0
	v_addc_co_u32_e32 v15, vcc, 0, v15, vcc
	v_add_co_u32_e32 v12, vcc, s22, v12
	v_add_u32_e32 v11, -4, v11
	s_nop 0
	v_addc_co_u32_e32 v13, vcc, 0, v13, vcc
	v_cmp_eq_u32_e32 vcc, 0, v11
	v_add_u32_e32 v5, s14, v5
	v_add_u32_e32 v4, s13, v4
	v_add_u32_e32 v3, s7, v3
	v_add_u32_e32 v2, s6, v2
	s_or_b64 s[4:5], vcc, s[4:5]
	global_store_short v[20:21], v195, off
	global_store_short v[16:17], v195, off
	global_store_short v[14:15], v195, off
	global_store_short v[12:13], v195, off
	s_andn2_b64 exec, exec, s[4:5]
	s_cbranch_execnz .LBB0_235
	s_or_b64 exec, exec, s[4:5]
	v_mad_u64_u32 v[2:3], s[4:5], v7, s12, v[0:1]
	v_cmp_ne_u32_e32 vcc, v6, v7
	s_orn2_b64 s[4:5], vcc, exec

.LBB0_243:
	v_ashrrev_i32_e32 v14, 7, v4
	v_ashrrev_i32_e32 v16, 7, v5
	v_ashrrev_i32_e32 v15, 31, v14
	v_ashrrev_i32_e32 v17, 31, v16
	v_lshl_add_u64 v[14:15], v[14:15], 2, v[2:3]
	v_lshl_add_u64 v[16:17], v[16:17], 2, v[2:3]
	global_load_dword v1, v[14:15], off
	global_load_dword v7, v[16:17], off
	v_add_u32_e32 v6, -2, v6
	v_ashrrev_i32_e32 v17, 31, v4
	v_mov_b32_e32 v16, v4
	v_cmp_eq_u32_e64 s[0:1], 0, v6
	v_ashrrev_i32_e32 v15, 31, v5
	v_mov_b32_e32 v14, v5
	v_lshl_add_u64 v[16:17], v[16:17], 1, s[6:7]
	v_add_u32_e32 v5, s14, v5
	v_add_u32_e32 v4, s13, v4
	s_or_b64 s[10:11], s[0:1], s[10:11]
	v_lshl_add_u64 v[14:15], v[14:15], 1, s[6:7]
	s_waitcnt vmcnt(0)
	v_cvt_pk_bf16_f32 v1, v1, v7
	global_store_short v[16:17], v1, off
	global_store_short_d16_hi v[14:15], v1, off
	s_andn2_b64 exec, exec, s[10:11]
	s_cbranch_execnz .LBB0_243
	s_or_b64 exec, exec, s[10:11]
	v_mad_u64_u32 v[4:5], s[0:1], v12, s12, v[0:1]
	v_cmp_ne_u32_e64 s[0:1], v10, v12
	s_and_b64 s[6:7], s[0:1], exec

.LBB0_249:
	v_ashrrev_i32_e32 v12, 7, v4
	v_ashrrev_i32_e32 v13, 31, v12
	v_lshl_add_u64 v[12:13], v[12:13], 2, v[2:3]
	global_load_dword v1, v[12:13], off
	v_add_u32_e32 v4, s12, v4
	v_cmp_lt_i32_e32 vcc, s62, v4
	s_or_b64 s[4:5], vcc, s[4:5]
	s_waitcnt vmcnt(0)
	v_cvt_pk_bf16_f32 v1, v1, s0
	global_store_short v[6:7], v1, off
	v_lshl_add_u64 v[6:7], v[6:7], 0, s[0:1]
	s_andn2_b64 exec, exec, s[4:5]
	s_cbranch_execnz .LBB0_249

.LBB0_252:
	s_or_b64 exec, exec, s[8:9]
	v_add_u32_e32 v0, s12, v0
	s_mov_b32 s8, 0xffff
	v_cmp_lt_i32_e32 vcc, s8, v0
	global_store_short v[2:3], v1, off
	v_lshl_add_u64 v[2:3], v[2:3], 0, s[2:3]
	s_or_b64 s[6:7], vcc, s[6:7]
	v_lshl_add_u64 v[4:5], v[4:5], 0, s[4:5]
	s_andn2_b64 exec, exec, s[6:7]
	s_cbranch_execz .LBB0_255

.LBB0_321:
	v_ashrrev_i32_e32 v21, 3, v53
	v_and_b32_e32 v25, -8, v21
	v_and_b32_e32 v0, 0x3fc0, v53
	v_add_u32_e32 v1, -2, v25
	v_cmp_eq_u32_e32 vcc, 0, v0
	v_and_b32_e32 v4, 0xfc, v52
	v_mov_b64_e32 v[16:17], s[12:13]
	v_cndmask_b32_e32 v2, v1, v25, vcc
	v_mad_i64_i32 v[0:1], s[2:3], v2, s86, v[16:17]
	v_lshlrev_b32_e32 v194, 1, v4
	v_lshl_add_u64 v[0:1], v[0:1], 0, v[194:195]
	global_load_dwordx2 v[44:45], v[0:1], off offset:1536
	global_load_dwordx2 v[56:57], v[0:1], off offset:2560
	v_or_b32_e32 v0, 1, v2
	v_mad_i64_i32 v[0:1], s[2:3], v0, s86, v[16:17]
	v_lshl_add_u64 v[0:1], v[0:1], 0, v[194:195]
	global_load_dwordx2 v[58:59], v[0:1], off offset:1536
	global_load_dwordx2 v[60:61], v[0:1], off offset:2560
	v_mad_i64_i32 v[0:1], s[2:3], v25, s86, v[16:17]
	v_lshl_add_u64 v[0:1], v[0:1], 0, v[194:195]
	global_load_dwordx2 v[62:63], v[0:1], off offset:1536
	v_or_b32_e32 v55, 1, v25
	v_mad_i64_i32 v[2:3], s[2:3], v55, s86, v[16:17]
	v_lshlrev_b32_e32 v24, 2, v4
	v_lshl_add_u64 v[18:19], v[2:3], 0, v[194:195]
	global_load_dwordx2 v[64:65], v[0:1], off offset:2560
	global_load_dwordx2 v[46:47], v[18:19], off offset:1536
	global_load_dwordx2 v[66:67], v[0:1], off offset:2048
	s_nop 0
	global_load_dwordx4 v[0:3], v24, s[8:9]
	global_load_dwordx4 v[4:7], v24, s[0:1]
	global_load_dwordx4 v[8:11], v24, s[0:1] offset:1024
	global_load_dwordx4 v[12:15], v24, s[0:1] offset:2048
	v_ashrrev_i32_e32 v20, 14, v53
	v_or_b32_e32 v54, 7, v21
	v_ashrrev_i32_e32 v21, 31, v20
	v_or_b32_e32 v71, 2, v25
	v_lshl_add_u64 v[26:27], v[20:21], 1, s[42:43]
	v_mad_i64_i32 v[20:21], s[2:3], v71, s86, v[16:17]
	v_lshl_add_u64 v[20:21], v[20:21], 0, v[194:195]
	global_load_dwordx2 v[72:73], v[18:19], off offset:2560
	global_load_dwordx2 v[74:75], v[20:21], off offset:1536
	global_load_dwordx2 v[76:77], v[20:21], off offset:2048
	global_load_dwordx2 v[78:79], v[18:19], off offset:2048
	v_or_b32_e32 v94, 3, v25
	v_or_b32_e32 v95, 4, v25
	v_or_b32_e32 v96, 5, v25
	v_or_b32_e32 v97, 6, v25
	v_mad_i64_i32 v[22:23], s[2:3], v54, s86, v[16:17]
	v_mad_i64_i32 v[28:29], s[2:3], v94, s86, v[16:17]
	v_mad_i64_i32 v[30:31], s[2:3], v95, s86, v[16:17]
	v_mad_i64_i32 v[32:33], s[2:3], v96, s86, v[16:17]
	v_mad_i64_i32 v[16:17], s[2:3], v97, s86, v[16:17]
	v_lshl_add_u64 v[68:69], v[22:23], 0, v[194:195]
	v_lshl_add_u64 v[22:23], v[28:29], 0, v[194:195]
	v_lshl_add_u64 v[28:29], v[30:31], 0, v[194:195]
	v_lshl_add_u64 v[30:31], v[32:33], 0, v[194:195]
	v_lshl_add_u64 v[32:33], v[16:17], 0, v[194:195]
	global_load_dwordx2 v[80:81], v[20:21], off offset:2560
	global_load_dwordx2 v[82:83], v[22:23], off offset:1536
	global_load_dwordx2 v[84:85], v[22:23], off offset:2560
	global_load_dwordx2 v[48:49], v[22:23], off offset:2048
	global_load_dwordx2 v[42:43], v[28:29], off offset:1536
	global_load_dwordx2 v[40:41], v[28:29], off offset:2560
	global_load_dwordx2 v[38:39], v[30:31], off offset:1536
	global_load_dwordx2 v[16:17], v[28:29], off offset:2048
	global_load_dwordx2 v[36:37], v[30:31], off offset:2560
	global_load_dwordx2 v[18:19], v[32:33], off offset:1536
	global_load_dwordx2 v[20:21], v[32:33], off offset:2048
	global_load_dwordx2 v[34:35], v[30:31], off offset:2048
	global_load_dwordx2 v[22:23], v[68:69], off offset:2560
	s_nop 0
	global_load_dwordx2 v[32:33], v[32:33], off offset:2560
	s_nop 0
	global_load_dwordx2 v[30:31], v[68:69], off offset:1536
	global_load_dwordx2 v[28:29], v[68:69], off offset:2048
	v_cndmask_b32_e64 v70, 1.0, 0, vcc
	s_waitcnt vmcnt(0) lgkmcnt(0)
	v_lshlrev_b32_e32 v68, 16, v44
	v_and_b32_e32 v69, 0xffff0000, v44
	v_lshlrev_b32_e32 v44, 16, v45
	v_and_b32_e32 v45, 0xffff0000, v45
	v_lshlrev_b32_e32 v86, 16, v56
	v_and_b32_e32 v87, 0xffff0000, v56
	v_lshlrev_b32_e32 v56, 16, v57
	v_and_b32_e32 v57, 0xffff0000, v57
	v_pk_mul_f32 v[44:45], v[70:71], v[44:45] op_sel_hi:[0,1]
	v_pk_mul_f32 v[68:69], v[70:71], v[68:69] op_sel_hi:[0,1]
	v_pk_mul_f32 v[44:45], v[44:45], v[56:57]
	v_lshlrev_b32_e32 v56, 16, v59
	v_and_b32_e32 v57, 0xffff0000, v59
	v_pk_mul_f32 v[68:69], v[68:69], v[86:87]
	v_lshlrev_b32_e32 v86, 16, v58
	v_and_b32_e32 v87, 0xffff0000, v58
	v_lshlrev_b32_e32 v58, 16, v61
	v_and_b32_e32 v59, 0xffff0000, v61
	v_pk_mul_f32 v[56:57], v[70:71], v[56:57] op_sel_hi:[0,1]
	v_lshlrev_b32_e32 v88, 16, v60
	v_and_b32_e32 v89, 0xffff0000, v60
	v_pk_mul_f32 v[56:57], v[56:57], v[58:59]
	v_lshlrev_b32_e32 v58, 16, v63
	v_and_b32_e32 v59, 0xffff0000, v63
	v_lshlrev_b32_e32 v60, 16, v65
	v_and_b32_e32 v61, 0xffff0000, v65
	v_pk_fma_f32 v[44:45], v[6:7], v[44:45], v[2:3]
	v_pk_mul_f32 v[86:87], v[70:71], v[86:87] op_sel_hi:[0,1]
	v_pk_mul_f32 v[58:59], v[58:59], v[60:61]
	v_pk_fma_f32 v[44:45], v[10:11], v[56:57], v[44:45]
	v_pk_mul_f32 v[86:87], v[86:87], v[88:89]
	v_lshlrev_b32_e32 v88, 16, v62
	v_and_b32_e32 v89, 0xffff0000, v62
	v_lshlrev_b32_e32 v62, 16, v67
	v_and_b32_e32 v63, 0xffff0000, v67
	v_pk_fma_f32 v[44:45], v[14:15], v[58:59], v[44:45]
	v_lshlrev_b32_e32 v90, 16, v64
	v_and_b32_e32 v91, 0xffff0000, v64
	v_pk_fma_f32 v[68:69], v[4:5], v[68:69], v[0:1]
	v_pk_mul_f32 v[60:61], v[44:45], v[62:63]
	v_mov_b64_e32 v[44:45], s[4:5]
	v_pk_mul_f32 v[88:89], v[88:89], v[90:91]
	v_pk_fma_f32 v[68:69], v[8:9], v[86:87], v[68:69]
	v_mad_i64_i32 v[62:63], s[2:3], v25, s86, v[44:45]
	v_lshlrev_b32_e32 v92, 16, v66
	v_and_b32_e32 v93, 0xffff0000, v66
	v_pk_fma_f32 v[68:69], v[12:13], v[88:89], v[68:69]
	v_cvt_pk_bf16_f32 v65, v60, v61
	v_lshl_add_u64 v[60:61], v[62:63], 0, v[194:195]
	v_pk_mul_f32 v[68:69], v[68:69], v[92:93]
	v_add_co_u32_e32 v60, vcc, s21, v60
	v_cvt_pk_bf16_f32 v64, v68, v69
	s_nop 0
	v_addc_co_u32_e32 v61, vcc, 0, v61, vcc
	global_store_dwordx2 v[60:61], v[64:65], off offset:2048
	v_lshlrev_b32_e32 v60, 16, v46
	v_and_b32_e32 v61, 0xffff0000, v46
	v_lshlrev_b32_e32 v62, 16, v72
	v_and_b32_e32 v63, 0xffff0000, v72
	v_pk_mul_f32 v[60:61], v[60:61], v[62:63]
	v_pk_fma_f32 v[62:63], v[4:5], v[86:87], v[0:1]
	v_lshlrev_b32_e32 v64, 16, v78
	v_pk_fma_f32 v[62:63], v[8:9], v[88:89], v[62:63]
	v_and_b32_e32 v65, 0xffff0000, v78
	v_pk_fma_f32 v[62:63], v[12:13], v[60:61], v[62:63]
	v_lshlrev_b32_e32 v46, 16, v47
	v_pk_mul_f32 v[62:63], v[62:63], v[64:65]
	v_and_b32_e32 v47, 0xffff0000, v47
	v_lshlrev_b32_e32 v64, 16, v73
	v_and_b32_e32 v65, 0xffff0000, v73
	v_pk_fma_f32 v[56:57], v[6:7], v[56:57], v[2:3]
	v_pk_mul_f32 v[46:47], v[46:47], v[64:65]
	v_pk_fma_f32 v[56:57], v[10:11], v[58:59], v[56:57]
	v_lshlrev_b32_e32 v66, 16, v79
	v_and_b32_e32 v67, 0xffff0000, v79
	v_pk_fma_f32 v[56:57], v[14:15], v[46:47], v[56:57]
	v_mad_i64_i32 v[64:65], s[2:3], v55, s86, v[44:45]
	v_pk_mul_f32 v[56:57], v[56:57], v[66:67]
	v_cvt_pk_bf16_f32 v62, v62, v63
	v_cvt_pk_bf16_f32 v63, v56, v57
	v_lshl_add_u64 v[56:57], v[64:65], 0, v[194:195]
	v_add_co_u32_e32 v56, vcc, s21, v56
	v_lshlrev_b32_e32 v64, 16, v76
	s_nop 0
	v_addc_co_u32_e32 v57, vcc, 0, v57, vcc
	global_store_dwordx2 v[56:57], v[62:63], off offset:2048
	v_lshlrev_b32_e32 v56, 16, v74
	v_and_b32_e32 v57, 0xffff0000, v74
	v_lshlrev_b32_e32 v62, 16, v80
	v_and_b32_e32 v63, 0xffff0000, v80
	v_pk_mul_f32 v[56:57], v[56:57], v[62:63]
	v_pk_fma_f32 v[62:63], v[4:5], v[88:89], v[0:1]
	v_and_b32_e32 v65, 0xffff0000, v76
	v_pk_fma_f32 v[62:63], v[8:9], v[60:61], v[62:63]
	v_lshlrev_b32_e32 v66, 16, v81
	v_pk_fma_f32 v[62:63], v[12:13], v[56:57], v[62:63]
	v_and_b32_e32 v67, 0xffff0000, v81
	v_pk_mul_f32 v[62:63], v[62:63], v[64:65]
	v_lshlrev_b32_e32 v64, 16, v75
	v_and_b32_e32 v65, 0xffff0000, v75
	v_pk_fma_f32 v[58:59], v[6:7], v[58:59], v[2:3]
	v_pk_mul_f32 v[64:65], v[64:65], v[66:67]
	v_pk_fma_f32 v[58:59], v[10:11], v[46:47], v[58:59]
	v_lshlrev_b32_e32 v68, 16, v77
	v_and_b32_e32 v69, 0xffff0000, v77
	v_pk_fma_f32 v[58:59], v[14:15], v[64:65], v[58:59]
	v_mad_i64_i32 v[66:67], s[2:3], v71, s86, v[44:45]
	v_pk_mul_f32 v[58:59], v[58:59], v[68:69]
	v_cvt_pk_bf16_f32 v62, v62, v63
	v_cvt_pk_bf16_f32 v63, v58, v59
	v_lshl_add_u64 v[58:59], v[66:67], 0, v[194:195]
	v_add_co_u32_e32 v58, vcc, s21, v58
	v_pk_fma_f32 v[60:61], v[4:5], v[60:61], v[0:1]
	s_nop 0
	v_addc_co_u32_e32 v59, vcc, 0, v59, vcc
	global_store_dwordx2 v[58:59], v[62:63], off offset:2048
	v_lshlrev_b32_e32 v58, 16, v82
	v_and_b32_e32 v59, 0xffff0000, v82
	v_lshlrev_b32_e32 v62, 16, v84
	v_and_b32_e32 v63, 0xffff0000, v84
	v_pk_mul_f32 v[58:59], v[58:59], v[62:63]
	v_pk_fma_f32 v[60:61], v[8:9], v[56:57], v[60:61]
	v_lshlrev_b32_e32 v66, 16, v48
	v_and_b32_e32 v67, 0xffff0000, v48
	v_pk_fma_f32 v[60:61], v[12:13], v[58:59], v[60:61]
	v_lshlrev_b32_e32 v62, 16, v83
	v_pk_mul_f32 v[60:61], v[60:61], v[66:67]
	v_and_b32_e32 v63, 0xffff0000, v83
	v_lshlrev_b32_e32 v66, 16, v85
	v_and_b32_e32 v67, 0xffff0000, v85
	v_pk_fma_f32 v[46:47], v[6:7], v[46:47], v[2:3]
	v_pk_mul_f32 v[62:63], v[62:63], v[66:67]
	v_pk_fma_f32 v[46:47], v[10:11], v[64:65], v[46:47]
	v_lshlrev_b32_e32 v48, 16, v49
	v_and_b32_e32 v49, 0xffff0000, v49
	v_pk_fma_f32 v[46:47], v[14:15], v[62:63], v[46:47]
	v_cvt_pk_bf16_f32 v60, v60, v61
	v_pk_mul_f32 v[46:47], v[46:47], v[48:49]
	v_mad_i64_i32 v[48:49], s[2:3], v94, s86, v[44:45]
	v_cvt_pk_bf16_f32 v61, v46, v47
	v_lshl_add_u64 v[46:47], v[48:49], 0, v[194:195]
	v_add_co_u32_e32 v46, vcc, s21, v46
	v_lshlrev_b32_e32 v48, 16, v40
	s_nop 0
	v_addc_co_u32_e32 v47, vcc, 0, v47, vcc
	global_store_dwordx2 v[46:47], v[60:61], off offset:2048
	v_lshlrev_b32_e32 v46, 16, v42
	v_and_b32_e32 v47, 0xffff0000, v42
	v_and_b32_e32 v49, 0xffff0000, v40
	v_lshlrev_b32_e32 v42, 16, v43
	v_and_b32_e32 v43, 0xffff0000, v43
	v_lshlrev_b32_e32 v40, 16, v41
	v_and_b32_e32 v41, 0xffff0000, v41
	v_pk_mul_f32 v[46:47], v[46:47], v[48:49]
	v_pk_fma_f32 v[48:49], v[4:5], v[56:57], v[0:1]
	v_pk_mul_f32 v[42:43], v[42:43], v[40:41]
	v_pk_fma_f32 v[40:41], v[6:7], v[64:65], v[2:3]
	v_pk_fma_f32 v[48:49], v[8:9], v[58:59], v[48:49]
	v_pk_fma_f32 v[40:41], v[10:11], v[62:63], v[40:41]
	v_lshlrev_b32_e32 v60, 16, v16
	v_and_b32_e32 v61, 0xffff0000, v16
	v_pk_fma_f32 v[48:49], v[12:13], v[46:47], v[48:49]
	v_lshlrev_b32_e32 v16, 16, v17
	v_and_b32_e32 v17, 0xffff0000, v17
	v_pk_fma_f32 v[40:41], v[14:15], v[42:43], v[40:41]
	v_pk_mul_f32 v[48:49], v[48:49], v[60:61]
	v_pk_mul_f32 v[16:17], v[40:41], v[16:17]
	v_mad_i64_i32 v[40:41], s[2:3], v95, s86, v[44:45]
	v_cvt_pk_bf16_f32 v48, v48, v49
	v_cvt_pk_bf16_f32 v49, v16, v17
	v_lshl_add_u64 v[16:17], v[40:41], 0, v[194:195]
	v_add_co_u32_e32 v16, vcc, s21, v16
	v_lshlrev_b32_e32 v40, 16, v36
	s_nop 0
	v_addc_co_u32_e32 v17, vcc, 0, v17, vcc
	global_store_dwordx2 v[16:17], v[48:49], off offset:2048
	v_mad_i64_i32 v[16:17], s[2:3], v96, s86, v[44:45]
	v_lshl_add_u64 v[48:49], v[16:17], 0, v[194:195]
	v_lshlrev_b32_e32 v16, 16, v38
	v_and_b32_e32 v17, 0xffff0000, v38
	v_and_b32_e32 v41, 0xffff0000, v36
	v_pk_fma_f32 v[56:57], v[4:5], v[58:59], v[0:1]
	v_pk_mul_f32 v[40:41], v[16:17], v[40:41]
	v_pk_fma_f32 v[56:57], v[8:9], v[46:47], v[56:57]
	v_lshlrev_b32_e32 v16, 16, v34
	v_and_b32_e32 v17, 0xffff0000, v34
	v_pk_fma_f32 v[56:57], v[12:13], v[40:41], v[56:57]
	v_pk_fma_f32 v[46:47], v[4:5], v[46:47], v[0:1]
	v_pk_mul_f32 v[16:17], v[56:57], v[16:17]
	v_lshlrev_b32_e32 v56, 16, v32
	v_cvt_pk_bf16_f32 v34, v16, v17
	v_lshlrev_b32_e32 v16, 16, v18
	v_and_b32_e32 v17, 0xffff0000, v18
	v_and_b32_e32 v57, 0xffff0000, v32
	v_pk_mul_f32 v[16:17], v[16:17], v[56:57]
	v_pk_fma_f32 v[46:47], v[8:9], v[40:41], v[46:47]
	v_lshlrev_b32_e32 v56, 16, v20
	v_and_b32_e32 v57, 0xffff0000, v20
	v_pk_fma_f32 v[46:47], v[12:13], v[16:17], v[46:47]
	v_lshlrev_b32_e32 v38, 16, v39
	v_pk_mul_f32 v[46:47], v[46:47], v[56:57]
	v_and_b32_e32 v39, 0xffff0000, v39
	v_lshlrev_b32_e32 v36, 16, v37
	v_and_b32_e32 v37, 0xffff0000, v37
	v_pk_fma_f32 v[56:57], v[6:7], v[62:63], v[2:3]
	v_pk_mul_f32 v[36:37], v[38:39], v[36:37]
	v_pk_fma_f32 v[56:57], v[10:11], v[42:43], v[56:57]
	v_lshlrev_b32_e32 v18, 16, v19
	v_and_b32_e32 v19, 0xffff0000, v19
	v_lshlrev_b32_e32 v32, 16, v33
	v_and_b32_e32 v33, 0xffff0000, v33
	v_lshlrev_b32_e32 v38, 16, v35
	v_and_b32_e32 v39, 0xffff0000, v35
	v_pk_fma_f32 v[56:57], v[14:15], v[36:37], v[56:57]
	v_pk_mul_f32 v[18:19], v[18:19], v[32:33]
	v_pk_fma_f32 v[32:33], v[6:7], v[42:43], v[2:3]
	v_pk_mul_f32 v[38:39], v[56:57], v[38:39]
	v_pk_fma_f32 v[32:33], v[10:11], v[36:37], v[32:33]
	v_cvt_pk_bf16_f32 v35, v38, v39
	v_add_co_u32_e32 v38, vcc, s21, v48
	v_lshlrev_b32_e32 v20, 16, v21
	v_and_b32_e32 v21, 0xffff0000, v21
	v_pk_fma_f32 v[32:33], v[14:15], v[18:19], v[32:33]
	v_addc_co_u32_e32 v39, vcc, 0, v49, vcc
	v_pk_mul_f32 v[20:21], v[32:33], v[20:21]
	v_mad_i64_i32 v[32:33], s[2:3], v97, s86, v[44:45]
	global_store_dwordx2 v[38:39], v[34:35], off offset:2048
	v_cvt_pk_bf16_f32 v35, v20, v21
	v_lshl_add_u64 v[20:21], v[32:33], 0, v[194:195]
	v_add_co_u32_e32 v20, vcc, 0x2040000, v20
	v_cvt_pk_bf16_f32 v34, v46, v47
	s_nop 0
	v_addc_co_u32_e32 v21, vcc, 0, v21, vcc
	global_store_dwordx2 v[20:21], v[34:35], off offset:2048
	v_bitop3_b32 v20, v25, s22, 6 bitop3:0xc8
	v_cmp_eq_u32_e32 vcc, s22, v20
	s_and_saveexec_b64 s[2:3], vcc
	s_cbranch_execz .LBB0_323
	v_lshlrev_b64 v[20:21], 10, v[26:27]
	v_lshl_add_u64 v[20:21], s[16:17], 0, v[20:21]
	v_mov_b32_e32 v25, v195
	v_lshl_add_u64 v[20:21], v[20:21], 0, v[24:25]
	global_store_dwordx4 v[20:21], v[16:19], off
.LBB0_323:
	s_or_b64 exec, exec, s[2:3]
	v_pk_fma_f32 v[0:1], v[4:5], v[40:41], v[0:1]
	v_lshlrev_b32_e32 v20, 16, v30
	v_and_b32_e32 v21, 0xffff0000, v30
	v_lshlrev_b32_e32 v34, 16, v22
	v_and_b32_e32 v35, 0xffff0000, v22
	v_pk_fma_f32 v[0:1], v[8:9], v[16:17], v[0:1]
	v_lshlrev_b32_e32 v4, 16, v31
	v_and_b32_e32 v5, 0xffff0000, v31
	v_lshlrev_b32_e32 v8, 16, v23
	v_and_b32_e32 v9, 0xffff0000, v23
	v_pk_fma_f32 v[2:3], v[6:7], v[36:37], v[2:3]
	v_pk_mul_f32 v[20:21], v[20:21], v[34:35]
	v_pk_mul_f32 v[22:23], v[4:5], v[8:9]
	v_pk_fma_f32 v[2:3], v[10:11], v[18:19], v[2:3]
	v_mad_i64_i32 v[32:33], s[2:3], v54, s86, 0
	v_lshlrev_b32_e32 v34, 16, v28
	v_and_b32_e32 v35, 0xffff0000, v28
	v_pk_fma_f32 v[0:1], v[12:13], v[20:21], v[0:1]
	v_lshlrev_b32_e32 v4, 16, v29
	v_and_b32_e32 v5, 0xffff0000, v29
	v_pk_fma_f32 v[2:3], v[14:15], v[22:23], v[2:3]
	v_pk_mul_f32 v[0:1], v[0:1], v[34:35]
	v_pk_mul_f32 v[2:3], v[2:3], v[4:5]
	v_lshl_add_u64 v[4:5], s[4:5], 0, v[32:33]
	v_cvt_pk_bf16_f32 v0, v0, v1
	v_cvt_pk_bf16_f32 v1, v2, v3
	v_lshl_add_u64 v[2:3], v[4:5], 0, v[194:195]
	v_add_co_u32_e32 v2, vcc, 0x2040000, v2
	s_movk_i32 s2, 0x7fd
	s_nop 0
	v_addc_co_u32_e32 v3, vcc, 0, v3, vcc
	global_store_dwordx2 v[2:3], v[0:1], off offset:2048
	v_and_b32_e32 v0, 0x7ff, v54
	v_cmp_lt_u32_e32 vcc, s2, v0
	s_and_saveexec_b64 s[2:3], vcc
	s_cbranch_execz .LBB0_320
	v_add_u32_e32 v194, 0xfffff802, v0
	v_lshl_add_u64 v[0:1], v[26:27], 0, v[194:195]
	v_lshlrev_b64 v[0:1], 10, v[0:1]
	v_lshl_add_u64 v[0:1], s[16:17], 0, v[0:1]
	v_mov_b32_e32 v25, v195
	v_lshl_add_u64 v[0:1], v[0:1], 0, v[24:25]
	global_store_dwordx4 v[0:1], v[20:23], off
	s_branch .LBB0_320

.LBB0_327:
	v_ashrrev_i32_e32 v16, 6, v50
	v_ashrrev_i32_e32 v17, 31, v16
	v_add_u32_e32 v2, 0x4000, v16
	v_lshlrev_b64 v[16:17], 9, v[16:17]
	v_lshl_add_u64 v[16:17], v[16:17], 0, s[42:43]
	v_and_b32_e32 v26, 0xfc, v51
	v_lshlrev_b64 v[28:29], 2, v[16:17]
	v_mov_b64_e32 v[0:1], s[4:5]
	v_lshlrev_b32_e32 v194, 2, v26
	v_lshl_add_u64 v[16:17], s[52:53], 0, v[28:29]
	v_mad_i64_i32 v[24:25], s[2:3], v2, s86, v[0:1]
	global_load_dwordx4 v[0:3], v194, s[0:1]
	global_load_dwordx4 v[4:7], v194, s[0:1] offset:1024
	global_load_dwordx4 v[8:11], v194, s[0:1] offset:2048
	global_load_dwordx4 v[12:15], v194, s[8:9]
	v_lshl_add_u64 v[20:21], v[16:17], 0, v[194:195]
	v_lshlrev_b32_e32 v26, 1, v26
	v_mov_b32_e32 v27, v195
	global_load_dwordx4 v[16:19], v[20:21], off
	s_nop 0
	global_load_dwordx4 v[20:23], v[20:21], off offset:1024
	v_lshl_add_u64 v[30:31], v[24:25], 0, v[26:27]
	global_load_dwordx2 v[26:27], v[30:31], off offset:1536
	global_load_dwordx2 v[32:33], v[30:31], off offset:2560
	global_load_dwordx2 v[34:35], v[30:31], off offset:2048
	v_add_u32_e32 v50, s72, v50
	s_movk_i32 s2, 0x1fff
	v_cmp_lt_i32_e32 vcc, s2, v50
	v_add_u32_e32 v51, s26, v51
	s_or_b64 s[6:7], vcc, s[6:7]
	s_waitcnt vmcnt(0)
	v_pk_fma_f32 v[2:3], v[2:3], v[18:19], v[14:15]
	v_pk_fma_f32 v[0:1], v[0:1], v[16:17], v[12:13]
	s_waitcnt lgkmcnt(0)
	v_lshlrev_b32_e32 v24, 16, v26
	v_and_b32_e32 v25, 0xffff0000, v26
	v_lshlrev_b32_e32 v36, 16, v32
	v_and_b32_e32 v37, 0xffff0000, v32
	v_pk_fma_f32 v[2:3], v[6:7], v[22:23], v[2:3]
	v_pk_fma_f32 v[0:1], v[4:5], v[20:21], v[0:1]
	v_lshlrev_b32_e32 v4, 16, v27
	v_and_b32_e32 v5, 0xffff0000, v27
	v_lshlrev_b32_e32 v6, 16, v33
	v_and_b32_e32 v7, 0xffff0000, v33
	v_pk_mul_f32 v[24:25], v[24:25], v[36:37]
	v_pk_mul_f32 v[26:27], v[4:5], v[6:7]
	v_lshlrev_b32_e32 v38, 16, v34
	v_and_b32_e32 v39, 0xffff0000, v34
	v_pk_fma_f32 v[0:1], v[8:9], v[24:25], v[0:1]
	v_lshlrev_b32_e32 v8, 16, v35
	v_and_b32_e32 v9, 0xffff0000, v35
	v_pk_fma_f32 v[2:3], v[10:11], v[26:27], v[2:3]
	v_pk_mul_f32 v[0:1], v[0:1], v[38:39]
	v_pk_mul_f32 v[2:3], v[2:3], v[8:9]
	v_cvt_pk_bf16_f32 v0, v0, v1
	v_cvt_pk_bf16_f32 v1, v2, v3
	global_store_dwordx2 v[30:31], v[0:1], off offset:2048
	v_lshl_add_u64 v[0:1], s[18:19], 0, v[28:29]
	v_lshl_add_u64 v[0:1], v[0:1], 0, v[194:195]
	global_store_dwordx4 v[0:1], v[20:23], off
	global_store_dwordx4 v[0:1], v[24:27], off offset:1024
	s_andn2_b64 exec, exec, s[6:7]
	s_cbranch_execnz .LBB0_327

.LBB0_331:
	s_or_b32 s18, s14, s4
	s_xor_b64 s[12:13], s[2:3], -1
	s_add_i32 s2, s18, s5
	v_lshl_or_b32 v4, s2, 7, v47
	s_ashr_i32 s3, s2, 31
	v_ashrrev_i32_e32 v5, 31, v4
	s_lshl_b64 s[2:3], s[2:3], 12
	v_lshl_add_u64 v[4:5], v[4:5], 2, s[10:11]
	v_lshl_add_u64 v[32:33], v[36:37], 0, s[2:3]
	global_load_dwordx2 v[40:41], v[4:5], off
	global_load_dwordx4 v[8:11], v[32:33], off offset:512
	global_load_dwordx4 v[12:15], v[32:33], off offset:1024
	global_load_dwordx4 v[16:19], v[32:33], off offset:1536
	global_load_dwordx4 v[20:23], v[32:33], off offset:2048
	global_load_dwordx4 v[24:27], v[32:33], off offset:2560
	global_load_dwordx4 v[28:31], v[32:33], off offset:3072
	global_load_dwordx4 v[4:7], v[32:33], off
	s_lshl_b32 s2, s18, 4
	global_load_dwordx4 v[32:35], v[32:33], off offset:3584
	s_ashr_i32 s3, s2, 31
	v_mov_b32_e32 v193, v192
	s_lshl_b64 s[14:15], s[2:3], 1
	s_mov_b64 s[2:3], -1
	s_mov_b32 s19, 0
	v_mov_b64_e32 v[44:45], v[192:193]
	s_waitcnt vmcnt(0) lgkmcnt(0)
	v_pk_mov_b32 v[42:43], v[40:41], v[40:41] op_sel:[1,0]
	v_cndmask_b32_e64 v11, v11, 0, s[8:9]
	v_cndmask_b32_e64 v10, v10, 0, s[8:9]
	v_cndmask_b32_e64 v9, v9, 0, s[8:9]
	v_cndmask_b32_e64 v8, v8, 0, s[8:9]
	v_cndmask_b32_e64 v15, v15, 0, s[8:9]
	v_cndmask_b32_e64 v14, v14, 0, s[8:9]
	v_cndmask_b32_e64 v7, v7, 0, s[8:9]
	v_cndmask_b32_e64 v6, v6, 0, s[8:9]
	v_cndmask_b32_e64 v5, v5, 0, s[8:9]
	v_cndmask_b32_e64 v4, v4, 0, s[8:9]
	v_cndmask_b32_e64 v13, v13, 0, s[8:9]
	v_cndmask_b32_e64 v12, v12, 0, s[8:9]
	v_cndmask_b32_e64 v19, v19, 0, s[8:9]
	v_cndmask_b32_e64 v18, v18, 0, s[8:9]
	v_cndmask_b32_e64 v17, v17, 0, s[8:9]
	v_cndmask_b32_e64 v16, v16, 0, s[8:9]
	v_cndmask_b32_e64 v23, v23, 0, s[8:9]
	v_cndmask_b32_e64 v22, v22, 0, s[8:9]
	v_cndmask_b32_e64 v21, v21, 0, s[8:9]
	v_cndmask_b32_e64 v20, v20, 0, s[8:9]
	v_cndmask_b32_e64 v27, v27, 0, s[8:9]
	v_cndmask_b32_e64 v26, v26, 0, s[8:9]
	v_cndmask_b32_e64 v25, v25, 0, s[8:9]
	v_cndmask_b32_e64 v24, v24, 0, s[8:9]
	v_cndmask_b32_e64 v31, v31, 0, s[8:9]
	v_cndmask_b32_e64 v30, v30, 0, s[8:9]
	v_cndmask_b32_e64 v29, v29, 0, s[8:9]
	v_cndmask_b32_e64 v28, v28, 0, s[8:9]
	v_cndmask_b32_e64 v35, v35, 0, s[8:9]
	v_cndmask_b32_e64 v34, v34, 0, s[8:9]
	v_cndmask_b32_e64 v33, v33, 0, s[8:9]
	v_cndmask_b32_e64 v32, v32, 0, s[8:9]
.LBB0_332:
	v_or_b32_e32 v51, s19, v50
	v_mov_b64_e32 v[56:57], s[0:1]
	s_xor_b64 s[16:17], s[2:3], -1
	v_mad_i64_i32 v[52:53], s[2:3], v51, s86, v[56:57]
	v_lshl_add_u64 v[52:53], v[52:53], 0, s[14:15]
	v_lshl_add_u64 v[52:53], v[52:53], 0, v[194:195]
	v_add_co_u32_e32 v52, vcc, 0x2040000, v52
	s_waitcnt lgkmcnt(0)
	v_or_b32_e32 v51, 16, v51
	s_nop 0
	v_addc_co_u32_e32 v53, vcc, 0, v53, vcc
	global_load_dwordx4 v[52:55], v[52:53], off offset:1024
	v_mad_i64_i32 v[56:57], s[2:3], v51, s86, v[56:57]
	v_lshl_add_u64 v[56:57], v[56:57], 0, s[14:15]
	v_lshl_add_u64 v[56:57], v[56:57], 0, v[194:195]
	v_add_co_u32_e32 v56, vcc, 0x2040000, v56
	v_add_u32_e32 v51, 0x8000, v49
	s_nop 0
	v_addc_co_u32_e32 v57, vcc, 0, v57, vcc
	global_load_dwordx4 v[56:59], v[56:57], off offset:1024
	s_mov_b32 s2, -8
	s_waitcnt vmcnt(0) lgkmcnt(0)
	v_cndmask_b32_e64 v55, v55, 0, s[8:9]
	v_cndmask_b32_e64 v54, v54, 0, s[8:9]
	v_cndmask_b32_e64 v53, v53, 0, s[8:9]
	v_cndmask_b32_e64 v52, v52, 0, s[8:9]
	s_nop 1
	v_mfma_f32_16x16x32_bf16 v[60:63], v[4:7], v[52:55], v[0:3]
	s_nop 7
	v_cvt_pk_bf16_f32 v64, v60, v61
	v_cvt_pk_bf16_f32 v65, v62, v63
	v_mfma_f32_16x16x32_bf16 v[60:63], v[8:11], v[52:55], v[0:3]
	s_nop 7
	v_cvt_pk_bf16_f32 v60, v60, v61
	v_cvt_pk_bf16_f32 v61, v62, v63
	ds_write2_b64 v51, v[64:65], v[60:61] offset1:4
	v_mfma_f32_16x16x32_bf16 v[60:63], v[12:15], v[52:55], v[0:3]
	s_nop 7
	v_cvt_pk_bf16_f32 v64, v60, v61
	v_cvt_pk_bf16_f32 v65, v62, v63
	v_mfma_f32_16x16x32_bf16 v[60:63], v[16:19], v[52:55], v[0:3]
	s_nop 7
	v_cvt_pk_bf16_f32 v60, v60, v61
	v_cvt_pk_bf16_f32 v61, v62, v63
	ds_write2_b64 v51, v[64:65], v[60:61] offset0:8 offset1:12
	v_mfma_f32_16x16x32_bf16 v[60:63], v[20:23], v[52:55], v[0:3]
	s_nop 7
	v_cvt_pk_bf16_f32 v64, v60, v61
	v_cvt_pk_bf16_f32 v65, v62, v63
	v_mfma_f32_16x16x32_bf16 v[60:63], v[24:27], v[52:55], v[0:3]
	s_nop 7
	v_cvt_pk_bf16_f32 v60, v60, v61
	v_cvt_pk_bf16_f32 v61, v62, v63
	ds_write2_b64 v51, v[64:65], v[60:61] offset0:16 offset1:20
	v_mfma_f32_16x16x32_bf16 v[60:63], v[28:31], v[52:55], v[0:3]
	v_mfma_f32_16x16x32_bf16 v[52:55], v[32:35], v[52:55], v[0:3]
	s_nop 6
	v_cvt_pk_bf16_f32 v60, v60, v61
	v_cvt_pk_bf16_f32 v61, v62, v63
	v_cvt_pk_bf16_f32 v52, v52, v53
	v_cvt_pk_bf16_f32 v53, v54, v55
	ds_write2_b64 v51, v[60:61], v[52:53] offset0:24 offset1:28
	v_cndmask_b32_e64 v55, v59, 0, s[8:9]
	v_cndmask_b32_e64 v54, v58, 0, s[8:9]
	v_cndmask_b32_e64 v53, v57, 0, s[8:9]
	v_cndmask_b32_e64 v52, v56, 0, s[8:9]
	v_add_u32_e32 v51, 0x9000, v49
	s_nop 0
	v_mfma_f32_16x16x32_bf16 v[56:59], v[4:7], v[52:55], v[0:3]
	s_nop 7
	v_cvt_pk_bf16_f32 v60, v56, v57
	v_cvt_pk_bf16_f32 v61, v58, v59
	v_mfma_f32_16x16x32_bf16 v[56:59], v[8:11], v[52:55], v[0:3]
	s_nop 7
	v_cvt_pk_bf16_f32 v56, v56, v57
	v_cvt_pk_bf16_f32 v57, v58, v59
	ds_write2_b64 v51, v[60:61], v[56:57] offset0:32 offset1:36
	v_mfma_f32_16x16x32_bf16 v[56:59], v[12:15], v[52:55], v[0:3]
	s_nop 7
	v_cvt_pk_bf16_f32 v60, v56, v57
	v_cvt_pk_bf16_f32 v61, v58, v59
	v_mfma_f32_16x16x32_bf16 v[56:59], v[16:19], v[52:55], v[0:3]
	s_nop 7
	v_cvt_pk_bf16_f32 v56, v56, v57
	v_cvt_pk_bf16_f32 v57, v58, v59
	ds_write2_b64 v51, v[60:61], v[56:57] offset0:40 offset1:44
	v_mfma_f32_16x16x32_bf16 v[56:59], v[20:23], v[52:55], v[0:3]
	s_nop 7
	v_cvt_pk_bf16_f32 v60, v56, v57
	v_cvt_pk_bf16_f32 v61, v58, v59
	v_mfma_f32_16x16x32_bf16 v[56:59], v[24:27], v[52:55], v[0:3]
	s_nop 7
	v_cvt_pk_bf16_f32 v56, v56, v57
	v_cvt_pk_bf16_f32 v57, v58, v59
	ds_write2_b64 v51, v[60:61], v[56:57] offset0:48 offset1:52
	v_mfma_f32_16x16x32_bf16 v[56:59], v[28:31], v[52:55], v[0:3]
	v_mfma_f32_16x16x32_bf16 v[52:55], v[32:35], v[52:55], v[0:3]
	s_nop 6
	v_cvt_pk_bf16_f32 v56, v56, v57
	v_cvt_pk_bf16_f32 v57, v58, v59
	v_cvt_pk_bf16_f32 v52, v52, v53
	v_cvt_pk_bf16_f32 v53, v54, v55
	ds_write2_b64 v51, v[56:57], v[52:53] offset0:56 offset1:60
	s_waitcnt lgkmcnt(0)
	v_mov_b32_e32 v51, v48
.LBB0_333:
	ds_read2_b32 v[52:53], v51 offset1:68
	ds_read2_b32 v[54:55], v51 offset0:136 offset1:204
	v_pk_mul_f32 v[60:61], v[40:41], v[44:45]
	v_pk_mul_f32 v[44:45], v[42:43], v[44:45]
	v_sub_f32_e32 v60, v60, v61
	v_add_f32_e32 v44, v44, v45
	s_waitcnt lgkmcnt(1)
	v_and_b32_e32 v45, 0xffff0000, v52
	v_lshlrev_b32_e32 v61, 16, v52
	v_add_f32_e32 v44, v44, v45
	v_add_f32_e32 v60, v60, v61
	v_pk_mul_f32 v[44:45], v[42:43], v[44:45] op_sel_hi:[1,0]
	v_lshlrev_b32_e32 v52, 16, v53
	v_pk_fma_f32 v[62:63], v[40:41], v[60:61], v[44:45] neg_lo:[0,0,1] neg_hi:[0,0,1]
	v_pk_fma_f32 v[44:45], v[40:41], v[60:61], v[44:45] op_sel_hi:[1,0,1]
	v_and_b32_e32 v53, 0xffff0000, v53
	v_mov_b32_e32 v63, v45
	v_pk_add_f32 v[44:45], v[62:63], v[52:53]
	v_add_u32_e32 v58, 0x400, v51
	v_pk_mul_f32 v[52:53], v[40:41], v[44:45]
	v_pk_mul_f32 v[44:45], v[40:41], v[44:45] op_sel:[0,1] op_sel_hi:[1,0]
	v_sub_f32_e32 v52, v52, v53
	v_add_f32_e32 v44, v44, v45
	s_waitcnt lgkmcnt(0)
	v_and_b32_e32 v45, 0xffff0000, v54
	v_lshlrev_b32_e32 v53, 16, v54
	v_add_f32_e32 v44, v44, v45
	v_add_f32_e32 v52, v52, v53
	v_pk_mul_f32 v[44:45], v[42:43], v[44:45] op_sel_hi:[1,0]
	ds_read2_b32 v[56:57], v58 offset0:16 offset1:84
	ds_read2_b32 v[58:59], v58 offset0:152 offset1:220
	v_pk_fma_f32 v[60:61], v[40:41], v[52:53], v[44:45] neg_lo:[0,0,1] neg_hi:[0,0,1]
	v_pk_fma_f32 v[44:45], v[40:41], v[52:53], v[44:45] op_sel_hi:[1,0,1]
	v_lshlrev_b32_e32 v54, 16, v55
	v_and_b32_e32 v55, 0xffff0000, v55
	v_mov_b32_e32 v61, v45
	v_pk_add_f32 v[44:45], v[60:61], v[54:55]
	s_waitcnt lgkmcnt(1)
	v_lshlrev_b32_e32 v54, 16, v57
	v_pk_mul_f32 v[52:53], v[40:41], v[44:45]
	v_pk_mul_f32 v[44:45], v[40:41], v[44:45] op_sel:[0,1] op_sel_hi:[1,0]
	v_sub_f32_e32 v52, v52, v53
	v_add_f32_e32 v44, v44, v45
	v_and_b32_e32 v45, 0xffff0000, v56
	v_lshlrev_b32_e32 v53, 16, v56
	v_add_f32_e32 v44, v44, v45
	v_add_f32_e32 v52, v52, v53
	v_pk_mul_f32 v[44:45], v[42:43], v[44:45] op_sel_hi:[1,0]
	v_and_b32_e32 v55, 0xffff0000, v57
	v_pk_fma_f32 v[56:57], v[40:41], v[52:53], v[44:45] neg_lo:[0,0,1] neg_hi:[0,0,1]
	v_pk_fma_f32 v[44:45], v[40:41], v[52:53], v[44:45] op_sel_hi:[1,0,1]
	s_add_i32 s2, s2, 8
	v_mov_b32_e32 v57, v45
	v_pk_add_f32 v[44:45], v[56:57], v[54:55]
	s_waitcnt lgkmcnt(0)
	v_lshlrev_b32_e32 v54, 16, v59
	v_pk_mul_f32 v[52:53], v[40:41], v[44:45]
	v_pk_mul_f32 v[44:45], v[40:41], v[44:45] op_sel:[0,1] op_sel_hi:[1,0]
	v_sub_f32_e32 v52, v52, v53
	v_add_f32_e32 v44, v44, v45
	v_and_b32_e32 v45, 0xffff0000, v58
	v_lshlrev_b32_e32 v53, 16, v58
	v_add_f32_e32 v44, v44, v45
	v_add_f32_e32 v52, v52, v53
	v_pk_mul_f32 v[44:45], v[42:43], v[44:45] op_sel_hi:[1,0]
	v_and_b32_e32 v55, 0xffff0000, v59
	v_pk_fma_f32 v[56:57], v[40:41], v[52:53], v[44:45] neg_lo:[0,0,1] neg_hi:[0,0,1]
	v_pk_fma_f32 v[44:45], v[40:41], v[52:53], v[44:45] op_sel_hi:[1,0,1]
	v_add_u32_e32 v51, 0x880, v51
	v_mov_b32_e32 v57, v45
	v_pk_add_f32 v[44:45], v[56:57], v[54:55]
	s_cmp_lt_u32 s2, 24
	s_cbranch_scc1 .LBB0_333
	s_mov_b32 s19, 32
	s_mov_b64 s[2:3], 0
	s_and_b64 vcc, exec, s[16:17]
	s_cbranch_vccz .LBB0_332
	s_add_i32 s2, s18, s7
	s_ashr_i32 s3, s2, 31
	s_lshl_b64 s[2:3], s[2:3], 9
	v_lshl_add_u64 v[4:5], v[38:39], 0, s[2:3]
	s_mov_b32 s14, 1
	s_mov_b64 s[2:3], 0
	s_and_b64 vcc, exec, s[12:13]
	global_store_dwordx2 v[4:5], v[44:45], off
	s_cbranch_vccz .LBB0_331
	s_add_i32 s6, s6, s81
	s_cmpk_gt_i32 s6, 0xff
	s_cbranch_scc0 .LBB0_330

.LBB0_342:
	v_or_b32_e32 v176, s0, v221
	s_waitcnt lgkmcnt(0)
	v_mov_b64_e32 v[0:1], s[10:11]
	v_mad_i64_i32 v[0:1], s[4:5], v176, s86, v[0:1]
	s_mov_b64 s[4:5], 0x2040c00
	s_nop 0
	v_lshl_add_u64 v[180:181], v[0:1], 0, s[4:5]
	v_bitop3_b32 v0, s0, v241, v221 bitop3:0xc8
	v_cmp_eq_u32_e32 vcc, 0, v0
	v_mov_b32_e32 v0, 0xffffec00
	v_mov_b32_e32 v159, v195
	v_cndmask_b32_e64 v185, -1, 0, vcc
	v_cndmask_b32_e64 v184, v0, 0, vcc
	v_lshl_add_u64 v[0:1], v[180:181], 0, v[194:195]
	global_load_dwordx4 v[116:119], v[0:1], off
	v_lshl_add_u64 v[182:183], v[180:181], 0, v[184:185]
	v_lshl_add_u64 v[0:1], v[182:183], 0, v[194:195]
	global_load_dwordx4 v[186:189], v[0:1], off
	global_load_dwordx4 v[80:83], v[122:123], off offset:3072
	global_load_dwordx4 v[206:209], v[122:123], off offset:3088
	v_lshl_add_u64 v[0:1], v[180:181], 0, v[158:159]
	global_load_dwordx4 v[104:107], v[0:1], off
	v_lshl_add_u64 v[0:1], v[182:183], 0, v[158:159]
	v_mov_b32_e32 v161, v195
	global_load_dwordx4 v[84:87], v[0:1], off
	global_load_dwordx4 v[108:111], v[122:123], off offset:3216
	global_load_dwordx4 v[112:115], v[122:123], off offset:3200
	v_lshl_add_u64 v[0:1], v[180:181], 0, v[160:161]
	global_load_dwordx4 v[88:91], v[0:1], off
	v_lshl_add_u64 v[0:1], v[182:183], 0, v[160:161]
	v_mov_b32_e32 v163, v195
	global_load_dwordx4 v[92:95], v[0:1], off
	global_load_dwordx4 v[96:99], v[122:123], off offset:3328
	global_load_dwordx4 v[100:103], v[122:123], off offset:3344
	v_lshl_add_u64 v[0:1], v[180:181], 0, v[162:163]
	v_cndmask_b32_e64 v178, 1.0, 0, vcc
	global_load_dwordx4 v[64:67], v[0:1], off
	v_lshl_add_u64 v[0:1], v[182:183], 0, v[162:163]
	global_load_dwordx4 v[68:71], v[0:1], off
	global_load_dwordx4 v[72:75], v[122:123], off offset:3456
	global_load_dwordx4 v[76:79], v[122:123], off offset:3472
	global_load_dwordx4 v[60:63], v[124:125], off
	global_load_dwordx4 v[56:59], v[124:125], off offset:64
	global_load_dwordx4 v[52:55], v[124:125], off offset:128
	global_load_dwordx4 v[48:51], v[124:125], off offset:192
	global_load_dwordx4 v[44:47], v[124:125], off offset:1024
	global_load_dwordx4 v[40:43], v[124:125], off offset:1088
	global_load_dwordx4 v[28:31], v[124:125], off offset:1152
	global_load_dwordx4 v[24:27], v[124:125], off offset:1216
	global_load_dwordx4 v[20:23], v[126:127], off
	global_load_dwordx4 v[0:3], v[128:129], off
	global_load_dwordx4 v[4:7], v[130:131], off
	global_load_dwordx4 v[8:11], v[132:133], off
	global_load_dwordx4 v[12:15], v[134:135], off
	global_load_dwordx4 v[16:19], v[136:137], off
	global_load_dwordx4 v[32:35], v[138:139], off
	global_load_dwordx4 v[36:39], v[140:141], off
	v_ashrrev_i32_e32 v177, 31, v176
	v_lshlrev_b64 v[212:213], 9, v[176:177]
	v_lshl_add_u64 v[212:213], v[156:157], 0, v[212:213]
	s_waitcnt vmcnt(0) lgkmcnt(0)
	v_and_b32_e32 v163, 0xffff0000, v116
	v_lshlrev_b32_e32 v165, 16, v117
	v_and_b32_e32 v167, 0xffff0000, v117
	v_lshlrev_b32_e32 v161, 16, v118
	v_and_b32_e32 v159, 0xffff0000, v118
	v_lshlrev_b32_e32 v118, 16, v119
	v_and_b32_e32 v117, 0xffff0000, v119
	v_and_b32_e32 v119, 0xffff0000, v186
	v_lshlrev_b32_e32 v169, 16, v187
	v_fma_f32 v119, v178, v119, -v163
	v_and_b32_e32 v171, 0xffff0000, v187
	v_fmac_f32_e32 v163, v81, v119
	v_fma_f32 v81, v178, v169, -v165
	v_lshlrev_b32_e32 v173, 16, v188
	v_fmac_f32_e32 v165, v82, v81
	v_fma_f32 v81, v178, v171, -v167
	v_and_b32_e32 v175, 0xffff0000, v188
	v_fmac_f32_e32 v167, v83, v81
	v_fma_f32 v81, v178, v173, -v161
	v_lshlrev_b32_e32 v187, 16, v189
	v_fmac_f32_e32 v161, v206, v81
	v_fma_f32 v81, v178, v175, -v159
	v_and_b32_e32 v188, 0xffff0000, v189
	v_fmac_f32_e32 v159, v207, v81
	v_fma_f32 v81, v178, v187, -v118
	v_fmac_f32_e32 v118, v208, v81
	v_fma_f32 v81, v178, v188, -v117
	v_fmac_f32_e32 v117, v209, v81
	v_lshlrev_b32_e32 v81, 16, v186
	v_lshlrev_b32_e32 v82, 16, v116
	v_fma_f32 v81, v178, v81, -v82
	v_fmac_f32_e32 v82, v80, v81
	v_add_f32_e32 v80, v82, v82
	v_add_f32_e32 v81, v163, v163
	v_mul_f32_e32 v80, 0x3fb8aa3b, v80
	v_mul_f32_e32 v81, 0x3fb8aa3b, v81
	v_exp_f32_e32 v80, v80
	v_exp_f32_e32 v81, v81
	v_add_f32_e32 v117, v117, v117
	v_mul_f32_e32 v117, 0x3fb8aa3b, v117
	v_exp_f32_e32 v117, v117
	v_pk_add_f32 v[80:81], v[80:81], 1.0 op_sel_hi:[1,0]
	v_mov_b32_e32 v169, v195
	v_mov_b32_e32 v171, v195
	v_mov_b32_e32 v173, v195
	v_mov_b32_e32 v175, v195
	v_rcp_f32_e32 v81, v81
	s_nop 0
	v_mul_f32_e32 v81, 2.0, v81
	v_rcp_f32_e32 v80, v80
	s_nop 0
	v_mul_f32_e32 v80, 2.0, v80
	v_add_f32_e32 v82, v165, v165
	v_add_f32_e32 v83, v167, v167
	v_mul_f32_e32 v82, 0x3fb8aa3b, v82
	v_mul_f32_e32 v83, 0x3fb8aa3b, v83
	v_exp_f32_e32 v82, v82
	v_exp_f32_e32 v83, v83
	v_pk_add_f32 v[80:81], v[80:81], 1.0 op_sel_hi:[1,0] neg_lo:[1,0] neg_hi:[1,0]
	v_pk_add_f32 v[82:83], v[82:83], 1.0 op_sel_hi:[1,0]
	s_nop 0
	v_cvt_pk_bf16_f32 v80, v80, v81
	v_rcp_f32_e32 v83, v83
	s_nop 0
	v_mul_f32_e32 v83, 2.0, v83
	v_rcp_f32_e32 v82, v82
	s_nop 0
	v_mul_f32_e32 v82, 2.0, v82
	v_add_f32_e32 v116, v161, v161
	v_mul_f32_e32 v116, 0x3fb8aa3b, v116
	v_exp_f32_e32 v186, v116
	v_add_f32_e32 v116, v159, v159
	v_mul_f32_e32 v116, 0x3fb8aa3b, v116
	v_exp_f32_e32 v187, v116
	v_pk_add_f32 v[82:83], v[82:83], 1.0 op_sel_hi:[1,0] neg_lo:[1,0] neg_hi:[1,0]
	v_mov_b32_e32 v165, v195
	v_cvt_pk_bf16_f32 v81, v82, v83
	v_pk_add_f32 v[186:187], v[186:187], 1.0 op_sel_hi:[1,0]
	v_mov_b32_e32 v167, v195
	v_rcp_f32_e32 v187, v187
	s_nop 0
	v_mul_f32_e32 v187, 2.0, v187
	v_rcp_f32_e32 v186, v186
	s_nop 0
	v_mul_f32_e32 v186, 2.0, v186
	v_add_f32_e32 v116, v118, v118
	v_mul_f32_e32 v116, 0x3fb8aa3b, v116
	v_exp_f32_e32 v116, v116
	v_pk_add_f32 v[186:187], v[186:187], 1.0 op_sel_hi:[1,0] neg_lo:[1,0] neg_hi:[1,0]
	v_pk_add_f32 v[116:117], v[116:117], 1.0 op_sel_hi:[1,0]
	s_nop 0
	v_cvt_pk_bf16_f32 v82, v186, v187
	v_rcp_f32_e32 v117, v117
	s_nop 0
	v_mul_f32_e32 v117, 2.0, v117
	v_rcp_f32_e32 v116, v116
	s_nop 0
	v_mul_f32_e32 v116, 2.0, v116
	v_pk_add_f32 v[116:117], v[116:117], 1.0 op_sel_hi:[1,0] neg_lo:[1,0] neg_hi:[1,0]
	v_lshlrev_b32_e32 v118, 16, v84
	v_cvt_pk_bf16_f32 v83, v116, v117
	v_lshlrev_b32_e32 v116, 16, v104
	v_and_b32_e32 v117, 0xffff0000, v104
	v_and_b32_e32 v119, 0xffff0000, v84
	v_lshlrev_b32_e32 v104, 16, v105
	v_and_b32_e32 v105, 0xffff0000, v105
	v_lshlrev_b32_e32 v84, 16, v85
	v_and_b32_e32 v85, 0xffff0000, v85
	v_pk_fma_f32 v[84:85], v[178:179], v[84:85], v[104:105] op_sel_hi:[0,1,1] neg_lo:[0,0,1] neg_hi:[0,0,1]
	v_pk_fma_f32 v[104:105], v[114:115], v[84:85], v[104:105]
	v_lshlrev_b32_e32 v84, 16, v106
	v_and_b32_e32 v85, 0xffff0000, v106
	v_lshlrev_b32_e32 v114, 16, v86
	v_and_b32_e32 v115, 0xffff0000, v86
	v_pk_fma_f32 v[114:115], v[178:179], v[114:115], v[84:85] op_sel_hi:[0,1,1] neg_lo:[0,0,1] neg_hi:[0,0,1]
	v_pk_fma_f32 v[108:109], v[108:109], v[114:115], v[84:85]
	v_lshlrev_b32_e32 v84, 16, v107
	v_and_b32_e32 v85, 0xffff0000, v107
	v_lshlrev_b32_e32 v86, 16, v87
	v_and_b32_e32 v87, 0xffff0000, v87
	v_pk_fma_f32 v[86:87], v[178:179], v[86:87], v[84:85] op_sel_hi:[0,1,1] neg_lo:[0,0,1] neg_hi:[0,0,1]
	v_pk_fma_f32 v[106:107], v[110:111], v[86:87], v[84:85]
	v_cvt_pk_bf16_f32 v85, v104, v105
	v_cvt_pk_bf16_f32 v87, v106, v107
	v_and_b32_e32 v104, 0xffff0000, v88
	v_lshlrev_b32_e32 v105, 16, v89
	v_and_b32_e32 v106, 0xffff0000, v89
	v_and_b32_e32 v89, 0xffff0000, v92
	v_cvt_pk_bf16_f32 v86, v108, v109
	v_lshlrev_b32_e32 v109, 16, v93
	v_fma_f32 v89, v178, v89, -v104
	v_and_b32_e32 v93, 0xffff0000, v93
	v_fmac_f32_e32 v104, v97, v89
	v_fma_f32 v89, v178, v109, -v105
	v_lshlrev_b32_e32 v107, 16, v90
	v_lshlrev_b32_e32 v110, 16, v94
	v_fmac_f32_e32 v105, v98, v89
	v_fma_f32 v89, v178, v93, -v106
	v_and_b32_e32 v90, 0xffff0000, v90
	v_and_b32_e32 v94, 0xffff0000, v94
	v_fmac_f32_e32 v106, v99, v89
	v_fma_f32 v89, v178, v110, -v107
	v_lshlrev_b32_e32 v108, 16, v91
	v_lshlrev_b32_e32 v111, 16, v95
	v_fmac_f32_e32 v107, v100, v89
	v_fma_f32 v89, v178, v94, -v90
	v_and_b32_e32 v91, 0xffff0000, v91
	v_and_b32_e32 v95, 0xffff0000, v95
	v_fmac_f32_e32 v90, v101, v89
	v_fma_f32 v89, v178, v111, -v108
	v_fmac_f32_e32 v108, v102, v89
	v_fma_f32 v89, v178, v95, -v91
	v_fmac_f32_e32 v91, v103, v89
	v_lshlrev_b32_e32 v89, 16, v92
	v_lshlrev_b32_e32 v88, 16, v88
	v_fma_f32 v89, v178, v89, -v88
	v_fmac_f32_e32 v88, v96, v89
	v_mul_f32_e32 v88, 0xbfb8aa3b, v88
	v_mul_f32_e32 v89, 0xbfb8aa3b, v104
	v_exp_f32_e32 v88, v88
	v_exp_f32_e32 v89, v89
	v_pk_fma_f32 v[118:119], v[178:179], v[118:119], v[116:117] op_sel_hi:[0,1,1] neg_lo:[0,0,1] neg_hi:[0,0,1]
	v_pk_fma_f32 v[112:113], v[112:113], v[118:119], v[116:117]
	v_pk_add_f32 v[88:89], v[88:89], 1.0 op_sel_hi:[1,0]
	s_nop 0
	v_cvt_pk_bf16_f32 v84, v112, v113
	v_rcp_f32_e32 v92, v89
	s_nop 0
	v_mfma_f32_16x16x32_bf16 v[16:19], v[16:19], v[84:87], 0
	v_rcp_f32_e32 v93, v88
	v_mul_f32_e32 v88, 0xbfb8aa3b, v105
	v_mul_f32_e32 v89, 0xbfb8aa3b, v106
	v_exp_f32_e32 v88, v88
	v_exp_f32_e32 v89, v89
	s_nop 0
	v_pk_add_f32 v[88:89], v[88:89], 1.0 op_sel_hi:[1,0]
	s_nop 0
	v_rcp_f32_e32 v94, v89
	v_rcp_f32_e32 v95, v88
	v_mul_f32_e32 v88, 0xbfb8aa3b, v107
	v_mul_f32_e32 v89, 0xbfb8aa3b, v90
	v_exp_f32_e32 v88, v88
	v_exp_f32_e32 v89, v89
	s_nop 0
	v_pk_add_f32 v[88:89], v[88:89], 1.0 op_sel_hi:[1,0]
	s_nop 0
	v_rcp_f32_e32 v90, v89
	v_rcp_f32_e32 v96, v88
	v_mul_f32_e32 v88, 0xbfb8aa3b, v108
	v_mul_f32_e32 v89, 0xbfb8aa3b, v91
	v_exp_f32_e32 v88, v88
	v_exp_f32_e32 v89, v89
	v_cvt_pk_bf16_f32 v90, v96, v90
	v_lshlrev_b32_e32 v96, 16, v67
	v_and_b32_e32 v67, 0xffff0000, v67
	v_pk_add_f32 v[88:89], v[88:89], 1.0 op_sel_hi:[1,0]
	s_nop 0
	v_rcp_f32_e32 v91, v89
	v_rcp_f32_e32 v97, v88
	v_cvt_pk_bf16_f32 v88, v93, v92
	v_cvt_pk_bf16_f32 v89, v95, v94
	v_and_b32_e32 v92, 0xffff0000, v64
	v_lshlrev_b32_e32 v93, 16, v65
	v_and_b32_e32 v94, 0xffff0000, v65
	v_and_b32_e32 v65, 0xffff0000, v68
	v_cvt_pk_bf16_f32 v91, v97, v91
	v_lshlrev_b32_e32 v97, 16, v69
	v_fma_f32 v65, v178, v65, -v92
	v_and_b32_e32 v69, 0xffff0000, v69
	v_fmac_f32_e32 v92, v73, v65
	v_fma_f32 v65, v178, v97, -v93
	v_lshlrev_b32_e32 v95, 16, v66
	v_lshlrev_b32_e32 v98, 16, v70
	v_fmac_f32_e32 v93, v74, v65
	v_fma_f32 v65, v178, v69, -v94
	v_and_b32_e32 v66, 0xffff0000, v66
	v_and_b32_e32 v70, 0xffff0000, v70
	v_fmac_f32_e32 v94, v75, v65
	v_fma_f32 v65, v178, v98, -v95
	v_lshlrev_b32_e32 v99, 16, v71
	v_fmac_f32_e32 v95, v76, v65
	v_fma_f32 v65, v178, v70, -v66
	v_and_b32_e32 v71, 0xffff0000, v71
	v_fmac_f32_e32 v66, v77, v65
	v_fma_f32 v65, v178, v99, -v96
	v_fmac_f32_e32 v96, v78, v65
	v_fma_f32 v65, v178, v71, -v67
	v_fmac_f32_e32 v67, v79, v65
	v_lshlrev_b32_e32 v65, 16, v68
	v_lshlrev_b32_e32 v64, 16, v64
	v_fma_f32 v65, v178, v65, -v64
	v_fmac_f32_e32 v64, v72, v65
	v_mul_f32_e32 v64, 0xbfb8aa3b, v64
	v_mul_f32_e32 v65, 0xbfb8aa3b, v92
	v_exp_f32_e32 v64, v64
	v_exp_f32_e32 v65, v65
	v_mfma_f32_16x16x32_bf16 v[28:31], v[28:31], v[88:91], 0
	v_add_f32_e64 v64, v64, 1.0
	v_add_f32_e64 v65, v65, 1.0
	v_mfma_f32_16x16x32_bf16 v[52:55], v[52:55], v[88:91], 0
	v_rcp_f32_e32 v68, v65
	v_rcp_f32_e32 v69, v64
	v_mul_f32_e32 v64, 0xbfb8aa3b, v93
	v_mul_f32_e32 v65, 0xbfb8aa3b, v94
	v_exp_f32_e32 v64, v64
	v_exp_f32_e32 v65, v65
	s_nop 0
	v_pk_add_f32 v[64:65], v[64:65], 1.0 op_sel_hi:[1,0]
	s_nop 0
	v_rcp_f32_e32 v70, v65
	v_rcp_f32_e32 v71, v64
	v_mul_f32_e32 v64, 0xbfb8aa3b, v95
	v_mul_f32_e32 v65, 0xbfb8aa3b, v66
	v_exp_f32_e32 v64, v64
	v_exp_f32_e32 v65, v65
	v_mfma_f32_16x16x32_bf16 v[92:95], v[56:59], v[84:87], 0
	v_add_f32_e64 v64, v64, 1.0
	v_add_f32_e64 v65, v65, 1.0
	v_mfma_f32_16x16x32_bf16 v[56:59], v[40:43], v[84:87], 0
	v_rcp_f32_e32 v66, v65
	v_rcp_f32_e32 v72, v64
	v_mul_f32_e32 v64, 0xbfb8aa3b, v96
	v_mul_f32_e32 v65, 0xbfb8aa3b, v67
	v_exp_f32_e32 v64, v64
	v_exp_f32_e32 v65, v65
	v_cvt_pk_bf16_f32 v66, v72, v66
	v_mfma_f32_16x16x32_bf16 v[96:99], v[60:63], v[80:83], 0
	v_add_f32_e64 v64, v64, 1.0
	v_add_f32_e64 v65, v65, 1.0
	v_mfma_f32_16x16x32_bf16 v[60:63], v[44:47], v[80:83], 0
	v_rcp_f32_e32 v67, v65
	v_rcp_f32_e32 v73, v64
	v_cvt_pk_bf16_f32 v64, v69, v68
	v_cvt_pk_bf16_f32 v65, v71, v70
	v_cvt_pk_bf16_f32 v67, v73, v67
	s_nop 1
	v_mfma_f32_16x16x32_bf16 v[40:43], v[24:27], v[64:67], v[28:31]
	v_mfma_f32_16x16x32_bf16 v[24:27], v[0:3], v[84:87], 0
	v_mfma_f32_16x16x32_bf16 v[0:3], v[4:7], v[88:91], 0
	v_mfma_f32_16x16x32_bf16 v[0:3], v[8:11], v[64:67], v[0:3]
	v_lshl_add_u64 v[8:9], v[180:181], 0, v[164:165]
	global_load_dwordx4 v[186:189], v[8:9], off
	v_lshl_add_u64 v[8:9], v[8:9], 0, v[184:185]
	v_mfma_f32_16x16x32_bf16 v[4:7], v[32:35], v[88:91], 0
	global_load_dwordx4 v[216:219], v[8:9], off
	global_load_dwordx4 v[222:225], v[142:143], off offset:16
	global_load_dwordx4 v[208:211], v[142:143], off
	v_lshl_add_u64 v[8:9], v[180:181], 0, v[166:167]
	global_load_dwordx4 v[72:75], v[8:9], off
	v_lshl_add_u64 v[8:9], v[182:183], 0, v[166:167]
	v_mfma_f32_16x16x32_bf16 v[48:51], v[48:51], v[64:67], v[52:55]
	v_cvt_pk_bf16_f32 v0, v0, v1
	v_cvt_pk_bf16_f32 v1, v2, v3
	s_waitcnt vmcnt(0) lgkmcnt(0)
	v_lshlrev_b32_e32 v184, 16, v186
	v_mfma_f32_16x16x32_bf16 v[4:7], v[36:39], v[64:67], v[4:7]
	global_load_dwordx4 v[68:71], v[8:9], off
	global_load_dwordx4 v[64:67], v[142:143], off offset:1040
	global_load_dwordx4 v[100:103], v[142:143], off offset:1024
	v_lshl_add_u64 v[8:9], v[180:181], 0, v[168:169]
	global_load_dwordx4 v[44:47], v[8:9], off
	v_lshl_add_u64 v[8:9], v[182:183], 0, v[168:169]
	v_mfma_f32_16x16x32_bf16 v[28:31], v[20:23], v[80:83], 0
	v_and_b32_e32 v185, 0xffff0000, v186
	v_lshlrev_b32_e32 v190, 16, v216
	v_and_b32_e32 v191, 0xffff0000, v216
	v_mfma_f32_16x16x32_bf16 v[20:23], v[12:15], v[80:83], 0
	global_load_dwordx4 v[36:39], v[8:9], off
	global_load_dwordx4 v[32:35], v[142:143], off offset:2064
	global_load_dwordx4 v[52:55], v[142:143], off offset:2048
	global_load_dwordx4 v[84:87], v[144:145], off offset:16
	global_load_dwordx4 v[116:119], v[144:145], off
	global_load_dwordx4 v[88:91], v[146:147], off offset:16
	global_load_dwordx4 v[112:115], v[146:147], off
	global_load_dwordx4 v[8:11], v[148:149], off
	global_load_dwordx4 v[12:15], v[148:149], off offset:16
	global_load_dwordx4 v[80:83], v[150:151], off offset:16
	global_load_dwordx4 v[108:111], v[150:151], off
	global_load_dwordx4 v[76:79], v[152:153], off offset:16
	global_load_dwordx4 v[104:107], v[152:153], off
	v_pk_fma_f32 v[190:191], v[178:179], v[190:191], v[184:185] op_sel_hi:[0,1,1] neg_lo:[0,0,1] neg_hi:[0,0,1]
	v_pk_fma_f32 v[208:209], v[208:209], v[190:191], v[184:185]
	v_lshlrev_b32_e32 v184, 16, v187
	v_and_b32_e32 v185, 0xffff0000, v187
	v_lshlrev_b32_e32 v186, 16, v217
	v_and_b32_e32 v187, 0xffff0000, v217
	v_pk_fma_f32 v[186:187], v[178:179], v[186:187], v[184:185] op_sel_hi:[0,1,1] neg_lo:[0,0,1] neg_hi:[0,0,1]
	v_pk_fma_f32 v[214:215], v[210:211], v[186:187], v[184:185]
	v_lshlrev_b32_e32 v184, 16, v188
	v_and_b32_e32 v185, 0xffff0000, v188
	v_lshlrev_b32_e32 v186, 16, v218
	v_and_b32_e32 v187, 0xffff0000, v218
	v_pk_fma_f32 v[186:187], v[178:179], v[186:187], v[184:185] op_sel_hi:[0,1,1] neg_lo:[0,0,1] neg_hi:[0,0,1]
	v_pk_fma_f32 v[216:217], v[222:223], v[186:187], v[184:185]
	v_lshlrev_b32_e32 v184, 16, v189
	v_and_b32_e32 v185, 0xffff0000, v189
	v_lshlrev_b32_e32 v186, 16, v219
	v_and_b32_e32 v187, 0xffff0000, v219
	v_pk_fma_f32 v[186:187], v[178:179], v[186:187], v[184:185] op_sel_hi:[0,1,1] neg_lo:[0,0,1] neg_hi:[0,0,1]
	v_pk_fma_f32 v[218:219], v[224:225], v[186:187], v[184:185]
	v_cvt_pk_bf16_f32 v2, v4, v5
	v_cvt_pk_bf16_f32 v3, v6, v7
	s_waitcnt vmcnt(0)
	v_add_f32_e32 v60, v60, v84
	v_add_f32_e32 v96, v96, v116
	v_max_f32_e64 v116, -v96, 0
	v_mul_f32_e64 v96, |v96|, s26
	v_exp_f32_e32 v96, v96
	v_add_f32_e32 v97, v97, v117
	v_add_f32_e32 v92, v92, v112
	v_max_f32_e64 v112, -v97, 0
	v_add_f32_e32 v96, 1.0, v96
	v_cmp_gt_f32_e32 vcc, s6, v96
	v_mul_f32_e64 v97, |v97|, s26
	v_exp_f32_e32 v97, v97
	v_cndmask_b32_e64 v159, 0, 32, vcc
	v_ldexp_f32 v96, v96, v159
	v_log_f32_e32 v96, v96
	v_add_f32_e32 v97, 1.0, v97
	v_add_f32_e32 v93, v93, v113
	v_mul_f32_e32 v92, 0xbfb8aa3b, v92
	v_mul_f32_e32 v159, 0x3f317217, v96
	v_fma_f32 v159, v96, s34, -v159
	v_fmac_f32_e32 v159, 0x3377d1cf, v96
	v_fmac_f32_e32 v159, 0x3f317217, v96
	v_cmp_lt_f32_e64 s[0:1], |v96|, s35
	v_mul_f32_e32 v93, 0xbfb8aa3b, v93
	v_exp_f32_e32 v92, v92
	v_cndmask_b32_e64 v96, v96, v159, s[0:1]
	v_cndmask_b32_e32 v159, 0, v242, vcc
	v_sub_f32_e32 v96, v96, v159
	v_cmp_gt_f32_e32 vcc, s6, v97
	v_add_f32_e32 v96, v116, v96
	v_exp_f32_e32 v93, v93
	v_cndmask_b32_e64 v116, 0, 32, vcc
	v_ldexp_f32 v97, v97, v116
	v_log_f32_e32 v97, v97
	v_pk_add_f32 v[92:93], v[92:93], 1.0 op_sel_hi:[1,0]
	s_waitcnt lgkmcnt(0)
	v_and_b32_e32 v117, 0xffff0000, v68
	v_and_b32_e32 v113, 0xffff0000, v72
	v_mul_f32_e32 v116, 0x3f317217, v97
	v_fma_f32 v116, v97, s34, -v116
	v_fmac_f32_e32 v116, 0x3377d1cf, v97
	v_fmac_f32_e32 v116, 0x3f317217, v97
	v_cmp_lt_f32_e64 s[0:1], |v97|, s35
	v_add_f32_e32 v61, v61, v85
	v_add_f32_e32 v56, v56, v88
	v_cndmask_b32_e64 v97, v97, v116, s[0:1]
	v_cndmask_b32_e32 v116, 0, v242, vcc
	v_sub_f32_e32 v97, v97, v116
	v_lshlrev_b32_e32 v116, 16, v68
	v_add_f32_e32 v97, v112, v97
	v_lshlrev_b32_e32 v112, 16, v72
	v_pk_fma_f32 v[116:117], v[178:179], v[116:117], v[112:113] op_sel_hi:[0,1,1] neg_lo:[0,0,1] neg_hi:[0,0,1]
	v_pk_fma_f32 v[184:185], v[100:101], v[116:117], v[112:113]
	v_add_f32_e32 v57, v57, v89
	v_rcp_f32_e32 v117, v93
	v_mul_f32_e32 v56, 0xbfb8aa3b, v56
	v_mul_f32_e32 v57, 0xbfb8aa3b, v57
	v_exp_f32_e32 v56, v56
	v_rcp_f32_e32 v116, v92
	v_add_f32_e32 v68, v98, v118
	v_max_f32_e64 v72, -v68, 0
	v_mul_f32_e64 v68, |v68|, s26
	v_exp_f32_e32 v68, v68
	v_pk_add_f32 v[92:93], v[116:117], -1.0 op_sel_hi:[1,0]
	v_exp_f32_e32 v57, v57
	v_pk_fma_f32 v[92:93], v[108:109], v[92:93], 1.0 op_sel_hi:[1,1,0]
	v_add_f32_e32 v68, 1.0, v68
	v_cmp_gt_f32_e32 vcc, s6, v68
	v_pk_mul_f32 v[92:93], v[184:185], v[92:93]
	v_and_b32_e32 v85, 0xffff0000, v74
	v_cndmask_b32_e64 v98, 0, 32, vcc
	v_ldexp_f32 v68, v68, v98
	v_log_f32_e32 v68, v68
	v_pk_mul_f32 v[100:101], v[208:209], v[92:93]
	v_lshlrev_b32_e32 v88, 16, v70
	v_fma_f32 v159, v104, v100, 0
	v_mul_f32_e32 v98, 0x3f317217, v68
	v_fma_f32 v98, v68, s34, -v98
	v_fmac_f32_e32 v98, 0x3377d1cf, v68
	v_fmac_f32_e32 v98, 0x3f317217, v68
	v_cmp_lt_f32_e64 s[0:1], |v68|, s35
	v_fmac_f32_e32 v159, v105, v101
	v_lshlrev_b32_e32 v100, 16, v73
	v_cndmask_b32_e64 v68, v68, v98, s[0:1]
	v_cndmask_b32_e32 v98, 0, v242, vcc
	v_sub_f32_e32 v68, v68, v98
	v_add_f32_e32 v68, v72, v68
	v_sub_f32_e32 v68, -0.5, v68
	v_mul_f32_e32 v68, 0x3fb8aa3b, v68
	v_exp_f32_e32 v68, v68
	v_and_b32_e32 v101, 0xffff0000, v73
	v_and_b32_e32 v89, 0xffff0000, v70
	v_pk_add_f32 v[56:57], v[56:57], 1.0 op_sel_hi:[1,0]
	v_xor_b32_e32 v72, 0x80000000, v68
	v_add_f32_e32 v68, v94, v114
	v_mul_f32_e32 v68, 0xbfb8aa3b, v68
	v_exp_f32_e32 v98, v68
	v_add_f32_e32 v68, v99, v119
	v_max_f32_e64 v94, -v68, 0
	v_mul_f32_e64 v68, |v68|, s26
	v_exp_f32_e32 v68, v68
	v_add_f32_e32 v62, v62, v86
	v_add_f32_e32 v58, v58, v90
	v_add_f32_e32 v59, v59, v91
	v_add_f32_e32 v68, 1.0, v68
	v_cmp_gt_f32_e32 vcc, s6, v68
	v_mul_f32_e32 v58, 0xbfb8aa3b, v58
	v_mul_f32_e32 v59, 0xbfb8aa3b, v59
	v_cndmask_b32_e64 v99, 0, 32, vcc
	v_ldexp_f32 v68, v68, v99
	v_log_f32_e32 v68, v68
	v_exp_f32_e32 v58, v58
	v_exp_f32_e32 v59, v59
	v_sub_f32_e32 v96, -0.5, v96
	v_mul_f32_e32 v99, 0x3f317217, v68
	v_fma_f32 v99, v68, s34, -v99
	v_fmac_f32_e32 v99, 0x3377d1cf, v68
	v_fmac_f32_e32 v99, 0x3f317217, v68
	v_cmp_lt_f32_e64 s[0:1], |v68|, s35
	v_pk_add_f32 v[58:59], v[58:59], 1.0 op_sel_hi:[1,0]
	v_sub_f32_e32 v97, -0.5, v97
	v_cndmask_b32_e64 v68, v68, v99, s[0:1]
	v_cndmask_b32_e32 v99, 0, v242, vcc
	v_sub_f32_e32 v68, v68, v99
	v_add_f32_e32 v68, v94, v68
	v_sub_f32_e32 v68, -0.5, v68
	v_mul_f32_e32 v68, 0x3fb8aa3b, v68
	v_exp_f32_e32 v68, v68
	v_mul_f32_e32 v96, 0x3fb8aa3b, v96
	v_mul_f32_e32 v97, 0x3fb8aa3b, v97
	v_exp_f32_e32 v96, v96
	v_xor_b32_e32 v94, 0x80000000, v68
	v_add_f32_e32 v68, v95, v115
	v_mul_f32_e32 v68, 0xbfb8aa3b, v68
	v_exp_f32_e32 v99, v68
	v_lshlrev_b32_e32 v68, 16, v69
	v_and_b32_e32 v69, 0xffff0000, v69
	v_pk_fma_f32 v[68:69], v[178:179], v[68:69], v[100:101] op_sel_hi:[0,1,1] neg_lo:[0,0,1] neg_hi:[0,0,1]
	v_pk_fma_f32 v[186:187], v[102:103], v[68:69], v[100:101]
	v_pk_add_f32 v[68:69], v[98:99], 1.0 op_sel_hi:[1,0]
	v_exp_f32_e32 v97, v97
	v_xor_b32_e32 v96, 0x80000000, v96
	v_xor_b32_e32 v97, 0x80000000, v97
	v_pk_mul_f32 v[8:9], v[184:185], v[8:9]
	v_rcp_f32_e32 v119, v69
	v_pk_mul_f32 v[10:11], v[186:187], v[10:11]
	v_max_f32_e64 v73, -v60, 0
	v_mul_f32_e64 v60, |v60|, s26
	v_exp_f32_e32 v60, v60
	v_rcp_f32_e32 v118, v68
	s_nop 0
	v_pk_add_f32 v[68:69], v[118:119], -1.0 op_sel_hi:[1,0]
	v_add_f32_e32 v60, 1.0, v60
	v_cmp_gt_f32_e32 vcc, s6, v60
	v_pk_fma_f32 v[68:69], v[110:111], v[68:69], 1.0 op_sel_hi:[1,1,0]
	s_nop 0
	v_cndmask_b32_e64 v84, 0, 32, vcc
	v_ldexp_f32 v60, v60, v84
	v_log_f32_e32 v60, v60
	v_pk_mul_f32 v[68:69], v[186:187], v[68:69]
	v_mul_f32_e32 v84, 0x3f317217, v60
	v_fma_f32 v84, v60, s34, -v84
	v_fmac_f32_e32 v84, 0x3377d1cf, v60
	v_fmac_f32_e32 v84, 0x3f317217, v60
	v_cmp_lt_f32_e64 s[0:1], |v60|, s35
	v_pk_mul_f32 v[98:99], v[214:215], v[68:69]
	s_nop 0
	v_cndmask_b32_e64 v60, v60, v84, s[0:1]
	v_cndmask_b32_e32 v84, 0, v242, vcc
	v_sub_f32_e32 v60, v60, v84
	v_add_f32_e32 v60, v73, v60
	v_max_f32_e64 v73, -v61, 0
	v_mul_f32_e64 v61, |v61|, s26
	v_exp_f32_e32 v61, v61
	v_fmac_f32_e32 v159, v106, v98
	v_fmac_f32_e32 v159, v107, v99
	v_sub_f32_e32 v60, -0.5, v60
	v_add_f32_e32 v61, 1.0, v61
	v_cmp_gt_f32_e32 vcc, s6, v61
	v_mul_f32_e32 v60, 0x3fb8aa3b, v60
	v_exp_f32_e32 v60, v60
	v_cndmask_b32_e64 v84, 0, 32, vcc
	v_ldexp_f32 v61, v61, v84
	v_log_f32_e32 v61, v61
	v_xor_b32_e32 v60, 0x80000000, v60
	v_mul_f32_e32 v84, 0x3f317217, v61
	v_fma_f32 v84, v61, s34, -v84
	v_fmac_f32_e32 v84, 0x3377d1cf, v61
	v_fmac_f32_e32 v84, 0x3f317217, v61
	v_cmp_lt_f32_e64 s[0:1], |v61|, s35
	s_nop 1
	v_cndmask_b32_e64 v61, v61, v84, s[0:1]
	v_cndmask_b32_e32 v84, 0, v242, vcc
	v_sub_f32_e32 v61, v61, v84
	v_lshlrev_b32_e32 v84, 16, v74
	v_pk_fma_f32 v[88:89], v[178:179], v[88:89], v[84:85] op_sel_hi:[0,1,1] neg_lo:[0,0,1] neg_hi:[0,0,1]
	v_pk_fma_f32 v[190:191], v[64:65], v[88:89], v[84:85]
	v_add_f32_e32 v61, v73, v61
	v_sub_f32_e32 v61, -0.5, v61
	v_mul_f32_e32 v61, 0x3fb8aa3b, v61
	v_rcp_f32_e32 v189, v57
	v_exp_f32_e32 v61, v61
	v_pk_mul_f32 v[6:7], v[190:191], v[12:13]
	v_rcp_f32_e32 v188, v56
	s_nop 0
	v_pk_add_f32 v[56:57], v[188:189], -1.0 op_sel_hi:[1,0]
	v_xor_b32_e32 v61, 0x80000000, v61
	v_pk_fma_f32 v[56:57], v[80:81], v[56:57], 1.0 op_sel_hi:[1,1,0]
	v_pk_mul_f32 v[12:13], v[6:7], v[6:7]
	v_pk_mul_f32 v[56:57], v[190:191], v[56:57]
	s_nop 0
	v_pk_mul_f32 v[64:65], v[216:217], v[56:57]
	s_nop 0
	v_fmac_f32_e32 v159, v76, v64
	v_max_f32_e64 v64, -v62, 0
	v_mul_f32_e64 v62, |v62|, s26
	v_exp_f32_e32 v62, v62
	v_fmac_f32_e32 v159, v77, v65
	v_add_f32_e32 v62, 1.0, v62
	v_cmp_gt_f32_e32 vcc, s6, v62
	s_nop 1
	v_cndmask_b32_e64 v65, 0, 32, vcc
	v_ldexp_f32 v62, v62, v65
	v_log_f32_e32 v62, v62
	s_nop 0
	v_mul_f32_e32 v65, 0x3f317217, v62
	v_fma_f32 v65, v62, s34, -v65
	v_fmac_f32_e32 v65, 0x3377d1cf, v62
	v_fmac_f32_e32 v65, 0x3f317217, v62
	v_cmp_lt_f32_e64 s[0:1], |v62|, s35
	s_nop 1
	v_cndmask_b32_e64 v62, v62, v65, s[0:1]
	v_cndmask_b32_e32 v65, 0, v242, vcc
	v_sub_f32_e32 v62, v62, v65
	v_add_f32_e32 v62, v64, v62
	v_sub_f32_e32 v62, -0.5, v62
	v_mul_f32_e32 v62, 0x3fb8aa3b, v62
	v_exp_f32_e32 v62, v62
	v_and_b32_e32 v65, 0xffff0000, v71
	v_xor_b32_e32 v70, 0x80000000, v62
	v_add_f32_e32 v62, v63, v87
	v_max_f32_e64 v63, -v62, 0
	v_mul_f32_e64 v62, |v62|, s26
	v_exp_f32_e32 v62, v62
	s_nop 0
	v_add_f32_e32 v62, 1.0, v62
	v_cmp_gt_f32_e32 vcc, s6, v62
	s_nop 1
	v_cndmask_b32_e64 v64, 0, 32, vcc
	v_ldexp_f32 v62, v62, v64
	v_log_f32_e32 v62, v62
	s_nop 0
	v_mul_f32_e32 v64, 0x3f317217, v62
	v_fma_f32 v64, v62, s34, -v64
	v_fmac_f32_e32 v64, 0x3377d1cf, v62
	v_fmac_f32_e32 v64, 0x3f317217, v62
	v_cmp_lt_f32_e64 s[0:1], |v62|, s35
	s_nop 1
	v_cndmask_b32_e64 v62, v62, v64, s[0:1]
	v_cndmask_b32_e32 v64, 0, v242, vcc
	v_sub_f32_e32 v62, v62, v64
	v_add_f32_e32 v62, v63, v62
	v_sub_f32_e32 v62, -0.5, v62
	v_mul_f32_e32 v62, 0x3fb8aa3b, v62
	v_exp_f32_e32 v62, v62
	v_and_b32_e32 v63, 0xffff0000, v75
	v_lshlrev_b32_e32 v64, 16, v71
	v_xor_b32_e32 v73, 0x80000000, v62
	v_lshlrev_b32_e32 v62, 16, v75
	v_pk_fma_f32 v[64:65], v[178:179], v[64:65], v[62:63] op_sel_hi:[0,1,1] neg_lo:[0,0,1] neg_hi:[0,0,1]
	v_pk_fma_f32 v[210:211], v[66:67], v[64:65], v[62:63]
	v_rcp_f32_e32 v207, v59
	v_rcp_f32_e32 v206, v58
	s_nop 0
	v_pk_add_f32 v[58:59], v[206:207], -1.0 op_sel_hi:[1,0]
	v_lshlrev_b32_e32 v64, 16, v36
	v_pk_fma_f32 v[58:59], v[82:83], v[58:59], 1.0 op_sel_hi:[1,1,0]
	v_and_b32_e32 v65, 0xffff0000, v36
	v_pk_mul_f32 v[58:59], v[210:211], v[58:59]
	v_lshlrev_b32_e32 v36, 16, v37
	v_pk_mul_f32 v[62:63], v[218:219], v[58:59]
	v_and_b32_e32 v37, 0xffff0000, v37
	v_fmac_f32_e32 v159, v78, v62
	v_fmac_f32_e32 v159, v79, v63
	v_lshlrev_b32_e32 v62, 16, v44
	v_and_b32_e32 v63, 0xffff0000, v44
	v_lshlrev_b32_e32 v44, 16, v45
	v_and_b32_e32 v45, 0xffff0000, v45
	v_pk_fma_f32 v[36:37], v[178:179], v[36:37], v[44:45] op_sel_hi:[0,1,1] neg_lo:[0,0,1] neg_hi:[0,0,1]
	v_pk_fma_f32 v[36:37], v[54:55], v[36:37], v[44:45]
	v_lshlrev_b32_e32 v44, 16, v46
	v_and_b32_e32 v45, 0xffff0000, v46
	v_lshlrev_b32_e32 v54, 16, v38
	v_and_b32_e32 v55, 0xffff0000, v38
	v_pk_fma_f32 v[54:55], v[178:179], v[54:55], v[44:45] op_sel_hi:[0,1,1] neg_lo:[0,0,1] neg_hi:[0,0,1]
	v_pk_fma_f32 v[44:45], v[32:33], v[54:55], v[44:45]
	v_lshlrev_b32_e32 v32, 16, v47
	v_and_b32_e32 v33, 0xffff0000, v47
	v_lshlrev_b32_e32 v38, 16, v39
	v_and_b32_e32 v39, 0xffff0000, v39
	v_pk_fma_f32 v[38:39], v[178:179], v[38:39], v[32:33] op_sel_hi:[0,1,1] neg_lo:[0,0,1] neg_hi:[0,0,1]
	v_pk_fma_f32 v[64:65], v[178:179], v[64:65], v[62:63] op_sel_hi:[0,1,1] neg_lo:[0,0,1] neg_hi:[0,0,1]
	v_pk_fma_f32 v[38:39], v[34:35], v[38:39], v[32:33]
	v_cvt_pk_bf16_f32 v32, v208, v209
	v_cvt_pk_bf16_f32 v33, v214, v215
	v_cvt_pk_bf16_f32 v34, v216, v217
	v_cvt_pk_bf16_f32 v35, v218, v219
	v_mad_i64_i32 v[208:209], s[0:1], v176, s23, v[154:155]
	v_pk_fma_f32 v[52:53], v[52:53], v[64:65], v[62:63]
	global_store_dwordx4 v[208:209], v[32:35], off
	s_nop 1
	v_cvt_pk_bf16_f32 v32, v92, v93
	v_cvt_pk_bf16_f32 v33, v68, v69
	v_cvt_pk_bf16_f32 v34, v56, v57
	v_cvt_pk_bf16_f32 v35, v58, v59
	global_store_dwordx4 v[208:209], v[32:35], off offset:512
	s_nop 1
	v_cvt_pk_bf16_f32 v32, v52, v53
	v_cvt_pk_bf16_f32 v33, v36, v37
	v_cvt_pk_bf16_f32 v34, v44, v45
	v_cvt_pk_bf16_f32 v35, v38, v39
	global_store_dwordx4 v[208:209], v[32:35], off offset:1024
	s_nop 1
	v_cvt_pk_bf16_f32 v32, v96, v97
	v_cvt_pk_bf16_f32 v33, v72, v94
	v_cvt_pk_bf16_f32 v34, v60, v61
	v_cvt_pk_bf16_f32 v35, v70, v73
	global_store_dwordx4 v[208:209], v[32:35], off offset:2560
	s_nop 1
	v_cvt_pk_bf16_f32 v32, v48, v49
	v_cvt_pk_bf16_f32 v33, v50, v51
	v_cvt_pk_bf16_f32 v34, v40, v41
	v_cvt_pk_bf16_f32 v35, v42, v43
	global_store_dwordx4 v[212:213], v[32:35], off
	s_nop 1
	v_lshl_add_u64 v[32:33], v[180:181], 0, v[170:171]
	global_load_dwordx4 v[108:111], v[32:33], off
	v_lshl_add_u64 v[32:33], v[182:183], 0, v[170:171]
	global_load_dwordx4 v[112:115], v[32:33], off
	global_load_dwordx4 v[104:107], v[142:143], off offset:144
	global_load_dwordx4 v[214:217], v[142:143], off offset:128
	v_lshl_add_u64 v[32:33], v[180:181], 0, v[172:173]
	global_load_dwordx4 v[60:63], v[32:33], off
	v_lshl_add_u64 v[32:33], v[182:183], 0, v[172:173]
	global_load_dwordx4 v[56:59], v[32:33], off
	global_load_dwordx4 v[52:55], v[142:143], off offset:1168
	global_load_dwordx4 v[84:87], v[142:143], off offset:1152
	v_lshl_add_u64 v[32:33], v[180:181], 0, v[174:175]
	global_load_dwordx4 v[40:43], v[32:33], off
	v_lshl_add_u64 v[32:33], v[182:183], 0, v[174:175]
	global_load_dwordx4 v[36:39], v[32:33], off
	s_nop 0
	global_load_dwordx4 v[32:35], v[142:143], off offset:2192
	global_load_dwordx4 v[44:47], v[142:143], off offset:2176
	global_load_dwordx4 v[64:67], v[144:145], off offset:144
	global_load_dwordx4 v[96:99], v[144:145], off offset:128
	global_load_dwordx4 v[80:83], v[146:147], off offset:144
	global_load_dwordx4 v[100:103], v[146:147], off offset:128
	global_load_dwordx4 v[68:71], v[148:149], off offset:144
	global_load_dwordx4 v[48:51], v[148:149], off offset:128
	global_load_dwordx4 v[76:79], v[150:151], off offset:144
	global_load_dwordx4 v[92:95], v[150:151], off offset:128
	global_load_dwordx4 v[72:75], v[152:153], off offset:144
	global_load_dwordx4 v[88:91], v[152:153], off offset:128
	s_waitcnt vmcnt(0) lgkmcnt(0)
	v_lshlrev_b32_e32 v180, 16, v108
	v_and_b32_e32 v181, 0xffff0000, v108
	v_add_f32_e32 v28, v28, v96
	v_max_f32_e64 v96, -v28, 0
	v_mul_f32_e64 v28, |v28|, s26
	v_lshlrev_b32_e32 v182, 16, v112
	v_and_b32_e32 v183, 0xffff0000, v112
	v_lshlrev_b32_e32 v108, 16, v109
	v_and_b32_e32 v109, 0xffff0000, v109
	v_lshlrev_b32_e32 v112, 16, v113
	v_and_b32_e32 v113, 0xffff0000, v113
	v_exp_f32_e32 v28, v28
	v_pk_fma_f32 v[182:183], v[178:179], v[182:183], v[180:181] op_sel_hi:[0,1,1] neg_lo:[0,0,1] neg_hi:[0,0,1]
	v_pk_fma_f32 v[112:113], v[178:179], v[112:113], v[108:109] op_sel_hi:[0,1,1] neg_lo:[0,0,1] neg_hi:[0,0,1]
	v_pk_fma_f32 v[180:181], v[214:215], v[182:183], v[180:181]
	v_pk_fma_f32 v[108:109], v[216:217], v[112:113], v[108:109]
	v_lshlrev_b32_e32 v112, 16, v110
	v_and_b32_e32 v113, 0xffff0000, v110
	v_lshlrev_b32_e32 v182, 16, v114
	v_and_b32_e32 v183, 0xffff0000, v114
	v_pk_fma_f32 v[182:183], v[178:179], v[182:183], v[112:113] op_sel_hi:[0,1,1] neg_lo:[0,0,1] neg_hi:[0,0,1]
	v_pk_fma_f32 v[104:105], v[104:105], v[182:183], v[112:113]
	v_lshlrev_b32_e32 v110, 16, v111
	v_and_b32_e32 v111, 0xffff0000, v111
	v_lshlrev_b32_e32 v112, 16, v115
	v_and_b32_e32 v113, 0xffff0000, v115
	v_add_f32_e32 v28, 1.0, v28
	v_pk_fma_f32 v[112:113], v[178:179], v[112:113], v[110:111] op_sel_hi:[0,1,1] neg_lo:[0,0,1] neg_hi:[0,0,1]
	v_cmp_gt_f32_e32 vcc, s6, v28
	v_pk_fma_f32 v[106:107], v[106:107], v[112:113], v[110:111]
	v_add_f32_e32 v24, v24, v100
	v_cndmask_b32_e64 v110, 0, 32, vcc
	v_ldexp_f32 v28, v28, v110
	v_log_f32_e32 v28, v28
	v_add_f32_e32 v25, v25, v101
	v_mul_f32_e32 v24, 0xbfb8aa3b, v24
	v_mul_f32_e32 v25, 0xbfb8aa3b, v25
	v_mul_f32_e32 v110, 0x3f317217, v28
	v_fma_f32 v110, v28, s34, -v110
	v_fmac_f32_e32 v110, 0x3377d1cf, v28
	v_fmac_f32_e32 v110, 0x3f317217, v28
	v_cmp_lt_f32_e64 s[0:1], |v28|, s35
	v_exp_f32_e32 v24, v24
	v_exp_f32_e32 v25, v25
	v_cndmask_b32_e64 v28, v28, v110, s[0:1]
	v_cndmask_b32_e32 v110, 0, v242, vcc
	v_sub_f32_e32 v28, v28, v110
	v_add_f32_e32 v28, v96, v28
	v_sub_f32_e32 v28, -0.5, v28
	v_mul_f32_e32 v28, 0x3fb8aa3b, v28
	v_exp_f32_e32 v28, v28
	v_pk_add_f32 v[24:25], v[24:25], 1.0 op_sel_hi:[1,0]
	v_lshlrev_b32_e32 v100, 16, v56
	v_and_b32_e32 v101, 0xffff0000, v56
	v_xor_b32_e32 v96, 0x80000000, v28
	v_add_f32_e32 v28, v29, v97
	v_max_f32_e64 v29, -v28, 0
	v_mul_f32_e64 v28, |v28|, s26
	v_exp_f32_e32 v28, v28
	v_add_f32_e32 v30, v30, v98
	v_add_f32_e32 v26, v26, v102
	v_add_f32_e32 v27, v27, v103
	v_add_f32_e32 v28, 1.0, v28
	v_cmp_gt_f32_e32 vcc, s6, v28
	v_mul_f32_e32 v26, 0xbfb8aa3b, v26
	v_mul_f32_e32 v27, 0xbfb8aa3b, v27
	v_cndmask_b32_e64 v97, 0, 32, vcc
	v_ldexp_f32 v28, v28, v97
	v_log_f32_e32 v28, v28
	v_exp_f32_e32 v26, v26
	v_exp_f32_e32 v27, v27
	v_add_f32_e32 v20, v20, v64
	v_mul_f32_e32 v97, 0x3f317217, v28
	v_fma_f32 v97, v28, s34, -v97
	v_fmac_f32_e32 v97, 0x3377d1cf, v28
	v_fmac_f32_e32 v97, 0x3f317217, v28
	v_cmp_lt_f32_e64 s[0:1], |v28|, s35
	v_pk_add_f32 v[26:27], v[26:27], 1.0 op_sel_hi:[1,0]
	v_add_f32_e32 v16, v16, v80
	v_cndmask_b32_e64 v28, v28, v97, s[0:1]
	v_cndmask_b32_e32 v97, 0, v242, vcc
	v_sub_f32_e32 v28, v28, v97
	v_add_f32_e32 v28, v29, v28
	v_sub_f32_e32 v28, -0.5, v28
	v_mul_f32_e32 v28, 0x3fb8aa3b, v28
	v_exp_f32_e32 v28, v28
	v_and_b32_e32 v29, 0xffff0000, v60
	v_xor_b32_e32 v97, 0x80000000, v28
	v_lshlrev_b32_e32 v28, 16, v60
	v_pk_fma_f32 v[100:101], v[178:179], v[100:101], v[28:29] op_sel_hi:[0,1,1] neg_lo:[0,0,1] neg_hi:[0,0,1]
	v_pk_fma_f32 v[28:29], v[84:85], v[100:101], v[28:29]
	v_add_f32_e32 v17, v17, v81
	v_rcp_f32_e32 v25, v25
	v_mul_f32_e32 v16, 0xbfb8aa3b, v16
	v_mul_f32_e32 v17, 0xbfb8aa3b, v17
	v_exp_f32_e32 v16, v16
	v_rcp_f32_e32 v24, v24
	v_max_f32_e64 v56, -v30, 0
	v_mul_f32_e64 v30, |v30|, s26
	v_exp_f32_e32 v30, v30
	v_pk_add_f32 v[84:85], v[24:25], -1.0 op_sel_hi:[1,0]
	v_exp_f32_e32 v17, v17
	v_pk_fma_f32 v[84:85], v[92:93], v[84:85], 1.0 op_sel_hi:[1,1,0]
	v_add_f32_e32 v30, 1.0, v30
	v_cmp_gt_f32_e32 vcc, s6, v30
	v_pk_mul_f32 v[84:85], v[28:29], v[84:85]
	v_pk_add_f32 v[16:17], v[16:17], 1.0 op_sel_hi:[1,0]
	v_cndmask_b32_e64 v60, 0, 32, vcc
	v_ldexp_f32 v30, v30, v60
	v_log_f32_e32 v30, v30
	v_pk_mul_f32 v[92:93], v[180:181], v[84:85]
	v_add_f32_e32 v22, v22, v66
	v_fmac_f32_e32 v159, v88, v92
	v_mul_f32_e32 v60, 0x3f317217, v30
	v_fma_f32 v60, v30, s34, -v60
	v_fmac_f32_e32 v60, 0x3377d1cf, v30
	v_fmac_f32_e32 v60, 0x3f317217, v30
	v_cmp_lt_f32_e64 s[0:1], |v30|, s35
	v_fmac_f32_e32 v159, v89, v93
	v_add_f32_e32 v18, v18, v82
	v_cndmask_b32_e64 v30, v30, v60, s[0:1]
	v_cndmask_b32_e32 v60, 0, v242, vcc
	v_sub_f32_e32 v30, v30, v60
	v_add_f32_e32 v30, v56, v30
	v_sub_f32_e32 v30, -0.5, v30
	v_mul_f32_e32 v30, 0x3fb8aa3b, v30
	v_exp_f32_e32 v30, v30
	v_add_f32_e32 v19, v19, v83
	v_mul_f32_e32 v18, 0xbfb8aa3b, v18
	v_mul_f32_e32 v19, 0xbfb8aa3b, v19
	v_xor_b32_e32 v88, 0x80000000, v30
	v_add_f32_e32 v30, v31, v99
	v_max_f32_e64 v31, -v30, 0
	v_mul_f32_e64 v30, |v30|, s26
	v_exp_f32_e32 v30, v30
	v_exp_f32_e32 v18, v18
	v_exp_f32_e32 v19, v19
	v_lshlrev_b32_e32 v66, 16, v36
	v_add_f32_e32 v30, 1.0, v30
	v_cmp_gt_f32_e32 vcc, s6, v30
	v_pk_add_f32 v[18:19], v[18:19], 1.0 op_sel_hi:[1,0]
	v_pk_mul_f32 v[28:29], v[28:29], v[48:49]
	v_cndmask_b32_e64 v56, 0, 32, vcc
	v_ldexp_f32 v30, v30, v56
	v_log_f32_e32 v30, v30
	s_nop 0
	v_mul_f32_e32 v56, 0x3f317217, v30
	v_fma_f32 v56, v30, s34, -v56
	v_fmac_f32_e32 v56, 0x3377d1cf, v30
	v_fmac_f32_e32 v56, 0x3f317217, v30
	v_cmp_lt_f32_e64 s[0:1], |v30|, s35
	s_nop 1
	v_cndmask_b32_e64 v30, v30, v56, s[0:1]
	v_cndmask_b32_e32 v56, 0, v242, vcc
	v_sub_f32_e32 v30, v30, v56
	v_add_f32_e32 v30, v31, v30
	v_sub_f32_e32 v30, -0.5, v30
	v_mul_f32_e32 v30, 0x3fb8aa3b, v30
	v_exp_f32_e32 v30, v30
	v_and_b32_e32 v31, 0xffff0000, v61
	v_lshlrev_b32_e32 v56, 16, v57
	v_and_b32_e32 v57, 0xffff0000, v57
	v_xor_b32_e32 v89, 0x80000000, v30
	v_lshlrev_b32_e32 v30, 16, v61
	v_pk_fma_f32 v[56:57], v[178:179], v[56:57], v[30:31] op_sel_hi:[0,1,1] neg_lo:[0,0,1] neg_hi:[0,0,1]
	v_pk_fma_f32 v[30:31], v[86:87], v[56:57], v[30:31]
	v_rcp_f32_e32 v27, v27
	v_rcp_f32_e32 v26, v26
	s_nop 0
	v_pk_add_f32 v[56:57], v[26:27], -1.0 op_sel_hi:[1,0]
	s_nop 0
	v_pk_fma_f32 v[56:57], v[94:95], v[56:57], 1.0 op_sel_hi:[1,1,0]
	s_nop 0
	v_pk_mul_f32 v[56:57], v[30:31], v[56:57]
	v_pk_mul_f32 v[30:31], v[30:31], v[50:51]
	v_pk_mul_f32 v[60:61], v[108:109], v[56:57]
	v_pk_mul_f32 v[50:51], v[30:31], v[30:31]
	v_fmac_f32_e32 v159, v90, v60
	v_max_f32_e64 v60, -v20, 0
	v_mul_f32_e64 v20, |v20|, s26
	v_exp_f32_e32 v20, v20
	v_fmac_f32_e32 v159, v91, v61
	v_add_f32_e32 v20, 1.0, v20
	v_cmp_gt_f32_e32 vcc, s6, v20
	s_nop 1
	v_cndmask_b32_e64 v61, 0, 32, vcc
	v_ldexp_f32 v20, v20, v61
	v_log_f32_e32 v20, v20
	s_nop 0
	v_mul_f32_e32 v61, 0x3f317217, v20
	v_fma_f32 v61, v20, s34, -v61
	v_fmac_f32_e32 v61, 0x3377d1cf, v20
	v_fmac_f32_e32 v61, 0x3f317217, v20
	v_cmp_lt_f32_e64 s[0:1], |v20|, s35
	s_nop 1
	v_cndmask_b32_e64 v20, v20, v61, s[0:1]
	v_cndmask_b32_e32 v61, 0, v242, vcc
	v_sub_f32_e32 v20, v20, v61
	v_add_f32_e32 v20, v60, v20
	v_sub_f32_e32 v20, -0.5, v20
	v_mul_f32_e32 v20, 0x3fb8aa3b, v20
	v_exp_f32_e32 v20, v20
	v_and_b32_e32 v61, 0xffff0000, v58
	v_xor_b32_e32 v64, 0x80000000, v20
	v_add_f32_e32 v20, v21, v65
	v_max_f32_e64 v21, -v20, 0
	v_mul_f32_e64 v20, |v20|, s26
	v_exp_f32_e32 v20, v20
	s_nop 0
	v_add_f32_e32 v20, 1.0, v20
	v_cmp_gt_f32_e32 vcc, s6, v20
	s_nop 1
	v_cndmask_b32_e64 v60, 0, 32, vcc
	v_ldexp_f32 v20, v20, v60
	v_log_f32_e32 v20, v20
	s_nop 0
	v_mul_f32_e32 v60, 0x3f317217, v20
	v_fma_f32 v60, v20, s34, -v60
	v_fmac_f32_e32 v60, 0x3377d1cf, v20
	v_fmac_f32_e32 v60, 0x3f317217, v20
	v_cmp_lt_f32_e64 s[0:1], |v20|, s35
	s_nop 1
	v_cndmask_b32_e64 v20, v20, v60, s[0:1]
	v_cndmask_b32_e32 v60, 0, v242, vcc
	v_sub_f32_e32 v20, v20, v60
	v_add_f32_e32 v20, v21, v20
	v_sub_f32_e32 v20, -0.5, v20
	v_mul_f32_e32 v20, 0x3fb8aa3b, v20
	v_exp_f32_e32 v20, v20
	v_and_b32_e32 v21, 0xffff0000, v62
	v_lshlrev_b32_e32 v60, 16, v58
	v_xor_b32_e32 v65, 0x80000000, v20
	v_lshlrev_b32_e32 v20, 16, v62
	v_pk_fma_f32 v[60:61], v[178:179], v[60:61], v[20:21] op_sel_hi:[0,1,1] neg_lo:[0,0,1] neg_hi:[0,0,1]
	v_pk_fma_f32 v[20:21], v[52:53], v[60:61], v[20:21]
	v_rcp_f32_e32 v17, v17
	v_max_f32_e64 v58, -v22, 0
	v_mul_f32_e64 v22, |v22|, s26
	v_exp_f32_e32 v22, v22
	v_rcp_f32_e32 v16, v16
	s_nop 0
	v_pk_add_f32 v[52:53], v[16:17], -1.0 op_sel_hi:[1,0]
	v_add_f32_e32 v22, 1.0, v22
	v_cmp_gt_f32_e32 vcc, s6, v22
	v_pk_fma_f32 v[52:53], v[76:77], v[52:53], 1.0 op_sel_hi:[1,1,0]
	s_nop 0
	v_cndmask_b32_e64 v62, 0, 32, vcc
	v_ldexp_f32 v22, v22, v62
	v_log_f32_e32 v22, v22
	v_pk_mul_f32 v[60:61], v[20:21], v[52:53]
	v_pk_mul_f32 v[20:21], v[20:21], v[68:69]
	v_pk_mul_f32 v[76:77], v[104:105], v[60:61]
	v_mul_f32_e32 v62, 0x3f317217, v22
	v_fma_f32 v62, v22, s34, -v62
	v_fmac_f32_e32 v62, 0x3377d1cf, v22
	v_fmac_f32_e32 v62, 0x3f317217, v22
	v_cmp_lt_f32_e64 s[0:1], |v22|, s35
	v_fmac_f32_e32 v159, v72, v76
	v_fmac_f32_e32 v159, v73, v77
	v_cndmask_b32_e64 v22, v22, v62, s[0:1]
	v_cndmask_b32_e32 v62, 0, v242, vcc
	v_sub_f32_e32 v22, v22, v62
	v_add_f32_e32 v22, v58, v22
	v_sub_f32_e32 v22, -0.5, v22
	v_mul_f32_e32 v22, 0x3fb8aa3b, v22
	v_exp_f32_e32 v22, v22
	v_pk_mul_f32 v[52:53], v[20:21], v[20:21]
	v_xor_b32_e32 v68, 0x80000000, v22
	v_add_f32_e32 v22, v23, v67
	v_max_f32_e64 v23, -v22, 0
	v_mul_f32_e64 v22, |v22|, s26
	v_exp_f32_e32 v22, v22
	v_and_b32_e32 v67, 0xffff0000, v36
	v_lshlrev_b32_e32 v36, 16, v37
	v_and_b32_e32 v37, 0xffff0000, v37
	v_add_f32_e32 v22, 1.0, v22
	v_cmp_gt_f32_e32 vcc, s6, v22
	s_nop 1
	v_cndmask_b32_e64 v58, 0, 32, vcc
	v_ldexp_f32 v22, v22, v58
	v_log_f32_e32 v22, v22
	s_nop 0
	v_mul_f32_e32 v58, 0x3f317217, v22
	v_fma_f32 v58, v22, s34, -v58
	v_fmac_f32_e32 v58, 0x3377d1cf, v22
	v_fmac_f32_e32 v58, 0x3f317217, v22
	v_cmp_lt_f32_e64 s[0:1], |v22|, s35
	s_nop 1
	v_cndmask_b32_e64 v22, v22, v58, s[0:1]
	v_cndmask_b32_e32 v58, 0, v242, vcc
	v_sub_f32_e32 v22, v22, v58
	v_add_f32_e32 v22, v23, v22
	v_sub_f32_e32 v22, -0.5, v22
	v_mul_f32_e32 v22, 0x3fb8aa3b, v22
	v_exp_f32_e32 v22, v22
	v_and_b32_e32 v23, 0xffff0000, v63
	v_lshlrev_b32_e32 v58, 16, v59
	v_and_b32_e32 v59, 0xffff0000, v59
	v_xor_b32_e32 v69, 0x80000000, v22
	v_lshlrev_b32_e32 v22, 16, v63
	v_pk_fma_f32 v[58:59], v[178:179], v[58:59], v[22:23] op_sel_hi:[0,1,1] neg_lo:[0,0,1] neg_hi:[0,0,1]
	v_pk_fma_f32 v[22:23], v[54:55], v[58:59], v[22:23]
	v_rcp_f32_e32 v19, v19
	v_rcp_f32_e32 v18, v18
	s_nop 0
	v_pk_add_f32 v[54:55], v[18:19], -1.0 op_sel_hi:[1,0]
	s_nop 0
	v_pk_fma_f32 v[54:55], v[78:79], v[54:55], 1.0 op_sel_hi:[1,1,0]
	s_nop 0
	v_pk_mul_f32 v[54:55], v[22:23], v[54:55]
	v_pk_mul_f32 v[22:23], v[22:23], v[70:71]
	v_pk_mul_f32 v[58:59], v[106:107], v[54:55]
	v_pk_mul_f32 v[62:63], v[22:23], v[22:23]
	v_fmac_f32_e32 v159, v74, v58
	v_fmac_f32_e32 v159, v75, v59
	v_lshlrev_b32_e32 v58, 16, v40
	v_and_b32_e32 v59, 0xffff0000, v40
	v_lshlrev_b32_e32 v40, 16, v41
	v_and_b32_e32 v41, 0xffff0000, v41
	v_pk_fma_f32 v[36:37], v[178:179], v[36:37], v[40:41] op_sel_hi:[0,1,1] neg_lo:[0,0,1] neg_hi:[0,0,1]
	v_pk_fma_f32 v[36:37], v[46:47], v[36:37], v[40:41]
	v_lshlrev_b32_e32 v40, 16, v42
	v_and_b32_e32 v41, 0xffff0000, v42
	v_lshlrev_b32_e32 v46, 16, v38
	v_and_b32_e32 v47, 0xffff0000, v38
	v_pk_fma_f32 v[46:47], v[178:179], v[46:47], v[40:41] op_sel_hi:[0,1,1] neg_lo:[0,0,1] neg_hi:[0,0,1]
	v_pk_fma_f32 v[40:41], v[32:33], v[46:47], v[40:41]
	v_lshlrev_b32_e32 v32, 16, v43
	v_and_b32_e32 v33, 0xffff0000, v43
	v_lshlrev_b32_e32 v38, 16, v39
	v_and_b32_e32 v39, 0xffff0000, v39
	v_pk_fma_f32 v[38:39], v[178:179], v[38:39], v[32:33] op_sel_hi:[0,1,1] neg_lo:[0,0,1] neg_hi:[0,0,1]
	v_pk_fma_f32 v[66:67], v[178:179], v[66:67], v[58:59] op_sel_hi:[0,1,1] neg_lo:[0,0,1] neg_hi:[0,0,1]
	v_pk_fma_f32 v[38:39], v[34:35], v[38:39], v[32:33]
	v_cvt_pk_bf16_f32 v32, v180, v181
	v_cvt_pk_bf16_f32 v33, v108, v109
	v_cvt_pk_bf16_f32 v34, v104, v105
	v_cvt_pk_bf16_f32 v35, v106, v107
	v_pk_fma_f32 v[44:45], v[44:45], v[66:67], v[58:59]
	global_store_dwordx4 v[208:209], v[32:35], off offset:64
	s_nop 1
	v_cvt_pk_bf16_f32 v32, v84, v85
	v_cvt_pk_bf16_f32 v33, v56, v57
	v_cvt_pk_bf16_f32 v34, v60, v61
	v_cvt_pk_bf16_f32 v35, v54, v55
	global_store_dwordx4 v[208:209], v[32:35], off offset:576
	s_nop 1
	v_cvt_pk_bf16_f32 v32, v44, v45
	v_cvt_pk_bf16_f32 v33, v36, v37
	v_cvt_pk_bf16_f32 v34, v40, v41
	v_cvt_pk_bf16_f32 v35, v38, v39
	global_store_dwordx4 v[208:209], v[32:35], off offset:1088
	s_nop 1
	v_cvt_pk_bf16_f32 v32, v96, v97
	v_cvt_pk_bf16_f32 v33, v88, v89
	v_cvt_pk_bf16_f32 v34, v64, v65
	v_cvt_pk_bf16_f32 v35, v68, v69
	global_store_dwordx4 v[208:209], v[32:35], off offset:2624
	global_store_dwordx4 v[212:213], v[0:3], off offset:64
	s_nop 0
	v_pk_mul_f32 v[32:33], v[8:9], v[8:9]
	v_pk_mul_f32 v[2:3], v[210:211], v[14:15]
	v_pk_mul_f32 v[14:15], v[10:11], v[10:11]
	v_add_f32_e32 v32, v32, v33
	v_add_f32_e32 v14, v14, v32
	v_add_f32_e32 v14, v15, v14
	v_add_f32_e32 v12, v14, v12
	v_pk_mul_f32 v[4:5], v[2:3], v[2:3]
	v_add_f32_e32 v12, v13, v12
	v_add_f32_e32 v4, v4, v12
	v_pk_mul_f32 v[34:35], v[28:29], v[28:29]
	v_add_f32_e32 v4, v5, v4
	v_add_f32_e32 v4, v4, v34
	v_add_f32_e32 v4, v35, v4
	v_add_f32_e32 v4, v50, v4
	v_and_b32_e32 v1, 64, v243
	v_add_f32_e32 v4, v51, v4
	v_xor_b32_e32 v0, 16, v243
	v_add_u32_e32 v1, 64, v1
	v_add_f32_e32 v4, v4, v52
	v_cmp_lt_i32_e32 vcc, v0, v1
	v_add_f32_e32 v4, v53, v4
	v_add_f32_e32 v4, v62, v4
	v_cndmask_b32_e32 v0, v243, v0, vcc
	v_lshlrev_b32_e32 v36, 2, v0
	v_add_f32_e32 v4, v63, v4
	ds_bpermute_b32 v5, v36, v4
	v_xor_b32_e32 v0, 32, v243
	v_cmp_lt_i32_e32 vcc, v0, v1
	s_waitcnt lgkmcnt(0)
	v_add_f32_e32 v4, v4, v5
	v_cndmask_b32_e32 v0, v243, v0, vcc
	v_lshlrev_b32_e32 v37, 2, v0
	ds_bpermute_b32 v5, v37, v4
	ds_bpermute_b32 v0, v36, v159
	s_waitcnt lgkmcnt(0)
	v_add_f32_e32 v4, v4, v5
	v_cmp_gt_f32_e32 vcc, s36, v4
	v_mul_f32_e32 v5, 0x4f800000, v4
	v_add_f32_e32 v0, v159, v0
	v_cndmask_b32_e32 v4, v4, v5, vcc
	v_sqrt_f32_e32 v5, v4
	ds_bpermute_b32 v1, v37, v0
	v_add_u32_e32 v12, -1, v5
	v_fma_f32 v13, -v12, v5, v4
	v_cmp_ge_f32_e64 s[0:1], 0, v13
	v_add_u32_e32 v13, 1, v5
	s_nop 0
	v_cndmask_b32_e64 v12, v5, v12, s[0:1]
	v_fma_f32 v5, -v13, v5, v4
	v_cmp_lt_f32_e64 s[0:1], 0, v5
	s_nop 1
	v_cndmask_b32_e64 v5, v12, v13, s[0:1]
	v_mul_f32_e32 v12, 0x37800000, v5
	v_cndmask_b32_e32 v5, v5, v12, vcc
	v_cmp_class_f32_e32 vcc, v4, v237
	s_nop 1
	v_cndmask_b32_e32 v4, v5, v4, vcc
	v_max_f32_e32 v4, 0x2b8cbccc, v4
	v_rcp_f32_e32 v12, v4
	s_nop 0
	v_pk_mul_f32 v[4:5], v[8:9], v[12:13] op_sel_hi:[1,0]
	v_pk_mul_f32 v[10:11], v[10:11], v[12:13] op_sel_hi:[1,0]
	v_pk_mul_f32 v[6:7], v[6:7], v[12:13] op_sel_hi:[1,0]
	v_pk_mul_f32 v[34:35], v[2:3], v[12:13] op_sel_hi:[1,0]
	v_pk_mul_f32 v[8:9], v[116:117], v[4:5]
	v_pk_mul_f32 v[14:15], v[118:119], v[10:11]
	v_pk_mul_f32 v[32:33], v[188:189], v[6:7]
	v_pk_mul_f32 v[36:37], v[206:207], v[34:35]
	v_cvt_pk_bf16_f32 v2, v4, v5
	v_cvt_pk_bf16_f32 v3, v10, v11
	v_cvt_pk_bf16_f32 v4, v6, v7
	v_cvt_pk_bf16_f32 v5, v34, v35
	global_store_dwordx4 v[208:209], v[2:5], off offset:1536
	v_pk_mul_f32 v[10:11], v[20:21], v[12:13] op_sel_hi:[1,0]
	s_nop 0
	v_cvt_pk_bf16_f32 v2, v8, v9
	v_cvt_pk_bf16_f32 v3, v14, v15
	v_cvt_pk_bf16_f32 v4, v32, v33
	v_cvt_pk_bf16_f32 v5, v36, v37
	global_store_dwordx4 v[208:209], v[2:5], off offset:2048
	v_pk_mul_f32 v[14:15], v[16:17], v[10:11]
	s_nop 0
	v_pk_mul_f32 v[2:3], v[28:29], v[12:13] op_sel_hi:[1,0]
	v_pk_mul_f32 v[4:5], v[30:31], v[12:13] op_sel_hi:[1,0]
	v_pk_mul_f32 v[12:13], v[22:23], v[12:13] op_sel_hi:[1,0]
	v_pk_mul_f32 v[6:7], v[24:25], v[2:3]
	v_pk_mul_f32 v[8:9], v[26:27], v[4:5]
	v_pk_mul_f32 v[16:17], v[18:19], v[12:13]
	v_cvt_pk_bf16_f32 v2, v2, v3
	v_cvt_pk_bf16_f32 v3, v4, v5
	v_cvt_pk_bf16_f32 v4, v10, v11
	v_cvt_pk_bf16_f32 v5, v12, v13
	global_store_dwordx4 v[208:209], v[2:5], off offset:1600
	s_nop 1
	v_cvt_pk_bf16_f32 v2, v6, v7
	v_cvt_pk_bf16_f32 v3, v8, v9
	v_cvt_pk_bf16_f32 v4, v14, v15
	v_cvt_pk_bf16_f32 v5, v16, v17
	global_store_dwordx4 v[208:209], v[2:5], off offset:2112
	s_and_saveexec_b64 s[0:1], s[8:9]
	s_cbranch_execz .LBB0_341
	v_lshl_add_u64 v[2:3], v[176:177], 4, s[16:17]
	s_waitcnt lgkmcnt(0)
	v_add_f32_e32 v0, v0, v1
	global_store_dword v[2:3], v0, off
	s_branch .LBB0_341

.LBB0_347:
	s_and_b32 s0, s3, -16
	s_addk_i32 s0, 0x4000
	v_or_b32_e32 v206, s0, v193
	s_waitcnt lgkmcnt(0)
	v_mov_b64_e32 v[0:1], s[10:11]
	v_mad_i64_i32 v[0:1], s[0:1], v206, s86, v[0:1]
	s_mov_b64 s[0:1], 0x2040c00
	s_nop 0
	v_lshl_add_u64 v[208:209], v[0:1], 0, s[0:1]
	v_add_u32_e32 v0, 0xffffc000, v206
	v_ashrrev_i32_e32 v1, 31, v0
	v_lshl_add_u64 v[0:1], v[0:1], 0, s[42:43]
	v_mov_b64_e32 v[2:3], s[46:47]
	s_movk_i32 s4, 0xe00
	v_mad_u64_u32 v[210:211], s[0:1], v0, s4, v[2:3]
	v_mad_i32_i24 v211, v1, s4, v211
	v_lshl_add_u64 v[0:1], v[208:209], 0, v[194:195]
	global_load_dwordx4 v[132:135], v[0:1], off
	v_mov_b32_e32 v175, v195
	v_lshl_add_u64 v[0:1], v[210:211], 0, v[174:175]
	global_load_dwordx4 v[128:131], v[0:1], off offset:3072
	global_load_dwordx4 v[212:215], v[0:1], off offset:3088
	global_load_dwordx4 v[84:87], v[136:137], off offset:3072
	global_load_dwordx4 v[216:219], v[136:137], off offset:3088
	v_mov_b32_e32 v177, v195
	v_lshl_add_u64 v[2:3], v[208:209], 0, v[176:177]
	v_mov_b32_e32 v179, v195
	global_load_dwordx4 v[108:111], v[2:3], off
	global_load_dwordx4 v[88:91], v[0:1], off offset:3216
	global_load_dwordx4 v[120:123], v[0:1], off offset:3200
	global_load_dwordx4 v[116:119], v[136:137], off offset:3216
	global_load_dwordx4 v[124:127], v[136:137], off offset:3200
	v_lshl_add_u64 v[2:3], v[208:209], 0, v[178:179]
	v_mov_b32_e32 v181, v195
	global_load_dwordx4 v[92:95], v[2:3], off
	global_load_dwordx4 v[96:99], v[0:1], off offset:3328
	global_load_dwordx4 v[104:107], v[0:1], off offset:3344
	global_load_dwordx4 v[100:103], v[136:137], off offset:3328
	global_load_dwordx4 v[112:115], v[136:137], off offset:3344
	v_lshl_add_u64 v[2:3], v[208:209], 0, v[180:181]
	global_load_dwordx4 v[64:67], v[2:3], off
	global_load_dwordx4 v[68:71], v[0:1], off offset:3456
	global_load_dwordx4 v[76:79], v[0:1], off offset:3472
	global_load_dwordx4 v[72:75], v[136:137], off offset:3456
	global_load_dwordx4 v[80:83], v[136:137], off offset:3472
	global_load_dwordx4 v[60:63], v[140:141], off
	global_load_dwordx4 v[56:59], v[140:141], off offset:64
	global_load_dwordx4 v[52:55], v[140:141], off offset:128
	global_load_dwordx4 v[28:31], v[140:141], off offset:192
	global_load_dwordx4 v[24:27], v[140:141], off offset:1024
	global_load_dwordx4 v[0:3], v[140:141], off offset:1088
	global_load_dwordx4 v[4:7], v[140:141], off offset:1152
	global_load_dwordx4 v[8:11], v[140:141], off offset:1216
	global_load_dwordx4 v[12:15], v[142:143], off
	global_load_dwordx4 v[16:19], v[144:145], off
	global_load_dwordx4 v[20:23], v[146:147], off
	global_load_dwordx4 v[32:35], v[148:149], off
	global_load_dwordx4 v[36:39], v[150:151], off
	global_load_dwordx4 v[40:43], v[152:153], off
	global_load_dwordx4 v[44:47], v[154:155], off
	global_load_dwordx4 v[48:51], v[156:157], off
	v_mov_b32_e32 v183, v195
	v_mov_b32_e32 v185, v195
	s_mov_b32 s4, 0x800000
	s_mov_b32 s5, 0x3f317217
	s_mov_b32 s6, 0x7f800000
	v_ashrrev_i32_e32 v207, 31, v206
	v_mov_b32_e32 v187, v195
	v_mov_b32_e32 v189, v195
	v_mov_b32_e32 v191, v195
	s_waitcnt vmcnt(0) lgkmcnt(0)
	v_and_b32_e32 v177, 0xffff0000, v132
	v_lshlrev_b32_e32 v179, 16, v133
	v_sub_f32_e32 v129, v129, v177
	v_and_b32_e32 v181, 0xffff0000, v133
	v_fmac_f32_e32 v177, v85, v129
	v_sub_f32_e32 v85, v130, v179
	v_lshlrev_b32_e32 v175, 16, v134
	v_fmac_f32_e32 v179, v86, v85
	v_sub_f32_e32 v85, v131, v181
	v_and_b32_e32 v139, 0xffff0000, v134
	v_fmac_f32_e32 v181, v87, v85
	v_sub_f32_e32 v85, v212, v175
	v_lshlrev_b32_e32 v134, 16, v135
	v_fmac_f32_e32 v175, v85, v216
	v_sub_f32_e32 v85, v213, v139
	v_and_b32_e32 v133, 0xffff0000, v135
	v_fmac_f32_e32 v139, v85, v217
	v_sub_f32_e32 v85, v214, v134
	v_fmac_f32_e32 v134, v85, v218
	v_sub_f32_e32 v85, v215, v133
	v_fmac_f32_e32 v133, v85, v219
	v_lshlrev_b32_e32 v85, 16, v132
	v_sub_f32_e32 v86, v128, v85
	v_fmac_f32_e32 v85, v84, v86
	v_add_f32_e32 v84, v85, v85
	v_add_f32_e32 v85, v177, v177
	v_mul_f32_e32 v84, 0x3fb8aa3b, v84
	v_mul_f32_e32 v85, 0x3fb8aa3b, v85
	v_exp_f32_e32 v84, v84
	v_exp_f32_e32 v85, v85
	v_lshlrev_b64 v[216:217], 9, v[206:207]
	v_lshl_add_u64 v[216:217], v[172:173], 0, v[216:217]
	v_pk_add_f32 v[84:85], v[84:85], 1.0 op_sel_hi:[1,0]
	s_nop 0
	v_rcp_f32_e32 v85, v85
	s_nop 0
	v_mul_f32_e32 v85, 2.0, v85
	v_rcp_f32_e32 v84, v84
	s_nop 0
	v_mul_f32_e32 v84, 2.0, v84
	v_add_f32_e32 v86, v179, v179
	v_add_f32_e32 v87, v181, v181
	v_mul_f32_e32 v86, 0x3fb8aa3b, v86
	v_mul_f32_e32 v87, 0x3fb8aa3b, v87
	v_exp_f32_e32 v86, v86
	v_exp_f32_e32 v87, v87
	v_pk_add_f32 v[84:85], v[84:85], 1.0 op_sel_hi:[1,0] neg_lo:[1,0] neg_hi:[1,0]
	v_pk_add_f32 v[86:87], v[86:87], 1.0 op_sel_hi:[1,0]
	s_nop 0
	v_cvt_pk_bf16_f32 v84, v84, v85
	v_rcp_f32_e32 v87, v87
	s_nop 0
	v_mul_f32_e32 v87, 2.0, v87
	v_rcp_f32_e32 v86, v86
	s_nop 0
	v_mul_f32_e32 v86, 2.0, v86
	v_add_f32_e32 v128, v175, v175
	v_add_f32_e32 v129, v139, v139
	v_mul_f32_e32 v128, 0x3fb8aa3b, v128
	v_mul_f32_e32 v129, 0x3fb8aa3b, v129
	v_exp_f32_e32 v128, v128
	v_exp_f32_e32 v129, v129
	v_pk_add_f32 v[86:87], v[86:87], 1.0 op_sel_hi:[1,0] neg_lo:[1,0] neg_hi:[1,0]
	v_pk_add_f32 v[128:129], v[128:129], 1.0 op_sel_hi:[1,0]
	s_nop 0
	v_cvt_pk_bf16_f32 v85, v86, v87
	v_rcp_f32_e32 v129, v129
	s_nop 0
	v_mul_f32_e32 v129, 2.0, v129
	v_rcp_f32_e32 v128, v128
	s_nop 0
	v_mul_f32_e32 v128, 2.0, v128
	v_add_f32_e32 v130, v134, v134
	v_add_f32_e32 v131, v133, v133
	v_pk_add_f32 v[128:129], v[128:129], 1.0 op_sel_hi:[1,0] neg_lo:[1,0] neg_hi:[1,0]
	v_mul_f32_e32 v130, 0x3fb8aa3b, v130
	v_mul_f32_e32 v131, 0x3fb8aa3b, v131
	v_exp_f32_e32 v130, v130
	v_exp_f32_e32 v131, v131
	v_cvt_pk_bf16_f32 v86, v128, v129
	v_lshlrev_b32_e32 v128, 16, v108
	v_and_b32_e32 v129, 0xffff0000, v108
	v_lshlrev_b32_e32 v108, 16, v109
	v_and_b32_e32 v109, 0xffff0000, v109
	v_pk_add_f32 v[122:123], v[122:123], v[108:109] neg_lo:[0,1] neg_hi:[0,1]
	v_pk_add_f32 v[130:131], v[130:131], 1.0 op_sel_hi:[1,0]
	v_pk_fma_f32 v[108:109], v[126:127], v[122:123], v[108:109]
	v_lshlrev_b32_e32 v122, 16, v110
	v_and_b32_e32 v123, 0xffff0000, v110
	v_pk_add_f32 v[88:89], v[88:89], v[122:123] neg_lo:[0,1] neg_hi:[0,1]
	s_nop 0
	v_pk_fma_f32 v[116:117], v[88:89], v[116:117], v[122:123]
	v_lshlrev_b32_e32 v88, 16, v111
	v_and_b32_e32 v89, 0xffff0000, v111
	v_pk_add_f32 v[90:91], v[90:91], v[88:89] neg_lo:[0,1] neg_hi:[0,1]
	s_nop 0
	v_pk_fma_f32 v[110:111], v[90:91], v[118:119], v[88:89]
	v_cvt_pk_bf16_f32 v89, v108, v109
	v_and_b32_e32 v108, 0xffff0000, v92
	v_cvt_pk_bf16_f32 v91, v110, v111
	v_lshlrev_b32_e32 v109, 16, v93
	v_and_b32_e32 v110, 0xffff0000, v93
	v_sub_f32_e32 v93, v97, v108
	v_fmac_f32_e32 v108, v101, v93
	v_sub_f32_e32 v93, v98, v109
	v_lshlrev_b32_e32 v111, 16, v94
	v_fmac_f32_e32 v109, v102, v93
	v_sub_f32_e32 v93, v99, v110
	v_and_b32_e32 v94, 0xffff0000, v94
	v_fmac_f32_e32 v110, v103, v93
	v_sub_f32_e32 v93, v104, v111
	v_cvt_pk_bf16_f32 v90, v116, v117
	v_lshlrev_b32_e32 v116, 16, v95
	v_fmac_f32_e32 v111, v93, v112
	v_sub_f32_e32 v93, v105, v94
	v_and_b32_e32 v95, 0xffff0000, v95
	v_fmac_f32_e32 v94, v93, v113
	v_sub_f32_e32 v93, v106, v116
	v_fmac_f32_e32 v116, v93, v114
	v_sub_f32_e32 v93, v107, v95
	v_lshlrev_b32_e32 v92, 16, v92
	v_fmac_f32_e32 v95, v93, v115
	v_sub_f32_e32 v93, v96, v92
	v_fmac_f32_e32 v92, v100, v93
	v_mul_f32_e32 v92, 0xbfb8aa3b, v92
	v_mul_f32_e32 v93, 0xbfb8aa3b, v108
	v_rcp_f32_e32 v131, v131
	s_nop 0
	v_mul_f32_e32 v131, 2.0, v131
	v_exp_f32_e32 v92, v92
	v_exp_f32_e32 v93, v93
	v_pk_add_f32 v[120:121], v[120:121], v[128:129] neg_lo:[0,1] neg_hi:[0,1]
	v_pk_add_f32 v[92:93], v[92:93], 1.0 op_sel_hi:[1,0]
	s_nop 0
	v_rcp_f32_e32 v96, v93
	v_rcp_f32_e32 v130, v130
	s_nop 0
	v_mul_f32_e32 v130, 2.0, v130
	v_pk_add_f32 v[130:131], v[130:131], 1.0 op_sel_hi:[1,0] neg_lo:[1,0] neg_hi:[1,0]
	v_pk_fma_f32 v[120:121], v[124:125], v[120:121], v[128:129]
	v_rcp_f32_e32 v97, v92
	v_mul_f32_e32 v92, 0xbfb8aa3b, v109
	v_mul_f32_e32 v93, 0xbfb8aa3b, v110
	v_exp_f32_e32 v92, v92
	v_exp_f32_e32 v93, v93
	v_cvt_pk_bf16_f32 v87, v130, v131
	v_cvt_pk_bf16_f32 v88, v120, v121
	v_pk_add_f32 v[92:93], v[92:93], 1.0 op_sel_hi:[1,0]
	s_nop 0
	v_rcp_f32_e32 v98, v93
	v_rcp_f32_e32 v99, v92
	v_mul_f32_e32 v92, 0xbfb8aa3b, v111
	v_mul_f32_e32 v93, 0xbfb8aa3b, v94
	v_exp_f32_e32 v92, v92
	v_exp_f32_e32 v93, v93
	s_nop 0
	v_pk_add_f32 v[92:93], v[92:93], 1.0 op_sel_hi:[1,0]
	s_nop 0
	v_rcp_f32_e32 v94, v93
	v_rcp_f32_e32 v100, v92
	v_mul_f32_e32 v92, 0xbfb8aa3b, v116
	v_mul_f32_e32 v93, 0xbfb8aa3b, v95
	v_exp_f32_e32 v92, v92
	v_exp_f32_e32 v93, v93
	v_cvt_pk_bf16_f32 v94, v100, v94
	v_lshlrev_b32_e32 v100, 16, v67
	v_and_b32_e32 v67, 0xffff0000, v67
	v_pk_add_f32 v[92:93], v[92:93], 1.0 op_sel_hi:[1,0]
	s_nop 0
	v_rcp_f32_e32 v95, v93
	v_rcp_f32_e32 v101, v92
	v_cvt_pk_bf16_f32 v92, v97, v96
	v_and_b32_e32 v96, 0xffff0000, v64
	v_cvt_pk_bf16_f32 v93, v99, v98
	v_lshlrev_b32_e32 v97, 16, v65
	v_and_b32_e32 v98, 0xffff0000, v65
	v_sub_f32_e32 v65, v69, v96
	v_fmac_f32_e32 v96, v73, v65
	v_sub_f32_e32 v65, v70, v97
	v_lshlrev_b32_e32 v99, 16, v66
	v_fmac_f32_e32 v97, v74, v65
	v_sub_f32_e32 v65, v71, v98
	v_and_b32_e32 v66, 0xffff0000, v66
	v_fmac_f32_e32 v98, v75, v65
	v_sub_f32_e32 v65, v76, v99
	v_fmac_f32_e32 v99, v65, v80
	v_sub_f32_e32 v65, v77, v66
	v_fmac_f32_e32 v66, v65, v81
	v_sub_f32_e32 v65, v78, v100
	v_fmac_f32_e32 v100, v65, v82
	v_sub_f32_e32 v65, v79, v67
	v_lshlrev_b32_e32 v64, 16, v64
	v_fmac_f32_e32 v67, v65, v83
	v_sub_f32_e32 v65, v68, v64
	v_fmac_f32_e32 v64, v72, v65
	v_mul_f32_e32 v64, 0xbfb8aa3b, v64
	v_mul_f32_e32 v65, 0xbfb8aa3b, v96
	v_exp_f32_e32 v64, v64
	v_exp_f32_e32 v65, v65
	v_cvt_pk_bf16_f32 v95, v101, v95
	v_pk_add_f32 v[64:65], v[64:65], 1.0 op_sel_hi:[1,0]
	s_nop 0
	v_mfma_f32_16x16x32_bf16 v[52:55], v[52:55], v[92:95], 0
	v_rcp_f32_e32 v68, v65
	v_rcp_f32_e32 v69, v64
	v_mul_f32_e32 v64, 0xbfb8aa3b, v97
	v_mul_f32_e32 v65, 0xbfb8aa3b, v98
	v_exp_f32_e32 v64, v64
	v_exp_f32_e32 v65, v65
	v_cvt_pk_bf16_f32 v68, v69, v68
	v_pk_add_f32 v[64:65], v[64:65], 1.0 op_sel_hi:[1,0]
	s_nop 0
	v_rcp_f32_e32 v70, v65
	v_rcp_f32_e32 v71, v64
	v_mul_f32_e32 v64, 0xbfb8aa3b, v99
	v_mul_f32_e32 v65, 0xbfb8aa3b, v66
	v_exp_f32_e32 v64, v64
	v_exp_f32_e32 v65, v65
	v_cvt_pk_bf16_f32 v69, v71, v70
	v_mfma_f32_16x16x32_bf16 v[96:99], v[56:59], v[88:91], 0
	v_add_f32_e64 v64, v64, 1.0
	v_add_f32_e64 v65, v65, 1.0
	v_rcp_f32_e32 v66, v65
	v_rcp_f32_e32 v72, v64
	v_mul_f32_e32 v64, 0xbfb8aa3b, v100
	v_mul_f32_e32 v65, 0xbfb8aa3b, v67
	v_exp_f32_e32 v64, v64
	v_exp_f32_e32 v65, v65
	v_mfma_f32_16x16x32_bf16 v[100:103], v[60:63], v[84:87], 0
	v_cvt_pk_bf16_f32 v70, v72, v66
	v_pk_add_f32 v[64:65], v[64:65], 1.0 op_sel_hi:[1,0]
	s_nop 0
	v_mfma_f32_16x16x32_bf16 v[60:63], v[0:3], v[88:91], 0
	v_rcp_f32_e32 v65, v65
	v_mfma_f32_16x16x32_bf16 v[0:3], v[4:7], v[92:95], 0
	v_rcp_f32_e32 v64, v64
	s_nop 0
	v_cvt_pk_bf16_f32 v71, v64, v65
	v_mfma_f32_16x16x32_bf16 v[4:7], v[44:47], v[92:95], 0
	s_nop 0
	v_mfma_f32_16x16x32_bf16 v[56:59], v[8:11], v[68:71], v[0:3]
	v_lshlrev_b32_e32 v8, 1, v138
	v_mov_b32_e32 v9, v195
	v_lshl_add_u64 v[8:9], v[208:209], 0, v[8:9]
	global_load_dwordx4 v[128:131], v[8:9], off
	v_lshlrev_b32_e32 v8, 2, v138
	v_mov_b32_e32 v9, v195
	v_lshl_add_u64 v[218:219], v[210:211], 0, v[8:9]
	v_mfma_f32_16x16x32_bf16 v[0:3], v[20:23], v[92:95], 0
	global_load_dwordx4 v[132:135], v[218:219], off offset:16
	global_load_dwordx4 v[212:215], v[218:219], off
	global_load_dwordx4 v[222:225], v[158:159], off offset:16
	global_load_dwordx4 v[226:229], v[158:159], off
	v_lshl_add_u64 v[8:9], v[208:209], 0, v[182:183]
	s_waitcnt vmcnt(0) lgkmcnt(0)
	v_lshlrev_b32_e32 v210, 16, v128
	v_mfma_f32_16x16x32_bf16 v[52:55], v[28:31], v[68:71], v[52:55]
	v_and_b32_e32 v211, 0xffff0000, v128
	v_pk_add_f32 v[212:213], v[212:213], v[210:211] neg_lo:[0,1] neg_hi:[0,1]
	v_lshlrev_b32_e32 v128, 16, v129
	v_mfma_f32_16x16x32_bf16 v[0:3], v[32:35], v[68:71], v[0:3]
	v_and_b32_e32 v129, 0xffff0000, v129
	v_pk_fma_f32 v[212:213], v[212:213], v[226:227], v[210:211]
	v_pk_add_f32 v[210:211], v[214:215], v[128:129] neg_lo:[0,1] neg_hi:[0,1]
	v_mfma_f32_16x16x32_bf16 v[4:7], v[48:51], v[68:71], v[4:7]
	global_load_dwordx4 v[68:71], v[8:9], off
	global_load_dwordx4 v[72:75], v[218:219], off offset:1040
	global_load_dwordx4 v[104:107], v[218:219], off offset:1024
	global_load_dwordx4 v[76:79], v[158:159], off offset:1040
	global_load_dwordx4 v[108:111], v[158:159], off offset:1024
	v_lshl_add_u64 v[8:9], v[208:209], 0, v[184:185]
	v_pk_fma_f32 v[220:221], v[210:211], v[228:229], v[128:129]
	v_mfma_f32_16x16x32_bf16 v[64:67], v[24:27], v[84:87], 0
	v_lshlrev_b32_e32 v128, 16, v130
	v_and_b32_e32 v129, 0xffff0000, v130
	v_pk_add_f32 v[132:133], v[132:133], v[128:129] neg_lo:[0,1] neg_hi:[0,1]
	v_mfma_f32_16x16x32_bf16 v[28:31], v[12:15], v[84:87], 0
	v_fma_f32 v222, v132, v222, v128
	v_fma_f32 v223, v133, v223, v129
	v_lshlrev_b32_e32 v128, 16, v131
	v_and_b32_e32 v129, 0xffff0000, v131
	v_mfma_f32_16x16x32_bf16 v[24:27], v[16:19], v[88:91], 0
	v_add_f32_e64 v130, v134, -v128
	v_add_f32_e64 v131, v135, -v129
	v_cvt_pk_bf16_f32 v0, v0, v1
	v_pk_fma_f32 v[224:225], v[130:131], v[224:225], v[128:129]
	v_mfma_f32_16x16x32_bf16 v[20:23], v[36:39], v[84:87], 0
	v_cvt_pk_bf16_f32 v1, v2, v3
	v_cvt_pk_bf16_f32 v2, v4, v5
	v_cvt_pk_bf16_f32 v3, v6, v7
	v_mfma_f32_16x16x32_bf16 v[16:19], v[40:43], v[88:91], 0
	global_load_dwordx4 v[40:43], v[8:9], off
	global_load_dwordx4 v[36:39], v[218:219], off offset:2064
	global_load_dwordx4 v[48:51], v[218:219], off offset:2048
	global_load_dwordx4 v[32:35], v[158:159], off offset:2064
	global_load_dwordx4 v[44:47], v[158:159], off offset:2048
	global_load_dwordx4 v[80:83], v[160:161], off offset:16
	global_load_dwordx4 v[124:127], v[160:161], off
	global_load_dwordx4 v[92:95], v[162:163], off offset:16
	global_load_dwordx4 v[120:123], v[162:163], off
	global_load_dwordx4 v[8:11], v[164:165], off
	global_load_dwordx4 v[12:15], v[164:165], off offset:16
	global_load_dwordx4 v[88:91], v[166:167], off offset:16
	global_load_dwordx4 v[116:119], v[166:167], off
	global_load_dwordx4 v[84:87], v[168:169], off offset:16
	global_load_dwordx4 v[112:115], v[168:169], off
	s_waitcnt vmcnt(0)
	v_add_f32_e32 v64, v64, v80
	v_add_f32_e32 v100, v100, v124
	v_max_f32_e64 v124, -v100, 0
	v_mul_f32_e64 v100, |v100|, s21
	v_exp_f32_e32 v100, v100
	v_add_f32_e32 v101, v101, v125
	v_add_f32_e32 v96, v96, v120
	v_max_f32_e64 v120, -v101, 0
	v_add_f32_e32 v100, 1.0, v100
	v_cmp_gt_f32_e32 vcc, s4, v100
	v_mul_f32_e64 v101, |v101|, s21
	v_exp_f32_e32 v101, v101
	v_cndmask_b32_e64 v128, 0, 32, vcc
	v_ldexp_f32 v100, v100, v128
	v_log_f32_e32 v100, v100
	v_add_f32_e32 v101, 1.0, v101
	v_add_f32_e32 v97, v97, v121
	v_mul_f32_e32 v96, 0xbfb8aa3b, v96
	v_mul_f32_e32 v128, 0x3f317217, v100
	v_fma_f32 v128, v100, s5, -v128
	v_fmac_f32_e32 v128, 0x3377d1cf, v100
	v_fmac_f32_e32 v128, 0x3f317217, v100
	v_cmp_lt_f32_e64 s[0:1], |v100|, s6
	v_mul_f32_e32 v97, 0xbfb8aa3b, v97
	v_exp_f32_e32 v96, v96
	v_cndmask_b32_e64 v100, v100, v128, s[0:1]
	v_cndmask_b32_e32 v128, 0, v242, vcc
	v_sub_f32_e32 v100, v100, v128
	v_cmp_gt_f32_e32 vcc, s4, v101
	v_add_f32_e32 v100, v124, v100
	v_exp_f32_e32 v97, v97
	v_cndmask_b32_e64 v124, 0, 32, vcc
	v_ldexp_f32 v101, v101, v124
	v_log_f32_e32 v101, v101
	s_waitcnt lgkmcnt(0)
	v_and_b32_e32 v121, 0xffff0000, v68
	v_pk_add_f32 v[96:97], v[96:97], 1.0 op_sel_hi:[1,0]
	v_max_f32_e64 v80, -v64, 0
	v_mul_f32_e32 v124, 0x3f317217, v101
	v_fma_f32 v124, v101, s5, -v124
	v_fmac_f32_e32 v124, 0x3377d1cf, v101
	v_fmac_f32_e32 v124, 0x3f317217, v101
	v_cmp_lt_f32_e64 s[0:1], |v101|, s6
	v_mul_f32_e64 v64, |v64|, s21
	v_exp_f32_e32 v64, v64
	v_cndmask_b32_e64 v101, v101, v124, s[0:1]
	v_cndmask_b32_e32 v124, 0, v242, vcc
	v_sub_f32_e32 v101, v101, v124
	v_add_f32_e32 v101, v120, v101
	v_lshlrev_b32_e32 v120, 16, v68
	v_pk_add_f32 v[104:105], v[104:105], v[120:121] neg_lo:[0,1] neg_hi:[0,1]
	s_nop 0
	v_pk_fma_f32 v[128:129], v[108:109], v[104:105], v[120:121]
	v_add_f32_e32 v64, 1.0, v64
	v_add_f32_e32 v65, v65, v81
	v_add_f32_e32 v60, v60, v92
	v_rcp_f32_e32 v125, v97
	v_add_f32_e32 v61, v61, v93
	v_mul_f32_e32 v60, 0xbfb8aa3b, v60
	v_mul_f32_e32 v61, 0xbfb8aa3b, v61
	v_rcp_f32_e32 v124, v96
	v_add_f32_e32 v68, v102, v126
	v_max_f32_e64 v102, -v68, 0
	v_mul_f32_e64 v68, |v68|, s21
	v_exp_f32_e32 v68, v68
	v_pk_add_f32 v[96:97], v[124:125], -1.0 op_sel_hi:[1,0]
	v_exp_f32_e32 v60, v60
	v_pk_fma_f32 v[96:97], v[116:117], v[96:97], 1.0 op_sel_hi:[1,1,0]
	v_add_f32_e32 v68, 1.0, v68
	v_pk_mul_f32 v[96:97], v[128:129], v[96:97]
	v_cmp_gt_f32_e32 vcc, s4, v68
	v_pk_mul_f32 v[104:105], v[212:213], v[96:97]
	v_exp_f32_e32 v61, v61
	v_fma_f32 v139, v112, v104, 0
	v_cndmask_b32_e64 v104, 0, 32, vcc
	v_ldexp_f32 v68, v68, v104
	v_log_f32_e32 v68, v68
	v_fmac_f32_e32 v139, v113, v105
	v_pk_add_f32 v[60:61], v[60:61], 1.0 op_sel_hi:[1,0]
	v_add_f32_e32 v66, v66, v82
	v_mul_f32_e32 v104, 0x3f317217, v68
	v_fma_f32 v104, v68, s5, -v104
	v_fmac_f32_e32 v104, 0x3377d1cf, v68
	v_fmac_f32_e32 v104, 0x3f317217, v68
	v_cmp_lt_f32_e64 s[0:1], |v68|, s6
	v_add_f32_e32 v62, v62, v94
	v_add_f32_e32 v63, v63, v95
	v_cndmask_b32_e64 v68, v68, v104, s[0:1]
	v_cndmask_b32_e32 v104, 0, v242, vcc
	v_sub_f32_e32 v68, v68, v104
	v_add_f32_e32 v68, v102, v68
	v_sub_f32_e32 v68, -0.5, v68
	v_mul_f32_e32 v68, 0x3fb8aa3b, v68
	v_exp_f32_e32 v68, v68
	v_mul_f32_e32 v62, 0xbfb8aa3b, v62
	v_mul_f32_e32 v63, 0xbfb8aa3b, v63
	v_exp_f32_e32 v62, v62
	v_xor_b32_e32 v102, 0x80000000, v68
	v_add_f32_e32 v68, v98, v122
	v_mul_f32_e32 v68, 0xbfb8aa3b, v68
	v_exp_f32_e32 v104, v68
	v_add_f32_e32 v68, v103, v127
	v_max_f32_e64 v98, -v68, 0
	v_mul_f32_e64 v68, |v68|, s21
	v_exp_f32_e32 v68, v68
	v_exp_f32_e32 v63, v63
	v_sub_f32_e32 v100, -0.5, v100
	v_sub_f32_e32 v101, -0.5, v101
	v_add_f32_e32 v68, 1.0, v68
	v_cmp_gt_f32_e32 vcc, s4, v68
	v_pk_add_f32 v[62:63], v[62:63], 1.0 op_sel_hi:[1,0]
	v_mul_f32_e32 v100, 0x3fb8aa3b, v100
	v_cndmask_b32_e64 v103, 0, 32, vcc
	v_ldexp_f32 v68, v68, v103
	v_log_f32_e32 v68, v68
	v_mul_f32_e32 v101, 0x3fb8aa3b, v101
	v_exp_f32_e32 v100, v100
	v_exp_f32_e32 v101, v101
	v_mul_f32_e32 v103, 0x3f317217, v68
	v_fma_f32 v103, v68, s5, -v103
	v_fmac_f32_e32 v103, 0x3377d1cf, v68
	v_fmac_f32_e32 v103, 0x3f317217, v68
	v_cmp_lt_f32_e64 s[0:1], |v68|, s6
	v_xor_b32_e32 v100, 0x80000000, v100
	v_xor_b32_e32 v101, 0x80000000, v101
	v_cndmask_b32_e64 v68, v68, v103, s[0:1]
	v_cndmask_b32_e32 v103, 0, v242, vcc
	v_sub_f32_e32 v68, v68, v103
	v_add_f32_e32 v68, v98, v68
	v_sub_f32_e32 v68, -0.5, v68
	v_mul_f32_e32 v68, 0x3fb8aa3b, v68
	v_exp_f32_e32 v68, v68
	v_pk_mul_f32 v[8:9], v[128:129], v[8:9]
	v_xor_b32_e32 v98, 0x80000000, v68
	v_add_f32_e32 v68, v99, v123
	v_mul_f32_e32 v68, 0xbfb8aa3b, v68
	v_exp_f32_e32 v105, v68
	v_lshlrev_b32_e32 v68, 16, v69
	v_and_b32_e32 v69, 0xffff0000, v69
	v_pk_add_f32 v[106:107], v[106:107], v[68:69] neg_lo:[0,1] neg_hi:[0,1]
	s_nop 0
	v_pk_fma_f32 v[130:131], v[110:111], v[106:107], v[68:69]
	v_pk_add_f32 v[68:69], v[104:105], 1.0 op_sel_hi:[1,0]
	v_pk_mul_f32 v[10:11], v[130:131], v[10:11]
	v_rcp_f32_e32 v127, v69
	v_cmp_gt_f32_e32 vcc, s4, v64
	v_rcp_f32_e32 v126, v68
	s_nop 0
	v_pk_add_f32 v[68:69], v[126:127], -1.0 op_sel_hi:[1,0]
	v_cndmask_b32_e64 v99, 0, 32, vcc
	v_ldexp_f32 v64, v64, v99
	v_log_f32_e32 v64, v64
	v_pk_fma_f32 v[68:69], v[118:119], v[68:69], 1.0 op_sel_hi:[1,1,0]
	v_mul_f32_e32 v99, 0x3f317217, v64
	v_fma_f32 v99, v64, s5, -v99
	v_fmac_f32_e32 v99, 0x3377d1cf, v64
	v_fmac_f32_e32 v99, 0x3f317217, v64
	v_cmp_lt_f32_e64 s[0:1], |v64|, s6
	v_pk_mul_f32 v[68:69], v[130:131], v[68:69]
	s_nop 0
	v_cndmask_b32_e64 v64, v64, v99, s[0:1]
	v_cndmask_b32_e32 v99, 0, v242, vcc
	v_sub_f32_e32 v64, v64, v99
	v_add_f32_e32 v64, v80, v64
	v_max_f32_e64 v80, -v65, 0
	v_mul_f32_e64 v65, |v65|, s21
	v_exp_f32_e32 v65, v65
	v_pk_mul_f32 v[104:105], v[220:221], v[68:69]
	v_sub_f32_e32 v64, -0.5, v64
	v_fmac_f32_e32 v139, v114, v104
	v_add_f32_e32 v65, 1.0, v65
	v_cmp_gt_f32_e32 vcc, s4, v65
	v_fmac_f32_e32 v139, v115, v105
	v_mul_f32_e32 v64, 0x3fb8aa3b, v64
	v_cndmask_b32_e64 v81, 0, 32, vcc
	v_ldexp_f32 v65, v65, v81
	v_log_f32_e32 v65, v65
	v_exp_f32_e32 v64, v64
	v_mul_f32_e32 v81, 0x3f317217, v65
	v_fma_f32 v81, v65, s5, -v81
	v_fmac_f32_e32 v81, 0x3377d1cf, v65
	v_fmac_f32_e32 v81, 0x3f317217, v65
	v_cmp_lt_f32_e64 s[0:1], |v65|, s6
	v_xor_b32_e32 v64, 0x80000000, v64
	s_nop 0
	v_cndmask_b32_e64 v65, v65, v81, s[0:1]
	v_cndmask_b32_e32 v81, 0, v242, vcc
	v_sub_f32_e32 v65, v65, v81
	v_add_f32_e32 v65, v80, v65
	v_lshlrev_b32_e32 v80, 16, v70
	v_and_b32_e32 v81, 0xffff0000, v70
	v_pk_add_f32 v[72:73], v[72:73], v[80:81] neg_lo:[0,1] neg_hi:[0,1]
	s_nop 0
	v_pk_fma_f32 v[134:135], v[72:73], v[76:77], v[80:81]
	v_sub_f32_e32 v65, -0.5, v65
	v_mul_f32_e32 v65, 0x3fb8aa3b, v65
	v_exp_f32_e32 v65, v65
	v_rcp_f32_e32 v133, v61
	v_xor_b32_e32 v65, 0x80000000, v65
	v_pk_mul_f32 v[6:7], v[134:135], v[12:13]
	v_max_f32_e64 v70, -v66, 0
	v_mul_f32_e64 v66, |v66|, s21
	v_exp_f32_e32 v66, v66
	v_rcp_f32_e32 v132, v60
	s_nop 0
	v_pk_add_f32 v[60:61], v[132:133], -1.0 op_sel_hi:[1,0]
	v_pk_mul_f32 v[12:13], v[6:7], v[6:7]
	v_pk_fma_f32 v[60:61], v[88:89], v[60:61], 1.0 op_sel_hi:[1,1,0]
	v_add_f32_e32 v66, 1.0, v66
	v_pk_mul_f32 v[60:61], v[134:135], v[60:61]
	v_cmp_gt_f32_e32 vcc, s4, v66
	v_pk_mul_f32 v[72:73], v[222:223], v[60:61]
	s_nop 0
	v_fmac_f32_e32 v139, v84, v72
	v_cndmask_b32_e64 v72, 0, 32, vcc
	v_ldexp_f32 v66, v66, v72
	v_log_f32_e32 v66, v66
	v_fmac_f32_e32 v139, v85, v73
	v_mul_f32_e32 v72, 0x3f317217, v66
	v_fma_f32 v72, v66, s5, -v72
	v_fmac_f32_e32 v72, 0x3377d1cf, v66
	v_fmac_f32_e32 v72, 0x3f317217, v66
	v_cmp_lt_f32_e64 s[0:1], |v66|, s6
	s_nop 1
	v_cndmask_b32_e64 v66, v66, v72, s[0:1]
	v_cndmask_b32_e32 v72, 0, v242, vcc
	v_sub_f32_e32 v66, v66, v72
	v_add_f32_e32 v66, v70, v66
	v_sub_f32_e32 v66, -0.5, v66
	v_mul_f32_e32 v66, 0x3fb8aa3b, v66
	v_exp_f32_e32 v66, v66
	s_nop 0
	v_xor_b32_e32 v72, 0x80000000, v66
	v_add_f32_e32 v66, v67, v83
	v_max_f32_e64 v67, -v66, 0
	v_mul_f32_e64 v66, |v66|, s21
	v_exp_f32_e32 v66, v66
	s_nop 0
	v_add_f32_e32 v66, 1.0, v66
	v_cmp_gt_f32_e32 vcc, s4, v66
	s_nop 1
	v_cndmask_b32_e64 v70, 0, 32, vcc
	v_ldexp_f32 v66, v66, v70
	v_log_f32_e32 v66, v66
	s_nop 0
	v_mul_f32_e32 v70, 0x3f317217, v66
	v_fma_f32 v70, v66, s5, -v70
	v_fmac_f32_e32 v70, 0x3377d1cf, v66
	v_fmac_f32_e32 v70, 0x3f317217, v66
	v_cmp_lt_f32_e64 s[0:1], |v66|, s6
	s_nop 1
	v_cndmask_b32_e64 v66, v66, v70, s[0:1]
	v_cndmask_b32_e32 v70, 0, v242, vcc
	v_sub_f32_e32 v66, v66, v70
	v_add_f32_e32 v66, v67, v66
	v_sub_f32_e32 v66, -0.5, v66
	v_mul_f32_e32 v66, 0x3fb8aa3b, v66
	v_exp_f32_e32 v66, v66
	v_and_b32_e32 v67, 0xffff0000, v71
	v_xor_b32_e32 v73, 0x80000000, v66
	v_lshlrev_b32_e32 v66, 16, v71
	v_pk_add_f32 v[70:71], v[74:75], v[66:67] neg_lo:[0,1] neg_hi:[0,1]
	s_nop 0
	v_pk_fma_f32 v[214:215], v[70:71], v[78:79], v[66:67]
	v_rcp_f32_e32 v211, v63
	v_rcp_f32_e32 v210, v62
	s_nop 0
	v_pk_add_f32 v[62:63], v[210:211], -1.0 op_sel_hi:[1,0]
	s_nop 0
	v_pk_fma_f32 v[62:63], v[90:91], v[62:63], 1.0 op_sel_hi:[1,1,0]
	s_nop 0
	v_pk_mul_f32 v[62:63], v[214:215], v[62:63]
	s_nop 0
	v_pk_mul_f32 v[66:67], v[224:225], v[62:63]
	s_nop 0
	v_fmac_f32_e32 v139, v86, v66
	v_fmac_f32_e32 v139, v87, v67
	v_lshlrev_b32_e32 v66, 16, v40
	v_and_b32_e32 v67, 0xffff0000, v40
	v_pk_add_f32 v[48:49], v[48:49], v[66:67] neg_lo:[0,1] neg_hi:[0,1]
	v_lshlrev_b32_e32 v40, 16, v41
	v_and_b32_e32 v41, 0xffff0000, v41
	v_pk_fma_f32 v[44:45], v[44:45], v[48:49], v[66:67]
	v_pk_add_f32 v[48:49], v[50:51], v[40:41] neg_lo:[0,1] neg_hi:[0,1]
	s_nop 0
	v_pk_fma_f32 v[40:41], v[46:47], v[48:49], v[40:41]
	v_lshlrev_b32_e32 v46, 16, v42
	v_and_b32_e32 v47, 0xffff0000, v42
	v_pk_add_f32 v[36:37], v[36:37], v[46:47] neg_lo:[0,1] neg_hi:[0,1]
	s_nop 0
	v_pk_fma_f32 v[36:37], v[36:37], v[32:33], v[46:47]
	v_lshlrev_b32_e32 v32, 16, v43
	v_and_b32_e32 v33, 0xffff0000, v43
	v_pk_add_f32 v[38:39], v[38:39], v[32:33] neg_lo:[0,1] neg_hi:[0,1]
	s_nop 0
	v_pk_fma_f32 v[38:39], v[38:39], v[34:35], v[32:33]
	v_cvt_pk_bf16_f32 v32, v212, v213
	v_cvt_pk_bf16_f32 v33, v220, v221
	v_cvt_pk_bf16_f32 v34, v222, v223
	v_cvt_pk_bf16_f32 v35, v224, v225
	v_mad_i64_i32 v[212:213], s[0:1], v206, s20, v[170:171]
	global_store_dwordx4 v[212:213], v[32:35], off
	s_nop 1
	v_cvt_pk_bf16_f32 v32, v96, v97
	v_cvt_pk_bf16_f32 v33, v68, v69
	v_cvt_pk_bf16_f32 v34, v60, v61
	v_cvt_pk_bf16_f32 v35, v62, v63
	global_store_dwordx4 v[212:213], v[32:35], off offset:512
	s_nop 1
	v_cvt_pk_bf16_f32 v32, v44, v45
	v_cvt_pk_bf16_f32 v33, v40, v41
	v_cvt_pk_bf16_f32 v34, v36, v37
	v_cvt_pk_bf16_f32 v35, v38, v39
	global_store_dwordx4 v[212:213], v[32:35], off offset:1024
	s_nop 1
	v_cvt_pk_bf16_f32 v32, v100, v101
	v_cvt_pk_bf16_f32 v33, v102, v98
	v_cvt_pk_bf16_f32 v34, v64, v65
	v_cvt_pk_bf16_f32 v35, v72, v73
	global_store_dwordx4 v[212:213], v[32:35], off offset:2560
	s_nop 1
	v_cvt_pk_bf16_f32 v32, v52, v53
	v_cvt_pk_bf16_f32 v33, v54, v55
	v_cvt_pk_bf16_f32 v34, v56, v57
	v_cvt_pk_bf16_f32 v35, v58, v59
	global_store_dwordx4 v[216:217], v[32:35], off
	s_nop 1
	v_lshl_add_u64 v[32:33], v[208:209], 0, v[186:187]
	global_load_dwordx4 v[112:115], v[32:33], off
	global_load_dwordx4 v[116:119], v[218:219], off offset:144
	global_load_dwordx4 v[220:223], v[218:219], off offset:128
	global_load_dwordx4 v[120:123], v[158:159], off offset:144
	global_load_dwordx4 v[224:227], v[158:159], off offset:128
	v_lshl_add_u64 v[32:33], v[208:209], 0, v[188:189]
	global_load_dwordx4 v[56:59], v[32:33], off
	global_load_dwordx4 v[60:63], v[218:219], off offset:1168
	global_load_dwordx4 v[88:91], v[218:219], off offset:1152
	global_load_dwordx4 v[64:67], v[158:159], off offset:1168
	global_load_dwordx4 v[92:95], v[158:159], off offset:1152
	v_lshl_add_u64 v[32:33], v[208:209], 0, v[190:191]
	global_load_dwordx4 v[40:43], v[32:33], off
	global_load_dwordx4 v[36:39], v[218:219], off offset:2192
	global_load_dwordx4 v[48:51], v[218:219], off offset:2176
	s_nop 0
	global_load_dwordx4 v[32:35], v[158:159], off offset:2192
	global_load_dwordx4 v[44:47], v[158:159], off offset:2176
	global_load_dwordx4 v[68:71], v[160:161], off offset:144
	global_load_dwordx4 v[108:111], v[160:161], off offset:128
	global_load_dwordx4 v[72:75], v[162:163], off offset:144
	global_load_dwordx4 v[96:99], v[162:163], off offset:128
	global_load_dwordx4 v[76:79], v[164:165], off offset:144
	global_load_dwordx4 v[52:55], v[164:165], off offset:128
	global_load_dwordx4 v[84:87], v[166:167], off offset:144
	global_load_dwordx4 v[104:107], v[166:167], off offset:128
	global_load_dwordx4 v[80:83], v[168:169], off offset:144
	global_load_dwordx4 v[100:103], v[168:169], off offset:128
	s_waitcnt vmcnt(0)
	v_add_f32_e32 v20, v20, v68
	v_add_f32_e32 v28, v28, v108
	v_max_f32_e64 v108, -v28, 0
	v_mul_f32_e64 v28, |v28|, s21
	v_exp_f32_e32 v28, v28
	s_waitcnt lgkmcnt(0)
	v_lshlrev_b32_e32 v208, 16, v112
	v_and_b32_e32 v209, 0xffff0000, v112
	v_pk_add_f32 v[218:219], v[220:221], v[208:209] neg_lo:[0,1] neg_hi:[0,1]
	v_lshlrev_b32_e32 v112, 16, v113
	v_and_b32_e32 v113, 0xffff0000, v113
	v_pk_fma_f32 v[208:209], v[218:219], v[224:225], v[208:209]
	v_pk_add_f32 v[218:219], v[222:223], v[112:113] neg_lo:[0,1] neg_hi:[0,1]
	v_add_f32_e32 v28, 1.0, v28
	v_pk_fma_f32 v[112:113], v[218:219], v[226:227], v[112:113]
	v_lshlrev_b32_e32 v218, 16, v114
	v_and_b32_e32 v219, 0xffff0000, v114
	v_lshlrev_b32_e32 v114, 16, v115
	v_and_b32_e32 v115, 0xffff0000, v115
	v_pk_add_f32 v[118:119], v[118:119], v[114:115] neg_lo:[0,1] neg_hi:[0,1]
	v_cmp_gt_f32_e32 vcc, s4, v28
	v_pk_fma_f32 v[114:115], v[118:119], v[122:123], v[114:115]
	v_add_f32_e32 v24, v24, v96
	v_cndmask_b32_e64 v118, 0, 32, vcc
	v_ldexp_f32 v28, v28, v118
	v_log_f32_e32 v28, v28
	v_add_f32_e32 v25, v25, v97
	v_mul_f32_e32 v24, 0xbfb8aa3b, v24
	v_mul_f32_e32 v25, 0xbfb8aa3b, v25
	v_mul_f32_e32 v118, 0x3f317217, v28
	v_fma_f32 v118, v28, s5, -v118
	v_fmac_f32_e32 v118, 0x3377d1cf, v28
	v_fmac_f32_e32 v118, 0x3f317217, v28
	v_cmp_lt_f32_e64 s[0:1], |v28|, s6
	v_exp_f32_e32 v24, v24
	v_exp_f32_e32 v25, v25
	v_cndmask_b32_e64 v28, v28, v118, s[0:1]
	v_cndmask_b32_e32 v118, 0, v242, vcc
	v_sub_f32_e32 v28, v28, v118
	v_add_f32_e32 v28, v108, v28
	v_sub_f32_e32 v28, -0.5, v28
	v_mul_f32_e32 v28, 0x3fb8aa3b, v28
	v_exp_f32_e32 v28, v28
	v_pk_add_f32 v[24:25], v[24:25], 1.0 op_sel_hi:[1,0]
	v_add_f32_e32 v30, v30, v110
	v_add_f32_e32 v26, v26, v98
	v_xor_b32_e32 v108, 0x80000000, v28
	v_add_f32_e32 v28, v29, v109
	v_max_f32_e64 v29, -v28, 0
	v_mul_f32_e64 v28, |v28|, s21
	v_exp_f32_e32 v28, v28
	v_add_f32_e32 v27, v27, v99
	v_mul_f32_e32 v26, 0xbfb8aa3b, v26
	v_mul_f32_e32 v27, 0xbfb8aa3b, v27
	v_add_f32_e32 v28, 1.0, v28
	v_cmp_gt_f32_e32 vcc, s4, v28
	v_exp_f32_e32 v26, v26
	v_exp_f32_e32 v27, v27
	v_cndmask_b32_e64 v96, 0, 32, vcc
	v_ldexp_f32 v28, v28, v96
	v_log_f32_e32 v28, v28
	v_pk_add_f32 v[26:27], v[26:27], 1.0 op_sel_hi:[1,0]
	v_max_f32_e64 v68, -v20, 0
	v_mul_f32_e64 v20, |v20|, s21
	v_mul_f32_e32 v96, 0x3f317217, v28
	v_fma_f32 v96, v28, s5, -v96
	v_fmac_f32_e32 v96, 0x3377d1cf, v28
	v_fmac_f32_e32 v96, 0x3f317217, v28
	v_cmp_lt_f32_e64 s[0:1], |v28|, s6
	v_exp_f32_e32 v20, v20
	v_add_f32_e32 v16, v16, v72
	v_cndmask_b32_e64 v28, v28, v96, s[0:1]
	v_cndmask_b32_e32 v96, 0, v242, vcc
	v_sub_f32_e32 v28, v28, v96
	v_add_f32_e32 v28, v29, v28
	v_sub_f32_e32 v28, -0.5, v28
	v_mul_f32_e32 v28, 0x3fb8aa3b, v28
	v_exp_f32_e32 v28, v28
	v_and_b32_e32 v29, 0xffff0000, v56
	v_add_f32_e32 v20, 1.0, v20
	v_add_f32_e32 v17, v17, v73
	v_xor_b32_e32 v96, 0x80000000, v28
	v_lshlrev_b32_e32 v28, 16, v56
	v_pk_add_f32 v[88:89], v[88:89], v[28:29] neg_lo:[0,1] neg_hi:[0,1]
	s_nop 0
	v_pk_fma_f32 v[28:29], v[92:93], v[88:89], v[28:29]
	v_mul_f32_e32 v16, 0xbfb8aa3b, v16
	v_mul_f32_e32 v17, 0xbfb8aa3b, v17
	v_exp_f32_e32 v16, v16
	v_rcp_f32_e32 v25, v25
	v_exp_f32_e32 v17, v17
	v_add_f32_e32 v22, v22, v70
	v_add_f32_e32 v18, v18, v74
	v_rcp_f32_e32 v24, v24
	v_max_f32_e64 v56, -v30, 0
	v_mul_f32_e64 v30, |v30|, s21
	v_exp_f32_e32 v30, v30
	v_pk_add_f32 v[88:89], v[24:25], -1.0 op_sel_hi:[1,0]
	v_pk_add_f32 v[16:17], v[16:17], 1.0 op_sel_hi:[1,0]
	v_pk_fma_f32 v[88:89], v[104:105], v[88:89], 1.0 op_sel_hi:[1,1,0]
	v_add_f32_e32 v30, 1.0, v30
	v_pk_mul_f32 v[88:89], v[28:29], v[88:89]
	v_cmp_gt_f32_e32 vcc, s4, v30
	v_pk_mul_f32 v[92:93], v[208:209], v[88:89]
	v_add_f32_e32 v19, v19, v75
	v_fmac_f32_e32 v139, v100, v92
	v_cndmask_b32_e64 v92, 0, 32, vcc
	v_ldexp_f32 v30, v30, v92
	v_log_f32_e32 v30, v30
	v_fmac_f32_e32 v139, v101, v93
	v_mul_f32_e32 v18, 0xbfb8aa3b, v18
	v_mul_f32_e32 v19, 0xbfb8aa3b, v19
	v_mul_f32_e32 v92, 0x3f317217, v30
	v_fma_f32 v92, v30, s5, -v92
	v_fmac_f32_e32 v92, 0x3377d1cf, v30
	v_fmac_f32_e32 v92, 0x3f317217, v30
	v_cmp_lt_f32_e64 s[0:1], |v30|, s6
	v_exp_f32_e32 v18, v18
	v_exp_f32_e32 v19, v19
	v_cndmask_b32_e64 v30, v30, v92, s[0:1]
	v_cndmask_b32_e32 v92, 0, v242, vcc
	v_sub_f32_e32 v30, v30, v92
	v_add_f32_e32 v30, v56, v30
	v_sub_f32_e32 v30, -0.5, v30
	v_mul_f32_e32 v30, 0x3fb8aa3b, v30
	v_exp_f32_e32 v30, v30
	v_pk_add_f32 v[18:19], v[18:19], 1.0 op_sel_hi:[1,0]
	v_pk_add_f32 v[116:117], v[116:117], v[218:219] neg_lo:[0,1] neg_hi:[0,1]
	v_pk_mul_f32 v[28:29], v[28:29], v[52:53]
	v_xor_b32_e32 v92, 0x80000000, v30
	v_add_f32_e32 v30, v31, v111
	v_max_f32_e64 v31, -v30, 0
	v_mul_f32_e64 v30, |v30|, s21
	v_exp_f32_e32 v30, v30
	v_pk_fma_f32 v[116:117], v[116:117], v[120:121], v[218:219]
	v_add_f32_e32 v30, 1.0, v30
	v_cmp_gt_f32_e32 vcc, s4, v30
	s_nop 1
	v_cndmask_b32_e64 v56, 0, 32, vcc
	v_ldexp_f32 v30, v30, v56
	v_log_f32_e32 v30, v30
	s_nop 0
	v_mul_f32_e32 v56, 0x3f317217, v30
	v_fma_f32 v56, v30, s5, -v56
	v_fmac_f32_e32 v56, 0x3377d1cf, v30
	v_fmac_f32_e32 v56, 0x3f317217, v30
	v_cmp_lt_f32_e64 s[0:1], |v30|, s6
	s_nop 1
	v_cndmask_b32_e64 v30, v30, v56, s[0:1]
	v_cndmask_b32_e32 v56, 0, v242, vcc
	v_sub_f32_e32 v30, v30, v56
	v_add_f32_e32 v30, v31, v30
	v_sub_f32_e32 v30, -0.5, v30
	v_mul_f32_e32 v30, 0x3fb8aa3b, v30
	v_exp_f32_e32 v30, v30
	v_and_b32_e32 v31, 0xffff0000, v57
	v_xor_b32_e32 v93, 0x80000000, v30
	v_lshlrev_b32_e32 v30, 16, v57
	v_pk_add_f32 v[56:57], v[90:91], v[30:31] neg_lo:[0,1] neg_hi:[0,1]
	s_nop 0
	v_pk_fma_f32 v[30:31], v[94:95], v[56:57], v[30:31]
	v_rcp_f32_e32 v27, v27
	v_rcp_f32_e32 v26, v26
	s_nop 0
	v_pk_add_f32 v[56:57], v[26:27], -1.0 op_sel_hi:[1,0]
	v_cmp_gt_f32_e32 vcc, s4, v20
	v_pk_fma_f32 v[56:57], v[106:107], v[56:57], 1.0 op_sel_hi:[1,1,0]
	s_nop 0
	v_pk_mul_f32 v[56:57], v[30:31], v[56:57]
	v_pk_mul_f32 v[30:31], v[30:31], v[54:55]
	v_pk_mul_f32 v[90:91], v[112:113], v[56:57]
	v_pk_mul_f32 v[54:55], v[30:31], v[30:31]
	v_fmac_f32_e32 v139, v102, v90
	v_cndmask_b32_e64 v90, 0, 32, vcc
	v_ldexp_f32 v20, v20, v90
	v_log_f32_e32 v20, v20
	v_fmac_f32_e32 v139, v103, v91
	v_mul_f32_e32 v90, 0x3f317217, v20
	v_fma_f32 v90, v20, s5, -v90
	v_fmac_f32_e32 v90, 0x3377d1cf, v20
	v_fmac_f32_e32 v90, 0x3f317217, v20
	v_cmp_lt_f32_e64 s[0:1], |v20|, s6
	s_nop 1
	v_cndmask_b32_e64 v20, v20, v90, s[0:1]
	v_cndmask_b32_e32 v90, 0, v242, vcc
	v_sub_f32_e32 v20, v20, v90
	v_add_f32_e32 v20, v68, v20
	v_sub_f32_e32 v20, -0.5, v20
	v_mul_f32_e32 v20, 0x3fb8aa3b, v20
	v_exp_f32_e32 v20, v20
	s_nop 0
	v_xor_b32_e32 v68, 0x80000000, v20
	v_add_f32_e32 v20, v21, v69
	v_max_f32_e64 v21, -v20, 0
	v_mul_f32_e64 v20, |v20|, s21
	v_exp_f32_e32 v20, v20
	s_nop 0
	v_add_f32_e32 v20, 1.0, v20
	v_cmp_gt_f32_e32 vcc, s4, v20
	s_nop 1
	v_cndmask_b32_e64 v69, 0, 32, vcc
	v_ldexp_f32 v20, v20, v69
	v_log_f32_e32 v20, v20
	s_nop 0
	v_mul_f32_e32 v69, 0x3f317217, v20
	v_fma_f32 v69, v20, s5, -v69
	v_fmac_f32_e32 v69, 0x3377d1cf, v20
	v_fmac_f32_e32 v69, 0x3f317217, v20
	v_cmp_lt_f32_e64 s[0:1], |v20|, s6
	s_nop 1
	v_cndmask_b32_e64 v20, v20, v69, s[0:1]
	v_cndmask_b32_e32 v69, 0, v242, vcc
	v_sub_f32_e32 v20, v20, v69
	v_add_f32_e32 v20, v21, v20
	v_sub_f32_e32 v20, -0.5, v20
	v_mul_f32_e32 v20, 0x3fb8aa3b, v20
	v_exp_f32_e32 v20, v20
	v_and_b32_e32 v21, 0xffff0000, v58
	v_xor_b32_e32 v69, 0x80000000, v20
	v_lshlrev_b32_e32 v20, 16, v58
	v_pk_add_f32 v[60:61], v[60:61], v[20:21] neg_lo:[0,1] neg_hi:[0,1]
	s_nop 0
	v_pk_fma_f32 v[20:21], v[60:61], v[64:65], v[20:21]
	v_rcp_f32_e32 v17, v17
	v_rcp_f32_e32 v16, v16
	v_max_f32_e64 v58, -v22, 0
	v_mul_f32_e64 v22, |v22|, s21
	v_exp_f32_e32 v22, v22
	v_pk_add_f32 v[60:61], v[16:17], -1.0 op_sel_hi:[1,0]
	v_add_f32_e32 v22, 1.0, v22
	v_cmp_gt_f32_e32 vcc, s4, v22
	v_pk_fma_f32 v[60:61], v[84:85], v[60:61], 1.0 op_sel_hi:[1,1,0]
	s_nop 0
	v_cndmask_b32_e64 v70, 0, 32, vcc
	v_ldexp_f32 v22, v22, v70
	v_log_f32_e32 v22, v22
	v_pk_mul_f32 v[64:65], v[20:21], v[60:61]
	v_pk_mul_f32 v[20:21], v[20:21], v[76:77]
	v_pk_mul_f32 v[72:73], v[116:117], v[64:65]
	v_mul_f32_e32 v70, 0x3f317217, v22
	v_fma_f32 v70, v22, s5, -v70
	v_fmac_f32_e32 v70, 0x3377d1cf, v22
	v_fmac_f32_e32 v70, 0x3f317217, v22
	v_cmp_lt_f32_e64 s[0:1], |v22|, s6
	v_fmac_f32_e32 v139, v80, v72
	v_fmac_f32_e32 v139, v81, v73
	v_cndmask_b32_e64 v22, v22, v70, s[0:1]
	v_cndmask_b32_e32 v70, 0, v242, vcc
	v_sub_f32_e32 v22, v22, v70
	v_add_f32_e32 v22, v58, v22
	v_sub_f32_e32 v22, -0.5, v22
	v_mul_f32_e32 v22, 0x3fb8aa3b, v22
	v_exp_f32_e32 v22, v22
	v_pk_mul_f32 v[60:61], v[20:21], v[20:21]
	v_xor_b32_e32 v70, 0x80000000, v22
	v_add_f32_e32 v22, v23, v71
	v_max_f32_e64 v23, -v22, 0
	v_mul_f32_e64 v22, |v22|, s21
	v_exp_f32_e32 v22, v22
	s_nop 0
	v_add_f32_e32 v22, 1.0, v22
	v_cmp_gt_f32_e32 vcc, s4, v22
	s_nop 1
	v_cndmask_b32_e64 v58, 0, 32, vcc
	v_ldexp_f32 v22, v22, v58
	v_log_f32_e32 v22, v22
	s_nop 0
	v_mul_f32_e32 v58, 0x3f317217, v22
	v_fma_f32 v58, v22, s5, -v58
	v_fmac_f32_e32 v58, 0x3377d1cf, v22
	v_fmac_f32_e32 v58, 0x3f317217, v22
	v_cmp_lt_f32_e64 s[0:1], |v22|, s6
	s_nop 1
	v_cndmask_b32_e64 v22, v22, v58, s[0:1]
	v_cndmask_b32_e32 v58, 0, v242, vcc
	v_sub_f32_e32 v22, v22, v58
	v_add_f32_e32 v22, v23, v22
	v_sub_f32_e32 v22, -0.5, v22
	v_mul_f32_e32 v22, 0x3fb8aa3b, v22
	v_exp_f32_e32 v22, v22
	v_and_b32_e32 v23, 0xffff0000, v59
	v_xor_b32_e32 v71, 0x80000000, v22
	v_lshlrev_b32_e32 v22, 16, v59
	v_pk_add_f32 v[58:59], v[62:63], v[22:23] neg_lo:[0,1] neg_hi:[0,1]
	s_nop 0
	v_pk_fma_f32 v[22:23], v[58:59], v[66:67], v[22:23]
	v_rcp_f32_e32 v19, v19
	v_rcp_f32_e32 v18, v18
	s_nop 0
	v_pk_add_f32 v[58:59], v[18:19], -1.0 op_sel_hi:[1,0]
	s_nop 0
	v_pk_fma_f32 v[58:59], v[86:87], v[58:59], 1.0 op_sel_hi:[1,1,0]
	s_nop 0
	v_pk_mul_f32 v[58:59], v[22:23], v[58:59]
	v_pk_mul_f32 v[22:23], v[22:23], v[78:79]
	v_pk_mul_f32 v[62:63], v[114:115], v[58:59]
	v_pk_mul_f32 v[66:67], v[22:23], v[22:23]
	v_fmac_f32_e32 v139, v82, v62
	v_fmac_f32_e32 v139, v83, v63
	v_lshlrev_b32_e32 v62, 16, v40
	v_and_b32_e32 v63, 0xffff0000, v40
	v_pk_add_f32 v[48:49], v[48:49], v[62:63] neg_lo:[0,1] neg_hi:[0,1]
	v_lshlrev_b32_e32 v40, 16, v41
	v_and_b32_e32 v41, 0xffff0000, v41
	v_pk_fma_f32 v[44:45], v[44:45], v[48:49], v[62:63]
	v_pk_add_f32 v[48:49], v[50:51], v[40:41] neg_lo:[0,1] neg_hi:[0,1]
	s_nop 0
	v_pk_fma_f32 v[40:41], v[46:47], v[48:49], v[40:41]
	v_lshlrev_b32_e32 v46, 16, v42
	v_and_b32_e32 v47, 0xffff0000, v42
	v_pk_add_f32 v[36:37], v[36:37], v[46:47] neg_lo:[0,1] neg_hi:[0,1]
	s_nop 0
	v_pk_fma_f32 v[36:37], v[36:37], v[32:33], v[46:47]
	v_lshlrev_b32_e32 v32, 16, v43
	v_and_b32_e32 v33, 0xffff0000, v43
	v_pk_add_f32 v[38:39], v[38:39], v[32:33] neg_lo:[0,1] neg_hi:[0,1]
	s_nop 0
	v_pk_fma_f32 v[38:39], v[38:39], v[34:35], v[32:33]
	v_cvt_pk_bf16_f32 v32, v208, v209
	v_cvt_pk_bf16_f32 v33, v112, v113
	v_cvt_pk_bf16_f32 v34, v116, v117
	v_cvt_pk_bf16_f32 v35, v114, v115
	global_store_dwordx4 v[212:213], v[32:35], off offset:64
	s_nop 1
	v_cvt_pk_bf16_f32 v32, v88, v89
	v_cvt_pk_bf16_f32 v33, v56, v57
	v_cvt_pk_bf16_f32 v34, v64, v65
	v_cvt_pk_bf16_f32 v35, v58, v59
	global_store_dwordx4 v[212:213], v[32:35], off offset:576
	s_nop 1
	v_cvt_pk_bf16_f32 v32, v44, v45
	v_cvt_pk_bf16_f32 v33, v40, v41
	v_cvt_pk_bf16_f32 v34, v36, v37
	v_cvt_pk_bf16_f32 v35, v38, v39
	global_store_dwordx4 v[212:213], v[32:35], off offset:1088
	s_nop 1
	v_cvt_pk_bf16_f32 v32, v108, v96
	v_cvt_pk_bf16_f32 v33, v92, v93
	v_cvt_pk_bf16_f32 v34, v68, v69
	v_cvt_pk_bf16_f32 v35, v70, v71
	global_store_dwordx4 v[212:213], v[32:35], off offset:2624
	global_store_dwordx4 v[216:217], v[0:3], off offset:64
	s_nop 0
	v_pk_mul_f32 v[32:33], v[8:9], v[8:9]
	v_pk_mul_f32 v[2:3], v[214:215], v[14:15]
	v_pk_mul_f32 v[14:15], v[10:11], v[10:11]
	v_add_f32_e32 v32, v32, v33
	v_add_f32_e32 v14, v14, v32
	v_add_f32_e32 v14, v15, v14
	v_add_f32_e32 v12, v14, v12
	v_pk_mul_f32 v[4:5], v[2:3], v[2:3]
	v_add_f32_e32 v12, v13, v12
	v_add_f32_e32 v4, v4, v12
	v_pk_mul_f32 v[34:35], v[28:29], v[28:29]
	v_add_f32_e32 v4, v5, v4
	v_add_f32_e32 v4, v4, v34
	v_add_f32_e32 v4, v35, v4
	v_add_f32_e32 v4, v54, v4
	v_and_b32_e32 v1, 64, v243
	v_add_f32_e32 v4, v55, v4
	v_xor_b32_e32 v0, 16, v243
	v_add_u32_e32 v1, 64, v1
	v_add_f32_e32 v4, v4, v60
	v_cmp_lt_i32_e32 vcc, v0, v1
	v_add_f32_e32 v4, v61, v4
	v_add_f32_e32 v4, v66, v4
	v_cndmask_b32_e32 v0, v243, v0, vcc
	v_lshlrev_b32_e32 v36, 2, v0
	v_add_f32_e32 v4, v67, v4
	ds_bpermute_b32 v5, v36, v4
	v_xor_b32_e32 v0, 32, v243
	v_cmp_lt_i32_e32 vcc, v0, v1
	s_waitcnt lgkmcnt(0)
	v_add_f32_e32 v4, v4, v5
	v_cndmask_b32_e32 v0, v243, v0, vcc
	v_lshlrev_b32_e32 v37, 2, v0
	ds_bpermute_b32 v5, v37, v4
	ds_bpermute_b32 v0, v36, v139
	s_waitcnt lgkmcnt(0)
	v_add_f32_e32 v4, v4, v5
	v_cmp_gt_f32_e32 vcc, s34, v4
	v_mul_f32_e32 v5, 0x4f800000, v4
	v_add_f32_e32 v0, v139, v0
	v_cndmask_b32_e32 v4, v4, v5, vcc
	v_sqrt_f32_e32 v5, v4
	ds_bpermute_b32 v1, v37, v0
	v_add_u32_e32 v12, -1, v5
	v_fma_f32 v13, -v12, v5, v4
	v_cmp_ge_f32_e64 s[0:1], 0, v13
	v_add_u32_e32 v13, 1, v5
	s_nop 0
	v_cndmask_b32_e64 v12, v5, v12, s[0:1]
	v_fma_f32 v5, -v13, v5, v4
	v_cmp_lt_f32_e64 s[0:1], 0, v5
	s_nop 1
	v_cndmask_b32_e64 v5, v12, v13, s[0:1]
	v_mul_f32_e32 v12, 0x37800000, v5
	v_cndmask_b32_e32 v5, v5, v12, vcc
	v_cmp_class_f32_e32 vcc, v4, v237
	s_nop 1
	v_cndmask_b32_e32 v4, v5, v4, vcc
	v_max_f32_e32 v4, 0x2b8cbccc, v4
	v_rcp_f32_e32 v12, v4
	s_nop 0
	v_pk_mul_f32 v[4:5], v[8:9], v[12:13] op_sel_hi:[1,0]
	v_pk_mul_f32 v[10:11], v[10:11], v[12:13] op_sel_hi:[1,0]
	v_pk_mul_f32 v[6:7], v[6:7], v[12:13] op_sel_hi:[1,0]
	v_pk_mul_f32 v[34:35], v[2:3], v[12:13] op_sel_hi:[1,0]
	v_pk_mul_f32 v[8:9], v[124:125], v[4:5]
	v_pk_mul_f32 v[14:15], v[126:127], v[10:11]
	v_pk_mul_f32 v[32:33], v[132:133], v[6:7]
	v_pk_mul_f32 v[36:37], v[210:211], v[34:35]
	v_cvt_pk_bf16_f32 v2, v4, v5
	v_cvt_pk_bf16_f32 v3, v10, v11
	v_cvt_pk_bf16_f32 v4, v6, v7
	v_cvt_pk_bf16_f32 v5, v34, v35
	global_store_dwordx4 v[212:213], v[2:5], off offset:1536
	v_pk_mul_f32 v[10:11], v[20:21], v[12:13] op_sel_hi:[1,0]
	s_nop 0
	v_cvt_pk_bf16_f32 v2, v8, v9
	v_cvt_pk_bf16_f32 v3, v14, v15
	v_cvt_pk_bf16_f32 v4, v32, v33
	v_cvt_pk_bf16_f32 v5, v36, v37
	global_store_dwordx4 v[212:213], v[2:5], off offset:2048
	v_pk_mul_f32 v[14:15], v[16:17], v[10:11]
	s_nop 0
	v_pk_mul_f32 v[2:3], v[28:29], v[12:13] op_sel_hi:[1,0]
	v_pk_mul_f32 v[4:5], v[30:31], v[12:13] op_sel_hi:[1,0]
	v_pk_mul_f32 v[12:13], v[22:23], v[12:13] op_sel_hi:[1,0]
	v_pk_mul_f32 v[6:7], v[24:25], v[2:3]
	v_pk_mul_f32 v[8:9], v[26:27], v[4:5]
	v_pk_mul_f32 v[16:17], v[18:19], v[12:13]
	v_cvt_pk_bf16_f32 v2, v2, v3
	v_cvt_pk_bf16_f32 v3, v4, v5
	v_cvt_pk_bf16_f32 v4, v10, v11
	v_cvt_pk_bf16_f32 v5, v12, v13
	global_store_dwordx4 v[212:213], v[2:5], off offset:1600
	s_nop 1
	v_cvt_pk_bf16_f32 v2, v6, v7
	v_cvt_pk_bf16_f32 v3, v8, v9
	v_cvt_pk_bf16_f32 v4, v14, v15
	v_cvt_pk_bf16_f32 v5, v16, v17
	global_store_dwordx4 v[212:213], v[2:5], off offset:2112
	s_and_saveexec_b64 s[0:1], s[8:9]
	s_cbranch_execz .LBB0_346
	v_lshl_add_u64 v[2:3], v[206:207], 4, s[12:13]
	s_waitcnt lgkmcnt(0)
	v_add_f32_e32 v0, v0, v1
	global_store_dword v[2:3], v0, off
	s_branch .LBB0_346

.LBB0_352:
	v_cndmask_b32_e64 v4, 0, 1, s[0:1]
	s_mul_i32 s42, s77, 0x600
	v_cmp_ne_u32_e32 vcc, 1, v4
	v_lshl_add_u64 v[4:5], s[42:43], 1, v[2:3]
	global_load_ushort v19, v[4:5], off
	global_load_ushort v20, v[4:5], off offset:512
	global_load_ushort v21, v[4:5], off offset:1536
	global_load_ushort v22, v[4:5], off offset:2048
	global_load_ushort v23, v[4:5], off offset:2560
	v_lshl_add_u64 v[6:7], v[4:5], 0, s[90:91]
	global_load_ushort v14, v[4:5], off offset:3072
	global_load_ushort v15, v[4:5], off offset:3584
	global_load_ushort v16, v[6:7], off offset:1536
	global_load_ushort v17, v[6:7], off offset:2048
	global_load_ushort v18, v[6:7], off offset:2560
	v_lshl_add_u64 v[24:25], v[6:7], 0, s[90:91]
	global_load_ushort v9, v[6:7], off offset:3072
	global_load_ushort v10, v[6:7], off offset:3584
	global_load_ushort v11, v[24:25], off offset:1536
	global_load_ushort v12, v[24:25], off offset:2048
	global_load_ushort v13, v[24:25], off offset:2560
	v_lshl_add_u64 v[26:27], v[24:25], 0, s[90:91]
	global_load_ushort v4, v[24:25], off offset:3072
	global_load_ushort v5, v[24:25], off offset:3584
	global_load_ushort v6, v[26:27], off offset:1536
	global_load_ushort v7, v[26:27], off offset:2048
	global_load_ushort v8, v[26:27], off offset:2560
	s_add_i32 s66, s42, 0x1800
	s_mov_b32 s67, s43
	v_lshl_add_u64 v[28:29], s[66:67], 1, v[2:3]
	global_load_ushort v24, v[28:29], off
	global_load_ushort v25, v[28:29], off offset:512
	global_load_ushort v26, v[28:29], off offset:1536
	global_load_ushort v27, v[28:29], off offset:2048
	s_nop 0
	global_load_ushort v28, v[28:29], off offset:2560
	s_add_i32 s56, s42, 0x1e00
	s_mov_b32 s57, s43
	v_lshl_add_u64 v[34:35], s[56:57], 1, v[2:3]
	global_load_ushort v29, v[34:35], off
	global_load_ushort v30, v[34:35], off offset:512
	global_load_ushort v31, v[34:35], off offset:1536
	global_load_ushort v32, v[34:35], off offset:2048
	global_load_ushort v33, v[34:35], off offset:2560
	s_add_i32 s38, s42, 0x2400
	s_mov_b32 s39, s43
	v_lshl_add_u64 v[38:39], s[38:39], 1, v[2:3]
	global_load_ushort v34, v[38:39], off
	global_load_ushort v35, v[38:39], off offset:512
	global_load_ushort v36, v[38:39], off offset:1536
	global_load_ushort v37, v[38:39], off offset:2048
	global_load_ushort v40, v[38:39], off offset:2560
	s_add_i32 s36, s42, 0x2a00
	s_mov_b32 s37, s43
	v_lshl_add_u64 v[38:39], s[36:37], 1, v[2:3]
	global_load_ushort v41, v[38:39], off
	global_load_ushort v42, v[38:39], off offset:512
	global_load_ushort v43, v[38:39], off offset:1536
	global_load_ushort v44, v[38:39], off offset:2048
	global_load_ushort v45, v[38:39], off offset:2560
	s_add_i32 s58, s42, 0x3000
	s_mov_b32 s59, s43
	v_lshl_add_u64 v[38:39], s[58:59], 1, v[2:3]
	global_load_ushort v46, v[38:39], off
	global_load_ushort v47, v[38:39], off offset:512
	global_load_ushort v48, v[38:39], off offset:1536
	global_load_ushort v49, v[38:39], off offset:2048
	global_load_ushort v50, v[38:39], off offset:2560
	s_add_i32 s2, s42, 0x3600
	s_mov_b32 s3, s43
	v_lshl_add_u64 v[38:39], s[2:3], 1, v[2:3]
	global_load_ushort v51, v[38:39], off
	global_load_ushort v52, v[38:39], off offset:512
	global_load_ushort v53, v[38:39], off offset:1536
	global_load_ushort v54, v[38:39], off offset:2048
	global_load_ushort v55, v[38:39], off offset:2560
	s_add_i32 s20, s42, 0x3c00
	s_mov_b32 s21, s43
	s_add_i32 s26, s42, 0x4200
	v_lshl_add_u64 v[38:39], s[20:21], 1, v[2:3]
	s_mov_b32 s27, s43
	s_add_i32 s24, s42, 0x4800
	global_load_ushort v56, v[38:39], off
	global_load_ushort v57, v[38:39], off offset:512
	global_load_ushort v58, v[38:39], off offset:1536
	global_load_ushort v59, v[38:39], off offset:2048
	global_load_ushort v60, v[38:39], off offset:2560
	v_lshl_add_u64 v[38:39], s[26:27], 1, v[2:3]
	s_mov_b32 s25, s43
	s_add_i32 s40, s42, 0x4e00
	global_load_ushort v61, v[38:39], off
	global_load_ushort v62, v[38:39], off offset:512
	global_load_ushort v63, v[38:39], off offset:1536
	global_load_ushort v64, v[38:39], off offset:2048
	global_load_ushort v65, v[38:39], off offset:2560
	v_lshl_add_u64 v[38:39], s[24:25], 1, v[2:3]
	s_mov_b32 s41, s43
	s_add_i32 s4, s42, 0x5400
	global_load_ushort v66, v[38:39], off
	global_load_ushort v67, v[38:39], off offset:512
	global_load_ushort v68, v[38:39], off offset:1536
	global_load_ushort v69, v[38:39], off offset:2048
	global_load_ushort v70, v[38:39], off offset:2560
	v_lshl_add_u64 v[38:39], s[40:41], 1, v[2:3]
	s_mov_b32 s5, s43
	s_add_i32 s0, s42, 0x5a00
	global_load_ushort v71, v[38:39], off
	global_load_ushort v72, v[38:39], off offset:512
	global_load_ushort v73, v[38:39], off offset:1536
	global_load_ushort v74, v[38:39], off offset:2048
	global_load_ushort v75, v[38:39], off offset:2560
	v_lshl_add_u64 v[38:39], s[4:5], 1, v[2:3]
	s_mov_b32 s1, s43
	global_load_ushort v76, v[38:39], off
	global_load_ushort v77, v[38:39], off offset:512
	global_load_ushort v78, v[38:39], off offset:1536
	global_load_ushort v79, v[38:39], off offset:2048
	global_load_ushort v80, v[38:39], off offset:2560
	v_lshl_add_u64 v[38:39], s[0:1], 1, v[2:3]
	global_load_ushort v81, v[38:39], off
	global_load_ushort v82, v[38:39], off offset:512
	global_load_ushort v83, v[38:39], off offset:1536
	global_load_ushort v84, v[38:39], off offset:2048
	s_nop 0
	global_load_ushort v38, v[38:39], off offset:2560
	s_and_b64 vcc, exec, vcc
	s_waitcnt vmcnt(0) lgkmcnt(0)
	v_lshlrev_b32_e32 v19, 16, v19
	v_lshlrev_b32_e32 v20, 16, v20
	v_lshlrev_b32_e32 v21, 16, v21
	v_lshlrev_b32_e32 v22, 16, v22
	v_lshlrev_b32_e32 v23, 16, v23
	v_add_f32_e32 v23, v1, v23
	v_mul_f32_e32 v1, 0x3fb8aa3b, v1
	v_exp_f32_e32 v1, v1
	v_mul_f32_e32 v85, 0xbfb8aa3b, v23
	v_exp_f32_e32 v85, v85
	v_mul_f32_e32 v39, 0x3fb8aa3b, v23
	v_mul_f32_e64 v1, v1, -v21
	v_cvt_pk_bf16_f32 v1, v1, s0
	s_mul_i32 s0, s77, 0x44
	v_or_b32_e32 v21, s0, v100
	v_lshl_add_u32 v21, v21, 1, s68
	v_exp_f32_e32 v39, v39
	ds_write_b16 v21, v1
	v_mul_f32_e32 v1, v85, v22
	v_cvt_pk_bf16_f32 v1, v1, s0
	ds_write_b16 v21, v1 offset:4352
	v_mul_f32_e32 v1, v85, v20
	v_cvt_pk_bf16_f32 v1, v1, s0
	ds_write_b16 v21, v1 offset:8704
	v_mul_f32_e32 v1, v39, v19
	v_cvt_pk_bf16_f32 v1, v1, s0
	ds_write_b16 v21, v1 offset:13056
	v_lshlrev_b32_e32 v1, 16, v18
	v_add_f32_e32 v1, v23, v1
	v_mul_f32_e32 v18, 0x3fb8aa3b, v1
	v_exp_f32_e32 v18, v18
	v_lshlrev_b32_e32 v13, 16, v13
	v_lshlrev_b32_e32 v14, 16, v14
	v_mul_f32_e32 v19, 0xbfb8aa3b, v1
	v_add_f32_e32 v1, v1, v13
	v_mul_f32_e32 v14, v18, v14
	v_mul_f32_e32 v13, 0x3fb8aa3b, v1
	v_cvt_pk_bf16_f32 v14, v14, s0
	v_exp_f32_e32 v13, v13
	v_lshlrev_b32_e32 v8, 16, v8
	ds_write_b16 v21, v14 offset:13192
	v_mul_f32_e32 v14, 0xbfb8aa3b, v1
	v_add_f32_e32 v1, v1, v8
	v_mul_f32_e32 v8, 0x3fb8aa3b, v1
	v_lshlrev_b32_e32 v9, 16, v9
	v_exp_f32_e32 v8, v8
	v_mul_f32_e32 v9, v13, v9
	v_cvt_pk_bf16_f32 v9, v9, s0
	ds_write_b16 v21, v9 offset:13328
	v_lshlrev_b32_e32 v4, 16, v4
	v_mul_f32_e32 v9, 0xbfb8aa3b, v1
	v_exp_f32_e32 v9, v9
	v_mul_f32_e32 v4, v8, v4
	v_lshlrev_b32_e32 v6, 16, v6
	v_cvt_pk_bf16_f32 v4, v4, s0
	v_mul_f32_e64 v6, v13, -v6
	ds_write_b16 v21, v4 offset:13464
	v_lshlrev_b32_e32 v4, 16, v28
	v_lshlrev_b32_e32 v5, 16, v5
	v_lshlrev_b32_e32 v7, 16, v7
	v_cvt_pk_bf16_f32 v6, v6, s0
	v_add_f32_e32 v1, v1, v4
	ds_write_b16 v21, v6 offset:408
	v_mul_f32_e32 v6, v9, v7
	v_mul_f32_e32 v5, v9, v5
	v_mul_f32_e32 v9, 0x3fb8aa3b, v1
	v_exp_f32_e32 v9, v9
	v_exp_f32_e32 v14, v14
	v_lshlrev_b32_e32 v4, 16, v24
	v_lshlrev_b32_e32 v10, 16, v10
	v_mul_f32_e32 v4, v9, v4
	v_mul_f32_e32 v10, v14, v10
	v_cvt_pk_bf16_f32 v4, v4, s0
	v_cvt_pk_bf16_f32 v10, v10, s0
	v_cvt_pk_bf16_f32 v6, v6, s0
	ds_write_b16 v21, v4 offset:13600
	v_lshlrev_b32_e32 v4, 16, v33
	ds_write_b16 v21, v10 offset:8976
	ds_write_b16 v21, v6 offset:4760
	v_lshlrev_b32_e32 v6, 16, v26
	v_mul_f32_e32 v10, 0xbfb8aa3b, v1
	v_add_f32_e32 v1, v1, v4
	v_mul_f32_e64 v6, v8, -v6
	v_mul_f32_e32 v8, 0x3fb8aa3b, v1
	v_exp_f32_e32 v8, v8
	v_exp_f32_e32 v10, v10
	v_lshlrev_b32_e32 v4, 16, v29
	v_lshlrev_b32_e32 v7, 16, v27
	v_cvt_pk_bf16_f32 v6, v6, s0
	v_mul_f32_e32 v4, v8, v4
	v_cvt_pk_bf16_f32 v5, v5, s0
	ds_write_b16 v21, v6 offset:544
	v_mul_f32_e32 v6, v10, v7
	v_cvt_pk_bf16_f32 v4, v4, s0
	ds_write_b16 v21, v5 offset:9112
	v_lshlrev_b32_e32 v5, 16, v25
	v_cvt_pk_bf16_f32 v6, v6, s0
	ds_write_b16 v21, v4 offset:13736
	v_lshlrev_b32_e32 v4, 16, v40
	ds_write_b16 v21, v6 offset:4896
	v_mul_f32_e32 v5, v10, v5
	v_lshlrev_b32_e32 v6, 16, v31
	v_mul_f32_e32 v10, 0xbfb8aa3b, v1
	v_add_f32_e32 v1, v1, v4
	v_mul_f32_e64 v6, v9, -v6
	v_mul_f32_e32 v9, 0x3fb8aa3b, v1
	v_exp_f32_e32 v9, v9
	v_exp_f32_e32 v10, v10
	v_lshlrev_b32_e32 v4, 16, v34
	v_lshlrev_b32_e32 v7, 16, v32
	v_cvt_pk_bf16_f32 v6, v6, s0
	v_mul_f32_e32 v4, v9, v4
	v_cvt_pk_bf16_f32 v5, v5, s0
	ds_write_b16 v21, v6 offset:680
	v_mul_f32_e32 v6, v10, v7
	v_cvt_pk_bf16_f32 v4, v4, s0
	ds_write_b16 v21, v5 offset:9248
	v_lshlrev_b32_e32 v5, 16, v30
	v_cvt_pk_bf16_f32 v6, v6, s0
	ds_write_b16 v21, v4 offset:13872
	v_lshlrev_b32_e32 v4, 16, v45
	ds_write_b16 v21, v6 offset:5032
	v_mul_f32_e32 v5, v10, v5
	v_lshlrev_b32_e32 v6, 16, v36
	v_mul_f32_e32 v10, 0xbfb8aa3b, v1
	v_add_f32_e32 v1, v1, v4
	v_mul_f32_e64 v6, v8, -v6
	v_mul_f32_e32 v8, 0x3fb8aa3b, v1
	v_exp_f32_e32 v8, v8
	v_exp_f32_e32 v10, v10
	v_lshlrev_b32_e32 v4, 16, v41
	v_lshlrev_b32_e32 v7, 16, v37
	v_cvt_pk_bf16_f32 v6, v6, s0
	v_mul_f32_e32 v4, v8, v4
	v_cvt_pk_bf16_f32 v5, v5, s0
	ds_write_b16 v21, v6 offset:816
	v_mul_f32_e32 v6, v10, v7
	v_cvt_pk_bf16_f32 v4, v4, s0
	ds_write_b16 v21, v5 offset:9384
	v_lshlrev_b32_e32 v5, 16, v35
	v_cvt_pk_bf16_f32 v6, v6, s0
	ds_write_b16 v21, v4 offset:14008
	v_lshlrev_b32_e32 v4, 16, v50
	ds_write_b16 v21, v6 offset:5168
	v_mul_f32_e32 v5, v10, v5
	v_lshlrev_b32_e32 v6, 16, v43
	v_mul_f32_e32 v10, 0xbfb8aa3b, v1
	v_add_f32_e32 v1, v1, v4
	v_mul_f32_e64 v6, v9, -v6
	v_mul_f32_e32 v9, 0x3fb8aa3b, v1
	v_exp_f32_e32 v9, v9
	v_exp_f32_e32 v10, v10
	v_lshlrev_b32_e32 v4, 16, v46
	v_lshlrev_b32_e32 v7, 16, v44
	v_cvt_pk_bf16_f32 v6, v6, s0
	v_mul_f32_e32 v4, v9, v4
	v_cvt_pk_bf16_f32 v5, v5, s0
	ds_write_b16 v21, v6 offset:952
	v_mul_f32_e32 v6, v10, v7
	v_cvt_pk_bf16_f32 v4, v4, s0
	ds_write_b16 v21, v5 offset:9520
	v_lshlrev_b32_e32 v5, 16, v42
	v_cvt_pk_bf16_f32 v6, v6, s0
	ds_write_b16 v21, v4 offset:14144
	v_lshlrev_b32_e32 v4, 16, v55
	ds_write_b16 v21, v6 offset:5304
	v_mul_f32_e32 v5, v10, v5
	v_lshlrev_b32_e32 v6, 16, v48
	v_mul_f32_e32 v10, 0xbfb8aa3b, v1
	v_add_f32_e32 v1, v1, v4
	v_mul_f32_e64 v6, v8, -v6
	v_mul_f32_e32 v8, 0x3fb8aa3b, v1
	v_exp_f32_e32 v8, v8
	v_exp_f32_e32 v10, v10
	v_lshlrev_b32_e32 v4, 16, v51
	v_lshlrev_b32_e32 v7, 16, v49
	v_cvt_pk_bf16_f32 v6, v6, s0
	v_mul_f32_e32 v4, v8, v4
	v_cvt_pk_bf16_f32 v5, v5, s0
	ds_write_b16 v21, v6 offset:1088
	v_mul_f32_e32 v6, v10, v7
	v_cvt_pk_bf16_f32 v4, v4, s0
	ds_write_b16 v21, v5 offset:9656
	v_lshlrev_b32_e32 v5, 16, v47
	v_cvt_pk_bf16_f32 v6, v6, s0
	ds_write_b16 v21, v4 offset:14280
	v_lshlrev_b32_e32 v4, 16, v60
	ds_write_b16 v21, v6 offset:5440
	v_mul_f32_e32 v5, v10, v5
	v_lshlrev_b32_e32 v6, 16, v53
	v_mul_f32_e32 v10, 0xbfb8aa3b, v1
	v_add_f32_e32 v1, v1, v4
	v_mul_f32_e64 v6, v9, -v6
	v_mul_f32_e32 v9, 0x3fb8aa3b, v1
	v_exp_f32_e32 v9, v9
	v_exp_f32_e32 v10, v10
	v_lshlrev_b32_e32 v4, 16, v56
	v_lshlrev_b32_e32 v7, 16, v54
	v_cvt_pk_bf16_f32 v6, v6, s0
	v_mul_f32_e32 v4, v9, v4
	v_cvt_pk_bf16_f32 v5, v5, s0
	ds_write_b16 v21, v6 offset:1224
	v_mul_f32_e32 v6, v10, v7
	v_cvt_pk_bf16_f32 v4, v4, s0
	ds_write_b16 v21, v5 offset:9792
	v_lshlrev_b32_e32 v5, 16, v52
	v_cvt_pk_bf16_f32 v6, v6, s0
	ds_write_b16 v21, v4 offset:14416
	v_lshlrev_b32_e32 v4, 16, v65
	ds_write_b16 v21, v6 offset:5576
	v_mul_f32_e32 v5, v10, v5
	v_lshlrev_b32_e32 v6, 16, v58
	v_mul_f32_e32 v10, 0xbfb8aa3b, v1
	v_add_f32_e32 v1, v1, v4
	v_mul_f32_e64 v6, v8, -v6
	v_mul_f32_e32 v8, 0x3fb8aa3b, v1
	v_exp_f32_e32 v8, v8
	v_exp_f32_e32 v10, v10
	v_lshlrev_b32_e32 v4, 16, v61
	v_lshlrev_b32_e32 v7, 16, v59
	v_cvt_pk_bf16_f32 v6, v6, s0
	v_mul_f32_e32 v4, v8, v4
	v_cvt_pk_bf16_f32 v5, v5, s0
	ds_write_b16 v21, v6 offset:1360
	v_mul_f32_e32 v6, v10, v7
	v_cvt_pk_bf16_f32 v4, v4, s0
	ds_write_b16 v21, v5 offset:9928
	v_lshlrev_b32_e32 v5, 16, v57
	v_cvt_pk_bf16_f32 v6, v6, s0
	ds_write_b16 v21, v4 offset:14552
	v_lshlrev_b32_e32 v4, 16, v70
	ds_write_b16 v21, v6 offset:5712
	v_mul_f32_e32 v5, v10, v5
	v_lshlrev_b32_e32 v6, 16, v63
	v_mul_f32_e32 v10, 0xbfb8aa3b, v1
	v_add_f32_e32 v1, v1, v4
	v_mul_f32_e64 v6, v9, -v6
	v_mul_f32_e32 v9, 0x3fb8aa3b, v1
	v_exp_f32_e32 v9, v9
	v_exp_f32_e32 v10, v10
	v_lshlrev_b32_e32 v4, 16, v66
	v_lshlrev_b32_e32 v7, 16, v64
	v_cvt_pk_bf16_f32 v6, v6, s0
	v_mul_f32_e32 v4, v9, v4
	v_cvt_pk_bf16_f32 v5, v5, s0
	ds_write_b16 v21, v6 offset:1496
	v_mul_f32_e32 v6, v10, v7
	v_cvt_pk_bf16_f32 v4, v4, s0
	ds_write_b16 v21, v5 offset:10064
	v_lshlrev_b32_e32 v5, 16, v62
	v_cvt_pk_bf16_f32 v6, v6, s0
	ds_write_b16 v21, v4 offset:14688
	v_lshlrev_b32_e32 v4, 16, v75
	ds_write_b16 v21, v6 offset:5848
	v_mul_f32_e32 v5, v10, v5
	v_lshlrev_b32_e32 v6, 16, v68
	v_mul_f32_e32 v10, 0xbfb8aa3b, v1
	v_add_f32_e32 v1, v1, v4
	v_mul_f32_e64 v6, v8, -v6
	v_mul_f32_e32 v8, 0x3fb8aa3b, v1
	v_exp_f32_e32 v8, v8
	v_exp_f32_e32 v10, v10
	v_lshlrev_b32_e32 v4, 16, v71
	v_lshlrev_b32_e32 v7, 16, v69
	v_cvt_pk_bf16_f32 v6, v6, s0
	v_mul_f32_e32 v4, v8, v4
	v_cvt_pk_bf16_f32 v5, v5, s0
	ds_write_b16 v21, v6 offset:1632
	v_mul_f32_e32 v6, v10, v7
	v_cvt_pk_bf16_f32 v4, v4, s0
	ds_write_b16 v21, v5 offset:10200
	v_lshlrev_b32_e32 v5, 16, v67
	v_cvt_pk_bf16_f32 v6, v6, s0
	ds_write_b16 v21, v4 offset:14824
	v_lshlrev_b32_e32 v4, 16, v80
	ds_write_b16 v21, v6 offset:5984
	v_mul_f32_e32 v5, v10, v5
	v_lshlrev_b32_e32 v6, 16, v73
	v_mul_f32_e32 v10, 0xbfb8aa3b, v1
	v_add_f32_e32 v1, v1, v4
	v_mul_f32_e64 v6, v9, -v6
	v_mul_f32_e32 v9, 0x3fb8aa3b, v1
	v_exp_f32_e32 v10, v10
	v_exp_f32_e32 v9, v9
	v_cvt_pk_bf16_f32 v5, v5, s0
	ds_write_b16 v21, v5 offset:10336
	v_lshlrev_b32_e32 v5, 16, v72
	v_lshlrev_b32_e32 v7, 16, v74
	v_cvt_pk_bf16_f32 v6, v6, s0
	v_lshlrev_b32_e32 v4, 16, v76
	ds_write_b16 v21, v6 offset:1768
	v_mul_f32_e32 v6, v10, v7
	v_mul_f32_e32 v5, v10, v5
	v_mul_f32_e32 v10, 0xbfb8aa3b, v1
	v_mul_f32_e32 v4, v9, v4
	v_cvt_pk_bf16_f32 v6, v6, s0
	v_exp_f32_e32 v10, v10
	v_cvt_pk_bf16_f32 v4, v4, s0
	ds_write_b16 v21, v6 offset:6120
	v_lshlrev_b32_e32 v6, 16, v78
	ds_write_b16 v21, v4 offset:14960
	v_lshlrev_b32_e32 v4, 16, v38
	v_mul_f32_e64 v6, v8, -v6
	v_add_f32_e32 v1, v1, v4
	v_lshlrev_b32_e32 v7, 16, v79
	v_cvt_pk_bf16_f32 v6, v6, s0
	v_mul_f32_e32 v8, 0x3fb8aa3b, v1
	v_cvt_pk_bf16_f32 v5, v5, s0
	ds_write_b16 v21, v6 offset:1904
	v_mul_f32_e32 v6, v10, v7
	v_exp_f32_e32 v171, v8
	v_mul_f32_e32 v8, 0xbfb8aa3b, v1
	v_exp_f32_e32 v19, v19
	ds_write_b16 v21, v5 offset:10472
	v_lshlrev_b32_e32 v5, 16, v77
	v_cvt_pk_bf16_f32 v6, v6, s0
	v_exp_f32_e32 v8, v8
	v_lshlrev_b32_e32 v16, 16, v16
	v_lshlrev_b32_e32 v11, 16, v11
	ds_write_b16 v21, v6 offset:6256
	v_mul_f32_e32 v5, v10, v5
	v_lshlrev_b32_e32 v6, 16, v83
	v_mul_f32_e64 v16, v39, -v16
	v_mul_f32_e64 v11, v18, -v11
	v_cvt_pk_bf16_f32 v5, v5, s0
	v_mul_f32_e64 v6, v9, -v6
	v_lshlrev_b32_e32 v15, 16, v15
	v_lshlrev_b32_e32 v17, 16, v17
	v_cvt_pk_bf16_f32 v16, v16, s0
	v_lshlrev_b32_e32 v12, 16, v12
	v_cvt_pk_bf16_f32 v11, v11, s0
	ds_write_b16 v21, v5 offset:10608
	v_lshlrev_b32_e32 v4, 16, v81
	v_lshlrev_b32_e32 v5, 16, v82
	v_lshlrev_b32_e32 v7, 16, v84
	v_cvt_pk_bf16_f32 v6, v6, s0
	ds_write_b16 v21, v16 offset:136
	v_mul_f32_e32 v16, v19, v17
	v_mul_f32_e32 v15, v19, v15
	ds_write_b16 v21, v11 offset:272
	v_mul_f32_e32 v11, v14, v12
	ds_write_b16 v21, v6 offset:2040
	v_mul_f32_e32 v6, v8, v7
	v_mul_f32_e32 v5, v8, v5
	v_mul_f32_e32 v4, v171, v4
	v_cvt_pk_bf16_f32 v16, v16, s0
	v_cvt_pk_bf16_f32 v15, v15, s0
	v_cvt_pk_bf16_f32 v11, v11, s0
	v_cvt_pk_bf16_f32 v6, v6, s0
	v_cvt_pk_bf16_f32 v5, v5, s0
	v_cvt_pk_bf16_f32 v4, v4, s0
	ds_write_b16 v21, v16 offset:4488
	ds_write_b16 v21, v15 offset:8840
	ds_write_b16 v21, v11 offset:4624
	ds_write_b16 v21, v6 offset:6392
	ds_write_b16 v21, v5 offset:10744
	ds_write_b16 v21, v4 offset:15096
	s_mov_b64 s[0:1], 0
	s_mov_b32 s77, 16
	s_cbranch_vccz .LBB0_352
	s_waitcnt lgkmcnt(0)
	v_add_u32_e32 v1, 0x1100, v101
	v_add_u32_e32 v4, 0x2200, v101
	ds_read2_b64 v[20:23], v1 offset1:1
	ds_read2_b64 v[72:75], v4 offset1:1
	v_add_u32_e32 v1, 0x3300, v101
	s_and_b32 s0, s73, 63
	s_and_b32 s1, s63, 0xffffff00
	v_add_u32_e32 v4, 0x1100, v152
	ds_read2_b64 v[84:87], v1 offset1:1
	ds_read2_b64 v[24:27], v4 offset1:1
	v_add_u32_e32 v1, 0x2200, v152
	s_or_b32 s0, s0, s1
	v_add_u32_e32 v4, 0x3300, v152
	ds_read2_b64 v[76:79], v1 offset1:1
	ds_read2_b64 v[32:35], v4 offset1:1
	v_add_u32_e32 v1, 0x1140, v101
	s_or_b32 s0, s0, s76
	v_add_u32_e32 v4, 0x2240, v101
	ds_read2_b64 v[28:31], v1 offset1:1
	ds_read2_b64 v[60:63], v4 offset1:1
	ds_read2_b64 v[96:99], v101 offset1:1
	ds_read2_b64 v[92:95], v101 offset0:8 offset1:9
	v_add_u32_e32 v1, 0x3340, v101
	s_mul_hi_i32 s1, s0, 0x7a00
	s_mulk_i32 s0, 0x7a00
	v_add_u32_e32 v4, 0x1140, v152
	ds_read2_b64 v[80:83], v1 offset1:1
	ds_read2_b64 v[52:55], v4 offset1:1
	v_add_u32_e32 v1, 0x2240, v152
	ds_read2_b64 v[88:91], v152 offset1:1
	ds_read2_b64 v[68:71], v152 offset0:8 offset1:9
	v_add_u32_e32 v4, 0x3340, v152
	ds_read2_b64 v[64:67], v1 offset1:1
	ds_read2_b64 v[56:59], v4 offset1:1
	s_add_u32 s0, s94, s0
	v_add_u32_e32 v1, 0x3000, v153
	s_addc_u32 s1, s95, s1
	ds_read2_b64 v[4:7], v1 offset0:96 offset1:100
	s_add_u32 s2, s0, 0x1000
	ds_read2_b64 v[8:11], v1 offset0:104 offset1:108
	s_addc_u32 s3, s1, 0
	v_mov_b32_e32 v135, v195
	v_lshl_add_u64 v[12:13], s[2:3], 0, v[134:135]
	v_mov_b32_e32 v119, v195
	v_lshl_add_u64 v[14:15], v[12:13], 0, v[118:119]
	v_mov_b32_e32 v121, v195
	s_waitcnt lgkmcnt(1)
	global_store_dwordx4 v[14:15], v[4:7], off
	v_add_u32_e32 v1, 0x3000, v154
	v_mov_b32_e32 v123, v195
	v_lshl_add_u64 v[4:5], v[12:13], 0, v[120:121]
	s_waitcnt lgkmcnt(0)
	global_store_dwordx4 v[4:5], v[8:11], off
	ds_read2_b64 v[4:7], v1 offset0:96 offset1:100
	ds_read2_b64 v[8:11], v1 offset0:104 offset1:108
	v_lshl_add_u64 v[12:13], s[2:3], 0, v[122:123]
	v_lshl_add_u64 v[14:15], v[12:13], 0, v[118:119]
	s_mov_b32 s2, 0
	s_waitcnt lgkmcnt(1)
	global_store_dwordx4 v[14:15], v[4:7], off
	s_mov_b64 s[4:5], -1
	s_nop 0
	v_lshl_add_u64 v[4:5], v[12:13], 0, v[120:121]
	s_waitcnt lgkmcnt(0)
	global_store_dwordx4 v[4:5], v[8:11], off
	s_waitcnt lgkmcnt(0)
	ds_read_b64_tr_b16 v[8:9], v155
	ds_read_b64_tr_b16 v[4:5], v155 offset:32
	ds_read_b64_tr_b16 v[12:13], v155 offset:64
	ds_read_b64_tr_b16 v[16:17], v155 offset:96
	ds_read_b64_tr_b16 v[10:11], v155 offset:544
	ds_read_b64_tr_b16 v[6:7], v155 offset:576
	ds_read_b64_tr_b16 v[14:15], v155 offset:608
	ds_read_b64_tr_b16 v[18:19], v155 offset:640
	ds_read_b64_tr_b16 v[48:49], v155 offset:8704
	ds_read_b64_tr_b16 v[44:45], v155 offset:8736
	ds_read_b64_tr_b16 v[40:41], v155 offset:8768
	ds_read_b64_tr_b16 v[36:37], v155 offset:8800
	ds_read_b64_tr_b16 v[50:51], v155 offset:9248
	ds_read_b64_tr_b16 v[46:47], v155 offset:9280
	ds_read_b64_tr_b16 v[42:43], v155 offset:9312
	ds_read_b64_tr_b16 v[38:39], v155 offset:9344
	ds_read_b64_tr_b16 v[150:151], v156 offset:4352
	ds_read_b64_tr_b16 v[146:147], v156 offset:4384
	ds_read_b64_tr_b16 v[142:143], v156 offset:4416
	ds_read_b64_tr_b16 v[138:139], v156 offset:4448
	ds_read_b64_tr_b16 v[148:149], v157 offset:4352
	ds_read_b64_tr_b16 v[144:145], v157 offset:4384
	ds_read_b64_tr_b16 v[140:141], v157 offset:4416
	ds_read_b64_tr_b16 v[136:137], v157 offset:4448
	s_waitcnt lgkmcnt(0)
	ds_write_b32 v158, v171 offset:12288
.LBB0_354:
	s_mul_i32 s42, s2, 0x600
	v_lshl_add_u64 v[172:173], s[42:43], 1, v[2:3]
	v_add_co_u32_e32 v174, vcc, 0x1000, v172
	global_load_ushort v1, v[172:173], off offset:1024
	s_nop 0
	v_addc_co_u32_e32 v175, vcc, 0, v173, vcc
	v_add_co_u32_e32 v172, vcc, 0x2000, v172
	global_load_ushort v119, v[174:175], off
	global_load_ushort v121, v[174:175], off offset:3072
	v_addc_co_u32_e32 v173, vcc, 0, v173, vcc
	s_add_i32 s20, s42, 0x1800
	s_mov_b32 s21, s43
	global_load_ushort v123, v[172:173], off offset:2048
	v_lshl_add_u64 v[172:173], s[20:21], 1, v[2:3]
	s_add_i32 s20, s42, 0x1e00
	global_load_ushort v125, v[172:173], off offset:1024
	v_lshl_add_u64 v[172:173], s[20:21], 1, v[2:3]
	s_add_i32 s20, s42, 0x2400
	global_load_ushort v127, v[172:173], off offset:1024
	v_lshl_add_u64 v[172:173], s[20:21], 1, v[2:3]
	s_add_i32 s20, s42, 0x2a00
	global_load_ushort v129, v[172:173], off offset:1024
	v_lshl_add_u64 v[172:173], s[20:21], 1, v[2:3]
	s_add_i32 s20, s42, 0x3000
	global_load_ushort v131, v[172:173], off offset:1024
	v_lshl_add_u64 v[172:173], s[20:21], 1, v[2:3]
	s_add_i32 s20, s42, 0x3600
	global_load_ushort v133, v[172:173], off offset:1024
	v_lshl_add_u64 v[172:173], s[20:21], 1, v[2:3]
	s_add_i32 s20, s42, 0x3c00
	global_load_ushort v135, v[172:173], off offset:1024
	v_lshl_add_u64 v[172:173], s[20:21], 1, v[2:3]
	s_add_i32 s20, s42, 0x4200
	global_load_ushort v174, v[172:173], off offset:1024
	v_lshl_add_u64 v[172:173], s[20:21], 1, v[2:3]
	s_add_i32 s20, s42, 0x4800
	global_load_ushort v175, v[172:173], off offset:1024
	v_lshl_add_u64 v[172:173], s[20:21], 1, v[2:3]
	s_add_i32 s20, s42, 0x4e00
	global_load_ushort v176, v[172:173], off offset:1024
	v_lshl_add_u64 v[172:173], s[20:21], 1, v[2:3]
	s_add_i32 s20, s42, 0x5400
	global_load_ushort v177, v[172:173], off offset:1024
	v_lshl_add_u64 v[172:173], s[20:21], 1, v[2:3]
	s_addk_i32 s42, 0x5a00
	global_load_ushort v178, v[172:173], off offset:1024
	v_lshl_add_u64 v[172:173], s[42:43], 1, v[2:3]
	global_load_ushort v172, v[172:173], off offset:1024
	s_mulk_i32 s2, 0x88
	v_add_u32_e32 v173, s2, v159
	s_add_i32 s3, s2, 0x88
	s_and_b64 vcc, exec, s[4:5]
	s_mov_b64 s[4:5], 0
	s_waitcnt vmcnt(0) lgkmcnt(0)
	ds_write_b16 v173, v1 offset:13056
	v_add_u32_e32 v1, s3, v159
	s_add_i32 s3, s2, 0x110
	ds_write_b16 v1, v119 offset:13056
	v_add_u32_e32 v1, s3, v159
	s_add_i32 s3, s2, 0x198
	ds_write_b16 v1, v121 offset:13056
	v_add_u32_e32 v1, s3, v159
	s_add_i32 s3, s2, 0x220
	ds_write_b16 v1, v123 offset:13056
	v_add_u32_e32 v1, s3, v159
	s_add_i32 s3, s2, 0x2a8
	ds_write_b16 v1, v125 offset:13056
	v_add_u32_e32 v1, s3, v159
	s_add_i32 s3, s2, 0x330
	ds_write_b16 v1, v127 offset:13056
	v_add_u32_e32 v1, s3, v159
	s_add_i32 s3, s2, 0x3b8
	ds_write_b16 v1, v129 offset:13056
	v_add_u32_e32 v1, s3, v159
	s_add_i32 s3, s2, 0x440
	ds_write_b16 v1, v131 offset:13056
	v_add_u32_e32 v1, s3, v159
	s_add_i32 s3, s2, 0x4c8
	ds_write_b16 v1, v133 offset:13056
	v_add_u32_e32 v1, s3, v159
	s_add_i32 s3, s2, 0x550
	ds_write_b16 v1, v135 offset:13056
	v_add_u32_e32 v1, s3, v159
	s_add_i32 s3, s2, 0x5d8
	ds_write_b16 v1, v174 offset:13056
	v_add_u32_e32 v1, s3, v159
	s_add_i32 s3, s2, 0x660
	ds_write_b16 v1, v175 offset:13056
	v_add_u32_e32 v1, s3, v159
	s_add_i32 s3, s2, 0x6e8
	ds_write_b16 v1, v176 offset:13056
	v_add_u32_e32 v1, s3, v159
	s_add_i32 s3, s2, 0x770
	ds_write_b16 v1, v177 offset:13056
	v_add_u32_e32 v1, s3, v159
	s_addk_i32 s2, 0x7f8
	ds_write_b16 v1, v178 offset:13056
	v_add_u32_e32 v1, s2, v159
	ds_write_b16 v1, v172 offset:13056
	s_mov_b32 s2, 16
	s_cbranch_vccnz .LBB0_354
	v_mov_b32_e32 v1, v0
	v_mov_b32_e32 v2, v0
	v_mov_b32_e32 v3, v0
	v_mov_b32_e32 v125, v195
	s_or_b64 vcc, s[28:29], s[8:9]
	v_mfma_f32_16x16x32_bf16 v[172:175], v[72:75], v[96:99], v[0:3]
	v_lshl_add_u64 v[184:185], s[0:1], 0, v[124:125]
	s_mov_b64 s[2:3], 0x2000
	v_lshl_add_u64 v[186:187], v[184:185], 0, s[2:3]
	v_mfma_f32_16x16x32_bf16 v[176:179], v[72:75], v[84:87], v[0:3]
	s_add_u32 s4, s0, 0x5800
	s_addc_u32 s5, s1, 0
	s_mov_b64 s[2:3], 0x2800
	v_mfma_f32_16x16x32_bf16 v[96:99], v[20:23], v[96:99], v[0:3]
	v_mov_b32_e32 v135, v195
	v_mfma_f32_16x16x32_bf16 v[84:87], v[20:23], v[84:87], v[0:3]
	v_mfma_f32_16x16x32_bf16 v[172:175], v[60:63], v[92:95], v[172:175]
	v_mfma_f32_16x16x32_bf16 v[176:179], v[60:63], v[80:83], v[176:179]
	v_mfma_f32_16x16x32_bf16 v[92:95], v[28:31], v[92:95], v[96:99]
	s_nop 5
	v_cndmask_b32_e64 v125, v0, v175, s[14:15]
	v_cndmask_b32_e64 v127, v0, v174, s[70:71]
	v_cndmask_b32_e64 v129, v0, v173, s[28:29]
	v_mfma_f32_16x16x32_bf16 v[80:83], v[28:31], v[80:83], v[84:87]
	v_cndmask_b32_e32 v131, v0, v172, vcc
	v_cndmask_b32_e64 v119, v176, v0, s[10:11]
	v_cndmask_b32_e64 v95, v0, v95, s[14:15]
	v_mfma_f32_16x16x32_bf16 v[96:99], v[24:27], v[88:91], v[0:3]
	v_cndmask_b32_e64 v94, v0, v94, s[70:71]
	v_cndmask_b32_e64 v93, v0, v93, s[28:29]
	v_cndmask_b32_e32 v92, v0, v92, vcc
	v_mfma_f32_16x16x32_bf16 v[172:175], v[72:75], v[88:91], v[0:3]
	v_cndmask_b32_e64 v119, v119, v176, s[8:9]
	v_cndmask_b32_e64 v121, v0, v177, s[8:9]
	v_cndmask_b32_e64 v123, v178, v0, s[12:13]
	v_mfma_f32_16x16x32_bf16 v[72:75], v[72:75], v[32:35], v[0:3]
	v_cndmask_b32_e64 v133, v179, v0, s[16:17]
	ds_write_b128 v160, v[92:95]
	v_cvt_pk_bf16_f32 v92, v131, v129
	v_cvt_pk_bf16_f32 v93, v127, v125
	v_cvt_pk_bf16_f32 v94, v0, v0
	v_cndmask_b32_e64 v84, v80, v0, s[10:11]
	ds_write_b64 v161, v[92:93] offset:4608
	v_cvt_pk_bf16_f32 v92, v119, v121
	v_cvt_pk_bf16_f32 v93, v123, v133
	v_mov_b32_e32 v95, v94
	v_cndmask_b32_e64 v80, v84, v80, s[8:9]
	v_cndmask_b32_e64 v81, v0, v81, s[8:9]
	v_mfma_f32_16x16x32_bf16 v[180:183], v[20:23], v[88:91], v[0:3]
	ds_write_b64 v161, v[92:93] offset:7168
	ds_write_b128 v160, v[0:3] offset:64
	ds_write_b64 v161, v[94:95] offset:4640
	ds_write_b64 v161, v[94:95] offset:7200
	v_cndmask_b32_e64 v93, v82, v0, s[12:13]
	v_mfma_f32_16x16x32_bf16 v[88:91], v[76:79], v[88:91], v[0:3]
	v_cndmask_b32_e64 v95, v83, v0, s[16:17]
	v_cvt_pk_bf16_f32 v92, v80, v81
	v_mov_b32_e32 v127, v195
	v_mfma_f32_16x16x32_bf16 v[76:79], v[76:79], v[32:35], v[0:3]
	v_mov_b32_e32 v129, v195
	v_cvt_pk_bf16_f32 v93, v93, v95
	v_mov_b32_e32 v95, v94
	v_mfma_f32_16x16x32_bf16 v[80:83], v[52:55], v[68:71], v[96:99]
	v_mov_b32_e32 v131, v195
	v_mov_b32_e32 v133, v195
	v_mov_b32_e32 v121, v167
	v_mfma_f32_16x16x32_bf16 v[96:99], v[60:63], v[68:71], v[172:175]
	v_mfma_f32_16x16x32_bf16 v[60:63], v[60:63], v[56:59], v[72:75]
	s_nop 1
	v_lshl_add_u64 v[172:173], v[186:187], 0, v[126:127]
	global_store_dwordx4 v[172:173], v[92:95], off
	v_mfma_f32_16x16x32_bf16 v[24:27], v[24:27], v[32:35], v[0:3]
	s_nop 1
	v_cvt_pk_bf16_f32 v72, v96, v97
	v_cvt_pk_bf16_f32 v75, v62, v63
	v_cvt_pk_bf16_f32 v74, v60, v61
	v_mfma_f32_16x16x32_bf16 v[20:23], v[20:23], v[32:35], v[0:3]
	v_cndmask_b32_e64 v60, v0, v80, s[8:9]
	v_cvt_pk_bf16_f32 v73, v98, v99
	v_add_u32_e32 v34, 0x1800, v163
	v_mfma_f32_16x16x32_bf16 v[84:87], v[28:31], v[68:71], v[180:183]
	v_mfma_f32_16x16x32_bf16 v[68:71], v[64:67], v[68:71], v[88:91]
	v_mfma_f32_16x16x32_bf16 v[62:65], v[64:67], v[56:59], v[76:79]
	s_nop 5
	ds_write_b128 v162, v[84:87]
	v_cndmask_b32_e64 v68, v0, v68, s[8:9]
	v_cndmask_b32_e64 v71, v0, v71, s[60:61]
	v_mfma_f32_16x16x32_bf16 v[24:27], v[52:55], v[56:59], v[24:27]
	v_cndmask_b32_e64 v70, v0, v70, s[30:31]
	v_cndmask_b32_e64 v61, v62, v0, s[10:11]
	v_cndmask_b32_e64 v66, v61, v62, s[8:9]
	v_mfma_f32_16x16x32_bf16 v[20:23], v[28:31], v[56:59], v[20:23]
	v_cndmask_b32_e64 v67, v0, v63, s[8:9]
	v_cndmask_b32_e64 v64, v64, v0, s[18:19]
	v_cndmask_b32_e64 v63, v0, v83, s[60:61]
	v_cndmask_b32_e64 v62, v0, v82, s[30:31]
	v_cndmask_b32_e64 v61, v0, v81, s[34:35]
	v_cndmask_b32_e64 v69, v0, v69, s[34:35]
	v_cndmask_b32_e64 v65, v65, v0, s[22:23]
	v_cndmask_b32_e64 v24, v24, v0, s[10:11]
	v_cndmask_b32_e64 v25, v25, v0, s[6:7]
	v_cndmask_b32_e64 v26, v26, v0, s[18:19]
	v_cndmask_b32_e64 v27, v27, v0, s[22:23]
	ds_write_b128 v162, v[60:63] offset:64
	v_cvt_pk_bf16_f32 v60, v68, v69
	v_cvt_pk_bf16_f32 v61, v70, v71
	v_add_u32_e32 v62, 0x1000, v163
	v_cvt_pk_bf16_f32 v32, v66, v67
	v_cvt_pk_bf16_f32 v33, v64, v65
	v_cvt_pk_bf16_f32 v20, v20, v21
	v_cvt_pk_bf16_f32 v21, v22, v23
	v_cvt_pk_bf16_f32 v22, v24, v25
	v_cvt_pk_bf16_f32 v23, v26, v27
	v_lshl_add_u64 v[24:25], v[186:187], 0, v[128:129]
	ds_write2_b64 v62, v[72:73], v[60:61] offset0:64 offset1:68
	ds_write2_b64 v34, v[74:75], v[32:33] offset0:128 offset1:132
	global_store_dwordx4 v[24:25], v[20:23], off
	s_waitcnt lgkmcnt(0)
	ds_read_b64_tr_b16 v[32:33], v155 offset:13056
	ds_read_b64_tr_b16 v[28:29], v155 offset:13088
	ds_read_b64_tr_b16 v[24:25], v155 offset:13120
	ds_read_b64_tr_b16 v[20:21], v155 offset:13152
	ds_read_b64_tr_b16 v[34:35], v155 offset:13600
	ds_read_b64_tr_b16 v[30:31], v155 offset:13632
	ds_read_b64_tr_b16 v[26:27], v155 offset:13664
	ds_read_b64_tr_b16 v[22:23], v155 offset:13696
	ds_read_b128 v[56:59], v164 offset:12288
	ds_read_b128 v[64:67], v164 offset:12352
	s_waitcnt lgkmcnt(5)
	v_mfma_f32_16x16x32_bf16 v[60:63], v[48:51], v[32:35], v[0:3]
	v_lshl_add_u64 v[52:53], v[184:185], 0, s[2:3]
	s_movk_i32 s2, 0x1000
	s_waitcnt lgkmcnt(1)
	s_nop 4
	v_pk_mul_f32 v[54:55], v[58:59], v[62:63]
	v_pk_mul_f32 v[60:61], v[56:57], v[60:61]
	s_nop 0
	v_cvt_pk_bf16_f32 v60, v60, v61
	v_cvt_pk_bf16_f32 v61, v54, v55
	v_lshl_add_u64 v[54:55], s[4:5], 0, v[102:103]
	global_store_dwordx2 v[54:55], v[60:61], off
	v_mfma_f32_16x16x32_bf16 v[60:63], v[48:51], v[28:31], v[0:3]
	v_add_co_u32_e32 v54, vcc, s2, v54
	s_add_u32 s2, s0, 0x4800
	s_nop 0
	v_addc_co_u32_e32 v55, vcc, 0, v55, vcc
	s_addc_u32 s3, s1, 0
	s_nop 2
	v_pk_mul_f32 v[62:63], v[58:59], v[62:63]
	v_pk_mul_f32 v[60:61], v[56:57], v[60:61]
	s_nop 0
	v_cvt_pk_bf16_f32 v60, v60, v61
	v_cvt_pk_bf16_f32 v61, v62, v63
	v_lshl_add_u64 v[62:63], s[4:5], 0, v[104:105]
	global_store_dwordx2 v[62:63], v[60:61], off
	v_mfma_f32_16x16x32_bf16 v[60:63], v[48:51], v[24:27], v[0:3]
	v_mfma_f32_16x16x32_bf16 v[48:51], v[48:51], v[20:23], v[0:3]
	s_nop 6
	v_mul_f32_e64 v62, v58, v62
	v_mul_f32_e64 v63, v59, v63
	v_pk_mul_f32 v[60:61], v[56:57], v[60:61]
	v_pk_mul_f32 v[48:49], v[56:57], v[48:49]
	v_cvt_pk_bf16_f32 v60, v60, v61
	v_cvt_pk_bf16_f32 v61, v62, v63
	v_add_u32_e32 v62, 0x3000, v165
	ds_read2_b32 v[56:57], v62 offset1:16
	v_pk_mul_f32 v[50:51], v[58:59], v[50:51]
	v_cvt_pk_bf16_f32 v48, v48, v49
	v_cvt_pk_bf16_f32 v49, v50, v51
	global_store_dwordx2 v[54:55], v[60:61], off
	global_store_dwordx2 v[54:55], v[48:49], off offset:2048
	v_lshlrev_b32_e32 v48, 16, v150
	v_and_b32_e32 v49, 0xffff0000, v150
	v_lshlrev_b32_e32 v50, 16, v151
	v_and_b32_e32 v51, 0xffff0000, v151
	v_lshlrev_b32_e32 v58, 16, v148
	v_and_b32_e32 v59, 0xffff0000, v148
	v_lshlrev_b32_e32 v60, 16, v149
	v_and_b32_e32 v61, 0xffff0000, v149
	s_waitcnt lgkmcnt(0)
	v_pk_mul_f32 v[48:49], v[56:57], v[48:49] op_sel_hi:[0,1]
	v_pk_mul_f32 v[50:51], v[56:57], v[50:51] op_sel_hi:[0,1]
	v_pk_mul_f32 v[58:59], v[56:57], v[58:59] op_sel_hi:[0,1]
	v_pk_mul_f32 v[60:61], v[56:57], v[60:61] op_sel_hi:[0,1]
	v_cvt_pk_bf16_f32 v48, v48, v49
	v_cvt_pk_bf16_f32 v49, v50, v51
	v_cvt_pk_bf16_f32 v50, v58, v59
	v_cvt_pk_bf16_f32 v51, v60, v61
	v_lshl_add_u64 v[58:59], v[52:53], 0, v[126:127]
	global_store_dwordx4 v[58:59], v[48:51], off
	v_lshlrev_b32_e32 v56, 16, v145
	s_nop 0
	v_mfma_f32_16x16x32_bf16 v[48:51], v[44:47], v[32:35], v[0:3]
	s_nop 7
	v_pk_mul_f32 v[50:51], v[66:67], v[50:51]
	v_pk_mul_f32 v[48:49], v[64:65], v[48:49]
	s_nop 0
	v_cvt_pk_bf16_f32 v48, v48, v49
	v_cvt_pk_bf16_f32 v49, v50, v51
	v_lshl_add_u64 v[50:51], s[4:5], 0, v[106:107]
	global_store_dwordx2 v[50:51], v[48:49], off
	v_mfma_f32_16x16x32_bf16 v[48:51], v[44:47], v[28:31], v[0:3]
	s_nop 7
	v_pk_mul_f32 v[50:51], v[66:67], v[50:51]
	v_pk_mul_f32 v[48:49], v[64:65], v[48:49]
	s_nop 0
	v_cvt_pk_bf16_f32 v48, v48, v49
	v_cvt_pk_bf16_f32 v49, v50, v51
	v_lshl_add_u64 v[50:51], s[4:5], 0, v[108:109]
	global_store_dwordx2 v[50:51], v[48:49], off
	v_mfma_f32_16x16x32_bf16 v[48:51], v[44:47], v[24:27], v[0:3]
	v_mfma_f32_16x16x32_bf16 v[44:47], v[44:47], v[20:23], v[0:3]
	s_nop 6
	v_mul_f32_e64 v50, v66, v50
	v_mul_f32_e64 v51, v67, v51
	v_pk_mul_f32 v[48:49], v[64:65], v[48:49]
	v_pk_mul_f32 v[46:47], v[66:67], v[46:47]
	v_pk_mul_f32 v[44:45], v[64:65], v[44:45]
	v_cvt_pk_bf16_f32 v48, v48, v49
	v_cvt_pk_bf16_f32 v49, v50, v51
	v_cvt_pk_bf16_f32 v44, v44, v45
	v_cvt_pk_bf16_f32 v45, v46, v47
	global_store_dwordx2 v[54:55], v[48:49], off offset:512
	global_store_dwordx2 v[54:55], v[44:45], off offset:2560
	v_lshlrev_b32_e32 v44, 16, v146
	v_and_b32_e32 v45, 0xffff0000, v146
	v_mov_b32_e32 v46, v57
	v_lshlrev_b32_e32 v48, 16, v147
	v_and_b32_e32 v49, 0xffff0000, v147
	v_lshlrev_b32_e32 v50, 16, v144
	v_and_b32_e32 v51, 0xffff0000, v144
	v_and_b32_e32 v57, 0xffff0000, v145
	v_pk_mul_f32 v[44:45], v[46:47], v[44:45] op_sel_hi:[0,1]
	v_pk_mul_f32 v[48:49], v[46:47], v[48:49] op_sel_hi:[0,1]
	v_pk_mul_f32 v[50:51], v[46:47], v[50:51] op_sel_hi:[0,1]
	v_pk_mul_f32 v[56:57], v[46:47], v[56:57] op_sel_hi:[0,1]
	v_cvt_pk_bf16_f32 v44, v44, v45
	v_cvt_pk_bf16_f32 v45, v48, v49
	v_cvt_pk_bf16_f32 v46, v50, v51
	v_cvt_pk_bf16_f32 v47, v56, v57
	v_lshl_add_u64 v[48:49], v[52:53], 0, v[128:129]
	global_store_dwordx4 v[48:49], v[44:47], off
	ds_read_b128 v[44:47], v164 offset:12416
	ds_read_b128 v[56:59], v164 offset:12480
	v_mfma_f32_16x16x32_bf16 v[48:51], v[40:43], v[32:35], v[0:3]
	s_waitcnt lgkmcnt(1)
	s_nop 6
	v_pk_mul_f32 v[50:51], v[46:47], v[50:51]
	v_pk_mul_f32 v[48:49], v[44:45], v[48:49]
	s_nop 0
	v_cvt_pk_bf16_f32 v48, v48, v49
	v_cvt_pk_bf16_f32 v49, v50, v51
	v_lshl_add_u64 v[50:51], s[4:5], 0, v[110:111]
	global_store_dwordx2 v[50:51], v[48:49], off
	v_mfma_f32_16x16x32_bf16 v[48:51], v[40:43], v[28:31], v[0:3]
	s_nop 7
	v_pk_mul_f32 v[50:51], v[46:47], v[50:51]
	v_pk_mul_f32 v[48:49], v[44:45], v[48:49]
	s_nop 0
	v_cvt_pk_bf16_f32 v48, v48, v49
	v_cvt_pk_bf16_f32 v49, v50, v51
	v_lshl_add_u64 v[50:51], s[4:5], 0, v[112:113]
	global_store_dwordx2 v[50:51], v[48:49], off
	v_mfma_f32_16x16x32_bf16 v[48:51], v[40:43], v[24:27], v[0:3]
	v_mfma_f32_16x16x32_bf16 v[40:43], v[40:43], v[20:23], v[0:3]
	s_nop 6
	v_mul_f32_e64 v48, v44, v48
	v_mul_f32_e64 v49, v45, v49
	v_pk_mul_f32 v[40:41], v[44:45], v[40:41]
	ds_read2_b32 v[44:45], v62 offset0:32 offset1:48
	v_pk_mul_f32 v[50:51], v[46:47], v[50:51]
	v_pk_mul_f32 v[42:43], v[46:47], v[42:43]
	v_cvt_pk_bf16_f32 v48, v48, v49
	v_cvt_pk_bf16_f32 v49, v50, v51
	v_cvt_pk_bf16_f32 v40, v40, v41
	v_cvt_pk_bf16_f32 v41, v42, v43
	global_store_dwordx2 v[54:55], v[48:49], off offset:1024
	global_store_dwordx2 v[54:55], v[40:41], off offset:3072
	v_lshlrev_b32_e32 v40, 16, v142
	v_and_b32_e32 v41, 0xffff0000, v142
	v_lshlrev_b32_e32 v42, 16, v143
	v_and_b32_e32 v43, 0xffff0000, v143
	v_lshlrev_b32_e32 v46, 16, v140
	v_and_b32_e32 v47, 0xffff0000, v140
	v_lshlrev_b32_e32 v48, 16, v141
	v_and_b32_e32 v49, 0xffff0000, v141
	s_waitcnt lgkmcnt(0)
	v_pk_mul_f32 v[40:41], v[44:45], v[40:41] op_sel_hi:[0,1]
	v_pk_mul_f32 v[42:43], v[44:45], v[42:43] op_sel_hi:[0,1]
	v_pk_mul_f32 v[46:47], v[44:45], v[46:47] op_sel_hi:[0,1]
	v_pk_mul_f32 v[48:49], v[44:45], v[48:49] op_sel_hi:[0,1]
	v_cvt_pk_bf16_f32 v40, v40, v41
	v_cvt_pk_bf16_f32 v41, v42, v43
	v_cvt_pk_bf16_f32 v42, v46, v47
	v_cvt_pk_bf16_f32 v43, v48, v49
	v_lshl_add_u64 v[46:47], v[52:53], 0, v[130:131]
	global_store_dwordx4 v[46:47], v[40:43], off
	s_nop 1
	v_mfma_f32_16x16x32_bf16 v[40:43], v[36:39], v[32:35], v[0:3]
	s_nop 7
	v_pk_mul_f32 v[42:43], v[58:59], v[42:43]
	v_pk_mul_f32 v[40:41], v[56:57], v[40:41]
	s_nop 0
	v_cvt_pk_bf16_f32 v40, v40, v41
	v_cvt_pk_bf16_f32 v41, v42, v43
	v_lshl_add_u64 v[42:43], s[4:5], 0, v[114:115]
	global_store_dwordx2 v[42:43], v[40:41], off
	v_mfma_f32_16x16x32_bf16 v[40:43], v[36:39], v[28:31], v[0:3]
	s_nop 7
	v_pk_mul_f32 v[42:43], v[58:59], v[42:43]
	v_pk_mul_f32 v[40:41], v[56:57], v[40:41]
	s_nop 0
	v_cvt_pk_bf16_f32 v40, v40, v41
	v_cvt_pk_bf16_f32 v41, v42, v43
	v_lshl_add_u64 v[42:43], s[4:5], 0, v[116:117]
	global_store_dwordx2 v[42:43], v[40:41], off
	v_mfma_f32_16x16x32_bf16 v[40:43], v[36:39], v[24:27], v[0:3]
	v_mfma_f32_16x16x32_bf16 v[36:39], v[36:39], v[20:23], v[0:3]
	s_nop 6
	v_mul_f32_e64 v42, v58, v42
	v_mul_f32_e64 v43, v59, v43
	v_pk_mul_f32 v[38:39], v[58:59], v[38:39]
	v_pk_mul_f32 v[36:37], v[56:57], v[36:37]
	v_pk_mul_f32 v[40:41], v[56:57], v[40:41]
	v_cvt_pk_bf16_f32 v36, v36, v37
	v_cvt_pk_bf16_f32 v37, v38, v39
	v_cvt_pk_bf16_f32 v40, v40, v41
	v_cvt_pk_bf16_f32 v41, v42, v43
	global_store_dwordx2 v[54:55], v[36:37], off offset:3584
	v_lshlrev_b32_e32 v36, 16, v138
	v_and_b32_e32 v37, 0xffff0000, v138
	v_mov_b32_e32 v38, v45
	v_lshlrev_b32_e32 v42, 16, v136
	v_and_b32_e32 v43, 0xffff0000, v136
	global_store_dwordx2 v[54:55], v[40:41], off offset:1536
	v_pk_mul_f32 v[36:37], v[38:39], v[36:37] op_sel_hi:[0,1]
	v_lshlrev_b32_e32 v40, 16, v139
	v_and_b32_e32 v41, 0xffff0000, v139
	v_pk_mul_f32 v[46:47], v[38:39], v[42:43] op_sel_hi:[0,1]
	v_lshlrev_b32_e32 v42, 16, v137
	v_and_b32_e32 v43, 0xffff0000, v137
	v_pk_mul_f32 v[40:41], v[38:39], v[40:41] op_sel_hi:[0,1]
	v_pk_mul_f32 v[48:49], v[38:39], v[42:43] op_sel_hi:[0,1]
	v_cvt_pk_bf16_f32 v38, v36, v37
	v_add_u32_e32 v36, v164, v166
	ds_read_b128 v[42:45], v36 offset:7168
	v_cvt_pk_bf16_f32 v39, v40, v41
	v_cvt_pk_bf16_f32 v40, v46, v47
	v_cvt_pk_bf16_f32 v41, v48, v49
	v_lshl_add_u64 v[46:47], v[52:53], 0, v[132:133]
	global_store_dwordx4 v[46:47], v[38:41], off
	ds_read_b128 v[38:41], v36 offset:8448
	s_waitcnt lgkmcnt(1)
	v_mfma_f32_16x16x32_bf16 v[46:49], v[42:45], v[32:35], v[0:3]
	v_mov_b32_e32 v37, v167
	s_nop 6
	v_cvt_pk_bf16_f32 v46, v46, v47
	v_cvt_pk_bf16_f32 v47, v48, v49
	v_lshl_add_u64 v[48:49], s[2:3], 0, v[102:103]
	global_store_dwordx2 v[48:49], v[46:47], off
	s_waitcnt lgkmcnt(0)
	v_mfma_f32_16x16x32_bf16 v[46:49], v[38:41], v[32:35], v[0:3]
	s_nop 7
	v_cvt_pk_bf16_f32 v46, v46, v47
	v_cvt_pk_bf16_f32 v47, v48, v49
	v_lshl_add_u64 v[48:49], s[2:3], 0, v[106:107]
	global_store_dwordx2 v[48:49], v[46:47], off
	v_mfma_f32_16x16x32_bf16 v[46:49], v[42:45], v[28:31], v[0:3]
	s_nop 7
	v_cvt_pk_bf16_f32 v46, v46, v47
	v_cvt_pk_bf16_f32 v47, v48, v49
	v_lshl_add_u64 v[48:49], s[2:3], 0, v[110:111]
	global_store_dwordx2 v[48:49], v[46:47], off
	v_mfma_f32_16x16x32_bf16 v[46:49], v[38:41], v[28:31], v[0:3]
	s_nop 7
	v_cvt_pk_bf16_f32 v46, v46, v47
	v_cvt_pk_bf16_f32 v47, v48, v49
	v_lshl_add_u64 v[48:49], s[2:3], 0, v[114:115]
	global_store_dwordx2 v[48:49], v[46:47], off
	v_mfma_f32_16x16x32_bf16 v[46:49], v[42:45], v[24:27], v[0:3]
	v_mfma_f32_16x16x32_bf16 v[42:45], v[42:45], v[20:23], v[0:3]
	s_nop 6
	v_cvt_pk_bf16_f32 v46, v46, v47
	v_cvt_pk_bf16_f32 v47, v48, v49
	v_lshl_add_u64 v[48:49], s[2:3], 0, v[104:105]
	global_store_dwordx2 v[48:49], v[46:47], off
	v_mfma_f32_16x16x32_bf16 v[46:49], v[38:41], v[24:27], v[0:3]
	v_cvt_pk_bf16_f32 v42, v42, v43
	v_cvt_pk_bf16_f32 v43, v44, v45
	v_lshl_add_u64 v[44:45], s[2:3], 0, v[112:113]
	v_mfma_f32_16x16x32_bf16 v[38:41], v[38:41], v[20:23], v[0:3]
	global_store_dwordx2 v[44:45], v[42:43], off
	s_nop 2
	v_cvt_pk_bf16_f32 v46, v46, v47
	v_cvt_pk_bf16_f32 v47, v48, v49
	v_lshl_add_u64 v[48:49], s[2:3], 0, v[108:109]
	global_store_dwordx2 v[48:49], v[46:47], off
	v_cvt_pk_bf16_f32 v38, v38, v39
	v_cvt_pk_bf16_f32 v39, v40, v41
	v_lshl_add_u64 v[40:41], s[2:3], 0, v[116:117]
	global_store_dwordx2 v[40:41], v[38:39], off
	s_waitcnt lgkmcnt(0)
	v_mov_b32_e32 v42, v167
	v_cmp_eq_u32_e32 vcc, 0, v37
	v_mov_b32_e32 v43, s68
	s_add_u32 s2, s0, 0x3800
	v_cndmask_b32_e64 v37, 0, 1.0, vcc
	ds_read_b128 v[38:41], v43 offset:144
	v_cmp_eq_u32_e32 vcc, 1, v42
	s_addc_u32 s3, s1, 0
	s_add_i32 s63, s63, s80
	v_cndmask_b32_e64 v42, 0, 1.0, vcc
	s_waitcnt lgkmcnt(0)
	v_mul_f32_e32 v39, 0, v39
	v_fmac_f32_e32 v39, v37, v38
	v_fmac_f32_e32 v39, 0, v40
	v_fmac_f32_e32 v39, 0, v41
	v_add_f32_e32 v38, v42, v39
	v_mov_b32_e32 v39, v167
	ds_read_b128 v[44:47], v43 offset:288
	v_cmp_eq_u32_e32 vcc, 2, v39
	s_cmpk_lt_i32 s63, 0x800
	s_waitcnt lgkmcnt(0)
	v_mul_f32_e32 v40, v38, v45
	v_fmac_f32_e32 v40, v37, v44
	v_fmac_f32_e32 v40, 0, v46
	v_cndmask_b32_e64 v39, 0, 1.0, vcc
	v_fmac_f32_e32 v40, 0, v47
	v_add_f32_e32 v39, v39, v40
	v_mov_b32_e32 v40, v167
	ds_read_b128 v[44:47], v43 offset:432
	v_cmp_eq_u32_e32 vcc, 3, v40
	s_waitcnt lgkmcnt(0)
	v_mul_f32_e32 v41, v38, v45
	v_fmac_f32_e32 v41, v37, v44
	v_fmac_f32_e32 v41, v39, v46
	v_cndmask_b32_e64 v40, 0, 1.0, vcc
	v_fmac_f32_e32 v41, 0, v47
	v_add_f32_e32 v40, v40, v41
	v_mov_b32_e32 v41, v167
	ds_read_b128 v[44:47], v43 offset:576
	v_cmp_eq_u32_e32 vcc, 4, v41
	s_waitcnt lgkmcnt(0)
	v_mul_f32_e32 v42, v38, v45
	v_fmac_f32_e32 v42, v37, v44
	v_fmac_f32_e32 v42, v39, v46
	v_cndmask_b32_e64 v41, 0, 1.0, vcc
	v_fmac_f32_e32 v42, v40, v47
	v_add_f32_e32 v41, v41, v42
	v_mov_b32_e32 v42, v167
	ds_read_b128 v[44:47], v43 offset:720
	ds_read_b128 v[48:51], v43 offset:736
	v_cmp_eq_u32_e32 vcc, 5, v42
	s_waitcnt lgkmcnt(1)
	v_mul_f32_e32 v45, v38, v45
	v_fmac_f32_e32 v45, v37, v44
	s_waitcnt lgkmcnt(0)
	v_mul_f32_e32 v44, 0, v49
	v_fmac_f32_e32 v45, v39, v46
	v_fmac_f32_e32 v44, v41, v48
	v_cndmask_b32_e64 v42, 0, 1.0, vcc
	v_fmac_f32_e32 v45, v40, v47
	v_fmac_f32_e32 v44, 0, v50
	v_add_f32_e32 v42, v42, v45
	v_fmac_f32_e32 v44, 0, v51
	v_add_f32_e32 v42, v42, v44
	v_mov_b32_e32 v48, v167
	ds_read_b128 v[44:47], v43 offset:864
	v_cmp_eq_u32_e32 vcc, 6, v48
	ds_read_b128 v[48:51], v43 offset:880
	s_waitcnt lgkmcnt(1)
	v_mul_f32_e32 v45, v38, v45
	v_fmac_f32_e32 v45, v37, v44
	v_fmac_f32_e32 v45, v39, v46
	v_cndmask_b32_e64 v52, 0, 1.0, vcc
	v_fmac_f32_e32 v45, v40, v47
	v_add_f32_e32 v44, v52, v45
	s_waitcnt lgkmcnt(0)
	v_mul_f32_e32 v45, v42, v49
	v_fmac_f32_e32 v45, v41, v48
	v_fmac_f32_e32 v45, 0, v50
	v_fmac_f32_e32 v45, 0, v51
	v_add_f32_e32 v44, v44, v45
	v_mov_b32_e32 v45, v167
	ds_read_b128 v[46:49], v43 offset:1008
	ds_read_b128 v[50:53], v43 offset:1024
	v_cmp_eq_u32_e32 vcc, 7, v45
	s_waitcnt lgkmcnt(1)
	v_mul_f32_e32 v47, v38, v47
	v_fmac_f32_e32 v47, v37, v46
	s_waitcnt lgkmcnt(0)
	v_mul_f32_e32 v46, v42, v51
	v_fmac_f32_e32 v47, v39, v48
	v_fmac_f32_e32 v46, v41, v50
	v_cndmask_b32_e64 v45, 0, 1.0, vcc
	v_fmac_f32_e32 v47, v40, v49
	v_fmac_f32_e32 v46, v44, v52
	v_add_f32_e32 v45, v45, v47
	v_fmac_f32_e32 v46, 0, v53
	v_add_f32_e32 v45, v45, v46
	v_mov_b32_e32 v50, v167
	ds_read_b128 v[46:49], v43 offset:1152
	v_cmp_eq_u32_e32 vcc, 8, v50
	ds_read_b128 v[50:53], v43 offset:1168
	s_waitcnt lgkmcnt(1)
	v_mul_f32_e32 v47, v38, v47
	v_fmac_f32_e32 v47, v37, v46
	v_fmac_f32_e32 v47, v39, v48
	v_cndmask_b32_e64 v54, 0, 1.0, vcc
	v_fmac_f32_e32 v47, v40, v49
	v_add_f32_e32 v46, v54, v47
	s_waitcnt lgkmcnt(0)
	v_mul_f32_e32 v47, v42, v51
	v_fmac_f32_e32 v47, v41, v50
	v_fmac_f32_e32 v47, v44, v52
	v_fmac_f32_e32 v47, v45, v53
	v_add_f32_e32 v46, v46, v47
	v_mov_b32_e32 v47, v167
	ds_read_b128 v[48:51], v43 offset:1296
	ds_read_b128 v[52:55], v43 offset:1312
	ds_read_b128 v[56:59], v43 offset:1328
	v_cmp_eq_u32_e32 vcc, 9, v47
	s_waitcnt lgkmcnt(2)
	v_mul_f32_e32 v49, v38, v49
	v_fmac_f32_e32 v49, v37, v48
	s_waitcnt lgkmcnt(1)
	v_mul_f32_e32 v48, v42, v53
	v_fmac_f32_e32 v49, v39, v50
	v_fmac_f32_e32 v48, v41, v52
	v_cndmask_b32_e64 v47, 0, 1.0, vcc
	v_fmac_f32_e32 v49, v40, v51
	v_fmac_f32_e32 v48, v44, v54
	v_add_f32_e32 v47, v47, v49
	v_fmac_f32_e32 v48, v45, v55
	v_add_f32_e32 v47, v47, v48
	s_waitcnt lgkmcnt(0)
	v_mul_f32_e32 v48, 0, v57
	v_fmac_f32_e32 v48, v46, v56
	v_fmac_f32_e32 v48, 0, v58
	v_fmac_f32_e32 v48, 0, v59
	v_add_f32_e32 v47, v47, v48
	v_mov_b32_e32 v52, v167
	ds_read_b128 v[48:51], v43 offset:1440
	v_cmp_eq_u32_e32 vcc, 10, v52
	ds_read_b128 v[52:55], v43 offset:1456
	ds_read_b128 v[56:59], v43 offset:1472
	v_cndmask_b32_e64 v60, 0, 1.0, vcc
	s_waitcnt lgkmcnt(2)
	v_mul_f32_e32 v49, v38, v49
	v_fmac_f32_e32 v49, v37, v48
	v_fmac_f32_e32 v49, v39, v50
	v_fmac_f32_e32 v49, v40, v51
	v_add_f32_e32 v48, v60, v49
	s_waitcnt lgkmcnt(1)
	v_mul_f32_e32 v49, v42, v53
	v_fmac_f32_e32 v49, v41, v52
	v_fmac_f32_e32 v49, v44, v54
	v_fmac_f32_e32 v49, v45, v55
	v_add_f32_e32 v48, v48, v49
	s_waitcnt lgkmcnt(0)
	v_mul_f32_e32 v49, v47, v57
	v_fmac_f32_e32 v49, v46, v56
	v_fmac_f32_e32 v49, 0, v58
	v_fmac_f32_e32 v49, 0, v59
	v_add_f32_e32 v48, v48, v49
	v_mov_b32_e32 v49, v167
	ds_read_b128 v[50:53], v43 offset:1584
	ds_read_b128 v[54:57], v43 offset:1600
	ds_read_b128 v[58:61], v43 offset:1616
	v_cmp_eq_u32_e32 vcc, 11, v49
	s_waitcnt lgkmcnt(2)
	v_mul_f32_e32 v51, v38, v51
	v_fmac_f32_e32 v51, v37, v50
	s_waitcnt lgkmcnt(1)
	v_mul_f32_e32 v50, v42, v55
	v_fmac_f32_e32 v51, v39, v52
	v_fmac_f32_e32 v50, v41, v54
	v_cndmask_b32_e64 v49, 0, 1.0, vcc
	v_fmac_f32_e32 v51, v40, v53
	v_fmac_f32_e32 v50, v44, v56
	v_add_f32_e32 v49, v49, v51
	v_fmac_f32_e32 v50, v45, v57
	v_add_f32_e32 v49, v49, v50
	s_waitcnt lgkmcnt(0)
	v_mul_f32_e32 v50, v47, v59
	v_fmac_f32_e32 v50, v46, v58
	v_fmac_f32_e32 v50, v48, v60
	v_fmac_f32_e32 v50, 0, v61
	v_add_f32_e32 v49, v49, v50
	v_mov_b32_e32 v54, v167
	ds_read_b128 v[50:53], v43 offset:1728
	v_cmp_eq_u32_e32 vcc, 12, v54
	ds_read_b128 v[54:57], v43 offset:1744
	ds_read_b128 v[58:61], v43 offset:1760
	v_cndmask_b32_e64 v62, 0, 1.0, vcc
	s_waitcnt lgkmcnt(2)
	v_mul_f32_e32 v51, v38, v51
	v_fmac_f32_e32 v51, v37, v50
	v_fmac_f32_e32 v51, v39, v52
	v_fmac_f32_e32 v51, v40, v53
	v_add_f32_e32 v50, v62, v51
	s_waitcnt lgkmcnt(1)
	v_mul_f32_e32 v51, v42, v55
	v_fmac_f32_e32 v51, v41, v54
	v_fmac_f32_e32 v51, v44, v56
	v_fmac_f32_e32 v51, v45, v57
	v_add_f32_e32 v50, v50, v51
	s_waitcnt lgkmcnt(0)
	v_mul_f32_e32 v51, v47, v59
	v_fmac_f32_e32 v51, v46, v58
	v_fmac_f32_e32 v51, v48, v60
	v_fmac_f32_e32 v51, v49, v61
	v_add_f32_e32 v50, v50, v51
	v_mov_b32_e32 v51, v167
	ds_read_b128 v[52:55], v43 offset:1872
	ds_read_b128 v[56:59], v43 offset:1888
	ds_read_b128 v[60:63], v43 offset:1904
	ds_read_b128 v[64:67], v43 offset:1920
	v_cmp_eq_u32_e32 vcc, 13, v51
	s_waitcnt lgkmcnt(3)
	v_mul_f32_e32 v53, v38, v53
	v_fmac_f32_e32 v53, v37, v52
	s_waitcnt lgkmcnt(2)
	v_mul_f32_e32 v52, v42, v57
	v_fmac_f32_e32 v53, v39, v54
	v_fmac_f32_e32 v52, v41, v56
	v_cndmask_b32_e64 v51, 0, 1.0, vcc
	v_fmac_f32_e32 v53, v40, v55
	v_fmac_f32_e32 v52, v44, v58
	v_add_f32_e32 v51, v51, v53
	v_fmac_f32_e32 v52, v45, v59
	v_add_f32_e32 v51, v51, v52
	s_waitcnt lgkmcnt(1)
	v_mul_f32_e32 v52, v47, v61
	v_fmac_f32_e32 v52, v46, v60
	v_fmac_f32_e32 v52, v48, v62
	v_fmac_f32_e32 v52, v49, v63
	v_add_f32_e32 v51, v51, v52
	s_waitcnt lgkmcnt(0)
	v_mul_f32_e32 v52, 0, v65
	v_fmac_f32_e32 v52, v50, v64
	v_fmac_f32_e32 v52, 0, v66
	v_fmac_f32_e32 v52, 0, v67
	v_add_f32_e32 v51, v51, v52
	v_mov_b32_e32 v56, v167
	ds_read_b128 v[52:55], v43 offset:2016
	v_cmp_eq_u32_e32 vcc, 14, v56
	ds_read_b128 v[56:59], v43 offset:2032
	ds_read_b128 v[60:63], v43 offset:2048
	ds_read_b128 v[64:67], v43 offset:2064
	v_cndmask_b32_e64 v68, 0, 1.0, vcc
	s_waitcnt lgkmcnt(3)
	v_mul_f32_e32 v53, v38, v53
	v_fmac_f32_e32 v53, v37, v52
	v_fmac_f32_e32 v53, v39, v54
	v_fmac_f32_e32 v53, v40, v55
	v_add_f32_e32 v52, v68, v53
	s_waitcnt lgkmcnt(2)
	v_mul_f32_e32 v53, v42, v57
	v_fmac_f32_e32 v53, v41, v56
	v_fmac_f32_e32 v53, v44, v58
	v_fmac_f32_e32 v53, v45, v59
	v_add_f32_e32 v52, v52, v53
	s_waitcnt lgkmcnt(1)
	v_mul_f32_e32 v53, v47, v61
	v_fmac_f32_e32 v53, v46, v60
	v_fmac_f32_e32 v53, v48, v62
	v_fmac_f32_e32 v53, v49, v63
	v_add_f32_e32 v52, v52, v53
	s_waitcnt lgkmcnt(0)
	v_mul_f32_e32 v53, v51, v65
	v_fmac_f32_e32 v53, v50, v64
	v_fmac_f32_e32 v53, 0, v66
	v_fmac_f32_e32 v53, 0, v67
	v_add_f32_e32 v52, v52, v53
	v_mov_b32_e32 v53, v167
	ds_read_b128 v[54:57], v43 offset:2160
	ds_read_b128 v[58:61], v43 offset:2176
	ds_read_b128 v[62:65], v43 offset:2192
	ds_read_b128 v[66:69], v43 offset:2208
	v_cmp_eq_u32_e32 vcc, 15, v53
	s_waitcnt lgkmcnt(3)
	v_mul_f32_e32 v55, v38, v55
	v_fmac_f32_e32 v55, v37, v54
	s_waitcnt lgkmcnt(2)
	v_mul_f32_e32 v54, v42, v59
	v_fmac_f32_e32 v55, v39, v56
	v_fmac_f32_e32 v54, v41, v58
	v_cndmask_b32_e64 v53, 0, 1.0, vcc
	v_fmac_f32_e32 v55, v40, v57
	v_fmac_f32_e32 v54, v44, v60
	v_add_f32_e32 v53, v53, v55
	v_fmac_f32_e32 v54, v45, v61
	v_add_f32_e32 v53, v53, v54
	s_waitcnt lgkmcnt(1)
	v_mul_f32_e32 v54, v47, v63
	v_fmac_f32_e32 v54, v46, v62
	v_fmac_f32_e32 v54, v48, v64
	v_fmac_f32_e32 v54, v49, v65
	v_add_f32_e32 v53, v53, v54
	s_waitcnt lgkmcnt(0)
	v_mul_f32_e32 v54, v51, v67
	v_fmac_f32_e32 v54, v50, v66
	v_fmac_f32_e32 v54, v52, v68
	v_fmac_f32_e32 v54, 0, v69
	v_add_f32_e32 v53, v53, v54
	v_mov_b32_e32 v58, v167
	ds_read_b128 v[54:57], v43 offset:2304
	v_cmp_eq_u32_e32 vcc, 16, v58
	ds_read_b128 v[58:61], v43 offset:2320
	ds_read_b128 v[62:65], v43 offset:2336
	ds_read_b128 v[66:69], v43 offset:2352
	v_cndmask_b32_e64 v70, 0, 1.0, vcc
	s_waitcnt lgkmcnt(3)
	v_mul_f32_e32 v55, v38, v55
	v_fmac_f32_e32 v55, v37, v54
	v_fmac_f32_e32 v55, v39, v56
	v_fmac_f32_e32 v55, v40, v57
	v_add_f32_e32 v54, v70, v55
	s_waitcnt lgkmcnt(2)
	v_mul_f32_e32 v55, v42, v59
	v_fmac_f32_e32 v55, v41, v58
	v_fmac_f32_e32 v55, v44, v60
	v_fmac_f32_e32 v55, v45, v61
	v_add_f32_e32 v54, v54, v55
	s_waitcnt lgkmcnt(1)
	v_mul_f32_e32 v55, v47, v63
	v_fmac_f32_e32 v55, v46, v62
	v_fmac_f32_e32 v55, v48, v64
	v_fmac_f32_e32 v55, v49, v65
	v_add_f32_e32 v54, v54, v55
	s_waitcnt lgkmcnt(0)
	v_mul_f32_e32 v55, v51, v67
	v_fmac_f32_e32 v55, v50, v66
	v_fmac_f32_e32 v55, v52, v68
	v_fmac_f32_e32 v55, v53, v69
	v_add_f32_e32 v54, v54, v55
	v_mov_b32_e32 v55, v167
	ds_read_b128 v[56:59], v43 offset:2448
	ds_read_b128 v[60:63], v43 offset:2464
	ds_read_b128 v[64:67], v43 offset:2480
	ds_read_b128 v[68:71], v43 offset:2496
	v_cmp_eq_u32_e32 vcc, 17, v55
	s_waitcnt lgkmcnt(3)
	v_mul_f32_e32 v57, v38, v57
	v_fmac_f32_e32 v57, v37, v56
	s_waitcnt lgkmcnt(2)
	v_mul_f32_e32 v56, v42, v61
	v_fmac_f32_e32 v57, v39, v58
	v_fmac_f32_e32 v56, v41, v60
	v_cndmask_b32_e64 v55, 0, 1.0, vcc
	v_fmac_f32_e32 v57, v40, v59
	v_fmac_f32_e32 v56, v44, v62
	v_add_f32_e32 v55, v55, v57
	v_fmac_f32_e32 v56, v45, v63
	v_add_f32_e32 v55, v55, v56
	s_waitcnt lgkmcnt(1)
	v_mul_f32_e32 v56, v47, v65
	v_fmac_f32_e32 v56, v46, v64
	v_fmac_f32_e32 v56, v48, v66
	v_fmac_f32_e32 v56, v49, v67
	v_add_f32_e32 v55, v55, v56
	ds_read_b128 v[56:59], v43 offset:2512
	s_waitcnt lgkmcnt(1)
	v_mul_f32_e32 v60, v51, v69
	v_fmac_f32_e32 v60, v50, v68
	v_fmac_f32_e32 v60, v52, v70
	v_fmac_f32_e32 v60, v53, v71
	s_waitcnt lgkmcnt(0)
	v_mul_f32_e32 v57, 0, v57
	v_fmac_f32_e32 v57, v54, v56
	v_fmac_f32_e32 v57, 0, v58
	v_add_f32_e32 v55, v55, v60
	v_fmac_f32_e32 v57, 0, v59
	v_add_f32_e32 v55, v55, v57
	v_mov_b32_e32 v60, v167
	ds_read_b128 v[56:59], v43 offset:2592
	v_cmp_eq_u32_e32 vcc, 18, v60
	ds_read_b128 v[60:63], v43 offset:2608
	ds_read_b128 v[64:67], v43 offset:2624
	ds_read_b128 v[68:71], v43 offset:2640
	v_cndmask_b32_e64 v72, 0, 1.0, vcc
	s_waitcnt lgkmcnt(3)
	v_mul_f32_e32 v57, v38, v57
	v_fmac_f32_e32 v57, v37, v56
	v_fmac_f32_e32 v57, v39, v58
	v_fmac_f32_e32 v57, v40, v59
	v_add_f32_e32 v56, v72, v57
	s_waitcnt lgkmcnt(2)
	v_mul_f32_e32 v57, v42, v61
	v_fmac_f32_e32 v57, v41, v60
	v_fmac_f32_e32 v57, v44, v62
	v_fmac_f32_e32 v57, v45, v63
	v_add_f32_e32 v56, v56, v57
	s_waitcnt lgkmcnt(1)
	v_mul_f32_e32 v57, v47, v65
	v_fmac_f32_e32 v57, v46, v64
	v_fmac_f32_e32 v57, v48, v66
	v_fmac_f32_e32 v57, v49, v67
	v_add_f32_e32 v60, v56, v57
	ds_read_b128 v[56:59], v43 offset:2656
	s_waitcnt lgkmcnt(1)
	v_mul_f32_e32 v61, v51, v69
	v_fmac_f32_e32 v61, v50, v68
	v_fmac_f32_e32 v61, v52, v70
	v_fmac_f32_e32 v61, v53, v71
	s_waitcnt lgkmcnt(0)
	v_mul_f32_e32 v57, v55, v57
	v_fmac_f32_e32 v57, v54, v56
	v_fmac_f32_e32 v57, 0, v58
	v_add_f32_e32 v60, v60, v61
	v_fmac_f32_e32 v57, 0, v59
	v_add_f32_e32 v56, v60, v57
	v_mov_b32_e32 v57, v167
	ds_read_b128 v[58:61], v43 offset:2736
	ds_read_b128 v[62:65], v43 offset:2752
	ds_read_b128 v[66:69], v43 offset:2768
	ds_read_b128 v[70:73], v43 offset:2784
	v_cmp_eq_u32_e32 vcc, 19, v57
	s_waitcnt lgkmcnt(3)
	v_mul_f32_e32 v59, v38, v59
	v_fmac_f32_e32 v59, v37, v58
	s_waitcnt lgkmcnt(2)
	v_mul_f32_e32 v58, v42, v63
	v_fmac_f32_e32 v59, v39, v60
	v_fmac_f32_e32 v58, v41, v62
	v_cndmask_b32_e64 v57, 0, 1.0, vcc
	v_fmac_f32_e32 v59, v40, v61
	v_fmac_f32_e32 v58, v44, v64
	v_add_f32_e32 v57, v57, v59
	v_fmac_f32_e32 v58, v45, v65
	v_add_f32_e32 v57, v57, v58
	s_waitcnt lgkmcnt(1)
	v_mul_f32_e32 v58, v47, v67
	v_fmac_f32_e32 v58, v46, v66
	v_fmac_f32_e32 v58, v48, v68
	v_fmac_f32_e32 v58, v49, v69
	v_add_f32_e32 v57, v57, v58
	ds_read_b128 v[58:61], v43 offset:2800
	s_waitcnt lgkmcnt(1)
	v_mul_f32_e32 v62, v51, v71
	v_fmac_f32_e32 v62, v50, v70
	v_fmac_f32_e32 v62, v52, v72
	v_fmac_f32_e32 v62, v53, v73
	s_waitcnt lgkmcnt(0)
	v_mul_f32_e32 v59, v55, v59
	v_fmac_f32_e32 v59, v54, v58
	v_fmac_f32_e32 v59, v56, v60
	v_add_f32_e32 v57, v57, v62
	v_fmac_f32_e32 v59, 0, v61
	v_add_f32_e32 v57, v57, v59
	v_mov_b32_e32 v62, v167
	ds_read_b128 v[58:61], v43 offset:2880
	v_cmp_eq_u32_e32 vcc, 20, v62
	ds_read_b128 v[62:65], v43 offset:2896
	ds_read_b128 v[66:69], v43 offset:2912
	ds_read_b128 v[70:73], v43 offset:2928
	v_cndmask_b32_e64 v74, 0, 1.0, vcc
	s_waitcnt lgkmcnt(3)
	v_mul_f32_e32 v59, v38, v59
	v_fmac_f32_e32 v59, v37, v58
	v_fmac_f32_e32 v59, v39, v60
	v_fmac_f32_e32 v59, v40, v61
	v_add_f32_e32 v58, v74, v59
	s_waitcnt lgkmcnt(2)
	v_mul_f32_e32 v59, v42, v63
	v_fmac_f32_e32 v59, v41, v62
	v_fmac_f32_e32 v59, v44, v64
	v_fmac_f32_e32 v59, v45, v65
	v_add_f32_e32 v58, v58, v59
	s_waitcnt lgkmcnt(1)
	v_mul_f32_e32 v59, v47, v67
	v_fmac_f32_e32 v59, v46, v66
	v_fmac_f32_e32 v59, v48, v68
	v_fmac_f32_e32 v59, v49, v69
	v_add_f32_e32 v62, v58, v59
	ds_read_b128 v[58:61], v43 offset:2944
	s_waitcnt lgkmcnt(1)
	v_mul_f32_e32 v63, v51, v71
	v_fmac_f32_e32 v63, v50, v70
	v_fmac_f32_e32 v63, v52, v72
	v_fmac_f32_e32 v63, v53, v73
	s_waitcnt lgkmcnt(0)
	v_mul_f32_e32 v59, v55, v59
	v_fmac_f32_e32 v59, v54, v58
	v_fmac_f32_e32 v59, v56, v60
	v_add_f32_e32 v62, v62, v63
	v_fmac_f32_e32 v59, v57, v61
	v_add_f32_e32 v58, v62, v59
	v_mov_b32_e32 v59, v167
	ds_read_b128 v[60:63], v43 offset:3024
	ds_read_b128 v[64:67], v43 offset:3040
	ds_read_b128 v[68:71], v43 offset:3056
	ds_read_b128 v[72:75], v43 offset:3072
	v_cmp_eq_u32_e32 vcc, 21, v59
	s_waitcnt lgkmcnt(3)
	v_mul_f32_e32 v61, v38, v61
	v_fmac_f32_e32 v61, v37, v60
	s_waitcnt lgkmcnt(2)
	v_mul_f32_e32 v60, v42, v65
	v_fmac_f32_e32 v61, v39, v62
	v_fmac_f32_e32 v60, v41, v64
	v_cndmask_b32_e64 v59, 0, 1.0, vcc
	v_fmac_f32_e32 v61, v40, v63
	v_fmac_f32_e32 v60, v44, v66
	v_add_f32_e32 v59, v59, v61
	v_fmac_f32_e32 v60, v45, v67
	v_add_f32_e32 v59, v59, v60
	s_waitcnt lgkmcnt(1)
	v_mul_f32_e32 v60, v47, v69
	v_fmac_f32_e32 v60, v46, v68
	s_waitcnt lgkmcnt(0)
	v_mul_f32_e32 v64, v51, v73
	v_fmac_f32_e32 v60, v48, v70
	v_fmac_f32_e32 v64, v50, v72
	v_fmac_f32_e32 v60, v49, v71
	v_fmac_f32_e32 v64, v52, v74
	v_add_f32_e32 v59, v59, v60
	ds_read_b128 v[60:63], v43 offset:3088
	v_fmac_f32_e32 v64, v53, v75
	v_add_f32_e32 v59, v59, v64
	ds_read_b128 v[64:67], v43 offset:3104
	s_waitcnt lgkmcnt(1)
	v_mul_f32_e32 v61, v55, v61
	v_fmac_f32_e32 v61, v54, v60
	v_fmac_f32_e32 v61, v56, v62
	s_waitcnt lgkmcnt(0)
	v_mul_f32_e32 v60, 0, v65
	v_fmac_f32_e32 v60, v58, v64
	v_fmac_f32_e32 v61, v57, v63
	v_fmac_f32_e32 v60, 0, v66
	v_add_f32_e32 v59, v59, v61
	v_fmac_f32_e32 v60, 0, v67
	v_add_f32_e32 v59, v59, v60
	v_mov_b32_e32 v64, v167
	ds_read_b128 v[60:63], v43 offset:3168
	v_cmp_eq_u32_e32 vcc, 22, v64
	ds_read_b128 v[64:67], v43 offset:3184
	ds_read_b128 v[68:71], v43 offset:3200
	ds_read_b128 v[72:75], v43 offset:3216
	v_cndmask_b32_e64 v76, 0, 1.0, vcc
	s_waitcnt lgkmcnt(3)
	v_mul_f32_e32 v61, v38, v61
	v_fmac_f32_e32 v61, v37, v60
	v_fmac_f32_e32 v61, v39, v62
	v_fmac_f32_e32 v61, v40, v63
	v_add_f32_e32 v60, v76, v61
	s_waitcnt lgkmcnt(2)
	v_mul_f32_e32 v61, v42, v65
	v_fmac_f32_e32 v61, v41, v64
	v_fmac_f32_e32 v61, v44, v66
	v_fmac_f32_e32 v61, v45, v67
	v_add_f32_e32 v60, v60, v61
	s_waitcnt lgkmcnt(1)
	v_mul_f32_e32 v61, v47, v69
	v_fmac_f32_e32 v61, v46, v68
	v_fmac_f32_e32 v61, v48, v70
	v_fmac_f32_e32 v61, v49, v71
	v_add_f32_e32 v64, v60, v61
	s_waitcnt lgkmcnt(0)
	v_mul_f32_e32 v65, v51, v73
	ds_read_b128 v[60:63], v43 offset:3232
	v_fmac_f32_e32 v65, v50, v72
	v_fmac_f32_e32 v65, v52, v74
	v_fmac_f32_e32 v65, v53, v75
	v_add_f32_e32 v68, v64, v65
	ds_read_b128 v[64:67], v43 offset:3248
	s_waitcnt lgkmcnt(1)
	v_mul_f32_e32 v61, v55, v61
	v_fmac_f32_e32 v61, v54, v60
	v_fmac_f32_e32 v61, v56, v62
	v_fmac_f32_e32 v61, v57, v63
	v_add_f32_e32 v60, v68, v61
	s_waitcnt lgkmcnt(0)
	v_mul_f32_e32 v61, v59, v65
	v_fmac_f32_e32 v61, v58, v64
	v_fmac_f32_e32 v61, 0, v66
	v_fmac_f32_e32 v61, 0, v67
	v_add_f32_e32 v60, v60, v61
	v_mov_b32_e32 v61, v167
	ds_read_b128 v[62:65], v43 offset:3312
	ds_read_b128 v[66:69], v43 offset:3328
	ds_read_b128 v[70:73], v43 offset:3344
	ds_read_b128 v[74:77], v43 offset:3360
	v_cmp_eq_u32_e32 vcc, 23, v61
	s_waitcnt lgkmcnt(3)
	v_mul_f32_e32 v63, v38, v63
	v_fmac_f32_e32 v63, v37, v62
	s_waitcnt lgkmcnt(2)
	v_mul_f32_e32 v62, v42, v67
	v_fmac_f32_e32 v63, v39, v64
	v_fmac_f32_e32 v62, v41, v66
	v_cndmask_b32_e64 v61, 0, 1.0, vcc
	v_fmac_f32_e32 v63, v40, v65
	v_fmac_f32_e32 v62, v44, v68
	v_add_f32_e32 v61, v61, v63
	v_fmac_f32_e32 v62, v45, v69
	v_add_f32_e32 v61, v61, v62
	s_waitcnt lgkmcnt(1)
	v_mul_f32_e32 v62, v47, v71
	v_fmac_f32_e32 v62, v46, v70
	s_waitcnt lgkmcnt(0)
	v_mul_f32_e32 v66, v51, v75
	v_fmac_f32_e32 v62, v48, v72
	v_fmac_f32_e32 v66, v50, v74
	v_fmac_f32_e32 v62, v49, v73
	v_fmac_f32_e32 v66, v52, v76
	v_add_f32_e32 v61, v61, v62
	ds_read_b128 v[62:65], v43 offset:3376
	v_fmac_f32_e32 v66, v53, v77
	v_add_f32_e32 v61, v61, v66
	ds_read_b128 v[66:69], v43 offset:3392
	s_waitcnt lgkmcnt(1)
	v_mul_f32_e32 v63, v55, v63
	v_fmac_f32_e32 v63, v54, v62
	v_fmac_f32_e32 v63, v56, v64
	s_waitcnt lgkmcnt(0)
	v_mul_f32_e32 v62, v59, v67
	v_fmac_f32_e32 v62, v58, v66
	v_fmac_f32_e32 v63, v57, v65
	v_fmac_f32_e32 v62, v60, v68
	v_add_f32_e32 v61, v61, v63
	v_fmac_f32_e32 v62, 0, v69
	v_add_f32_e32 v61, v61, v62
	v_mov_b32_e32 v66, v167
	ds_read_b128 v[62:65], v43 offset:3456
	v_cmp_eq_u32_e32 vcc, 24, v66
	ds_read_b128 v[66:69], v43 offset:3472
	ds_read_b128 v[70:73], v43 offset:3488
	ds_read_b128 v[74:77], v43 offset:3504
	v_cndmask_b32_e64 v78, 0, 1.0, vcc
	s_waitcnt lgkmcnt(3)
	v_mul_f32_e32 v63, v38, v63
	v_fmac_f32_e32 v63, v37, v62
	v_fmac_f32_e32 v63, v39, v64
	v_fmac_f32_e32 v63, v40, v65
	v_add_f32_e32 v62, v78, v63
	s_waitcnt lgkmcnt(2)
	v_mul_f32_e32 v63, v42, v67
	v_fmac_f32_e32 v63, v41, v66
	v_fmac_f32_e32 v63, v44, v68
	v_fmac_f32_e32 v63, v45, v69
	v_add_f32_e32 v62, v62, v63
	s_waitcnt lgkmcnt(1)
	v_mul_f32_e32 v63, v47, v71
	v_fmac_f32_e32 v63, v46, v70
	v_fmac_f32_e32 v63, v48, v72
	v_fmac_f32_e32 v63, v49, v73
	v_add_f32_e32 v66, v62, v63
	s_waitcnt lgkmcnt(0)
	v_mul_f32_e32 v67, v51, v75
	ds_read_b128 v[62:65], v43 offset:3520
	v_fmac_f32_e32 v67, v50, v74
	v_fmac_f32_e32 v67, v52, v76
	v_fmac_f32_e32 v67, v53, v77
	v_add_f32_e32 v70, v66, v67
	ds_read_b128 v[66:69], v43 offset:3536
	s_waitcnt lgkmcnt(1)
	v_mul_f32_e32 v63, v55, v63
	v_fmac_f32_e32 v63, v54, v62
	v_fmac_f32_e32 v63, v56, v64
	v_fmac_f32_e32 v63, v57, v65
	v_add_f32_e32 v62, v70, v63
	s_waitcnt lgkmcnt(0)
	v_mul_f32_e32 v63, v59, v67
	v_fmac_f32_e32 v63, v58, v66
	v_fmac_f32_e32 v63, v60, v68
	v_fmac_f32_e32 v63, v61, v69
	v_add_f32_e32 v62, v62, v63
	v_mov_b32_e32 v63, v167
	ds_read_b128 v[64:67], v43 offset:3600
	ds_read_b128 v[68:71], v43 offset:3616
	ds_read_b128 v[72:75], v43 offset:3632
	ds_read_b128 v[76:79], v43 offset:3648
	v_cmp_eq_u32_e32 vcc, 25, v63
	s_waitcnt lgkmcnt(3)
	v_mul_f32_e32 v65, v38, v65
	v_fmac_f32_e32 v65, v37, v64
	s_waitcnt lgkmcnt(2)
	v_mul_f32_e32 v64, v42, v69
	v_fmac_f32_e32 v65, v39, v66
	v_fmac_f32_e32 v64, v41, v68
	v_cndmask_b32_e64 v63, 0, 1.0, vcc
	v_fmac_f32_e32 v65, v40, v67
	v_fmac_f32_e32 v64, v44, v70
	v_add_f32_e32 v63, v63, v65
	v_fmac_f32_e32 v64, v45, v71
	v_add_f32_e32 v63, v63, v64
	s_waitcnt lgkmcnt(1)
	v_mul_f32_e32 v64, v47, v73
	v_fmac_f32_e32 v64, v46, v72
	v_fmac_f32_e32 v64, v48, v74
	v_fmac_f32_e32 v64, v49, v75
	v_add_f32_e32 v63, v63, v64
	ds_read_b128 v[64:67], v43 offset:3664
	s_waitcnt lgkmcnt(1)
	v_mul_f32_e32 v68, v51, v77
	v_fmac_f32_e32 v68, v50, v76
	v_fmac_f32_e32 v68, v52, v78
	v_fmac_f32_e32 v68, v53, v79
	v_add_f32_e32 v63, v63, v68
	ds_read_b128 v[68:71], v43 offset:3680
	s_waitcnt lgkmcnt(1)
	v_mul_f32_e32 v65, v55, v65
	v_fmac_f32_e32 v65, v54, v64
	v_fmac_f32_e32 v65, v56, v66
	v_fmac_f32_e32 v65, v57, v67
	v_add_f32_e32 v63, v63, v65
	ds_read_b128 v[64:67], v43 offset:3696
	s_waitcnt lgkmcnt(1)
	v_mul_f32_e32 v69, v59, v69
	v_fmac_f32_e32 v69, v58, v68
	v_fmac_f32_e32 v69, v60, v70
	v_fmac_f32_e32 v69, v61, v71
	s_waitcnt lgkmcnt(0)
	v_mul_f32_e32 v65, 0, v65
	v_fmac_f32_e32 v65, v62, v64
	v_fmac_f32_e32 v65, 0, v66
	v_add_f32_e32 v63, v63, v69
	v_fmac_f32_e32 v65, 0, v67
	v_add_f32_e32 v63, v63, v65
	v_mov_b32_e32 v68, v167
	ds_read_b128 v[64:67], v43 offset:3744
	v_cmp_eq_u32_e32 vcc, 26, v68
	ds_read_b128 v[68:71], v43 offset:3760
	ds_read_b128 v[72:75], v43 offset:3776
	ds_read_b128 v[76:79], v43 offset:3792
	v_cndmask_b32_e64 v80, 0, 1.0, vcc
	s_waitcnt lgkmcnt(3)
	v_mul_f32_e32 v65, v38, v65
	v_fmac_f32_e32 v65, v37, v64
	v_fmac_f32_e32 v65, v39, v66
	v_fmac_f32_e32 v65, v40, v67
	v_add_f32_e32 v64, v80, v65
	s_waitcnt lgkmcnt(2)
	v_mul_f32_e32 v65, v42, v69
	v_fmac_f32_e32 v65, v41, v68
	v_fmac_f32_e32 v65, v44, v70
	v_fmac_f32_e32 v65, v45, v71
	v_add_f32_e32 v64, v64, v65
	s_waitcnt lgkmcnt(1)
	v_mul_f32_e32 v65, v47, v73
	v_fmac_f32_e32 v65, v46, v72
	v_fmac_f32_e32 v65, v48, v74
	v_fmac_f32_e32 v65, v49, v75
	v_add_f32_e32 v68, v64, v65
	ds_read_b128 v[64:67], v43 offset:3808
	s_waitcnt lgkmcnt(1)
	v_mul_f32_e32 v69, v51, v77
	v_fmac_f32_e32 v69, v50, v76
	v_fmac_f32_e32 v69, v52, v78
	v_fmac_f32_e32 v69, v53, v79
	v_add_f32_e32 v72, v68, v69
	ds_read_b128 v[68:71], v43 offset:3824
	s_waitcnt lgkmcnt(1)
	v_mul_f32_e32 v65, v55, v65
	v_fmac_f32_e32 v65, v54, v64
	v_fmac_f32_e32 v65, v56, v66
	v_fmac_f32_e32 v65, v57, v67
	v_add_f32_e32 v72, v72, v65
	ds_read_b128 v[64:67], v43 offset:3840
	s_waitcnt lgkmcnt(1)
	v_mul_f32_e32 v69, v59, v69
	v_fmac_f32_e32 v69, v58, v68
	v_fmac_f32_e32 v69, v60, v70
	v_fmac_f32_e32 v69, v61, v71
	s_waitcnt lgkmcnt(0)
	v_mul_f32_e32 v65, v63, v65
	v_fmac_f32_e32 v65, v62, v64
	v_fmac_f32_e32 v65, 0, v66
	v_add_f32_e32 v68, v72, v69
	v_fmac_f32_e32 v65, 0, v67
	v_add_f32_e32 v64, v68, v65
	v_mov_b32_e32 v65, v167
	ds_read_b128 v[66:69], v43 offset:3888
	ds_read_b128 v[70:73], v43 offset:3904
	ds_read_b128 v[74:77], v43 offset:3920
	ds_read_b128 v[78:81], v43 offset:3936
	v_cmp_eq_u32_e32 vcc, 27, v65
	s_waitcnt lgkmcnt(3)
	v_mul_f32_e32 v67, v38, v67
	v_fmac_f32_e32 v67, v37, v66
	s_waitcnt lgkmcnt(2)
	v_mul_f32_e32 v66, v42, v71
	v_fmac_f32_e32 v67, v39, v68
	v_fmac_f32_e32 v66, v41, v70
	v_cndmask_b32_e64 v65, 0, 1.0, vcc
	v_fmac_f32_e32 v67, v40, v69
	v_fmac_f32_e32 v66, v44, v72
	v_add_f32_e32 v65, v65, v67
	v_fmac_f32_e32 v66, v45, v73
	v_add_f32_e32 v65, v65, v66
	s_waitcnt lgkmcnt(1)
	v_mul_f32_e32 v66, v47, v75
	v_fmac_f32_e32 v66, v46, v74
	v_fmac_f32_e32 v66, v48, v76
	v_fmac_f32_e32 v66, v49, v77
	v_add_f32_e32 v65, v65, v66
	ds_read_b128 v[66:69], v43 offset:3952
	s_waitcnt lgkmcnt(1)
	v_mul_f32_e32 v70, v51, v79
	v_fmac_f32_e32 v70, v50, v78
	v_fmac_f32_e32 v70, v52, v80
	v_fmac_f32_e32 v70, v53, v81
	v_add_f32_e32 v65, v65, v70
	ds_read_b128 v[70:73], v43 offset:3968
	s_waitcnt lgkmcnt(1)
	v_mul_f32_e32 v67, v55, v67
	v_fmac_f32_e32 v67, v54, v66
	v_fmac_f32_e32 v67, v56, v68
	v_fmac_f32_e32 v67, v57, v69
	v_add_f32_e32 v65, v65, v67
	ds_read_b128 v[66:69], v43 offset:3984
	s_waitcnt lgkmcnt(1)
	v_mul_f32_e32 v71, v59, v71
	v_fmac_f32_e32 v71, v58, v70
	v_fmac_f32_e32 v71, v60, v72
	v_fmac_f32_e32 v71, v61, v73
	s_waitcnt lgkmcnt(0)
	v_mul_f32_e32 v67, v63, v67
	v_fmac_f32_e32 v67, v62, v66
	v_fmac_f32_e32 v67, v64, v68
	v_add_f32_e32 v65, v65, v71
	v_fmac_f32_e32 v67, 0, v69
	v_add_f32_e32 v65, v65, v67
	v_mov_b32_e32 v70, v167
	ds_read_b128 v[66:69], v43 offset:4032
	v_cmp_eq_u32_e32 vcc, 28, v70
	ds_read_b128 v[70:73], v43 offset:4048
	ds_read_b128 v[74:77], v43 offset:4064
	ds_read_b128 v[78:81], v43 offset:4080
	v_cndmask_b32_e64 v82, 0, 1.0, vcc
	s_waitcnt lgkmcnt(3)
	v_mul_f32_e32 v67, v38, v67
	v_fmac_f32_e32 v67, v37, v66
	v_fmac_f32_e32 v67, v39, v68
	v_fmac_f32_e32 v67, v40, v69
	v_add_f32_e32 v66, v82, v67
	s_waitcnt lgkmcnt(2)
	v_mul_f32_e32 v67, v42, v71
	v_fmac_f32_e32 v67, v41, v70
	v_fmac_f32_e32 v67, v44, v72
	v_fmac_f32_e32 v67, v45, v73
	v_add_f32_e32 v66, v66, v67
	s_waitcnt lgkmcnt(1)
	v_mul_f32_e32 v67, v47, v75
	v_fmac_f32_e32 v67, v46, v74
	v_fmac_f32_e32 v67, v48, v76
	v_fmac_f32_e32 v67, v49, v77
	v_add_f32_e32 v70, v66, v67
	ds_read_b128 v[66:69], v43 offset:4096
	s_waitcnt lgkmcnt(1)
	v_mul_f32_e32 v71, v51, v79
	v_fmac_f32_e32 v71, v50, v78
	v_fmac_f32_e32 v71, v52, v80
	v_fmac_f32_e32 v71, v53, v81
	v_add_f32_e32 v74, v70, v71
	ds_read_b128 v[70:73], v43 offset:4112
	s_waitcnt lgkmcnt(1)
	v_mul_f32_e32 v67, v55, v67
	v_fmac_f32_e32 v67, v54, v66
	v_fmac_f32_e32 v67, v56, v68
	v_fmac_f32_e32 v67, v57, v69
	v_add_f32_e32 v74, v74, v67
	ds_read_b128 v[66:69], v43 offset:4128
	s_waitcnt lgkmcnt(1)
	v_mul_f32_e32 v71, v59, v71
	v_fmac_f32_e32 v71, v58, v70
	v_fmac_f32_e32 v71, v60, v72
	v_fmac_f32_e32 v71, v61, v73
	s_waitcnt lgkmcnt(0)
	v_mul_f32_e32 v67, v63, v67
	v_fmac_f32_e32 v67, v62, v66
	v_fmac_f32_e32 v67, v64, v68
	v_add_f32_e32 v70, v74, v71
	v_fmac_f32_e32 v67, v65, v69
	v_add_f32_e32 v98, v70, v67
	v_mov_b32_e32 v70, v167
	ds_read_b128 v[66:69], v43 offset:4176
	v_cmp_eq_u32_e32 vcc, 29, v70
	ds_read_b128 v[70:73], v43 offset:4192
	ds_read_b128 v[74:77], v43 offset:4208
	ds_read_b128 v[78:81], v43 offset:4224
	v_cndmask_b32_e64 v82, 0, 1.0, vcc
	s_waitcnt lgkmcnt(3)
	v_mul_f32_e32 v67, v38, v67
	v_fmac_f32_e32 v67, v37, v66
	v_fmac_f32_e32 v67, v39, v68
	v_fmac_f32_e32 v67, v40, v69
	v_add_f32_e32 v66, v82, v67
	s_waitcnt lgkmcnt(2)
	v_mul_f32_e32 v67, v42, v71
	v_fmac_f32_e32 v67, v41, v70
	v_fmac_f32_e32 v67, v44, v72
	v_fmac_f32_e32 v67, v45, v73
	v_add_f32_e32 v66, v66, v67
	s_waitcnt lgkmcnt(1)
	v_mul_f32_e32 v67, v47, v75
	v_fmac_f32_e32 v67, v46, v74
	v_fmac_f32_e32 v67, v48, v76
	v_fmac_f32_e32 v67, v49, v77
	v_add_f32_e32 v70, v66, v67
	s_waitcnt lgkmcnt(0)
	v_mul_f32_e32 v71, v51, v79
	ds_read_b128 v[66:69], v43 offset:4240
	v_fmac_f32_e32 v71, v50, v78
	v_fmac_f32_e32 v71, v52, v80
	v_fmac_f32_e32 v71, v53, v81
	v_add_f32_e32 v74, v70, v71
	ds_read_b128 v[70:73], v43 offset:4256
	s_waitcnt lgkmcnt(1)
	v_mul_f32_e32 v67, v55, v67
	v_fmac_f32_e32 v67, v54, v66
	v_fmac_f32_e32 v67, v56, v68
	v_fmac_f32_e32 v67, v57, v69
	v_add_f32_e32 v74, v74, v67
	s_waitcnt lgkmcnt(0)
	v_mul_f32_e32 v71, v59, v71
	ds_read_b128 v[66:69], v43 offset:4272
	v_fmac_f32_e32 v71, v58, v70
	v_fmac_f32_e32 v71, v60, v72
	v_fmac_f32_e32 v71, v61, v73
	v_add_f32_e32 v74, v74, v71
	ds_read_b128 v[70:73], v43 offset:4288
	s_waitcnt lgkmcnt(1)
	v_mul_f32_e32 v67, v63, v67
	v_fmac_f32_e32 v67, v62, v66
	v_fmac_f32_e32 v67, v64, v68
	v_fmac_f32_e32 v67, v65, v69
	v_add_f32_e32 v66, v74, v67
	s_waitcnt lgkmcnt(0)
	v_mul_f32_e32 v67, 0, v71
	v_fmac_f32_e32 v67, v98, v70
	v_fmac_f32_e32 v67, 0, v72
	v_fmac_f32_e32 v67, 0, v73
	v_add_f32_e32 v99, v66, v67
	v_mov_b32_e32 v70, v167
	ds_read_b128 v[66:69], v43 offset:4320
	v_cmp_eq_u32_e32 vcc, 30, v70
	ds_read_b128 v[70:73], v43 offset:4336
	ds_read_b128 v[74:77], v43 offset:4352
	ds_read_b128 v[78:81], v43 offset:4368
	v_cndmask_b32_e64 v82, 0, 1.0, vcc
	s_waitcnt lgkmcnt(3)
	v_mul_f32_e32 v67, v38, v67
	v_fmac_f32_e32 v67, v37, v66
	v_fmac_f32_e32 v67, v39, v68
	v_fmac_f32_e32 v67, v40, v69
	v_add_f32_e32 v66, v82, v67
	s_waitcnt lgkmcnt(2)
	v_mul_f32_e32 v67, v42, v71
	v_fmac_f32_e32 v67, v41, v70
	v_fmac_f32_e32 v67, v44, v72
	v_fmac_f32_e32 v67, v45, v73
	v_add_f32_e32 v66, v66, v67
	s_waitcnt lgkmcnt(1)
	v_mul_f32_e32 v67, v47, v75
	v_fmac_f32_e32 v67, v46, v74
	v_fmac_f32_e32 v67, v48, v76
	v_fmac_f32_e32 v67, v49, v77
	v_add_f32_e32 v70, v66, v67
	s_waitcnt lgkmcnt(0)
	v_mul_f32_e32 v71, v51, v79
	ds_read_b128 v[66:69], v43 offset:4384
	v_fmac_f32_e32 v71, v50, v78
	v_fmac_f32_e32 v71, v52, v80
	v_fmac_f32_e32 v71, v53, v81
	v_add_f32_e32 v74, v70, v71
	ds_read_b128 v[70:73], v43 offset:4400
	s_waitcnt lgkmcnt(1)
	v_mul_f32_e32 v67, v55, v67
	v_fmac_f32_e32 v67, v54, v66
	v_fmac_f32_e32 v67, v56, v68
	v_fmac_f32_e32 v67, v57, v69
	v_add_f32_e32 v74, v74, v67
	s_waitcnt lgkmcnt(0)
	v_mul_f32_e32 v71, v59, v71
	ds_read_b128 v[66:69], v43 offset:4416
	v_fmac_f32_e32 v71, v58, v70
	v_fmac_f32_e32 v71, v60, v72
	v_fmac_f32_e32 v71, v61, v73
	v_add_f32_e32 v74, v74, v71
	ds_read_b128 v[70:73], v43 offset:4432
	s_waitcnt lgkmcnt(1)
	v_mul_f32_e32 v67, v63, v67
	v_fmac_f32_e32 v67, v62, v66
	v_fmac_f32_e32 v67, v64, v68
	v_fmac_f32_e32 v67, v65, v69
	v_add_f32_e32 v66, v74, v67
	s_waitcnt lgkmcnt(0)
	v_mul_f32_e32 v67, v99, v71
	v_fmac_f32_e32 v67, v98, v70
	v_fmac_f32_e32 v67, 0, v72
	v_fmac_f32_e32 v67, 0, v73
	v_add_f32_e32 v119, v66, v67
	ds_read_b128 v[66:69], v43 offset:4464
	ds_read_b128 v[70:73], v43 offset:4480
	ds_read_b128 v[74:77], v43 offset:4496
	ds_read_b128 v[78:81], v43 offset:4512
	ds_read_b128 v[82:85], v43 offset:4528
	ds_read_b128 v[86:89], v43 offset:4544
	ds_read_b128 v[90:93], v43 offset:4560
	ds_read_b128 v[94:97], v43 offset:4576
	s_waitcnt lgkmcnt(7)
	v_mul_f32_e32 v67, v38, v67
	v_fmac_f32_e32 v67, v37, v66
	s_waitcnt lgkmcnt(6)
	v_mul_f32_e32 v66, v42, v71
	v_cmp_eq_u32_e32 vcc, 31, v121
	v_fmac_f32_e32 v67, v39, v68
	v_fmac_f32_e32 v66, v41, v70
	v_cndmask_b32_e64 v43, 0, 1.0, vcc
	v_fmac_f32_e32 v67, v40, v69
	v_fmac_f32_e32 v66, v44, v72
	v_add_f32_e32 v43, v43, v67
	v_fmac_f32_e32 v66, v45, v73
	v_add_f32_e32 v43, v43, v66
	s_waitcnt lgkmcnt(5)
	v_mul_f32_e32 v66, v47, v75
	v_fmac_f32_e32 v66, v46, v74
	v_fmac_f32_e32 v66, v48, v76
	v_fmac_f32_e32 v66, v49, v77
	v_add_f32_e32 v43, v43, v66
	s_waitcnt lgkmcnt(4)
	v_mul_f32_e32 v66, v51, v79
	v_fmac_f32_e32 v66, v50, v78
	v_fmac_f32_e32 v66, v52, v80
	v_fmac_f32_e32 v66, v53, v81
	v_add_f32_e32 v43, v43, v66
	s_waitcnt lgkmcnt(3)
	v_mul_f32_e32 v66, v55, v83
	v_fmac_f32_e32 v66, v54, v82
	v_fmac_f32_e32 v66, v56, v84
	v_fmac_f32_e32 v66, v57, v85
	v_add_f32_e32 v43, v43, v66
	s_waitcnt lgkmcnt(2)
	v_mul_f32_e32 v66, v59, v87
	v_fmac_f32_e32 v66, v58, v86
	v_fmac_f32_e32 v66, v60, v88
	v_fmac_f32_e32 v66, v61, v89
	v_add_f32_e32 v43, v43, v66
	s_waitcnt lgkmcnt(1)
	v_mul_f32_e32 v66, v63, v91
	v_fmac_f32_e32 v66, v62, v90
	v_fmac_f32_e32 v66, v64, v92
	v_fmac_f32_e32 v66, v65, v93
	v_add_f32_e32 v43, v43, v66
	s_waitcnt lgkmcnt(0)
	v_mul_f32_e32 v66, v99, v95
	v_fmac_f32_e32 v66, v98, v94
	v_fmac_f32_e32 v66, v119, v96
	v_fmac_f32_e32 v66, 0, v97
	v_add_f32_e32 v43, v43, v66
	v_cvt_pk_bf16_f32 v37, v37, s0
	ds_write_b16 v168, v37 offset:9728
	v_cvt_pk_bf16_f32 v37, v38, s0
	ds_write_b16 v168, v37 offset:9808
	v_cvt_pk_bf16_f32 v37, v39, s0
	ds_write_b16 v168, v37 offset:9888
	v_cvt_pk_bf16_f32 v37, v40, s0
	ds_write_b16 v168, v37 offset:9968
	v_cvt_pk_bf16_f32 v37, v41, s0
	ds_write_b16 v168, v37 offset:10048
	v_cvt_pk_bf16_f32 v37, v42, s0
	ds_write_b16 v168, v37 offset:10128
	v_cvt_pk_bf16_f32 v37, v44, s0
	ds_write_b16 v168, v37 offset:10208
	v_cvt_pk_bf16_f32 v37, v45, s0
	ds_write_b16 v168, v37 offset:10288
	v_cvt_pk_bf16_f32 v37, v46, s0
	ds_write_b16 v168, v37 offset:10368
	v_cvt_pk_bf16_f32 v37, v47, s0
	ds_write_b16 v168, v37 offset:10448
	v_cvt_pk_bf16_f32 v37, v48, s0
	ds_write_b16 v168, v37 offset:10528
	v_cvt_pk_bf16_f32 v37, v49, s0
	ds_write_b16 v168, v37 offset:10608
	v_cvt_pk_bf16_f32 v37, v50, s0
	ds_write_b16 v168, v37 offset:10688
	v_cvt_pk_bf16_f32 v37, v51, s0
	ds_write_b16 v168, v37 offset:10768
	v_cvt_pk_bf16_f32 v37, v52, s0
	ds_write_b16 v168, v37 offset:10848
	v_cvt_pk_bf16_f32 v37, v53, s0
	ds_write_b16 v168, v37 offset:10928
	v_cvt_pk_bf16_f32 v37, v54, s0
	ds_write_b16 v168, v37 offset:11008
	v_cvt_pk_bf16_f32 v37, v55, s0
	ds_write_b16 v168, v37 offset:11088
	v_cvt_pk_bf16_f32 v37, v56, s0
	ds_write_b16 v168, v37 offset:11168
	v_cvt_pk_bf16_f32 v37, v57, s0
	ds_write_b16 v168, v37 offset:11248
	v_cvt_pk_bf16_f32 v37, v58, s0
	ds_write_b16 v168, v37 offset:11328
	v_cvt_pk_bf16_f32 v37, v59, s0
	ds_write_b16 v168, v37 offset:11408
	v_cvt_pk_bf16_f32 v37, v60, s0
	ds_write_b16 v168, v37 offset:11488
	v_cvt_pk_bf16_f32 v37, v61, s0
	ds_write_b16 v168, v37 offset:11568
	v_cvt_pk_bf16_f32 v37, v62, s0
	ds_write_b16 v168, v37 offset:11648
	v_cvt_pk_bf16_f32 v37, v63, s0
	ds_write_b16 v168, v37 offset:11728
	v_cvt_pk_bf16_f32 v37, v64, s0
	ds_write_b16 v168, v37 offset:11808
	v_cvt_pk_bf16_f32 v37, v65, s0
	ds_write_b16 v168, v37 offset:11888
	v_cvt_pk_bf16_f32 v37, v98, s0
	ds_write_b16 v168, v37 offset:11968
	v_cvt_pk_bf16_f32 v37, v99, s0
	ds_write_b16 v168, v37 offset:12048
	v_cvt_pk_bf16_f32 v37, v119, s0
	ds_write_b16 v168, v37 offset:12128
	v_cvt_pk_bf16_f32 v37, v43, s0
	ds_write_b16 v168, v37 offset:12208
	ds_read_b128 v[38:41], v36 offset:9728
	ds_read_b128 v[42:45], v36 offset:11008
	s_waitcnt lgkmcnt(1)
	v_mfma_f32_16x16x32_bf16 v[46:49], v[8:11], v[38:41], v[0:3]
	v_lshl_add_u64 v[58:59], s[0:1], 0, v[134:135]
	v_mov_b32_e32 v119, v195
	v_mov_b32_e32 v121, v195
	v_mfma_f32_16x16x32_bf16 v[50:53], v[4:7], v[38:41], v[0:3]
	s_waitcnt lgkmcnt(0)
	v_mfma_f32_16x16x32_bf16 v[8:11], v[8:11], v[42:45], v[0:3]
	v_mfma_f32_16x16x32_bf16 v[4:7], v[4:7], v[42:45], v[0:3]
	v_mfma_f32_16x16x32_bf16 v[54:57], v[12:15], v[38:41], v[0:3]
	s_nop 5
	v_cvt_pk_bf16_f32 v8, v8, v9
	v_cvt_pk_bf16_f32 v9, v10, v11
	v_cvt_pk_bf16_f32 v10, v4, v5
	v_mfma_f32_16x16x32_bf16 v[38:41], v[16:19], v[38:41], v[0:3]
	v_cvt_pk_bf16_f32 v11, v6, v7
	ds_read_b128 v[4:7], v36 offset:5888
	v_mfma_f32_16x16x32_bf16 v[12:15], v[12:15], v[42:45], v[0:3]
	v_mfma_f32_16x16x32_bf16 v[16:19], v[16:19], v[42:45], v[0:3]
	v_cvt_pk_bf16_f32 v42, v46, v47
	v_cvt_pk_bf16_f32 v43, v48, v49
	v_cvt_pk_bf16_f32 v44, v50, v51
	v_cvt_pk_bf16_f32 v45, v52, v53
	v_lshl_add_u64 v[46:47], v[58:59], 0, v[118:119]
	global_store_dwordx4 v[46:47], v[42:45], off
	v_lshl_add_u64 v[48:49], v[58:59], 0, v[120:121]
	global_store_dwordx4 v[46:47], v[8:11], off offset:2048
	v_cvt_pk_bf16_f32 v44, v38, v39
	v_cvt_pk_bf16_f32 v45, v40, v41
	ds_read_b128 v[38:41], v36 offset:4608
	v_cvt_pk_bf16_f32 v42, v54, v55
	v_cvt_pk_bf16_f32 v43, v56, v57
	v_add_u32_e32 v11, 0x2000, v169
	global_store_dwordx4 v[48:49], v[42:45], off
	ds_read2_b64 v[42:45], v11 offset0:192 offset1:196
	v_cvt_pk_bf16_f32 v10, v16, v17
	v_cvt_pk_bf16_f32 v11, v18, v19
	ds_read2_b64 v[16:19], v170 offset0:192 offset1:196
	v_cvt_pk_bf16_f32 v8, v12, v13
	v_cvt_pk_bf16_f32 v9, v14, v15
	s_waitcnt lgkmcnt(2)
	v_mfma_f32_16x16x32_bf16 v[12:15], v[38:41], v[32:35], v[0:3]
	global_store_dwordx4 v[48:49], v[8:11], off offset:2048
	v_mfma_f32_16x16x32_bf16 v[32:35], v[4:7], v[32:35], v[0:3]
	s_nop 5
	v_cvt_pk_bf16_f32 v12, v12, v13
	v_cvt_pk_bf16_f32 v13, v14, v15
	v_cvt_pk_bf16_f32 v14, v32, v33
	v_cvt_pk_bf16_f32 v15, v34, v35
	s_waitcnt lgkmcnt(1)
	s_nop 0
	v_mfma_f32_16x16x32_bf16 v[32:35], v[42:45], v[12:15], v[0:3]
	s_waitcnt lgkmcnt(0)
	v_mfma_f32_16x16x32_bf16 v[8:11], v[16:19], v[12:15], v[0:3]
	v_mfma_f32_16x16x32_bf16 v[12:15], v[38:41], v[28:31], v[0:3]
	s_nop 4
	v_cvt_pk_bf16_f32 v32, v32, v33
	v_cvt_pk_bf16_f32 v33, v34, v35
	v_lshl_add_u64 v[34:35], s[2:3], 0, v[102:103]
	global_store_dwordx2 v[34:35], v[32:33], off
	v_cvt_pk_bf16_f32 v32, v8, v9
	v_cvt_pk_bf16_f32 v33, v10, v11
	v_mfma_f32_16x16x32_bf16 v[8:11], v[4:7], v[28:31], v[0:3]
	v_cvt_pk_bf16_f32 v12, v12, v13
	v_cvt_pk_bf16_f32 v13, v14, v15
	v_lshl_add_u64 v[28:29], s[2:3], 0, v[106:107]
	global_store_dwordx2 v[28:29], v[32:33], off
	v_lshl_add_u64 v[30:31], s[2:3], 0, v[114:115]
	s_nop 2
	v_cvt_pk_bf16_f32 v14, v8, v9
	v_cvt_pk_bf16_f32 v15, v10, v11
	s_nop 1
	v_mfma_f32_16x16x32_bf16 v[8:11], v[42:45], v[12:15], v[0:3]
	v_mfma_f32_16x16x32_bf16 v[12:15], v[16:19], v[12:15], v[0:3]
	s_nop 6
	v_cvt_pk_bf16_f32 v8, v8, v9
	v_cvt_pk_bf16_f32 v9, v10, v11
	v_lshl_add_u64 v[10:11], s[2:3], 0, v[110:111]
	global_store_dwordx2 v[10:11], v[8:9], off
	v_mfma_f32_16x16x32_bf16 v[8:11], v[38:41], v[24:27], v[0:3]
	v_cvt_pk_bf16_f32 v28, v12, v13
	v_cvt_pk_bf16_f32 v29, v14, v15
	global_store_dwordx2 v[30:31], v[28:29], off
	v_mfma_f32_16x16x32_bf16 v[12:15], v[4:7], v[24:27], v[0:3]
	v_mfma_f32_16x16x32_bf16 v[4:7], v[4:7], v[20:23], v[0:3]
	s_nop 2
	v_cvt_pk_bf16_f32 v8, v8, v9
	v_cvt_pk_bf16_f32 v9, v10, v11
	s_nop 1
	v_cvt_pk_bf16_f32 v10, v12, v13
	v_cvt_pk_bf16_f32 v11, v14, v15
	s_nop 1
	v_mfma_f32_16x16x32_bf16 v[12:15], v[42:45], v[8:11], v[0:3]
	v_mfma_f32_16x16x32_bf16 v[8:11], v[16:19], v[8:11], v[0:3]
	s_nop 6
	v_cvt_pk_bf16_f32 v12, v12, v13
	v_cvt_pk_bf16_f32 v13, v14, v15
	v_lshl_add_u64 v[14:15], s[2:3], 0, v[104:105]
	global_store_dwordx2 v[14:15], v[12:13], off
	v_mfma_f32_16x16x32_bf16 v[12:15], v[38:41], v[20:23], v[0:3]
	v_cvt_pk_bf16_f32 v8, v8, v9
	v_cvt_pk_bf16_f32 v9, v10, v11
	v_lshl_add_u64 v[10:11], s[2:3], 0, v[108:109]
	global_store_dwordx2 v[10:11], v[8:9], off
	v_cvt_pk_bf16_f32 v10, v4, v5
	s_nop 2
	v_cvt_pk_bf16_f32 v8, v12, v13
	v_cvt_pk_bf16_f32 v9, v14, v15
	v_cvt_pk_bf16_f32 v11, v6, v7
	s_nop 1
	v_mfma_f32_16x16x32_bf16 v[4:7], v[42:45], v[8:11], v[0:3]
	v_mfma_f32_16x16x32_bf16 v[0:3], v[16:19], v[8:11], v[0:3]
	s_nop 6
	v_cvt_pk_bf16_f32 v4, v4, v5
	v_cvt_pk_bf16_f32 v0, v0, v1
	v_cvt_pk_bf16_f32 v1, v2, v3
	v_lshl_add_u64 v[2:3], s[2:3], 0, v[116:117]
	global_store_dwordx2 v[2:3], v[0:1], off
	v_lshl_add_u64 v[0:1], s[0:1], 0, v[194:195]
	v_add_co_u32_e32 v0, vcc, 0x7000, v0
	v_cvt_pk_bf16_f32 v5, v6, v7
	v_lshl_add_u64 v[6:7], s[2:3], 0, v[112:113]
	v_cvt_pk_bf16_f32 v2, v171, s0
	v_addc_co_u32_e32 v1, vcc, 0, v1, vcc
	global_store_dwordx2 v[6:7], v[4:5], off
	global_store_short v[0:1], v2, off offset:2048
	s_waitcnt lgkmcnt(0)
	s_cbranch_scc1 .LBB0_351
	v_readlane_b32 s38, v255, 9
	v_readlane_b32 s90, v255, 24
	v_readlane_b32 s76, v255, 4
	v_readlane_b32 s73, v255, 5
	v_readlane_b32 s77, v255, 6
	v_readlane_b32 s39, v255, 10
	v_readlane_b32 s72, v253, 20
	s_mov_b64 s[70:71], 0x80
	s_mov_b64 s[68:69], 0xc00
	v_readlane_b32 s91, v255, 25
	s_mov_b32 s56, s96

.LBB0_360:
	s_or_b64 exec, exec, s[10:11]
	global_load_ushort v2, v[6:7], off
	s_movk_i32 s12, 0xe00
	v_add_u32_e32 v10, s72, v10
	s_waitcnt vmcnt(0) lgkmcnt(0)
	v_lshlrev_b32_e32 v6, 16, v2
	v_mov_b64_e32 v[2:3], s[94:95]
	v_mad_u64_u32 v[2:3], s[10:11], v4, s12, v[2:3]
	v_mov_b32_e32 v4, v3
	v_mad_u64_u32 v[4:5], s[10:11], v5, s12, v[4:5]
	v_mov_b32_e32 v3, v4
	s_mov_b32 s10, 0x1dbff
	v_lshl_add_u64 v[2:3], v[2:3], 0, v[8:9]
	v_cmp_lt_i32_e32 vcc, s10, v10
	v_lshl_add_u64 v[0:1], v[0:1], 2, v[2:3]
	s_or_b64 s[8:9], vcc, s[8:9]
	global_store_dword v[0:1], v6, off
	s_andn2_b64 exec, exec, s[8:9]
	s_cbranch_execz .LBB0_365

.LBB0_430:
	v_mov_b32_e32 v0, v192
	v_mov_b32_e32 v4, v192
	v_mov_b32_e32 v8, v192
	v_mov_b32_e32 v12, v192
	v_mov_b32_e32 v16, v192
	v_mov_b32_e32 v20, v192
	v_mov_b32_e32 v24, v192
	v_mov_b32_e32 v28, v195
	s_waitcnt lgkmcnt(0)
	s_barrier
	global_load_dwordx4 v[32:35], v[70:71], off
	global_load_dwordx4 v[36:39], v[72:73], off
	ds_read_b128 v[40:43], v118
	v_mov_b32_e32 v1, v0
	v_mov_b32_e32 v2, v0
	v_mov_b32_e32 v3, v0
	v_mov_b32_e32 v5, v4
	v_mov_b32_e32 v6, v4
	v_mov_b32_e32 v7, v4
	v_mov_b32_e32 v9, v8
	v_mov_b32_e32 v10, v8
	v_mov_b32_e32 v11, v8
	v_mov_b32_e32 v13, v12
	v_mov_b32_e32 v14, v12
	v_mov_b32_e32 v15, v12
	v_mov_b32_e32 v17, v16
	v_mov_b32_e32 v18, v16
	v_mov_b32_e32 v19, v16
	v_mov_b32_e32 v21, v20
	v_mov_b32_e32 v22, v20
	v_mov_b32_e32 v23, v20
	v_mov_b32_e32 v25, v24
	v_mov_b32_e32 v26, v24
	v_mov_b32_e32 v27, v24
	v_mov_b32_e32 v29, v28
	v_mov_b32_e32 v30, v28
	v_mov_b32_e32 v31, v28
	s_add_i32 s39, s39, s81
	s_cmpk_gt_i32 s39, 0xff
	s_waitcnt vmcnt(0) lgkmcnt(0)
	v_mfma_f32_16x16x32_bf16 v[0:3], v[32:35], v[40:43], v[0:3]
	v_mfma_f32_16x16x32_bf16 v[4:7], v[36:39], v[40:43], v[4:7]
	ds_read_b128 v[40:43], v118 offset:8448
	s_waitcnt lgkmcnt(0)
	v_mfma_f32_16x16x32_bf16 v[8:11], v[32:35], v[40:43], v[8:11]
	v_mfma_f32_16x16x32_bf16 v[12:15], v[36:39], v[40:43], v[12:15]
	ds_read_b128 v[40:43], v118 offset:16896
	s_waitcnt lgkmcnt(0)
	v_mfma_f32_16x16x32_bf16 v[16:19], v[32:35], v[40:43], v[16:19]
	v_mfma_f32_16x16x32_bf16 v[20:23], v[36:39], v[40:43], v[20:23]
	ds_read_b128 v[40:43], v118 offset:25344
	s_waitcnt lgkmcnt(0)
	v_mfma_f32_16x16x32_bf16 v[24:27], v[32:35], v[40:43], v[24:27]
	v_mfma_f32_16x16x32_bf16 v[28:31], v[36:39], v[40:43], v[28:31]
	global_load_dwordx4 v[32:35], v[70:71], off offset:64
	global_load_dwordx4 v[36:39], v[72:73], off offset:64
	ds_read_b128 v[40:43], v118 offset:64
	s_waitcnt vmcnt(0) lgkmcnt(0)
	v_mfma_f32_16x16x32_bf16 v[0:3], v[32:35], v[40:43], v[0:3]
	v_mfma_f32_16x16x32_bf16 v[4:7], v[36:39], v[40:43], v[4:7]
	ds_read_b128 v[40:43], v118 offset:8512
	s_waitcnt lgkmcnt(0)
	v_mfma_f32_16x16x32_bf16 v[8:11], v[32:35], v[40:43], v[8:11]
	v_mfma_f32_16x16x32_bf16 v[12:15], v[36:39], v[40:43], v[12:15]
	ds_read_b128 v[40:43], v118 offset:16960
	s_waitcnt lgkmcnt(0)
	v_mfma_f32_16x16x32_bf16 v[16:19], v[32:35], v[40:43], v[16:19]
	v_mfma_f32_16x16x32_bf16 v[20:23], v[36:39], v[40:43], v[20:23]
	ds_read_b128 v[40:43], v118 offset:25408
	s_waitcnt lgkmcnt(0)
	v_mfma_f32_16x16x32_bf16 v[24:27], v[32:35], v[40:43], v[24:27]
	v_mfma_f32_16x16x32_bf16 v[28:31], v[36:39], v[40:43], v[28:31]
	global_load_dwordx4 v[32:35], v[70:71], off offset:128
	global_load_dwordx4 v[36:39], v[72:73], off offset:128
	ds_read_b128 v[40:43], v118 offset:128
	s_waitcnt vmcnt(0) lgkmcnt(0)
	v_mfma_f32_16x16x32_bf16 v[0:3], v[32:35], v[40:43], v[0:3]
	v_mfma_f32_16x16x32_bf16 v[4:7], v[36:39], v[40:43], v[4:7]
	ds_read_b128 v[40:43], v118 offset:8576
	s_waitcnt lgkmcnt(0)
	v_mfma_f32_16x16x32_bf16 v[8:11], v[32:35], v[40:43], v[8:11]
	v_mfma_f32_16x16x32_bf16 v[12:15], v[36:39], v[40:43], v[12:15]
	ds_read_b128 v[40:43], v118 offset:17024
	s_waitcnt lgkmcnt(0)
	v_mfma_f32_16x16x32_bf16 v[16:19], v[32:35], v[40:43], v[16:19]
	v_mfma_f32_16x16x32_bf16 v[20:23], v[36:39], v[40:43], v[20:23]
	ds_read_b128 v[40:43], v118 offset:25472
	s_waitcnt lgkmcnt(0)
	v_mfma_f32_16x16x32_bf16 v[24:27], v[32:35], v[40:43], v[24:27]
	v_mfma_f32_16x16x32_bf16 v[28:31], v[36:39], v[40:43], v[28:31]
	global_load_dwordx4 v[32:35], v[70:71], off offset:192
	global_load_dwordx4 v[36:39], v[72:73], off offset:192
	ds_read_b128 v[40:43], v118 offset:192
	s_waitcnt vmcnt(0) lgkmcnt(0)
	v_mfma_f32_16x16x32_bf16 v[0:3], v[32:35], v[40:43], v[0:3]
	v_mfma_f32_16x16x32_bf16 v[4:7], v[36:39], v[40:43], v[4:7]
	ds_read_b128 v[40:43], v118 offset:8640
	s_waitcnt lgkmcnt(0)
	v_mfma_f32_16x16x32_bf16 v[8:11], v[32:35], v[40:43], v[8:11]
	v_mfma_f32_16x16x32_bf16 v[12:15], v[36:39], v[40:43], v[12:15]
	ds_read_b128 v[40:43], v118 offset:17088
	s_waitcnt lgkmcnt(0)
	v_mfma_f32_16x16x32_bf16 v[16:19], v[32:35], v[40:43], v[16:19]
	v_mfma_f32_16x16x32_bf16 v[20:23], v[36:39], v[40:43], v[20:23]
	ds_read_b128 v[40:43], v118 offset:25536
	s_waitcnt lgkmcnt(0)
	v_mfma_f32_16x16x32_bf16 v[24:27], v[32:35], v[40:43], v[24:27]
	v_mfma_f32_16x16x32_bf16 v[28:31], v[36:39], v[40:43], v[28:31]
	global_load_dwordx4 v[32:35], v[70:71], off offset:256
	global_load_dwordx4 v[36:39], v[72:73], off offset:256
	ds_read_b128 v[40:43], v118 offset:256
	s_waitcnt vmcnt(0) lgkmcnt(0)
	v_mfma_f32_16x16x32_bf16 v[0:3], v[32:35], v[40:43], v[0:3]
	v_mfma_f32_16x16x32_bf16 v[4:7], v[36:39], v[40:43], v[4:7]
	ds_read_b128 v[40:43], v118 offset:8704
	s_waitcnt lgkmcnt(0)
	v_mfma_f32_16x16x32_bf16 v[8:11], v[32:35], v[40:43], v[8:11]
	v_mfma_f32_16x16x32_bf16 v[12:15], v[36:39], v[40:43], v[12:15]
	ds_read_b128 v[40:43], v118 offset:17152
	s_waitcnt lgkmcnt(0)
	v_mfma_f32_16x16x32_bf16 v[16:19], v[32:35], v[40:43], v[16:19]
	v_mfma_f32_16x16x32_bf16 v[20:23], v[36:39], v[40:43], v[20:23]
	ds_read_b128 v[40:43], v118 offset:25600
	s_waitcnt lgkmcnt(0)
	v_mfma_f32_16x16x32_bf16 v[24:27], v[32:35], v[40:43], v[24:27]
	v_mfma_f32_16x16x32_bf16 v[28:31], v[36:39], v[40:43], v[28:31]
	global_load_dwordx4 v[32:35], v[70:71], off offset:320
	global_load_dwordx4 v[36:39], v[72:73], off offset:320
	ds_read_b128 v[40:43], v118 offset:320
	s_waitcnt vmcnt(0) lgkmcnt(0)
	v_mfma_f32_16x16x32_bf16 v[0:3], v[32:35], v[40:43], v[0:3]
	v_mfma_f32_16x16x32_bf16 v[4:7], v[36:39], v[40:43], v[4:7]
	ds_read_b128 v[40:43], v118 offset:8768
	s_waitcnt lgkmcnt(0)
	v_mfma_f32_16x16x32_bf16 v[8:11], v[32:35], v[40:43], v[8:11]
	v_mfma_f32_16x16x32_bf16 v[12:15], v[36:39], v[40:43], v[12:15]
	ds_read_b128 v[40:43], v118 offset:17216
	s_waitcnt lgkmcnt(0)
	v_mfma_f32_16x16x32_bf16 v[44:47], v[32:35], v[40:43], v[16:19]
	s_nop 2
	ds_read_b128 v[16:19], v118 offset:25664
	global_load_dwordx4 v[48:51], v[70:71], off offset:384
	global_load_dwordx4 v[52:55], v[72:73], off offset:384
	v_mfma_f32_16x16x32_bf16 v[40:43], v[36:39], v[40:43], v[20:23]
	s_waitcnt lgkmcnt(0)
	v_mfma_f32_16x16x32_bf16 v[32:35], v[32:35], v[16:19], v[24:27]
	v_mfma_f32_16x16x32_bf16 v[36:39], v[36:39], v[16:19], v[28:31]
	ds_read_b128 v[16:19], v118 offset:384
	s_waitcnt vmcnt(0) lgkmcnt(0)
	v_mfma_f32_16x16x32_bf16 v[24:27], v[48:51], v[16:19], v[0:3]
	s_nop 2
	ds_read_b128 v[0:3], v118 offset:8832
	v_mfma_f32_16x16x32_bf16 v[28:31], v[52:55], v[16:19], v[4:7]
	s_nop 2
	ds_read_b128 v[4:7], v118 offset:17280
	s_waitcnt lgkmcnt(1)
	v_mfma_f32_16x16x32_bf16 v[16:19], v[48:51], v[0:3], v[8:11]
	v_mfma_f32_16x16x32_bf16 v[20:23], v[52:55], v[0:3], v[12:15]
	s_waitcnt lgkmcnt(0)
	v_mfma_f32_16x16x32_bf16 v[0:3], v[48:51], v[4:7], v[44:47]
	s_nop 0
	ds_read_b128 v[12:15], v118 offset:25728
	v_mfma_f32_16x16x32_bf16 v[4:7], v[52:55], v[4:7], v[40:43]
	s_nop 2
	global_load_dwordx4 v[40:43], v[70:71], off offset:448
	global_load_dwordx4 v[44:47], v[72:73], off offset:448
	s_waitcnt lgkmcnt(0)
	v_mfma_f32_16x16x32_bf16 v[8:11], v[48:51], v[12:15], v[32:35]
	s_nop 2
	ds_read_b128 v[32:35], v118 offset:448
	v_mfma_f32_16x16x32_bf16 v[12:15], v[52:55], v[12:15], v[36:39]
	s_waitcnt vmcnt(0) lgkmcnt(0)
	v_mfma_f32_16x16x32_bf16 v[36:39], v[40:43], v[32:35], v[24:27]
	s_nop 2
	ds_read_b128 v[24:27], v118 offset:8896
	v_mfma_f32_16x16x32_bf16 v[32:35], v[44:47], v[32:35], v[28:31]
	s_waitcnt lgkmcnt(0)
	v_mfma_f32_16x16x32_bf16 v[28:31], v[40:43], v[24:27], v[16:19]
	s_nop 2
	ds_read_b128 v[16:19], v118 offset:17344
	v_mfma_f32_16x16x32_bf16 v[24:27], v[44:47], v[24:27], v[20:23]
	s_waitcnt lgkmcnt(0)
	v_mfma_f32_16x16x32_bf16 v[20:23], v[40:43], v[16:19], v[0:3]
	s_nop 2
	ds_read_b128 v[0:3], v118 offset:25792
	v_mfma_f32_16x16x32_bf16 v[16:19], v[44:47], v[16:19], v[4:7]
	s_waitcnt lgkmcnt(0)
	v_mfma_f32_16x16x32_bf16 v[8:11], v[40:43], v[0:3], v[8:11]
	v_mfma_f32_16x16x32_bf16 v[0:3], v[44:47], v[0:3], v[12:15]
	s_nop 2
	global_load_dwordx4 v[12:15], v[74:75], off
	global_load_dwordx4 v[4:7], v[74:75], off offset:64
	ds_read_b64 v[40:41], v59
	s_waitcnt lgkmcnt(0)
	v_lshlrev_b32_e32 v42, 16, v40
	v_and_b32_e32 v43, 0xffff0000, v40
	s_waitcnt vmcnt(1)
	v_add_f32_e32 v36, v36, v12
	v_add_f32_e32 v37, v37, v13
	v_mul_f32_e32 v36, 0xbfb8aa3b, v36
	v_mul_f32_e32 v37, 0xbfb8aa3b, v37
	v_exp_f32_e32 v36, v36
	v_exp_f32_e32 v37, v37
	v_add_f32_e32 v38, v38, v14
	v_add_f32_e32 v39, v39, v15
	v_mul_f32_e32 v38, 0xbfb8aa3b, v38
	v_pk_add_f32 v[36:37], v[36:37], 1.0 op_sel_hi:[1,0]
	v_mul_f32_e32 v39, 0xbfb8aa3b, v39
	v_exp_f32_e32 v38, v38
	v_exp_f32_e32 v39, v39
	s_waitcnt vmcnt(0)
	v_add_f32_e32 v32, v32, v4
	v_rcp_f32_e32 v37, v37
	v_pk_add_f32 v[38:39], v[38:39], 1.0 op_sel_hi:[1,0]
	v_add_f32_e32 v33, v33, v5
	v_mul_f32_e32 v32, 0xbfb8aa3b, v32
	v_rcp_f32_e32 v36, v36
	s_nop 0
	v_pk_mul_f32 v[36:37], v[36:37], v[42:43]
	v_lshlrev_b32_e32 v40, 16, v41
	v_and_b32_e32 v41, 0xffff0000, v41
	v_mul_f32_e32 v33, 0xbfb8aa3b, v33
	v_rcp_f32_e32 v39, v39
	v_exp_f32_e32 v32, v32
	v_exp_f32_e32 v33, v33
	v_add_f32_e32 v34, v34, v6
	v_rcp_f32_e32 v38, v38
	s_nop 0
	v_pk_mul_f32 v[38:39], v[38:39], v[40:41]
	v_cvt_pk_bf16_f32 v40, v36, v37
	v_mov_b64_e32 v[36:37], s[26:27]
	v_cvt_pk_bf16_f32 v41, v38, v39
	v_mad_i64_i32 v[38:39], s[0:1], v119, s86, v[36:37]
	v_lshl_add_u64 v[38:39], v[38:39], 0, s[74:75]
	v_lshl_add_u64 v[42:43], v[38:39], 0, v[84:85]
	global_store_dwordx2 v[42:43], v[40:41], off
	ds_read_b64 v[40:41], v59 offset:32
	v_pk_add_f32 v[32:33], v[32:33], 1.0 op_sel_hi:[1,0]
	v_add_f32_e32 v35, v35, v7
	v_mul_f32_e32 v34, 0xbfb8aa3b, v34
	v_mul_f32_e32 v35, 0xbfb8aa3b, v35
	s_waitcnt lgkmcnt(0)
	v_lshlrev_b32_e32 v42, 16, v40
	v_and_b32_e32 v43, 0xffff0000, v40
	v_exp_f32_e32 v34, v34
	v_exp_f32_e32 v35, v35
	v_add_f32_e32 v28, v28, v12
	v_rcp_f32_e32 v33, v33
	v_pk_add_f32 v[34:35], v[34:35], 1.0 op_sel_hi:[1,0]
	v_add_f32_e32 v29, v29, v13
	v_mul_f32_e32 v28, 0xbfb8aa3b, v28
	v_rcp_f32_e32 v32, v32
	s_nop 0
	v_pk_mul_f32 v[32:33], v[32:33], v[42:43]
	v_lshlrev_b32_e32 v40, 16, v41
	v_and_b32_e32 v41, 0xffff0000, v41
	v_cvt_pk_bf16_f32 v32, v32, v33
	v_rcp_f32_e32 v35, v35
	v_mul_f32_e32 v29, 0xbfb8aa3b, v29
	v_exp_f32_e32 v28, v28
	v_exp_f32_e32 v29, v29
	v_rcp_f32_e32 v34, v34
	s_nop 0
	v_pk_mul_f32 v[34:35], v[34:35], v[40:41]
	v_pk_add_f32 v[28:29], v[28:29], 1.0 op_sel_hi:[1,0]
	v_cvt_pk_bf16_f32 v33, v34, v35
	v_lshl_add_u64 v[34:35], v[38:39], 0, v[86:87]
	global_store_dwordx2 v[34:35], v[32:33], off
	ds_read_b64 v[32:33], v112
	v_add_f32_e32 v30, v30, v14
	v_add_f32_e32 v31, v31, v15
	v_mul_f32_e32 v30, 0xbfb8aa3b, v30
	v_mul_f32_e32 v31, 0xbfb8aa3b, v31
	s_waitcnt lgkmcnt(0)
	v_lshlrev_b32_e32 v34, 16, v32
	v_and_b32_e32 v35, 0xffff0000, v32
	v_exp_f32_e32 v30, v30
	v_exp_f32_e32 v31, v31
	v_or_b32_e32 v38, s40, v61
	v_rcp_f32_e32 v29, v29
	v_pk_add_f32 v[30:31], v[30:31], 1.0 op_sel_hi:[1,0]
	v_add_f32_e32 v24, v24, v4
	v_add_f32_e32 v25, v25, v5
	v_rcp_f32_e32 v28, v28
	s_nop 0
	v_pk_mul_f32 v[28:29], v[28:29], v[34:35]
	v_lshlrev_b32_e32 v32, 16, v33
	v_and_b32_e32 v33, 0xffff0000, v33
	v_cvt_pk_bf16_f32 v28, v28, v29
	v_rcp_f32_e32 v31, v31
	v_mul_f32_e32 v24, 0xbfb8aa3b, v24
	v_mul_f32_e32 v25, 0xbfb8aa3b, v25
	v_exp_f32_e32 v24, v24
	v_rcp_f32_e32 v30, v30
	s_nop 0
	v_pk_mul_f32 v[30:31], v[30:31], v[32:33]
	v_exp_f32_e32 v25, v25
	v_cvt_pk_bf16_f32 v29, v30, v31
	v_mad_i64_i32 v[30:31], s[0:1], v38, s86, v[36:37]
	v_lshl_add_u64 v[30:31], v[30:31], 0, s[74:75]
	v_lshl_add_u64 v[32:33], v[30:31], 0, v[84:85]
	global_store_dwordx2 v[32:33], v[28:29], off
	ds_read_b64 v[28:29], v112 offset:32
	v_pk_add_f32 v[24:25], v[24:25], 1.0 op_sel_hi:[1,0]
	v_add_f32_e32 v26, v26, v6
	v_add_f32_e32 v27, v27, v7
	v_mul_f32_e32 v26, 0xbfb8aa3b, v26
	s_waitcnt lgkmcnt(0)
	v_lshlrev_b32_e32 v32, 16, v28
	v_and_b32_e32 v33, 0xffff0000, v28
	v_mul_f32_e32 v27, 0xbfb8aa3b, v27
	v_exp_f32_e32 v26, v26
	v_exp_f32_e32 v27, v27
	v_rcp_f32_e32 v25, v25
	v_pk_add_f32 v[26:27], v[26:27], 1.0 op_sel_hi:[1,0]
	v_add_f32_e32 v20, v20, v12
	v_add_f32_e32 v21, v21, v13
	v_rcp_f32_e32 v24, v24
	s_nop 0
	v_pk_mul_f32 v[24:25], v[24:25], v[32:33]
	v_lshlrev_b32_e32 v28, 16, v29
	v_and_b32_e32 v29, 0xffff0000, v29
	v_cvt_pk_bf16_f32 v24, v24, v25
	v_rcp_f32_e32 v27, v27
	v_mul_f32_e32 v20, 0xbfb8aa3b, v20
	v_mul_f32_e32 v21, 0xbfb8aa3b, v21
	v_exp_f32_e32 v20, v20
	v_rcp_f32_e32 v26, v26
	s_nop 0
	v_pk_mul_f32 v[26:27], v[26:27], v[28:29]
	v_exp_f32_e32 v21, v21
	v_cvt_pk_bf16_f32 v25, v26, v27
	v_lshl_add_u64 v[26:27], v[30:31], 0, v[86:87]
	global_store_dwordx2 v[26:27], v[24:25], off
	ds_read_b64 v[24:25], v113
	v_pk_add_f32 v[20:21], v[20:21], 1.0 op_sel_hi:[1,0]
	v_add_f32_e32 v22, v22, v14
	v_add_f32_e32 v23, v23, v15
	v_mul_f32_e32 v22, 0xbfb8aa3b, v22
	s_waitcnt lgkmcnt(0)
	v_lshlrev_b32_e32 v26, 16, v24
	v_and_b32_e32 v27, 0xffff0000, v24
	v_mul_f32_e32 v23, 0xbfb8aa3b, v23
	v_exp_f32_e32 v22, v22
	v_exp_f32_e32 v23, v23
	v_rcp_f32_e32 v21, v21
	v_pk_add_f32 v[22:23], v[22:23], 1.0 op_sel_hi:[1,0]
	v_or_b32_e32 v28, s40, v81
	v_add_f32_e32 v16, v16, v4
	v_rcp_f32_e32 v20, v20
	s_nop 0
	v_pk_mul_f32 v[20:21], v[20:21], v[26:27]
	v_lshlrev_b32_e32 v24, 16, v25
	v_and_b32_e32 v25, 0xffff0000, v25
	v_cvt_pk_bf16_f32 v20, v20, v21
	v_rcp_f32_e32 v23, v23
	v_add_f32_e32 v17, v17, v5
	v_mul_f32_e32 v16, 0xbfb8aa3b, v16
	v_mul_f32_e32 v17, 0xbfb8aa3b, v17
	v_rcp_f32_e32 v22, v22
	s_nop 0
	v_pk_mul_f32 v[22:23], v[22:23], v[24:25]
	v_exp_f32_e32 v16, v16
	v_cvt_pk_bf16_f32 v21, v22, v23
	v_mad_i64_i32 v[22:23], s[0:1], v28, s86, v[36:37]
	v_lshl_add_u64 v[22:23], v[22:23], 0, s[74:75]
	v_lshl_add_u64 v[24:25], v[22:23], 0, v[84:85]
	global_store_dwordx2 v[24:25], v[20:21], off
	ds_read_b64 v[20:21], v113 offset:32
	v_exp_f32_e32 v17, v17
	v_add_f32_e32 v18, v18, v6
	v_add_f32_e32 v19, v19, v7
	v_mul_f32_e32 v18, 0xbfb8aa3b, v18
	v_pk_add_f32 v[16:17], v[16:17], 1.0 op_sel_hi:[1,0]
	s_waitcnt lgkmcnt(0)
	v_lshlrev_b32_e32 v24, 16, v20
	v_and_b32_e32 v25, 0xffff0000, v20
	v_mul_f32_e32 v19, 0xbfb8aa3b, v19
	v_exp_f32_e32 v18, v18
	v_exp_f32_e32 v19, v19
	v_rcp_f32_e32 v17, v17
	v_pk_add_f32 v[18:19], v[18:19], 1.0 op_sel_hi:[1,0]
	v_add_f32_e32 v8, v8, v12
	v_add_f32_e32 v9, v9, v13
	v_rcp_f32_e32 v16, v16
	s_nop 0
	v_pk_mul_f32 v[16:17], v[16:17], v[24:25]
	v_lshlrev_b32_e32 v20, 16, v21
	v_and_b32_e32 v21, 0xffff0000, v21
	v_cvt_pk_bf16_f32 v16, v16, v17
	v_rcp_f32_e32 v19, v19
	v_mul_f32_e32 v8, 0xbfb8aa3b, v8
	v_mul_f32_e32 v9, 0xbfb8aa3b, v9
	v_exp_f32_e32 v8, v8
	v_rcp_f32_e32 v18, v18
	s_nop 0
	v_pk_mul_f32 v[18:19], v[18:19], v[20:21]
	v_exp_f32_e32 v9, v9
	v_cvt_pk_bf16_f32 v17, v18, v19
	v_lshl_add_u64 v[18:19], v[22:23], 0, v[86:87]
	global_store_dwordx2 v[18:19], v[16:17], off
	ds_read_b64 v[16:17], v114
	v_pk_add_f32 v[8:9], v[8:9], 1.0 op_sel_hi:[1,0]
	v_add_f32_e32 v10, v10, v14
	v_add_f32_e32 v11, v11, v15
	v_mul_f32_e32 v10, 0xbfb8aa3b, v10
	s_waitcnt lgkmcnt(0)
	v_lshlrev_b32_e32 v12, 16, v16
	v_and_b32_e32 v13, 0xffff0000, v16
	v_mul_f32_e32 v11, 0xbfb8aa3b, v11
	v_exp_f32_e32 v10, v10
	v_exp_f32_e32 v11, v11
	v_rcp_f32_e32 v9, v9
	v_pk_add_f32 v[10:11], v[10:11], 1.0 op_sel_hi:[1,0]
	v_or_b32_e32 v18, s40, v110
	v_rcp_f32_e32 v8, v8
	s_nop 0
	v_pk_mul_f32 v[8:9], v[8:9], v[12:13]
	v_lshlrev_b32_e32 v12, 16, v17
	v_and_b32_e32 v13, 0xffff0000, v17
	v_rcp_f32_e32 v11, v11
	v_cvt_pk_bf16_f32 v8, v8, v9
	v_add_f32_e32 v0, v0, v4
	v_add_f32_e32 v1, v1, v5
	v_rcp_f32_e32 v10, v10
	s_nop 0
	v_pk_mul_f32 v[10:11], v[10:11], v[12:13]
	v_mul_f32_e32 v0, 0xbfb8aa3b, v0
	v_cvt_pk_bf16_f32 v9, v10, v11
	v_mad_i64_i32 v[10:11], s[0:1], v18, s86, v[36:37]
	v_lshl_add_u64 v[10:11], v[10:11], 0, s[74:75]
	v_lshl_add_u64 v[12:13], v[10:11], 0, v[84:85]
	global_store_dwordx2 v[12:13], v[8:9], off
	v_mul_f32_e32 v1, 0xbfb8aa3b, v1
	ds_read_b64 v[8:9], v114 offset:32
	v_exp_f32_e32 v0, v0
	v_exp_f32_e32 v1, v1
	v_add_f32_e32 v2, v2, v6
	v_add_f32_e32 v3, v3, v7
	s_waitcnt lgkmcnt(0)
	v_lshlrev_b32_e32 v4, 16, v8
	v_pk_add_f32 v[0:1], v[0:1], 1.0 op_sel_hi:[1,0]
	v_and_b32_e32 v5, 0xffff0000, v8
	v_mul_f32_e32 v2, 0xbfb8aa3b, v2
	v_mul_f32_e32 v3, 0xbfb8aa3b, v3
	v_exp_f32_e32 v2, v2
	v_rcp_f32_e32 v1, v1
	v_exp_f32_e32 v3, v3
	s_nop 0
	v_pk_add_f32 v[2:3], v[2:3], 1.0 op_sel_hi:[1,0]
	v_rcp_f32_e32 v0, v0
	s_nop 0
	v_pk_mul_f32 v[0:1], v[0:1], v[4:5]
	v_lshlrev_b32_e32 v4, 16, v9
	v_and_b32_e32 v5, 0xffff0000, v9
	v_rcp_f32_e32 v3, v3
	v_cvt_pk_bf16_f32 v0, v0, v1
	v_rcp_f32_e32 v2, v2
	s_nop 0
	v_pk_mul_f32 v[2:3], v[2:3], v[4:5]
	s_nop 0
	v_cvt_pk_bf16_f32 v1, v2, v3
	v_lshl_add_u64 v[2:3], v[10:11], 0, v[86:87]
	global_store_dwordx2 v[2:3], v[0:1], off
	s_waitcnt lgkmcnt(0)
	s_barrier
	s_cbranch_scc1 .LBB0_443

.LBB0_433:
	s_or_b32 s28, s2, s36
	s_add_i32 s34, s28, s37
	v_lshl_or_b32 v4, s34, 7, v77
	v_ashrrev_i32_e32 v5, 31, v4
	s_ashr_i32 s35, s34, 31
	v_lshl_add_u64 v[4:5], v[4:5], 2, s[22:23]
	s_lshl_b64 s[0:1], s[34:35], 12
	v_lshl_add_u64 v[6:7], v[62:63], 0, s[0:1]
	global_load_dwordx2 v[90:91], v[4:5], off
	global_load_dwordx4 v[8:11], v[6:7], off
	global_load_dwordx4 v[12:15], v[6:7], off offset:512
	global_load_dwordx4 v[16:19], v[6:7], off offset:1024
	global_load_dwordx4 v[20:23], v[6:7], off offset:1536
	global_load_dwordx4 v[24:27], v[6:7], off offset:2048
	global_load_dwordx4 v[28:31], v[6:7], off offset:2560
	global_load_dwordx4 v[32:35], v[6:7], off offset:3072
	global_load_dwordx4 v[36:39], v[6:7], off offset:3584
	s_lshl_b64 s[0:1], s[34:35], 6
	v_lshl_add_u64 v[4:5], v[64:65], 0, s[0:1]
	global_load_dwordx4 v[4:7], v[4:5], off
	s_andn2_b64 vcc, exec, s[6:7]
	s_cbranch_vccnz .LBB0_436
	s_waitcnt vmcnt(0) lgkmcnt(0)
	v_mul_f32_e32 v40, v91, v91
	v_add_f32_e32 v42, v90, v90
	v_pk_fma_f32 v[40:41], v[90:91], v[90:91], v[40:41] op_sel_hi:[1,1,0] neg_lo:[0,0,1] neg_hi:[0,0,1]
	v_mul_f32_e32 v43, v91, v42
	v_mul_f32_e32 v42, v43, v43
	v_mov_b32_e32 v196, v40
	v_pk_mul_f32 v[44:45], v[40:41], v[196:197] op_sel_hi:[0,1]
	v_pk_fma_f32 v[40:41], v[40:41], v[196:197], v[42:43] op_sel_hi:[0,1,1] neg_lo:[0,0,1] neg_hi:[0,0,1]
	v_pk_mul_f32 v[46:47], v[44:45], v[42:43]
	v_pk_mov_b32 v[42:43], v[42:43], v[40:41] op_sel:[1,0]
	v_mov_b32_e32 v196, v45
	v_pk_mul_f32 v[42:43], v[42:43], v[196:197]
	v_mov_b32_e32 v48, v40
	v_mov_b32_e32 v49, v47
	v_mov_b32_e32 v41, v43
	v_pk_mul_f32 v[40:41], v[48:49], v[40:41]
	v_pk_mul_f32 v[44:45], v[46:47], v[42:43]
	v_pk_fma_f32 v[42:43], v[46:47], v[42:43], v[40:41] op_sel:[1,0,0] neg_lo:[1,0,0] neg_hi:[1,0,0]
	v_pk_mul_f32 v[44:45], v[40:41], v[44:45]
	v_mov_b32_e32 v196, v42
	v_pk_mul_f32 v[46:47], v[42:43], v[196:197] op_sel_hi:[0,1]
	v_mov_b32_e32 v40, v45
	v_pk_fma_f32 v[42:43], v[42:43], v[196:197], v[40:41] op_sel_hi:[0,1,1] neg_lo:[0,0,1] neg_hi:[0,0,1]
	v_pk_mul_f32 v[40:41], v[46:47], v[40:41]
	v_mov_b32_e32 v92, 0
	v_mov_b32_e32 v43, v41
	v_mul_f32_e32 v40, v42, v42
	v_pk_fma_f32 v[44:45], v[42:43], v[42:43], v[40:41] op_sel_hi:[1,1,0] neg_lo:[1,0,0] neg_hi:[1,0,0]
	v_add_f32_e32 v40, v42, v42
	v_mov_b32_e32 v42, v41
	v_mov_b32_e32 v43, v45
	v_mov_b32_e32 v41, v45
	v_pk_mul_f32 v[42:43], v[42:43], v[40:41]
	s_add_i32 s4, s72, s2
	v_pk_mov_b32 v[40:41], v[44:45], v[42:43] op_sel:[1,0]
	v_mov_b32_e32 v44, v197
	v_mov_b32_e32 v45, v42
	v_pk_mul_f32 v[46:47], v[40:41], v[44:45]
	v_pk_fma_f32 v[40:41], v[40:41], v[44:45], v[42:43] neg_lo:[1,0,0] neg_hi:[1,0,0]
	v_pk_mul_f32 v[42:43], v[42:43], v[46:47]
	v_mov_b32_e32 v45, v41
	v_mov_b32_e32 v44, v42
	v_mov_b32_e32 v46, v41
	v_mov_b32_e32 v47, v41
	v_mov_b32_e32 v48, v42
	v_mov_b32_e32 v49, v42
	v_pk_mov_b32 v[50:51], v[40:41], v[42:43] op_sel:[1,0]
	s_mov_b32 s2, 0
	v_mov_b32_e32 v93, v92
.LBB0_435:
	s_add_i32 s3, s2, 1
	s_cmp_lt_u32 s3, s41
	s_cselect_b64 vcc, -1, 0
	s_and_b64 s[0:1], vcc, exec
	s_cselect_b32 s0, s3, s2
	s_add_i32 s0, s0, s42
	s_lshl_b32 s0, s0, 4
	s_add_i32 s0, s0, s28
	s_ashr_i32 s1, s0, 31
	s_lshl_b64 s[0:1], s[0:1], 9
	s_add_i32 s3, s2, 2
	s_cmp_lt_u32 s3, s41
	v_lshl_add_u64 v[52:53], v[66:67], 0, s[0:1]
	s_cselect_b64 s[0:1], -1, 0
	s_and_b64 s[10:11], s[0:1], exec
	s_cselect_b32 s3, s3, s2
	s_add_i32 s3, s3, s42
	s_lshl_b32 s3, s3, 4
	s_add_i32 s10, s3, s28
	s_ashr_i32 s11, s10, 31
	s_lshl_b64 s[10:11], s[10:11], 9
	s_add_i32 s3, s2, 3
	s_cmp_lt_u32 s3, s41
	v_lshl_add_u64 v[54:55], v[66:67], 0, s[10:11]
	s_cselect_b64 s[10:11], -1, 0
	s_and_b64 s[12:13], s[10:11], exec
	s_cselect_b32 s3, s3, s2
	s_add_i32 s3, s3, s42
	s_lshl_b32 s3, s3, 4
	s_add_i32 s12, s3, s28
	s_ashr_i32 s13, s12, 31
	s_lshl_b64 s[12:13], s[12:13], 9
	s_add_i32 s3, s2, 4
	s_cmp_lt_u32 s3, s41
	v_lshl_add_u64 v[94:95], v[66:67], 0, s[12:13]
	s_cselect_b64 s[12:13], -1, 0
	s_and_b64 s[14:15], s[12:13], exec
	s_cselect_b32 s3, s3, s2
	s_add_i32 s3, s3, s42
	s_lshl_b32 s3, s3, 4
	s_add_i32 s14, s3, s28
	s_ashr_i32 s15, s14, 31
	s_lshl_b64 s[14:15], s[14:15], 9
	s_add_i32 s3, s2, 5
	s_cmp_lt_u32 s3, s41
	v_lshl_add_u64 v[96:97], v[66:67], 0, s[14:15]
	s_cselect_b64 s[14:15], -1, 0
	s_and_b64 s[16:17], s[14:15], exec
	s_cselect_b32 s3, s3, s2
	s_add_i32 s3, s3, s42
	s_lshl_b32 s3, s3, 4
	s_add_i32 s16, s3, s28
	s_ashr_i32 s17, s16, 31
	s_lshl_b64 s[16:17], s[16:17], 9
	s_add_i32 s3, s2, 6
	s_cmp_lt_u32 s3, s41
	v_lshl_add_u64 v[98:99], v[66:67], 0, s[16:17]
	s_cselect_b64 s[16:17], -1, 0
	s_and_b64 s[18:19], s[16:17], exec
	s_cselect_b32 s3, s3, s2
	s_add_i32 s3, s3, s42
	s_lshl_b32 s3, s3, 4
	s_add_i32 s18, s3, s28
	s_ashr_i32 s19, s18, 31
	s_lshl_b64 s[18:19], s[18:19], 9
	s_add_i32 s3, s2, 7
	s_cmp_lt_u32 s3, s41
	v_lshl_add_u64 v[100:101], v[66:67], 0, s[18:19]
	s_cselect_b64 s[18:19], -1, 0
	s_and_b64 s[58:59], s[18:19], exec
	s_cselect_b32 s3, s3, s2
	s_add_i32 s3, s3, s42
	s_lshl_b32 s3, s3, 4
	s_add_i32 s58, s3, s28
	s_ashr_i32 s59, s58, 31
	s_lshl_b64 s[58:59], s[58:59], 9
	s_ashr_i32 s5, s4, 31
	v_lshl_add_u64 v[102:103], v[66:67], 0, s[58:59]
	s_lshl_b64 s[58:59], s[4:5], 9
	v_lshl_add_u64 v[120:121], v[66:67], 0, s[58:59]
	global_load_dwordx2 v[98:99], v[98:99], off
	v_pk_mul_f32 v[122:123], v[48:49], v[92:93]
	global_load_dwordx2 v[100:101], v[100:101], off
	v_pk_fma_f32 v[124:125], v[46:47], v[92:93], v[122:123] op_sel:[0,0,1] op_sel_hi:[1,1,0]
	global_load_dwordx2 v[102:103], v[102:103], off
	v_pk_fma_f32 v[92:93], v[46:47], v[92:93], v[122:123] op_sel:[0,0,1] op_sel_hi:[1,1,0] neg_lo:[0,0,1] neg_hi:[0,0,1]
	global_load_dwordx2 v[120:121], v[120:121], off
	v_mov_b32_e32 v93, v125
	global_load_dwordx2 v[52:53], v[52:53], off
	s_add_i32 s2, s2, 8
	global_load_dwordx2 v[54:55], v[54:55], off
	s_addk_i32 s4, 0x80
	global_load_dwordx2 v[94:95], v[94:95], off
	s_cmp_lt_u32 s2, s41
	global_load_dwordx2 v[96:97], v[96:97], off
	s_waitcnt vmcnt(0) lgkmcnt(0)
	v_pk_add_f32 v[92:93], v[92:93], v[120:121]
	s_nop 0
	v_pk_mul_f32 v[120:121], v[48:49], v[92:93]
	s_nop 0
	v_pk_fma_f32 v[122:123], v[46:47], v[92:93], v[120:121] op_sel:[0,0,1] op_sel_hi:[1,1,0]
	v_pk_fma_f32 v[120:121], v[46:47], v[92:93], v[120:121] op_sel:[0,0,1] op_sel_hi:[1,1,0] neg_lo:[0,0,1] neg_hi:[0,0,1]
	s_nop 0
	v_mov_b32_e32 v121, v123
	v_pk_add_f32 v[52:53], v[52:53], v[120:121]
	s_nop 0
	v_cndmask_b32_e32 v53, v93, v53, vcc
	v_cndmask_b32_e32 v52, v92, v52, vcc
	v_pk_mul_f32 v[92:93], v[48:49], v[52:53]
	s_nop 0
	v_pk_fma_f32 v[120:121], v[46:47], v[52:53], v[92:93] op_sel:[0,0,1] op_sel_hi:[1,1,0]
	v_pk_fma_f32 v[92:93], v[46:47], v[52:53], v[92:93] op_sel:[0,0,1] op_sel_hi:[1,1,0] neg_lo:[0,0,1] neg_hi:[0,0,1]
	s_nop 0
	v_mov_b32_e32 v93, v121
	v_pk_add_f32 v[54:55], v[54:55], v[92:93]
	s_nop 0
	v_cndmask_b32_e64 v53, v53, v55, s[0:1]
	v_cndmask_b32_e64 v52, v52, v54, s[0:1]
	v_pk_mul_f32 v[54:55], v[50:51], v[52:53]
	s_nop 0
	v_sub_f32_e32 v40, v54, v55
	v_pk_mul_f32 v[54:55], v[44:45], v[52:53]
	v_add_f32_e32 v40, v94, v40
	v_add_f32_e32 v43, v55, v54
	v_add_f32_e32 v43, v95, v43
	v_cndmask_b32_e64 v43, v53, v43, s[10:11]
	v_cndmask_b32_e64 v40, v52, v40, s[10:11]
	v_mul_f32_e32 v52, v42, v43
	v_mul_f32_e32 v53, v42, v40
	v_fma_f32 v52, v41, v40, -v52
	v_fmac_f32_e32 v53, v41, v43
	v_add_f32_e32 v52, v96, v52
	v_add_f32_e32 v53, v97, v53
	v_cndmask_b32_e64 v43, v43, v53, s[12:13]
	v_cndmask_b32_e64 v40, v40, v52, s[12:13]
	v_mul_f32_e32 v52, v42, v43
	v_mul_f32_e32 v53, v42, v40
	v_fma_f32 v52, v41, v40, -v52
	v_fmac_f32_e32 v53, v41, v43
	v_add_f32_e32 v52, v98, v52
	v_add_f32_e32 v53, v99, v53
	v_cndmask_b32_e64 v43, v43, v53, s[14:15]
	v_cndmask_b32_e64 v40, v40, v52, s[14:15]
	v_mul_f32_e32 v52, v42, v43
	v_mul_f32_e32 v53, v42, v40
	v_fma_f32 v52, v41, v40, -v52
	v_fmac_f32_e32 v53, v41, v43
	v_add_f32_e32 v52, v100, v52
	v_add_f32_e32 v53, v101, v53
	v_cndmask_b32_e64 v43, v43, v53, s[16:17]
	v_cndmask_b32_e64 v40, v40, v52, s[16:17]
	v_mul_f32_e32 v52, v42, v43
	v_mul_f32_e32 v53, v42, v40
	v_fma_f32 v52, v41, v40, -v52
	v_fmac_f32_e32 v53, v41, v43
	v_add_f32_e32 v52, v102, v52
	v_add_f32_e32 v53, v103, v53
	v_cndmask_b32_e64 v93, v43, v53, s[18:19]
	v_cndmask_b32_e64 v92, v40, v52, s[18:19]
	s_cbranch_scc1 .LBB0_435
	s_branch .LBB0_437

.LBB0_438:
	v_or_b32_e32 v121, s14, v119
	v_mov_b64_e32 v[100:101], s[26:27]
	v_mad_i64_i32 v[102:103], s[2:3], v121, s86, v[100:101]
	v_lshl_add_u64 v[102:103], v[102:103], 0, s[10:11]
	v_lshl_add_u64 v[102:103], v[102:103], 0, s[74:75]
	s_waitcnt lgkmcnt(0)
	v_lshl_add_u64 v[122:123], v[102:103], 0, v[194:195]
	global_load_dwordx4 v[122:125], v[122:123], off
	v_or_b32_e32 v121, 16, v121
	v_mad_i64_i32 v[100:101], s[2:3], v121, s86, v[100:101]
	v_lshl_add_u64 v[100:101], v[100:101], 0, s[10:11]
	v_lshl_add_u64 v[100:101], v[100:101], 0, s[74:75]
	v_lshl_add_u64 v[126:127], v[100:101], 0, v[194:195]
	global_load_dwordx4 v[126:129], v[126:127], off
	v_mov_b32_e32 v83, v195
	v_lshl_add_u64 v[102:103], v[102:103], 0, v[82:83]
	v_lshl_add_u64 v[100:101], v[100:101], 0, v[82:83]
	global_load_dwordx2 v[102:103], v[102:103], off
	v_add_u32_e32 v83, 0x8000, v116
	global_load_dwordx2 v[100:101], v[100:101], off
	s_xor_b64 s[12:13], s[4:5], -1
	s_mov_b32 s2, -8
	s_waitcnt vmcnt(0) lgkmcnt(0)
	v_cndmask_b32_e64 v125, v125, 0, s[8:9]
	v_cndmask_b32_e64 v124, v124, 0, s[8:9]
	v_cndmask_b32_e64 v123, v123, 0, s[8:9]
	v_cndmask_b32_e64 v122, v122, 0, s[8:9]
	s_nop 1
	v_mfma_f32_16x16x32_bf16 v[130:133], v[8:11], v[122:125], v[0:3]
	s_nop 7
	v_cvt_pk_bf16_f32 v134, v130, v131
	v_cvt_pk_bf16_f32 v135, v132, v133
	v_mfma_f32_16x16x32_bf16 v[130:133], v[12:15], v[122:125], v[0:3]
	s_nop 7
	v_cvt_pk_bf16_f32 v130, v130, v131
	v_cvt_pk_bf16_f32 v131, v132, v133
	ds_write2_b64 v83, v[134:135], v[130:131] offset1:4
	v_mfma_f32_16x16x32_bf16 v[130:133], v[16:19], v[122:125], v[0:3]
	s_nop 7
	v_cvt_pk_bf16_f32 v134, v130, v131
	v_cvt_pk_bf16_f32 v135, v132, v133
	v_mfma_f32_16x16x32_bf16 v[130:133], v[20:23], v[122:125], v[0:3]
	s_nop 7
	v_cvt_pk_bf16_f32 v130, v130, v131
	v_cvt_pk_bf16_f32 v131, v132, v133
	ds_write2_b64 v83, v[134:135], v[130:131] offset0:8 offset1:12
	v_mfma_f32_16x16x32_bf16 v[130:133], v[24:27], v[122:125], v[0:3]
	s_nop 7
	v_cvt_pk_bf16_f32 v134, v130, v131
	v_cvt_pk_bf16_f32 v135, v132, v133
	v_mfma_f32_16x16x32_bf16 v[130:133], v[28:31], v[122:125], v[0:3]
	s_nop 7
	v_cvt_pk_bf16_f32 v130, v130, v131
	v_cvt_pk_bf16_f32 v131, v132, v133
	ds_write2_b64 v83, v[134:135], v[130:131] offset0:16 offset1:20
	v_mfma_f32_16x16x32_bf16 v[130:133], v[32:35], v[122:125], v[0:3]
	v_mfma_f32_16x16x32_bf16 v[122:125], v[36:39], v[122:125], v[0:3]
	s_nop 6
	v_cvt_pk_bf16_f32 v130, v130, v131
	v_cvt_pk_bf16_f32 v131, v132, v133
	v_cvt_pk_bf16_f32 v122, v122, v123
	v_cvt_pk_bf16_f32 v123, v124, v125
	ds_write2_b64 v83, v[130:131], v[122:123] offset0:24 offset1:28
	v_cndmask_b32_e64 v125, v129, 0, s[8:9]
	v_cndmask_b32_e64 v124, v128, 0, s[8:9]
	v_cndmask_b32_e64 v123, v127, 0, s[8:9]
	v_cndmask_b32_e64 v122, v126, 0, s[8:9]
	v_add_u32_e32 v83, 0x9000, v116
	s_nop 0
	v_mfma_f32_16x16x32_bf16 v[126:129], v[8:11], v[122:125], v[0:3]
	s_nop 7
	v_cvt_pk_bf16_f32 v130, v126, v127
	v_cvt_pk_bf16_f32 v131, v128, v129
	v_mfma_f32_16x16x32_bf16 v[126:129], v[12:15], v[122:125], v[0:3]
	s_nop 7
	v_cvt_pk_bf16_f32 v126, v126, v127
	v_cvt_pk_bf16_f32 v127, v128, v129
	ds_write2_b64 v83, v[130:131], v[126:127] offset0:32 offset1:36
	v_mfma_f32_16x16x32_bf16 v[126:129], v[16:19], v[122:125], v[0:3]
	s_nop 7
	v_cvt_pk_bf16_f32 v130, v126, v127
	v_cvt_pk_bf16_f32 v131, v128, v129
	v_mfma_f32_16x16x32_bf16 v[126:129], v[20:23], v[122:125], v[0:3]
	s_nop 7
	v_cvt_pk_bf16_f32 v126, v126, v127
	v_cvt_pk_bf16_f32 v127, v128, v129
	ds_write2_b64 v83, v[130:131], v[126:127] offset0:40 offset1:44
	v_mfma_f32_16x16x32_bf16 v[126:129], v[24:27], v[122:125], v[0:3]
	s_nop 7
	v_cvt_pk_bf16_f32 v130, v126, v127
	v_cvt_pk_bf16_f32 v131, v128, v129
	v_mfma_f32_16x16x32_bf16 v[126:129], v[28:31], v[122:125], v[0:3]
	s_nop 7
	v_cvt_pk_bf16_f32 v126, v126, v127
	v_cvt_pk_bf16_f32 v127, v128, v129
	ds_write2_b64 v83, v[130:131], v[126:127] offset0:48 offset1:52
	v_mfma_f32_16x16x32_bf16 v[126:129], v[32:35], v[122:125], v[0:3]
	v_mfma_f32_16x16x32_bf16 v[122:125], v[36:39], v[122:125], v[0:3]
	s_nop 6
	v_cvt_pk_bf16_f32 v126, v126, v127
	v_cvt_pk_bf16_f32 v127, v128, v129
	v_cvt_pk_bf16_f32 v122, v122, v123
	v_cvt_pk_bf16_f32 v123, v124, v125
	ds_write2_b64 v83, v[126:127], v[122:123] offset0:56 offset1:60
	s_waitcnt lgkmcnt(0)
	v_mov_b32_e32 v83, v115

.LBB0_445:
	s_waitcnt vmcnt(0)
	v_add_f32_e32 v4, v28, v4
	v_add_f32_e32 v5, v29, v5
	v_add_u32_e32 v10, v121, v32
	v_mul_f32_e32 v4, 0xbfb8aa3b, v4
	v_mul_f32_e32 v5, 0xbfb8aa3b, v5
	ds_read_b64 v[10:11], v10
	v_exp_f32_e32 v4, v4
	v_exp_f32_e32 v5, v5
	v_add_f32_e32 v6, v30, v6
	v_add_f32_e32 v7, v31, v7
	s_waitcnt lgkmcnt(0)
	v_lshlrev_b32_e32 v12, 16, v10
	v_pk_add_f32 v[4:5], v[4:5], 1.0 op_sel_hi:[1,0]
	v_and_b32_e32 v13, 0xffff0000, v10
	v_mul_f32_e32 v6, 0xbfb8aa3b, v6
	v_mul_f32_e32 v7, 0xbfb8aa3b, v7
	v_exp_f32_e32 v6, v6
	v_rcp_f32_e32 v5, v5
	v_exp_f32_e32 v7, v7
	v_or_b32_e32 v8, s18, v33
	v_mul_i32_i24_e32 v8, 0x1400, v8
	v_rcp_f32_e32 v4, v4
	v_pk_add_f32 v[6:7], v[6:7], 1.0 op_sel_hi:[1,0]
	v_pk_mul_f32 v[4:5], v[4:5], v[12:13]
	v_lshlrev_b32_e32 v10, 16, v11
	v_and_b32_e32 v11, 0xffff0000, v11
	v_mov_b32_e32 v9, v195
	v_rcp_f32_e32 v7, v7
	v_cvt_pk_bf16_f32 v4, v4, v5
	v_add_f32_e32 v0, v20, v0
	v_add_f32_e32 v1, v21, v1
	v_rcp_f32_e32 v6, v6
	s_nop 0
	v_pk_mul_f32 v[6:7], v[6:7], v[10:11]
	v_mul_f32_e32 v0, 0xbfb8aa3b, v0
	v_cvt_pk_bf16_f32 v5, v6, v7
	v_lshl_add_u64 v[6:7], s[26:27], 0, v[8:9]
	v_lshl_add_u64 v[6:7], v[6:7], 0, s[74:75]
	v_lshl_add_u64 v[8:9], v[92:93], 1, v[6:7]
	global_store_dwordx2 v[8:9], v[4:5], off
	v_add_u32_e32 v4, v127, v32
	v_mul_f32_e32 v1, 0xbfb8aa3b, v1
	ds_read_b64 v[4:5], v4
	v_exp_f32_e32 v0, v0
	v_exp_f32_e32 v1, v1
	v_add_f32_e32 v2, v22, v2
	v_add_f32_e32 v3, v23, v3
	s_waitcnt lgkmcnt(0)
	v_lshlrev_b32_e32 v8, 16, v4
	v_pk_add_f32 v[0:1], v[0:1], 1.0 op_sel_hi:[1,0]
	v_and_b32_e32 v9, 0xffff0000, v4
	v_mul_f32_e32 v2, 0xbfb8aa3b, v2
	v_mul_f32_e32 v3, 0xbfb8aa3b, v3
	v_exp_f32_e32 v2, v2
	v_rcp_f32_e32 v1, v1
	v_exp_f32_e32 v3, v3
	s_add_i32 s17, s17, s81
	s_cmp_gt_u32 s17, 3
	v_rcp_f32_e32 v0, v0
	v_pk_add_f32 v[2:3], v[2:3], 1.0 op_sel_hi:[1,0]
	v_pk_mul_f32 v[0:1], v[0:1], v[8:9]
	v_lshlrev_b32_e32 v4, 16, v5
	v_and_b32_e32 v5, 0xffff0000, v5
	v_cvt_pk_bf16_f32 v0, v0, v1
	v_rcp_f32_e32 v3, v3
	s_movk_i32 s11, 0x210
	v_rcp_f32_e32 v2, v2
	s_nop 0
	v_pk_mul_f32 v[2:3], v[2:3], v[4:5]
	s_nop 0
	v_cvt_pk_bf16_f32 v1, v2, v3
	v_lshl_add_u64 v[2:3], v[94:95], 1, v[6:7]
	global_store_dwordx2 v[2:3], v[0:1], off
	s_waitcnt lgkmcnt(0)
	s_barrier
	s_cbranch_scc1 .LBB0_454

.LBB0_447:
	s_or_b32 s12, s4, s6
	s_xor_b64 s[10:11], s[2:3], -1
	s_add_i32 s2, s12, s7
	v_lshl_or_b32 v4, s2, 7, v77
	s_ashr_i32 s3, s2, 31
	v_ashrrev_i32_e32 v5, 31, v4
	s_lshl_b64 s[4:5], s[2:3], 12
	v_lshl_add_u64 v[4:5], v[4:5], 2, s[0:1]
	v_lshl_add_u64 v[8:9], v[82:83], 0, s[4:5]
	global_load_dwordx2 v[102:103], v[4:5], off
	s_lshl_b64 s[2:3], s[2:3], 6
	global_load_dwordx4 v[4:7], v[8:9], off
	v_readlane_b32 s56, v252, 18
	v_readlane_b32 s57, v252, 19
	v_readlane_b32 s58, v252, 20
	v_readlane_b32 s59, v252, 21
	v_readlane_b32 s60, v252, 22
	v_readlane_b32 s61, v252, 23
	v_readlane_b32 s62, v252, 24
	v_readlane_b32 s63, v252, 25
	v_readlane_b32 s64, v252, 26
	v_readlane_b32 s65, v252, 27
	v_readlane_b32 s66, v252, 28
	v_readlane_b32 s67, v252, 29
	v_readlane_b32 s68, v252, 30
	v_readlane_b32 s69, v252, 31
	v_readlane_b32 s70, v252, 32
	v_readlane_b32 s71, v252, 33
	s_mov_b64 s[56:57], s[60:61]
	s_mov_b64 s[58:59], s[62:63]
	v_lshlrev_b32_e32 v100, 1, v80
	v_mov_b32_e32 v101, v195
	v_add_u32_e32 v108, 0x8000, v129
	s_ashr_i32 s13, s12, 31
	s_mov_b64 s[14:15], -1
	s_mov_b64 s[60:61], s[64:65]
	s_mov_b64 s[62:63], s[66:67]
	s_mov_b64 s[64:65], s[68:69]
	s_mov_b64 s[66:67], s[70:71]
	s_waitcnt vmcnt(0) lgkmcnt(0)
	v_cndmask_b32_e64 v55, v7, 0, s[8:9]
	v_cndmask_b32_e64 v54, v6, 0, s[8:9]
	v_cndmask_b32_e64 v53, v5, 0, s[8:9]
	v_cndmask_b32_e64 v52, v4, 0, s[8:9]
	global_load_dwordx4 v[4:7], v[8:9], off offset:512
	s_waitcnt vmcnt(0) lgkmcnt(0)
	v_cndmask_b32_e64 v51, v7, 0, s[8:9]
	v_cndmask_b32_e64 v50, v6, 0, s[8:9]
	v_cndmask_b32_e64 v49, v5, 0, s[8:9]
	v_cndmask_b32_e64 v48, v4, 0, s[8:9]
	global_load_dwordx4 v[4:7], v[8:9], off offset:1024
	s_waitcnt vmcnt(0) lgkmcnt(0)
	v_cndmask_b32_e64 v47, v7, 0, s[8:9]
	v_cndmask_b32_e64 v46, v6, 0, s[8:9]
	v_cndmask_b32_e64 v45, v5, 0, s[8:9]
	v_cndmask_b32_e64 v44, v4, 0, s[8:9]
	global_load_dwordx4 v[4:7], v[8:9], off offset:1536
	s_waitcnt vmcnt(0) lgkmcnt(0)
	v_cndmask_b32_e64 v43, v7, 0, s[8:9]
	v_cndmask_b32_e64 v42, v6, 0, s[8:9]
	v_cndmask_b32_e64 v41, v5, 0, s[8:9]
	v_cndmask_b32_e64 v40, v4, 0, s[8:9]
	global_load_dwordx4 v[4:7], v[8:9], off offset:2048
	s_waitcnt vmcnt(0) lgkmcnt(0)
	v_cndmask_b32_e64 v59, v7, 0, s[8:9]
	v_cndmask_b32_e64 v58, v6, 0, s[8:9]
	v_cndmask_b32_e64 v57, v5, 0, s[8:9]
	v_cndmask_b32_e64 v56, v4, 0, s[8:9]
	global_load_dwordx4 v[4:7], v[8:9], off offset:2560
	s_waitcnt vmcnt(0) lgkmcnt(0)
	v_cndmask_b32_e64 v63, v7, 0, s[8:9]
	v_cndmask_b32_e64 v62, v6, 0, s[8:9]
	v_cndmask_b32_e64 v61, v5, 0, s[8:9]
	v_cndmask_b32_e64 v60, v4, 0, s[8:9]
	global_load_dwordx4 v[4:7], v[8:9], off offset:3072
	s_waitcnt vmcnt(0) lgkmcnt(0)
	v_cndmask_b32_e64 v67, v7, 0, s[8:9]
	v_cndmask_b32_e64 v66, v6, 0, s[8:9]
	v_cndmask_b32_e64 v65, v5, 0, s[8:9]
	v_cndmask_b32_e64 v64, v4, 0, s[8:9]
	global_load_dwordx4 v[4:7], v[8:9], off offset:3584
	v_lshlrev_b32_e32 v8, 2, v80
	v_lshlrev_b32_e32 v9, 8, v78
	v_or3_b32 v8, s4, v9, v8
	v_mov_b32_e32 v9, s5
	v_lshl_add_u64 v[10:11], s[56:57], 0, v[8:9]
	v_lshl_add_u64 v[12:13], s[58:59], 0, v[8:9]
	global_load_dwordx4 v[32:35], v[10:11], off offset:192
	s_lshl_b64 s[4:5], s[12:13], 6
	v_mov_b32_e32 v107, s5
	v_or_b32_e32 v106, s4, v76
	s_waitcnt vmcnt(0) lgkmcnt(0)
	v_cndmask_b32_e64 v69, v5, 0, s[8:9]
	v_cndmask_b32_e64 v68, v4, 0, s[8:9]
	v_lshl_add_u64 v[4:5], v[84:85], 0, s[2:3]
	s_lshl_b32 s2, s12, 4
	s_ashr_i32 s3, s2, 31
	s_lshl_b64 s[2:3], s[2:3], 1
	v_lshl_add_u64 v[72:73], v[96:97], 0, s[2:3]
	v_cndmask_b32_e64 v71, v7, 0, s[8:9]
	v_cndmask_b32_e64 v70, v6, 0, s[8:9]
	global_load_dwordx4 v[4:7], v[4:5], off
	s_nop 0
	global_load_dwordx4 v[36:39], v[12:13], off offset:192
	global_load_dwordx4 v[24:27], v[10:11], off offset:128
	global_load_dwordx4 v[28:31], v[12:13], off offset:128
	global_load_dwordx4 v[16:19], v[10:11], off offset:64
	global_load_dwordx4 v[20:23], v[12:13], off offset:64
	s_nop 0
	global_load_dwordx4 v[8:11], v[10:11], off
	s_nop 0
	global_load_dwordx4 v[12:15], v[12:13], off
	s_waitcnt lgkmcnt(0)
	v_lshl_add_u64 v[74:75], v[72:73], 0, v[194:195]
	global_load_dwordx4 v[138:141], v[74:75], off
	v_lshl_add_u64 v[72:73], v[72:73], 0, v[100:101]
	v_lshl_add_u64 v[142:143], v[98:99], 0, s[2:3]
	global_load_dwordx2 v[104:105], v[72:73], off
	v_lshl_add_u64 v[72:73], v[142:143], 0, v[194:195]
	global_load_dwordx4 v[72:75], v[72:73], off
	v_lshl_add_u64 v[100:101], v[142:143], 0, v[100:101]
	global_load_dwordx2 v[100:101], v[100:101], off
	s_mov_b32 s2, 0
	s_waitcnt vmcnt(0) lgkmcnt(0)
	v_cndmask_b32_e64 v141, v141, 0, s[8:9]
	v_cndmask_b32_e64 v140, v140, 0, s[8:9]
	v_cndmask_b32_e64 v139, v139, 0, s[8:9]
	v_cndmask_b32_e64 v138, v138, 0, s[8:9]
	v_cndmask_b32_e64 v75, v75, 0, s[8:9]
	s_nop 0
	v_mfma_f32_16x16x32_bf16 v[142:145], v[52:55], v[138:141], v[0:3]
	v_cndmask_b32_e64 v74, v74, 0, s[8:9]
	v_cndmask_b32_e64 v73, v73, 0, s[8:9]
	v_cndmask_b32_e64 v72, v72, 0, s[8:9]
	s_nop 1
	v_mfma_f32_16x16x32_bf16 v[52:55], v[52:55], v[72:75], v[0:3]
	s_nop 1
	v_cvt_pk_bf16_f32 v146, v142, v143
	v_cvt_pk_bf16_f32 v147, v144, v145
	v_mfma_f32_16x16x32_bf16 v[142:145], v[48:51], v[138:141], v[0:3]
	v_mfma_f32_16x16x32_bf16 v[48:51], v[48:51], v[72:75], v[0:3]
	s_nop 1
	v_cvt_pk_bf16_f32 v52, v52, v53
	s_nop 3
	v_cvt_pk_bf16_f32 v142, v142, v143
	v_cvt_pk_bf16_f32 v143, v144, v145
	ds_write2_b64 v108, v[146:147], v[142:143] offset1:4
	v_mfma_f32_16x16x32_bf16 v[142:145], v[44:47], v[138:141], v[0:3]
	v_cvt_pk_bf16_f32 v48, v48, v49
	v_cvt_pk_bf16_f32 v49, v50, v51
	v_add_u32_e32 v50, 0x9000, v129
	v_mfma_f32_16x16x32_bf16 v[44:47], v[44:47], v[72:75], v[0:3]
	v_cvt_pk_bf16_f32 v53, v54, v55
	s_nop 2
	v_cvt_pk_bf16_f32 v146, v142, v143
	v_cvt_pk_bf16_f32 v147, v144, v145
	v_mfma_f32_16x16x32_bf16 v[142:145], v[40:43], v[138:141], v[0:3]
	ds_write2_b64 v50, v[52:53], v[48:49] offset0:32 offset1:36
	v_cvt_pk_bf16_f32 v44, v44, v45
	v_cvt_pk_bf16_f32 v45, v46, v47
	v_mfma_f32_16x16x32_bf16 v[40:43], v[40:43], v[72:75], v[0:3]
	s_nop 3
	v_cvt_pk_bf16_f32 v142, v142, v143
	s_nop 2
	v_cvt_pk_bf16_f32 v40, v40, v41
	v_cvt_pk_bf16_f32 v41, v42, v43
	ds_write2_b64 v50, v[44:45], v[40:41] offset0:40 offset1:44
	v_mfma_f32_16x16x32_bf16 v[40:43], v[56:59], v[72:75], v[0:3]
	v_cvt_pk_bf16_f32 v143, v144, v145
	ds_write2_b64 v108, v[146:147], v[142:143] offset0:8 offset1:12
	v_mfma_f32_16x16x32_bf16 v[142:145], v[56:59], v[138:141], v[0:3]
	s_nop 4
	v_cvt_pk_bf16_f32 v44, v40, v41
	v_cvt_pk_bf16_f32 v45, v42, v43
	v_mfma_f32_16x16x32_bf16 v[40:43], v[60:63], v[72:75], v[0:3]
	v_cvt_pk_bf16_f32 v146, v142, v143
	v_cvt_pk_bf16_f32 v147, v144, v145
	v_mfma_f32_16x16x32_bf16 v[142:145], v[60:63], v[138:141], v[0:3]
	s_nop 4
	v_cvt_pk_bf16_f32 v40, v40, v41
	v_cvt_pk_bf16_f32 v41, v42, v43
	ds_write2_b64 v50, v[44:45], v[40:41] offset0:48 offset1:52
	v_mfma_f32_16x16x32_bf16 v[40:43], v[64:67], v[72:75], v[0:3]
	v_cvt_pk_bf16_f32 v142, v142, v143
	v_cvt_pk_bf16_f32 v143, v144, v145
	ds_write2_b64 v108, v[146:147], v[142:143] offset0:16 offset1:20
	v_mfma_f32_16x16x32_bf16 v[142:145], v[64:67], v[138:141], v[0:3]
	v_mfma_f32_16x16x32_bf16 v[138:141], v[68:71], v[138:141], v[0:3]
	s_nop 2
	v_cvt_pk_bf16_f32 v44, v40, v41
	v_cvt_pk_bf16_f32 v45, v42, v43
	s_nop 1
	v_cvt_pk_bf16_f32 v142, v142, v143
	v_mfma_f32_16x16x32_bf16 v[40:43], v[68:71], v[72:75], v[0:3]
	v_cvt_pk_bf16_f32 v143, v144, v145
	v_cvt_pk_bf16_f32 v138, v138, v139
	v_cvt_pk_bf16_f32 v139, v140, v141
	ds_write2_b64 v108, v[142:143], v[138:139] offset0:24 offset1:28
	s_nop 3
	v_cvt_pk_bf16_f32 v40, v40, v41
	v_cvt_pk_bf16_f32 v41, v42, v43
	ds_write2_b64 v50, v[44:45], v[40:41] offset0:56 offset1:60
	s_waitcnt lgkmcnt(0)
	v_pk_mov_b32 v[40:41], v[102:103], v[102:103] op_sel:[1,0]
.LBB0_448:
	s_or_b32 s3, s2, s20
	s_lshl_b32 s42, s3, 10
	v_lshl_add_u64 v[42:43], v[106:107], 0, s[42:43]
	v_lshlrev_b64 v[42:43], 2, v[42:43]
	v_lshl_add_u64 v[46:47], s[50:51], 0, v[42:43]
	v_lshl_add_u64 v[44:45], s[48:49], 0, v[42:43]
	global_load_dword v138, v[46:47], off
	global_load_dword v136, v[44:45], off
	v_add_co_u32_e32 v48, vcc, 0x1000, v44
	s_mulk_i32 s2, 0x110
	s_nop 0
	v_addc_co_u32_e32 v49, vcc, 0, v45, vcc
	global_load_dword v130, v[48:49], off
	v_add_co_u32_e32 v48, vcc, 0x1000, v46
	v_lshl_add_u64 v[42:43], s[94:95], 0, v[42:43]
	s_nop 0
	v_addc_co_u32_e32 v49, vcc, 0, v47, vcc
	global_load_dword v134, v[48:49], off
	v_add_co_u32_e32 v48, vcc, s22, v44
	s_mov_b32 s3, 0x647d000
	s_nop 0
	v_addc_co_u32_e32 v49, vcc, 0, v45, vcc
	v_add_co_u32_e32 v50, vcc, s22, v46
	global_load_dword v128, v[48:49], off offset:-4096
	s_nop 0
	v_addc_co_u32_e32 v51, vcc, 0, v47, vcc
	global_load_dword v132, v[50:51], off offset:-4096
	global_load_dword v124, v[48:49], off
	global_load_dword v126, v[50:51], off
	v_add_co_u32_e32 v48, vcc, s84, v44
	s_waitcnt vmcnt(7)
	v_pk_mul_f32 v[138:139], v[40:41], v[138:139] op_sel_hi:[1,0]
	v_addc_co_u32_e32 v49, vcc, 0, v45, vcc
	v_add_co_u32_e32 v50, vcc, s84, v46
	global_load_dword v120, v[48:49], off offset:-4096
	s_nop 0
	v_addc_co_u32_e32 v51, vcc, 0, v47, vcc
	global_load_dword v122, v[50:51], off offset:-4096
	global_load_dword v116, v[48:49], off
	global_load_dword v118, v[50:51], off
	v_add_co_u32_e32 v48, vcc, s23, v44
	s_waitcnt vmcnt(10)
	v_pk_fma_f32 v[144:145], v[102:103], v[136:137], v[138:139] neg_lo:[0,0,1] neg_hi:[0,0,1]
	v_addc_co_u32_e32 v49, vcc, 0, v45, vcc
	v_add_co_u32_e32 v50, vcc, s23, v46
	global_load_dword v112, v[48:49], off offset:-4096
	s_nop 0
	v_addc_co_u32_e32 v51, vcc, 0, v47, vcc
	global_load_dword v114, v[50:51], off offset:-4096
	global_load_dword v108, v[48:49], off
	global_load_dword v110, v[50:51], off
	v_add_co_u32_e32 v48, vcc, s33, v44
	v_pk_fma_f32 v[138:139], v[102:103], v[136:137], v[138:139] op_sel_hi:[1,0,1]
	s_nop 0
	v_addc_co_u32_e32 v49, vcc, 0, v45, vcc
	v_add_co_u32_e32 v50, vcc, s33, v46
	global_load_dword v72, v[48:49], off offset:-4096
	s_nop 0
	v_addc_co_u32_e32 v51, vcc, 0, v47, vcc
	global_load_dword v74, v[50:51], off offset:-4096
	global_load_dword v68, v[48:49], off
	global_load_dword v70, v[50:51], off
	v_add_co_u32_e32 v48, vcc, s87, v44
	v_mov_b32_e32 v145, v139
	s_nop 0
	v_addc_co_u32_e32 v49, vcc, 0, v45, vcc
	v_add_co_u32_e32 v50, vcc, s87, v46
	global_load_dword v64, v[48:49], off offset:-4096
	s_nop 0
	v_addc_co_u32_e32 v51, vcc, 0, v47, vcc
	global_load_dword v66, v[50:51], off offset:-4096
	global_load_dword v60, v[48:49], off
	global_load_dword v62, v[50:51], off
	v_add_co_u32_e32 v48, vcc, s85, v44
	s_waitcnt vmcnt(6)
	v_pk_mul_f32 v[74:75], v[40:41], v[74:75] op_sel_hi:[1,0]
	v_addc_co_u32_e32 v49, vcc, 0, v45, vcc
	v_add_co_u32_e32 v50, vcc, s85, v46
	global_load_dword v56, v[48:49], off offset:-4096
	s_nop 0
	v_addc_co_u32_e32 v51, vcc, 0, v47, vcc
	v_add_co_u32_e32 v44, vcc, s88, v44
	global_load_dword v58, v[50:51], off offset:-4096
	global_load_dword v52, v[48:49], off
	global_load_dword v54, v[50:51], off
	v_addc_co_u32_e32 v45, vcc, 0, v45, vcc
	v_add_co_u32_e32 v46, vcc, s88, v46
	global_load_dword v48, v[44:45], off offset:-4096
	s_nop 0
	v_addc_co_u32_e32 v47, vcc, 0, v47, vcc
	global_load_dword v50, v[46:47], off offset:-4096
	s_nop 0
	global_load_dword v44, v[44:45], off
	s_nop 0
	global_load_dword v46, v[46:47], off
	v_add_u32_e32 v45, s2, v115
	v_add_u32_e32 v47, 0x8000, v45
	ds_read2_b32 v[140:141], v47 offset1:68
	s_waitcnt vmcnt(12)
	v_pk_mul_f32 v[70:71], v[40:41], v[70:71] op_sel_hi:[1,0]
	s_waitcnt vmcnt(10)
	v_pk_mul_f32 v[66:67], v[40:41], v[66:67] op_sel_hi:[1,0]
	s_waitcnt vmcnt(8)
	v_pk_mul_f32 v[62:63], v[40:41], v[62:63] op_sel_hi:[1,0]
	s_mov_b32 s2, 16
	s_waitcnt lgkmcnt(0)
	v_lshlrev_b32_e32 v142, 16, v140
	v_and_b32_e32 v143, 0xffff0000, v140
	v_pk_add_f32 v[138:139], v[144:145], v[142:143]
	v_add_co_u32_e32 v142, vcc, s3, v42
	s_mov_b32 s3, 0x669d000
	s_nop 0
	v_addc_co_u32_e32 v143, vcc, 0, v43, vcc
	v_add_co_u32_e32 v144, vcc, s3, v42
	v_cvt_pk_bf16_f32 v49, v138, v139
	s_nop 0
	v_addc_co_u32_e32 v145, vcc, 0, v43, vcc
	global_store_dword v[142:143], v138, off offset:-4096
	global_store_dword v[144:145], v139, off offset:-4096
	v_lshlrev_b32_e32 v138, 16, v141
	v_and_b32_e32 v139, 0xffff0000, v141
	v_pk_mul_f32 v[140:141], v[40:41], v[134:135] op_sel_hi:[1,0]
	s_mov_b32 s3, 0x647f000
	v_pk_fma_f32 v[146:147], v[102:103], v[130:131], v[140:141] neg_lo:[0,0,1] neg_hi:[0,0,1]
	v_pk_fma_f32 v[140:141], v[102:103], v[130:131], v[140:141] op_sel_hi:[1,0,1]
	s_waitcnt vmcnt(8)
	v_pk_mul_f32 v[58:59], v[40:41], v[58:59] op_sel_hi:[1,0]
	v_mov_b32_e32 v147, v141
	v_pk_add_f32 v[138:139], v[146:147], v[138:139]
	s_waitcnt vmcnt(6)
	v_pk_mul_f32 v[54:55], v[40:41], v[54:55] op_sel_hi:[1,0]
	v_cvt_pk_bf16_f32 v51, v138, v139
	ds_write2_b32 v47, v49, v51 offset1:68
	global_store_dword v[142:143], v138, off
	global_store_dword v[144:145], v139, off
	ds_read2_b32 v[138:139], v47 offset0:136 offset1:204
	v_pk_mul_f32 v[142:143], v[40:41], v[132:133] op_sel_hi:[1,0]
	s_waitcnt lgkmcnt(0)
	v_lshlrev_b32_e32 v140, 16, v138
	v_pk_fma_f32 v[144:145], v[102:103], v[128:129], v[142:143] neg_lo:[0,0,1] neg_hi:[0,0,1]
	v_pk_fma_f32 v[142:143], v[102:103], v[128:129], v[142:143] op_sel_hi:[1,0,1]
	v_and_b32_e32 v141, 0xffff0000, v138
	v_add_co_u32_e32 v142, vcc, s3, v42
	v_mov_b32_e32 v145, v143
	s_nop 0
	v_addc_co_u32_e32 v143, vcc, 0, v43, vcc
	s_mov_b32 s3, 0x669f000
	v_pk_add_f32 v[140:141], v[144:145], v[140:141]
	v_add_co_u32_e32 v144, vcc, s3, v42
	v_cvt_pk_bf16_f32 v49, v140, v141
	s_nop 0
	v_addc_co_u32_e32 v145, vcc, 0, v43, vcc
	global_store_dword v[142:143], v140, off offset:-4096
	global_store_dword v[144:145], v141, off offset:-4096
	v_pk_mul_f32 v[140:141], v[40:41], v[126:127] op_sel_hi:[1,0]
	v_lshlrev_b32_e32 v138, 16, v139
	v_pk_fma_f32 v[146:147], v[102:103], v[124:125], v[140:141] neg_lo:[0,0,1] neg_hi:[0,0,1]
	v_pk_fma_f32 v[140:141], v[102:103], v[124:125], v[140:141] op_sel_hi:[1,0,1]
	v_and_b32_e32 v139, 0xffff0000, v139
	v_mov_b32_e32 v147, v141
	v_pk_add_f32 v[138:139], v[146:147], v[138:139]
	s_mov_b32 s3, 0x6481000
	v_cvt_pk_bf16_f32 v51, v138, v139
	ds_write2_b32 v47, v49, v51 offset0:136 offset1:204
	global_store_dword v[142:143], v138, off
	global_store_dword v[144:145], v139, off
	v_add_u32_e32 v47, 0x8400, v45
	ds_read2_b32 v[138:139], v47 offset0:16 offset1:84
	v_pk_mul_f32 v[142:143], v[40:41], v[122:123] op_sel_hi:[1,0]
	s_waitcnt lgkmcnt(0)
	v_lshlrev_b32_e32 v140, 16, v138
	v_pk_fma_f32 v[144:145], v[102:103], v[120:121], v[142:143] neg_lo:[0,0,1] neg_hi:[0,0,1]
	v_pk_fma_f32 v[142:143], v[102:103], v[120:121], v[142:143] op_sel_hi:[1,0,1]
	v_and_b32_e32 v141, 0xffff0000, v138
	v_add_co_u32_e32 v142, vcc, s3, v42
	v_mov_b32_e32 v145, v143
	s_nop 0
	v_addc_co_u32_e32 v143, vcc, 0, v43, vcc
	s_mov_b32 s3, 0x66a1000
	v_pk_add_f32 v[140:141], v[144:145], v[140:141]
	v_add_co_u32_e32 v144, vcc, s3, v42
	v_cvt_pk_bf16_f32 v49, v140, v141
	s_nop 0
	v_addc_co_u32_e32 v145, vcc, 0, v43, vcc
	global_store_dword v[142:143], v140, off offset:-4096
	global_store_dword v[144:145], v141, off offset:-4096
	v_pk_mul_f32 v[140:141], v[40:41], v[118:119] op_sel_hi:[1,0]
	v_lshlrev_b32_e32 v138, 16, v139
	v_pk_fma_f32 v[146:147], v[102:103], v[116:117], v[140:141] neg_lo:[0,0,1] neg_hi:[0,0,1]
	v_pk_fma_f32 v[140:141], v[102:103], v[116:117], v[140:141] op_sel_hi:[1,0,1]
	v_and_b32_e32 v139, 0xffff0000, v139
	v_mov_b32_e32 v147, v141
	v_pk_add_f32 v[138:139], v[146:147], v[138:139]
	s_mov_b32 s3, 0x6483000
	v_cvt_pk_bf16_f32 v51, v138, v139
	ds_write2_b32 v47, v49, v51 offset0:16 offset1:84
	global_store_dword v[142:143], v138, off
	global_store_dword v[144:145], v139, off
	ds_read2_b32 v[138:139], v47 offset0:152 offset1:220
	v_pk_mul_f32 v[142:143], v[40:41], v[114:115] op_sel_hi:[1,0]
	s_waitcnt lgkmcnt(0)
	v_lshlrev_b32_e32 v140, 16, v138
	v_pk_fma_f32 v[144:145], v[102:103], v[112:113], v[142:143] neg_lo:[0,0,1] neg_hi:[0,0,1]
	v_pk_fma_f32 v[142:143], v[102:103], v[112:113], v[142:143] op_sel_hi:[1,0,1]
	v_and_b32_e32 v141, 0xffff0000, v138
	v_add_co_u32_e32 v142, vcc, s3, v42
	v_mov_b32_e32 v145, v143
	s_nop 0
	v_addc_co_u32_e32 v143, vcc, 0, v43, vcc
	s_mov_b32 s3, 0x66a3000
	v_pk_add_f32 v[140:141], v[144:145], v[140:141]
	v_add_co_u32_e32 v144, vcc, s3, v42
	v_cvt_pk_bf16_f32 v49, v140, v141
	s_nop 0
	v_addc_co_u32_e32 v145, vcc, 0, v43, vcc
	global_store_dword v[142:143], v140, off offset:-4096
	global_store_dword v[144:145], v141, off offset:-4096
	v_pk_mul_f32 v[140:141], v[40:41], v[110:111] op_sel_hi:[1,0]
	v_lshlrev_b32_e32 v138, 16, v139
	v_pk_fma_f32 v[146:147], v[102:103], v[108:109], v[140:141] neg_lo:[0,0,1] neg_hi:[0,0,1]
	v_pk_fma_f32 v[140:141], v[102:103], v[108:109], v[140:141] op_sel_hi:[1,0,1]
	v_and_b32_e32 v139, 0xffff0000, v139
	v_mov_b32_e32 v147, v141
	v_pk_add_f32 v[138:139], v[146:147], v[138:139]
	s_mov_b32 s3, 0x6485000
	v_cvt_pk_bf16_f32 v51, v138, v139
	ds_write2_b32 v47, v49, v51 offset0:152 offset1:220
	global_store_dword v[142:143], v138, off
	global_store_dword v[144:145], v139, off
	v_add_u32_e32 v47, 0x8800, v45
	ds_read2_b32 v[138:139], v47 offset0:32 offset1:100
	v_pk_fma_f32 v[142:143], v[102:103], v[72:73], v[74:75] neg_lo:[0,0,1] neg_hi:[0,0,1]
	v_pk_fma_f32 v[72:73], v[102:103], v[72:73], v[74:75] op_sel_hi:[1,0,1]
	v_add_co_u32_e32 v74, vcc, s3, v42
	s_waitcnt lgkmcnt(0)
	v_lshlrev_b32_e32 v140, 16, v138
	v_and_b32_e32 v141, 0xffff0000, v138
	v_mov_b32_e32 v143, v73
	v_addc_co_u32_e32 v75, vcc, 0, v43, vcc
	s_mov_b32 s3, 0x66a5000
	v_pk_add_f32 v[72:73], v[142:143], v[140:141]
	v_add_co_u32_e32 v140, vcc, s3, v42
	v_cvt_pk_bf16_f32 v49, v72, v73
	s_nop 0
	v_addc_co_u32_e32 v141, vcc, 0, v43, vcc
	global_store_dword v[74:75], v72, off offset:-4096
	global_store_dword v[140:141], v73, off offset:-4096
	v_lshlrev_b32_e32 v72, 16, v139
	v_and_b32_e32 v73, 0xffff0000, v139
	v_pk_fma_f32 v[138:139], v[102:103], v[68:69], v[70:71] neg_lo:[0,0,1] neg_hi:[0,0,1]
	v_pk_fma_f32 v[68:69], v[102:103], v[68:69], v[70:71] op_sel_hi:[1,0,1]
	s_mov_b32 s3, 0x6487000
	v_mov_b32_e32 v139, v69
	v_pk_add_f32 v[68:69], v[138:139], v[72:73]
	v_pk_fma_f32 v[72:73], v[102:103], v[64:65], v[66:67] neg_lo:[0,0,1] neg_hi:[0,0,1]
	v_cvt_pk_bf16_f32 v51, v68, v69
	ds_write2_b32 v47, v49, v51 offset0:32 offset1:100
	global_store_dword v[74:75], v68, off
	global_store_dword v[140:141], v69, off
	ds_read2_b32 v[68:69], v47 offset0:168 offset1:236
	v_pk_fma_f32 v[64:65], v[102:103], v[64:65], v[66:67] op_sel_hi:[1,0,1]
	v_add_co_u32_e32 v66, vcc, s3, v42
	v_mov_b32_e32 v73, v65
	s_waitcnt lgkmcnt(0)
	v_lshlrev_b32_e32 v70, 16, v68
	v_and_b32_e32 v71, 0xffff0000, v68
	v_addc_co_u32_e32 v67, vcc, 0, v43, vcc
	s_mov_b32 s3, 0x66a7000
	v_pk_add_f32 v[64:65], v[72:73], v[70:71]
	v_add_co_u32_e32 v70, vcc, s3, v42
	v_cvt_pk_bf16_f32 v49, v64, v65
	s_nop 0
	v_addc_co_u32_e32 v71, vcc, 0, v43, vcc
	global_store_dword v[66:67], v64, off offset:-4096
	global_store_dword v[70:71], v65, off offset:-4096
	v_lshlrev_b32_e32 v64, 16, v69
	v_and_b32_e32 v65, 0xffff0000, v69
	v_pk_fma_f32 v[68:69], v[102:103], v[60:61], v[62:63] neg_lo:[0,0,1] neg_hi:[0,0,1]
	v_pk_fma_f32 v[60:61], v[102:103], v[60:61], v[62:63] op_sel_hi:[1,0,1]
	s_mov_b32 s3, 0x6489000
	v_mov_b32_e32 v69, v61
	v_pk_add_f32 v[60:61], v[68:69], v[64:65]
	v_pk_fma_f32 v[64:65], v[102:103], v[56:57], v[58:59] neg_lo:[0,0,1] neg_hi:[0,0,1]
	v_cvt_pk_bf16_f32 v51, v60, v61
	ds_write2_b32 v47, v49, v51 offset0:168 offset1:236
	global_store_dword v[66:67], v60, off
	global_store_dword v[70:71], v61, off
	v_add_u32_e32 v66, 0x8c00, v45
	ds_read2_b32 v[60:61], v66 offset0:48 offset1:116
	v_pk_fma_f32 v[56:57], v[102:103], v[56:57], v[58:59] op_sel_hi:[1,0,1]
	v_add_co_u32_e32 v58, vcc, s3, v42
	v_mov_b32_e32 v65, v57
	s_waitcnt lgkmcnt(0)
	v_lshlrev_b32_e32 v62, 16, v60
	v_and_b32_e32 v63, 0xffff0000, v60
	v_addc_co_u32_e32 v59, vcc, 0, v43, vcc
	s_mov_b32 s3, 0x66a9000
	v_pk_add_f32 v[56:57], v[64:65], v[62:63]
	v_add_co_u32_e32 v62, vcc, s3, v42
	v_cvt_pk_bf16_f32 v45, v56, v57
	s_nop 0
	v_addc_co_u32_e32 v63, vcc, 0, v43, vcc
	global_store_dword v[58:59], v56, off offset:-4096
	global_store_dword v[62:63], v57, off offset:-4096
	v_lshlrev_b32_e32 v56, 16, v61
	v_and_b32_e32 v57, 0xffff0000, v61
	v_pk_fma_f32 v[60:61], v[102:103], v[52:53], v[54:55] neg_lo:[0,0,1] neg_hi:[0,0,1]
	v_pk_fma_f32 v[52:53], v[102:103], v[52:53], v[54:55] op_sel_hi:[1,0,1]
	s_waitcnt vmcnt(28)
	v_pk_mul_f32 v[50:51], v[40:41], v[50:51] op_sel_hi:[1,0]
	v_mov_b32_e32 v61, v53
	v_pk_add_f32 v[52:53], v[60:61], v[56:57]
	v_pk_fma_f32 v[56:57], v[102:103], v[48:49], v[50:51] neg_lo:[0,0,1] neg_hi:[0,0,1]
	v_cvt_pk_bf16_f32 v47, v52, v53
	ds_write2_b32 v66, v45, v47 offset0:48 offset1:116
	global_store_dword v[58:59], v52, off
	global_store_dword v[62:63], v53, off
	ds_read2_b32 v[52:53], v66 offset0:184 offset1:252
	v_pk_fma_f32 v[48:49], v[102:103], v[48:49], v[50:51] op_sel_hi:[1,0,1]
	s_mov_b32 s3, 0x648a000
	v_mov_b32_e32 v57, v49
	v_add_co_u32_e32 v50, vcc, s3, v42
	s_waitcnt lgkmcnt(0)
	v_lshlrev_b32_e32 v54, 16, v52
	v_and_b32_e32 v55, 0xffff0000, v52
	v_pk_add_f32 v[48:49], v[56:57], v[54:55]
	v_addc_co_u32_e32 v51, vcc, 0, v43, vcc
	s_mov_b32 s3, 0x66aa000
	global_store_dword v[50:51], v48, off
	v_add_co_u32_e32 v50, vcc, s3, v42
	s_waitcnt vmcnt(29)
	v_pk_mul_f32 v[46:47], v[40:41], v[46:47] op_sel_hi:[1,0]
	v_addc_co_u32_e32 v51, vcc, 0, v43, vcc
	global_store_dword v[50:51], v49, off
	v_pk_fma_f32 v[50:51], v[102:103], v[44:45], v[46:47] neg_lo:[0,0,1] neg_hi:[0,0,1]
	v_pk_fma_f32 v[44:45], v[102:103], v[44:45], v[46:47] op_sel_hi:[1,0,1]
	v_cvt_pk_bf16_f32 v52, v48, v49
	v_lshlrev_b32_e32 v48, 16, v53
	v_and_b32_e32 v49, 0xffff0000, v53
	v_mov_b32_e32 v51, v45
	v_pk_add_f32 v[44:45], v[50:51], v[48:49]
	s_nop 0
	v_cvt_pk_bf16_f32 v46, v44, v45
	ds_write2_b32 v66, v52, v46 offset0:184 offset1:252
	v_add_co_u32_e32 v46, vcc, 0x648b000, v42
	s_nop 1
	v_addc_co_u32_e32 v47, vcc, 0, v43, vcc
	v_add_co_u32_e32 v42, vcc, 0x66ab000, v42
	global_store_dword v[46:47], v44, off
	s_nop 0
	v_addc_co_u32_e32 v43, vcc, 0, v43, vcc
	global_store_dword v[42:43], v45, off
	s_and_b64 vcc, exec, s[14:15]
	s_mov_b64 s[14:15], 0
	s_cbranch_vccnz .LBB0_448
	v_xor_b32_e32 v12, 0x80000000, v12
	v_cvt_pk_bf16_f32 v8, v8, v12
	v_xor_b32_e32 v12, 0x80000000, v13
	v_cvt_pk_bf16_f32 v9, v9, v12
	v_xor_b32_e32 v12, 0x80000000, v14
	v_cvt_pk_bf16_f32 v10, v10, v12
	v_xor_b32_e32 v12, 0x80000000, v15
	s_waitcnt lgkmcnt(0)
	v_xor_b32_e32 v20, 0x80000000, v20
	v_cvt_pk_bf16_f32 v11, v11, v12
	ds_read_b128 v[12:15], v131 offset:32768
	v_cvt_pk_bf16_f32 v16, v16, v20
	v_xor_b32_e32 v20, 0x80000000, v21
	v_cvt_pk_bf16_f32 v17, v17, v20
	v_xor_b32_e32 v20, 0x80000000, v22
	v_cvt_pk_bf16_f32 v18, v18, v20
	v_xor_b32_e32 v20, 0x80000000, v23
	v_cvt_pk_bf16_f32 v19, v19, v20
	ds_read_b128 v[20:23], v131 offset:32832
	v_xor_b32_e32 v28, 0x80000000, v28
	s_waitcnt lgkmcnt(1)
	v_mfma_f32_16x16x32_bf16 v[12:15], v[8:11], v[12:15], v[0:3]
	v_cvt_pk_bf16_f32 v24, v24, v28
	v_xor_b32_e32 v28, 0x80000000, v29
	v_cvt_pk_bf16_f32 v25, v25, v28
	v_xor_b32_e32 v28, 0x80000000, v30
	v_cvt_pk_bf16_f32 v26, v26, v28
	v_xor_b32_e32 v28, 0x80000000, v31
	v_cvt_pk_bf16_f32 v27, v27, v28
	s_waitcnt lgkmcnt(0)
	v_mfma_f32_16x16x32_bf16 v[12:15], v[16:19], v[20:23], v[12:15]
	ds_read_b128 v[20:23], v131 offset:32896
	v_xor_b32_e32 v36, 0x80000000, v36
	v_cvt_pk_bf16_f32 v32, v32, v36
	v_xor_b32_e32 v36, 0x80000000, v37
	v_cvt_pk_bf16_f32 v33, v33, v36
	v_xor_b32_e32 v36, 0x80000000, v38
	v_cvt_pk_bf16_f32 v34, v34, v36
	v_xor_b32_e32 v36, 0x80000000, v39
	v_cvt_pk_bf16_f32 v35, v35, v36
	s_waitcnt lgkmcnt(0)
	v_mfma_f32_16x16x32_bf16 v[12:15], v[24:27], v[20:23], v[12:15]
	ds_read_b128 v[20:23], v131 offset:32960
	s_mov_b32 s4, 1
	s_waitcnt lgkmcnt(0)
	v_mfma_f32_16x16x32_bf16 v[12:15], v[32:35], v[20:23], v[12:15]
	v_lshlrev_b32_e32 v20, 16, v104
	v_and_b32_e32 v21, 0xffff0000, v104
	s_nop 5
	v_pk_fma_f32 v[12:13], v[4:5], v[20:21], v[12:13]
	s_nop 0
	v_mul_f32_e32 v20, 0x3d372713, v12
	v_mul_f32_e32 v21, 0x3d372713, v13
	v_mul_f32_e32 v20, v12, v20
	v_mul_f32_e32 v21, v13, v21
	v_fma_f32 v20, v12, v20, v12
	v_fma_f32 v21, v13, v21, v13
	v_mul_f32_e32 v20, 0x3f4c422a, v20
	v_mul_f32_e32 v21, 0x3f4c422a, v21
	v_add_f32_e32 v20, v20, v20
	v_add_f32_e32 v21, v21, v21
	v_mul_f32_e32 v20, 0xbfb8aa3b, v20
	v_mul_f32_e32 v21, 0xbfb8aa3b, v21
	v_exp_f32_e32 v20, v20
	v_exp_f32_e32 v21, v21
	s_nop 0
	v_pk_add_f32 v[20:21], v[20:21], 1.0 op_sel_hi:[1,0]
	s_nop 0
	v_rcp_f32_e32 v21, v21
	v_rcp_f32_e32 v20, v20
	s_nop 0
	v_pk_mul_f32 v[12:13], v[12:13], v[20:21]
	v_lshlrev_b32_e32 v20, 16, v105
	v_and_b32_e32 v21, 0xffff0000, v105
	v_pk_fma_f32 v[14:15], v[6:7], v[20:21], v[14:15]
	v_cvt_pk_bf16_f32 v12, v12, v13
	v_mul_f32_e32 v20, 0x3d372713, v14
	v_mul_f32_e32 v21, 0x3d372713, v15
	v_mul_f32_e32 v20, v14, v20
	v_mul_f32_e32 v21, v15, v21
	v_fma_f32 v20, v14, v20, v14
	v_fma_f32 v21, v15, v21, v15
	v_mul_f32_e32 v20, 0x3f4c422a, v20
	v_mul_f32_e32 v21, 0x3f4c422a, v21
	v_add_f32_e32 v20, v20, v20
	v_add_f32_e32 v21, v21, v21
	v_mul_f32_e32 v20, 0xbfb8aa3b, v20
	v_mul_f32_e32 v21, 0xbfb8aa3b, v21
	v_exp_f32_e32 v20, v20
	v_exp_f32_e32 v21, v21
	s_nop 0
	v_pk_add_f32 v[20:21], v[20:21], 1.0 op_sel_hi:[1,0]
	s_nop 0
	v_rcp_f32_e32 v21, v21
	v_rcp_f32_e32 v20, v20
	s_nop 0
	v_pk_mul_f32 v[14:15], v[14:15], v[20:21]
	v_lshl_add_u32 v20, s12, 5, v137
	v_cvt_pk_bf16_f32 v13, v14, v15
	ds_write_b64 v20, v[12:13]
	ds_read_b128 v[12:15], v131 offset:37120
	s_waitcnt lgkmcnt(0)
	v_mfma_f32_16x16x32_bf16 v[8:11], v[8:11], v[12:15], v[0:3]
	ds_read_b128 v[12:15], v131 offset:37184
	s_waitcnt lgkmcnt(0)
	v_mfma_f32_16x16x32_bf16 v[8:11], v[16:19], v[12:15], v[8:11]
	ds_read_b128 v[12:15], v131 offset:37248
	s_waitcnt lgkmcnt(0)
	v_mfma_f32_16x16x32_bf16 v[8:11], v[24:27], v[12:15], v[8:11]
	ds_read_b128 v[12:15], v131 offset:37312
	s_waitcnt lgkmcnt(0)
	v_mfma_f32_16x16x32_bf16 v[8:11], v[32:35], v[12:15], v[8:11]
	v_lshlrev_b32_e32 v12, 16, v100
	v_and_b32_e32 v13, 0xffff0000, v100
	s_nop 5
	v_pk_fma_f32 v[4:5], v[4:5], v[12:13], v[8:9]
	s_nop 0
	v_mul_f32_e32 v8, 0x3d372713, v4
	v_mul_f32_e32 v9, 0x3d372713, v5
	v_mul_f32_e32 v8, v4, v8
	v_mul_f32_e32 v9, v5, v9
	v_fma_f32 v8, v4, v8, v4
	v_fma_f32 v9, v5, v9, v5
	v_mul_f32_e32 v8, 0x3f4c422a, v8
	v_mul_f32_e32 v9, 0x3f4c422a, v9
	v_add_f32_e32 v8, v8, v8
	v_add_f32_e32 v9, v9, v9
	v_mul_f32_e32 v8, 0xbfb8aa3b, v8
	v_mul_f32_e32 v9, 0xbfb8aa3b, v9
	v_exp_f32_e32 v8, v8
	v_exp_f32_e32 v9, v9
	s_nop 0
	v_pk_add_f32 v[8:9], v[8:9], 1.0 op_sel_hi:[1,0]
	s_nop 0
	v_rcp_f32_e32 v9, v9
	v_rcp_f32_e32 v8, v8
	s_nop 0
	v_pk_mul_f32 v[4:5], v[4:5], v[8:9]
	v_lshlrev_b32_e32 v8, 16, v101
	v_and_b32_e32 v9, 0xffff0000, v101
	v_pk_fma_f32 v[6:7], v[6:7], v[8:9], v[10:11]
	v_cvt_pk_bf16_f32 v4, v4, v5
	v_mul_f32_e32 v8, 0x3d372713, v6
	v_mul_f32_e32 v9, 0x3d372713, v7
	v_mul_f32_e32 v8, v6, v8
	v_mul_f32_e32 v9, v7, v9
	v_fma_f32 v8, v6, v8, v6
	v_fma_f32 v9, v7, v9, v7
	v_mul_f32_e32 v8, 0x3f4c422a, v8
	v_mul_f32_e32 v9, 0x3f4c422a, v9
	v_add_f32_e32 v8, v8, v8
	v_add_f32_e32 v9, v9, v9
	v_mul_f32_e32 v8, 0xbfb8aa3b, v8
	v_mul_f32_e32 v9, 0xbfb8aa3b, v9
	v_exp_f32_e32 v8, v8
	v_exp_f32_e32 v9, v9
	s_nop 0
	v_pk_add_f32 v[8:9], v[8:9], 1.0 op_sel_hi:[1,0]
	s_nop 0
	v_rcp_f32_e32 v9, v9
	s_mov_b64 s[2:3], 0
	v_rcp_f32_e32 v8, v8
	s_nop 0
	v_pk_mul_f32 v[6:7], v[6:7], v[8:9]
	s_andn2_b64 vcc, exec, s[10:11]
	v_cvt_pk_bf16_f32 v5, v6, v7
	ds_write_b64 v20, v[4:5] offset:8448
	s_nop 7
	s_cbranch_vccnz .LBB0_447
	v_mov_b32_e32 v0, v192
	v_mov_b32_e32 v4, v192
	v_mov_b32_e32 v8, v192
	v_mov_b32_e32 v12, v192
	v_mov_b32_e32 v16, v192
	v_mov_b32_e32 v20, v192
	v_mov_b32_e32 v24, v192
	v_mov_b32_e32 v28, v192
	s_waitcnt lgkmcnt(0)
	s_barrier
	global_load_dwordx4 v[32:35], v[86:87], off
	global_load_dwordx4 v[36:39], v[88:89], off
	ds_read_b128 v[40:43], v133
	v_mov_b32_e32 v1, v0
	v_mov_b32_e32 v2, v0
	v_mov_b32_e32 v3, v0
	v_mov_b32_e32 v5, v4
	v_mov_b32_e32 v6, v4
	v_mov_b32_e32 v7, v4
	v_mov_b32_e32 v9, v8
	v_mov_b32_e32 v10, v8
	v_mov_b32_e32 v11, v8
	v_mov_b32_e32 v13, v12
	v_mov_b32_e32 v14, v12
	v_mov_b32_e32 v15, v12
	v_mov_b32_e32 v17, v16
	v_mov_b32_e32 v18, v16
	v_mov_b32_e32 v19, v16
	v_mov_b32_e32 v21, v20
	v_mov_b32_e32 v22, v20
	v_mov_b32_e32 v23, v20
	v_mov_b32_e32 v25, v24
	v_mov_b32_e32 v26, v24
	v_mov_b32_e32 v27, v24
	v_mov_b32_e32 v29, v28
	v_mov_b32_e32 v30, v28
	v_mov_b32_e32 v31, v28
	s_cmp_lg_u32 s19, 0
	s_mov_b64 s[2:3], -1
	s_waitcnt vmcnt(0) lgkmcnt(0)
	v_mfma_f32_16x16x32_bf16 v[0:3], v[32:35], v[40:43], v[0:3]
	v_mfma_f32_16x16x32_bf16 v[4:7], v[36:39], v[40:43], v[4:7]
	ds_read_b128 v[40:43], v133 offset:8448
	s_waitcnt lgkmcnt(0)
	v_mfma_f32_16x16x32_bf16 v[8:11], v[32:35], v[40:43], v[8:11]
	v_mfma_f32_16x16x32_bf16 v[12:15], v[36:39], v[40:43], v[12:15]
	ds_read_b128 v[40:43], v133 offset:16896
	s_waitcnt lgkmcnt(0)
	v_mfma_f32_16x16x32_bf16 v[16:19], v[32:35], v[40:43], v[16:19]
	v_mfma_f32_16x16x32_bf16 v[20:23], v[36:39], v[40:43], v[20:23]
	ds_read_b128 v[40:43], v133 offset:25344
	s_waitcnt lgkmcnt(0)
	v_mfma_f32_16x16x32_bf16 v[24:27], v[32:35], v[40:43], v[24:27]
	v_mfma_f32_16x16x32_bf16 v[28:31], v[36:39], v[40:43], v[28:31]
	global_load_dwordx4 v[32:35], v[86:87], off offset:64
	global_load_dwordx4 v[36:39], v[88:89], off offset:64
	ds_read_b128 v[40:43], v133 offset:64
	s_waitcnt vmcnt(0) lgkmcnt(0)
	v_mfma_f32_16x16x32_bf16 v[0:3], v[32:35], v[40:43], v[0:3]
	v_mfma_f32_16x16x32_bf16 v[4:7], v[36:39], v[40:43], v[4:7]
	ds_read_b128 v[40:43], v133 offset:8512
	s_waitcnt lgkmcnt(0)
	v_mfma_f32_16x16x32_bf16 v[8:11], v[32:35], v[40:43], v[8:11]
	v_mfma_f32_16x16x32_bf16 v[12:15], v[36:39], v[40:43], v[12:15]
	ds_read_b128 v[40:43], v133 offset:16960
	s_waitcnt lgkmcnt(0)
	v_mfma_f32_16x16x32_bf16 v[16:19], v[32:35], v[40:43], v[16:19]
	v_mfma_f32_16x16x32_bf16 v[20:23], v[36:39], v[40:43], v[20:23]
	ds_read_b128 v[40:43], v133 offset:25408
	s_waitcnt lgkmcnt(0)
	v_mfma_f32_16x16x32_bf16 v[24:27], v[32:35], v[40:43], v[24:27]
	v_mfma_f32_16x16x32_bf16 v[28:31], v[36:39], v[40:43], v[28:31]
	global_load_dwordx4 v[32:35], v[86:87], off offset:128
	global_load_dwordx4 v[36:39], v[88:89], off offset:128
	ds_read_b128 v[40:43], v133 offset:128
	s_waitcnt vmcnt(0) lgkmcnt(0)
	v_mfma_f32_16x16x32_bf16 v[0:3], v[32:35], v[40:43], v[0:3]
	v_mfma_f32_16x16x32_bf16 v[4:7], v[36:39], v[40:43], v[4:7]
	ds_read_b128 v[40:43], v133 offset:8576
	s_waitcnt lgkmcnt(0)
	v_mfma_f32_16x16x32_bf16 v[8:11], v[32:35], v[40:43], v[8:11]
	v_mfma_f32_16x16x32_bf16 v[12:15], v[36:39], v[40:43], v[12:15]
	ds_read_b128 v[40:43], v133 offset:17024
	s_waitcnt lgkmcnt(0)
	v_mfma_f32_16x16x32_bf16 v[16:19], v[32:35], v[40:43], v[16:19]
	v_mfma_f32_16x16x32_bf16 v[20:23], v[36:39], v[40:43], v[20:23]
	ds_read_b128 v[40:43], v133 offset:25472
	s_waitcnt lgkmcnt(0)
	v_mfma_f32_16x16x32_bf16 v[24:27], v[32:35], v[40:43], v[24:27]
	v_mfma_f32_16x16x32_bf16 v[28:31], v[36:39], v[40:43], v[28:31]
	global_load_dwordx4 v[32:35], v[86:87], off offset:192
	global_load_dwordx4 v[36:39], v[88:89], off offset:192
	ds_read_b128 v[40:43], v133 offset:192
	s_waitcnt vmcnt(0) lgkmcnt(0)
	v_mfma_f32_16x16x32_bf16 v[0:3], v[32:35], v[40:43], v[0:3]
	v_mfma_f32_16x16x32_bf16 v[4:7], v[36:39], v[40:43], v[4:7]
	ds_read_b128 v[40:43], v133 offset:8640
	s_waitcnt lgkmcnt(0)
	v_mfma_f32_16x16x32_bf16 v[8:11], v[32:35], v[40:43], v[8:11]
	v_mfma_f32_16x16x32_bf16 v[12:15], v[36:39], v[40:43], v[12:15]
	ds_read_b128 v[40:43], v133 offset:17088
	s_waitcnt lgkmcnt(0)
	v_mfma_f32_16x16x32_bf16 v[16:19], v[32:35], v[40:43], v[16:19]
	v_mfma_f32_16x16x32_bf16 v[20:23], v[36:39], v[40:43], v[20:23]
	ds_read_b128 v[40:43], v133 offset:25536
	s_waitcnt lgkmcnt(0)
	v_mfma_f32_16x16x32_bf16 v[24:27], v[32:35], v[40:43], v[24:27]
	v_mfma_f32_16x16x32_bf16 v[28:31], v[36:39], v[40:43], v[28:31]
	global_load_dwordx4 v[32:35], v[86:87], off offset:256
	global_load_dwordx4 v[36:39], v[88:89], off offset:256
	ds_read_b128 v[40:43], v133 offset:256
	s_waitcnt vmcnt(0) lgkmcnt(0)
	v_mfma_f32_16x16x32_bf16 v[0:3], v[32:35], v[40:43], v[0:3]
	v_mfma_f32_16x16x32_bf16 v[4:7], v[36:39], v[40:43], v[4:7]
	ds_read_b128 v[40:43], v133 offset:8704
	s_waitcnt lgkmcnt(0)
	v_mfma_f32_16x16x32_bf16 v[8:11], v[32:35], v[40:43], v[8:11]
	v_mfma_f32_16x16x32_bf16 v[12:15], v[36:39], v[40:43], v[12:15]
	ds_read_b128 v[40:43], v133 offset:17152
	s_waitcnt lgkmcnt(0)
	v_mfma_f32_16x16x32_bf16 v[16:19], v[32:35], v[40:43], v[16:19]
	v_mfma_f32_16x16x32_bf16 v[20:23], v[36:39], v[40:43], v[20:23]
	ds_read_b128 v[40:43], v133 offset:25600
	s_waitcnt lgkmcnt(0)
	v_mfma_f32_16x16x32_bf16 v[24:27], v[32:35], v[40:43], v[24:27]
	v_mfma_f32_16x16x32_bf16 v[28:31], v[36:39], v[40:43], v[28:31]
	global_load_dwordx4 v[32:35], v[86:87], off offset:320
	global_load_dwordx4 v[36:39], v[88:89], off offset:320
	ds_read_b128 v[40:43], v133 offset:320
	s_waitcnt vmcnt(0) lgkmcnt(0)
	v_mfma_f32_16x16x32_bf16 v[0:3], v[32:35], v[40:43], v[0:3]
	v_mfma_f32_16x16x32_bf16 v[4:7], v[36:39], v[40:43], v[4:7]
	ds_read_b128 v[40:43], v133 offset:8768
	s_waitcnt lgkmcnt(0)
	v_mfma_f32_16x16x32_bf16 v[8:11], v[32:35], v[40:43], v[8:11]
	v_mfma_f32_16x16x32_bf16 v[12:15], v[36:39], v[40:43], v[12:15]
	ds_read_b128 v[40:43], v133 offset:17216
	s_waitcnt lgkmcnt(0)
	v_mfma_f32_16x16x32_bf16 v[16:19], v[32:35], v[40:43], v[16:19]
	v_mfma_f32_16x16x32_bf16 v[20:23], v[36:39], v[40:43], v[20:23]
	ds_read_b128 v[40:43], v133 offset:25664
	s_waitcnt lgkmcnt(0)
	v_mfma_f32_16x16x32_bf16 v[24:27], v[32:35], v[40:43], v[24:27]
	v_mfma_f32_16x16x32_bf16 v[28:31], v[36:39], v[40:43], v[28:31]
	global_load_dwordx4 v[32:35], v[86:87], off offset:384
	global_load_dwordx4 v[36:39], v[88:89], off offset:384
	ds_read_b128 v[40:43], v133 offset:384
	s_waitcnt vmcnt(0) lgkmcnt(0)
	v_mfma_f32_16x16x32_bf16 v[0:3], v[32:35], v[40:43], v[0:3]
	v_mfma_f32_16x16x32_bf16 v[4:7], v[36:39], v[40:43], v[4:7]
	ds_read_b128 v[40:43], v133 offset:8832
	s_waitcnt lgkmcnt(0)
	v_mfma_f32_16x16x32_bf16 v[8:11], v[32:35], v[40:43], v[8:11]
	v_mfma_f32_16x16x32_bf16 v[40:43], v[36:39], v[40:43], v[12:15]
	s_nop 2
	ds_read_b128 v[12:15], v133 offset:17280
	s_waitcnt lgkmcnt(0)
	v_mfma_f32_16x16x32_bf16 v[44:47], v[32:35], v[12:15], v[16:19]
	v_mfma_f32_16x16x32_bf16 v[20:23], v[36:39], v[12:15], v[20:23]
	ds_read_b128 v[12:15], v133 offset:25728
	s_waitcnt lgkmcnt(0)
	v_mfma_f32_16x16x32_bf16 v[52:55], v[36:39], v[12:15], v[28:31]
	s_nop 2
	global_load_dwordx4 v[28:31], v[86:87], off offset:448
	global_load_dwordx4 v[56:59], v[88:89], off offset:448
	v_mfma_f32_16x16x32_bf16 v[48:51], v[32:35], v[12:15], v[24:27]
	ds_read_b128 v[12:15], v133 offset:448
	s_waitcnt vmcnt(0) lgkmcnt(0)
	v_mfma_f32_16x16x32_bf16 v[24:27], v[28:31], v[12:15], v[0:3]
	s_nop 2
	ds_read_b128 v[0:3], v133 offset:8896
	v_mfma_f32_16x16x32_bf16 v[16:19], v[56:59], v[12:15], v[4:7]
	s_waitcnt lgkmcnt(0)
	v_mfma_f32_16x16x32_bf16 v[12:15], v[28:31], v[0:3], v[8:11]
	v_mfma_f32_16x16x32_bf16 v[8:11], v[56:59], v[0:3], v[40:43]
	ds_read_b128 v[0:3], v133 offset:17344
	s_waitcnt lgkmcnt(0)
	v_mfma_f32_16x16x32_bf16 v[36:39], v[28:31], v[0:3], v[44:47]
	v_mfma_f32_16x16x32_bf16 v[32:35], v[56:59], v[0:3], v[20:23]
	ds_read_b128 v[0:3], v133 offset:25792
	s_waitcnt lgkmcnt(0)
	v_mfma_f32_16x16x32_bf16 v[28:31], v[28:31], v[0:3], v[48:51]
	v_mfma_f32_16x16x32_bf16 v[20:23], v[56:59], v[0:3], v[52:55]
	global_load_dwordx4 v[4:7], v[90:91], off
	global_load_dwordx4 v[0:3], v[90:91], off offset:64
	s_cbranch_scc0 .LBB0_452
	s_waitcnt vmcnt(1)
	v_add_f32_e32 v36, v36, v4
	v_add_f32_e32 v37, v37, v5
	v_mul_f32_e32 v36, 0xbfb8aa3b, v36
	v_mul_f32_e32 v37, 0xbfb8aa3b, v37
	ds_read_b64 v[42:43], v125
	v_exp_f32_e32 v36, v36
	v_exp_f32_e32 v37, v37
	v_add_f32_e32 v38, v38, v6
	v_add_f32_e32 v39, v39, v7
	s_waitcnt lgkmcnt(0)
	v_lshlrev_b32_e32 v44, 16, v42
	v_pk_add_f32 v[36:37], v[36:37], 1.0 op_sel_hi:[1,0]
	v_and_b32_e32 v45, 0xffff0000, v42
	v_mul_f32_e32 v38, 0xbfb8aa3b, v38
	v_mul_f32_e32 v39, 0xbfb8aa3b, v39
	v_exp_f32_e32 v38, v38
	v_rcp_f32_e32 v37, v37
	v_exp_f32_e32 v39, v39
	v_or_b32_e32 v40, s18, v81
	v_mul_u32_u24_e32 v40, 0x1400, v40
	v_rcp_f32_e32 v36, v36
	v_pk_add_f32 v[38:39], v[38:39], 1.0 op_sel_hi:[1,0]
	v_pk_mul_f32 v[36:37], v[36:37], v[44:45]
	v_lshlrev_b32_e32 v42, 16, v43
	v_and_b32_e32 v43, 0xffff0000, v43
	v_mov_b32_e32 v41, v195
	v_rcp_f32_e32 v39, v39
	v_cvt_pk_bf16_f32 v36, v36, v37
	s_waitcnt vmcnt(0)
	v_add_f32_e32 v32, v32, v0
	v_add_f32_e32 v33, v33, v1
	v_rcp_f32_e32 v38, v38
	s_nop 0
	v_pk_mul_f32 v[38:39], v[38:39], v[42:43]
	v_mul_f32_e32 v32, 0xbfb8aa3b, v32
	v_cvt_pk_bf16_f32 v37, v38, v39
	v_lshl_add_u64 v[38:39], s[26:27], 0, v[40:41]
	v_lshl_add_u64 v[38:39], v[38:39], 0, s[74:75]
	v_lshl_add_u64 v[40:41], v[92:93], 1, v[38:39]
	global_store_dwordx2 v[40:41], v[36:37], off
	v_mul_f32_e32 v33, 0xbfb8aa3b, v33
	ds_read_b64 v[36:37], v125 offset:32
	v_exp_f32_e32 v32, v32
	v_exp_f32_e32 v33, v33
	v_add_f32_e32 v34, v34, v2
	v_add_f32_e32 v35, v35, v3
	s_waitcnt lgkmcnt(0)
	v_lshlrev_b32_e32 v40, 16, v36
	v_pk_add_f32 v[32:33], v[32:33], 1.0 op_sel_hi:[1,0]
	v_and_b32_e32 v41, 0xffff0000, v36
	v_mul_f32_e32 v34, 0xbfb8aa3b, v34
	v_mul_f32_e32 v35, 0xbfb8aa3b, v35
	v_exp_f32_e32 v34, v34
	v_rcp_f32_e32 v33, v33
	v_exp_f32_e32 v35, v35
	v_rcp_f32_e32 v32, v32
	v_pk_add_f32 v[34:35], v[34:35], 1.0 op_sel_hi:[1,0]
	v_pk_mul_f32 v[32:33], v[32:33], v[40:41]
	v_lshlrev_b32_e32 v36, 16, v37
	v_and_b32_e32 v37, 0xffff0000, v37
	v_cvt_pk_bf16_f32 v32, v32, v33
	v_rcp_f32_e32 v35, v35
	s_mov_b64 s[2:3], 0
	v_rcp_f32_e32 v34, v34
	s_nop 0
	v_pk_mul_f32 v[34:35], v[34:35], v[36:37]
	s_nop 0
	v_cvt_pk_bf16_f32 v33, v34, v35
	v_lshl_add_u64 v[34:35], v[94:95], 1, v[38:39]
	global_store_dwordx2 v[34:35], v[32:33], off
	s_nop 7
.LBB0_452:
	s_andn2_b64 vcc, exec, s[2:3]
	v_mov_b32_e32 v33, v111
	v_mov_b32_e32 v32, v119
	v_readlane_b32 s65, v255, 11
	v_readlane_b32 s64, v255, 12
	s_movk_i32 s62, 0x7fff
	s_mov_b64 s[70:71], 0x80
	s_mov_b64 s[68:69], 0xc00
	s_mov_b32 s56, s96
	s_cbranch_vccnz .LBB0_445
	s_waitcnt vmcnt(0)
	v_add_f32_e32 v24, v24, v4
	v_add_f32_e32 v25, v25, v5
	v_mul_f32_e32 v24, 0xbfb8aa3b, v24
	v_mul_f32_e32 v25, 0xbfb8aa3b, v25
	ds_read_b64 v[22:23], v123
	v_exp_f32_e32 v24, v24
	v_exp_f32_e32 v25, v25
	v_mul_u32_u24_e32 v20, 0x1400, v135
	v_mov_b32_e32 v21, v195
	s_waitcnt lgkmcnt(0)
	v_lshlrev_b32_e32 v28, 16, v22
	v_pk_add_f32 v[24:25], v[24:25], 1.0 op_sel_hi:[1,0]
	v_and_b32_e32 v29, 0xffff0000, v22
	v_lshl_add_u64 v[20:21], s[26:27], 0, v[20:21]
	v_lshl_add_u64 v[20:21], v[20:21], 0, s[74:75]
	v_add_f32_e32 v16, v16, v0
	v_rcp_f32_e32 v25, v25
	v_add_f32_e32 v17, v17, v1
	v_mul_f32_e32 v16, 0xbfb8aa3b, v16
	v_mul_f32_e32 v17, 0xbfb8aa3b, v17
	v_rcp_f32_e32 v24, v24
	v_add_f32_e32 v22, v26, v6
	v_mul_f32_e32 v22, 0xbfb8aa3b, v22
	v_exp_f32_e32 v26, v22
	v_add_f32_e32 v22, v27, v7
	v_mul_f32_e32 v22, 0xbfb8aa3b, v22
	v_exp_f32_e32 v27, v22
	v_pk_mul_f32 v[24:25], v[24:25], v[28:29]
	v_lshlrev_b32_e32 v22, 16, v23
	v_and_b32_e32 v23, 0xffff0000, v23
	v_pk_add_f32 v[26:27], v[26:27], 1.0 op_sel_hi:[1,0]
	v_cvt_pk_bf16_f32 v24, v24, v25
	v_exp_f32_e32 v16, v16
	v_exp_f32_e32 v17, v17
	v_add_f32_e32 v18, v18, v2
	v_rcp_f32_e32 v27, v27
	v_pk_add_f32 v[16:17], v[16:17], 1.0 op_sel_hi:[1,0]
	v_add_f32_e32 v19, v19, v3
	v_mul_f32_e32 v18, 0xbfb8aa3b, v18
	v_rcp_f32_e32 v26, v26
	s_nop 0
	v_pk_mul_f32 v[22:23], v[26:27], v[22:23]
	v_mul_f32_e32 v19, 0xbfb8aa3b, v19
	v_cvt_pk_bf16_f32 v25, v22, v23
	v_lshl_add_u64 v[22:23], v[92:93], 1, v[20:21]
	global_store_dwordx2 v[22:23], v[24:25], off
	ds_read_b64 v[22:23], v123 offset:32
	v_exp_f32_e32 v18, v18
	v_exp_f32_e32 v19, v19
	v_mov_b32_e32 v33, v79
	v_mov_b32_e32 v32, v117
	s_waitcnt lgkmcnt(0)
	v_lshlrev_b32_e32 v24, 16, v22
	v_and_b32_e32 v25, 0xffff0000, v22
	v_pk_add_f32 v[18:19], v[18:19], 1.0 op_sel_hi:[1,0]
	v_rcp_f32_e32 v17, v17
	v_rcp_f32_e32 v16, v16
	s_nop 0
	v_pk_mul_f32 v[16:17], v[16:17], v[24:25]
	v_lshlrev_b32_e32 v22, 16, v23
	v_and_b32_e32 v23, 0xffff0000, v23
	v_cvt_pk_bf16_f32 v16, v16, v17
	v_rcp_f32_e32 v19, v19
	v_rcp_f32_e32 v18, v18
	s_nop 0
	v_pk_mul_f32 v[18:19], v[18:19], v[22:23]
	v_mov_b64_e32 v[30:31], v[14:15]
	v_cvt_pk_bf16_f32 v17, v18, v19
	v_lshl_add_u64 v[18:19], v[94:95], 1, v[20:21]
	v_mov_b64_e32 v[22:23], v[10:11]
	v_mov_b64_e32 v[28:29], v[12:13]
	v_mov_b64_e32 v[20:21], v[8:9]
	global_store_dwordx2 v[18:19], v[16:17], off
	s_branch .LBB0_445

.LBB0_457:
	v_or_b32_e32 v51, s6, v72
	v_or_b32_e32 v51, s10, v51
	v_mad_i64_i32 v[70:71], s[2:3], v51, s86, v[40:41]
	v_add_lshl_u32 v51, s5, v72, 2
	global_load_dwordx2 v[64:65], v[70:71], off offset:96
	global_load_dwordx2 v[66:67], v[70:71], off offset:64
	global_load_dwordx2 v[68:69], v[70:71], off offset:32
	global_load_dword v62, v51, s[8:9] offset:64
	s_nop 0
	global_load_dwordx2 v[70:71], v[70:71], off
	v_or_b32_e32 v51, s5, v72
	v_or_b32_e32 v53, s10, v51
	v_mad_i64_i32 v[74:75], s[2:3], v53, s86, v[40:41]
	v_lshlrev_b32_e32 v51, 2, v51
	global_load_dwordx2 v[78:79], v[74:75], off offset:96
	global_load_dwordx2 v[80:81], v[74:75], off offset:64
	global_load_dwordx2 v[82:83], v[74:75], off offset:32
	global_load_dword v72, v51, s[8:9]
	global_load_dwordx2 v[84:85], v[74:75], off
	v_or_b32_e32 v51, s5, v49
	v_mov_b64_e32 v[74:75], s[0:1]
	v_mad_i64_i32 v[76:77], s[2:3], v51, s86, v[74:75]
	s_mov_b64 s[10:11], 0x2040600
	v_lshl_add_u64 v[76:77], v[76:77], 0, s[10:11]
	s_add_i32 s19, s19, s81
	s_waitcnt vmcnt(0) lgkmcnt(0)
	v_lshlrev_b32_e32 v90, 16, v84
	v_mul_f32_e32 v51, 0x3d372713, v90
	v_mul_f32_e32 v51, v51, v90
	v_mov_b32_e32 v53, v90
	v_fmac_f32_e32 v53, v51, v53
	v_mul_f32_e32 v51, 0x3f4c422a, v53
	v_add_f32_e32 v51, v51, v51
	v_and_b32_e32 v91, 0xffff0000, v84
	v_mul_f32_e32 v51, 0xbfb8aa3b, v51
	v_exp_f32_e32 v92, v51
	v_mul_f32_e32 v51, 0x3d372713, v91
	v_mul_f32_e32 v51, v51, v91
	v_mov_b32_e32 v53, v91
	v_fmac_f32_e32 v53, v51, v53
	v_mul_f32_e32 v51, 0x3f4c422a, v53
	v_add_f32_e32 v51, v51, v51
	v_mul_f32_e32 v51, 0xbfb8aa3b, v51
	v_exp_f32_e32 v93, v51
	s_nop 0
	v_pk_add_f32 v[92:93], v[92:93], 1.0 op_sel_hi:[1,0]
	s_nop 0
	v_rcp_f32_e32 v93, v93
	v_lshlrev_b32_e32 v84, 16, v85
	v_rcp_f32_e32 v92, v92
	v_mul_f32_e32 v51, 0x3d372713, v84
	v_mul_f32_e32 v51, v51, v84
	v_mov_b32_e32 v53, v84
	v_fmac_f32_e32 v53, v51, v53
	v_mul_f32_e32 v51, 0x3f4c422a, v53
	v_add_f32_e32 v51, v51, v51
	v_pk_mul_f32 v[90:91], v[92:93], v[90:91]
	v_pk_add_f32 v[28:29], v[28:29], v[72:73] op_sel_hi:[1,0]
	v_and_b32_e32 v85, 0xffff0000, v85
	v_mul_f32_e32 v51, 0xbfb8aa3b, v51
	v_pk_mul_f32 v[28:29], v[28:29], v[90:91]
	v_exp_f32_e32 v90, v51
	v_mul_f32_e32 v51, 0x3d372713, v85
	v_mul_f32_e32 v51, v51, v85
	v_mov_b32_e32 v53, v85
	v_fmac_f32_e32 v53, v51, v53
	v_mul_f32_e32 v51, 0x3f4c422a, v53
	v_add_f32_e32 v51, v51, v51
	v_mul_f32_e32 v51, 0xbfb8aa3b, v51
	v_exp_f32_e32 v91, v51
	v_cvt_pk_bf16_f32 v28, v28, v29
	v_pk_add_f32 v[90:91], v[90:91], 1.0 op_sel_hi:[1,0]
	s_nop 0
	v_rcp_f32_e32 v91, v91
	v_rcp_f32_e32 v90, v90
	s_nop 0
	v_pk_mul_f32 v[84:85], v[90:91], v[84:85]
	v_pk_add_f32 v[30:31], v[30:31], v[72:73] op_sel_hi:[1,0]
	s_nop 0
	v_pk_mul_f32 v[30:31], v[30:31], v[84:85]
	s_nop 0
	v_cvt_pk_bf16_f32 v29, v30, v31
	v_lshl_add_u64 v[30:31], v[76:77], 0, v[54:55]
	global_store_dwordx2 v[30:31], v[28:29], off
	v_lshlrev_b32_e32 v28, 16, v82
	v_mul_f32_e32 v30, 0x3d372713, v28
	v_mul_f32_e32 v30, v30, v28
	v_mov_b32_e32 v31, v28
	v_and_b32_e32 v29, 0xffff0000, v82
	v_fmac_f32_e32 v31, v30, v31
	v_mul_f32_e32 v30, 0x3f4c422a, v31
	v_mul_f32_e32 v31, 0x3d372713, v29
	v_mul_f32_e32 v31, v31, v29
	v_mov_b32_e32 v51, v29
	v_fmac_f32_e32 v51, v31, v51
	v_mul_f32_e32 v31, 0x3f4c422a, v51
	v_add_f32_e32 v30, v30, v30
	v_add_f32_e32 v31, v31, v31
	v_mul_f32_e32 v30, 0xbfb8aa3b, v30
	v_mul_f32_e32 v31, 0xbfb8aa3b, v31
	v_exp_f32_e32 v30, v30
	v_exp_f32_e32 v31, v31
	s_nop 0
	v_pk_add_f32 v[30:31], v[30:31], 1.0 op_sel_hi:[1,0]
	s_nop 0
	v_rcp_f32_e32 v31, v31
	v_rcp_f32_e32 v30, v30
	s_nop 0
	v_pk_mul_f32 v[28:29], v[30:31], v[28:29]
	v_pk_add_f32 v[24:25], v[24:25], v[72:73] op_sel_hi:[1,0]
	s_nop 0
	v_pk_mul_f32 v[24:25], v[24:25], v[28:29]
	v_lshlrev_b32_e32 v28, 16, v83
	v_mul_f32_e32 v30, 0x3d372713, v28
	v_mul_f32_e32 v30, v30, v28
	v_mov_b32_e32 v31, v28
	v_and_b32_e32 v29, 0xffff0000, v83
	v_fmac_f32_e32 v31, v30, v31
	v_mul_f32_e32 v30, 0x3f4c422a, v31
	v_mul_f32_e32 v31, 0x3d372713, v29
	v_mul_f32_e32 v31, v31, v29
	v_mov_b32_e32 v51, v29
	v_fmac_f32_e32 v51, v31, v51
	v_mul_f32_e32 v31, 0x3f4c422a, v51
	v_add_f32_e32 v30, v30, v30
	v_add_f32_e32 v31, v31, v31
	v_mul_f32_e32 v30, 0xbfb8aa3b, v30
	v_mul_f32_e32 v31, 0xbfb8aa3b, v31
	v_exp_f32_e32 v30, v30
	v_exp_f32_e32 v31, v31
	v_cvt_pk_bf16_f32 v24, v24, v25
	v_pk_add_f32 v[30:31], v[30:31], 1.0 op_sel_hi:[1,0]
	s_nop 0
	v_rcp_f32_e32 v31, v31
	v_rcp_f32_e32 v30, v30
	s_nop 0
	v_pk_mul_f32 v[28:29], v[30:31], v[28:29]
	v_pk_add_f32 v[26:27], v[26:27], v[72:73] op_sel_hi:[1,0]
	v_pk_add_f32 v[20:21], v[20:21], v[72:73] op_sel_hi:[1,0]
	v_pk_mul_f32 v[26:27], v[26:27], v[28:29]
	v_pk_add_f32 v[22:23], v[22:23], v[72:73] op_sel_hi:[1,0]
	v_cvt_pk_bf16_f32 v25, v26, v27
	v_lshl_add_u64 v[26:27], v[76:77], 0, v[56:57]
	global_store_dwordx2 v[26:27], v[24:25], off
	v_lshlrev_b32_e32 v24, 16, v80
	v_mul_f32_e32 v26, 0x3d372713, v24
	v_mul_f32_e32 v26, v26, v24
	v_mov_b32_e32 v27, v24
	v_and_b32_e32 v25, 0xffff0000, v80
	v_fmac_f32_e32 v27, v26, v27
	v_mul_f32_e32 v26, 0x3f4c422a, v27
	v_mul_f32_e32 v27, 0x3d372713, v25
	v_mul_f32_e32 v27, v27, v25
	v_mov_b32_e32 v28, v25
	v_fmac_f32_e32 v28, v27, v28
	v_mul_f32_e32 v27, 0x3f4c422a, v28
	v_add_f32_e32 v26, v26, v26
	v_add_f32_e32 v27, v27, v27
	v_mul_f32_e32 v26, 0xbfb8aa3b, v26
	v_mul_f32_e32 v27, 0xbfb8aa3b, v27
	v_exp_f32_e32 v26, v26
	v_exp_f32_e32 v27, v27
	v_pk_add_f32 v[16:17], v[16:17], v[72:73] op_sel_hi:[1,0]
	v_pk_add_f32 v[18:19], v[18:19], v[72:73] op_sel_hi:[1,0]
	v_pk_add_f32 v[12:13], v[12:13], v[62:63] op_sel_hi:[1,0]
	v_pk_add_f32 v[26:27], v[26:27], 1.0 op_sel_hi:[1,0]
	v_pk_add_f32 v[14:15], v[14:15], v[62:63] op_sel_hi:[1,0]
	v_pk_add_f32 v[8:9], v[62:63], v[8:9] op_sel_hi:[0,1]
	v_pk_add_f32 v[10:11], v[62:63], v[10:11] op_sel_hi:[0,1]
	v_pk_add_f32 v[4:5], v[62:63], v[4:5] op_sel_hi:[0,1]
	v_rcp_f32_e32 v27, v27
	v_pk_add_f32 v[6:7], v[62:63], v[6:7] op_sel_hi:[0,1]
	v_pk_add_f32 v[0:1], v[62:63], v[0:1] op_sel_hi:[0,1]
	v_pk_add_f32 v[2:3], v[62:63], v[2:3] op_sel_hi:[0,1]
	v_rcp_f32_e32 v26, v26
	s_nop 0
	v_pk_mul_f32 v[24:25], v[26:27], v[24:25]
	s_nop 0
	v_pk_mul_f32 v[20:21], v[20:21], v[24:25]
	v_lshlrev_b32_e32 v24, 16, v81
	v_mul_f32_e32 v26, 0x3d372713, v24
	v_mul_f32_e32 v26, v26, v24
	v_mov_b32_e32 v27, v24
	v_and_b32_e32 v25, 0xffff0000, v81
	v_fmac_f32_e32 v27, v26, v27
	v_mul_f32_e32 v26, 0x3f4c422a, v27
	v_mul_f32_e32 v27, 0x3d372713, v25
	v_mul_f32_e32 v27, v27, v25
	v_mov_b32_e32 v28, v25
	v_fmac_f32_e32 v28, v27, v28
	v_mul_f32_e32 v27, 0x3f4c422a, v28
	v_add_f32_e32 v26, v26, v26
	v_add_f32_e32 v27, v27, v27
	v_mul_f32_e32 v26, 0xbfb8aa3b, v26
	v_mul_f32_e32 v27, 0xbfb8aa3b, v27
	v_exp_f32_e32 v26, v26
	v_exp_f32_e32 v27, v27
	v_cvt_pk_bf16_f32 v20, v20, v21
	v_pk_add_f32 v[26:27], v[26:27], 1.0 op_sel_hi:[1,0]
	s_nop 0
	v_rcp_f32_e32 v27, v27
	v_rcp_f32_e32 v26, v26
	s_nop 0
	v_pk_mul_f32 v[24:25], v[26:27], v[24:25]
	s_nop 0
	v_pk_mul_f32 v[22:23], v[22:23], v[24:25]
	s_nop 0
	v_cvt_pk_bf16_f32 v21, v22, v23
	v_lshl_add_u64 v[22:23], v[76:77], 0, v[58:59]
	global_store_dwordx2 v[22:23], v[20:21], off
	v_lshlrev_b32_e32 v20, 16, v78
	v_mul_f32_e32 v22, 0x3d372713, v20
	v_mul_f32_e32 v22, v22, v20
	v_mov_b32_e32 v23, v20
	v_and_b32_e32 v21, 0xffff0000, v78
	v_fmac_f32_e32 v23, v22, v23
	v_mul_f32_e32 v22, 0x3f4c422a, v23
	v_mul_f32_e32 v23, 0x3d372713, v21
	v_mul_f32_e32 v23, v23, v21
	v_mov_b32_e32 v24, v21
	v_fmac_f32_e32 v24, v23, v24
	v_mul_f32_e32 v23, 0x3f4c422a, v24
	v_add_f32_e32 v22, v22, v22
	v_add_f32_e32 v23, v23, v23
	v_mul_f32_e32 v22, 0xbfb8aa3b, v22
	v_mul_f32_e32 v23, 0xbfb8aa3b, v23
	v_exp_f32_e32 v22, v22
	v_exp_f32_e32 v23, v23
	s_nop 0
	v_pk_add_f32 v[22:23], v[22:23], 1.0 op_sel_hi:[1,0]
	s_nop 0
	v_rcp_f32_e32 v23, v23
	v_rcp_f32_e32 v22, v22
	s_nop 0
	v_pk_mul_f32 v[20:21], v[22:23], v[20:21]
	s_nop 0
	v_pk_mul_f32 v[16:17], v[16:17], v[20:21]
	v_lshlrev_b32_e32 v20, 16, v79
	v_mul_f32_e32 v22, 0x3d372713, v20
	v_mul_f32_e32 v22, v22, v20
	v_mov_b32_e32 v23, v20
	v_and_b32_e32 v21, 0xffff0000, v79
	v_fmac_f32_e32 v23, v22, v23
	v_mul_f32_e32 v22, 0x3f4c422a, v23
	v_mul_f32_e32 v23, 0x3d372713, v21
	v_mul_f32_e32 v23, v23, v21
	v_mov_b32_e32 v24, v21
	v_fmac_f32_e32 v24, v23, v24
	v_mul_f32_e32 v23, 0x3f4c422a, v24
	v_add_f32_e32 v22, v22, v22
	v_add_f32_e32 v23, v23, v23
	v_mul_f32_e32 v22, 0xbfb8aa3b, v22
	v_mul_f32_e32 v23, 0xbfb8aa3b, v23
	v_exp_f32_e32 v22, v22
	v_exp_f32_e32 v23, v23
	v_cvt_pk_bf16_f32 v16, v16, v17
	v_pk_add_f32 v[22:23], v[22:23], 1.0 op_sel_hi:[1,0]
	s_nop 0
	v_rcp_f32_e32 v23, v23
	v_rcp_f32_e32 v22, v22
	s_nop 0
	v_pk_mul_f32 v[20:21], v[22:23], v[20:21]
	s_nop 0
	v_pk_mul_f32 v[18:19], v[18:19], v[20:21]
	s_nop 0
	v_cvt_pk_bf16_f32 v17, v18, v19
	v_lshl_add_u64 v[18:19], v[76:77], 0, v[60:61]
	global_store_dwordx2 v[18:19], v[16:17], off
	v_lshlrev_b32_e32 v18, 16, v70
	v_mul_f32_e32 v20, 0x3d372713, v18
	v_mul_f32_e32 v20, v20, v18
	v_mov_b32_e32 v21, v18
	v_and_b32_e32 v19, 0xffff0000, v70
	v_fmac_f32_e32 v21, v20, v21
	v_mul_f32_e32 v20, 0x3f4c422a, v21
	v_mul_f32_e32 v21, 0x3d372713, v19
	v_mul_f32_e32 v21, v21, v19
	v_mov_b32_e32 v22, v19
	v_fmac_f32_e32 v22, v21, v22
	v_mul_f32_e32 v21, 0x3f4c422a, v22
	v_add_f32_e32 v20, v20, v20
	v_add_f32_e32 v21, v21, v21
	v_mul_f32_e32 v20, 0xbfb8aa3b, v20
	v_mul_f32_e32 v21, 0xbfb8aa3b, v21
	v_exp_f32_e32 v20, v20
	v_exp_f32_e32 v21, v21
	v_or_b32_e32 v16, s6, v49
	v_mad_i64_i32 v[16:17], s[2:3], v16, s86, v[74:75]
	v_pk_add_f32 v[20:21], v[20:21], 1.0 op_sel_hi:[1,0]
	v_lshl_add_u64 v[16:17], v[16:17], 0, s[10:11]
	v_rcp_f32_e32 v21, v21
	v_rcp_f32_e32 v20, v20
	s_nop 0
	v_pk_mul_f32 v[18:19], v[20:21], v[18:19]
	s_nop 0
	v_pk_mul_f32 v[12:13], v[12:13], v[18:19]
	v_lshlrev_b32_e32 v18, 16, v71
	v_mul_f32_e32 v20, 0x3d372713, v18
	v_mul_f32_e32 v20, v20, v18
	v_mov_b32_e32 v21, v18
	v_and_b32_e32 v19, 0xffff0000, v71
	v_fmac_f32_e32 v21, v20, v21
	v_mul_f32_e32 v20, 0x3f4c422a, v21
	v_mul_f32_e32 v21, 0x3d372713, v19
	v_mul_f32_e32 v21, v21, v19
	v_mov_b32_e32 v22, v19
	v_fmac_f32_e32 v22, v21, v22
	v_mul_f32_e32 v21, 0x3f4c422a, v22
	v_add_f32_e32 v20, v20, v20
	v_add_f32_e32 v21, v21, v21
	v_mul_f32_e32 v20, 0xbfb8aa3b, v20
	v_mul_f32_e32 v21, 0xbfb8aa3b, v21
	v_exp_f32_e32 v20, v20
	v_exp_f32_e32 v21, v21
	v_cvt_pk_bf16_f32 v12, v12, v13
	v_pk_add_f32 v[20:21], v[20:21], 1.0 op_sel_hi:[1,0]
	s_nop 0
	v_rcp_f32_e32 v21, v21
	v_rcp_f32_e32 v20, v20
	s_nop 0
	v_pk_mul_f32 v[18:19], v[20:21], v[18:19]
	s_nop 0
	v_pk_mul_f32 v[14:15], v[14:15], v[18:19]
	s_nop 0
	v_cvt_pk_bf16_f32 v13, v14, v15
	v_lshl_add_u64 v[14:15], v[16:17], 0, v[54:55]
	global_store_dwordx2 v[14:15], v[12:13], off
	v_lshlrev_b32_e32 v12, 16, v68
	v_mul_f32_e32 v14, 0x3d372713, v12
	v_mul_f32_e32 v14, v14, v12
	v_mov_b32_e32 v15, v12
	v_and_b32_e32 v13, 0xffff0000, v68
	v_fmac_f32_e32 v15, v14, v15
	v_mul_f32_e32 v14, 0x3f4c422a, v15
	v_mul_f32_e32 v15, 0x3d372713, v13
	v_mul_f32_e32 v15, v15, v13
	v_mov_b32_e32 v18, v13
	v_fmac_f32_e32 v18, v15, v18
	v_mul_f32_e32 v15, 0x3f4c422a, v18
	v_add_f32_e32 v14, v14, v14
	v_add_f32_e32 v15, v15, v15
	v_mul_f32_e32 v14, 0xbfb8aa3b, v14
	v_mul_f32_e32 v15, 0xbfb8aa3b, v15
	v_exp_f32_e32 v14, v14
	v_exp_f32_e32 v15, v15
	s_nop 0
	v_pk_add_f32 v[14:15], v[14:15], 1.0 op_sel_hi:[1,0]
	s_nop 0
	v_rcp_f32_e32 v15, v15
	v_rcp_f32_e32 v14, v14
	s_nop 0
	v_pk_mul_f32 v[12:13], v[14:15], v[12:13]
	s_nop 0
	v_pk_mul_f32 v[8:9], v[8:9], v[12:13]
	v_lshlrev_b32_e32 v12, 16, v69
	v_mul_f32_e32 v14, 0x3d372713, v12
	v_mul_f32_e32 v14, v14, v12
	v_mov_b32_e32 v15, v12
	v_and_b32_e32 v13, 0xffff0000, v69
	v_fmac_f32_e32 v15, v14, v15
	v_mul_f32_e32 v14, 0x3f4c422a, v15
	v_mul_f32_e32 v15, 0x3d372713, v13
	v_mul_f32_e32 v15, v15, v13
	v_mov_b32_e32 v18, v13
	v_fmac_f32_e32 v18, v15, v18
	v_mul_f32_e32 v15, 0x3f4c422a, v18
	v_add_f32_e32 v14, v14, v14
	v_add_f32_e32 v15, v15, v15
	v_mul_f32_e32 v14, 0xbfb8aa3b, v14
	v_mul_f32_e32 v15, 0xbfb8aa3b, v15
	v_exp_f32_e32 v14, v14
	v_exp_f32_e32 v15, v15
	v_cvt_pk_bf16_f32 v8, v8, v9
	v_pk_add_f32 v[14:15], v[14:15], 1.0 op_sel_hi:[1,0]
	s_nop 0
	v_rcp_f32_e32 v15, v15
	v_rcp_f32_e32 v14, v14
	s_nop 0
	v_pk_mul_f32 v[12:13], v[14:15], v[12:13]
	s_nop 0
	v_pk_mul_f32 v[10:11], v[10:11], v[12:13]
	s_nop 0
	v_cvt_pk_bf16_f32 v9, v10, v11
	v_lshl_add_u64 v[10:11], v[16:17], 0, v[56:57]
	global_store_dwordx2 v[10:11], v[8:9], off
	v_lshlrev_b32_e32 v8, 16, v66
	v_mul_f32_e32 v10, 0x3d372713, v8
	v_mul_f32_e32 v10, v10, v8
	v_mov_b32_e32 v11, v8
	v_and_b32_e32 v9, 0xffff0000, v66
	v_fmac_f32_e32 v11, v10, v11
	v_mul_f32_e32 v10, 0x3f4c422a, v11
	v_mul_f32_e32 v11, 0x3d372713, v9
	v_mul_f32_e32 v11, v11, v9
	v_mov_b32_e32 v12, v9
	v_fmac_f32_e32 v12, v11, v12
	v_mul_f32_e32 v11, 0x3f4c422a, v12
	v_add_f32_e32 v10, v10, v10
	v_add_f32_e32 v11, v11, v11
	v_mul_f32_e32 v10, 0xbfb8aa3b, v10
	v_mul_f32_e32 v11, 0xbfb8aa3b, v11
	v_exp_f32_e32 v10, v10
	v_exp_f32_e32 v11, v11
	s_nop 0
	v_pk_add_f32 v[10:11], v[10:11], 1.0 op_sel_hi:[1,0]
	s_nop 0
	v_rcp_f32_e32 v11, v11
	v_rcp_f32_e32 v10, v10
	s_nop 0
	v_pk_mul_f32 v[8:9], v[10:11], v[8:9]
	s_nop 0
	v_pk_mul_f32 v[4:5], v[4:5], v[8:9]
	v_lshlrev_b32_e32 v8, 16, v67
	v_mul_f32_e32 v10, 0x3d372713, v8
	v_mul_f32_e32 v10, v10, v8
	v_mov_b32_e32 v11, v8
	v_and_b32_e32 v9, 0xffff0000, v67
	v_fmac_f32_e32 v11, v10, v11
	v_mul_f32_e32 v10, 0x3f4c422a, v11
	v_mul_f32_e32 v11, 0x3d372713, v9
	v_mul_f32_e32 v11, v11, v9
	v_mov_b32_e32 v12, v9
	v_fmac_f32_e32 v12, v11, v12
	v_mul_f32_e32 v11, 0x3f4c422a, v12
	v_add_f32_e32 v10, v10, v10
	v_add_f32_e32 v11, v11, v11
	v_mul_f32_e32 v10, 0xbfb8aa3b, v10
	v_mul_f32_e32 v11, 0xbfb8aa3b, v11
	v_exp_f32_e32 v10, v10
	v_exp_f32_e32 v11, v11
	v_cvt_pk_bf16_f32 v4, v4, v5
	v_pk_add_f32 v[10:11], v[10:11], 1.0 op_sel_hi:[1,0]
	s_nop 0
	v_rcp_f32_e32 v11, v11
	v_rcp_f32_e32 v10, v10
	s_nop 0
	v_pk_mul_f32 v[8:9], v[10:11], v[8:9]
	s_nop 0
	v_pk_mul_f32 v[6:7], v[6:7], v[8:9]
	s_nop 0
	v_cvt_pk_bf16_f32 v5, v6, v7
	v_lshl_add_u64 v[6:7], v[16:17], 0, v[58:59]
	global_store_dwordx2 v[6:7], v[4:5], off
	v_lshlrev_b32_e32 v4, 16, v64
	v_mul_f32_e32 v6, 0x3d372713, v4
	v_mul_f32_e32 v6, v6, v4
	v_mov_b32_e32 v7, v4
	v_and_b32_e32 v5, 0xffff0000, v64
	v_fmac_f32_e32 v7, v6, v7
	v_mul_f32_e32 v6, 0x3f4c422a, v7
	v_mul_f32_e32 v7, 0x3d372713, v5
	v_mul_f32_e32 v7, v7, v5
	v_mov_b32_e32 v8, v5
	v_fmac_f32_e32 v8, v7, v8
	v_mul_f32_e32 v7, 0x3f4c422a, v8
	v_add_f32_e32 v6, v6, v6
	v_add_f32_e32 v7, v7, v7
	v_mul_f32_e32 v6, 0xbfb8aa3b, v6
	v_mul_f32_e32 v7, 0xbfb8aa3b, v7
	v_exp_f32_e32 v6, v6
	v_exp_f32_e32 v7, v7
	s_nop 0
	v_pk_add_f32 v[6:7], v[6:7], 1.0 op_sel_hi:[1,0]
	s_nop 0
	v_rcp_f32_e32 v7, v7
	v_rcp_f32_e32 v6, v6
	s_nop 0
	v_pk_mul_f32 v[4:5], v[6:7], v[4:5]
	s_nop 0
	v_pk_mul_f32 v[0:1], v[0:1], v[4:5]
	v_lshlrev_b32_e32 v4, 16, v65
	v_mul_f32_e32 v6, 0x3d372713, v4
	v_mul_f32_e32 v6, v6, v4
	v_mov_b32_e32 v7, v4
	v_and_b32_e32 v5, 0xffff0000, v65
	v_fmac_f32_e32 v7, v6, v7
	v_mul_f32_e32 v6, 0x3f4c422a, v7
	v_mul_f32_e32 v7, 0x3d372713, v5
	v_mul_f32_e32 v7, v7, v5
	v_mov_b32_e32 v8, v5
	v_fmac_f32_e32 v8, v7, v8
	v_mul_f32_e32 v7, 0x3f4c422a, v8
	v_add_f32_e32 v6, v6, v6
	v_add_f32_e32 v7, v7, v7
	v_mul_f32_e32 v6, 0xbfb8aa3b, v6
	v_mul_f32_e32 v7, 0xbfb8aa3b, v7
	v_exp_f32_e32 v6, v6
	v_exp_f32_e32 v7, v7
	v_cvt_pk_bf16_f32 v0, v0, v1
	v_pk_add_f32 v[6:7], v[6:7], 1.0 op_sel_hi:[1,0]
	s_nop 0
	v_rcp_f32_e32 v7, v7
	v_readlane_b32 s2, v254, 6
	s_add_i32 s18, s18, s2
	s_cmpk_gt_i32 s19, 0xff
	v_rcp_f32_e32 v6, v6
	s_nop 0
	v_pk_mul_f32 v[4:5], v[6:7], v[4:5]
	s_nop 0
	v_pk_mul_f32 v[2:3], v[2:3], v[4:5]
	s_nop 0
	v_cvt_pk_bf16_f32 v1, v2, v3
	v_lshl_add_u64 v[2:3], v[16:17], 0, v[60:61]
	global_store_dwordx2 v[2:3], v[0:1], off
	s_waitcnt lgkmcnt(0)
	s_barrier
	s_cbranch_scc1 .LBB0_465

.LBB0_460:
	s_add_i32 s24, s3, s21
	s_mul_i32 s25, s24, 0x1400
	s_add_i32 s22, s24, 0x58
	s_add_i32 s23, s25, 0x6e000
	s_mul_hi_i32 s22, s22, 0x1400
	s_add_u32 s23, s0, s23
	s_addc_u32 s26, s1, s22
	s_add_u32 s22, s23, 0x2040200
	s_addc_u32 s23, s26, 0
	v_mov_b32_e32 v49, v195
	v_mov_b32_e32 v51, v195
	v_mov_b32_e32 v53, v195
	v_lshl_add_u64 v[24:25], s[22:23], 0, v[194:195]
	v_lshl_add_u64 v[64:65], s[22:23], 0, v[48:49]
	v_lshl_add_u64 v[66:67], s[22:23], 0, v[50:51]
	v_lshl_add_u64 v[68:69], s[22:23], 0, v[52:53]
	s_add_i32 s22, s24, 0x60
	s_add_i32 s23, s25, 0x78000
	s_mul_hi_i32 s22, s22, 0x1400
	s_add_u32 s23, s0, s23
	s_addc_u32 s26, s1, s22
	s_add_u32 s22, s23, 0x2040200
	s_addc_u32 s23, s26, 0
	v_lshl_add_u64 v[26:27], s[22:23], 0, v[194:195]
	v_lshl_add_u64 v[28:29], s[22:23], 0, v[48:49]
	v_lshl_add_u64 v[30:31], s[22:23], 0, v[50:51]
	v_lshl_add_u64 v[62:63], s[22:23], 0, v[52:53]
	s_add_i32 s22, s24, 0x68
	s_add_i32 s23, s25, 0x82000
	s_mul_hi_i32 s22, s22, 0x1400
	s_add_u32 s23, s0, s23
	s_addc_u32 s26, s1, s22
	s_add_u32 s22, s23, 0x2040200
	s_addc_u32 s23, s26, 0
	v_lshl_add_u64 v[16:17], s[22:23], 0, v[194:195]
	v_lshl_add_u64 v[18:19], s[22:23], 0, v[48:49]
	v_lshl_add_u64 v[20:21], s[22:23], 0, v[50:51]
	v_lshl_add_u64 v[22:23], s[22:23], 0, v[52:53]
	s_add_i32 s22, s24, 0x70
	s_add_i32 s23, s25, 0x8c000
	s_mul_hi_i32 s22, s22, 0x1400
	s_add_u32 s23, s0, s23
	s_addc_u32 s26, s1, s22
	s_add_u32 s22, s23, 0x2040200
	s_addc_u32 s23, s26, 0
	s_addk_i32 s24, 0x78
	s_add_i32 s25, s25, 0x96000
	v_lshl_add_u64 v[0:1], s[22:23], 0, v[194:195]
	v_lshl_add_u64 v[2:3], s[22:23], 0, v[48:49]
	v_lshl_add_u64 v[4:5], s[22:23], 0, v[50:51]
	v_lshl_add_u64 v[6:7], s[22:23], 0, v[52:53]
	s_mul_hi_i32 s22, s24, 0x1400
	s_add_u32 s23, s0, s25
	v_lshl_add_u64 v[74:75], s[14:15], 0, v[46:47]
	s_addc_u32 s24, s1, s22
	s_add_u32 s22, s23, 0x2040200
	v_add_co_u32_e32 v76, vcc, s31, v74
	s_addc_u32 s23, s24, 0
	s_nop 0
	v_addc_co_u32_e32 v77, vcc, 0, v75, vcc
	v_lshl_add_u64 v[10:11], s[22:23], 0, v[48:49]
	v_lshl_add_u64 v[12:13], s[22:23], 0, v[50:51]
	global_load_ushort v49, v[76:77], off offset:512
	global_load_ushort v51, v[76:77], off offset:640
	v_lshl_add_u64 v[8:9], s[22:23], 0, v[194:195]
	v_lshl_add_u64 v[14:15], s[22:23], 0, v[52:53]
	v_lshl_add_u64 v[72:73], s[12:13], 0, v[46:47]
	v_lshl_add_u64 v[70:71], s[10:11], 0, v[46:47]
	s_add_i32 s21, s21, 64
	s_add_u32 s10, s10, 0x50000
	s_addc_u32 s11, s11, 0
	s_add_u32 s12, s12, 0x50000
	s_addc_u32 s13, s13, 0
	s_add_u32 s14, s14, 0x50000
	s_addc_u32 s15, s15, 0
	s_cmp_ge_i32 s21, s2
	s_waitcnt vmcnt(0) lgkmcnt(0)
	v_lshlrev_b32_e32 v74, 16, v49
	v_mul_f32_e32 v49, 0x3d372713, v74
	v_lshlrev_b32_e32 v75, 16, v51
	v_mul_f32_e32 v49, v49, v74
	v_mov_b32_e32 v51, v74
	v_fmac_f32_e32 v51, v49, v51
	v_mul_f32_e32 v49, 0x3f4c422a, v51
	v_add_f32_e32 v49, v49, v49
	v_mul_f32_e32 v49, 0xbfb8aa3b, v49
	v_exp_f32_e32 v78, v49
	v_mul_f32_e32 v49, 0x3d372713, v75
	v_mul_f32_e32 v49, v49, v75
	v_mov_b32_e32 v51, v75
	v_fmac_f32_e32 v51, v49, v51
	v_mul_f32_e32 v49, 0x3f4c422a, v51
	v_add_f32_e32 v49, v49, v49
	v_mul_f32_e32 v49, 0xbfb8aa3b, v49
	v_exp_f32_e32 v79, v49
	s_nop 0
	v_pk_add_f32 v[78:79], v[78:79], 1.0 op_sel_hi:[1,0]
	s_nop 0
	v_rcp_f32_e32 v79, v79
	global_load_ushort v51, v[76:77], off offset:768
	global_load_ushort v53, v[76:77], off offset:896
	v_rcp_f32_e32 v78, v78
	s_nop 0
	v_pk_mul_f32 v[74:75], v[78:79], v[74:75]
	s_waitcnt vmcnt(0) lgkmcnt(0)
	v_lshlrev_b32_e32 v76, 16, v51
	v_mul_f32_e32 v51, 0x3d372713, v76
	v_lshlrev_b32_e32 v77, 16, v53
	v_mul_f32_e32 v51, v51, v76
	v_mov_b32_e32 v53, v76
	v_fmac_f32_e32 v53, v51, v53
	v_mul_f32_e32 v51, 0x3f4c422a, v53
	v_add_f32_e32 v51, v51, v51
	v_mul_f32_e32 v51, 0xbfb8aa3b, v51
	v_exp_f32_e32 v94, v51
	v_mul_f32_e32 v51, 0x3d372713, v77
	v_mul_f32_e32 v51, v51, v77
	v_mov_b32_e32 v53, v77
	v_fmac_f32_e32 v53, v51, v53
	v_mul_f32_e32 v51, 0x3f4c422a, v53
	v_add_f32_e32 v51, v51, v51
	v_mul_f32_e32 v51, 0xbfb8aa3b, v51
	v_exp_f32_e32 v95, v51
	v_add_f32_e32 v49, 0, v74
	v_add_f32_e32 v49, v49, v75
	v_pk_mul_f32 v[78:79], v[74:75], v[74:75]
	v_pk_add_f32 v[94:95], v[94:95], 1.0 op_sel_hi:[1,0]
	s_nop 0
	v_rcp_f32_e32 v95, v95
	v_rcp_f32_e32 v94, v94
	s_nop 0
	v_pk_mul_f32 v[76:77], v[94:95], v[76:77]
	v_add_f32_e32 v51, v78, v79
	v_add_f32_e32 v49, v49, v76
	v_add_f32_e32 v49, v49, v77
	v_pk_mul_f32 v[94:95], v[76:77], v[76:77]
	s_nop 0
	v_add_f32_dpp v49, v49, v49 quad_perm:[1,0,3,2] row_mask:0xf bank_mask:0xf bound_ctrl:1
	v_add_f32_e32 v51, v51, v94
	v_add_f32_e32 v51, v51, v95
	v_add_f32_dpp v49, v49, v49 quad_perm:[2,3,0,1] row_mask:0xf bank_mask:0xf bound_ctrl:1
	s_nop 1
	v_add_f32_dpp v49, v49, v49 row_half_mirror row_mask:0xf bank_mask:0xf bound_ctrl:1
	s_nop 1
	v_add_f32_dpp v49, v49, v49 row_mirror row_mask:0xf bank_mask:0xf bound_ctrl:1
	s_nop 0
	v_readlane_b32 s23, v49, 0
	v_readlane_b32 s26, v49, 16
	v_readlane_b32 s25, v49, 32
	v_readlane_b32 s27, v49, 48
	v_add_f32_dpp v49, v51, v51 quad_perm:[1,0,3,2] row_mask:0xf bank_mask:0xf bound_ctrl:1
	v_mov_b32_e32 v79, s26
	v_mov_b32_e32 v95, s27
	v_add_f32_dpp v49, v49, v49 quad_perm:[2,3,0,1] row_mask:0xf bank_mask:0xf bound_ctrl:1
	s_nop 1
	v_add_f32_dpp v49, v49, v49 row_half_mirror row_mask:0xf bank_mask:0xf bound_ctrl:1
	s_nop 1
	v_add_f32_dpp v49, v49, v49 row_mirror row_mask:0xf bank_mask:0xf bound_ctrl:1
	s_nop 0
	v_readlane_b32 s28, v49, 16
	v_readlane_b32 s29, v49, 48
	v_readlane_b32 s22, v49, 0
	v_readlane_b32 s24, v49, 32
	v_mov_b32_e32 v78, s28
	v_mov_b32_e32 v94, s29
	v_pk_add_f32 v[78:79], s[22:23], v[78:79]
	v_pk_add_f32 v[94:95], s[24:25], v[94:95]
	s_nop 0
	v_pk_add_f32 v[78:79], v[78:79], v[94:95]
	s_nop 0
	v_pk_mul_f32 v[78:79], v[78:79], s[34:35] op_sel_hi:[1,0]
	s_nop 0
	v_fma_f32 v49, -v79, v79, v78
	v_max_f32_e32 v49, 0, v49
	v_add_f32_e32 v49, 0x3727c5ac, v49
	v_cmp_gt_f32_e32 vcc, s30, v49
	v_mul_f32_e32 v51, 0x4b800000, v49
	s_nop 0
	v_cndmask_b32_e32 v49, v49, v51, vcc
	v_rsq_f32_e32 v49, v49
	s_nop 0
	v_mul_f32_e32 v51, 0x45800000, v49
	v_cndmask_b32_e32 v49, v49, v51, vcc
	v_add_co_u32_e32 v72, vcc, s31, v72
	v_sub_f32_e32 v51, v74, v79
	s_nop 0
	v_addc_co_u32_e32 v73, vcc, 0, v73, vcc
	global_load_ushort v74, v[72:73], off offset:512
	global_load_ushort v78, v[72:73], off offset:640
	global_load_ushort v93, v[72:73], off offset:768
	s_nop 0
	global_load_ushort v72, v[72:73], off offset:896
	v_add_co_u32_e32 v70, vcc, s31, v70
	v_mul_f32_e32 v51, v51, v49
	s_nop 0
	v_addc_co_u32_e32 v71, vcc, 0, v71, vcc
	global_load_ushort v73, v[70:71], off offset:512
	global_load_ushort v94, v[70:71], off offset:640
	global_load_ushort v95, v[70:71], off offset:768
	s_nop 0
	global_load_ushort v70, v[70:71], off offset:896
	s_nop 0
	global_load_ushort v71, v[24:25], off
	global_load_ushort v96, v[64:65], off
	s_nop 0
	global_load_ushort v64, v[66:67], off
	global_load_ushort v65, v[68:69], off
	global_load_ushort v53, v[26:27], off
	s_nop 0
	global_load_ushort v28, v[28:29], off
	s_nop 0
	global_load_ushort v26, v[30:31], off
	global_load_ushort v27, v[62:63], off
	global_load_ushort v24, v[16:17], off
	global_load_ushort v25, v[18:19], off
	s_nop 0
	global_load_ushort v18, v[20:21], off
	global_load_ushort v19, v[22:23], off
	global_load_ushort v16, v[0:1], off
	global_load_ushort v17, v[2:3], off
	s_nop 0
	global_load_ushort v4, v[4:5], off
	s_nop 0
	global_load_ushort v5, v[6:7], off
	global_load_ushort v2, v[8:9], off
	global_load_ushort v3, v[10:11], off
	global_load_ushort v0, v[12:13], off
	global_load_ushort v1, v[14:15], off
	v_sub_f32_e32 v6, v75, v79
	v_mul_f32_e32 v6, v6, v49
	v_fma_f32 v6, v81, v6, v85
	v_cvt_pk_bf16_f32 v6, v6, s0
	ds_write_b16 v92, v6 offset:16896
	v_sub_f32_e32 v6, v76, v79
	v_mul_f32_e32 v6, v6, v49
	v_fma_f32 v6, v82, v6, v90
	v_cvt_pk_bf16_f32 v6, v6, s0
	ds_write_b16 v92, v6 offset:33792
	v_sub_f32_e32 v6, v77, v79
	v_mul_f32_e32 v6, v6, v49
	v_fma_f32 v6, v83, v6, v91
	v_cvt_pk_bf16_f32 v6, v6, s0
	ds_write_b16 v92, v6 offset:50688
	v_fma_f32 v51, v80, v51, v84
	v_cvt_pk_bf16_f32 v51, v51, s0
	ds_write_b16 v92, v51
	s_waitcnt vmcnt(0) lgkmcnt(0)
	v_lshlrev_b32_e32 v6, 16, v74
	v_mul_f32_e32 v8, 0x3d372713, v6
	v_mul_f32_e32 v8, v8, v6
	v_mov_b32_e32 v9, v6
	v_lshlrev_b32_e32 v7, 16, v78
	v_fmac_f32_e32 v9, v8, v9
	v_mul_f32_e32 v8, 0x3f4c422a, v9
	v_mul_f32_e32 v9, 0x3d372713, v7
	v_mul_f32_e32 v9, v9, v7
	v_mov_b32_e32 v10, v7
	v_fmac_f32_e32 v10, v9, v10
	v_mul_f32_e32 v9, 0x3f4c422a, v10
	v_add_f32_e32 v8, v8, v8
	v_add_f32_e32 v9, v9, v9
	v_mul_f32_e32 v8, 0xbfb8aa3b, v8
	v_mul_f32_e32 v9, 0xbfb8aa3b, v9
	v_exp_f32_e32 v8, v8
	v_exp_f32_e32 v9, v9
	v_lshlrev_b32_e32 v4, 16, v4
	v_lshlrev_b32_e32 v5, 16, v5
	v_lshlrev_b32_e32 v2, 16, v2
	v_pk_add_f32 v[8:9], v[8:9], 1.0 op_sel_hi:[1,0]
	v_lshlrev_b32_e32 v3, 16, v3
	v_lshlrev_b32_e32 v0, 16, v0
	v_lshlrev_b32_e32 v1, 16, v1
	v_rcp_f32_e32 v9, v9
	v_rcp_f32_e32 v8, v8
	v_lshlrev_b32_e32 v10, 16, v93
	v_mul_f32_e32 v12, 0x3d372713, v10
	v_mul_f32_e32 v12, v12, v10
	v_mov_b32_e32 v13, v10
	v_lshlrev_b32_e32 v11, 16, v72
	v_fmac_f32_e32 v13, v12, v13
	v_mul_f32_e32 v12, 0x3f4c422a, v13
	v_mul_f32_e32 v13, 0x3d372713, v11
	v_mul_f32_e32 v13, v13, v11
	v_mov_b32_e32 v15, v11
	v_fmac_f32_e32 v15, v13, v15
	v_mul_f32_e32 v13, 0x3f4c422a, v15
	v_add_f32_e32 v12, v12, v12
	v_add_f32_e32 v13, v13, v13
	v_mul_f32_e32 v12, 0xbfb8aa3b, v12
	v_mul_f32_e32 v13, 0xbfb8aa3b, v13
	v_exp_f32_e32 v12, v12
	v_exp_f32_e32 v13, v13
	v_pk_mul_f32 v[6:7], v[8:9], v[6:7]
	v_pk_add_f32 v[12:13], v[12:13], 1.0 op_sel_hi:[1,0]
	s_nop 0
	v_add_f32_e32 v8, 0, v6
	v_add_f32_e32 v14, v8, v7
	v_pk_mul_f32 v[8:9], v[6:7], v[6:7]
	v_rcp_f32_e32 v13, v13
	v_add_f32_e32 v8, v8, v9
	v_rcp_f32_e32 v12, v12
	s_nop 0
	v_pk_mul_f32 v[10:11], v[12:13], v[10:11]
	s_nop 0
	v_add_f32_e32 v12, v14, v10
	v_add_f32_e32 v14, v12, v11
	v_pk_mul_f32 v[12:13], v[10:11], v[10:11]
	s_nop 0
	v_add_f32_e32 v8, v8, v12
	v_add_f32_e32 v8, v8, v13
	v_add_f32_dpp v9, v14, v14 quad_perm:[1,0,3,2] row_mask:0xf bank_mask:0xf bound_ctrl:1
	s_nop 0
	v_add_f32_dpp v8, v8, v8 quad_perm:[1,0,3,2] row_mask:0xf bank_mask:0xf bound_ctrl:1
	v_add_f32_dpp v9, v9, v9 quad_perm:[2,3,0,1] row_mask:0xf bank_mask:0xf bound_ctrl:1
	s_nop 0
	v_add_f32_dpp v8, v8, v8 quad_perm:[2,3,0,1] row_mask:0xf bank_mask:0xf bound_ctrl:1
	v_add_f32_dpp v9, v9, v9 row_half_mirror row_mask:0xf bank_mask:0xf bound_ctrl:1
	s_nop 0
	v_add_f32_dpp v8, v8, v8 row_half_mirror row_mask:0xf bank_mask:0xf bound_ctrl:1
	v_add_f32_dpp v9, v9, v9 row_mirror row_mask:0xf bank_mask:0xf bound_ctrl:1
	s_nop 0
	v_add_f32_dpp v8, v8, v8 row_mirror row_mask:0xf bank_mask:0xf bound_ctrl:1
	v_readlane_b32 s26, v9, 16
	v_readlane_b32 s27, v9, 48
	v_readlane_b32 s28, v8, 16
	v_readlane_b32 s29, v8, 48
	v_readlane_b32 s23, v9, 0
	v_readlane_b32 s25, v9, 32
	v_readlane_b32 s22, v8, 0
	v_readlane_b32 s24, v8, 32
	v_mov_b32_e32 v8, s28
	v_mov_b32_e32 v9, s26
	v_mov_b32_e32 v12, s29
	v_mov_b32_e32 v13, s27
	v_pk_add_f32 v[8:9], s[22:23], v[8:9]
	v_pk_add_f32 v[12:13], s[24:25], v[12:13]
	s_nop 0
	v_pk_add_f32 v[8:9], v[8:9], v[12:13]
	s_nop 0
	v_pk_mul_f32 v[8:9], v[8:9], s[34:35] op_sel_hi:[1,0]
	s_nop 0
	v_fma_f32 v8, -v9, v9, v8
	v_max_f32_e32 v8, 0, v8
	v_add_f32_e32 v8, 0x3727c5ac, v8
	v_cmp_gt_f32_e32 vcc, s30, v8
	v_mul_f32_e32 v12, 0x4b800000, v8
	v_sub_f32_e32 v6, v6, v9
	v_cndmask_b32_e32 v8, v8, v12, vcc
	v_rsq_f32_e32 v8, v8
	s_nop 0
	v_mul_f32_e32 v12, 0x45800000, v8
	v_cndmask_b32_e32 v8, v8, v12, vcc
	v_mul_f32_e32 v6, v6, v8
	v_fma_f32 v6, v80, v6, v84
	v_cvt_pk_bf16_f32 v6, v6, s0
	ds_write_b16 v92, v6 offset:16
	v_sub_f32_e32 v6, v7, v9
	v_mul_f32_e32 v6, v6, v8
	v_fma_f32 v6, v81, v6, v85
	v_cvt_pk_bf16_f32 v6, v6, s0
	ds_write_b16 v92, v6 offset:16912
	v_sub_f32_e32 v6, v10, v9
	v_mul_f32_e32 v6, v6, v8
	v_fma_f32 v6, v82, v6, v90
	v_cvt_pk_bf16_f32 v6, v6, s0
	ds_write_b16 v92, v6 offset:33808
	v_sub_f32_e32 v6, v11, v9
	v_mul_f32_e32 v6, v6, v8
	v_fma_f32 v6, v83, v6, v91
	v_cvt_pk_bf16_f32 v6, v6, s0
	ds_write_b16 v92, v6 offset:50704
	v_lshlrev_b32_e32 v6, 16, v73
	v_mul_f32_e32 v8, 0x3d372713, v6
	v_mul_f32_e32 v8, v8, v6
	v_mov_b32_e32 v9, v6
	v_lshlrev_b32_e32 v7, 16, v94
	v_fmac_f32_e32 v9, v8, v9
	v_mul_f32_e32 v8, 0x3f4c422a, v9
	v_mul_f32_e32 v9, 0x3d372713, v7
	v_mul_f32_e32 v9, v9, v7
	v_mov_b32_e32 v10, v7
	v_fmac_f32_e32 v10, v9, v10
	v_mul_f32_e32 v9, 0x3f4c422a, v10
	v_add_f32_e32 v8, v8, v8
	v_add_f32_e32 v9, v9, v9
	v_mul_f32_e32 v8, 0xbfb8aa3b, v8
	v_mul_f32_e32 v9, 0xbfb8aa3b, v9
	v_exp_f32_e32 v8, v8
	v_exp_f32_e32 v9, v9
	s_nop 0
	v_pk_add_f32 v[8:9], v[8:9], 1.0 op_sel_hi:[1,0]
	s_nop 0
	v_rcp_f32_e32 v9, v9
	v_rcp_f32_e32 v8, v8
	v_lshlrev_b32_e32 v10, 16, v95
	v_mul_f32_e32 v12, 0x3d372713, v10
	v_mul_f32_e32 v12, v12, v10
	v_mov_b32_e32 v13, v10
	v_lshlrev_b32_e32 v11, 16, v70
	v_fmac_f32_e32 v13, v12, v13
	v_mul_f32_e32 v12, 0x3f4c422a, v13
	v_mul_f32_e32 v13, 0x3d372713, v11
	v_mul_f32_e32 v13, v13, v11
	v_mov_b32_e32 v15, v11
	v_fmac_f32_e32 v15, v13, v15
	v_mul_f32_e32 v13, 0x3f4c422a, v15
	v_add_f32_e32 v12, v12, v12
	v_add_f32_e32 v13, v13, v13
	v_mul_f32_e32 v12, 0xbfb8aa3b, v12
	v_mul_f32_e32 v13, 0xbfb8aa3b, v13
	v_exp_f32_e32 v12, v12
	v_exp_f32_e32 v13, v13
	v_pk_mul_f32 v[6:7], v[8:9], v[6:7]
	v_pk_add_f32 v[12:13], v[12:13], 1.0 op_sel_hi:[1,0]
	s_nop 0
	v_add_f32_e32 v8, 0, v6
	v_add_f32_e32 v14, v8, v7
	v_pk_mul_f32 v[8:9], v[6:7], v[6:7]
	v_rcp_f32_e32 v13, v13
	v_add_f32_e32 v8, v8, v9
	v_rcp_f32_e32 v12, v12
	s_nop 0
	v_pk_mul_f32 v[10:11], v[12:13], v[10:11]
	s_nop 0
	v_add_f32_e32 v12, v14, v10
	v_add_f32_e32 v14, v12, v11
	v_pk_mul_f32 v[12:13], v[10:11], v[10:11]
	s_nop 0
	v_add_f32_e32 v8, v8, v12
	v_add_f32_e32 v8, v8, v13
	v_add_f32_dpp v9, v14, v14 quad_perm:[1,0,3,2] row_mask:0xf bank_mask:0xf bound_ctrl:1
	s_nop 0
	v_add_f32_dpp v8, v8, v8 quad_perm:[1,0,3,2] row_mask:0xf bank_mask:0xf bound_ctrl:1
	v_add_f32_dpp v9, v9, v9 quad_perm:[2,3,0,1] row_mask:0xf bank_mask:0xf bound_ctrl:1
	s_nop 0
	v_add_f32_dpp v8, v8, v8 quad_perm:[2,3,0,1] row_mask:0xf bank_mask:0xf bound_ctrl:1
	v_add_f32_dpp v9, v9, v9 row_half_mirror row_mask:0xf bank_mask:0xf bound_ctrl:1
	s_nop 0
	v_add_f32_dpp v8, v8, v8 row_half_mirror row_mask:0xf bank_mask:0xf bound_ctrl:1
	v_add_f32_dpp v9, v9, v9 row_mirror row_mask:0xf bank_mask:0xf bound_ctrl:1
	s_nop 0
	v_add_f32_dpp v8, v8, v8 row_mirror row_mask:0xf bank_mask:0xf bound_ctrl:1
	v_readlane_b32 s26, v9, 16
	v_readlane_b32 s27, v9, 48
	v_readlane_b32 s28, v8, 16
	v_readlane_b32 s29, v8, 48
	v_readlane_b32 s23, v9, 0
	v_readlane_b32 s25, v9, 32
	v_readlane_b32 s22, v8, 0
	v_readlane_b32 s24, v8, 32
	v_mov_b32_e32 v8, s28
	v_mov_b32_e32 v9, s26
	v_mov_b32_e32 v12, s29
	v_mov_b32_e32 v13, s27
	v_pk_add_f32 v[8:9], s[22:23], v[8:9]
	v_pk_add_f32 v[12:13], s[24:25], v[12:13]
	s_nop 0
	v_pk_add_f32 v[8:9], v[8:9], v[12:13]
	s_nop 0
	v_pk_mul_f32 v[8:9], v[8:9], s[34:35] op_sel_hi:[1,0]
	s_nop 0
	v_fma_f32 v8, -v9, v9, v8
	v_max_f32_e32 v8, 0, v8
	v_add_f32_e32 v8, 0x3727c5ac, v8
	v_cmp_gt_f32_e32 vcc, s30, v8
	v_mul_f32_e32 v12, 0x4b800000, v8
	v_sub_f32_e32 v6, v6, v9
	v_cndmask_b32_e32 v8, v8, v12, vcc
	v_rsq_f32_e32 v8, v8
	s_nop 0
	v_mul_f32_e32 v12, 0x45800000, v8
	v_cndmask_b32_e32 v8, v8, v12, vcc
	v_mul_f32_e32 v6, v6, v8
	v_fma_f32 v6, v80, v6, v84
	v_cvt_pk_bf16_f32 v6, v6, s0
	ds_write_b16 v92, v6 offset:32
	v_sub_f32_e32 v6, v7, v9
	v_mul_f32_e32 v6, v6, v8
	v_fma_f32 v6, v81, v6, v85
	v_cvt_pk_bf16_f32 v6, v6, s0
	ds_write_b16 v92, v6 offset:16928
	v_sub_f32_e32 v6, v10, v9
	v_mul_f32_e32 v6, v6, v8
	v_fma_f32 v6, v82, v6, v90
	v_cvt_pk_bf16_f32 v6, v6, s0
	ds_write_b16 v92, v6 offset:33824
	v_sub_f32_e32 v6, v11, v9
	v_mul_f32_e32 v6, v6, v8
	v_fma_f32 v6, v83, v6, v91
	v_cvt_pk_bf16_f32 v6, v6, s0
	ds_write_b16 v92, v6 offset:50720
	v_lshlrev_b32_e32 v6, 16, v71
	v_mul_f32_e32 v8, 0x3d372713, v6
	v_mul_f32_e32 v8, v8, v6
	v_mov_b32_e32 v9, v6
	v_lshlrev_b32_e32 v7, 16, v96
	v_fmac_f32_e32 v9, v8, v9
	v_mul_f32_e32 v8, 0x3f4c422a, v9
	v_mul_f32_e32 v9, 0x3d372713, v7
	v_mul_f32_e32 v9, v9, v7
	v_mov_b32_e32 v10, v7
	v_fmac_f32_e32 v10, v9, v10
	v_mul_f32_e32 v9, 0x3f4c422a, v10
	v_add_f32_e32 v8, v8, v8
	v_add_f32_e32 v9, v9, v9
	v_mul_f32_e32 v8, 0xbfb8aa3b, v8
	v_mul_f32_e32 v9, 0xbfb8aa3b, v9
	v_exp_f32_e32 v8, v8
	v_exp_f32_e32 v9, v9
	s_nop 0
	v_pk_add_f32 v[8:9], v[8:9], 1.0 op_sel_hi:[1,0]
	s_nop 0
	v_rcp_f32_e32 v9, v9
	v_rcp_f32_e32 v8, v8
	v_lshlrev_b32_e32 v10, 16, v64
	v_mul_f32_e32 v12, 0x3d372713, v10
	v_mul_f32_e32 v12, v12, v10
	v_mov_b32_e32 v13, v10
	v_lshlrev_b32_e32 v11, 16, v65
	v_fmac_f32_e32 v13, v12, v13
	v_mul_f32_e32 v12, 0x3f4c422a, v13
	v_mul_f32_e32 v13, 0x3d372713, v11
	v_mul_f32_e32 v13, v13, v11
	v_mov_b32_e32 v15, v11
	v_fmac_f32_e32 v15, v13, v15
	v_mul_f32_e32 v13, 0x3f4c422a, v15
	v_add_f32_e32 v12, v12, v12
	v_add_f32_e32 v13, v13, v13
	v_mul_f32_e32 v12, 0xbfb8aa3b, v12
	v_mul_f32_e32 v13, 0xbfb8aa3b, v13
	v_exp_f32_e32 v12, v12
	v_exp_f32_e32 v13, v13
	v_pk_mul_f32 v[6:7], v[8:9], v[6:7]
	v_pk_add_f32 v[12:13], v[12:13], 1.0 op_sel_hi:[1,0]
	s_nop 0
	v_add_f32_e32 v8, 0, v6
	v_add_f32_e32 v14, v8, v7
	v_pk_mul_f32 v[8:9], v[6:7], v[6:7]
	v_rcp_f32_e32 v13, v13
	v_add_f32_e32 v8, v8, v9
	v_rcp_f32_e32 v12, v12
	s_nop 0
	v_pk_mul_f32 v[10:11], v[12:13], v[10:11]
	s_nop 0
	v_add_f32_e32 v12, v14, v10
	v_add_f32_e32 v14, v12, v11
	v_pk_mul_f32 v[12:13], v[10:11], v[10:11]
	s_nop 0
	v_add_f32_e32 v8, v8, v12
	v_add_f32_e32 v8, v8, v13
	v_add_f32_dpp v9, v14, v14 quad_perm:[1,0,3,2] row_mask:0xf bank_mask:0xf bound_ctrl:1
	s_nop 0
	v_add_f32_dpp v8, v8, v8 quad_perm:[1,0,3,2] row_mask:0xf bank_mask:0xf bound_ctrl:1
	v_add_f32_dpp v9, v9, v9 quad_perm:[2,3,0,1] row_mask:0xf bank_mask:0xf bound_ctrl:1
	s_nop 0
	v_add_f32_dpp v8, v8, v8 quad_perm:[2,3,0,1] row_mask:0xf bank_mask:0xf bound_ctrl:1
	v_add_f32_dpp v9, v9, v9 row_half_mirror row_mask:0xf bank_mask:0xf bound_ctrl:1
	s_nop 0
	v_add_f32_dpp v8, v8, v8 row_half_mirror row_mask:0xf bank_mask:0xf bound_ctrl:1
	v_add_f32_dpp v9, v9, v9 row_mirror row_mask:0xf bank_mask:0xf bound_ctrl:1
	s_nop 0
	v_add_f32_dpp v8, v8, v8 row_mirror row_mask:0xf bank_mask:0xf bound_ctrl:1
	v_readlane_b32 s26, v9, 16
	v_readlane_b32 s27, v9, 48
	v_readlane_b32 s28, v8, 16
	v_readlane_b32 s29, v8, 48
	v_readlane_b32 s23, v9, 0
	v_readlane_b32 s25, v9, 32
	v_readlane_b32 s22, v8, 0
	v_readlane_b32 s24, v8, 32
	v_mov_b32_e32 v8, s28
	v_mov_b32_e32 v9, s26
	v_mov_b32_e32 v12, s29
	v_mov_b32_e32 v13, s27
	v_pk_add_f32 v[8:9], s[22:23], v[8:9]
	v_pk_add_f32 v[12:13], s[24:25], v[12:13]
	s_nop 0
	v_pk_add_f32 v[8:9], v[8:9], v[12:13]
	s_nop 0
	v_pk_mul_f32 v[8:9], v[8:9], s[34:35] op_sel_hi:[1,0]
	s_nop 0
	v_fma_f32 v8, -v9, v9, v8
	v_max_f32_e32 v8, 0, v8
	v_add_f32_e32 v8, 0x3727c5ac, v8
	v_cmp_gt_f32_e32 vcc, s30, v8
	v_mul_f32_e32 v12, 0x4b800000, v8
	v_sub_f32_e32 v6, v6, v9
	v_cndmask_b32_e32 v8, v8, v12, vcc
	v_rsq_f32_e32 v8, v8
	s_nop 0
	v_mul_f32_e32 v12, 0x45800000, v8
	v_cndmask_b32_e32 v8, v8, v12, vcc
	v_mul_f32_e32 v6, v6, v8
	v_fma_f32 v6, v80, v6, v84
	v_cvt_pk_bf16_f32 v6, v6, s0
	ds_write_b16 v92, v6 offset:48
	v_sub_f32_e32 v6, v7, v9
	v_mul_f32_e32 v6, v6, v8
	v_fma_f32 v6, v81, v6, v85
	v_cvt_pk_bf16_f32 v6, v6, s0
	ds_write_b16 v92, v6 offset:16944
	v_sub_f32_e32 v6, v10, v9
	v_mul_f32_e32 v6, v6, v8
	v_fma_f32 v6, v82, v6, v90
	v_cvt_pk_bf16_f32 v6, v6, s0
	ds_write_b16 v92, v6 offset:33840
	v_sub_f32_e32 v6, v11, v9
	v_mul_f32_e32 v6, v6, v8
	v_fma_f32 v6, v83, v6, v91
	v_cvt_pk_bf16_f32 v6, v6, s0
	ds_write_b16 v92, v6 offset:50736
	v_lshlrev_b32_e32 v6, 16, v53
	v_mul_f32_e32 v8, 0x3d372713, v6
	v_mul_f32_e32 v8, v8, v6
	v_mov_b32_e32 v9, v6
	v_lshlrev_b32_e32 v7, 16, v28
	v_fmac_f32_e32 v9, v8, v9
	v_mul_f32_e32 v8, 0x3f4c422a, v9
	v_mul_f32_e32 v9, 0x3d372713, v7
	v_mul_f32_e32 v9, v9, v7
	v_mov_b32_e32 v10, v7
	v_fmac_f32_e32 v10, v9, v10
	v_mul_f32_e32 v9, 0x3f4c422a, v10
	v_add_f32_e32 v8, v8, v8
	v_add_f32_e32 v9, v9, v9
	v_mul_f32_e32 v8, 0xbfb8aa3b, v8
	v_mul_f32_e32 v9, 0xbfb8aa3b, v9
	v_exp_f32_e32 v8, v8
	v_exp_f32_e32 v9, v9
	s_nop 0
	v_pk_add_f32 v[8:9], v[8:9], 1.0 op_sel_hi:[1,0]
	s_nop 0
	v_rcp_f32_e32 v9, v9
	v_rcp_f32_e32 v8, v8
	v_lshlrev_b32_e32 v10, 16, v26
	v_mul_f32_e32 v12, 0x3d372713, v10
	v_mul_f32_e32 v12, v12, v10
	v_mov_b32_e32 v13, v10
	v_lshlrev_b32_e32 v11, 16, v27
	v_fmac_f32_e32 v13, v12, v13
	v_mul_f32_e32 v12, 0x3f4c422a, v13
	v_mul_f32_e32 v13, 0x3d372713, v11
	v_mul_f32_e32 v13, v13, v11
	v_mov_b32_e32 v15, v11
	v_fmac_f32_e32 v15, v13, v15
	v_mul_f32_e32 v13, 0x3f4c422a, v15
	v_add_f32_e32 v12, v12, v12
	v_add_f32_e32 v13, v13, v13
	v_mul_f32_e32 v12, 0xbfb8aa3b, v12
	v_mul_f32_e32 v13, 0xbfb8aa3b, v13
	v_exp_f32_e32 v12, v12
	v_exp_f32_e32 v13, v13
	v_pk_mul_f32 v[6:7], v[8:9], v[6:7]
	v_pk_add_f32 v[12:13], v[12:13], 1.0 op_sel_hi:[1,0]
	s_nop 0
	v_add_f32_e32 v8, 0, v6
	v_add_f32_e32 v14, v8, v7
	v_pk_mul_f32 v[8:9], v[6:7], v[6:7]
	v_rcp_f32_e32 v13, v13
	v_add_f32_e32 v8, v8, v9
	v_rcp_f32_e32 v12, v12
	s_nop 0
	v_pk_mul_f32 v[10:11], v[12:13], v[10:11]
	s_nop 0
	v_add_f32_e32 v12, v14, v10
	v_add_f32_e32 v14, v12, v11
	v_pk_mul_f32 v[12:13], v[10:11], v[10:11]
	s_nop 0
	v_add_f32_e32 v8, v8, v12
	v_add_f32_e32 v8, v8, v13
	v_add_f32_dpp v9, v14, v14 quad_perm:[1,0,3,2] row_mask:0xf bank_mask:0xf bound_ctrl:1
	s_nop 0
	v_add_f32_dpp v8, v8, v8 quad_perm:[1,0,3,2] row_mask:0xf bank_mask:0xf bound_ctrl:1
	v_add_f32_dpp v9, v9, v9 quad_perm:[2,3,0,1] row_mask:0xf bank_mask:0xf bound_ctrl:1
	s_nop 0
	v_add_f32_dpp v8, v8, v8 quad_perm:[2,3,0,1] row_mask:0xf bank_mask:0xf bound_ctrl:1
	v_add_f32_dpp v9, v9, v9 row_half_mirror row_mask:0xf bank_mask:0xf bound_ctrl:1
	s_nop 0
	v_add_f32_dpp v8, v8, v8 row_half_mirror row_mask:0xf bank_mask:0xf bound_ctrl:1
	v_add_f32_dpp v9, v9, v9 row_mirror row_mask:0xf bank_mask:0xf bound_ctrl:1
	s_nop 0
	v_add_f32_dpp v8, v8, v8 row_mirror row_mask:0xf bank_mask:0xf bound_ctrl:1
	v_readlane_b32 s26, v9, 16
	v_readlane_b32 s27, v9, 48
	v_readlane_b32 s28, v8, 16
	v_readlane_b32 s29, v8, 48
	v_readlane_b32 s23, v9, 0
	v_readlane_b32 s25, v9, 32
	v_readlane_b32 s22, v8, 0
	v_readlane_b32 s24, v8, 32
	v_mov_b32_e32 v8, s28
	v_mov_b32_e32 v9, s26
	v_mov_b32_e32 v12, s29
	v_mov_b32_e32 v13, s27
	v_pk_add_f32 v[8:9], s[22:23], v[8:9]
	v_pk_add_f32 v[12:13], s[24:25], v[12:13]
	s_nop 0
	v_pk_add_f32 v[8:9], v[8:9], v[12:13]
	s_nop 0
	v_pk_mul_f32 v[8:9], v[8:9], s[34:35] op_sel_hi:[1,0]
	s_nop 0
	v_fma_f32 v8, -v9, v9, v8
	v_max_f32_e32 v8, 0, v8
	v_add_f32_e32 v8, 0x3727c5ac, v8
	v_cmp_gt_f32_e32 vcc, s30, v8
	v_mul_f32_e32 v12, 0x4b800000, v8
	v_sub_f32_e32 v6, v6, v9
	v_cndmask_b32_e32 v8, v8, v12, vcc
	v_rsq_f32_e32 v8, v8
	s_nop 0
	v_mul_f32_e32 v12, 0x45800000, v8
	v_cndmask_b32_e32 v8, v8, v12, vcc
	v_mul_f32_e32 v6, v6, v8
	v_fma_f32 v6, v80, v6, v84
	v_cvt_pk_bf16_f32 v6, v6, s0
	ds_write_b16 v92, v6 offset:64
	v_sub_f32_e32 v6, v7, v9
	v_mul_f32_e32 v6, v6, v8
	v_fma_f32 v6, v81, v6, v85
	v_cvt_pk_bf16_f32 v6, v6, s0
	ds_write_b16 v92, v6 offset:16960
	v_sub_f32_e32 v6, v10, v9
	v_mul_f32_e32 v6, v6, v8
	v_fma_f32 v6, v82, v6, v90
	v_cvt_pk_bf16_f32 v6, v6, s0
	ds_write_b16 v92, v6 offset:33856
	v_sub_f32_e32 v6, v11, v9
	v_mul_f32_e32 v6, v6, v8
	v_fma_f32 v6, v83, v6, v91
	v_cvt_pk_bf16_f32 v6, v6, s0
	ds_write_b16 v92, v6 offset:50752
	v_lshlrev_b32_e32 v6, 16, v24
	v_mul_f32_e32 v8, 0x3d372713, v6
	v_mul_f32_e32 v8, v8, v6
	v_mov_b32_e32 v9, v6
	v_lshlrev_b32_e32 v7, 16, v25
	v_fmac_f32_e32 v9, v8, v9
	v_mul_f32_e32 v8, 0x3f4c422a, v9
	v_mul_f32_e32 v9, 0x3d372713, v7
	v_mul_f32_e32 v9, v9, v7
	v_mov_b32_e32 v10, v7
	v_fmac_f32_e32 v10, v9, v10
	v_mul_f32_e32 v9, 0x3f4c422a, v10
	v_add_f32_e32 v8, v8, v8
	v_add_f32_e32 v9, v9, v9
	v_mul_f32_e32 v8, 0xbfb8aa3b, v8
	v_mul_f32_e32 v9, 0xbfb8aa3b, v9
	v_exp_f32_e32 v8, v8
	v_exp_f32_e32 v9, v9
	s_nop 0
	v_pk_add_f32 v[8:9], v[8:9], 1.0 op_sel_hi:[1,0]
	s_nop 0
	v_rcp_f32_e32 v9, v9
	v_rcp_f32_e32 v8, v8
	v_lshlrev_b32_e32 v10, 16, v18
	v_mul_f32_e32 v12, 0x3d372713, v10
	v_mul_f32_e32 v12, v12, v10
	v_mov_b32_e32 v13, v10
	v_lshlrev_b32_e32 v11, 16, v19
	v_fmac_f32_e32 v13, v12, v13
	v_mul_f32_e32 v12, 0x3f4c422a, v13
	v_mul_f32_e32 v13, 0x3d372713, v11
	v_mul_f32_e32 v13, v13, v11
	v_mov_b32_e32 v15, v11
	v_fmac_f32_e32 v15, v13, v15
	v_mul_f32_e32 v13, 0x3f4c422a, v15
	v_add_f32_e32 v12, v12, v12
	v_add_f32_e32 v13, v13, v13
	v_mul_f32_e32 v12, 0xbfb8aa3b, v12
	v_mul_f32_e32 v13, 0xbfb8aa3b, v13
	v_exp_f32_e32 v12, v12
	v_exp_f32_e32 v13, v13
	v_pk_mul_f32 v[6:7], v[8:9], v[6:7]
	v_pk_add_f32 v[12:13], v[12:13], 1.0 op_sel_hi:[1,0]
	s_nop 0
	v_add_f32_e32 v8, 0, v6
	v_add_f32_e32 v14, v8, v7
	v_pk_mul_f32 v[8:9], v[6:7], v[6:7]
	v_rcp_f32_e32 v13, v13
	v_add_f32_e32 v8, v8, v9
	v_rcp_f32_e32 v12, v12
	s_nop 0
	v_pk_mul_f32 v[10:11], v[12:13], v[10:11]
	s_nop 0
	v_add_f32_e32 v12, v14, v10
	v_add_f32_e32 v14, v12, v11
	v_pk_mul_f32 v[12:13], v[10:11], v[10:11]
	s_nop 0
	v_add_f32_e32 v8, v8, v12
	v_add_f32_e32 v8, v8, v13
	v_add_f32_dpp v9, v14, v14 quad_perm:[1,0,3,2] row_mask:0xf bank_mask:0xf bound_ctrl:1
	s_nop 0
	v_add_f32_dpp v8, v8, v8 quad_perm:[1,0,3,2] row_mask:0xf bank_mask:0xf bound_ctrl:1
	v_add_f32_dpp v9, v9, v9 quad_perm:[2,3,0,1] row_mask:0xf bank_mask:0xf bound_ctrl:1
	s_nop 0
	v_add_f32_dpp v8, v8, v8 quad_perm:[2,3,0,1] row_mask:0xf bank_mask:0xf bound_ctrl:1
	v_add_f32_dpp v9, v9, v9 row_half_mirror row_mask:0xf bank_mask:0xf bound_ctrl:1
	s_nop 0
	v_add_f32_dpp v8, v8, v8 row_half_mirror row_mask:0xf bank_mask:0xf bound_ctrl:1
	v_add_f32_dpp v9, v9, v9 row_mirror row_mask:0xf bank_mask:0xf bound_ctrl:1
	s_nop 0
	v_add_f32_dpp v8, v8, v8 row_mirror row_mask:0xf bank_mask:0xf bound_ctrl:1
	v_readlane_b32 s26, v9, 16
	v_readlane_b32 s27, v9, 48
	v_readlane_b32 s28, v8, 16
	v_readlane_b32 s29, v8, 48
	v_readlane_b32 s23, v9, 0
	v_readlane_b32 s25, v9, 32
	v_readlane_b32 s22, v8, 0
	v_readlane_b32 s24, v8, 32
	v_mov_b32_e32 v8, s28
	v_mov_b32_e32 v9, s26
	v_mov_b32_e32 v12, s29
	v_mov_b32_e32 v13, s27
	v_pk_add_f32 v[8:9], s[22:23], v[8:9]
	v_pk_add_f32 v[12:13], s[24:25], v[12:13]
	s_nop 0
	v_pk_add_f32 v[8:9], v[8:9], v[12:13]
	s_nop 0
	v_pk_mul_f32 v[8:9], v[8:9], s[34:35] op_sel_hi:[1,0]
	s_nop 0
	v_fma_f32 v8, -v9, v9, v8
	v_max_f32_e32 v8, 0, v8
	v_add_f32_e32 v8, 0x3727c5ac, v8
	v_cmp_gt_f32_e32 vcc, s30, v8
	v_mul_f32_e32 v12, 0x4b800000, v8
	v_sub_f32_e32 v6, v6, v9
	v_cndmask_b32_e32 v8, v8, v12, vcc
	v_rsq_f32_e32 v8, v8
	s_nop 0
	v_mul_f32_e32 v12, 0x45800000, v8
	v_cndmask_b32_e32 v8, v8, v12, vcc
	v_mul_f32_e32 v6, v6, v8
	v_fma_f32 v6, v80, v6, v84
	v_cvt_pk_bf16_f32 v6, v6, s0
	ds_write_b16 v92, v6 offset:80
	v_sub_f32_e32 v6, v7, v9
	v_mul_f32_e32 v6, v6, v8
	v_fma_f32 v6, v81, v6, v85
	v_cvt_pk_bf16_f32 v6, v6, s0
	ds_write_b16 v92, v6 offset:16976
	v_sub_f32_e32 v6, v10, v9
	v_mul_f32_e32 v6, v6, v8
	v_fma_f32 v6, v82, v6, v90
	v_cvt_pk_bf16_f32 v6, v6, s0
	ds_write_b16 v92, v6 offset:33872
	v_sub_f32_e32 v6, v11, v9
	v_mul_f32_e32 v6, v6, v8
	v_fma_f32 v6, v83, v6, v91
	v_cvt_pk_bf16_f32 v6, v6, s0
	ds_write_b16 v92, v6 offset:50768
	v_lshlrev_b32_e32 v6, 16, v16
	v_mul_f32_e32 v8, 0x3d372713, v6
	v_mul_f32_e32 v8, v8, v6
	v_mov_b32_e32 v9, v6
	v_lshlrev_b32_e32 v7, 16, v17
	v_fmac_f32_e32 v9, v8, v9
	v_mul_f32_e32 v8, 0x3f4c422a, v9
	v_mul_f32_e32 v9, 0x3d372713, v7
	v_mul_f32_e32 v9, v9, v7
	v_mov_b32_e32 v10, v7
	v_fmac_f32_e32 v10, v9, v10
	v_mul_f32_e32 v9, 0x3f4c422a, v10
	v_add_f32_e32 v8, v8, v8
	v_add_f32_e32 v9, v9, v9
	v_mul_f32_e32 v8, 0xbfb8aa3b, v8
	v_mul_f32_e32 v9, 0xbfb8aa3b, v9
	v_exp_f32_e32 v8, v8
	v_exp_f32_e32 v9, v9
	s_nop 0
	v_pk_add_f32 v[8:9], v[8:9], 1.0 op_sel_hi:[1,0]
	s_nop 0
	v_rcp_f32_e32 v9, v9
	v_rcp_f32_e32 v8, v8
	v_mul_f32_e32 v10, 0x3d372713, v4
	v_mul_f32_e32 v10, v10, v4
	v_mov_b32_e32 v11, v4
	v_fmac_f32_e32 v11, v10, v11
	v_mul_f32_e32 v10, 0x3f4c422a, v11
	v_mul_f32_e32 v11, 0x3d372713, v5
	v_mul_f32_e32 v11, v11, v5
	v_mov_b32_e32 v13, v5
	v_fmac_f32_e32 v13, v11, v13
	v_mul_f32_e32 v11, 0x3f4c422a, v13
	v_add_f32_e32 v10, v10, v10
	v_add_f32_e32 v11, v11, v11
	v_mul_f32_e32 v10, 0xbfb8aa3b, v10
	v_mul_f32_e32 v11, 0xbfb8aa3b, v11
	v_exp_f32_e32 v10, v10
	v_exp_f32_e32 v11, v11
	v_pk_mul_f32 v[6:7], v[8:9], v[6:7]
	v_pk_add_f32 v[10:11], v[10:11], 1.0 op_sel_hi:[1,0]
	s_nop 0
	v_add_f32_e32 v8, 0, v6
	v_add_f32_e32 v12, v8, v7
	v_pk_mul_f32 v[8:9], v[6:7], v[6:7]
	v_rcp_f32_e32 v11, v11
	v_add_f32_e32 v8, v8, v9
	v_rcp_f32_e32 v10, v10
	s_nop 0
	v_pk_mul_f32 v[4:5], v[10:11], v[4:5]
	s_nop 0
	v_add_f32_e32 v10, v12, v4
	v_add_f32_e32 v12, v10, v5
	v_pk_mul_f32 v[10:11], v[4:5], v[4:5]
	s_nop 0
	v_add_f32_e32 v8, v8, v10
	v_add_f32_e32 v8, v8, v11
	v_add_f32_dpp v9, v12, v12 quad_perm:[1,0,3,2] row_mask:0xf bank_mask:0xf bound_ctrl:1
	s_nop 0
	v_add_f32_dpp v8, v8, v8 quad_perm:[1,0,3,2] row_mask:0xf bank_mask:0xf bound_ctrl:1
	v_add_f32_dpp v9, v9, v9 quad_perm:[2,3,0,1] row_mask:0xf bank_mask:0xf bound_ctrl:1
	s_nop 0
	v_add_f32_dpp v8, v8, v8 quad_perm:[2,3,0,1] row_mask:0xf bank_mask:0xf bound_ctrl:1
	v_add_f32_dpp v9, v9, v9 row_half_mirror row_mask:0xf bank_mask:0xf bound_ctrl:1
	s_nop 0
	v_add_f32_dpp v8, v8, v8 row_half_mirror row_mask:0xf bank_mask:0xf bound_ctrl:1
	v_add_f32_dpp v9, v9, v9 row_mirror row_mask:0xf bank_mask:0xf bound_ctrl:1
	s_nop 0
	v_add_f32_dpp v8, v8, v8 row_mirror row_mask:0xf bank_mask:0xf bound_ctrl:1
	v_readlane_b32 s26, v9, 16
	v_readlane_b32 s27, v9, 48
	v_readlane_b32 s28, v8, 16
	v_readlane_b32 s29, v8, 48
	v_readlane_b32 s23, v9, 0
	v_readlane_b32 s25, v9, 32
	v_readlane_b32 s22, v8, 0
	v_readlane_b32 s24, v8, 32
	v_mov_b32_e32 v8, s28
	v_mov_b32_e32 v9, s26
	v_mov_b32_e32 v10, s29
	v_mov_b32_e32 v11, s27
	v_pk_add_f32 v[8:9], s[22:23], v[8:9]
	v_pk_add_f32 v[10:11], s[24:25], v[10:11]
	s_nop 0
	v_pk_add_f32 v[8:9], v[8:9], v[10:11]
	s_nop 0
	v_pk_mul_f32 v[8:9], v[8:9], s[34:35] op_sel_hi:[1,0]
	s_nop 0
	v_fma_f32 v8, -v9, v9, v8
	v_max_f32_e32 v8, 0, v8
	v_add_f32_e32 v8, 0x3727c5ac, v8
	v_cmp_gt_f32_e32 vcc, s30, v8
	v_mul_f32_e32 v10, 0x4b800000, v8
	v_sub_f32_e32 v4, v4, v9
	v_cndmask_b32_e32 v8, v8, v10, vcc
	v_rsq_f32_e32 v8, v8
	v_sub_f32_e32 v6, v6, v9
	v_mul_f32_e32 v10, 0x45800000, v8
	v_cndmask_b32_e32 v8, v8, v10, vcc
	v_mul_f32_e32 v4, v4, v8
	v_fma_f32 v4, v82, v4, v90
	v_cvt_pk_bf16_f32 v4, v4, s0
	ds_write_b16 v92, v4 offset:33888
	v_sub_f32_e32 v4, v5, v9
	v_mul_f32_e32 v6, v6, v8
	v_mul_f32_e32 v4, v4, v8
	v_fma_f32 v6, v80, v6, v84
	v_fma_f32 v4, v83, v4, v91
	v_cvt_pk_bf16_f32 v6, v6, s0
	v_cvt_pk_bf16_f32 v4, v4, s0
	ds_write_b16 v92, v6 offset:96
	v_sub_f32_e32 v6, v7, v9
	ds_write_b16 v92, v4 offset:50784
	v_mul_f32_e32 v4, 0x3d372713, v2
	v_mul_f32_e32 v6, v6, v8
	v_mul_f32_e32 v4, v4, v2
	v_mov_b32_e32 v5, v2
	v_fma_f32 v6, v81, v6, v85
	v_fmac_f32_e32 v5, v4, v5
	v_cvt_pk_bf16_f32 v6, v6, s0
	v_mul_f32_e32 v4, 0x3f4c422a, v5
	v_mul_f32_e32 v5, 0x3d372713, v3
	ds_write_b16 v92, v6 offset:16992
	v_mul_f32_e32 v5, v5, v3
	v_mov_b32_e32 v6, v3
	v_fmac_f32_e32 v6, v5, v6
	v_mul_f32_e32 v5, 0x3f4c422a, v6
	v_add_f32_e32 v4, v4, v4
	v_add_f32_e32 v5, v5, v5
	v_mul_f32_e32 v4, 0xbfb8aa3b, v4
	v_mul_f32_e32 v5, 0xbfb8aa3b, v5
	v_exp_f32_e32 v4, v4
	v_exp_f32_e32 v5, v5
	s_nop 0
	v_pk_add_f32 v[4:5], v[4:5], 1.0 op_sel_hi:[1,0]
	s_nop 0
	v_rcp_f32_e32 v5, v5
	v_rcp_f32_e32 v4, v4
	v_mul_f32_e32 v6, 0x3d372713, v0
	v_mul_f32_e32 v6, v6, v0
	v_mov_b32_e32 v7, v0
	v_fmac_f32_e32 v7, v6, v7
	v_mul_f32_e32 v6, 0x3f4c422a, v7
	v_mul_f32_e32 v7, 0x3d372713, v1
	v_mul_f32_e32 v7, v7, v1
	v_mov_b32_e32 v9, v1
	v_fmac_f32_e32 v9, v7, v9
	v_mul_f32_e32 v7, 0x3f4c422a, v9
	v_add_f32_e32 v6, v6, v6
	v_add_f32_e32 v7, v7, v7
	v_mul_f32_e32 v6, 0xbfb8aa3b, v6
	v_mul_f32_e32 v7, 0xbfb8aa3b, v7
	v_exp_f32_e32 v6, v6
	v_exp_f32_e32 v7, v7
	v_pk_mul_f32 v[2:3], v[4:5], v[2:3]
	v_pk_add_f32 v[6:7], v[6:7], 1.0 op_sel_hi:[1,0]
	s_nop 0
	v_add_f32_e32 v4, 0, v2
	v_add_f32_e32 v8, v4, v3
	v_pk_mul_f32 v[4:5], v[2:3], v[2:3]
	v_rcp_f32_e32 v7, v7
	v_add_f32_e32 v4, v4, v5
	v_rcp_f32_e32 v6, v6
	s_nop 0
	v_pk_mul_f32 v[0:1], v[6:7], v[0:1]
	s_nop 0
	v_add_f32_e32 v6, v8, v0
	v_add_f32_e32 v8, v6, v1
	v_pk_mul_f32 v[6:7], v[0:1], v[0:1]
	s_nop 0
	v_add_f32_e32 v4, v4, v6
	v_add_f32_e32 v4, v4, v7
	v_add_f32_dpp v5, v8, v8 quad_perm:[1,0,3,2] row_mask:0xf bank_mask:0xf bound_ctrl:1
	s_nop 0
	v_add_f32_dpp v4, v4, v4 quad_perm:[1,0,3,2] row_mask:0xf bank_mask:0xf bound_ctrl:1
	v_add_f32_dpp v5, v5, v5 quad_perm:[2,3,0,1] row_mask:0xf bank_mask:0xf bound_ctrl:1
	s_nop 0
	v_add_f32_dpp v4, v4, v4 quad_perm:[2,3,0,1] row_mask:0xf bank_mask:0xf bound_ctrl:1
	v_add_f32_dpp v5, v5, v5 row_half_mirror row_mask:0xf bank_mask:0xf bound_ctrl:1
	s_nop 0
	v_add_f32_dpp v4, v4, v4 row_half_mirror row_mask:0xf bank_mask:0xf bound_ctrl:1
	v_add_f32_dpp v5, v5, v5 row_mirror row_mask:0xf bank_mask:0xf bound_ctrl:1
	s_nop 0
	v_add_f32_dpp v4, v4, v4 row_mirror row_mask:0xf bank_mask:0xf bound_ctrl:1
	v_readlane_b32 s26, v5, 16
	v_readlane_b32 s27, v5, 48
	v_readlane_b32 s28, v4, 16
	v_readlane_b32 s29, v4, 48
	v_readlane_b32 s23, v5, 0
	v_readlane_b32 s25, v5, 32
	v_readlane_b32 s22, v4, 0
	v_readlane_b32 s24, v4, 32
	v_mov_b32_e32 v4, s28
	v_mov_b32_e32 v5, s26
	v_mov_b32_e32 v6, s29
	v_mov_b32_e32 v7, s27
	v_pk_add_f32 v[4:5], s[22:23], v[4:5]
	v_pk_add_f32 v[6:7], s[24:25], v[6:7]
	s_nop 0
	v_pk_add_f32 v[4:5], v[4:5], v[6:7]
	s_nop 0
	v_pk_mul_f32 v[4:5], v[4:5], s[34:35] op_sel_hi:[1,0]
	s_nop 0
	v_fma_f32 v4, -v5, v5, v4
	v_max_f32_e32 v4, 0, v4
	v_add_f32_e32 v4, 0x3727c5ac, v4
	v_cmp_gt_f32_e32 vcc, s30, v4
	v_mul_f32_e32 v6, 0x4b800000, v4
	v_sub_f32_e32 v2, v2, v5
	v_cndmask_b32_e32 v4, v4, v6, vcc
	v_rsq_f32_e32 v4, v4
	v_sub_f32_e32 v0, v0, v5
	v_mul_f32_e32 v6, 0x45800000, v4
	v_cndmask_b32_e32 v4, v4, v6, vcc
	v_mul_f32_e32 v2, v2, v4
	v_mul_f32_e32 v0, v0, v4
	v_fma_f32 v2, v80, v2, v84
	v_fma_f32 v0, v82, v0, v90
	v_cvt_pk_bf16_f32 v2, v2, s0
	v_cvt_pk_bf16_f32 v0, v0, s0
	ds_write_b16 v92, v2 offset:112
	v_sub_f32_e32 v2, v3, v5
	ds_write_b16 v92, v0 offset:33904
	v_sub_f32_e32 v0, v1, v5
	v_mul_f32_e32 v2, v2, v4
	v_mul_f32_e32 v0, v0, v4
	v_fma_f32 v2, v81, v2, v85
	v_fma_f32 v0, v83, v0, v91
	v_cvt_pk_bf16_f32 v2, v2, s0
	v_cvt_pk_bf16_f32 v0, v0, s0
	ds_write_b16 v92, v2 offset:17008
	ds_write_b16 v92, v0 offset:50800
	v_add_u32_e32 v92, 0x80, v92
	s_cbranch_scc0 .LBB0_460
.LBB0_461:
	s_lshl_b32 s10, s19, 6
	s_and_b32 s2, s10, 0xffffff80
	s_mov_b32 s97, 0x2040000
	s_mov_b32 s83, 0x800000
	v_or_b32_e32 v51, s2, v86
	s_mov_b64 s[2:3], -1
	s_cmp_lg_u32 s20, 0
	v_add_u32_e32 v64, 0x1080, v89
	v_add_u32_e32 v65, 0x2100, v89
	v_add_u32_e32 v66, 0x3180, v89
	v_add_u32_e32 v63, 0x10c0, v89
	v_add_u32_e32 v62, 0x2140, v89
	v_add_u32_e32 v53, 0x31c0, v89
	s_waitcnt lgkmcnt(0)
	s_barrier
	s_cbranch_scc0 .LBB0_463
	v_mov_b32_e32 v0, v192
	v_mov_b32_e32 v4, v192
	v_mov_b32_e32 v8, v192
	v_mov_b32_e32 v12, v192
	v_mov_b32_e32 v16, v192
	v_mov_b32_e32 v20, v192
	v_mov_b32_e32 v24, v192
	v_mov_b32_e32 v28, v195
	global_load_dwordx4 v[68:71], v[36:37], off
	global_load_dwordx4 v[72:75], v[38:39], off
	global_load_dwordx4 v[76:79], v[36:37], off offset:64
	ds_read2_b64 v[80:83], v89 offset1:1
	ds_read2_b64 v[90:93], v64 offset1:1
	ds_read2_b64 v[94:97], v65 offset1:1
	ds_read2_b64 v[98:101], v66 offset1:1
	v_mov_b32_e32 v1, v0
	v_mov_b32_e32 v2, v0
	v_mov_b32_e32 v3, v0
	v_mov_b32_e32 v5, v4
	v_mov_b32_e32 v6, v4
	v_mov_b32_e32 v7, v4
	v_mov_b32_e32 v9, v8
	v_mov_b32_e32 v10, v8
	v_mov_b32_e32 v11, v8
	v_mov_b32_e32 v13, v12
	v_mov_b32_e32 v14, v12
	v_mov_b32_e32 v15, v12
	v_mov_b32_e32 v17, v16
	v_mov_b32_e32 v18, v16
	v_mov_b32_e32 v19, v16
	v_mov_b32_e32 v21, v20
	v_mov_b32_e32 v22, v20
	v_mov_b32_e32 v23, v20
	v_mov_b32_e32 v25, v24
	v_mov_b32_e32 v26, v24
	v_mov_b32_e32 v27, v24
	v_mov_b32_e32 v29, v28
	v_mov_b32_e32 v30, v28
	v_mov_b32_e32 v31, v28
	v_add_u32_e32 v49, 0x1100, v89
	s_mov_b64 s[2:3], 0
	s_waitcnt vmcnt(0) lgkmcnt(0)
	v_mfma_f32_16x16x32_bf16 v[0:3], v[80:83], v[68:71], v[0:3]
	v_mfma_f32_16x16x32_bf16 v[4:7], v[90:93], v[68:71], v[4:7]
	v_mfma_f32_16x16x32_bf16 v[8:11], v[94:97], v[68:71], v[8:11]
	v_mfma_f32_16x16x32_bf16 v[12:15], v[98:101], v[68:71], v[12:15]
	ds_read2_b64 v[68:71], v89 offset0:8 offset1:9
	v_mfma_f32_16x16x32_bf16 v[16:19], v[80:83], v[72:75], v[16:19]
	ds_read2_b64 v[80:83], v62 offset1:1
	v_mfma_f32_16x16x32_bf16 v[20:23], v[90:93], v[72:75], v[20:23]
	ds_read2_b64 v[90:93], v53 offset1:1
	v_mfma_f32_16x16x32_bf16 v[24:27], v[94:97], v[72:75], v[24:27]
	v_mfma_f32_16x16x32_bf16 v[28:31], v[98:101], v[72:75], v[28:31]
	ds_read2_b64 v[72:75], v63 offset1:1
	global_load_dwordx4 v[98:101], v[38:39], off offset:192
	s_waitcnt lgkmcnt(0)
	v_mfma_f32_16x16x32_bf16 v[0:3], v[68:71], v[76:79], v[0:3]
	v_mfma_f32_16x16x32_bf16 v[4:7], v[72:75], v[76:79], v[4:7]
	v_mfma_f32_16x16x32_bf16 v[8:11], v[80:83], v[76:79], v[8:11]
	v_mfma_f32_16x16x32_bf16 v[12:15], v[90:93], v[76:79], v[12:15]
	global_load_dwordx4 v[76:79], v[38:39], off offset:64
	s_waitcnt vmcnt(0) lgkmcnt(0)
	v_mfma_f32_16x16x32_bf16 v[16:19], v[68:71], v[76:79], v[16:19]
	global_load_dwordx4 v[68:71], v[36:37], off offset:128
	v_mfma_f32_16x16x32_bf16 v[20:23], v[72:75], v[76:79], v[20:23]
	ds_read2_b64 v[72:75], v89 offset0:16 offset1:17
	v_mfma_f32_16x16x32_bf16 v[24:27], v[80:83], v[76:79], v[24:27]
	v_mfma_f32_16x16x32_bf16 v[28:31], v[90:93], v[76:79], v[28:31]
	ds_read2_b64 v[76:79], v49 offset1:1
	v_add_u32_e32 v49, 0x2180, v89
	ds_read2_b64 v[80:83], v49 offset1:1
	v_add_u32_e32 v49, 0x3200, v89
	ds_read2_b64 v[90:93], v49 offset1:1
	v_add_u32_e32 v49, 0x3240, v89
	s_waitcnt vmcnt(0) lgkmcnt(0)
	v_mfma_f32_16x16x32_bf16 v[0:3], v[72:75], v[68:71], v[0:3]
	ds_read2_b64 v[94:97], v49 offset1:1
	v_or_b32_e32 v49, 64, v51
	v_mfma_f32_16x16x32_bf16 v[4:7], v[76:79], v[68:71], v[4:7]
	v_mfma_f32_16x16x32_bf16 v[8:11], v[80:83], v[68:71], v[8:11]
	v_mfma_f32_16x16x32_bf16 v[12:15], v[90:93], v[68:71], v[12:15]
	global_load_dwordx4 v[68:71], v[38:39], off offset:128
	s_waitcnt vmcnt(0) lgkmcnt(0)
	v_mfma_f32_16x16x32_bf16 v[72:75], v[72:75], v[68:71], v[16:19]
	s_nop 2
	global_load_dwordx4 v[16:19], v[36:37], off offset:192
	v_mfma_f32_16x16x32_bf16 v[76:79], v[76:79], v[68:71], v[20:23]
	v_mfma_f32_16x16x32_bf16 v[80:83], v[80:83], v[68:71], v[24:27]
	s_nop 1
	v_add_u32_e32 v20, 0x1140, v89
	v_mfma_f32_16x16x32_bf16 v[68:71], v[90:93], v[68:71], v[28:31]
	ds_read2_b64 v[90:93], v89 offset0:24 offset1:25
	s_waitcnt vmcnt(0) lgkmcnt(0)
	v_mfma_f32_16x16x32_bf16 v[28:31], v[90:93], v[16:19], v[0:3]
	s_nop 2
	ds_read2_b64 v[0:3], v20 offset1:1
	v_add_u32_e32 v20, 0x21c0, v89
	s_waitcnt lgkmcnt(0)
	v_mfma_f32_16x16x32_bf16 v[24:27], v[0:3], v[16:19], v[4:7]
	s_nop 2
	ds_read2_b64 v[4:7], v20 offset1:1
	s_waitcnt lgkmcnt(0)
	v_mfma_f32_16x16x32_bf16 v[20:23], v[4:7], v[16:19], v[8:11]
	v_mfma_f32_16x16x32_bf16 v[16:19], v[94:97], v[16:19], v[12:15]
	v_mfma_f32_16x16x32_bf16 v[12:15], v[90:93], v[98:101], v[72:75]
	v_mfma_f32_16x16x32_bf16 v[8:11], v[0:3], v[98:101], v[76:79]
	v_mfma_f32_16x16x32_bf16 v[4:7], v[4:7], v[98:101], v[80:83]
	v_mfma_f32_16x16x32_bf16 v[0:3], v[94:97], v[98:101], v[68:71]
.LBB0_463:
	s_andn2_b64 vcc, exec, s[2:3]
	v_mov_b32_e32 v72, v87
	s_cbranch_vccnz .LBB0_457
	s_nop 4
	v_mov_b32_e32 v0, v192
	v_mov_b32_e32 v4, v192
	v_mov_b32_e32 v8, v192
	v_mov_b32_e32 v12, v192
	v_mov_b32_e32 v16, v192
	v_mov_b32_e32 v20, v192
	v_mov_b32_e32 v24, v192
	v_mov_b32_e32 v28, v195
	global_load_dwordx4 v[68:71], v[42:43], off
	global_load_dwordx4 v[72:75], v[44:45], off
	global_load_dwordx4 v[76:79], v[42:43], off offset:64
	ds_read2_b64 v[80:83], v89 offset1:1
	ds_read2_b64 v[90:93], v64 offset1:1
	ds_read2_b64 v[94:97], v65 offset1:1
	ds_read2_b64 v[64:67], v66 offset1:1
	v_mov_b32_e32 v1, v0
	v_mov_b32_e32 v2, v0
	v_mov_b32_e32 v3, v0
	v_mov_b32_e32 v5, v4
	v_mov_b32_e32 v6, v4
	v_mov_b32_e32 v7, v4
	v_mov_b32_e32 v9, v8
	v_mov_b32_e32 v10, v8
	v_mov_b32_e32 v11, v8
	v_mov_b32_e32 v13, v12
	v_mov_b32_e32 v14, v12
	v_mov_b32_e32 v15, v12
	v_mov_b32_e32 v17, v16
	v_mov_b32_e32 v18, v16
	v_mov_b32_e32 v19, v16
	v_mov_b32_e32 v21, v20
	v_mov_b32_e32 v22, v20
	v_mov_b32_e32 v23, v20
	v_mov_b32_e32 v25, v24
	v_mov_b32_e32 v26, v24
	v_mov_b32_e32 v27, v24
	v_mov_b32_e32 v29, v28
	v_mov_b32_e32 v30, v28
	v_mov_b32_e32 v31, v28
	v_mov_b32_e32 v49, v51
	s_waitcnt vmcnt(0) lgkmcnt(0)
	v_mfma_f32_16x16x32_bf16 v[0:3], v[80:83], v[68:71], v[0:3]
	v_mfma_f32_16x16x32_bf16 v[4:7], v[90:93], v[68:71], v[4:7]
	v_mfma_f32_16x16x32_bf16 v[8:11], v[94:97], v[68:71], v[8:11]
	v_mfma_f32_16x16x32_bf16 v[12:15], v[64:67], v[68:71], v[12:15]
	v_mfma_f32_16x16x32_bf16 v[68:71], v[80:83], v[72:75], v[16:19]
	v_mfma_f32_16x16x32_bf16 v[80:83], v[90:93], v[72:75], v[20:23]
	v_mfma_f32_16x16x32_bf16 v[90:93], v[94:97], v[72:75], v[24:27]
	ds_read2_b64 v[94:97], v53 offset1:1
	v_mfma_f32_16x16x32_bf16 v[64:67], v[64:67], v[72:75], v[28:31]
	ds_read2_b64 v[72:75], v89 offset0:8 offset1:9
	s_waitcnt lgkmcnt(0)
	v_mfma_f32_16x16x32_bf16 v[28:31], v[72:75], v[76:79], v[0:3]
	s_nop 2
	ds_read2_b64 v[0:3], v63 offset1:1
	s_waitcnt lgkmcnt(0)
	v_mfma_f32_16x16x32_bf16 v[24:27], v[0:3], v[76:79], v[4:7]
	s_nop 2
	ds_read2_b64 v[4:7], v62 offset1:1
	s_waitcnt lgkmcnt(0)
	v_mfma_f32_16x16x32_bf16 v[20:23], v[4:7], v[76:79], v[8:11]
	v_mfma_f32_16x16x32_bf16 v[16:19], v[94:97], v[76:79], v[12:15]
	global_load_dwordx4 v[76:79], v[44:45], off offset:64
	s_waitcnt vmcnt(0) lgkmcnt(0)
	v_mfma_f32_16x16x32_bf16 v[12:15], v[72:75], v[76:79], v[68:71]
	v_mov_b32_e32 v72, v86
	v_mfma_f32_16x16x32_bf16 v[8:11], v[0:3], v[76:79], v[80:83]
	v_mfma_f32_16x16x32_bf16 v[4:7], v[4:7], v[76:79], v[90:93]
	v_mfma_f32_16x16x32_bf16 v[0:3], v[94:97], v[76:79], v[64:67]
	s_branch .LBB0_457

.LBB0_467:
	global_load_dwordx2 v[30:31], v[18:19], off offset:512
	global_load_dwordx2 v[24:25], v[18:19], off
	global_load_dwordx4 v[0:3], v[8:9], off
	global_load_dwordx4 v[4:7], v[10:11], off
	global_load_dword v20, v[12:13], off
	global_load_dword v22, v[14:15], off
	s_add_i32 s0, s0, s80
	s_cmpk_lt_i32 s0, 0x80
	s_waitcnt vmcnt(0) lgkmcnt(0)
	v_lshlrev_b32_e32 v26, 16, v30
	v_mul_f32_e32 v21, 0x3d372713, v26
	v_mul_f32_e32 v21, v21, v26
	v_mov_b32_e32 v23, v26
	v_fmac_f32_e32 v23, v21, v23
	v_mul_f32_e32 v21, 0x3f4c422a, v23
	v_add_f32_e32 v21, v21, v21
	v_and_b32_e32 v27, 0xffff0000, v30
	v_mul_f32_e32 v21, 0xbfb8aa3b, v21
	v_exp_f32_e32 v28, v21
	v_mul_f32_e32 v21, 0x3d372713, v27
	v_mul_f32_e32 v21, v21, v27
	v_mov_b32_e32 v23, v27
	v_fmac_f32_e32 v23, v21, v23
	v_mul_f32_e32 v21, 0x3f4c422a, v23
	v_add_f32_e32 v21, v21, v21
	v_mul_f32_e32 v21, 0xbfb8aa3b, v21
	v_exp_f32_e32 v29, v21
	s_nop 0
	v_pk_add_f32 v[28:29], v[28:29], 1.0 op_sel_hi:[1,0]
	s_nop 0
	v_rcp_f32_e32 v29, v29
	v_rcp_f32_e32 v28, v28
	v_lshlrev_b32_e32 v30, 16, v31
	v_pk_mul_f32 v[32:33], v[28:29], v[26:27]
	v_mul_f32_e32 v23, 0x3d372713, v30
	v_add_f32_e32 v21, 0, v32
	v_mul_f32_e32 v23, v23, v30
	v_mov_b32_e32 v32, v30
	v_fmac_f32_e32 v32, v23, v32
	v_mul_f32_e32 v23, 0x3f4c422a, v32
	v_add_f32_e32 v23, v23, v23
	v_and_b32_e32 v31, 0xffff0000, v31
	v_mul_f32_e32 v23, 0xbfb8aa3b, v23
	v_exp_f32_e32 v32, v23
	v_mul_f32_e32 v23, 0x3d372713, v31
	v_add_f32_e32 v21, v33, v21
	v_mul_f32_e32 v23, v23, v31
	v_mov_b32_e32 v33, v31
	v_fmac_f32_e32 v33, v23, v33
	v_mul_f32_e32 v23, 0x3f4c422a, v33
	v_add_f32_e32 v23, v23, v23
	v_mul_f32_e32 v23, 0xbfb8aa3b, v23
	v_exp_f32_e32 v33, v23
	s_nop 0
	v_pk_add_f32 v[32:33], v[32:33], 1.0 op_sel_hi:[1,0]
	s_nop 0
	v_rcp_f32_e32 v33, v33
	v_rcp_f32_e32 v32, v32
	s_nop 0
	v_pk_mul_f32 v[34:35], v[32:33], v[30:31]
	s_nop 0
	v_add_f32_e32 v21, v34, v21
	v_add_f32_e32 v21, v35, v21
	s_nop 1
	v_add_f32_dpp v21, v21, v21 quad_perm:[1,0,3,2] row_mask:0xf bank_mask:0xf bound_ctrl:1
	s_nop 1
	v_add_f32_dpp v21, v21, v21 quad_perm:[2,3,0,1] row_mask:0xf bank_mask:0xf bound_ctrl:1
	s_nop 1
	v_add_f32_dpp v21, v21, v21 row_half_mirror row_mask:0xf bank_mask:0xf bound_ctrl:1
	s_nop 1
	v_add_f32_dpp v21, v21, v21 row_mirror row_mask:0xf bank_mask:0xf bound_ctrl:1
	s_nop 0
	v_readlane_b32 s1, v21, 16
	v_readlane_b32 s4, v21, 48
	v_readlane_b32 s2, v21, 0
	v_readlane_b32 s3, v21, 32
	v_mov_b32_e32 v34, s1
	v_mov_b32_e32 v35, s4
	v_pk_add_f32 v[34:35], s[2:3], v[34:35]
	s_nop 0
	v_add_f32_e32 v21, v34, v35
	v_mul_f32_e32 v34, 0x3b800000, v21
	v_pk_fma_f32 v[26:27], v[28:29], v[26:27], v[34:35] op_sel_hi:[1,1,0] neg_lo:[0,0,1] neg_hi:[0,0,1]
	v_pk_fma_f32 v[30:31], v[32:33], v[30:31], v[34:35] op_sel_hi:[1,1,0] neg_lo:[0,0,1] neg_hi:[0,0,1]
	v_pk_mul_f32 v[28:29], v[26:27], v[26:27]
	v_pk_mul_f32 v[32:33], v[30:31], v[30:31]
	v_add_f32_e32 v21, v28, v29
	v_add_f32_e32 v21, v32, v21
	v_add_f32_e32 v21, v33, v21
	s_nop 1
	v_add_f32_dpp v21, v21, v21 quad_perm:[1,0,3,2] row_mask:0xf bank_mask:0xf bound_ctrl:1
	s_nop 1
	v_add_f32_dpp v21, v21, v21 quad_perm:[2,3,0,1] row_mask:0xf bank_mask:0xf bound_ctrl:1
	s_nop 1
	v_add_f32_dpp v21, v21, v21 row_half_mirror row_mask:0xf bank_mask:0xf bound_ctrl:1
	s_nop 1
	v_add_f32_dpp v21, v21, v21 row_mirror row_mask:0xf bank_mask:0xf bound_ctrl:1
	s_nop 0
	v_readlane_b32 s1, v21, 16
	v_readlane_b32 s4, v21, 48
	v_readlane_b32 s2, v21, 0
	v_readlane_b32 s3, v21, 32
	v_mov_b32_e32 v28, s1
	v_mov_b32_e32 v29, s4
	v_pk_add_f32 v[28:29], s[2:3], v[28:29]
	s_nop 0
	v_add_f32_e32 v21, v28, v29
	v_fmamk_f32 v21, v21, 0x3b800000, v238
	v_cmp_gt_f32_e32 vcc, s5, v21
	v_mul_f32_e32 v23, 0x4b800000, v21
	s_nop 0
	v_cndmask_b32_e32 v21, v21, v23, vcc
	v_rsq_f32_e32 v21, v21
	s_nop 0
	v_mul_f32_e32 v23, 0x45800000, v21
	v_cndmask_b32_e32 v28, v21, v23, vcc
	v_pk_mul_f32 v[26:27], v[26:27], v[28:29] op_sel_hi:[1,0]
	s_nop 0
	v_pk_fma_f32 v[0:1], v[0:1], v[26:27], v[4:5]
	v_lshlrev_b32_e32 v4, 16, v24
	v_mul_f32_e32 v21, 0x3d372713, v4
	v_mul_f32_e32 v21, v21, v4
	v_mov_b32_e32 v23, v4
	v_fmac_f32_e32 v23, v21, v23
	v_mul_f32_e32 v21, 0x3f4c422a, v23
	v_add_f32_e32 v21, v21, v21
	v_and_b32_e32 v5, 0xffff0000, v24
	v_mul_f32_e32 v21, 0xbfb8aa3b, v21
	v_exp_f32_e32 v26, v21
	v_mul_f32_e32 v21, 0x3d372713, v5
	v_mul_f32_e32 v21, v21, v5
	v_mov_b32_e32 v23, v5
	v_fmac_f32_e32 v23, v21, v23
	v_mul_f32_e32 v21, 0x3f4c422a, v23
	v_add_f32_e32 v21, v21, v21
	v_mul_f32_e32 v21, 0xbfb8aa3b, v21
	v_exp_f32_e32 v27, v21
	s_nop 0
	v_pk_add_f32 v[26:27], v[26:27], 1.0 op_sel_hi:[1,0]
	s_nop 0
	v_rcp_f32_e32 v27, v27
	v_rcp_f32_e32 v26, v26
	s_nop 0
	v_pk_mul_f32 v[4:5], v[26:27], v[4:5]
	v_pk_fma_f32 v[26:27], v[20:21], v[0:1], v[22:23] op_sel_hi:[0,1,0]
	v_pk_mul_f32 v[4:5], v[4:5], v[26:27]
	v_pk_mul_f32 v[26:27], v[30:31], v[28:29] op_sel_hi:[1,0]
	s_nop 0
	v_pk_fma_f32 v[2:3], v[2:3], v[26:27], v[6:7]
	v_lshlrev_b32_e32 v6, 16, v25
	v_mul_f32_e32 v21, 0x3d372713, v6
	v_mul_f32_e32 v21, v21, v6
	v_mov_b32_e32 v23, v6
	v_fmac_f32_e32 v23, v21, v23
	v_mul_f32_e32 v21, 0x3f4c422a, v23
	v_add_f32_e32 v21, v21, v21
	v_and_b32_e32 v7, 0xffff0000, v25
	v_mul_f32_e32 v21, 0xbfb8aa3b, v21
	v_exp_f32_e32 v24, v21
	v_mul_f32_e32 v21, 0x3d372713, v7
	v_mul_f32_e32 v21, v21, v7
	v_mov_b32_e32 v23, v7
	v_fmac_f32_e32 v23, v21, v23
	v_mul_f32_e32 v21, 0x3f4c422a, v23
	v_add_f32_e32 v21, v21, v21
	v_mul_f32_e32 v21, 0xbfb8aa3b, v21
	v_exp_f32_e32 v25, v21
	global_store_dwordx4 v[16:17], v[0:3], off
	v_lshl_add_u64 v[16:17], v[16:17], 0, s[6:7]
	v_pk_add_f32 v[24:25], v[24:25], 1.0 op_sel_hi:[1,0]
	s_nop 0
	v_cvt_pk_bf16_f32 v0, v4, v5
	v_rcp_f32_e32 v25, v25
	v_rcp_f32_e32 v24, v24
	s_nop 0
	v_pk_mul_f32 v[6:7], v[24:25], v[6:7]
	v_pk_fma_f32 v[20:21], v[20:21], v[2:3], v[22:23] op_sel_hi:[0,1,0]
	v_pk_mul_f32 v[6:7], v[6:7], v[20:21]
	s_nop 0
	v_cvt_pk_bf16_f32 v1, v6, v7
	global_store_dwordx2 v[18:19], v[0:1], off offset:1536
	v_lshl_add_u64 v[18:19], v[18:19], 0, s[8:9]
	s_cbranch_scc1 .LBB0_467
	s_mov_b32 s83, 0x800000

.LBB0_472:
	s_ashr_i32 s4, s36, 4
	s_add_i32 s2, s4, 0x4000
	s_bfe_u32 s58, s36, 0x20002
	s_ashr_i32 s3, s2, 31
	s_mul_i32 s1, s2, 0xc00
	s_mul_hi_i32 s0, s2, 0xc00
	s_add_u32 s1, s37, s1
	s_addc_u32 s5, s38, s0
	s_lshl_b32 s0, s58, 7
	s_add_u32 s0, s1, s0
	s_addc_u32 s1, s5, 0
	v_lshlrev_b32_e32 v194, 1, v8
	v_lshl_add_u64 v[0:1], s[0:1], 0, v[194:195]
	global_load_ushort v2, v[0:1], off
	s_add_i32 s4, s4, s39
	s_ashr_i32 s5, s4, 31
	s_lshl_b64 s[34:35], s[4:5], 16
	s_lshl_b32 s4, s58, 14
	s_and_b32 s57, s56, 48
	s_or_b32 s34, s34, s4
	v_lshl_add_u64 v[12:13], v[10:11], 0, s[34:35]
	s_lshl_b32 s30, s57, 8
	s_mov_b32 s31, s43
	s_lshl_b32 s4, s57, 1
	s_add_u32 s0, s0, s4
	s_addc_u32 s1, s1, 0
	s_mov_b32 s21, s43
	s_mov_b32 s29, s43
	s_mov_b32 s25, s43
	s_mov_b32 s7, s43
	s_mov_b32 s23, s43
	s_mov_b32 s27, s43
	s_mov_b32 s19, s43
	s_mov_b32 s17, s43
	s_mov_b32 s15, s43
	s_mov_b32 s13, s43
	s_mov_b32 s11, s43
	s_mov_b32 s9, s43
	s_mov_b32 s5, s43
	v_lshlrev_b32_e32 v194, 2, v8
	s_waitcnt vmcnt(0) lgkmcnt(0)
	v_lshlrev_b32_e32 v9, 16, v2
	global_load_ushort v2, v[0:1], off offset:512
	s_waitcnt vmcnt(0) lgkmcnt(0)
	v_lshlrev_b32_e32 v14, 16, v2
	global_load_ushort v2, v[0:1], off offset:1536
	s_waitcnt vmcnt(0) lgkmcnt(0)
	v_lshlrev_b32_e32 v16, 16, v2
	global_load_ushort v2, v[0:1], off offset:2048
	s_waitcnt vmcnt(0) lgkmcnt(0)
	v_lshlrev_b32_e32 v15, 16, v2
	global_load_ushort v0, v[0:1], off offset:2560
	s_waitcnt vmcnt(0) lgkmcnt(0)
	v_lshlrev_b32_e32 v0, 16, v0
	v_mul_f32_e32 v33, 0x3fb8aa3b, v0
	v_lshl_add_u64 v[0:1], v[12:13], 0, s[30:31]
	global_load_dword v34, v[0:1], off
	v_mov_b64_e32 v[0:1], s[0:1]
	s_or_b32 s0, s57, 1
	s_lshl_b32 s42, s0, 8
	s_or_b32 s0, s57, 2
	s_lshl_b32 s20, s0, 8
	s_or_b32 s0, s57, 3
	s_lshl_b32 s28, s0, 8
	s_or_b32 s0, s57, 4
	v_lshl_add_u64 v[2:3], v[12:13], 0, s[42:43]
	s_lshl_b32 s24, s0, 8
	s_or_b32 s0, s57, 5
	global_load_dword v32, v[2:3], off
	v_lshl_add_u64 v[2:3], v[12:13], 0, s[20:21]
	s_lshl_b32 s6, s0, 8
	s_or_b32 s0, s57, 6
	global_load_dword v31, v[2:3], off
	v_lshl_add_u64 v[2:3], v[12:13], 0, s[28:29]
	s_lshl_b32 s22, s0, 8
	s_or_b32 s0, s57, 7
	global_load_dword v30, v[2:3], off
	v_lshl_add_u64 v[2:3], v[12:13], 0, s[24:25]
	s_lshl_b32 s26, s0, 8
	s_or_b32 s0, s57, 8
	global_load_dwordx4 v[4:7], v[0:1], off offset:1024
	global_load_dword v29, v[2:3], off
	v_lshl_add_u64 v[2:3], v[12:13], 0, s[6:7]
	s_lshl_b32 s18, s0, 8
	s_or_b32 s0, s57, 9
	global_load_dword v28, v[2:3], off
	v_lshl_add_u64 v[2:3], v[12:13], 0, s[22:23]
	s_lshl_b32 s16, s0, 8
	s_or_b32 s0, s57, 10
	global_load_dword v27, v[2:3], off
	v_lshl_add_u64 v[2:3], v[12:13], 0, s[26:27]
	s_lshl_b32 s14, s0, 8
	s_or_b32 s0, s57, 11
	global_load_dword v26, v[2:3], off
	v_lshl_add_u64 v[2:3], v[12:13], 0, s[18:19]
	v_lshl_add_u64 v[18:19], v[12:13], 0, s[16:17]
	s_lshl_b32 s12, s0, 8
	s_or_b32 s0, s57, 12
	global_load_dword v25, v[2:3], off
	s_nop 0
	global_load_dwordx4 v[0:3], v[0:1], off offset:1040
	s_lshl_b32 s10, s0, 8
	global_load_dword v24, v[18:19], off
	v_lshl_add_u64 v[18:19], v[12:13], 0, s[14:15]
	s_or_b32 s0, s57, 13
	global_load_dword v23, v[18:19], off
	v_lshl_add_u64 v[18:19], v[12:13], 0, s[12:13]
	s_lshl_b32 s8, s0, 8
	s_or_b32 s0, s57, 14
	global_load_dword v22, v[18:19], off
	v_lshl_add_u64 v[18:19], v[12:13], 0, s[10:11]
	s_lshl_b32 s4, s0, 8
	s_or_b32 s0, s57, 15
	global_load_dword v21, v[18:19], off
	v_lshl_add_u64 v[18:19], v[12:13], 0, s[8:9]
	s_lshl_b32 s0, s0, 8
	s_mov_b32 s1, s43
	global_load_dword v20, v[18:19], off
	v_lshl_add_u64 v[18:19], v[12:13], 0, s[4:5]
	v_lshl_add_u64 v[12:13], v[12:13], 0, s[0:1]
	global_load_dword v19, v[18:19], off
	s_add_u32 s34, s94, s34
	global_load_dword v17, v[12:13], off
	s_addc_u32 s35, s95, s35
	s_lshl_b64 s[2:3], s[2:3], 10
	s_add_u32 s1, s40, s2
	v_lshl_add_u64 v[12:13], s[34:35], 0, v[194:195]
	s_mov_b64 s[34:35], 0x4280000
	s_addc_u32 s2, s41, s3
	s_lshl_b32 s3, s58, 8
	v_lshl_add_u64 v[12:13], v[12:13], 0, s[34:35]
	s_add_u32 s34, s1, s3
	s_addc_u32 s35, s2, 0
	v_exp_f32_e32 v18, v33
	s_waitcnt vmcnt(0)
	v_mul_f32_e32 v35, v34, v16
	s_nop 1
	v_mov_b32_dpp v35, v35 quad_perm:[1,0,3,2] row_mask:0xf bank_mask:0xf bound_ctrl:1
	v_fmac_f32_e32 v35, v34, v16
	s_waitcnt lgkmcnt(0)
	v_lshlrev_b32_e32 v33, 16, v4
	v_add_f32_dpp v35, v35, v35 quad_perm:[2,3,0,1] row_mask:0xf bank_mask:0xf bound_ctrl:1
	s_nop 1
	v_add_f32_dpp v35, v35, v35 row_half_mirror row_mask:0xf bank_mask:0xf bound_ctrl:1
	s_nop 1
	v_add_f32_dpp v35, v35, v35 row_mirror row_mask:0xf bank_mask:0xf bound_ctrl:1
	s_nop 0
	v_readlane_b32 s2, v35, 16
	v_readlane_b32 s5, v35, 48
	v_readlane_b32 s1, v35, 0
	v_readlane_b32 s3, v35, 32
	v_mov_b32_e32 v35, s2
	v_mov_b32_e32 v36, s5
	v_add_f32_e32 v35, s1, v35
	v_add_f32_e32 v36, s3, v36
	v_add_f32_e32 v35, v35, v36
	v_mul_f32_e32 v35, v35, v15
	v_fma_f32 v36, v34, v18, -v35
	v_fmac_f32_e32 v36, v14, v33
	v_mul_f32_e32 v33, v36, v9
	v_lshl_add_u64 v[34:35], v[12:13], 0, s[30:31]
	global_store_dword v[34:35], v36, off
	v_mov_b32_dpp v33, v33 quad_perm:[1,0,3,2] row_mask:0xf bank_mask:0xf bound_ctrl:1
	v_fmac_f32_e32 v33, v36, v9
	s_nop 1
	v_add_f32_dpp v33, v33, v33 quad_perm:[2,3,0,1] row_mask:0xf bank_mask:0xf bound_ctrl:1
	s_nop 1
	v_add_f32_dpp v33, v33, v33 row_half_mirror row_mask:0xf bank_mask:0xf bound_ctrl:1
	s_nop 1
	v_add_f32_dpp v33, v33, v33 row_mirror row_mask:0xf bank_mask:0xf bound_ctrl:1
	s_nop 0
	v_readlane_b32 s2, v33, 0
	v_readlane_b32 s1, v33, 16
	v_readlane_b32 s3, v33, 32
	v_readlane_b32 s5, v33, 48
	s_and_saveexec_b64 s[30:31], vcc
	s_cbranch_execz .LBB0_474
	s_lshl_b32 s7, s57, 2
	s_add_u32 s58, s34, s7
	v_mov_b32_e32 v34, s1
	v_mov_b32_e32 v35, s5
	s_addc_u32 s59, s35, 0
	v_pk_add_f32 v[34:35], s[2:3], v[34:35]
	s_nop 0
	v_add_f32_e32 v33, v34, v35
	v_mov_b64_e32 v[34:35], s[58:59]
	global_store_dword v[34:35], v33, off
.LBB0_474:
	s_or_b64 exec, exec, s[30:31]
	v_mul_f32_e32 v33, v32, v16
	v_and_b32_e32 v4, 0xffff0000, v4
	s_nop 0
	v_mov_b32_dpp v33, v33 quad_perm:[1,0,3,2] row_mask:0xf bank_mask:0xf bound_ctrl:1
	v_fmac_f32_e32 v33, v32, v16
	s_nop 1
	v_add_f32_dpp v33, v33, v33 quad_perm:[2,3,0,1] row_mask:0xf bank_mask:0xf bound_ctrl:1
	s_nop 1
	v_add_f32_dpp v33, v33, v33 row_half_mirror row_mask:0xf bank_mask:0xf bound_ctrl:1
	s_nop 1
	v_add_f32_dpp v33, v33, v33 row_mirror row_mask:0xf bank_mask:0xf bound_ctrl:1
	s_nop 0
	v_readlane_b32 s2, v33, 16
	v_readlane_b32 s5, v33, 48
	v_readlane_b32 s1, v33, 0
	v_readlane_b32 s3, v33, 32
	v_mov_b32_e32 v33, s2
	v_mov_b32_e32 v34, s5
	v_add_f32_e32 v33, s1, v33
	v_add_f32_e32 v34, s3, v34
	v_add_f32_e32 v33, v33, v34
	v_mul_f32_e32 v33, v33, v15
	v_fma_f32 v34, v32, v18, -v33
	v_fmac_f32_e32 v34, v14, v4
	v_mul_f32_e32 v4, v34, v9
	v_lshl_add_u64 v[32:33], v[12:13], 0, s[42:43]
	global_store_dword v[32:33], v34, off
	v_mov_b32_dpp v4, v4 quad_perm:[1,0,3,2] row_mask:0xf bank_mask:0xf bound_ctrl:1
	v_fmac_f32_e32 v4, v34, v9
	s_nop 1
	v_add_f32_dpp v4, v4, v4 quad_perm:[2,3,0,1] row_mask:0xf bank_mask:0xf bound_ctrl:1
	s_nop 1
	v_add_f32_dpp v4, v4, v4 row_half_mirror row_mask:0xf bank_mask:0xf bound_ctrl:1
	s_nop 1
	v_add_f32_dpp v4, v4, v4 row_mirror row_mask:0xf bank_mask:0xf bound_ctrl:1
	s_nop 0
	v_readlane_b32 s2, v4, 0
	v_readlane_b32 s1, v4, 16
	v_readlane_b32 s3, v4, 32
	v_readlane_b32 s5, v4, 48
	s_and_saveexec_b64 s[30:31], vcc
	s_cbranch_execz .LBB0_476
	s_lshl_b32 s7, s57, 2
	s_add_u32 s58, s34, s7
	v_mov_b32_e32 v32, s1
	v_mov_b32_e32 v33, s5
	s_addc_u32 s59, s35, 0
	v_pk_add_f32 v[32:33], s[2:3], v[32:33]
	s_nop 0
	v_add_f32_e32 v4, v32, v33
	v_mov_b64_e32 v[32:33], s[58:59]
	global_store_dword v[32:33], v4, off offset:4
.LBB0_476:
	s_or_b64 exec, exec, s[30:31]
	v_mul_f32_e32 v32, v31, v16
	v_lshlrev_b32_e32 v4, 16, v5
	s_mov_b32 s21, s43
	v_mov_b32_dpp v32, v32 quad_perm:[1,0,3,2] row_mask:0xf bank_mask:0xf bound_ctrl:1
	v_fmac_f32_e32 v32, v31, v16
	s_nop 1
	v_add_f32_dpp v32, v32, v32 quad_perm:[2,3,0,1] row_mask:0xf bank_mask:0xf bound_ctrl:1
	s_nop 1
	v_add_f32_dpp v32, v32, v32 row_half_mirror row_mask:0xf bank_mask:0xf bound_ctrl:1
	s_nop 1
	v_add_f32_dpp v32, v32, v32 row_mirror row_mask:0xf bank_mask:0xf bound_ctrl:1
	s_nop 0
	v_readlane_b32 s2, v32, 16
	v_readlane_b32 s5, v32, 48
	v_readlane_b32 s1, v32, 0
	v_readlane_b32 s3, v32, 32
	v_mov_b32_e32 v32, s2
	v_mov_b32_e32 v33, s5
	v_add_f32_e32 v32, s1, v32
	v_add_f32_e32 v33, s3, v33
	v_add_f32_e32 v32, v32, v33
	v_mul_f32_e32 v32, v32, v15
	v_fma_f32 v31, v18, v31, -v32
	v_fmac_f32_e32 v31, v14, v4
	v_mul_f32_e32 v4, v31, v9
	v_lshl_add_u64 v[32:33], v[12:13], 0, s[20:21]
	global_store_dword v[32:33], v31, off
	v_mov_b32_dpp v4, v4 quad_perm:[1,0,3,2] row_mask:0xf bank_mask:0xf bound_ctrl:1
	v_fmac_f32_e32 v4, v31, v9
	s_nop 1
	v_add_f32_dpp v4, v4, v4 quad_perm:[2,3,0,1] row_mask:0xf bank_mask:0xf bound_ctrl:1
	s_nop 1
	v_add_f32_dpp v4, v4, v4 row_half_mirror row_mask:0xf bank_mask:0xf bound_ctrl:1
	s_nop 1
	v_add_f32_dpp v4, v4, v4 row_mirror row_mask:0xf bank_mask:0xf bound_ctrl:1
	s_nop 0
	v_readlane_b32 s2, v4, 0
	v_readlane_b32 s1, v4, 16
	v_readlane_b32 s3, v4, 32
	v_readlane_b32 s5, v4, 48
	s_and_saveexec_b64 s[20:21], vcc
	s_cbranch_execz .LBB0_478
	s_lshl_b32 s7, s57, 2
	s_add_u32 s30, s34, s7
	v_mov_b32_e32 v32, s1
	v_mov_b32_e32 v33, s5
	s_addc_u32 s31, s35, 0
	v_pk_add_f32 v[32:33], s[2:3], v[32:33]
	s_nop 0
	v_add_f32_e32 v4, v32, v33
	v_mov_b64_e32 v[32:33], s[30:31]
	global_store_dword v[32:33], v4, off offset:8
.LBB0_478:
	s_or_b64 exec, exec, s[20:21]
	v_and_b32_e32 v4, 0xffff0000, v5
	v_mul_f32_e32 v5, v30, v16
	s_mov_b32 s29, s43
	s_nop 0
	v_mov_b32_dpp v5, v5 quad_perm:[1,0,3,2] row_mask:0xf bank_mask:0xf bound_ctrl:1
	v_fmac_f32_e32 v5, v30, v16
	s_nop 1
	v_add_f32_dpp v5, v5, v5 quad_perm:[2,3,0,1] row_mask:0xf bank_mask:0xf bound_ctrl:1
	s_nop 1
	v_add_f32_dpp v5, v5, v5 row_half_mirror row_mask:0xf bank_mask:0xf bound_ctrl:1
	s_nop 1
	v_add_f32_dpp v5, v5, v5 row_mirror row_mask:0xf bank_mask:0xf bound_ctrl:1
	s_nop 0
	v_readlane_b32 s2, v5, 16
	v_readlane_b32 s5, v5, 48
	v_readlane_b32 s1, v5, 0
	v_readlane_b32 s3, v5, 32
	v_mov_b32_e32 v5, s2
	v_mov_b32_e32 v31, s5
	v_add_f32_e32 v5, s1, v5
	v_add_f32_e32 v31, s3, v31
	v_add_f32_e32 v5, v5, v31
	v_mul_f32_e32 v5, v5, v15
	v_fma_f32 v30, v18, v30, -v5
	v_fmac_f32_e32 v30, v14, v4
	v_mul_f32_e32 v4, v30, v9
	s_nop 1
	v_mov_b32_dpp v4, v4 quad_perm:[1,0,3,2] row_mask:0xf bank_mask:0xf bound_ctrl:1
	v_fmac_f32_e32 v4, v30, v9
	s_nop 1
	v_add_f32_dpp v4, v4, v4 quad_perm:[2,3,0,1] row_mask:0xf bank_mask:0xf bound_ctrl:1
	s_nop 1
	v_add_f32_dpp v4, v4, v4 row_half_mirror row_mask:0xf bank_mask:0xf bound_ctrl:1
	s_nop 1
	v_add_f32_dpp v4, v4, v4 row_mirror row_mask:0xf bank_mask:0xf bound_ctrl:1
	s_nop 0
	v_readlane_b32 s2, v4, 0
	v_readlane_b32 s1, v4, 16
	v_readlane_b32 s3, v4, 32
	v_readlane_b32 s5, v4, 48
	v_lshl_add_u64 v[4:5], v[12:13], 0, s[28:29]
	global_store_dword v[4:5], v30, off
	s_and_saveexec_b64 s[20:21], vcc
	s_cbranch_execz .LBB0_480
	s_lshl_b32 s7, s57, 2
	s_add_u32 s28, s34, s7
	v_mov_b32_e32 v4, s1
	v_mov_b32_e32 v5, s5
	s_addc_u32 s29, s35, 0
	v_pk_add_f32 v[4:5], s[2:3], v[4:5]
	s_nop 0
	v_add_f32_e32 v30, v4, v5
	v_mov_b64_e32 v[4:5], s[28:29]
	global_store_dword v[4:5], v30, off offset:12
.LBB0_480:
	s_or_b64 exec, exec, s[20:21]
	v_mul_f32_e32 v5, v29, v16
	v_lshlrev_b32_e32 v4, 16, v6
	s_mov_b32 s25, s43
	v_mov_b32_dpp v5, v5 quad_perm:[1,0,3,2] row_mask:0xf bank_mask:0xf bound_ctrl:1
	v_fmac_f32_e32 v5, v29, v16
	s_nop 1
	v_add_f32_dpp v5, v5, v5 quad_perm:[2,3,0,1] row_mask:0xf bank_mask:0xf bound_ctrl:1
	s_nop 1
	v_add_f32_dpp v5, v5, v5 row_half_mirror row_mask:0xf bank_mask:0xf bound_ctrl:1
	s_nop 1
	v_add_f32_dpp v5, v5, v5 row_mirror row_mask:0xf bank_mask:0xf bound_ctrl:1
	s_nop 0
	v_readlane_b32 s2, v5, 16
	v_readlane_b32 s5, v5, 48
	v_readlane_b32 s1, v5, 0
	v_readlane_b32 s3, v5, 32
	v_mov_b32_e32 v5, s2
	v_mov_b32_e32 v30, s5
	v_add_f32_e32 v5, s1, v5
	v_add_f32_e32 v30, s3, v30
	v_add_f32_e32 v5, v5, v30
	v_mul_f32_e32 v5, v5, v15
	v_fma_f32 v29, v18, v29, -v5
	v_fmac_f32_e32 v29, v14, v4
	v_mul_f32_e32 v4, v29, v9
	s_nop 1
	v_mov_b32_dpp v4, v4 quad_perm:[1,0,3,2] row_mask:0xf bank_mask:0xf bound_ctrl:1
	v_fmac_f32_e32 v4, v29, v9
	s_nop 1
	v_add_f32_dpp v4, v4, v4 quad_perm:[2,3,0,1] row_mask:0xf bank_mask:0xf bound_ctrl:1
	s_nop 1
	v_add_f32_dpp v4, v4, v4 row_half_mirror row_mask:0xf bank_mask:0xf bound_ctrl:1
	s_nop 1
	v_add_f32_dpp v4, v4, v4 row_mirror row_mask:0xf bank_mask:0xf bound_ctrl:1
	s_nop 0
	v_readlane_b32 s2, v4, 0
	v_readlane_b32 s1, v4, 16
	v_readlane_b32 s3, v4, 32
	v_readlane_b32 s5, v4, 48
	v_lshl_add_u64 v[4:5], v[12:13], 0, s[24:25]
	global_store_dword v[4:5], v29, off
	s_and_saveexec_b64 s[20:21], vcc
	s_cbranch_execz .LBB0_482
	s_lshl_b32 s7, s57, 2
	s_add_u32 s24, s34, s7
	v_mov_b32_e32 v4, s1
	v_mov_b32_e32 v5, s5
	s_addc_u32 s25, s35, 0
	v_pk_add_f32 v[4:5], s[2:3], v[4:5]
	s_nop 0
	v_add_f32_e32 v29, v4, v5
	v_mov_b64_e32 v[4:5], s[24:25]
	global_store_dword v[4:5], v29, off offset:16
.LBB0_482:
	s_or_b64 exec, exec, s[20:21]
	v_mul_f32_e32 v5, v28, v16
	v_and_b32_e32 v4, 0xffff0000, v6
	s_mov_b32 s7, s43
	v_mov_b32_dpp v5, v5 quad_perm:[1,0,3,2] row_mask:0xf bank_mask:0xf bound_ctrl:1
	v_fmac_f32_e32 v5, v28, v16
	s_nop 1
	v_add_f32_dpp v5, v5, v5 quad_perm:[2,3,0,1] row_mask:0xf bank_mask:0xf bound_ctrl:1
	s_nop 1
	v_add_f32_dpp v5, v5, v5 row_half_mirror row_mask:0xf bank_mask:0xf bound_ctrl:1
	s_nop 1
	v_add_f32_dpp v5, v5, v5 row_mirror row_mask:0xf bank_mask:0xf bound_ctrl:1
	s_nop 0
	v_readlane_b32 s2, v5, 16
	v_readlane_b32 s5, v5, 48
	v_readlane_b32 s1, v5, 0
	v_readlane_b32 s3, v5, 32
	v_mov_b32_e32 v5, s2
	v_mov_b32_e32 v6, s5
	v_add_f32_e32 v5, s1, v5
	v_add_f32_e32 v6, s3, v6
	v_add_f32_e32 v5, v5, v6
	v_mul_f32_e32 v5, v5, v15
	v_fma_f32 v6, v18, v28, -v5
	v_fmac_f32_e32 v6, v14, v4
	v_mul_f32_e32 v4, v6, v9
	s_nop 1
	v_mov_b32_dpp v4, v4 quad_perm:[1,0,3,2] row_mask:0xf bank_mask:0xf bound_ctrl:1
	v_fmac_f32_e32 v4, v6, v9
	s_nop 1
	v_add_f32_dpp v4, v4, v4 quad_perm:[2,3,0,1] row_mask:0xf bank_mask:0xf bound_ctrl:1
	s_nop 1
	v_add_f32_dpp v4, v4, v4 row_half_mirror row_mask:0xf bank_mask:0xf bound_ctrl:1
	s_nop 1
	v_add_f32_dpp v4, v4, v4 row_mirror row_mask:0xf bank_mask:0xf bound_ctrl:1
	s_nop 0
	v_readlane_b32 s2, v4, 0
	v_readlane_b32 s1, v4, 16
	v_readlane_b32 s3, v4, 32
	v_readlane_b32 s5, v4, 48
	v_lshl_add_u64 v[4:5], v[12:13], 0, s[6:7]
	global_store_dword v[4:5], v6, off
	s_and_saveexec_b64 s[6:7], vcc
	s_cbranch_execz .LBB0_484
	s_lshl_b32 s9, s57, 2
	s_add_u32 s20, s34, s9
	v_mov_b32_e32 v4, s1
	v_mov_b32_e32 v5, s5
	s_addc_u32 s21, s35, 0
	v_pk_add_f32 v[4:5], s[2:3], v[4:5]
	s_nop 0
	v_add_f32_e32 v6, v4, v5
	v_mov_b64_e32 v[4:5], s[20:21]
	global_store_dword v[4:5], v6, off offset:20
.LBB0_484:
	s_or_b64 exec, exec, s[6:7]
	v_mul_f32_e32 v5, v27, v16
	v_lshlrev_b32_e32 v4, 16, v7
	s_mov_b32 s23, s43
	v_mov_b32_dpp v5, v5 quad_perm:[1,0,3,2] row_mask:0xf bank_mask:0xf bound_ctrl:1
	v_fmac_f32_e32 v5, v27, v16
	s_nop 1
	v_add_f32_dpp v5, v5, v5 quad_perm:[2,3,0,1] row_mask:0xf bank_mask:0xf bound_ctrl:1
	s_nop 1
	v_add_f32_dpp v5, v5, v5 row_half_mirror row_mask:0xf bank_mask:0xf bound_ctrl:1
	s_nop 1
	v_add_f32_dpp v5, v5, v5 row_mirror row_mask:0xf bank_mask:0xf bound_ctrl:1
	s_nop 0
	v_readlane_b32 s2, v5, 16
	v_readlane_b32 s5, v5, 48
	v_readlane_b32 s1, v5, 0
	v_readlane_b32 s3, v5, 32
	v_mov_b32_e32 v5, s2
	v_mov_b32_e32 v6, s5
	v_add_f32_e32 v5, s1, v5
	v_add_f32_e32 v6, s3, v6
	v_add_f32_e32 v5, v5, v6
	v_mul_f32_e32 v5, v5, v15
	v_fma_f32 v6, v18, v27, -v5
	v_fmac_f32_e32 v6, v14, v4
	v_mul_f32_e32 v4, v6, v9
	s_nop 1
	v_mov_b32_dpp v4, v4 quad_perm:[1,0,3,2] row_mask:0xf bank_mask:0xf bound_ctrl:1
	v_fmac_f32_e32 v4, v6, v9
	s_nop 1
	v_add_f32_dpp v4, v4, v4 quad_perm:[2,3,0,1] row_mask:0xf bank_mask:0xf bound_ctrl:1
	s_nop 1
	v_add_f32_dpp v4, v4, v4 row_half_mirror row_mask:0xf bank_mask:0xf bound_ctrl:1
	s_nop 1
	v_add_f32_dpp v4, v4, v4 row_mirror row_mask:0xf bank_mask:0xf bound_ctrl:1
	s_nop 0
	v_readlane_b32 s2, v4, 0
	v_readlane_b32 s1, v4, 16
	v_readlane_b32 s3, v4, 32
	v_readlane_b32 s5, v4, 48
	v_lshl_add_u64 v[4:5], v[12:13], 0, s[22:23]
	global_store_dword v[4:5], v6, off
	s_and_saveexec_b64 s[6:7], vcc
	s_cbranch_execz .LBB0_486
	s_lshl_b32 s9, s57, 2
	s_add_u32 s20, s34, s9
	v_mov_b32_e32 v4, s1
	v_mov_b32_e32 v5, s5
	s_addc_u32 s21, s35, 0
	v_pk_add_f32 v[4:5], s[2:3], v[4:5]
	s_nop 0
	v_add_f32_e32 v6, v4, v5
	v_mov_b64_e32 v[4:5], s[20:21]
	global_store_dword v[4:5], v6, off offset:24
.LBB0_486:
	s_or_b64 exec, exec, s[6:7]
	v_mul_f32_e32 v5, v26, v16
	v_and_b32_e32 v4, 0xffff0000, v7
	s_mov_b32 s27, s43
	v_mov_b32_dpp v5, v5 quad_perm:[1,0,3,2] row_mask:0xf bank_mask:0xf bound_ctrl:1
	v_fmac_f32_e32 v5, v26, v16
	s_nop 1
	v_add_f32_dpp v5, v5, v5 quad_perm:[2,3,0,1] row_mask:0xf bank_mask:0xf bound_ctrl:1
	s_nop 1
	v_add_f32_dpp v5, v5, v5 row_half_mirror row_mask:0xf bank_mask:0xf bound_ctrl:1
	s_nop 1
	v_add_f32_dpp v5, v5, v5 row_mirror row_mask:0xf bank_mask:0xf bound_ctrl:1
	s_nop 0
	v_readlane_b32 s2, v5, 16
	v_readlane_b32 s5, v5, 48
	v_readlane_b32 s1, v5, 0
	v_readlane_b32 s3, v5, 32
	v_mov_b32_e32 v5, s2
	v_mov_b32_e32 v6, s5
	v_add_f32_e32 v5, s1, v5
	v_add_f32_e32 v6, s3, v6
	v_add_f32_e32 v5, v5, v6
	v_mul_f32_e32 v5, v5, v15
	v_fma_f32 v6, v18, v26, -v5
	v_fmac_f32_e32 v6, v14, v4
	v_mul_f32_e32 v4, v6, v9
	s_nop 1
	v_mov_b32_dpp v4, v4 quad_perm:[1,0,3,2] row_mask:0xf bank_mask:0xf bound_ctrl:1
	v_fmac_f32_e32 v4, v6, v9
	s_nop 1
	v_add_f32_dpp v4, v4, v4 quad_perm:[2,3,0,1] row_mask:0xf bank_mask:0xf bound_ctrl:1
	s_nop 1
	v_add_f32_dpp v4, v4, v4 row_half_mirror row_mask:0xf bank_mask:0xf bound_ctrl:1
	s_nop 1
	v_add_f32_dpp v4, v4, v4 row_mirror row_mask:0xf bank_mask:0xf bound_ctrl:1
	s_nop 0
	v_readlane_b32 s2, v4, 0
	v_readlane_b32 s1, v4, 16
	v_readlane_b32 s3, v4, 32
	v_readlane_b32 s5, v4, 48
	v_lshl_add_u64 v[4:5], v[12:13], 0, s[26:27]
	global_store_dword v[4:5], v6, off
	s_and_saveexec_b64 s[6:7], vcc
	s_cbranch_execz .LBB0_488
	s_lshl_b32 s9, s57, 2
	s_add_u32 s20, s34, s9
	v_mov_b32_e32 v4, s1
	v_mov_b32_e32 v5, s5
	s_addc_u32 s21, s35, 0
	v_pk_add_f32 v[4:5], s[2:3], v[4:5]
	s_nop 0
	v_add_f32_e32 v6, v4, v5
	v_mov_b64_e32 v[4:5], s[20:21]
	global_store_dword v[4:5], v6, off offset:28
.LBB0_488:
	s_or_b64 exec, exec, s[6:7]
	v_mul_f32_e32 v5, v25, v16
	v_lshlrev_b32_e32 v4, 16, v0
	s_mov_b32 s19, s43
	v_mov_b32_dpp v5, v5 quad_perm:[1,0,3,2] row_mask:0xf bank_mask:0xf bound_ctrl:1
	v_fmac_f32_e32 v5, v25, v16
	s_nop 1
	v_add_f32_dpp v5, v5, v5 quad_perm:[2,3,0,1] row_mask:0xf bank_mask:0xf bound_ctrl:1
	s_nop 1
	v_add_f32_dpp v5, v5, v5 row_half_mirror row_mask:0xf bank_mask:0xf bound_ctrl:1
	s_nop 1
	v_add_f32_dpp v5, v5, v5 row_mirror row_mask:0xf bank_mask:0xf bound_ctrl:1
	s_nop 0
	v_readlane_b32 s2, v5, 16
	v_readlane_b32 s5, v5, 48
	v_readlane_b32 s1, v5, 0
	v_readlane_b32 s3, v5, 32
	v_mov_b32_e32 v5, s2
	v_mov_b32_e32 v6, s5
	v_add_f32_e32 v5, s1, v5
	v_add_f32_e32 v6, s3, v6
	v_add_f32_e32 v5, v5, v6
	v_mul_f32_e32 v5, v5, v15
	v_fma_f32 v6, v18, v25, -v5
	v_fmac_f32_e32 v6, v14, v4
	v_mul_f32_e32 v4, v6, v9
	s_nop 1
	v_mov_b32_dpp v4, v4 quad_perm:[1,0,3,2] row_mask:0xf bank_mask:0xf bound_ctrl:1
	v_fmac_f32_e32 v4, v6, v9
	s_nop 1
	v_add_f32_dpp v4, v4, v4 quad_perm:[2,3,0,1] row_mask:0xf bank_mask:0xf bound_ctrl:1
	s_nop 1
	v_add_f32_dpp v4, v4, v4 row_half_mirror row_mask:0xf bank_mask:0xf bound_ctrl:1
	s_nop 1
	v_add_f32_dpp v4, v4, v4 row_mirror row_mask:0xf bank_mask:0xf bound_ctrl:1
	s_nop 0
	v_readlane_b32 s2, v4, 0
	v_readlane_b32 s1, v4, 16
	v_readlane_b32 s3, v4, 32
	v_readlane_b32 s5, v4, 48
	v_lshl_add_u64 v[4:5], v[12:13], 0, s[18:19]
	global_store_dword v[4:5], v6, off
	s_and_saveexec_b64 s[6:7], vcc
	s_cbranch_execz .LBB0_490
	s_lshl_b32 s9, s57, 2
	s_add_u32 s18, s34, s9
	v_mov_b32_e32 v4, s1
	v_mov_b32_e32 v5, s5
	s_addc_u32 s19, s35, 0
	v_pk_add_f32 v[4:5], s[2:3], v[4:5]
	s_nop 0
	v_add_f32_e32 v6, v4, v5
	v_mov_b64_e32 v[4:5], s[18:19]
	global_store_dword v[4:5], v6, off offset:32
.LBB0_490:
	s_or_b64 exec, exec, s[6:7]
	v_mul_f32_e32 v4, v24, v16
	v_and_b32_e32 v0, 0xffff0000, v0
	s_mov_b32 s17, s43
	v_mov_b32_dpp v4, v4 quad_perm:[1,0,3,2] row_mask:0xf bank_mask:0xf bound_ctrl:1
	v_fmac_f32_e32 v4, v24, v16
	s_nop 1
	v_add_f32_dpp v4, v4, v4 quad_perm:[2,3,0,1] row_mask:0xf bank_mask:0xf bound_ctrl:1
	s_nop 1
	v_add_f32_dpp v4, v4, v4 row_half_mirror row_mask:0xf bank_mask:0xf bound_ctrl:1
	s_nop 1
	v_add_f32_dpp v4, v4, v4 row_mirror row_mask:0xf bank_mask:0xf bound_ctrl:1
	s_nop 0
	v_readlane_b32 s2, v4, 16
	v_readlane_b32 s5, v4, 48
	v_readlane_b32 s1, v4, 0
	v_readlane_b32 s3, v4, 32
	v_mov_b32_e32 v4, s2
	v_mov_b32_e32 v5, s5
	v_add_f32_e32 v4, s1, v4
	v_add_f32_e32 v5, s3, v5
	v_add_f32_e32 v4, v4, v5
	v_mul_f32_e32 v4, v4, v15
	v_fma_f32 v6, v18, v24, -v4
	v_fmac_f32_e32 v6, v14, v0
	v_mul_f32_e32 v0, v6, v9
	v_lshl_add_u64 v[4:5], v[12:13], 0, s[16:17]
	global_store_dword v[4:5], v6, off
	v_mov_b32_dpp v0, v0 quad_perm:[1,0,3,2] row_mask:0xf bank_mask:0xf bound_ctrl:1
	v_fmac_f32_e32 v0, v6, v9
	s_nop 1
	v_add_f32_dpp v0, v0, v0 quad_perm:[2,3,0,1] row_mask:0xf bank_mask:0xf bound_ctrl:1
	s_nop 1
	v_add_f32_dpp v0, v0, v0 row_half_mirror row_mask:0xf bank_mask:0xf bound_ctrl:1
	s_nop 1
	v_add_f32_dpp v0, v0, v0 row_mirror row_mask:0xf bank_mask:0xf bound_ctrl:1
	s_nop 0
	v_readlane_b32 s2, v0, 0
	v_readlane_b32 s1, v0, 16
	v_readlane_b32 s3, v0, 32
	v_readlane_b32 s5, v0, 48
	s_and_saveexec_b64 s[6:7], vcc
	s_cbranch_execz .LBB0_492
	s_lshl_b32 s9, s57, 2
	s_add_u32 s16, s34, s9
	v_mov_b32_e32 v4, s1
	v_mov_b32_e32 v5, s5
	s_addc_u32 s17, s35, 0
	v_pk_add_f32 v[4:5], s[2:3], v[4:5]
	s_nop 0
	v_add_f32_e32 v0, v4, v5
	v_mov_b64_e32 v[4:5], s[16:17]
	global_store_dword v[4:5], v0, off offset:36
.LBB0_492:
	s_or_b64 exec, exec, s[6:7]
	v_mul_f32_e32 v4, v23, v16
	v_lshlrev_b32_e32 v0, 16, v1
	s_mov_b32 s15, s43
	v_mov_b32_dpp v4, v4 quad_perm:[1,0,3,2] row_mask:0xf bank_mask:0xf bound_ctrl:1
	v_fmac_f32_e32 v4, v23, v16
	s_nop 1
	v_add_f32_dpp v4, v4, v4 quad_perm:[2,3,0,1] row_mask:0xf bank_mask:0xf bound_ctrl:1
	s_nop 1
	v_add_f32_dpp v4, v4, v4 row_half_mirror row_mask:0xf bank_mask:0xf bound_ctrl:1
	s_nop 1
	v_add_f32_dpp v4, v4, v4 row_mirror row_mask:0xf bank_mask:0xf bound_ctrl:1
	s_nop 0
	v_readlane_b32 s2, v4, 16
	v_readlane_b32 s5, v4, 48
	v_readlane_b32 s1, v4, 0
	v_readlane_b32 s3, v4, 32
	v_mov_b32_e32 v4, s2
	v_mov_b32_e32 v5, s5
	v_add_f32_e32 v4, s1, v4
	v_add_f32_e32 v5, s3, v5
	v_add_f32_e32 v4, v4, v5
	v_mul_f32_e32 v4, v4, v15
	v_fma_f32 v6, v18, v23, -v4
	v_fmac_f32_e32 v6, v14, v0
	v_mul_f32_e32 v0, v6, v9
	v_lshl_add_u64 v[4:5], v[12:13], 0, s[14:15]
	global_store_dword v[4:5], v6, off
	v_mov_b32_dpp v0, v0 quad_perm:[1,0,3,2] row_mask:0xf bank_mask:0xf bound_ctrl:1
	v_fmac_f32_e32 v0, v6, v9
	s_nop 1
	v_add_f32_dpp v0, v0, v0 quad_perm:[2,3,0,1] row_mask:0xf bank_mask:0xf bound_ctrl:1
	s_nop 1
	v_add_f32_dpp v0, v0, v0 row_half_mirror row_mask:0xf bank_mask:0xf bound_ctrl:1
	s_nop 1
	v_add_f32_dpp v0, v0, v0 row_mirror row_mask:0xf bank_mask:0xf bound_ctrl:1
	s_nop 0
	v_readlane_b32 s2, v0, 0
	v_readlane_b32 s1, v0, 16
	v_readlane_b32 s3, v0, 32
	v_readlane_b32 s5, v0, 48
	s_and_saveexec_b64 s[6:7], vcc
	s_cbranch_execz .LBB0_494
	s_lshl_b32 s9, s57, 2
	s_add_u32 s14, s34, s9
	v_mov_b32_e32 v4, s1
	v_mov_b32_e32 v5, s5
	s_addc_u32 s15, s35, 0
	v_pk_add_f32 v[4:5], s[2:3], v[4:5]
	s_nop 0
	v_add_f32_e32 v0, v4, v5
	v_mov_b64_e32 v[4:5], s[14:15]
	global_store_dword v[4:5], v0, off offset:40
.LBB0_494:
	s_or_b64 exec, exec, s[6:7]
	v_and_b32_e32 v0, 0xffff0000, v1
	v_mul_f32_e32 v1, v22, v16
	s_mov_b32 s13, s43
	s_nop 0
	v_mov_b32_dpp v1, v1 quad_perm:[1,0,3,2] row_mask:0xf bank_mask:0xf bound_ctrl:1
	v_fmac_f32_e32 v1, v22, v16
	s_nop 1
	v_add_f32_dpp v1, v1, v1 quad_perm:[2,3,0,1] row_mask:0xf bank_mask:0xf bound_ctrl:1
	s_nop 1
	v_add_f32_dpp v1, v1, v1 row_half_mirror row_mask:0xf bank_mask:0xf bound_ctrl:1
	s_nop 1
	v_add_f32_dpp v1, v1, v1 row_mirror row_mask:0xf bank_mask:0xf bound_ctrl:1
	s_nop 0
	v_readlane_b32 s2, v1, 16
	v_readlane_b32 s5, v1, 48
	v_readlane_b32 s1, v1, 0
	v_readlane_b32 s3, v1, 32
	v_mov_b32_e32 v1, s2
	v_mov_b32_e32 v4, s5
	v_add_f32_e32 v1, s1, v1
	v_add_f32_e32 v4, s3, v4
	v_add_f32_e32 v1, v1, v4
	v_mul_f32_e32 v1, v1, v15
	v_fma_f32 v4, v18, v22, -v1
	v_fmac_f32_e32 v4, v14, v0
	v_mul_f32_e32 v0, v4, v9
	s_nop 1
	v_mov_b32_dpp v0, v0 quad_perm:[1,0,3,2] row_mask:0xf bank_mask:0xf bound_ctrl:1
	v_fmac_f32_e32 v0, v4, v9
	s_nop 1
	v_add_f32_dpp v0, v0, v0 quad_perm:[2,3,0,1] row_mask:0xf bank_mask:0xf bound_ctrl:1
	s_nop 1
	v_add_f32_dpp v0, v0, v0 row_half_mirror row_mask:0xf bank_mask:0xf bound_ctrl:1
	s_nop 1
	v_add_f32_dpp v0, v0, v0 row_mirror row_mask:0xf bank_mask:0xf bound_ctrl:1
	s_nop 0
	v_readlane_b32 s2, v0, 0
	v_readlane_b32 s1, v0, 16
	v_readlane_b32 s3, v0, 32
	v_readlane_b32 s5, v0, 48
	v_lshl_add_u64 v[0:1], v[12:13], 0, s[12:13]
	global_store_dword v[0:1], v4, off
	s_and_saveexec_b64 s[6:7], vcc
	s_cbranch_execz .LBB0_496
	s_lshl_b32 s9, s57, 2
	s_add_u32 s12, s34, s9
	v_mov_b32_e32 v0, s1
	v_mov_b32_e32 v1, s5
	s_addc_u32 s13, s35, 0
	v_pk_add_f32 v[0:1], s[2:3], v[0:1]
	s_nop 0
	v_add_f32_e32 v4, v0, v1
	v_mov_b64_e32 v[0:1], s[12:13]
	global_store_dword v[0:1], v4, off offset:44
.LBB0_496:
	s_or_b64 exec, exec, s[6:7]
	v_mul_f32_e32 v1, v21, v16
	v_lshlrev_b32_e32 v0, 16, v2
	s_mov_b32 s11, s43
	v_mov_b32_dpp v1, v1 quad_perm:[1,0,3,2] row_mask:0xf bank_mask:0xf bound_ctrl:1
	v_fmac_f32_e32 v1, v21, v16
	s_nop 1
	v_add_f32_dpp v1, v1, v1 quad_perm:[2,3,0,1] row_mask:0xf bank_mask:0xf bound_ctrl:1
	s_nop 1
	v_add_f32_dpp v1, v1, v1 row_half_mirror row_mask:0xf bank_mask:0xf bound_ctrl:1
	s_nop 1
	v_add_f32_dpp v1, v1, v1 row_mirror row_mask:0xf bank_mask:0xf bound_ctrl:1
	s_nop 0
	v_readlane_b32 s2, v1, 16
	v_readlane_b32 s5, v1, 48
	v_readlane_b32 s1, v1, 0
	v_readlane_b32 s3, v1, 32
	v_mov_b32_e32 v1, s2
	v_mov_b32_e32 v4, s5
	v_add_f32_e32 v1, s1, v1
	v_add_f32_e32 v4, s3, v4
	v_add_f32_e32 v1, v1, v4
	v_mul_f32_e32 v1, v1, v15
	v_fma_f32 v4, v18, v21, -v1
	v_fmac_f32_e32 v4, v14, v0
	v_mul_f32_e32 v0, v4, v9
	s_nop 1
	v_mov_b32_dpp v0, v0 quad_perm:[1,0,3,2] row_mask:0xf bank_mask:0xf bound_ctrl:1
	v_fmac_f32_e32 v0, v4, v9
	s_nop 1
	v_add_f32_dpp v0, v0, v0 quad_perm:[2,3,0,1] row_mask:0xf bank_mask:0xf bound_ctrl:1
	s_nop 1
	v_add_f32_dpp v0, v0, v0 row_half_mirror row_mask:0xf bank_mask:0xf bound_ctrl:1
	s_nop 1
	v_add_f32_dpp v0, v0, v0 row_mirror row_mask:0xf bank_mask:0xf bound_ctrl:1
	s_nop 0
	v_readlane_b32 s2, v0, 0
	v_readlane_b32 s1, v0, 16
	v_readlane_b32 s3, v0, 32
	v_readlane_b32 s5, v0, 48
	v_lshl_add_u64 v[0:1], v[12:13], 0, s[10:11]
	global_store_dword v[0:1], v4, off
	s_and_saveexec_b64 s[6:7], vcc
	s_cbranch_execz .LBB0_498
	s_lshl_b32 s9, s57, 2
	s_add_u32 s10, s34, s9
	v_mov_b32_e32 v0, s1
	v_mov_b32_e32 v1, s5
	s_addc_u32 s11, s35, 0
	v_pk_add_f32 v[0:1], s[2:3], v[0:1]
	s_nop 0
	v_add_f32_e32 v4, v0, v1
	v_mov_b64_e32 v[0:1], s[10:11]
	global_store_dword v[0:1], v4, off offset:48
.LBB0_498:
	s_or_b64 exec, exec, s[6:7]
	v_mul_f32_e32 v1, v20, v16
	v_and_b32_e32 v0, 0xffff0000, v2
	s_mov_b32 s9, s43
	v_mov_b32_dpp v1, v1 quad_perm:[1,0,3,2] row_mask:0xf bank_mask:0xf bound_ctrl:1
	v_fmac_f32_e32 v1, v20, v16
	s_nop 1
	v_add_f32_dpp v1, v1, v1 quad_perm:[2,3,0,1] row_mask:0xf bank_mask:0xf bound_ctrl:1
	s_nop 1
	v_add_f32_dpp v1, v1, v1 row_half_mirror row_mask:0xf bank_mask:0xf bound_ctrl:1
	s_nop 1
	v_add_f32_dpp v1, v1, v1 row_mirror row_mask:0xf bank_mask:0xf bound_ctrl:1
	s_nop 0
	v_readlane_b32 s2, v1, 16
	v_readlane_b32 s5, v1, 48
	v_readlane_b32 s1, v1, 0
	v_readlane_b32 s3, v1, 32
	v_mov_b32_e32 v1, s2
	v_mov_b32_e32 v2, s5
	v_add_f32_e32 v1, s1, v1
	v_add_f32_e32 v2, s3, v2
	v_add_f32_e32 v1, v1, v2
	v_mul_f32_e32 v1, v1, v15
	v_fma_f32 v2, v18, v20, -v1
	v_fmac_f32_e32 v2, v14, v0
	v_mul_f32_e32 v0, v2, v9
	s_nop 1
	v_mov_b32_dpp v0, v0 quad_perm:[1,0,3,2] row_mask:0xf bank_mask:0xf bound_ctrl:1
	v_fmac_f32_e32 v0, v2, v9
	s_nop 1
	v_add_f32_dpp v0, v0, v0 quad_perm:[2,3,0,1] row_mask:0xf bank_mask:0xf bound_ctrl:1
	s_nop 1
	v_add_f32_dpp v0, v0, v0 row_half_mirror row_mask:0xf bank_mask:0xf bound_ctrl:1
	s_nop 1
	v_add_f32_dpp v0, v0, v0 row_mirror row_mask:0xf bank_mask:0xf bound_ctrl:1
	s_nop 0
	v_readlane_b32 s2, v0, 0
	v_readlane_b32 s1, v0, 16
	v_readlane_b32 s3, v0, 32
	v_readlane_b32 s5, v0, 48
	v_lshl_add_u64 v[0:1], v[12:13], 0, s[8:9]
	global_store_dword v[0:1], v2, off
	s_and_saveexec_b64 s[6:7], vcc
	s_cbranch_execz .LBB0_500
	s_lshl_b32 s8, s57, 2
	s_add_u32 s8, s34, s8
	v_mov_b32_e32 v0, s1
	v_mov_b32_e32 v1, s5
	s_addc_u32 s9, s35, 0
	v_pk_add_f32 v[0:1], s[2:3], v[0:1]
	s_nop 0
	v_add_f32_e32 v2, v0, v1
	v_mov_b64_e32 v[0:1], s[8:9]
	global_store_dword v[0:1], v2, off offset:52
.LBB0_500:
	s_or_b64 exec, exec, s[6:7]
	v_mul_f32_e32 v1, v19, v16
	v_lshlrev_b32_e32 v0, 16, v3
	s_nop 0
	v_mov_b32_dpp v1, v1 quad_perm:[1,0,3,2] row_mask:0xf bank_mask:0xf bound_ctrl:1
	v_fmac_f32_e32 v1, v19, v16
	s_nop 1
	v_add_f32_dpp v1, v1, v1 quad_perm:[2,3,0,1] row_mask:0xf bank_mask:0xf bound_ctrl:1
	s_nop 1
	v_add_f32_dpp v1, v1, v1 row_half_mirror row_mask:0xf bank_mask:0xf bound_ctrl:1
	s_nop 1
	v_add_f32_dpp v1, v1, v1 row_mirror row_mask:0xf bank_mask:0xf bound_ctrl:1
	s_nop 0
	v_readlane_b32 s2, v1, 16
	v_readlane_b32 s5, v1, 48
	v_readlane_b32 s1, v1, 0
	v_readlane_b32 s3, v1, 32
	v_mov_b32_e32 v1, s2
	v_mov_b32_e32 v2, s5
	v_add_f32_e32 v1, s1, v1
	v_add_f32_e32 v2, s3, v2
	v_add_f32_e32 v1, v1, v2
	v_mul_f32_e32 v1, v1, v15
	v_fma_f32 v2, v18, v19, -v1
	v_fmac_f32_e32 v2, v14, v0
	v_mul_f32_e32 v0, v2, v9
	s_mov_b32 s5, s43
	s_nop 0
	v_mov_b32_dpp v0, v0 quad_perm:[1,0,3,2] row_mask:0xf bank_mask:0xf bound_ctrl:1
	v_fmac_f32_e32 v0, v2, v9
	s_nop 1
	v_add_f32_dpp v0, v0, v0 quad_perm:[2,3,0,1] row_mask:0xf bank_mask:0xf bound_ctrl:1
	s_nop 1
	v_add_f32_dpp v0, v0, v0 row_half_mirror row_mask:0xf bank_mask:0xf bound_ctrl:1
	s_nop 1
	v_add_f32_dpp v0, v0, v0 row_mirror row_mask:0xf bank_mask:0xf bound_ctrl:1
	s_nop 0
	v_readlane_b32 s2, v0, 0
	v_readlane_b32 s1, v0, 16
	v_readlane_b32 s3, v0, 32
	v_readlane_b32 s6, v0, 48
	v_lshl_add_u64 v[0:1], v[12:13], 0, s[4:5]
	global_store_dword v[0:1], v2, off
	s_and_saveexec_b64 s[4:5], vcc
	s_cbranch_execz .LBB0_502
	s_lshl_b32 s7, s57, 2
	s_add_u32 s8, s34, s7
	v_mov_b32_e32 v0, s1
	v_mov_b32_e32 v1, s6
	s_addc_u32 s9, s35, 0
	v_pk_add_f32 v[0:1], s[2:3], v[0:1]
	s_nop 0
	v_add_f32_e32 v2, v0, v1
	v_mov_b64_e32 v[0:1], s[8:9]
	global_store_dword v[0:1], v2, off offset:56
.LBB0_502:
	s_or_b64 exec, exec, s[4:5]
	v_mul_f32_e32 v1, v17, v16
	v_and_b32_e32 v0, 0xffff0000, v3
	s_nop 0
	v_mov_b32_dpp v1, v1 quad_perm:[1,0,3,2] row_mask:0xf bank_mask:0xf bound_ctrl:1
	v_fmac_f32_e32 v1, v17, v16
	s_nop 1
	v_add_f32_dpp v1, v1, v1 quad_perm:[2,3,0,1] row_mask:0xf bank_mask:0xf bound_ctrl:1
	s_nop 1
	v_add_f32_dpp v1, v1, v1 row_half_mirror row_mask:0xf bank_mask:0xf bound_ctrl:1
	s_nop 1
	v_add_f32_dpp v1, v1, v1 row_mirror row_mask:0xf bank_mask:0xf bound_ctrl:1
	s_nop 0
	v_readlane_b32 s2, v1, 16
	v_readlane_b32 s4, v1, 48
	v_readlane_b32 s1, v1, 0
	v_readlane_b32 s3, v1, 32
	v_mov_b32_e32 v1, s2
	v_mov_b32_e32 v2, s4
	v_add_f32_e32 v1, s1, v1
	v_add_f32_e32 v2, s3, v2
	v_add_f32_e32 v1, v1, v2
	v_mul_f32_e32 v1, v1, v15
	v_fma_f32 v2, v18, v17, -v1
	v_fmac_f32_e32 v2, v14, v0
	v_mul_f32_e32 v0, v2, v9
	s_mov_b32 s1, s43
	s_nop 0
	v_mov_b32_dpp v0, v0 quad_perm:[1,0,3,2] row_mask:0xf bank_mask:0xf bound_ctrl:1
	v_fmac_f32_e32 v0, v2, v9
	s_nop 1
	v_add_f32_dpp v0, v0, v0 quad_perm:[2,3,0,1] row_mask:0xf bank_mask:0xf bound_ctrl:1
	s_nop 1
	v_add_f32_dpp v0, v0, v0 row_half_mirror row_mask:0xf bank_mask:0xf bound_ctrl:1
	s_nop 1
	v_add_f32_dpp v0, v0, v0 row_mirror row_mask:0xf bank_mask:0xf bound_ctrl:1
	s_nop 0
	v_readlane_b32 s2, v0, 0
	v_readlane_b32 s4, v0, 16
	v_readlane_b32 s3, v0, 32
	v_readlane_b32 s5, v0, 48
	v_lshl_add_u64 v[0:1], v[12:13], 0, s[0:1]
	global_store_dword v[0:1], v2, off
	s_and_saveexec_b64 s[0:1], vcc
	s_cbranch_execz .LBB0_471
	s_lshl_b32 s6, s57, 2
	s_add_u32 s6, s34, s6
	v_mov_b32_e32 v0, s4
	v_mov_b32_e32 v1, s5
	s_addc_u32 s7, s35, 0
	v_pk_add_f32 v[0:1], s[2:3], v[0:1]
	s_nop 0
	v_add_f32_e32 v2, v0, v1
	v_mov_b64_e32 v[0:1], s[6:7]
	global_store_dword v[0:1], v2, off offset:60
	s_branch .LBB0_471

.LBB0_509:
	s_mul_i32 s2, s18, 37
	s_bfe_u32 s3, s2, 0x80008
	s_lshr_b32 s2, s2, 8
	s_sub_i32 s2, s18, s2
	s_bfe_u32 s2, s2, 0x70001
	s_add_i32 s2, s2, s3
	s_bfe_u32 s2, s2, 0x60002
	s_mul_i32 s2, s2, 7
	s_sub_i32 s2, s18, s2
	s_and_b32 s2, s2, 0xff
	s_mulk_i32 s2, 0x4c00
	s_add_i32 s2, s2, 0
	v_add_u32_e32 v98, s2, v33
	v_add_u32_e32 v58, s2, v34
	v_add_u32_e32 v74, s2, v35
	v_add3_u32 v37, s2, v17, v32
	ds_read2st64_b64 v[38:41], v98 offset0:28 offset1:29
	ds_read2st64_b64 v[42:45], v98 offset0:30 offset1:31
	ds_read_b128 v[46:49], v58
	ds_read_b128 v[50:53], v58 offset:2048
	ds_read_b128 v[54:57], v58 offset:4096
	ds_read_b128 v[58:61], v58 offset:6144
	ds_read_b128 v[62:65], v74
	ds_read_b128 v[66:69], v74 offset:2048
	ds_read_b128 v[70:73], v74 offset:4096
	ds_read_b128 v[74:77], v74 offset:6144
	ds_read_b128 v[78:81], v37 offset:8192
	ds_read_b128 v[82:85], v37 offset:9216
	v_cvt_pk_bf16_f32 v86, v4, v5
	v_cvt_pk_bf16_f32 v87, v6, v7
	v_cvt_pk_bf16_f32 v88, v8, v9
	v_cvt_pk_bf16_f32 v89, v10, v11
	s_waitcnt lgkmcnt(0)
	v_lshlrev_b32_e32 v92, 16, v38
	v_and_b32_e32 v93, 0xffff0000, v38
	v_lshlrev_b32_e32 v94, 16, v39
	v_and_b32_e32 v95, 0xffff0000, v39
	v_cvt_pk_bf16_f32 v90, v12, v13
	v_cvt_pk_bf16_f32 v91, v14, v15
	v_mfma_f32_16x16x32_bf16 v[46:49], v[46:49], v[86:89], v[92:95]
	v_lshlrev_b32_e32 v38, 16, v40
	v_and_b32_e32 v39, 0xffff0000, v40
	v_lshlrev_b32_e32 v40, 16, v41
	v_cvt_pk_bf16_f32 v92, v0, v1
	v_cvt_pk_bf16_f32 v93, v2, v3
	v_and_b32_e32 v41, 0xffff0000, v41
	v_add_u32_e32 v99, s2, v36
	v_mfma_f32_16x16x32_bf16 v[46:49], v[62:65], v[90:93], v[46:49]
	v_lshlrev_b32_e32 v62, 16, v42
	v_and_b32_e32 v63, 0xffff0000, v42
	v_lshlrev_b32_e32 v64, 16, v43
	v_and_b32_e32 v65, 0xffff0000, v43
	v_mfma_f32_16x16x32_bf16 v[38:41], v[50:53], v[86:89], v[38:41]
	s_nop 2
	v_cvt_pk_bf16_f32 v46, v46, v47
	v_cvt_pk_bf16_f32 v47, v48, v49
	v_lshlrev_b32_e32 v42, 16, v44
	v_mfma_f32_16x16x32_bf16 v[54:57], v[54:57], v[86:89], v[62:65]
	v_and_b32_e32 v43, 0xffff0000, v44
	v_lshlrev_b32_e32 v44, 16, v45
	v_and_b32_e32 v45, 0xffff0000, v45
	v_mfma_f32_16x16x32_bf16 v[38:41], v[66:69], v[90:93], v[38:41]
	v_add_u32_e32 v102, 0x4800, v99
	ds_read_b128 v[62:65], v37 offset:10240
	ds_read_b128 v[94:97], v37 offset:11264
	s_add_u32 s0, s0, 0x7a00
	v_mfma_f32_16x16x32_bf16 v[54:57], v[70:73], v[90:93], v[54:57]
	s_nop 2
	v_cvt_pk_bf16_f32 v48, v38, v39
	v_cvt_pk_bf16_f32 v49, v40, v41
	ds_read2_b64 v[50:53], v102 offset1:4
	ds_read2st64_b64 v[70:73], v98 offset0:32 offset1:33
	ds_read2st64_b64 v[98:101], v98 offset0:34 offset1:35
	v_mfma_f32_16x16x32_bf16 v[38:41], v[78:81], v[46:49], v[54:57]
	s_addc_u32 s1, s1, 0
	s_add_i32 s17, s17, 1
	s_mov_b64 s[2:3], 0x8000
	v_mfma_f32_16x16x32_bf16 v[42:45], v[58:61], v[86:89], v[42:45]
	v_add_co_u32_e32 v54, vcc, s21, v28
	ds_read2_b64 v[58:61], v102 offset0:8 offset1:12
	ds_read_b128 v[66:69], v37 offset:12288
	ds_read_b128 v[86:89], v37 offset:13312
	v_addc_co_u32_e32 v55, vcc, -1, v29, vcc
	global_store_dword v[54:55], v38, off
	v_add_co_u32_e32 v54, vcc, s22, v28
	v_mfma_f32_16x16x32_bf16 v[42:45], v[74:77], v[90:93], v[42:45]
	s_nop 0
	v_addc_co_u32_e32 v55, vcc, -1, v29, vcc
	v_add_co_u32_e32 v38, vcc, s23, v28
	global_store_dword v[54:55], v39, off
	s_nop 0
	v_addc_co_u32_e32 v39, vcc, -1, v29, vcc
	global_store_dword v[38:39], v40, off
	v_add_co_u32_e32 v38, vcc, s19, v28
	s_waitcnt lgkmcnt(0)
	v_mov_b32_e32 v37, v50
	v_addc_co_u32_e32 v39, vcc, -1, v29, vcc
	global_store_dword v[38:39], v41, off
	v_mfma_f32_16x16x32_bf16 v[38:41], v[82:85], v[46:49], v[42:45]
	s_cmp_eq_u32 s0, 0x1e8000
	s_nop 1
	v_add_co_u32_e32 v42, vcc, s24, v28
	s_nop 1
	v_addc_co_u32_e32 v43, vcc, -1, v29, vcc
	s_nop 0
	global_store_dword v[42:43], v38, off
	v_add_co_u32_e32 v42, vcc, s25, v28
	s_nop 1
	v_addc_co_u32_e32 v43, vcc, -1, v29, vcc
	v_add_co_u32_e32 v38, vcc, s20, v28
	global_store_dword v[42:43], v39, off
	s_nop 0
	v_addc_co_u32_e32 v39, vcc, -1, v29, vcc
	global_store_dword v[38:39], v40, off
	global_store_dword v[28:29], v41, off
	v_mov_b32_e32 v41, v71
	v_lshl_add_u64 v[28:29], v[28:29], 0, s[2:3]
	v_lshlrev_b32_e32 v40, 16, v41
	v_and_b32_e32 v41, 0xffff0000, v41
	v_lshlrev_b32_e32 v44, 16, v51
	v_and_b32_e32 v45, 0xffff0000, v51
	v_lshlrev_b32_e32 v38, 16, v70
	v_and_b32_e32 v39, 0xffff0000, v70
	v_lshlrev_b32_e32 v42, 16, v37
	v_and_b32_e32 v43, 0xffff0000, v37
	v_pk_fma_f32 v[6:7], v[6:7], v[44:45], v[40:41]
	v_mov_b32_e32 v37, v73
	v_mov_b32_e32 v45, v53
	v_pk_fma_f32 v[4:5], v[4:5], v[42:43], v[38:39]
	s_nop 0
	v_lshlrev_b32_e32 v38, 16, v72
	v_and_b32_e32 v39, 0xffff0000, v72
	v_lshlrev_b32_e32 v42, 16, v52
	v_and_b32_e32 v43, 0xffff0000, v52
	v_lshlrev_b32_e32 v40, 16, v37
	v_and_b32_e32 v41, 0xffff0000, v37
	v_lshlrev_b32_e32 v44, 16, v45
	v_and_b32_e32 v45, 0xffff0000, v45
	v_pk_fma_f32 v[8:9], v[8:9], v[42:43], v[38:39]
	v_mov_b32_e32 v37, v98
	v_mov_b32_e32 v43, v58
	v_pk_fma_f32 v[10:11], v[10:11], v[44:45], v[40:41]
	v_mfma_f32_16x16x32_bf16 v[4:7], v[62:65], v[46:49], v[4:7]
	v_lshlrev_b32_e32 v40, 16, v99
	v_and_b32_e32 v41, 0xffff0000, v99
	v_lshlrev_b32_e32 v44, 16, v59
	v_and_b32_e32 v45, 0xffff0000, v59
	v_lshlrev_b32_e32 v38, 16, v37
	v_and_b32_e32 v39, 0xffff0000, v37
	v_pk_fma_f32 v[14:15], v[14:15], v[44:45], v[40:41]
	v_mov_b32_e32 v37, v101
	v_mov_b32_e32 v45, v61
	v_lshlrev_b32_e32 v42, 16, v43
	v_and_b32_e32 v43, 0xffff0000, v43
	v_pk_fma_f32 v[12:13], v[12:13], v[42:43], v[38:39]
	v_lshlrev_b32_e32 v38, 16, v100
	v_and_b32_e32 v39, 0xffff0000, v100
	v_lshlrev_b32_e32 v40, 16, v37
	v_and_b32_e32 v41, 0xffff0000, v37
	v_lshlrev_b32_e32 v42, 16, v60
	v_and_b32_e32 v43, 0xffff0000, v60
	v_lshlrev_b32_e32 v44, 16, v45
	v_and_b32_e32 v45, 0xffff0000, v45
	v_pk_fma_f32 v[2:3], v[2:3], v[44:45], v[40:41]
	v_pk_fma_f32 v[0:1], v[0:1], v[42:43], v[38:39]
	v_mfma_f32_16x16x32_bf16 v[8:11], v[94:97], v[46:49], v[8:11]
	v_mfma_f32_16x16x32_bf16 v[12:15], v[66:69], v[46:49], v[12:15]
	v_mfma_f32_16x16x32_bf16 v[0:3], v[86:89], v[46:49], v[0:3]
	s_cbranch_scc1 .LBB0_507

.LBB0_527:
	s_and_b64 vcc, exec, s[0:1]
	s_cbranch_vccz .LBB0_605
	v_readlane_b32 s2, v253, 9
	v_readlane_b32 s3, v253, 10
	s_mov_b64 s[0:1], -1
	s_and_b64 vcc, exec, s[2:3]
	s_cbranch_vccz .LBB0_600
	s_mov_b32 s38, s89
	v_mbcnt_lo_u32_b32 v11, -1, 0
	v_mbcnt_hi_u32_b32 v11, -1, v11
	s_mov_b64 s[0:1], s[78:79]
	v_and_b32_e32 v10, 63, v11
	s_mov_b64 s[4:5], -1
	s_mov_b64 s[8:9], 0
	s_cmp_lt_i32 s38, 1
	s_mov_b64 s[2:3], 0
	s_cbranch_scc1 .LBB0_534
	s_cmp_eq_u32 s38, 1
	s_cbranch_scc0 .LBB0_532
	s_mov_b32 s57, s43
	s_lshl_b64 s[2:3], s[56:57], 18
	s_lshl_b64 s[4:5], s[56:57], 11
	s_lshl_b64 s[10:11], s[56:57], 17
	v_readlane_b32 s6, v254, 18
	s_add_u32 s6, s0, s6
	v_readlane_b32 s7, v254, 17
	s_addc_u32 s7, s1, s7
	v_lshlrev_b32_e32 v194, 3, v10
	v_lshl_add_u64 v[0:1], s[6:7], 0, v[194:195]
	s_mov_b64 s[6:7], 0x2040000
	v_lshl_add_u64 v[8:9], v[0:1], 0, s[6:7]
	global_load_dwordx2 v[22:23], v[8:9], off offset:512
	v_add_co_u32_e32 v0, vcc, s97, v0
	v_readlane_b32 s12, v252, 2
	s_nop 0
	v_addc_co_u32_e32 v1, vcc, 0, v1, vcc
	global_load_dwordx2 v[14:15], v[0:1], off
	v_readlane_b32 s13, v252, 3
	v_readlane_b32 s14, v252, 4
	v_readlane_b32 s12, v255, 41
	v_readlane_b32 s15, v252, 5
	v_readlane_b32 s13, v255, 42
	s_add_u32 s6, s14, s12
	v_readlane_b32 s16, v252, 6
	s_addc_u32 s7, s15, s13
	v_lshlrev_b32_e32 v13, 4, v10
	v_readlane_b32 s17, v252, 7
	global_load_dwordx4 v[0:3], v13, s[6:7]
	s_add_u32 s6, s16, s12
	v_readlane_b32 s18, v252, 8
	s_addc_u32 s7, s17, s13
	v_lshrrev_b32_e32 v16, 4, v10
	v_readlane_b32 s19, v252, 9
	s_add_u32 s2, s18, s2
	v_readlane_b32 s20, v252, 10
	s_addc_u32 s3, s19, s3
	v_lshlrev_b32_e32 v12, 16, v16
	v_readlane_b32 s21, v252, 11
	global_load_dword v12, v12, s[2:3]
	s_add_u32 s2, s20, s4
	s_addc_u32 s3, s21, s5
	v_lshlrev_b32_e32 v16, 9, v16
	global_load_dword v16, v16, s[2:3]
	v_readlane_b32 s22, v252, 12
	global_load_dwordx4 v[4:7], v13, s[6:7]
	v_readlane_b32 s23, v252, 13
	v_readlane_b32 s24, v252, 14
	v_readlane_b32 s25, v252, 15
	v_readlane_b32 s26, v252, 16
	v_readlane_b32 s27, v252, 17
	s_waitcnt vmcnt(0) lgkmcnt(0)
	v_lshlrev_b32_e32 v18, 16, v22
	v_mul_f32_e32 v17, 0x3d372713, v18
	v_mul_f32_e32 v17, v17, v18
	v_mov_b32_e32 v20, v18
	v_fmac_f32_e32 v20, v17, v20
	v_mul_f32_e32 v17, 0x3f4c422a, v20
	v_add_f32_e32 v17, v17, v17
	v_and_b32_e32 v19, 0xffff0000, v22
	v_mul_f32_e32 v17, 0xbfb8aa3b, v17
	v_exp_f32_e32 v20, v17
	v_mul_f32_e32 v17, 0x3d372713, v19
	v_mul_f32_e32 v17, v17, v19
	v_mov_b32_e32 v21, v19
	v_fmac_f32_e32 v21, v17, v21
	v_mul_f32_e32 v17, 0x3f4c422a, v21
	v_add_f32_e32 v17, v17, v17
	v_mul_f32_e32 v17, 0xbfb8aa3b, v17
	v_exp_f32_e32 v21, v17
	s_nop 0
	v_pk_add_f32 v[20:21], v[20:21], 1.0 op_sel_hi:[1,0]
	s_nop 0
	v_rcp_f32_e32 v21, v21
	v_rcp_f32_e32 v20, v20
	s_nop 0
	v_pk_mul_f32 v[24:25], v[20:21], v[18:19]
	v_lshlrev_b32_e32 v22, 16, v23
	v_add_f32_e32 v17, 0, v24
	v_mul_f32_e32 v24, 0x3d372713, v22
	v_add_f32_e32 v17, v25, v17
	v_mul_f32_e32 v24, v24, v22
	v_mov_b32_e32 v25, v22
	v_and_b32_e32 v23, 0xffff0000, v23
	v_fmac_f32_e32 v25, v24, v25
	v_mul_f32_e32 v24, 0x3f4c422a, v25
	v_mul_f32_e32 v25, 0x3d372713, v23
	v_mul_f32_e32 v25, v25, v23
	v_mov_b32_e32 v26, v23
	v_fmac_f32_e32 v26, v25, v26
	v_mul_f32_e32 v25, 0x3f4c422a, v26
	v_add_f32_e32 v24, v24, v24
	v_add_f32_e32 v25, v25, v25
	v_mul_f32_e32 v24, 0xbfb8aa3b, v24
	v_mul_f32_e32 v25, 0xbfb8aa3b, v25
	v_exp_f32_e32 v24, v24
	v_exp_f32_e32 v25, v25
	s_nop 0
	v_pk_add_f32 v[24:25], v[24:25], 1.0 op_sel_hi:[1,0]
	s_nop 0
	v_rcp_f32_e32 v25, v25
	v_rcp_f32_e32 v24, v24
	s_nop 0
	v_pk_mul_f32 v[26:27], v[24:25], v[22:23]
	s_nop 0
	v_add_f32_e32 v17, v26, v17
	v_add_f32_e32 v17, v27, v17
	s_nop 1
	v_add_f32_dpp v17, v17, v17 quad_perm:[1,0,3,2] row_mask:0xf bank_mask:0xf bound_ctrl:1
	s_nop 1
	v_add_f32_dpp v17, v17, v17 quad_perm:[2,3,0,1] row_mask:0xf bank_mask:0xf bound_ctrl:1
	s_nop 1
	v_add_f32_dpp v17, v17, v17 row_half_mirror row_mask:0xf bank_mask:0xf bound_ctrl:1
	s_nop 1
	v_add_f32_dpp v17, v17, v17 row_mirror row_mask:0xf bank_mask:0xf bound_ctrl:1
	s_nop 0
	v_readlane_b32 s4, v17, 16
	v_readlane_b32 s5, v17, 48
	v_readlane_b32 s2, v17, 0
	v_readlane_b32 s3, v17, 32
	v_mov_b32_e32 v26, s4
	v_mov_b32_e32 v27, s5
	v_pk_add_f32 v[26:27], s[2:3], v[26:27]
	s_nop 0
	v_add_f32_e32 v17, v26, v27
	v_mul_f32_e32 v26, 0x3b800000, v17
	v_pk_fma_f32 v[18:19], v[20:21], v[18:19], v[26:27] op_sel_hi:[1,1,0] neg_lo:[0,0,1] neg_hi:[0,0,1]
	v_pk_fma_f32 v[22:23], v[24:25], v[22:23], v[26:27] op_sel_hi:[1,1,0] neg_lo:[0,0,1] neg_hi:[0,0,1]
	v_pk_mul_f32 v[20:21], v[18:19], v[18:19]
	v_pk_mul_f32 v[24:25], v[22:23], v[22:23]
	v_add_f32_e32 v17, v20, v21
	v_add_f32_e32 v17, v24, v17
	v_add_f32_e32 v17, v25, v17
	s_nop 1
	v_add_f32_dpp v17, v17, v17 quad_perm:[1,0,3,2] row_mask:0xf bank_mask:0xf bound_ctrl:1
	s_nop 1
	v_add_f32_dpp v17, v17, v17 quad_perm:[2,3,0,1] row_mask:0xf bank_mask:0xf bound_ctrl:1
	s_nop 1
	v_add_f32_dpp v17, v17, v17 row_half_mirror row_mask:0xf bank_mask:0xf bound_ctrl:1
	s_nop 1
	v_add_f32_dpp v17, v17, v17 row_mirror row_mask:0xf bank_mask:0xf bound_ctrl:1
	s_nop 0
	v_readlane_b32 s4, v17, 16
	v_readlane_b32 s5, v17, 48
	v_readlane_b32 s2, v17, 0
	v_readlane_b32 s3, v17, 32
	v_mov_b32_e32 v20, s4
	v_mov_b32_e32 v21, s5
	v_pk_add_f32 v[20:21], s[2:3], v[20:21]
	s_nop 0
	v_add_f32_e32 v17, v20, v21
	v_fmamk_f32 v17, v17, 0x3b800000, v238
	v_cmp_gt_f32_e32 vcc, s83, v17
	v_mul_f32_e32 v20, 0x4b800000, v17
	s_nop 0
	v_cndmask_b32_e32 v17, v17, v20, vcc
	v_rsq_f32_e32 v17, v17
	s_nop 0
	v_mul_f32_e32 v20, 0x45800000, v17
	v_cndmask_b32_e32 v20, v17, v20, vcc
	v_pk_mul_f32 v[18:19], v[18:19], v[20:21] op_sel_hi:[1,0]
	s_nop 0
	v_pk_fma_f32 v[0:1], v[0:1], v[18:19], v[4:5]
	v_lshlrev_b32_e32 v4, 16, v14
	v_and_b32_e32 v5, 0xffff0000, v14
	v_mul_f32_e32 v14, 0x3d372713, v4
	v_mul_f32_e32 v14, v14, v4
	v_mov_b32_e32 v17, v4
	v_fmac_f32_e32 v17, v14, v17
	v_mul_f32_e32 v14, 0x3f4c422a, v17
	v_add_f32_e32 v14, v14, v14
	v_mul_f32_e32 v14, 0xbfb8aa3b, v14
	v_exp_f32_e32 v18, v14
	v_mul_f32_e32 v14, 0x3d372713, v5
	v_mul_f32_e32 v14, v14, v5
	v_mov_b32_e32 v17, v5
	v_fmac_f32_e32 v17, v14, v17
	v_mul_f32_e32 v14, 0x3f4c422a, v17
	v_add_f32_e32 v14, v14, v14
	v_mul_f32_e32 v14, 0xbfb8aa3b, v14
	v_exp_f32_e32 v19, v14
	s_nop 0
	v_pk_add_f32 v[18:19], v[18:19], 1.0 op_sel_hi:[1,0]
	s_nop 0
	v_rcp_f32_e32 v19, v19
	v_rcp_f32_e32 v18, v18
	s_nop 0
	v_pk_mul_f32 v[4:5], v[18:19], v[4:5]
	v_pk_fma_f32 v[18:19], v[12:13], v[0:1], v[16:17] op_sel_hi:[0,1,0]
	v_pk_mul_f32 v[4:5], v[4:5], v[18:19]
	v_pk_mul_f32 v[18:19], v[22:23], v[20:21] op_sel_hi:[1,0]
	s_nop 0
	v_pk_fma_f32 v[2:3], v[2:3], v[18:19], v[6:7]
	v_lshlrev_b32_e32 v6, 16, v15
	v_mul_f32_e32 v14, 0x3d372713, v6
	v_and_b32_e32 v7, 0xffff0000, v15
	v_mul_f32_e32 v14, v14, v6
	v_mov_b32_e32 v15, v6
	v_fmac_f32_e32 v15, v14, v15
	v_mul_f32_e32 v14, 0x3f4c422a, v15
	v_mul_f32_e32 v15, 0x3d372713, v7
	v_mul_f32_e32 v15, v15, v7
	v_mov_b32_e32 v17, v7
	v_fmac_f32_e32 v17, v15, v17
	v_mul_f32_e32 v15, 0x3f4c422a, v17
	v_add_f32_e32 v14, v14, v14
	v_add_f32_e32 v15, v15, v15
	v_mul_f32_e32 v14, 0xbfb8aa3b, v14
	v_mul_f32_e32 v15, 0xbfb8aa3b, v15
	v_exp_f32_e32 v14, v14
	v_exp_f32_e32 v15, v15
	s_nop 0
	v_pk_add_f32 v[14:15], v[14:15], 1.0 op_sel_hi:[1,0]
	s_nop 0
	v_rcp_f32_e32 v15, v15
	v_readlane_b32 s2, v253, 33
	s_add_u32 s2, s2, s10
	v_readlane_b32 s3, v253, 35
	v_rcp_f32_e32 v14, v14
	s_nop 0
	v_pk_mul_f32 v[6:7], v[14:15], v[6:7]
	v_pk_fma_f32 v[14:15], v[12:13], v[2:3], v[16:17] op_sel_hi:[0,1,0]
	v_pk_mul_f32 v[6:7], v[6:7], v[14:15]
	s_addc_u32 s3, s3, s11
	global_store_dwordx4 v13, v[0:3], s[2:3]
	s_nop 1
	v_cvt_pk_bf16_f32 v0, v4, v5
	v_cvt_pk_bf16_f32 v1, v6, v7
	global_store_dwordx2 v[8:9], v[0:1], off offset:1536

.LBB0_539:
	s_addk_i32 s58, 0x380
	s_ashr_i32 s6, s58, 4
	s_add_i32 s2, s6, 0x4000
	s_bfe_u32 s61, s58, 0x20002
	s_ashr_i32 s3, s2, 31
	s_mul_i32 s5, s2, 0xc00
	s_mul_hi_i32 s4, s2, 0xc00
	s_add_u32 s5, s39, s5
	s_addc_u32 s7, s40, s4
	s_lshl_b32 s4, s61, 7
	s_add_u32 s4, s5, s4
	s_addc_u32 s5, s7, 0
	v_lshlrev_b32_e32 v194, 1, v10
	v_lshl_add_u64 v[0:1], s[4:5], 0, v[194:195]
	global_load_ushort v2, v[0:1], off
	s_add_i32 s6, s6, s41
	s_ashr_i32 s7, s6, 31
	s_lshl_b64 s[36:37], s[6:7], 16
	s_lshl_b32 s6, s61, 14
	s_and_b32 s60, s59, 48
	s_or_b32 s36, s36, s6
	v_lshl_add_u64 v[12:13], v[8:9], 0, s[36:37]
	s_lshl_b32 s34, s60, 8
	s_mov_b32 s35, s43
	s_lshl_b32 s6, s60, 1
	s_add_u32 s4, s4, s6
	s_addc_u32 s5, s5, 0
	s_mov_b32 s21, s43
	s_mov_b32 s31, s43
	s_mov_b32 s29, s43
	s_mov_b32 s25, s43
	s_mov_b32 s7, s43
	s_mov_b32 s23, s43
	s_mov_b32 s27, s43
	s_mov_b32 s19, s43
	s_mov_b32 s17, s43
	s_mov_b32 s15, s43
	s_mov_b32 s13, s43
	s_mov_b32 s11, s43
	s_mov_b32 s9, s43
	v_lshlrev_b32_e32 v194, 2, v10
	s_waitcnt vmcnt(0) lgkmcnt(0)
	v_lshlrev_b32_e32 v14, 16, v2
	global_load_ushort v2, v[0:1], off offset:512
	s_waitcnt vmcnt(0) lgkmcnt(0)
	v_lshlrev_b32_e32 v15, 16, v2
	global_load_ushort v2, v[0:1], off offset:1536
	s_waitcnt vmcnt(0) lgkmcnt(0)
	v_lshlrev_b32_e32 v17, 16, v2
	global_load_ushort v2, v[0:1], off offset:2048
	s_waitcnt vmcnt(0) lgkmcnt(0)
	v_lshlrev_b32_e32 v16, 16, v2
	global_load_ushort v0, v[0:1], off offset:2560
	s_waitcnt vmcnt(0) lgkmcnt(0)
	v_lshlrev_b32_e32 v0, 16, v0
	v_mul_f32_e32 v34, 0x3fb8aa3b, v0
	v_lshl_add_u64 v[0:1], v[12:13], 0, s[34:35]
	global_load_dword v35, v[0:1], off
	v_mov_b64_e32 v[0:1], s[4:5]
	s_or_b32 s4, s60, 1
	s_lshl_b32 s42, s4, 8
	s_or_b32 s4, s60, 2
	s_lshl_b32 s20, s4, 8
	s_or_b32 s4, s60, 3
	s_lshl_b32 s30, s4, 8
	s_or_b32 s4, s60, 4
	v_lshl_add_u64 v[2:3], v[12:13], 0, s[42:43]
	s_lshl_b32 s28, s4, 8
	s_or_b32 s4, s60, 5
	global_load_dword v33, v[2:3], off
	v_lshl_add_u64 v[2:3], v[12:13], 0, s[20:21]
	s_lshl_b32 s24, s4, 8
	s_or_b32 s4, s60, 6
	global_load_dword v32, v[2:3], off
	v_lshl_add_u64 v[2:3], v[12:13], 0, s[30:31]
	s_lshl_b32 s6, s4, 8
	s_or_b32 s4, s60, 7
	global_load_dword v31, v[2:3], off
	v_lshl_add_u64 v[2:3], v[12:13], 0, s[28:29]
	s_lshl_b32 s22, s4, 8
	s_or_b32 s4, s60, 8
	global_load_dwordx4 v[4:7], v[0:1], off offset:1024
	global_load_dword v30, v[2:3], off
	v_lshl_add_u64 v[2:3], v[12:13], 0, s[24:25]
	s_lshl_b32 s26, s4, 8
	s_or_b32 s4, s60, 9
	global_load_dword v29, v[2:3], off
	v_lshl_add_u64 v[2:3], v[12:13], 0, s[6:7]
	s_lshl_b32 s18, s4, 8
	s_or_b32 s4, s60, 10
	global_load_dword v28, v[2:3], off
	v_lshl_add_u64 v[2:3], v[12:13], 0, s[22:23]
	s_lshl_b32 s16, s4, 8
	s_or_b32 s4, s60, 11
	global_load_dword v27, v[2:3], off
	v_lshl_add_u64 v[2:3], v[12:13], 0, s[26:27]
	v_lshl_add_u64 v[18:19], v[12:13], 0, s[18:19]
	s_lshl_b32 s14, s4, 8
	s_or_b32 s4, s60, 12
	global_load_dword v26, v[2:3], off
	s_nop 0
	global_load_dwordx4 v[0:3], v[0:1], off offset:1040
	s_lshl_b32 s12, s4, 8
	global_load_dword v25, v[18:19], off
	v_lshl_add_u64 v[18:19], v[12:13], 0, s[16:17]
	s_or_b32 s4, s60, 13
	global_load_dword v24, v[18:19], off
	v_lshl_add_u64 v[18:19], v[12:13], 0, s[14:15]
	s_lshl_b32 s10, s4, 8
	s_or_b32 s4, s60, 14
	global_load_dword v23, v[18:19], off
	v_lshl_add_u64 v[18:19], v[12:13], 0, s[12:13]
	s_lshl_b32 s8, s4, 8
	s_or_b32 s4, s60, 15
	global_load_dword v22, v[18:19], off
	v_lshl_add_u64 v[18:19], v[12:13], 0, s[10:11]
	s_lshl_b32 s4, s4, 8
	s_mov_b32 s5, s43
	global_load_dword v21, v[18:19], off
	v_lshl_add_u64 v[18:19], v[12:13], 0, s[8:9]
	v_lshl_add_u64 v[12:13], v[12:13], 0, s[4:5]
	global_load_dword v20, v[18:19], off
	s_add_u32 s36, s94, s36
	global_load_dword v18, v[12:13], off
	s_addc_u32 s37, s95, s37
	s_lshl_b64 s[2:3], s[2:3], 10
	s_add_u32 s2, s56, s2
	v_lshl_add_u64 v[12:13], s[36:37], 0, v[194:195]
	s_mov_b64 s[36:37], 0x4280000
	s_addc_u32 s3, s57, s3
	s_lshl_b32 s5, s61, 8
	v_lshl_add_u64 v[12:13], v[12:13], 0, s[36:37]
	s_add_u32 s36, s2, s5
	s_addc_u32 s37, s3, 0
	v_exp_f32_e32 v19, v34
	s_waitcnt vmcnt(0)
	v_mul_f32_e32 v36, v35, v17
	s_nop 1
	v_mov_b32_dpp v36, v36 quad_perm:[1,0,3,2] row_mask:0xf bank_mask:0xf bound_ctrl:1
	v_fmac_f32_e32 v36, v35, v17
	s_waitcnt lgkmcnt(0)
	v_lshlrev_b32_e32 v34, 16, v4
	v_add_f32_dpp v36, v36, v36 quad_perm:[2,3,0,1] row_mask:0xf bank_mask:0xf bound_ctrl:1
	s_nop 1
	v_add_f32_dpp v36, v36, v36 row_half_mirror row_mask:0xf bank_mask:0xf bound_ctrl:1
	s_nop 1
	v_add_f32_dpp v36, v36, v36 row_mirror row_mask:0xf bank_mask:0xf bound_ctrl:1
	s_nop 0
	v_readlane_b32 s3, v36, 16
	v_readlane_b32 s7, v36, 48
	v_readlane_b32 s2, v36, 0
	v_readlane_b32 s5, v36, 32
	v_mov_b32_e32 v36, s3
	v_mov_b32_e32 v37, s7
	v_add_f32_e32 v36, s2, v36
	v_add_f32_e32 v37, s5, v37
	v_add_f32_e32 v36, v36, v37
	v_mul_f32_e32 v36, v36, v16
	v_fma_f32 v36, v35, v19, -v36
	v_fmac_f32_e32 v36, v15, v34
	v_mul_f32_e32 v34, v36, v14
	s_nop 1
	v_mov_b32_dpp v34, v34 quad_perm:[1,0,3,2] row_mask:0xf bank_mask:0xf bound_ctrl:1
	v_fmac_f32_e32 v34, v36, v14
	s_nop 1
	v_add_f32_dpp v34, v34, v34 quad_perm:[2,3,0,1] row_mask:0xf bank_mask:0xf bound_ctrl:1
	s_nop 1
	v_add_f32_dpp v34, v34, v34 row_half_mirror row_mask:0xf bank_mask:0xf bound_ctrl:1
	s_nop 1
	v_add_f32_dpp v34, v34, v34 row_mirror row_mask:0xf bank_mask:0xf bound_ctrl:1
	s_nop 0
	v_readlane_b32 s2, v34, 0
	v_readlane_b32 s5, v34, 16
	v_readlane_b32 s3, v34, 32
	v_readlane_b32 s7, v34, 48
	v_lshl_add_u64 v[34:35], v[12:13], 0, s[34:35]
	global_store_dword v[34:35], v36, off
	s_and_saveexec_b64 s[34:35], vcc
	s_cbranch_execz .LBB0_541
	s_lshl_b32 s9, s60, 2
	s_add_u32 s66, s36, s9
	v_mov_b32_e32 v34, s5
	v_mov_b32_e32 v35, s7
	s_addc_u32 s67, s37, 0
	v_pk_add_f32 v[34:35], s[2:3], v[34:35]
	s_nop 0
	v_add_f32_e32 v36, v34, v35
	v_mov_b64_e32 v[34:35], s[66:67]
	global_store_dword v[34:35], v36, off
.LBB0_541:
	s_or_b64 exec, exec, s[34:35]
	v_mul_f32_e32 v34, v33, v17
	v_and_b32_e32 v4, 0xffff0000, v4
	s_nop 0
	v_mov_b32_dpp v34, v34 quad_perm:[1,0,3,2] row_mask:0xf bank_mask:0xf bound_ctrl:1
	v_fmac_f32_e32 v34, v33, v17
	s_nop 1
	v_add_f32_dpp v34, v34, v34 quad_perm:[2,3,0,1] row_mask:0xf bank_mask:0xf bound_ctrl:1
	s_nop 1
	v_add_f32_dpp v34, v34, v34 row_half_mirror row_mask:0xf bank_mask:0xf bound_ctrl:1
	s_nop 1
	v_add_f32_dpp v34, v34, v34 row_mirror row_mask:0xf bank_mask:0xf bound_ctrl:1
	s_nop 0
	v_readlane_b32 s3, v34, 16
	v_readlane_b32 s7, v34, 48
	v_readlane_b32 s2, v34, 0
	v_readlane_b32 s5, v34, 32
	v_mov_b32_e32 v34, s3
	v_mov_b32_e32 v35, s7
	v_add_f32_e32 v34, s2, v34
	v_add_f32_e32 v35, s5, v35
	v_add_f32_e32 v34, v34, v35
	v_mul_f32_e32 v34, v34, v16
	v_fma_f32 v33, v33, v19, -v34
	v_fmac_f32_e32 v33, v15, v4
	v_mul_f32_e32 v4, v33, v14
	v_lshl_add_u64 v[34:35], v[12:13], 0, s[42:43]
	global_store_dword v[34:35], v33, off
	v_mov_b32_dpp v4, v4 quad_perm:[1,0,3,2] row_mask:0xf bank_mask:0xf bound_ctrl:1
	v_fmac_f32_e32 v4, v33, v14
	s_nop 1
	v_add_f32_dpp v4, v4, v4 quad_perm:[2,3,0,1] row_mask:0xf bank_mask:0xf bound_ctrl:1
	s_nop 1
	v_add_f32_dpp v4, v4, v4 row_half_mirror row_mask:0xf bank_mask:0xf bound_ctrl:1
	s_nop 1
	v_add_f32_dpp v4, v4, v4 row_mirror row_mask:0xf bank_mask:0xf bound_ctrl:1
	s_nop 0
	v_readlane_b32 s2, v4, 0
	v_readlane_b32 s5, v4, 16
	v_readlane_b32 s3, v4, 32
	v_readlane_b32 s7, v4, 48
	s_and_saveexec_b64 s[34:35], vcc
	s_cbranch_execz .LBB0_543
	s_lshl_b32 s9, s60, 2
	s_add_u32 s66, s36, s9
	v_mov_b32_e32 v34, s5
	v_mov_b32_e32 v35, s7
	s_addc_u32 s67, s37, 0
	v_pk_add_f32 v[34:35], s[2:3], v[34:35]
	s_nop 0
	v_add_f32_e32 v4, v34, v35
	v_mov_b64_e32 v[34:35], s[66:67]
	global_store_dword v[34:35], v4, off offset:4
.LBB0_543:
	s_or_b64 exec, exec, s[34:35]
	v_mul_f32_e32 v33, v32, v17
	v_lshlrev_b32_e32 v4, 16, v5
	s_mov_b32 s21, s43
	v_mov_b32_dpp v33, v33 quad_perm:[1,0,3,2] row_mask:0xf bank_mask:0xf bound_ctrl:1
	v_fmac_f32_e32 v33, v32, v17
	s_nop 1
	v_add_f32_dpp v33, v33, v33 quad_perm:[2,3,0,1] row_mask:0xf bank_mask:0xf bound_ctrl:1
	s_nop 1
	v_add_f32_dpp v33, v33, v33 row_half_mirror row_mask:0xf bank_mask:0xf bound_ctrl:1
	s_nop 1
	v_add_f32_dpp v33, v33, v33 row_mirror row_mask:0xf bank_mask:0xf bound_ctrl:1
	s_nop 0
	v_readlane_b32 s3, v33, 16
	v_readlane_b32 s7, v33, 48
	v_readlane_b32 s2, v33, 0
	v_readlane_b32 s5, v33, 32
	v_mov_b32_e32 v33, s3
	v_mov_b32_e32 v34, s7
	v_add_f32_e32 v33, s2, v33
	v_add_f32_e32 v34, s5, v34
	v_add_f32_e32 v33, v33, v34
	v_mul_f32_e32 v33, v33, v16
	v_fma_f32 v34, v19, v32, -v33
	v_fmac_f32_e32 v34, v15, v4
	v_mul_f32_e32 v4, v34, v14
	v_lshl_add_u64 v[32:33], v[12:13], 0, s[20:21]
	global_store_dword v[32:33], v34, off
	v_mov_b32_dpp v4, v4 quad_perm:[1,0,3,2] row_mask:0xf bank_mask:0xf bound_ctrl:1
	v_fmac_f32_e32 v4, v34, v14
	s_nop 1
	v_add_f32_dpp v4, v4, v4 quad_perm:[2,3,0,1] row_mask:0xf bank_mask:0xf bound_ctrl:1
	s_nop 1
	v_add_f32_dpp v4, v4, v4 row_half_mirror row_mask:0xf bank_mask:0xf bound_ctrl:1
	s_nop 1
	v_add_f32_dpp v4, v4, v4 row_mirror row_mask:0xf bank_mask:0xf bound_ctrl:1
	s_nop 0
	v_readlane_b32 s2, v4, 0
	v_readlane_b32 s5, v4, 16
	v_readlane_b32 s3, v4, 32
	v_readlane_b32 s7, v4, 48
	s_and_saveexec_b64 s[20:21], vcc
	s_cbranch_execz .LBB0_545
	s_lshl_b32 s9, s60, 2
	s_add_u32 s34, s36, s9
	v_mov_b32_e32 v32, s5
	v_mov_b32_e32 v33, s7
	s_addc_u32 s35, s37, 0
	v_pk_add_f32 v[32:33], s[2:3], v[32:33]
	s_nop 0
	v_add_f32_e32 v4, v32, v33
	v_mov_b64_e32 v[32:33], s[34:35]
	global_store_dword v[32:33], v4, off offset:8
.LBB0_545:
	s_or_b64 exec, exec, s[20:21]
	v_and_b32_e32 v4, 0xffff0000, v5
	v_mul_f32_e32 v5, v31, v17
	s_mov_b32 s31, s43
	s_nop 0
	v_mov_b32_dpp v5, v5 quad_perm:[1,0,3,2] row_mask:0xf bank_mask:0xf bound_ctrl:1
	v_fmac_f32_e32 v5, v31, v17
	s_nop 1
	v_add_f32_dpp v5, v5, v5 quad_perm:[2,3,0,1] row_mask:0xf bank_mask:0xf bound_ctrl:1
	s_nop 1
	v_add_f32_dpp v5, v5, v5 row_half_mirror row_mask:0xf bank_mask:0xf bound_ctrl:1
	s_nop 1
	v_add_f32_dpp v5, v5, v5 row_mirror row_mask:0xf bank_mask:0xf bound_ctrl:1
	s_nop 0
	v_readlane_b32 s3, v5, 16
	v_readlane_b32 s7, v5, 48
	v_readlane_b32 s2, v5, 0
	v_readlane_b32 s5, v5, 32
	v_mov_b32_e32 v5, s3
	v_mov_b32_e32 v32, s7
	v_add_f32_e32 v5, s2, v5
	v_add_f32_e32 v32, s5, v32
	v_add_f32_e32 v5, v5, v32
	v_mul_f32_e32 v5, v5, v16
	v_fma_f32 v31, v19, v31, -v5
	v_fmac_f32_e32 v31, v15, v4
	v_mul_f32_e32 v4, v31, v14
	s_nop 1
	v_mov_b32_dpp v4, v4 quad_perm:[1,0,3,2] row_mask:0xf bank_mask:0xf bound_ctrl:1
	v_fmac_f32_e32 v4, v31, v14
	s_nop 1
	v_add_f32_dpp v4, v4, v4 quad_perm:[2,3,0,1] row_mask:0xf bank_mask:0xf bound_ctrl:1
	s_nop 1
	v_add_f32_dpp v4, v4, v4 row_half_mirror row_mask:0xf bank_mask:0xf bound_ctrl:1
	s_nop 1
	v_add_f32_dpp v4, v4, v4 row_mirror row_mask:0xf bank_mask:0xf bound_ctrl:1
	s_nop 0
	v_readlane_b32 s2, v4, 0
	v_readlane_b32 s5, v4, 16
	v_readlane_b32 s3, v4, 32
	v_readlane_b32 s7, v4, 48
	v_lshl_add_u64 v[4:5], v[12:13], 0, s[30:31]
	global_store_dword v[4:5], v31, off
	s_and_saveexec_b64 s[20:21], vcc
	s_cbranch_execz .LBB0_547
	s_lshl_b32 s9, s60, 2
	s_add_u32 s30, s36, s9
	v_mov_b32_e32 v4, s5
	v_mov_b32_e32 v5, s7
	s_addc_u32 s31, s37, 0
	v_pk_add_f32 v[4:5], s[2:3], v[4:5]
	s_nop 0
	v_add_f32_e32 v31, v4, v5
	v_mov_b64_e32 v[4:5], s[30:31]
	global_store_dword v[4:5], v31, off offset:12
.LBB0_547:
	s_or_b64 exec, exec, s[20:21]
	v_mul_f32_e32 v5, v30, v17
	v_lshlrev_b32_e32 v4, 16, v6
	s_mov_b32 s29, s43
	v_mov_b32_dpp v5, v5 quad_perm:[1,0,3,2] row_mask:0xf bank_mask:0xf bound_ctrl:1
	v_fmac_f32_e32 v5, v30, v17
	s_nop 1
	v_add_f32_dpp v5, v5, v5 quad_perm:[2,3,0,1] row_mask:0xf bank_mask:0xf bound_ctrl:1
	s_nop 1
	v_add_f32_dpp v5, v5, v5 row_half_mirror row_mask:0xf bank_mask:0xf bound_ctrl:1
	s_nop 1
	v_add_f32_dpp v5, v5, v5 row_mirror row_mask:0xf bank_mask:0xf bound_ctrl:1
	s_nop 0
	v_readlane_b32 s3, v5, 16
	v_readlane_b32 s7, v5, 48
	v_readlane_b32 s2, v5, 0
	v_readlane_b32 s5, v5, 32
	v_mov_b32_e32 v5, s3
	v_mov_b32_e32 v31, s7
	v_add_f32_e32 v5, s2, v5
	v_add_f32_e32 v31, s5, v31
	v_add_f32_e32 v5, v5, v31
	v_mul_f32_e32 v5, v5, v16
	v_fma_f32 v30, v19, v30, -v5
	v_fmac_f32_e32 v30, v15, v4
	v_mul_f32_e32 v4, v30, v14
	s_nop 1
	v_mov_b32_dpp v4, v4 quad_perm:[1,0,3,2] row_mask:0xf bank_mask:0xf bound_ctrl:1
	v_fmac_f32_e32 v4, v30, v14
	s_nop 1
	v_add_f32_dpp v4, v4, v4 quad_perm:[2,3,0,1] row_mask:0xf bank_mask:0xf bound_ctrl:1
	s_nop 1
	v_add_f32_dpp v4, v4, v4 row_half_mirror row_mask:0xf bank_mask:0xf bound_ctrl:1
	s_nop 1
	v_add_f32_dpp v4, v4, v4 row_mirror row_mask:0xf bank_mask:0xf bound_ctrl:1
	s_nop 0
	v_readlane_b32 s2, v4, 0
	v_readlane_b32 s5, v4, 16
	v_readlane_b32 s3, v4, 32
	v_readlane_b32 s7, v4, 48
	v_lshl_add_u64 v[4:5], v[12:13], 0, s[28:29]
	global_store_dword v[4:5], v30, off
	s_and_saveexec_b64 s[20:21], vcc
	s_cbranch_execz .LBB0_549
	s_lshl_b32 s9, s60, 2
	s_add_u32 s28, s36, s9
	v_mov_b32_e32 v4, s5
	v_mov_b32_e32 v5, s7
	s_addc_u32 s29, s37, 0
	v_pk_add_f32 v[4:5], s[2:3], v[4:5]
	s_nop 0
	v_add_f32_e32 v30, v4, v5
	v_mov_b64_e32 v[4:5], s[28:29]
	global_store_dword v[4:5], v30, off offset:16
.LBB0_549:
	s_or_b64 exec, exec, s[20:21]
	v_mul_f32_e32 v5, v29, v17
	v_and_b32_e32 v4, 0xffff0000, v6
	s_mov_b32 s25, s43
	v_mov_b32_dpp v5, v5 quad_perm:[1,0,3,2] row_mask:0xf bank_mask:0xf bound_ctrl:1
	v_fmac_f32_e32 v5, v29, v17
	s_nop 1
	v_add_f32_dpp v5, v5, v5 quad_perm:[2,3,0,1] row_mask:0xf bank_mask:0xf bound_ctrl:1
	s_nop 1
	v_add_f32_dpp v5, v5, v5 row_half_mirror row_mask:0xf bank_mask:0xf bound_ctrl:1
	s_nop 1
	v_add_f32_dpp v5, v5, v5 row_mirror row_mask:0xf bank_mask:0xf bound_ctrl:1
	s_nop 0
	v_readlane_b32 s3, v5, 16
	v_readlane_b32 s7, v5, 48
	v_readlane_b32 s2, v5, 0
	v_readlane_b32 s5, v5, 32
	v_mov_b32_e32 v5, s3
	v_mov_b32_e32 v6, s7
	v_add_f32_e32 v5, s2, v5
	v_add_f32_e32 v6, s5, v6
	v_add_f32_e32 v5, v5, v6
	v_mul_f32_e32 v5, v5, v16
	v_fma_f32 v6, v19, v29, -v5
	v_fmac_f32_e32 v6, v15, v4
	v_mul_f32_e32 v4, v6, v14
	s_nop 1
	v_mov_b32_dpp v4, v4 quad_perm:[1,0,3,2] row_mask:0xf bank_mask:0xf bound_ctrl:1
	v_fmac_f32_e32 v4, v6, v14
	s_nop 1
	v_add_f32_dpp v4, v4, v4 quad_perm:[2,3,0,1] row_mask:0xf bank_mask:0xf bound_ctrl:1
	s_nop 1
	v_add_f32_dpp v4, v4, v4 row_half_mirror row_mask:0xf bank_mask:0xf bound_ctrl:1
	s_nop 1
	v_add_f32_dpp v4, v4, v4 row_mirror row_mask:0xf bank_mask:0xf bound_ctrl:1
	s_nop 0
	v_readlane_b32 s2, v4, 0
	v_readlane_b32 s5, v4, 16
	v_readlane_b32 s3, v4, 32
	v_readlane_b32 s7, v4, 48
	v_lshl_add_u64 v[4:5], v[12:13], 0, s[24:25]
	global_store_dword v[4:5], v6, off
	s_and_saveexec_b64 s[20:21], vcc
	s_cbranch_execz .LBB0_551
	s_lshl_b32 s9, s60, 2
	s_add_u32 s24, s36, s9
	v_mov_b32_e32 v4, s5
	v_mov_b32_e32 v5, s7
	s_addc_u32 s25, s37, 0
	v_pk_add_f32 v[4:5], s[2:3], v[4:5]
	s_nop 0
	v_add_f32_e32 v6, v4, v5
	v_mov_b64_e32 v[4:5], s[24:25]
	global_store_dword v[4:5], v6, off offset:20
.LBB0_551:
	s_or_b64 exec, exec, s[20:21]
	v_mul_f32_e32 v5, v28, v17
	v_lshlrev_b32_e32 v4, 16, v7
	s_nop 0
	v_mov_b32_dpp v5, v5 quad_perm:[1,0,3,2] row_mask:0xf bank_mask:0xf bound_ctrl:1
	v_fmac_f32_e32 v5, v28, v17
	s_nop 1
	v_add_f32_dpp v5, v5, v5 quad_perm:[2,3,0,1] row_mask:0xf bank_mask:0xf bound_ctrl:1
	s_nop 1
	v_add_f32_dpp v5, v5, v5 row_half_mirror row_mask:0xf bank_mask:0xf bound_ctrl:1
	s_nop 1
	v_add_f32_dpp v5, v5, v5 row_mirror row_mask:0xf bank_mask:0xf bound_ctrl:1
	s_nop 0
	v_readlane_b32 s3, v5, 16
	v_readlane_b32 s7, v5, 48
	v_readlane_b32 s2, v5, 0
	v_readlane_b32 s5, v5, 32
	v_mov_b32_e32 v5, s3
	v_mov_b32_e32 v6, s7
	v_add_f32_e32 v5, s2, v5
	v_add_f32_e32 v6, s5, v6
	v_add_f32_e32 v5, v5, v6
	v_mul_f32_e32 v5, v5, v16
	v_fma_f32 v6, v19, v28, -v5
	v_fmac_f32_e32 v6, v15, v4
	v_mul_f32_e32 v4, v6, v14
	s_mov_b32 s7, s43
	s_nop 0
	v_mov_b32_dpp v4, v4 quad_perm:[1,0,3,2] row_mask:0xf bank_mask:0xf bound_ctrl:1
	v_fmac_f32_e32 v4, v6, v14
	s_nop 1
	v_add_f32_dpp v4, v4, v4 quad_perm:[2,3,0,1] row_mask:0xf bank_mask:0xf bound_ctrl:1
	s_nop 1
	v_add_f32_dpp v4, v4, v4 row_half_mirror row_mask:0xf bank_mask:0xf bound_ctrl:1
	s_nop 1
	v_add_f32_dpp v4, v4, v4 row_mirror row_mask:0xf bank_mask:0xf bound_ctrl:1
	s_nop 0
	v_readlane_b32 s2, v4, 0
	v_readlane_b32 s5, v4, 16
	v_readlane_b32 s3, v4, 32
	v_readlane_b32 s9, v4, 48
	v_lshl_add_u64 v[4:5], v[12:13], 0, s[6:7]
	global_store_dword v[4:5], v6, off
	s_and_saveexec_b64 s[6:7], vcc
	s_cbranch_execz .LBB0_553
	s_lshl_b32 s11, s60, 2
	s_add_u32 s20, s36, s11
	v_mov_b32_e32 v4, s5
	v_mov_b32_e32 v5, s9
	s_addc_u32 s21, s37, 0
	v_pk_add_f32 v[4:5], s[2:3], v[4:5]
	s_nop 0
	v_add_f32_e32 v6, v4, v5
	v_mov_b64_e32 v[4:5], s[20:21]
	global_store_dword v[4:5], v6, off offset:24
.LBB0_553:
	s_or_b64 exec, exec, s[6:7]
	v_mul_f32_e32 v5, v27, v17
	v_and_b32_e32 v4, 0xffff0000, v7
	s_mov_b32 s23, s43
	v_mov_b32_dpp v5, v5 quad_perm:[1,0,3,2] row_mask:0xf bank_mask:0xf bound_ctrl:1
	v_fmac_f32_e32 v5, v27, v17
	s_nop 1
	v_add_f32_dpp v5, v5, v5 quad_perm:[2,3,0,1] row_mask:0xf bank_mask:0xf bound_ctrl:1
	s_nop 1
	v_add_f32_dpp v5, v5, v5 row_half_mirror row_mask:0xf bank_mask:0xf bound_ctrl:1
	s_nop 1
	v_add_f32_dpp v5, v5, v5 row_mirror row_mask:0xf bank_mask:0xf bound_ctrl:1
	s_nop 0
	v_readlane_b32 s3, v5, 16
	v_readlane_b32 s6, v5, 48
	v_readlane_b32 s2, v5, 0
	v_readlane_b32 s5, v5, 32
	v_mov_b32_e32 v5, s3
	v_mov_b32_e32 v6, s6
	v_add_f32_e32 v5, s2, v5
	v_add_f32_e32 v6, s5, v6
	v_add_f32_e32 v5, v5, v6
	v_mul_f32_e32 v5, v5, v16
	v_fma_f32 v6, v19, v27, -v5
	v_fmac_f32_e32 v6, v15, v4
	v_mul_f32_e32 v4, v6, v14
	s_nop 1
	v_mov_b32_dpp v4, v4 quad_perm:[1,0,3,2] row_mask:0xf bank_mask:0xf bound_ctrl:1
	v_fmac_f32_e32 v4, v6, v14
	s_nop 1
	v_add_f32_dpp v4, v4, v4 quad_perm:[2,3,0,1] row_mask:0xf bank_mask:0xf bound_ctrl:1
	s_nop 1
	v_add_f32_dpp v4, v4, v4 row_half_mirror row_mask:0xf bank_mask:0xf bound_ctrl:1
	s_nop 1
	v_add_f32_dpp v4, v4, v4 row_mirror row_mask:0xf bank_mask:0xf bound_ctrl:1
	s_nop 0
	v_readlane_b32 s2, v4, 0
	v_readlane_b32 s5, v4, 16
	v_readlane_b32 s3, v4, 32
	v_readlane_b32 s9, v4, 48
	v_lshl_add_u64 v[4:5], v[12:13], 0, s[22:23]
	global_store_dword v[4:5], v6, off
	s_and_saveexec_b64 s[6:7], vcc
	s_cbranch_execz .LBB0_555
	s_lshl_b32 s11, s60, 2
	s_add_u32 s20, s36, s11
	v_mov_b32_e32 v4, s5
	v_mov_b32_e32 v5, s9
	s_addc_u32 s21, s37, 0
	v_pk_add_f32 v[4:5], s[2:3], v[4:5]
	s_nop 0
	v_add_f32_e32 v6, v4, v5
	v_mov_b64_e32 v[4:5], s[20:21]
	global_store_dword v[4:5], v6, off offset:28
.LBB0_555:
	s_or_b64 exec, exec, s[6:7]
	v_mul_f32_e32 v5, v26, v17
	v_lshlrev_b32_e32 v4, 16, v0
	s_mov_b32 s27, s43
	v_mov_b32_dpp v5, v5 quad_perm:[1,0,3,2] row_mask:0xf bank_mask:0xf bound_ctrl:1
	v_fmac_f32_e32 v5, v26, v17
	s_nop 1
	v_add_f32_dpp v5, v5, v5 quad_perm:[2,3,0,1] row_mask:0xf bank_mask:0xf bound_ctrl:1
	s_nop 1
	v_add_f32_dpp v5, v5, v5 row_half_mirror row_mask:0xf bank_mask:0xf bound_ctrl:1
	s_nop 1
	v_add_f32_dpp v5, v5, v5 row_mirror row_mask:0xf bank_mask:0xf bound_ctrl:1
	s_nop 0
	v_readlane_b32 s3, v5, 16
	v_readlane_b32 s6, v5, 48
	v_readlane_b32 s2, v5, 0
	v_readlane_b32 s5, v5, 32
	v_mov_b32_e32 v5, s3
	v_mov_b32_e32 v6, s6
	v_add_f32_e32 v5, s2, v5
	v_add_f32_e32 v6, s5, v6
	v_add_f32_e32 v5, v5, v6
	v_mul_f32_e32 v5, v5, v16
	v_fma_f32 v6, v19, v26, -v5
	v_fmac_f32_e32 v6, v15, v4
	v_mul_f32_e32 v4, v6, v14
	s_nop 1
	v_mov_b32_dpp v4, v4 quad_perm:[1,0,3,2] row_mask:0xf bank_mask:0xf bound_ctrl:1
	v_fmac_f32_e32 v4, v6, v14
	s_nop 1
	v_add_f32_dpp v4, v4, v4 quad_perm:[2,3,0,1] row_mask:0xf bank_mask:0xf bound_ctrl:1
	s_nop 1
	v_add_f32_dpp v4, v4, v4 row_half_mirror row_mask:0xf bank_mask:0xf bound_ctrl:1
	s_nop 1
	v_add_f32_dpp v4, v4, v4 row_mirror row_mask:0xf bank_mask:0xf bound_ctrl:1
	s_nop 0
	v_readlane_b32 s2, v4, 0
	v_readlane_b32 s5, v4, 16
	v_readlane_b32 s3, v4, 32
	v_readlane_b32 s9, v4, 48
	v_lshl_add_u64 v[4:5], v[12:13], 0, s[26:27]
	global_store_dword v[4:5], v6, off
	s_and_saveexec_b64 s[6:7], vcc
	s_cbranch_execz .LBB0_557
	s_lshl_b32 s11, s60, 2
	s_add_u32 s20, s36, s11
	v_mov_b32_e32 v4, s5
	v_mov_b32_e32 v5, s9
	s_addc_u32 s21, s37, 0
	v_pk_add_f32 v[4:5], s[2:3], v[4:5]
	s_nop 0
	v_add_f32_e32 v6, v4, v5
	v_mov_b64_e32 v[4:5], s[20:21]
	global_store_dword v[4:5], v6, off offset:32
.LBB0_557:
	s_or_b64 exec, exec, s[6:7]
	v_mul_f32_e32 v4, v25, v17
	v_and_b32_e32 v0, 0xffff0000, v0
	s_mov_b32 s19, s43
	v_mov_b32_dpp v4, v4 quad_perm:[1,0,3,2] row_mask:0xf bank_mask:0xf bound_ctrl:1
	v_fmac_f32_e32 v4, v25, v17
	s_nop 1
	v_add_f32_dpp v4, v4, v4 quad_perm:[2,3,0,1] row_mask:0xf bank_mask:0xf bound_ctrl:1
	s_nop 1
	v_add_f32_dpp v4, v4, v4 row_half_mirror row_mask:0xf bank_mask:0xf bound_ctrl:1
	s_nop 1
	v_add_f32_dpp v4, v4, v4 row_mirror row_mask:0xf bank_mask:0xf bound_ctrl:1
	s_nop 0
	v_readlane_b32 s3, v4, 16
	v_readlane_b32 s6, v4, 48
	v_readlane_b32 s2, v4, 0
	v_readlane_b32 s5, v4, 32
	v_mov_b32_e32 v4, s3
	v_mov_b32_e32 v5, s6
	v_add_f32_e32 v4, s2, v4
	v_add_f32_e32 v5, s5, v5
	v_add_f32_e32 v4, v4, v5
	v_mul_f32_e32 v4, v4, v16
	v_fma_f32 v6, v19, v25, -v4
	v_fmac_f32_e32 v6, v15, v0
	v_mul_f32_e32 v0, v6, v14
	v_lshl_add_u64 v[4:5], v[12:13], 0, s[18:19]
	global_store_dword v[4:5], v6, off
	v_mov_b32_dpp v0, v0 quad_perm:[1,0,3,2] row_mask:0xf bank_mask:0xf bound_ctrl:1
	v_fmac_f32_e32 v0, v6, v14
	s_nop 1
	v_add_f32_dpp v0, v0, v0 quad_perm:[2,3,0,1] row_mask:0xf bank_mask:0xf bound_ctrl:1
	s_nop 1
	v_add_f32_dpp v0, v0, v0 row_half_mirror row_mask:0xf bank_mask:0xf bound_ctrl:1
	s_nop 1
	v_add_f32_dpp v0, v0, v0 row_mirror row_mask:0xf bank_mask:0xf bound_ctrl:1
	s_nop 0
	v_readlane_b32 s2, v0, 0
	v_readlane_b32 s5, v0, 16
	v_readlane_b32 s3, v0, 32
	v_readlane_b32 s9, v0, 48
	s_and_saveexec_b64 s[6:7], vcc
	s_cbranch_execz .LBB0_559
	s_lshl_b32 s11, s60, 2
	s_add_u32 s18, s36, s11
	v_mov_b32_e32 v4, s5
	v_mov_b32_e32 v5, s9
	s_addc_u32 s19, s37, 0
	v_pk_add_f32 v[4:5], s[2:3], v[4:5]
	s_nop 0
	v_add_f32_e32 v0, v4, v5
	v_mov_b64_e32 v[4:5], s[18:19]
	global_store_dword v[4:5], v0, off offset:36
.LBB0_559:
	s_or_b64 exec, exec, s[6:7]
	v_mul_f32_e32 v4, v24, v17
	v_lshlrev_b32_e32 v0, 16, v1
	s_mov_b32 s17, s43
	v_mov_b32_dpp v4, v4 quad_perm:[1,0,3,2] row_mask:0xf bank_mask:0xf bound_ctrl:1
	v_fmac_f32_e32 v4, v24, v17
	s_nop 1
	v_add_f32_dpp v4, v4, v4 quad_perm:[2,3,0,1] row_mask:0xf bank_mask:0xf bound_ctrl:1
	s_nop 1
	v_add_f32_dpp v4, v4, v4 row_half_mirror row_mask:0xf bank_mask:0xf bound_ctrl:1
	s_nop 1
	v_add_f32_dpp v4, v4, v4 row_mirror row_mask:0xf bank_mask:0xf bound_ctrl:1
	s_nop 0
	v_readlane_b32 s3, v4, 16
	v_readlane_b32 s6, v4, 48
	v_readlane_b32 s2, v4, 0
	v_readlane_b32 s5, v4, 32
	v_mov_b32_e32 v4, s3
	v_mov_b32_e32 v5, s6
	v_add_f32_e32 v4, s2, v4
	v_add_f32_e32 v5, s5, v5
	v_add_f32_e32 v4, v4, v5
	v_mul_f32_e32 v4, v4, v16
	v_fma_f32 v6, v19, v24, -v4
	v_fmac_f32_e32 v6, v15, v0
	v_mul_f32_e32 v0, v6, v14
	v_lshl_add_u64 v[4:5], v[12:13], 0, s[16:17]
	global_store_dword v[4:5], v6, off
	v_mov_b32_dpp v0, v0 quad_perm:[1,0,3,2] row_mask:0xf bank_mask:0xf bound_ctrl:1
	v_fmac_f32_e32 v0, v6, v14
	s_nop 1
	v_add_f32_dpp v0, v0, v0 quad_perm:[2,3,0,1] row_mask:0xf bank_mask:0xf bound_ctrl:1
	s_nop 1
	v_add_f32_dpp v0, v0, v0 row_half_mirror row_mask:0xf bank_mask:0xf bound_ctrl:1
	s_nop 1
	v_add_f32_dpp v0, v0, v0 row_mirror row_mask:0xf bank_mask:0xf bound_ctrl:1
	s_nop 0
	v_readlane_b32 s2, v0, 0
	v_readlane_b32 s5, v0, 16
	v_readlane_b32 s3, v0, 32
	v_readlane_b32 s9, v0, 48
	s_and_saveexec_b64 s[6:7], vcc
	s_cbranch_execz .LBB0_561
	s_lshl_b32 s11, s60, 2
	s_add_u32 s16, s36, s11
	v_mov_b32_e32 v4, s5
	v_mov_b32_e32 v5, s9
	s_addc_u32 s17, s37, 0
	v_pk_add_f32 v[4:5], s[2:3], v[4:5]
	s_nop 0
	v_add_f32_e32 v0, v4, v5
	v_mov_b64_e32 v[4:5], s[16:17]
	global_store_dword v[4:5], v0, off offset:40
.LBB0_561:
	s_or_b64 exec, exec, s[6:7]
	v_and_b32_e32 v0, 0xffff0000, v1
	v_mul_f32_e32 v1, v23, v17
	s_mov_b32 s15, s43
	s_nop 0
	v_mov_b32_dpp v1, v1 quad_perm:[1,0,3,2] row_mask:0xf bank_mask:0xf bound_ctrl:1
	v_fmac_f32_e32 v1, v23, v17
	s_nop 1
	v_add_f32_dpp v1, v1, v1 quad_perm:[2,3,0,1] row_mask:0xf bank_mask:0xf bound_ctrl:1
	s_nop 1
	v_add_f32_dpp v1, v1, v1 row_half_mirror row_mask:0xf bank_mask:0xf bound_ctrl:1
	s_nop 1
	v_add_f32_dpp v1, v1, v1 row_mirror row_mask:0xf bank_mask:0xf bound_ctrl:1
	s_nop 0
	v_readlane_b32 s3, v1, 16
	v_readlane_b32 s6, v1, 48
	v_readlane_b32 s2, v1, 0
	v_readlane_b32 s5, v1, 32
	v_mov_b32_e32 v1, s3
	v_mov_b32_e32 v4, s6
	v_add_f32_e32 v1, s2, v1
	v_add_f32_e32 v4, s5, v4
	v_add_f32_e32 v1, v1, v4
	v_mul_f32_e32 v1, v1, v16
	v_fma_f32 v4, v19, v23, -v1
	v_fmac_f32_e32 v4, v15, v0
	v_mul_f32_e32 v0, v4, v14
	s_nop 1
	v_mov_b32_dpp v0, v0 quad_perm:[1,0,3,2] row_mask:0xf bank_mask:0xf bound_ctrl:1
	v_fmac_f32_e32 v0, v4, v14
	s_nop 1
	v_add_f32_dpp v0, v0, v0 quad_perm:[2,3,0,1] row_mask:0xf bank_mask:0xf bound_ctrl:1
	s_nop 1
	v_add_f32_dpp v0, v0, v0 row_half_mirror row_mask:0xf bank_mask:0xf bound_ctrl:1
	s_nop 1
	v_add_f32_dpp v0, v0, v0 row_mirror row_mask:0xf bank_mask:0xf bound_ctrl:1
	s_nop 0
	v_readlane_b32 s2, v0, 0
	v_readlane_b32 s5, v0, 16
	v_readlane_b32 s3, v0, 32
	v_readlane_b32 s9, v0, 48
	v_lshl_add_u64 v[0:1], v[12:13], 0, s[14:15]
	global_store_dword v[0:1], v4, off
	s_and_saveexec_b64 s[6:7], vcc
	s_cbranch_execz .LBB0_563
	s_lshl_b32 s11, s60, 2
	s_add_u32 s14, s36, s11
	v_mov_b32_e32 v0, s5
	v_mov_b32_e32 v1, s9
	s_addc_u32 s15, s37, 0
	v_pk_add_f32 v[0:1], s[2:3], v[0:1]
	s_nop 0
	v_add_f32_e32 v4, v0, v1
	v_mov_b64_e32 v[0:1], s[14:15]
	global_store_dword v[0:1], v4, off offset:44
.LBB0_563:
	s_or_b64 exec, exec, s[6:7]
	v_mul_f32_e32 v1, v22, v17
	v_lshlrev_b32_e32 v0, 16, v2
	s_mov_b32 s13, s43
	v_mov_b32_dpp v1, v1 quad_perm:[1,0,3,2] row_mask:0xf bank_mask:0xf bound_ctrl:1
	v_fmac_f32_e32 v1, v22, v17
	s_nop 1
	v_add_f32_dpp v1, v1, v1 quad_perm:[2,3,0,1] row_mask:0xf bank_mask:0xf bound_ctrl:1
	s_nop 1
	v_add_f32_dpp v1, v1, v1 row_half_mirror row_mask:0xf bank_mask:0xf bound_ctrl:1
	s_nop 1
	v_add_f32_dpp v1, v1, v1 row_mirror row_mask:0xf bank_mask:0xf bound_ctrl:1
	s_nop 0
	v_readlane_b32 s3, v1, 16
	v_readlane_b32 s6, v1, 48
	v_readlane_b32 s2, v1, 0
	v_readlane_b32 s5, v1, 32
	v_mov_b32_e32 v1, s3
	v_mov_b32_e32 v4, s6
	v_add_f32_e32 v1, s2, v1
	v_add_f32_e32 v4, s5, v4
	v_add_f32_e32 v1, v1, v4
	v_mul_f32_e32 v1, v1, v16
	v_fma_f32 v4, v19, v22, -v1
	v_fmac_f32_e32 v4, v15, v0
	v_mul_f32_e32 v0, v4, v14
	s_nop 1
	v_mov_b32_dpp v0, v0 quad_perm:[1,0,3,2] row_mask:0xf bank_mask:0xf bound_ctrl:1
	v_fmac_f32_e32 v0, v4, v14
	s_nop 1
	v_add_f32_dpp v0, v0, v0 quad_perm:[2,3,0,1] row_mask:0xf bank_mask:0xf bound_ctrl:1
	s_nop 1
	v_add_f32_dpp v0, v0, v0 row_half_mirror row_mask:0xf bank_mask:0xf bound_ctrl:1
	s_nop 1
	v_add_f32_dpp v0, v0, v0 row_mirror row_mask:0xf bank_mask:0xf bound_ctrl:1
	s_nop 0
	v_readlane_b32 s2, v0, 0
	v_readlane_b32 s5, v0, 16
	v_readlane_b32 s3, v0, 32
	v_readlane_b32 s9, v0, 48
	v_lshl_add_u64 v[0:1], v[12:13], 0, s[12:13]
	global_store_dword v[0:1], v4, off
	s_and_saveexec_b64 s[6:7], vcc
	s_cbranch_execz .LBB0_565
	s_lshl_b32 s11, s60, 2
	s_add_u32 s12, s36, s11
	v_mov_b32_e32 v0, s5
	v_mov_b32_e32 v1, s9
	s_addc_u32 s13, s37, 0
	v_pk_add_f32 v[0:1], s[2:3], v[0:1]
	s_nop 0
	v_add_f32_e32 v4, v0, v1
	v_mov_b64_e32 v[0:1], s[12:13]
	global_store_dword v[0:1], v4, off offset:48
.LBB0_565:
	s_or_b64 exec, exec, s[6:7]
	v_mul_f32_e32 v1, v21, v17
	v_and_b32_e32 v0, 0xffff0000, v2
	s_mov_b32 s11, s43
	v_mov_b32_dpp v1, v1 quad_perm:[1,0,3,2] row_mask:0xf bank_mask:0xf bound_ctrl:1
	v_fmac_f32_e32 v1, v21, v17
	s_nop 1
	v_add_f32_dpp v1, v1, v1 quad_perm:[2,3,0,1] row_mask:0xf bank_mask:0xf bound_ctrl:1
	s_nop 1
	v_add_f32_dpp v1, v1, v1 row_half_mirror row_mask:0xf bank_mask:0xf bound_ctrl:1
	s_nop 1
	v_add_f32_dpp v1, v1, v1 row_mirror row_mask:0xf bank_mask:0xf bound_ctrl:1
	s_nop 0
	v_readlane_b32 s3, v1, 16
	v_readlane_b32 s6, v1, 48
	v_readlane_b32 s2, v1, 0
	v_readlane_b32 s5, v1, 32
	v_mov_b32_e32 v1, s3
	v_mov_b32_e32 v2, s6
	v_add_f32_e32 v1, s2, v1
	v_add_f32_e32 v2, s5, v2
	v_add_f32_e32 v1, v1, v2
	v_mul_f32_e32 v1, v1, v16
	v_fma_f32 v2, v19, v21, -v1
	v_fmac_f32_e32 v2, v15, v0
	v_mul_f32_e32 v0, v2, v14
	s_nop 1
	v_mov_b32_dpp v0, v0 quad_perm:[1,0,3,2] row_mask:0xf bank_mask:0xf bound_ctrl:1
	v_fmac_f32_e32 v0, v2, v14
	s_nop 1
	v_add_f32_dpp v0, v0, v0 quad_perm:[2,3,0,1] row_mask:0xf bank_mask:0xf bound_ctrl:1
	s_nop 1
	v_add_f32_dpp v0, v0, v0 row_half_mirror row_mask:0xf bank_mask:0xf bound_ctrl:1
	s_nop 1
	v_add_f32_dpp v0, v0, v0 row_mirror row_mask:0xf bank_mask:0xf bound_ctrl:1
	s_nop 0
	v_readlane_b32 s2, v0, 0
	v_readlane_b32 s5, v0, 16
	v_readlane_b32 s3, v0, 32
	v_readlane_b32 s9, v0, 48
	v_lshl_add_u64 v[0:1], v[12:13], 0, s[10:11]
	global_store_dword v[0:1], v2, off
	s_and_saveexec_b64 s[6:7], vcc
	s_cbranch_execz .LBB0_567
	s_lshl_b32 s10, s60, 2
	s_add_u32 s10, s36, s10
	v_mov_b32_e32 v0, s5
	v_mov_b32_e32 v1, s9
	s_addc_u32 s11, s37, 0
	v_pk_add_f32 v[0:1], s[2:3], v[0:1]
	s_nop 0
	v_add_f32_e32 v2, v0, v1
	v_mov_b64_e32 v[0:1], s[10:11]
	global_store_dword v[0:1], v2, off offset:52
.LBB0_567:
	s_or_b64 exec, exec, s[6:7]
	v_mul_f32_e32 v1, v20, v17
	v_lshlrev_b32_e32 v0, 16, v3
	s_mov_b32 s9, s43
	v_mov_b32_dpp v1, v1 quad_perm:[1,0,3,2] row_mask:0xf bank_mask:0xf bound_ctrl:1
	v_fmac_f32_e32 v1, v20, v17
	s_nop 1
	v_add_f32_dpp v1, v1, v1 quad_perm:[2,3,0,1] row_mask:0xf bank_mask:0xf bound_ctrl:1
	s_nop 1
	v_add_f32_dpp v1, v1, v1 row_half_mirror row_mask:0xf bank_mask:0xf bound_ctrl:1
	s_nop 1
	v_add_f32_dpp v1, v1, v1 row_mirror row_mask:0xf bank_mask:0xf bound_ctrl:1
	s_nop 0
	v_readlane_b32 s3, v1, 16
	v_readlane_b32 s6, v1, 48
	v_readlane_b32 s2, v1, 0
	v_readlane_b32 s5, v1, 32
	v_mov_b32_e32 v1, s3
	v_mov_b32_e32 v2, s6
	v_add_f32_e32 v1, s2, v1
	v_add_f32_e32 v2, s5, v2
	v_add_f32_e32 v1, v1, v2
	v_mul_f32_e32 v1, v1, v16
	v_fma_f32 v2, v19, v20, -v1
	v_fmac_f32_e32 v2, v15, v0
	v_mul_f32_e32 v0, v2, v14
	s_nop 1
	v_mov_b32_dpp v0, v0 quad_perm:[1,0,3,2] row_mask:0xf bank_mask:0xf bound_ctrl:1
	v_fmac_f32_e32 v0, v2, v14
	s_nop 1
	v_add_f32_dpp v0, v0, v0 quad_perm:[2,3,0,1] row_mask:0xf bank_mask:0xf bound_ctrl:1
	s_nop 1
	v_add_f32_dpp v0, v0, v0 row_half_mirror row_mask:0xf bank_mask:0xf bound_ctrl:1
	s_nop 1
	v_add_f32_dpp v0, v0, v0 row_mirror row_mask:0xf bank_mask:0xf bound_ctrl:1
	s_nop 0
	v_readlane_b32 s2, v0, 0
	v_readlane_b32 s5, v0, 16
	v_readlane_b32 s3, v0, 32
	v_readlane_b32 s10, v0, 48
	v_lshl_add_u64 v[0:1], v[12:13], 0, s[8:9]
	global_store_dword v[0:1], v2, off
	s_and_saveexec_b64 s[6:7], vcc
	s_cbranch_execz .LBB0_569
	s_lshl_b32 s8, s60, 2
	s_add_u32 s8, s36, s8
	v_mov_b32_e32 v0, s5
	v_mov_b32_e32 v1, s10
	s_addc_u32 s9, s37, 0
	v_pk_add_f32 v[0:1], s[2:3], v[0:1]
	s_nop 0
	v_add_f32_e32 v2, v0, v1
	v_mov_b64_e32 v[0:1], s[8:9]
	global_store_dword v[0:1], v2, off offset:56
.LBB0_569:
	s_or_b64 exec, exec, s[6:7]
	v_mul_f32_e32 v1, v18, v17
	v_and_b32_e32 v0, 0xffff0000, v3
	s_nop 0
	v_mov_b32_dpp v1, v1 quad_perm:[1,0,3,2] row_mask:0xf bank_mask:0xf bound_ctrl:1
	v_fmac_f32_e32 v1, v18, v17
	s_nop 1
	v_add_f32_dpp v1, v1, v1 quad_perm:[2,3,0,1] row_mask:0xf bank_mask:0xf bound_ctrl:1
	s_nop 1
	v_add_f32_dpp v1, v1, v1 row_half_mirror row_mask:0xf bank_mask:0xf bound_ctrl:1
	s_nop 1
	v_add_f32_dpp v1, v1, v1 row_mirror row_mask:0xf bank_mask:0xf bound_ctrl:1
	s_nop 0
	v_readlane_b32 s3, v1, 16
	v_readlane_b32 s6, v1, 48
	v_readlane_b32 s2, v1, 0
	v_readlane_b32 s5, v1, 32
	v_mov_b32_e32 v1, s3
	v_mov_b32_e32 v2, s6
	v_add_f32_e32 v1, s2, v1
	v_add_f32_e32 v2, s5, v2
	v_add_f32_e32 v1, v1, v2
	v_mul_f32_e32 v1, v1, v16
	v_fma_f32 v2, v19, v18, -v1
	v_fmac_f32_e32 v2, v15, v0
	v_mul_f32_e32 v0, v2, v14
	s_mov_b32 s5, s43
	s_nop 0
	v_mov_b32_dpp v0, v0 quad_perm:[1,0,3,2] row_mask:0xf bank_mask:0xf bound_ctrl:1
	v_fmac_f32_e32 v0, v2, v14
	s_nop 1
	v_add_f32_dpp v0, v0, v0 quad_perm:[2,3,0,1] row_mask:0xf bank_mask:0xf bound_ctrl:1
	s_nop 1
	v_add_f32_dpp v0, v0, v0 row_half_mirror row_mask:0xf bank_mask:0xf bound_ctrl:1
	s_nop 1
	v_add_f32_dpp v0, v0, v0 row_mirror row_mask:0xf bank_mask:0xf bound_ctrl:1
	s_nop 0
	v_readlane_b32 s2, v0, 0
	v_readlane_b32 s6, v0, 16
	v_readlane_b32 s3, v0, 32
	v_readlane_b32 s7, v0, 48
	v_lshl_add_u64 v[0:1], v[12:13], 0, s[4:5]
	global_store_dword v[0:1], v2, off
	s_and_saveexec_b64 s[4:5], vcc
	s_cbranch_execz .LBB0_538
	s_lshl_b32 s8, s60, 2
	s_add_u32 s8, s36, s8
	v_mov_b32_e32 v0, s6
	v_mov_b32_e32 v1, s7
	s_addc_u32 s9, s37, 0
	v_pk_add_f32 v[0:1], s[2:3], v[0:1]
	s_nop 0
	v_add_f32_e32 v2, v0, v1
	v_mov_b64_e32 v[0:1], s[8:9]
	global_store_dword v[0:1], v2, off offset:60
	s_branch .LBB0_538

.LBB0_573:
	s_or_b64 exec, exec, s[10:11]
	global_load_ushort v2, v[6:7], off
	s_movk_i32 s12, 0xe00
	s_waitcnt vmcnt(0) lgkmcnt(0)
	v_lshlrev_b32_e32 v6, 16, v2
	v_mov_b64_e32 v[2:3], s[94:95]
	v_mad_u64_u32 v[2:3], s[10:11], v4, s12, v[2:3]
	v_mov_b32_e32 v4, v3
	v_mad_u64_u32 v[4:5], s[10:11], v5, s12, v[4:5]
	v_mov_b32_e32 v3, v4
	v_lshl_add_u64 v[2:3], v[2:3], 0, v[8:9]
	v_lshl_add_u64 v[0:1], v[0:1], 2, v[2:3]
	s_mov_b32 s10, 0xfbff
	global_store_dword v[0:1], v6, off
	v_add_u32_e32 v0, 0xe000, v12
	v_cmp_lt_i32_e32 vcc, s10, v12
	s_or_b64 s[8:9], vcc, s[8:9]
	v_mov_b32_e32 v12, v0
	s_andn2_b64 exec, exec, s[8:9]
	s_cbranch_execz .LBB0_578

.LBB0_581:
	s_mul_i32 s2, s11, 37
	s_bfe_u32 s3, s2, 0x80008
	s_lshr_b32 s2, s2, 8
	s_sub_i32 s2, s11, s2
	s_bfe_u32 s2, s2, 0x70001
	s_add_i32 s2, s2, s3
	s_bfe_u32 s2, s2, 0x60002
	s_mul_i32 s2, s2, 7
	s_sub_i32 s2, s11, s2
	s_and_b32 s2, s2, 0xff
	s_mulk_i32 s2, 0x4c00
	s_add_i32 s2, s2, 0
	v_add_u32_e32 v92, s2, v28
	v_add_u32_e32 v52, s2, v29
	v_add_u32_e32 v68, s2, v30
	v_add3_u32 v96, s2, v26, v27
	ds_read2st64_b64 v[32:35], v92 offset0:28 offset1:29
	ds_read2st64_b64 v[36:39], v92 offset0:30 offset1:31
	ds_read_b128 v[40:43], v52
	ds_read_b128 v[44:47], v52 offset:2048
	ds_read_b128 v[48:51], v52 offset:4096
	ds_read_b128 v[52:55], v52 offset:6144
	ds_read_b128 v[56:59], v68
	ds_read_b128 v[60:63], v68 offset:2048
	ds_read_b128 v[64:67], v68 offset:4096
	ds_read_b128 v[68:71], v68 offset:6144
	ds_read_b128 v[72:75], v96 offset:8192
	ds_read_b128 v[76:79], v96 offset:9216
	v_cvt_pk_bf16_f32 v80, v0, v1
	v_cvt_pk_bf16_f32 v81, v2, v3
	v_cvt_pk_bf16_f32 v82, v4, v5
	v_cvt_pk_bf16_f32 v83, v6, v7
	s_waitcnt lgkmcnt(0)
	v_lshlrev_b32_e32 v86, 16, v32
	v_and_b32_e32 v87, 0xffff0000, v32
	v_lshlrev_b32_e32 v88, 16, v33
	v_and_b32_e32 v89, 0xffff0000, v33
	v_cvt_pk_bf16_f32 v84, v8, v9
	v_cvt_pk_bf16_f32 v85, v10, v11
	v_mfma_f32_16x16x32_bf16 v[40:43], v[40:43], v[80:83], v[86:89]
	v_lshlrev_b32_e32 v32, 16, v34
	v_and_b32_e32 v33, 0xffff0000, v34
	v_lshlrev_b32_e32 v34, 16, v35
	v_cvt_pk_bf16_f32 v86, v12, v13
	v_cvt_pk_bf16_f32 v87, v14, v15
	v_and_b32_e32 v35, 0xffff0000, v35
	v_add_u32_e32 v93, s2, v31
	v_mfma_f32_16x16x32_bf16 v[40:43], v[56:59], v[84:87], v[40:43]
	v_lshlrev_b32_e32 v56, 16, v36
	v_and_b32_e32 v57, 0xffff0000, v36
	v_lshlrev_b32_e32 v58, 16, v37
	v_and_b32_e32 v59, 0xffff0000, v37
	v_mfma_f32_16x16x32_bf16 v[32:35], v[44:47], v[80:83], v[32:35]
	s_nop 2
	v_cvt_pk_bf16_f32 v40, v40, v41
	v_cvt_pk_bf16_f32 v41, v42, v43
	v_lshlrev_b32_e32 v36, 16, v38
	v_mfma_f32_16x16x32_bf16 v[48:51], v[48:51], v[80:83], v[56:59]
	v_and_b32_e32 v37, 0xffff0000, v38
	v_lshlrev_b32_e32 v38, 16, v39
	v_and_b32_e32 v39, 0xffff0000, v39
	v_mfma_f32_16x16x32_bf16 v[32:35], v[60:63], v[84:87], v[32:35]
	v_add_u32_e32 v97, 0x4800, v93
	ds_read_b128 v[56:59], v96 offset:10240
	ds_read_b128 v[88:91], v96 offset:11264
	s_add_u32 s0, s0, 0x7a00
	v_mfma_f32_16x16x32_bf16 v[48:51], v[64:67], v[84:87], v[48:51]
	s_nop 2
	v_cvt_pk_bf16_f32 v42, v32, v33
	v_cvt_pk_bf16_f32 v43, v34, v35
	ds_read2_b64 v[44:47], v97 offset1:4
	ds_read2st64_b64 v[64:67], v92 offset0:32 offset1:33
	ds_read2st64_b64 v[92:95], v92 offset0:34 offset1:35
	v_mfma_f32_16x16x32_bf16 v[32:35], v[72:75], v[40:43], v[48:51]
	s_addc_u32 s1, s1, 0
	s_add_i32 s10, s10, 1
	s_mov_b64 s[2:3], 0x8000
	v_mfma_f32_16x16x32_bf16 v[36:39], v[52:55], v[80:83], v[36:39]
	v_add_co_u32_e32 v48, vcc, s14, v24
	ds_read2_b64 v[52:55], v97 offset0:8 offset1:12
	ds_read_b128 v[60:63], v96 offset:12288
	ds_read_b128 v[80:83], v96 offset:13312
	v_addc_co_u32_e32 v49, vcc, -1, v25, vcc
	global_store_dword v[48:49], v32, off
	v_add_co_u32_e32 v48, vcc, s15, v24
	v_mfma_f32_16x16x32_bf16 v[36:39], v[68:71], v[84:87], v[36:39]
	s_nop 0
	v_addc_co_u32_e32 v49, vcc, -1, v25, vcc
	v_add_co_u32_e32 v32, vcc, s16, v24
	global_store_dword v[48:49], v33, off
	s_nop 0
	v_addc_co_u32_e32 v33, vcc, -1, v25, vcc
	global_store_dword v[32:33], v34, off
	v_add_co_u32_e32 v32, vcc, s12, v24
	s_cmp_eq_u32 s0, 0x1e8000
	s_nop 0
	v_addc_co_u32_e32 v33, vcc, -1, v25, vcc
	global_store_dword v[32:33], v35, off
	v_mfma_f32_16x16x32_bf16 v[32:35], v[76:79], v[40:43], v[36:39]
	s_nop 2
	v_add_co_u32_e32 v36, vcc, s17, v24
	s_nop 1
	v_addc_co_u32_e32 v37, vcc, -1, v25, vcc
	s_nop 0
	global_store_dword v[36:37], v32, off
	v_add_co_u32_e32 v36, vcc, s18, v24
	s_nop 1
	v_addc_co_u32_e32 v37, vcc, -1, v25, vcc
	v_add_co_u32_e32 v32, vcc, s13, v24
	global_store_dword v[36:37], v33, off
	s_nop 0
	v_addc_co_u32_e32 v33, vcc, -1, v25, vcc
	global_store_dword v[32:33], v34, off
	global_store_dword v[24:25], v35, off
	s_waitcnt lgkmcnt(0)
	v_mov_b32_e32 v37, v44
	v_mov_b32_e32 v35, v65
	v_lshl_add_u64 v[24:25], v[24:25], 0, s[2:3]
	v_lshlrev_b32_e32 v34, 16, v35
	v_and_b32_e32 v35, 0xffff0000, v35
	v_lshlrev_b32_e32 v38, 16, v45
	v_and_b32_e32 v39, 0xffff0000, v45
	v_lshlrev_b32_e32 v32, 16, v64
	v_and_b32_e32 v33, 0xffff0000, v64
	v_lshlrev_b32_e32 v36, 16, v37
	v_and_b32_e32 v37, 0xffff0000, v37
	v_pk_fma_f32 v[2:3], v[2:3], v[38:39], v[34:35]
	v_mov_b32_e32 v35, v67
	v_mov_b32_e32 v39, v47
	v_pk_fma_f32 v[0:1], v[0:1], v[36:37], v[32:33]
	s_nop 0
	v_lshlrev_b32_e32 v32, 16, v66
	v_and_b32_e32 v33, 0xffff0000, v66
	v_lshlrev_b32_e32 v36, 16, v46
	v_and_b32_e32 v37, 0xffff0000, v46
	v_pk_fma_f32 v[4:5], v[4:5], v[36:37], v[32:33]
	v_mov_b32_e32 v33, v92
	v_mov_b32_e32 v37, v52
	v_lshlrev_b32_e32 v34, 16, v35
	v_and_b32_e32 v35, 0xffff0000, v35
	v_lshlrev_b32_e32 v38, 16, v39
	v_and_b32_e32 v39, 0xffff0000, v39
	v_pk_fma_f32 v[6:7], v[6:7], v[38:39], v[34:35]
	v_lshlrev_b32_e32 v32, 16, v33
	v_and_b32_e32 v33, 0xffff0000, v33
	v_lshlrev_b32_e32 v34, 16, v93
	v_and_b32_e32 v35, 0xffff0000, v93
	v_lshlrev_b32_e32 v36, 16, v37
	v_and_b32_e32 v37, 0xffff0000, v37
	v_lshlrev_b32_e32 v38, 16, v53
	v_and_b32_e32 v39, 0xffff0000, v53
	v_pk_fma_f32 v[10:11], v[10:11], v[38:39], v[34:35]
	v_pk_fma_f32 v[8:9], v[8:9], v[36:37], v[32:33]
	v_mov_b32_e32 v37, v54
	v_mov_b32_e32 v35, v95
	v_mfma_f32_16x16x32_bf16 v[0:3], v[56:59], v[40:43], v[0:3]
	v_lshlrev_b32_e32 v32, 16, v94
	v_and_b32_e32 v33, 0xffff0000, v94
	v_lshlrev_b32_e32 v34, 16, v35
	v_and_b32_e32 v35, 0xffff0000, v35
	v_lshlrev_b32_e32 v36, 16, v37
	v_and_b32_e32 v37, 0xffff0000, v37
	v_lshlrev_b32_e32 v38, 16, v55
	v_and_b32_e32 v39, 0xffff0000, v55
	v_pk_fma_f32 v[14:15], v[14:15], v[38:39], v[34:35]
	v_pk_fma_f32 v[12:13], v[12:13], v[36:37], v[32:33]
	v_mfma_f32_16x16x32_bf16 v[4:7], v[88:91], v[40:43], v[4:7]
	v_mfma_f32_16x16x32_bf16 v[8:11], v[60:63], v[40:43], v[8:11]
	v_mfma_f32_16x16x32_bf16 v[12:15], v[80:83], v[40:43], v[12:15]
	s_cbranch_scc1 .LBB0_598

.LBB0_600:
	s_and_b64 vcc, exec, s[0:1]
	s_cbranch_vccz .LBB0_605
	s_mov_b32 s5, s89
	s_lshl_b32 s2, s5, 5
	s_and_b32 s3, s2, 32
	s_ashr_i32 s2, s5, 1
	s_lshl_b32 s10, s2, 7
	v_readlane_b32 s12, v252, 2
	s_ashr_i32 s11, s10, 31
	s_lshl_b32 s4, s56, 11
	v_readlane_b32 s20, v252, 10
	v_readlane_b32 s21, v252, 11
	s_add_u32 s4, s20, s4
	s_addc_u32 s8, s21, 0
	s_lshl_b64 s[6:7], s[10:11], 2
	s_add_u32 s6, s4, s6
	s_addc_u32 s7, s8, s7
	s_lshl_b32 s8, s2, 6
	v_readlane_b32 s13, v252, 3
	s_ashr_i32 s9, s8, 31
	s_mov_b64 s[0:1], s[78:79]
	s_lshl_b64 s[12:13], s[8:9], 1
	v_mbcnt_lo_u32_b32 v57, -1, 0
	v_mbcnt_hi_u32_b32 v57, -1, v57
	s_add_u32 s12, s0, s12
	v_bfe_u32 v47, v57, 4, 2
	v_and_b32_e32 v37, 15, v57
	s_addc_u32 s13, s1, s13
	v_lshlrev_b32_e32 v194, 3, v47
	v_lshl_add_u64 v[0:1], s[12:13], 0, v[194:195]
	s_mov_b64 s[12:13], 0x2040000
	v_or_b32_e32 v2, s3, v37
	v_readlane_b32 s4, v253, 36
	v_lshl_add_u64 v[0:1], v[0:1], 0, s[12:13]
	v_lshlrev_b32_e32 v4, 2, v2
	v_or_b32_e32 v2, s4, v2
	v_mad_i64_i32 v[2:3], s[12:13], v2, s86, v[0:1]
	s_or_b32 s2, s3, 16
	global_load_dwordx2 v[74:75], v[2:3], off
	global_load_dwordx2 v[72:73], v[2:3], off offset:32
	global_load_dwordx2 v[70:71], v[2:3], off offset:64
	global_load_dwordx2 v[68:69], v[2:3], off offset:96
	v_or_b32_e32 v2, s2, v37
	v_or_b32_e32 v2, s4, v2
	v_or_b32_e32 v5, 64, v37
	v_mad_i64_i32 v[2:3], s[12:13], v2, s86, v[0:1]
	v_or_b32_e32 v6, s3, v5
	global_load_dwordx2 v[64:65], v[2:3], off
	global_load_dwordx2 v[62:63], v[2:3], off offset:32
	global_load_dwordx2 v[60:61], v[2:3], off offset:64
	global_load_dwordx2 v[58:59], v[2:3], off offset:96
	v_or_b32_e32 v2, s4, v6
	v_mad_i64_i32 v[2:3], s[12:13], v2, s86, v[0:1]
	global_load_dword v66, v4, s[6:7]
	global_load_dword v56, v4, s[6:7] offset:64
	global_load_dword v46, v4, s[6:7] offset:256
	global_load_dwordx2 v[54:55], v[2:3], off
	global_load_dwordx2 v[52:53], v[2:3], off offset:32
	global_load_dwordx2 v[50:51], v[2:3], off offset:64
	global_load_dwordx2 v[48:49], v[2:3], off offset:96
	v_or_b32_e32 v2, s2, v5
	v_lshlrev_b32_e32 v3, 2, v6
	v_or_b32_e32 v2, s4, v2
	global_load_dword v36, v3, s[6:7] offset:64
	v_mad_i64_i32 v[0:1], s[6:7], v2, s86, v[0:1]
	global_load_dwordx2 v[44:45], v[0:1], off
	global_load_dwordx2 v[42:43], v[0:1], off offset:32
	global_load_dwordx2 v[40:41], v[0:1], off offset:64
	global_load_dwordx2 v[38:39], v[0:1], off offset:96
	s_cmpk_gt_i32 s5, 0x7f
	v_readlane_b32 s14, v252, 4
	v_readlane_b32 s15, v252, 5
	v_readlane_b32 s16, v252, 6
	v_readlane_b32 s17, v252, 7
	v_readlane_b32 s18, v252, 8
	v_readlane_b32 s19, v252, 9
	v_readlane_b32 s22, v252, 12
	v_readlane_b32 s23, v252, 13
	v_readlane_b32 s24, v252, 14
	v_readlane_b32 s25, v252, 15
	v_readlane_b32 s26, v252, 16
	v_readlane_b32 s27, v252, 17
	s_cbranch_scc1 .LBB0_604
	v_readlane_b32 s12, v252, 2
	v_readlane_b32 s13, v252, 3
	v_readlane_b32 s16, v252, 6
	v_readlane_b32 s12, v255, 41
	v_readlane_b32 s17, v252, 7
	v_readlane_b32 s13, v255, 42
	s_add_u32 s6, s16, s12
	v_readlane_b32 s14, v252, 4
	s_addc_u32 s7, s17, s13
	v_and_b32_e32 v4, 63, v57
	v_readlane_b32 s15, v252, 5
	s_add_u32 s12, s14, s12
	s_addc_u32 s13, s15, s13
	v_lshlrev_b32_e32 v194, 2, v4
	global_load_dword v67, v194, s[12:13]
	global_load_dword v106, v194, s[6:7]
	global_load_dword v107, v194, s[12:13] offset:256
	global_load_dword v108, v194, s[6:7] offset:256
	global_load_dword v110, v194, s[12:13] offset:512
	global_load_dword v111, v194, s[6:7] offset:512
	global_load_dword v112, v194, s[12:13] offset:768
	global_load_dword v113, v194, s[6:7] offset:768
	s_add_i32 s4, s5, 0xffffff80
	s_lshl_b32 s5, s5, 1
	s_add_i32 s5, s5, 0
	v_readlane_b32 s18, v252, 8
	v_readlane_b32 s20, v252, 10
	v_or_b32_e32 v6, 64, v4
	v_or_b32_e32 v8, 0x80, v4
	v_or_b32_e32 v10, 0xc0, v4
	v_mov_b32_e32 v5, s5
	s_movk_i32 s5, 0x108
	s_mov_b32 s20, 0x3b800000
	s_mov_b32 s18, 0x800000
	v_lshl_add_u64 v[0:1], s[12:13], 0, v[194:195]
	v_lshl_add_u64 v[2:3], s[6:7], 0, v[194:195]
	v_mad_u32_u24 v114, v4, s5, v5
	v_lshlrev_b32_e32 v194, 1, v4
	v_lshlrev_b32_e32 v4, 1, v6
	v_lshlrev_b32_e32 v6, 1, v8
	v_lshlrev_b32_e32 v8, 1, v10
	v_readlane_b32 s19, v252, 9
	v_readlane_b32 s21, v252, 11
	v_readlane_b32 s22, v252, 12
	v_readlane_b32 s23, v252, 13
	v_readlane_b32 s24, v252, 14
	v_readlane_b32 s25, v252, 15
	v_readlane_b32 s26, v252, 16
	v_readlane_b32 s27, v252, 17
.LBB0_603:
	s_add_i32 s6, s65, s4
	s_mul_i32 s5, s6, 0x1400
	s_add_i32 s7, s6, 0xffffc080
	s_add_i32 s9, s5, 0xfb0a0000
	s_mul_hi_i32 s7, s7, 0x1400
	s_add_u32 s9, s0, s9
	s_addc_u32 s7, s1, s7
	s_add_u32 s12, s9, 0x2040200
	s_addc_u32 s13, s7, 0
	s_add_i32 s7, s6, 0xffffc088
	s_add_i32 s9, s5, 0xfb0aa000
	s_mul_hi_i32 s7, s7, 0x1400
	s_add_u32 s9, s0, s9
	v_mov_b32_e32 v5, v195
	v_mov_b32_e32 v7, v195
	v_mov_b32_e32 v9, v195
	s_addc_u32 s7, s1, s7
	v_lshl_add_u64 v[116:117], s[12:13], 0, v[194:195]
	v_lshl_add_u64 v[118:119], s[12:13], 0, v[4:5]
	v_lshl_add_u64 v[120:121], s[12:13], 0, v[6:7]
	v_lshl_add_u64 v[122:123], s[12:13], 0, v[8:9]
	s_add_u32 s12, s9, 0x2040200
	s_addc_u32 s13, s7, 0
	s_add_i32 s7, s6, 0xffffc090
	s_add_i32 s9, s5, 0xfb0b4000
	s_mul_hi_i32 s7, s7, 0x1400
	s_add_u32 s9, s0, s9
	s_addc_u32 s7, s1, s7
	v_lshl_add_u64 v[10:11], s[12:13], 0, v[194:195]
	v_lshl_add_u64 v[12:13], s[12:13], 0, v[4:5]
	v_lshl_add_u64 v[14:15], s[12:13], 0, v[6:7]
	v_lshl_add_u64 v[16:17], s[12:13], 0, v[8:9]
	s_add_u32 s12, s9, 0x2040200
	s_addc_u32 s13, s7, 0
	s_add_i32 s7, s6, 0xffffc098
	s_add_i32 s9, s5, 0xfb0be000
	s_mul_hi_i32 s7, s7, 0x1400
	s_add_u32 s9, s0, s9
	s_addc_u32 s7, s1, s7
	v_lshl_add_u64 v[18:19], s[12:13], 0, v[194:195]
	v_lshl_add_u64 v[20:21], s[12:13], 0, v[4:5]
	v_lshl_add_u64 v[22:23], s[12:13], 0, v[6:7]
	v_lshl_add_u64 v[24:25], s[12:13], 0, v[8:9]
	s_add_u32 s12, s9, 0x2040200
	s_addc_u32 s13, s7, 0
	s_add_i32 s7, s6, 0xffffc0a0
	s_add_i32 s9, s5, 0xfb0c8000
	s_mul_hi_i32 s7, s7, 0x1400
	s_add_u32 s9, s0, s9
	s_addc_u32 s7, s1, s7
	v_lshl_add_u64 v[26:27], s[12:13], 0, v[194:195]
	v_lshl_add_u64 v[28:29], s[12:13], 0, v[4:5]
	v_lshl_add_u64 v[30:31], s[12:13], 0, v[6:7]
	v_lshl_add_u64 v[32:33], s[12:13], 0, v[8:9]
	s_add_u32 s12, s9, 0x2040200
	s_addc_u32 s13, s7, 0
	s_add_i32 s7, s6, 0xffffc0a8
	s_add_i32 s9, s5, 0xfb0d2000
	s_mul_hi_i32 s7, s7, 0x1400
	s_add_u32 s9, s0, s9
	s_addc_u32 s7, s1, s7
	v_lshl_add_u64 v[34:35], s[12:13], 0, v[194:195]
	v_lshl_add_u64 v[76:77], s[12:13], 0, v[4:5]
	v_lshl_add_u64 v[78:79], s[12:13], 0, v[6:7]
	v_lshl_add_u64 v[80:81], s[12:13], 0, v[8:9]
	s_add_u32 s12, s9, 0x2040200
	s_addc_u32 s13, s7, 0
	s_add_i32 s7, s6, 0xffffc0b0
	s_add_i32 s9, s5, 0xfb0dc000
	s_mul_hi_i32 s7, s7, 0x1400
	s_add_u32 s9, s0, s9
	s_addc_u32 s7, s1, s7
	v_lshl_add_u64 v[82:83], s[12:13], 0, v[194:195]
	v_lshl_add_u64 v[84:85], s[12:13], 0, v[4:5]
	v_lshl_add_u64 v[86:87], s[12:13], 0, v[6:7]
	v_lshl_add_u64 v[88:89], s[12:13], 0, v[8:9]
	s_add_u32 s12, s9, 0x2040200
	s_addc_u32 s13, s7, 0
	s_add_i32 s7, s6, 0xffffc0b8
	s_add_i32 s9, s5, 0xfb0e6000
	s_mul_hi_i32 s7, s7, 0x1400
	s_add_u32 s9, s0, s9
	s_addc_u32 s7, s1, s7
	v_lshl_add_u64 v[90:91], s[12:13], 0, v[194:195]
	v_lshl_add_u64 v[92:93], s[12:13], 0, v[4:5]
	v_lshl_add_u64 v[94:95], s[12:13], 0, v[6:7]
	v_lshl_add_u64 v[96:97], s[12:13], 0, v[8:9]
	s_add_u32 s12, s9, 0x2040200
	s_addc_u32 s13, s7, 0
	s_add_i32 s7, s6, 0xffffc0c0
	s_add_i32 s9, s5, 0xfb0f0000
	s_mul_hi_i32 s7, s7, 0x1400
	s_add_u32 s9, s0, s9
	s_addc_u32 s7, s1, s7
	v_lshl_add_u64 v[98:99], s[12:13], 0, v[194:195]
	v_lshl_add_u64 v[100:101], s[12:13], 0, v[4:5]
	v_lshl_add_u64 v[102:103], s[12:13], 0, v[6:7]
	v_lshl_add_u64 v[104:105], s[12:13], 0, v[8:9]
	s_add_u32 s12, s9, 0x2040200
	s_addc_u32 s13, s7, 0
	s_add_i32 s7, s6, 0xffffc0c8
	s_add_i32 s9, s5, 0xfb0fa000
	s_mul_hi_i32 s7, s7, 0x1400
	s_add_u32 s9, s0, s9
	s_addc_u32 s7, s1, s7
	v_lshl_add_u64 v[124:125], s[12:13], 0, v[194:195]
	v_lshl_add_u64 v[126:127], s[12:13], 0, v[4:5]
	v_lshl_add_u64 v[128:129], s[12:13], 0, v[6:7]
	v_lshl_add_u64 v[130:131], s[12:13], 0, v[8:9]
	s_add_u32 s12, s9, 0x2040200
	s_addc_u32 s13, s7, 0
	s_add_i32 s7, s6, 0xffffc0d0
	s_add_i32 s9, s5, 0xfb104000
	s_mul_hi_i32 s7, s7, 0x1400
	s_add_u32 s9, s0, s9
	s_addc_u32 s7, s1, s7
	v_lshl_add_u64 v[132:133], s[12:13], 0, v[194:195]
	v_lshl_add_u64 v[134:135], s[12:13], 0, v[4:5]
	v_lshl_add_u64 v[136:137], s[12:13], 0, v[6:7]
	v_lshl_add_u64 v[138:139], s[12:13], 0, v[8:9]
	s_add_u32 s12, s9, 0x2040200
	s_addc_u32 s13, s7, 0
	s_add_i32 s7, s6, 0xffffc0d8
	s_add_i32 s9, s5, 0xfb10e000
	s_mul_hi_i32 s7, s7, 0x1400
	s_add_u32 s9, s0, s9
	s_addc_u32 s7, s1, s7
	v_lshl_add_u64 v[140:141], s[12:13], 0, v[194:195]
	v_lshl_add_u64 v[142:143], s[12:13], 0, v[4:5]
	v_lshl_add_u64 v[144:145], s[12:13], 0, v[6:7]
	v_lshl_add_u64 v[146:147], s[12:13], 0, v[8:9]
	s_add_u32 s12, s9, 0x2040200
	s_addc_u32 s13, s7, 0
	s_add_i32 s7, s6, 0xffffc0e0
	s_add_i32 s9, s5, 0xfb118000
	s_mul_hi_i32 s7, s7, 0x1400
	s_add_u32 s9, s0, s9
	s_addc_u32 s7, s1, s7
	v_lshl_add_u64 v[148:149], s[12:13], 0, v[194:195]
	v_lshl_add_u64 v[150:151], s[12:13], 0, v[4:5]
	v_lshl_add_u64 v[152:153], s[12:13], 0, v[6:7]
	v_lshl_add_u64 v[154:155], s[12:13], 0, v[8:9]
	s_add_u32 s12, s9, 0x2040200
	s_addc_u32 s13, s7, 0
	s_add_i32 s7, s6, 0xffffc0e8
	s_add_i32 s9, s5, 0xfb122000
	s_mul_hi_i32 s7, s7, 0x1400
	s_add_u32 s9, s0, s9
	s_addc_u32 s7, s1, s7
	v_lshl_add_u64 v[156:157], s[12:13], 0, v[194:195]
	v_lshl_add_u64 v[158:159], s[12:13], 0, v[4:5]
	v_lshl_add_u64 v[160:161], s[12:13], 0, v[6:7]
	v_lshl_add_u64 v[162:163], s[12:13], 0, v[8:9]
	s_add_u32 s12, s9, 0x2040200
	s_addc_u32 s13, s7, 0
	s_add_i32 s7, s6, 0xffffc0f0
	s_add_i32 s9, s5, 0xfb12c000
	s_mul_hi_i32 s7, s7, 0x1400
	s_add_u32 s9, s0, s9
	s_addc_u32 s7, s1, s7
	v_lshl_add_u64 v[164:165], s[12:13], 0, v[194:195]
	v_lshl_add_u64 v[166:167], s[12:13], 0, v[4:5]
	v_lshl_add_u64 v[168:169], s[12:13], 0, v[6:7]
	v_lshl_add_u64 v[170:171], s[12:13], 0, v[8:9]
	s_add_u32 s12, s9, 0x2040200
	s_addc_u32 s13, s7, 0
	s_addk_i32 s6, 0xc0f8
	s_add_i32 s5, s5, 0xfb136000
	s_mul_hi_i32 s6, s6, 0x1400
	s_add_u32 s5, s0, s5
	s_addc_u32 s7, s1, s6
	s_add_u32 s6, s5, 0x2040200
	s_addc_u32 s7, s7, 0
	v_lshl_add_u64 v[174:175], s[12:13], 0, v[4:5]
	v_lshl_add_u64 v[176:177], s[12:13], 0, v[6:7]
	v_lshl_add_u64 v[182:183], s[6:7], 0, v[4:5]
	v_lshl_add_u64 v[184:185], s[6:7], 0, v[6:7]
	global_load_ushort v5, v[116:117], off
	global_load_ushort v7, v[118:119], off
	v_lshl_add_u64 v[180:181], s[6:7], 0, v[194:195]
	v_lshl_add_u64 v[186:187], s[6:7], 0, v[8:9]
	v_lshl_add_u64 v[178:179], s[12:13], 0, v[8:9]
	v_lshl_add_u64 v[172:173], s[12:13], 0, v[194:195]
	s_addk_i32 s4, 0x80
	s_cmp_lt_i32 s4, 0
	s_waitcnt vmcnt(0) lgkmcnt(0)
	v_lshlrev_b32_e32 v116, 16, v5
	v_mul_f32_e32 v5, 0x3d372713, v116
	v_lshlrev_b32_e32 v117, 16, v7
	v_mul_f32_e32 v5, v5, v116
	v_mov_b32_e32 v7, v116
	v_fmac_f32_e32 v7, v5, v7
	v_mul_f32_e32 v5, 0x3f4c422a, v7
	v_add_f32_e32 v5, v5, v5
	v_mul_f32_e32 v5, 0xbfb8aa3b, v5
	v_exp_f32_e32 v118, v5
	v_mul_f32_e32 v5, 0x3d372713, v117
	v_mul_f32_e32 v5, v5, v117
	v_mov_b32_e32 v7, v117
	v_fmac_f32_e32 v7, v5, v7
	v_mul_f32_e32 v5, 0x3f4c422a, v7
	v_add_f32_e32 v5, v5, v5
	v_mul_f32_e32 v5, 0xbfb8aa3b, v5
	v_exp_f32_e32 v119, v5
	s_nop 0
	v_pk_add_f32 v[118:119], v[118:119], 1.0 op_sel_hi:[1,0]
	s_nop 0
	v_rcp_f32_e32 v119, v119
	global_load_ushort v7, v[120:121], off
	global_load_ushort v9, v[122:123], off
	v_rcp_f32_e32 v118, v118
	s_nop 0
	v_pk_mul_f32 v[188:189], v[118:119], v[116:117]
	s_waitcnt vmcnt(0) lgkmcnt(0)
	v_lshlrev_b32_e32 v118, 16, v7
	v_mul_f32_e32 v7, 0x3d372713, v118
	v_lshlrev_b32_e32 v119, 16, v9
	v_mul_f32_e32 v7, v7, v118
	v_mov_b32_e32 v9, v118
	v_fmac_f32_e32 v9, v7, v9
	v_mul_f32_e32 v7, 0x3f4c422a, v9
	v_add_f32_e32 v7, v7, v7
	v_mul_f32_e32 v7, 0xbfb8aa3b, v7
	v_exp_f32_e32 v120, v7
	v_mul_f32_e32 v7, 0x3d372713, v119
	v_mul_f32_e32 v7, v7, v119
	v_mov_b32_e32 v9, v119
	v_fmac_f32_e32 v9, v7, v9
	v_mul_f32_e32 v7, 0x3f4c422a, v9
	v_add_f32_e32 v7, v7, v7
	v_mul_f32_e32 v7, 0xbfb8aa3b, v7
	v_exp_f32_e32 v121, v7
	v_add_f32_e32 v5, 0, v188
	v_add_f32_e32 v5, v5, v189
	v_pk_mul_f32 v[116:117], v[188:189], v[188:189]
	v_pk_add_f32 v[120:121], v[120:121], 1.0 op_sel_hi:[1,0]
	s_nop 0
	v_rcp_f32_e32 v121, v121
	v_rcp_f32_e32 v120, v120
	s_nop 0
	v_pk_mul_f32 v[122:123], v[120:121], v[118:119]
	v_add_f32_e32 v7, v116, v117
	v_add_f32_e32 v5, v5, v122
	v_add_f32_e32 v5, v5, v123
	v_pk_mul_f32 v[118:119], v[122:123], v[122:123]
	s_nop 0
	v_add_f32_dpp v5, v5, v5 quad_perm:[1,0,3,2] row_mask:0xf bank_mask:0xf bound_ctrl:1
	v_add_f32_e32 v7, v7, v118
	v_add_f32_e32 v7, v7, v119
	v_add_f32_dpp v5, v5, v5 quad_perm:[2,3,0,1] row_mask:0xf bank_mask:0xf bound_ctrl:1
	s_nop 1
	v_add_f32_dpp v5, v5, v5 row_half_mirror row_mask:0xf bank_mask:0xf bound_ctrl:1
	s_nop 1
	v_add_f32_dpp v5, v5, v5 row_mirror row_mask:0xf bank_mask:0xf bound_ctrl:1
	s_nop 0
	v_readlane_b32 s7, v5, 0
	v_readlane_b32 s5, v5, 16
	v_readlane_b32 s13, v5, 32
	v_readlane_b32 s9, v5, 48
	v_add_f32_dpp v5, v7, v7 quad_perm:[1,0,3,2] row_mask:0xf bank_mask:0xf bound_ctrl:1
	v_mov_b32_e32 v117, s5
	v_mov_b32_e32 v119, s9
	v_add_f32_dpp v5, v5, v5 quad_perm:[2,3,0,1] row_mask:0xf bank_mask:0xf bound_ctrl:1
	s_nop 1
	v_add_f32_dpp v5, v5, v5 row_half_mirror row_mask:0xf bank_mask:0xf bound_ctrl:1
	s_nop 1
	v_add_f32_dpp v5, v5, v5 row_mirror row_mask:0xf bank_mask:0xf bound_ctrl:1
	s_nop 0
	v_readlane_b32 s11, v5, 16
	v_readlane_b32 s14, v5, 48
	v_readlane_b32 s6, v5, 0
	v_readlane_b32 s12, v5, 32
	v_mov_b32_e32 v116, s11
	v_mov_b32_e32 v118, s14
	v_pk_add_f32 v[116:117], s[6:7], v[116:117]
	v_pk_add_f32 v[118:119], s[12:13], v[118:119]
	s_nop 0
	v_pk_add_f32 v[116:117], v[116:117], v[118:119]
	s_nop 0
	v_pk_mul_f32 v[120:121], v[116:117], s[20:21] op_sel_hi:[1,0]
	s_nop 0
	v_fma_f32 v5, -v121, v121, v120
	v_max_f32_e32 v5, 0, v5
	v_add_f32_e32 v5, 0x3727c5ac, v5
	v_cmp_gt_f32_e32 vcc, s18, v5
	v_mul_f32_e32 v7, 0x4b800000, v5
	s_nop 0
	v_cndmask_b32_e32 v5, v5, v7, vcc
	v_rsq_f32_e32 v5, v5
	s_nop 0
	v_mul_f32_e32 v7, 0x45800000, v5
	v_cndmask_b32_e32 v190, v5, v7, vcc
	v_sub_f32_e32 v5, v188, v121
	v_mul_f32_e32 v5, v5, v190
	v_fma_f32 v5, v67, v5, v106
	v_cvt_pk_bf16_f32 v188, v5, s0
	global_load_ushort v191, v[10:11], off
	global_load_ushort v193, v[12:13], off
	global_load_ushort v196, v[14:15], off
	global_load_ushort v202, v[16:17], off
	global_load_ushort v203, v[18:19], off
	global_load_ushort v206, v[20:21], off
	global_load_ushort v207, v[22:23], off
	global_load_ushort v208, v[24:25], off
	global_load_ushort v209, v[26:27], off
	global_load_ushort v210, v[28:29], off
	global_load_ushort v211, v[30:31], off
	global_load_ushort v212, v[32:33], off
	global_load_ushort v119, v[34:35], off
	global_load_ushort v120, v[76:77], off
	global_load_ushort v117, v[78:79], off
	global_load_ushort v118, v[80:81], off
	global_load_ushort v115, v[82:83], off
	global_load_ushort v116, v[84:85], off
	s_nop 0
	global_load_ushort v87, v[86:87], off
	s_nop 0
	global_load_ushort v88, v[88:89], off
	s_nop 0
	global_load_ushort v85, v[90:91], off
	global_load_ushort v86, v[92:93], off
	global_load_ushort v83, v[94:95], off
	global_load_ushort v84, v[96:97], off
	global_load_ushort v81, v[98:99], off
	global_load_ushort v82, v[100:101], off
	global_load_ushort v79, v[102:103], off
	global_load_ushort v80, v[104:105], off
	global_load_ushort v77, v[124:125], off
	global_load_ushort v78, v[126:127], off
	global_load_ushort v14, v[128:129], off
	global_load_ushort v15, v[130:131], off
	global_load_ushort v12, v[132:133], off
	global_load_ushort v13, v[134:135], off
	global_load_ushort v10, v[136:137], off
	global_load_ushort v11, v[138:139], off
	global_load_ushort v35, v[140:141], off
	global_load_ushort v76, v[142:143], off
	global_load_ushort v33, v[144:145], off
	global_load_ushort v34, v[146:147], off
	global_load_ushort v31, v[148:149], off
	global_load_ushort v32, v[150:151], off
	global_load_ushort v29, v[152:153], off
	global_load_ushort v30, v[154:155], off
	global_load_ushort v27, v[156:157], off
	global_load_ushort v28, v[158:159], off
	global_load_ushort v25, v[160:161], off
	global_load_ushort v26, v[162:163], off
	global_load_ushort v23, v[164:165], off
	global_load_ushort v24, v[166:167], off
	global_load_ushort v21, v[168:169], off
	global_load_ushort v22, v[170:171], off
	global_load_ushort v19, v[172:173], off
	global_load_ushort v20, v[174:175], off
	global_load_ushort v17, v[176:177], off
	global_load_ushort v18, v[178:179], off
	global_load_ushort v9, v[180:181], off
	global_load_ushort v16, v[182:183], off
	global_load_ushort v5, v[184:185], off
	global_load_ushort v7, v[186:187], off
	v_sub_f32_e32 v89, v189, v121
	v_mul_f32_e32 v89, v89, v190
	v_fma_f32 v89, v107, v89, v108
	v_cvt_pk_bf16_f32 v89, v89, s0
	ds_write_b16 v114, v89 offset:16896
	v_sub_f32_e32 v89, v122, v121
	v_mul_f32_e32 v89, v89, v190
	v_fma_f32 v89, v110, v89, v111
	v_cvt_pk_bf16_f32 v89, v89, s0
	ds_write_b16 v114, v89 offset:33792
	v_sub_f32_e32 v89, v123, v121
	v_mul_f32_e32 v89, v89, v190
	v_fma_f32 v89, v112, v89, v113
	v_cvt_pk_bf16_f32 v89, v89, s0
	ds_write_b16 v114, v89 offset:50688
	ds_write_b16 v114, v188
	s_waitcnt vmcnt(0) lgkmcnt(0)
	v_lshlrev_b32_e32 v90, 16, v191
	v_mul_f32_e32 v89, 0x3d372713, v90
	v_mul_f32_e32 v89, v89, v90
	v_mov_b32_e32 v92, v90
	v_fmac_f32_e32 v92, v89, v92
	v_mul_f32_e32 v89, 0x3f4c422a, v92
	v_add_f32_e32 v89, v89, v89
	v_lshlrev_b32_e32 v91, 16, v193
	v_mul_f32_e32 v89, 0xbfb8aa3b, v89
	v_exp_f32_e32 v92, v89
	v_mul_f32_e32 v89, 0x3d372713, v91
	v_mul_f32_e32 v89, v89, v91
	v_mov_b32_e32 v93, v91
	v_fmac_f32_e32 v93, v89, v93
	v_mul_f32_e32 v89, 0x3f4c422a, v93
	v_add_f32_e32 v89, v89, v89
	v_mul_f32_e32 v89, 0xbfb8aa3b, v89
	v_exp_f32_e32 v93, v89
	v_lshlrev_b32_e32 v14, 16, v14
	v_pk_add_f32 v[92:93], v[92:93], 1.0 op_sel_hi:[1,0]
	v_lshlrev_b32_e32 v15, 16, v15
	v_lshlrev_b32_e32 v12, 16, v12
	v_lshlrev_b32_e32 v13, 16, v13
	v_lshlrev_b32_e32 v10, 16, v10
	v_rcp_f32_e32 v93, v93
	v_lshlrev_b32_e32 v11, 16, v11
	v_lshlrev_b32_e32 v94, 16, v196
	v_mul_f32_e32 v96, 0x3d372713, v94
	v_mul_f32_e32 v96, v96, v94
	v_mov_b32_e32 v97, v94
	v_lshlrev_b32_e32 v95, 16, v202
	v_fmac_f32_e32 v97, v96, v97
	v_mul_f32_e32 v96, 0x3f4c422a, v97
	v_mul_f32_e32 v97, 0x3d372713, v95
	v_mul_f32_e32 v97, v97, v95
	v_mov_b32_e32 v98, v95
	v_fmac_f32_e32 v98, v97, v98
	v_mul_f32_e32 v97, 0x3f4c422a, v98
	v_add_f32_e32 v96, v96, v96
	v_add_f32_e32 v97, v97, v97
	v_mul_f32_e32 v96, 0xbfb8aa3b, v96
	v_mul_f32_e32 v97, 0xbfb8aa3b, v97
	v_exp_f32_e32 v96, v96
	v_exp_f32_e32 v97, v97
	v_rcp_f32_e32 v92, v92
	s_nop 0
	v_pk_mul_f32 v[90:91], v[92:93], v[90:91]
	v_pk_add_f32 v[96:97], v[96:97], 1.0 op_sel_hi:[1,0]
	s_nop 0
	v_add_f32_e32 v89, 0, v90
	v_add_f32_e32 v89, v89, v91
	v_pk_mul_f32 v[92:93], v[90:91], v[90:91]
	v_rcp_f32_e32 v97, v97
	v_add_f32_e32 v92, v92, v93
	v_rcp_f32_e32 v96, v96
	s_nop 0
	v_pk_mul_f32 v[94:95], v[96:97], v[94:95]
	s_nop 0
	v_add_f32_e32 v89, v89, v94
	v_add_f32_e32 v89, v89, v95
	v_pk_mul_f32 v[96:97], v[94:95], v[94:95]
	s_nop 0
	v_add_f32_dpp v89, v89, v89 quad_perm:[1,0,3,2] row_mask:0xf bank_mask:0xf bound_ctrl:1
	v_add_f32_e32 v92, v92, v96
	v_add_f32_e32 v92, v92, v97
	v_add_f32_dpp v89, v89, v89 quad_perm:[2,3,0,1] row_mask:0xf bank_mask:0xf bound_ctrl:1
	s_nop 1
	v_add_f32_dpp v89, v89, v89 row_half_mirror row_mask:0xf bank_mask:0xf bound_ctrl:1
	s_nop 1
	v_add_f32_dpp v89, v89, v89 row_mirror row_mask:0xf bank_mask:0xf bound_ctrl:1
	s_nop 0
	v_readlane_b32 s7, v89, 0
	v_readlane_b32 s5, v89, 16
	v_readlane_b32 s13, v89, 32
	v_readlane_b32 s9, v89, 48
	v_add_f32_dpp v89, v92, v92 quad_perm:[1,0,3,2] row_mask:0xf bank_mask:0xf bound_ctrl:1
	v_mov_b32_e32 v93, s5
	v_mov_b32_e32 v97, s9
	v_add_f32_dpp v89, v89, v89 quad_perm:[2,3,0,1] row_mask:0xf bank_mask:0xf bound_ctrl:1
	s_nop 1
	v_add_f32_dpp v89, v89, v89 row_half_mirror row_mask:0xf bank_mask:0xf bound_ctrl:1
	s_nop 1
	v_add_f32_dpp v89, v89, v89 row_mirror row_mask:0xf bank_mask:0xf bound_ctrl:1
	s_nop 0
	v_readlane_b32 s11, v89, 16
	v_readlane_b32 s14, v89, 48
	v_readlane_b32 s6, v89, 0
	v_readlane_b32 s12, v89, 32
	v_mov_b32_e32 v92, s11
	v_mov_b32_e32 v96, s14
	v_pk_add_f32 v[92:93], s[6:7], v[92:93]
	v_pk_add_f32 v[96:97], s[12:13], v[96:97]
	s_nop 0
	v_pk_add_f32 v[92:93], v[92:93], v[96:97]
	s_nop 0
	v_pk_mul_f32 v[92:93], v[92:93], s[20:21] op_sel_hi:[1,0]
	s_nop 0
	v_fma_f32 v89, -v93, v93, v92
	v_max_f32_e32 v89, 0, v89
	v_add_f32_e32 v89, 0x3727c5ac, v89
	v_cmp_gt_f32_e32 vcc, s18, v89
	v_mul_f32_e32 v92, 0x4b800000, v89
	v_sub_f32_e32 v90, v90, v93
	v_cndmask_b32_e32 v89, v89, v92, vcc
	v_rsq_f32_e32 v89, v89
	s_nop 0
	v_mul_f32_e32 v92, 0x45800000, v89
	v_cndmask_b32_e32 v89, v89, v92, vcc
	v_mul_f32_e32 v90, v90, v89
	v_fma_f32 v90, v67, v90, v106
	v_cvt_pk_bf16_f32 v90, v90, s0
	ds_write_b16 v114, v90 offset:16
	v_sub_f32_e32 v90, v91, v93
	v_mul_f32_e32 v90, v90, v89
	v_fma_f32 v90, v107, v90, v108
	v_cvt_pk_bf16_f32 v90, v90, s0
	ds_write_b16 v114, v90 offset:16912
	v_sub_f32_e32 v90, v94, v93
	v_mul_f32_e32 v90, v90, v89
	v_fma_f32 v90, v110, v90, v111
	v_cvt_pk_bf16_f32 v90, v90, s0
	ds_write_b16 v114, v90 offset:33808
	v_sub_f32_e32 v90, v95, v93
	v_mul_f32_e32 v89, v90, v89
	v_fma_f32 v89, v112, v89, v113
	v_cvt_pk_bf16_f32 v89, v89, s0
	v_lshlrev_b32_e32 v90, 16, v203
	ds_write_b16 v114, v89 offset:50704
	v_mul_f32_e32 v89, 0x3d372713, v90
	v_mul_f32_e32 v89, v89, v90
	v_mov_b32_e32 v92, v90
	v_fmac_f32_e32 v92, v89, v92
	v_mul_f32_e32 v89, 0x3f4c422a, v92
	v_add_f32_e32 v89, v89, v89
	v_lshlrev_b32_e32 v91, 16, v206
	v_mul_f32_e32 v89, 0xbfb8aa3b, v89
	v_exp_f32_e32 v92, v89
	v_mul_f32_e32 v89, 0x3d372713, v91
	v_mul_f32_e32 v89, v89, v91
	v_mov_b32_e32 v93, v91
	v_fmac_f32_e32 v93, v89, v93
	v_mul_f32_e32 v89, 0x3f4c422a, v93
	v_add_f32_e32 v89, v89, v89
	v_mul_f32_e32 v89, 0xbfb8aa3b, v89
	v_exp_f32_e32 v93, v89
	s_nop 0
	v_pk_add_f32 v[92:93], v[92:93], 1.0 op_sel_hi:[1,0]
	s_nop 0
	v_rcp_f32_e32 v93, v93
	v_lshlrev_b32_e32 v94, 16, v207
	v_mul_f32_e32 v96, 0x3d372713, v94
	v_mul_f32_e32 v96, v96, v94
	v_mov_b32_e32 v97, v94
	v_lshlrev_b32_e32 v95, 16, v208
	v_fmac_f32_e32 v97, v96, v97
	v_mul_f32_e32 v96, 0x3f4c422a, v97
	v_mul_f32_e32 v97, 0x3d372713, v95
	v_mul_f32_e32 v97, v97, v95
	v_mov_b32_e32 v98, v95
	v_fmac_f32_e32 v98, v97, v98
	v_mul_f32_e32 v97, 0x3f4c422a, v98
	v_add_f32_e32 v96, v96, v96
	v_add_f32_e32 v97, v97, v97
	v_mul_f32_e32 v96, 0xbfb8aa3b, v96
	v_mul_f32_e32 v97, 0xbfb8aa3b, v97
	v_exp_f32_e32 v96, v96
	v_exp_f32_e32 v97, v97
	v_rcp_f32_e32 v92, v92
	s_nop 0
	v_pk_mul_f32 v[90:91], v[92:93], v[90:91]
	v_pk_add_f32 v[96:97], v[96:97], 1.0 op_sel_hi:[1,0]
	s_nop 0
	v_add_f32_e32 v89, 0, v90
	v_add_f32_e32 v89, v89, v91
	v_pk_mul_f32 v[92:93], v[90:91], v[90:91]
	v_rcp_f32_e32 v97, v97
	v_add_f32_e32 v92, v92, v93
	v_rcp_f32_e32 v96, v96
	s_nop 0
	v_pk_mul_f32 v[94:95], v[96:97], v[94:95]
	s_nop 0
	v_add_f32_e32 v89, v89, v94
	v_add_f32_e32 v89, v89, v95
	v_pk_mul_f32 v[96:97], v[94:95], v[94:95]
	s_nop 0
	v_add_f32_dpp v89, v89, v89 quad_perm:[1,0,3,2] row_mask:0xf bank_mask:0xf bound_ctrl:1
	v_add_f32_e32 v92, v92, v96
	v_add_f32_e32 v92, v92, v97
	v_add_f32_dpp v89, v89, v89 quad_perm:[2,3,0,1] row_mask:0xf bank_mask:0xf bound_ctrl:1
	s_nop 1
	v_add_f32_dpp v89, v89, v89 row_half_mirror row_mask:0xf bank_mask:0xf bound_ctrl:1
	s_nop 1
	v_add_f32_dpp v89, v89, v89 row_mirror row_mask:0xf bank_mask:0xf bound_ctrl:1
	s_nop 0
	v_readlane_b32 s7, v89, 0
	v_readlane_b32 s5, v89, 16
	v_readlane_b32 s13, v89, 32
	v_readlane_b32 s9, v89, 48
	v_add_f32_dpp v89, v92, v92 quad_perm:[1,0,3,2] row_mask:0xf bank_mask:0xf bound_ctrl:1
	v_mov_b32_e32 v93, s5
	v_mov_b32_e32 v97, s9
	v_add_f32_dpp v89, v89, v89 quad_perm:[2,3,0,1] row_mask:0xf bank_mask:0xf bound_ctrl:1
	s_nop 1
	v_add_f32_dpp v89, v89, v89 row_half_mirror row_mask:0xf bank_mask:0xf bound_ctrl:1
	s_nop 1
	v_add_f32_dpp v89, v89, v89 row_mirror row_mask:0xf bank_mask:0xf bound_ctrl:1
	s_nop 0
	v_readlane_b32 s11, v89, 16
	v_readlane_b32 s14, v89, 48
	v_readlane_b32 s6, v89, 0
	v_readlane_b32 s12, v89, 32
	v_mov_b32_e32 v92, s11
	v_mov_b32_e32 v96, s14
	v_pk_add_f32 v[92:93], s[6:7], v[92:93]
	v_pk_add_f32 v[96:97], s[12:13], v[96:97]
	s_nop 0
	v_pk_add_f32 v[92:93], v[92:93], v[96:97]
	s_nop 0
	v_pk_mul_f32 v[92:93], v[92:93], s[20:21] op_sel_hi:[1,0]
	s_nop 0
	v_fma_f32 v89, -v93, v93, v92
	v_max_f32_e32 v89, 0, v89
	v_add_f32_e32 v89, 0x3727c5ac, v89
	v_cmp_gt_f32_e32 vcc, s18, v89
	v_mul_f32_e32 v92, 0x4b800000, v89
	v_sub_f32_e32 v90, v90, v93
	v_cndmask_b32_e32 v89, v89, v92, vcc
	v_rsq_f32_e32 v89, v89
	s_nop 0
	v_mul_f32_e32 v92, 0x45800000, v89
	v_cndmask_b32_e32 v89, v89, v92, vcc
	v_mul_f32_e32 v90, v90, v89
	v_fma_f32 v90, v67, v90, v106
	v_cvt_pk_bf16_f32 v90, v90, s0
	ds_write_b16 v114, v90 offset:32
	v_sub_f32_e32 v90, v91, v93
	v_mul_f32_e32 v90, v90, v89
	v_fma_f32 v90, v107, v90, v108
	v_cvt_pk_bf16_f32 v90, v90, s0
	ds_write_b16 v114, v90 offset:16928
	v_sub_f32_e32 v90, v94, v93
	v_mul_f32_e32 v90, v90, v89
	v_fma_f32 v90, v110, v90, v111
	v_cvt_pk_bf16_f32 v90, v90, s0
	ds_write_b16 v114, v90 offset:33824
	v_sub_f32_e32 v90, v95, v93
	v_mul_f32_e32 v89, v90, v89
	v_fma_f32 v89, v112, v89, v113
	v_cvt_pk_bf16_f32 v89, v89, s0
	v_lshlrev_b32_e32 v90, 16, v209
	ds_write_b16 v114, v89 offset:50720
	v_mul_f32_e32 v89, 0x3d372713, v90
	v_mul_f32_e32 v89, v89, v90
	v_mov_b32_e32 v92, v90
	v_fmac_f32_e32 v92, v89, v92
	v_mul_f32_e32 v89, 0x3f4c422a, v92
	v_add_f32_e32 v89, v89, v89
	v_lshlrev_b32_e32 v91, 16, v210
	v_mul_f32_e32 v89, 0xbfb8aa3b, v89
	v_exp_f32_e32 v92, v89
	v_mul_f32_e32 v89, 0x3d372713, v91
	v_mul_f32_e32 v89, v89, v91
	v_mov_b32_e32 v93, v91
	v_fmac_f32_e32 v93, v89, v93
	v_mul_f32_e32 v89, 0x3f4c422a, v93
	v_add_f32_e32 v89, v89, v89
	v_mul_f32_e32 v89, 0xbfb8aa3b, v89
	v_exp_f32_e32 v93, v89
	s_nop 0
	v_pk_add_f32 v[92:93], v[92:93], 1.0 op_sel_hi:[1,0]
	s_nop 0
	v_rcp_f32_e32 v93, v93
	v_lshlrev_b32_e32 v94, 16, v211
	v_mul_f32_e32 v96, 0x3d372713, v94
	v_mul_f32_e32 v96, v96, v94
	v_mov_b32_e32 v97, v94
	v_lshlrev_b32_e32 v95, 16, v212
	v_fmac_f32_e32 v97, v96, v97
	v_mul_f32_e32 v96, 0x3f4c422a, v97
	v_mul_f32_e32 v97, 0x3d372713, v95
	v_mul_f32_e32 v97, v97, v95
	v_mov_b32_e32 v98, v95
	v_fmac_f32_e32 v98, v97, v98
	v_mul_f32_e32 v97, 0x3f4c422a, v98
	v_add_f32_e32 v96, v96, v96
	v_add_f32_e32 v97, v97, v97
	v_mul_f32_e32 v96, 0xbfb8aa3b, v96
	v_mul_f32_e32 v97, 0xbfb8aa3b, v97
	v_exp_f32_e32 v96, v96
	v_exp_f32_e32 v97, v97
	v_rcp_f32_e32 v92, v92
	s_nop 0
	v_pk_mul_f32 v[90:91], v[92:93], v[90:91]
	v_pk_add_f32 v[96:97], v[96:97], 1.0 op_sel_hi:[1,0]
	s_nop 0
	v_add_f32_e32 v89, 0, v90
	v_add_f32_e32 v89, v89, v91
	v_pk_mul_f32 v[92:93], v[90:91], v[90:91]
	v_rcp_f32_e32 v97, v97
	v_add_f32_e32 v92, v92, v93
	v_rcp_f32_e32 v96, v96
	s_nop 0
	v_pk_mul_f32 v[94:95], v[96:97], v[94:95]
	s_nop 0
	v_add_f32_e32 v89, v89, v94
	v_add_f32_e32 v89, v89, v95
	v_pk_mul_f32 v[96:97], v[94:95], v[94:95]
	s_nop 0
	v_add_f32_dpp v89, v89, v89 quad_perm:[1,0,3,2] row_mask:0xf bank_mask:0xf bound_ctrl:1
	v_add_f32_e32 v92, v92, v96
	v_add_f32_e32 v92, v92, v97
	v_add_f32_dpp v89, v89, v89 quad_perm:[2,3,0,1] row_mask:0xf bank_mask:0xf bound_ctrl:1
	s_nop 1
	v_add_f32_dpp v89, v89, v89 row_half_mirror row_mask:0xf bank_mask:0xf bound_ctrl:1
	s_nop 1
	v_add_f32_dpp v89, v89, v89 row_mirror row_mask:0xf bank_mask:0xf bound_ctrl:1
	s_nop 0
	v_readlane_b32 s7, v89, 0
	v_readlane_b32 s5, v89, 16
	v_readlane_b32 s13, v89, 32
	v_readlane_b32 s9, v89, 48
	v_add_f32_dpp v89, v92, v92 quad_perm:[1,0,3,2] row_mask:0xf bank_mask:0xf bound_ctrl:1
	v_mov_b32_e32 v93, s5
	v_mov_b32_e32 v97, s9
	v_add_f32_dpp v89, v89, v89 quad_perm:[2,3,0,1] row_mask:0xf bank_mask:0xf bound_ctrl:1
	s_nop 1
	v_add_f32_dpp v89, v89, v89 row_half_mirror row_mask:0xf bank_mask:0xf bound_ctrl:1
	s_nop 1
	v_add_f32_dpp v89, v89, v89 row_mirror row_mask:0xf bank_mask:0xf bound_ctrl:1
	s_nop 0
	v_readlane_b32 s11, v89, 16
	v_readlane_b32 s14, v89, 48
	v_readlane_b32 s6, v89, 0
	v_readlane_b32 s12, v89, 32
	v_mov_b32_e32 v92, s11
	v_mov_b32_e32 v96, s14
	v_pk_add_f32 v[92:93], s[6:7], v[92:93]
	v_pk_add_f32 v[96:97], s[12:13], v[96:97]
	s_nop 0
	v_pk_add_f32 v[92:93], v[92:93], v[96:97]
	s_nop 0
	v_pk_mul_f32 v[92:93], v[92:93], s[20:21] op_sel_hi:[1,0]
	s_nop 0
	v_fma_f32 v89, -v93, v93, v92
	v_max_f32_e32 v89, 0, v89
	v_add_f32_e32 v89, 0x3727c5ac, v89
	v_cmp_gt_f32_e32 vcc, s18, v89
	v_mul_f32_e32 v92, 0x4b800000, v89
	v_sub_f32_e32 v90, v90, v93
	v_cndmask_b32_e32 v89, v89, v92, vcc
	v_rsq_f32_e32 v89, v89
	s_nop 0
	v_mul_f32_e32 v92, 0x45800000, v89
	v_cndmask_b32_e32 v89, v89, v92, vcc
	v_mul_f32_e32 v90, v90, v89
	v_fma_f32 v90, v67, v90, v106
	v_cvt_pk_bf16_f32 v90, v90, s0
	ds_write_b16 v114, v90 offset:48
	v_sub_f32_e32 v90, v91, v93
	v_mul_f32_e32 v90, v90, v89
	v_fma_f32 v90, v107, v90, v108
	v_cvt_pk_bf16_f32 v90, v90, s0
	ds_write_b16 v114, v90 offset:16944
	v_sub_f32_e32 v90, v94, v93
	v_mul_f32_e32 v90, v90, v89
	v_fma_f32 v90, v110, v90, v111
	v_cvt_pk_bf16_f32 v90, v90, s0
	ds_write_b16 v114, v90 offset:33840
	v_sub_f32_e32 v90, v95, v93
	v_mul_f32_e32 v89, v90, v89
	v_fma_f32 v89, v112, v89, v113
	v_cvt_pk_bf16_f32 v89, v89, s0
	v_lshlrev_b32_e32 v90, 16, v119
	ds_write_b16 v114, v89 offset:50736
	v_mul_f32_e32 v89, 0x3d372713, v90
	v_mul_f32_e32 v89, v89, v90
	v_mov_b32_e32 v92, v90
	v_fmac_f32_e32 v92, v89, v92
	v_mul_f32_e32 v89, 0x3f4c422a, v92
	v_add_f32_e32 v89, v89, v89
	v_lshlrev_b32_e32 v91, 16, v120
	v_mul_f32_e32 v89, 0xbfb8aa3b, v89
	v_exp_f32_e32 v92, v89
	v_mul_f32_e32 v89, 0x3d372713, v91
	v_mul_f32_e32 v89, v89, v91
	v_mov_b32_e32 v93, v91
	v_fmac_f32_e32 v93, v89, v93
	v_mul_f32_e32 v89, 0x3f4c422a, v93
	v_add_f32_e32 v89, v89, v89
	v_mul_f32_e32 v89, 0xbfb8aa3b, v89
	v_exp_f32_e32 v93, v89
	s_nop 0
	v_pk_add_f32 v[92:93], v[92:93], 1.0 op_sel_hi:[1,0]
	s_nop 0
	v_rcp_f32_e32 v93, v93
	v_lshlrev_b32_e32 v94, 16, v117
	v_mul_f32_e32 v96, 0x3d372713, v94
	v_mul_f32_e32 v96, v96, v94
	v_mov_b32_e32 v97, v94
	v_lshlrev_b32_e32 v95, 16, v118
	v_fmac_f32_e32 v97, v96, v97
	v_mul_f32_e32 v96, 0x3f4c422a, v97
	v_mul_f32_e32 v97, 0x3d372713, v95
	v_mul_f32_e32 v97, v97, v95
	v_mov_b32_e32 v98, v95
	v_fmac_f32_e32 v98, v97, v98
	v_mul_f32_e32 v97, 0x3f4c422a, v98
	v_add_f32_e32 v96, v96, v96
	v_add_f32_e32 v97, v97, v97
	v_mul_f32_e32 v96, 0xbfb8aa3b, v96
	v_mul_f32_e32 v97, 0xbfb8aa3b, v97
	v_exp_f32_e32 v96, v96
	v_exp_f32_e32 v97, v97
	v_rcp_f32_e32 v92, v92
	s_nop 0
	v_pk_mul_f32 v[90:91], v[92:93], v[90:91]
	v_pk_add_f32 v[96:97], v[96:97], 1.0 op_sel_hi:[1,0]
	s_nop 0
	v_add_f32_e32 v89, 0, v90
	v_add_f32_e32 v89, v89, v91
	v_pk_mul_f32 v[92:93], v[90:91], v[90:91]
	v_rcp_f32_e32 v97, v97
	v_add_f32_e32 v92, v92, v93
	v_rcp_f32_e32 v96, v96
	s_nop 0
	v_pk_mul_f32 v[94:95], v[96:97], v[94:95]
	s_nop 0
	v_add_f32_e32 v89, v89, v94
	v_add_f32_e32 v89, v89, v95
	v_pk_mul_f32 v[96:97], v[94:95], v[94:95]
	s_nop 0
	v_add_f32_dpp v89, v89, v89 quad_perm:[1,0,3,2] row_mask:0xf bank_mask:0xf bound_ctrl:1
	v_add_f32_e32 v92, v92, v96
	v_add_f32_e32 v92, v92, v97
	v_add_f32_dpp v89, v89, v89 quad_perm:[2,3,0,1] row_mask:0xf bank_mask:0xf bound_ctrl:1
	s_nop 1
	v_add_f32_dpp v89, v89, v89 row_half_mirror row_mask:0xf bank_mask:0xf bound_ctrl:1
	s_nop 1
	v_add_f32_dpp v89, v89, v89 row_mirror row_mask:0xf bank_mask:0xf bound_ctrl:1
	s_nop 0
	v_readlane_b32 s7, v89, 0
	v_readlane_b32 s5, v89, 16
	v_readlane_b32 s13, v89, 32
	v_readlane_b32 s9, v89, 48
	v_add_f32_dpp v89, v92, v92 quad_perm:[1,0,3,2] row_mask:0xf bank_mask:0xf bound_ctrl:1
	v_mov_b32_e32 v93, s5
	v_mov_b32_e32 v97, s9
	v_add_f32_dpp v89, v89, v89 quad_perm:[2,3,0,1] row_mask:0xf bank_mask:0xf bound_ctrl:1
	s_nop 1
	v_add_f32_dpp v89, v89, v89 row_half_mirror row_mask:0xf bank_mask:0xf bound_ctrl:1
	s_nop 1
	v_add_f32_dpp v89, v89, v89 row_mirror row_mask:0xf bank_mask:0xf bound_ctrl:1
	s_nop 0
	v_readlane_b32 s11, v89, 16
	v_readlane_b32 s14, v89, 48
	v_readlane_b32 s6, v89, 0
	v_readlane_b32 s12, v89, 32
	v_mov_b32_e32 v92, s11
	v_mov_b32_e32 v96, s14
	v_pk_add_f32 v[92:93], s[6:7], v[92:93]
	v_pk_add_f32 v[96:97], s[12:13], v[96:97]
	s_nop 0
	v_pk_add_f32 v[92:93], v[92:93], v[96:97]
	s_nop 0
	v_pk_mul_f32 v[92:93], v[92:93], s[20:21] op_sel_hi:[1,0]
	s_nop 0
	v_fma_f32 v89, -v93, v93, v92
	v_max_f32_e32 v89, 0, v89
	v_add_f32_e32 v89, 0x3727c5ac, v89
	v_cmp_gt_f32_e32 vcc, s18, v89
	v_mul_f32_e32 v92, 0x4b800000, v89
	v_sub_f32_e32 v90, v90, v93
	v_cndmask_b32_e32 v89, v89, v92, vcc
	v_rsq_f32_e32 v89, v89
	s_nop 0
	v_mul_f32_e32 v92, 0x45800000, v89
	v_cndmask_b32_e32 v89, v89, v92, vcc
	v_mul_f32_e32 v90, v90, v89
	v_fma_f32 v90, v67, v90, v106
	v_cvt_pk_bf16_f32 v90, v90, s0
	ds_write_b16 v114, v90 offset:64
	v_sub_f32_e32 v90, v91, v93
	v_mul_f32_e32 v90, v90, v89
	v_fma_f32 v90, v107, v90, v108
	v_cvt_pk_bf16_f32 v90, v90, s0
	ds_write_b16 v114, v90 offset:16960
	v_sub_f32_e32 v90, v94, v93
	v_mul_f32_e32 v90, v90, v89
	v_fma_f32 v90, v110, v90, v111
	v_cvt_pk_bf16_f32 v90, v90, s0
	ds_write_b16 v114, v90 offset:33856
	v_sub_f32_e32 v90, v95, v93
	v_mul_f32_e32 v89, v90, v89
	v_fma_f32 v89, v112, v89, v113
	v_cvt_pk_bf16_f32 v89, v89, s0
	v_lshlrev_b32_e32 v90, 16, v115
	ds_write_b16 v114, v89 offset:50752
	v_mul_f32_e32 v89, 0x3d372713, v90
	v_mul_f32_e32 v89, v89, v90
	v_mov_b32_e32 v92, v90
	v_fmac_f32_e32 v92, v89, v92
	v_mul_f32_e32 v89, 0x3f4c422a, v92
	v_add_f32_e32 v89, v89, v89
	v_lshlrev_b32_e32 v91, 16, v116
	v_mul_f32_e32 v89, 0xbfb8aa3b, v89
	v_exp_f32_e32 v92, v89
	v_mul_f32_e32 v89, 0x3d372713, v91
	v_mul_f32_e32 v89, v89, v91
	v_mov_b32_e32 v93, v91
	v_fmac_f32_e32 v93, v89, v93
	v_mul_f32_e32 v89, 0x3f4c422a, v93
	v_add_f32_e32 v89, v89, v89
	v_mul_f32_e32 v89, 0xbfb8aa3b, v89
	v_exp_f32_e32 v93, v89
	s_nop 0
	v_pk_add_f32 v[92:93], v[92:93], 1.0 op_sel_hi:[1,0]
	s_nop 0
	v_rcp_f32_e32 v93, v93
	v_rcp_f32_e32 v92, v92
	s_nop 0
	v_pk_mul_f32 v[90:91], v[92:93], v[90:91]
	s_nop 0
	v_add_f32_e32 v89, 0, v90
	v_add_f32_e32 v96, v89, v91
	v_lshlrev_b32_e32 v89, 16, v88
	v_lshlrev_b32_e32 v88, 16, v87
	v_mul_f32_e32 v87, 0x3d372713, v88
	v_mul_f32_e32 v87, v87, v88
	v_mov_b32_e32 v94, v88
	v_fmac_f32_e32 v94, v87, v94
	v_mul_f32_e32 v87, 0x3f4c422a, v94
	v_add_f32_e32 v87, v87, v87
	v_mul_f32_e32 v87, 0xbfb8aa3b, v87
	v_exp_f32_e32 v94, v87
	v_mul_f32_e32 v87, 0x3d372713, v89
	v_mul_f32_e32 v87, v87, v89
	v_mov_b32_e32 v95, v89
	v_fmac_f32_e32 v95, v87, v95
	v_mul_f32_e32 v87, 0x3f4c422a, v95
	v_add_f32_e32 v87, v87, v87
	v_mul_f32_e32 v87, 0xbfb8aa3b, v87
	v_exp_f32_e32 v95, v87
	v_pk_mul_f32 v[92:93], v[90:91], v[90:91]
	v_pk_add_f32 v[94:95], v[94:95], 1.0 op_sel_hi:[1,0]
	s_nop 0
	v_add_f32_e32 v92, v92, v93
	v_rcp_f32_e32 v95, v95
	v_rcp_f32_e32 v94, v94
	s_nop 0
	v_pk_mul_f32 v[88:89], v[94:95], v[88:89]
	s_nop 0
	v_add_f32_e32 v87, v96, v88
	v_add_f32_e32 v87, v87, v89
	v_pk_mul_f32 v[94:95], v[88:89], v[88:89]
	s_nop 0
	v_add_f32_dpp v87, v87, v87 quad_perm:[1,0,3,2] row_mask:0xf bank_mask:0xf bound_ctrl:1
	v_add_f32_e32 v92, v92, v94
	v_add_f32_e32 v92, v92, v95
	v_add_f32_dpp v87, v87, v87 quad_perm:[2,3,0,1] row_mask:0xf bank_mask:0xf bound_ctrl:1
	s_nop 1
	v_add_f32_dpp v87, v87, v87 row_half_mirror row_mask:0xf bank_mask:0xf bound_ctrl:1
	s_nop 1
	v_add_f32_dpp v87, v87, v87 row_mirror row_mask:0xf bank_mask:0xf bound_ctrl:1
	s_nop 0
	v_readlane_b32 s7, v87, 0
	v_readlane_b32 s5, v87, 16
	v_readlane_b32 s13, v87, 32
	v_readlane_b32 s9, v87, 48
	v_add_f32_dpp v87, v92, v92 quad_perm:[1,0,3,2] row_mask:0xf bank_mask:0xf bound_ctrl:1
	v_mov_b32_e32 v93, s5
	v_mov_b32_e32 v95, s9
	v_add_f32_dpp v87, v87, v87 quad_perm:[2,3,0,1] row_mask:0xf bank_mask:0xf bound_ctrl:1
	s_nop 1
	v_add_f32_dpp v87, v87, v87 row_half_mirror row_mask:0xf bank_mask:0xf bound_ctrl:1
	s_nop 1
	v_add_f32_dpp v87, v87, v87 row_mirror row_mask:0xf bank_mask:0xf bound_ctrl:1
	s_nop 0
	v_readlane_b32 s11, v87, 16
	v_readlane_b32 s14, v87, 48
	v_readlane_b32 s6, v87, 0
	v_readlane_b32 s12, v87, 32
	v_mov_b32_e32 v92, s11
	v_mov_b32_e32 v94, s14
	v_pk_add_f32 v[92:93], s[6:7], v[92:93]
	v_pk_add_f32 v[94:95], s[12:13], v[94:95]
	s_nop 0
	v_pk_add_f32 v[92:93], v[92:93], v[94:95]
	s_nop 0
	v_pk_mul_f32 v[92:93], v[92:93], s[20:21] op_sel_hi:[1,0]
	s_nop 0
	v_fma_f32 v87, -v93, v93, v92
	v_max_f32_e32 v87, 0, v87
	v_add_f32_e32 v87, 0x3727c5ac, v87
	v_cmp_gt_f32_e32 vcc, s18, v87
	v_mul_f32_e32 v92, 0x4b800000, v87
	v_sub_f32_e32 v90, v90, v93
	v_cndmask_b32_e32 v87, v87, v92, vcc
	v_rsq_f32_e32 v87, v87
	v_sub_f32_e32 v88, v88, v93
	v_mul_f32_e32 v92, 0x45800000, v87
	v_cndmask_b32_e32 v87, v87, v92, vcc
	v_mul_f32_e32 v90, v90, v87
	v_mul_f32_e32 v88, v88, v87
	v_fma_f32 v90, v67, v90, v106
	v_fma_f32 v88, v110, v88, v111
	v_cvt_pk_bf16_f32 v90, v90, s0
	v_cvt_pk_bf16_f32 v88, v88, s0
	ds_write_b16 v114, v90 offset:80
	v_sub_f32_e32 v90, v91, v93
	ds_write_b16 v114, v88 offset:33872
	v_sub_f32_e32 v88, v89, v93
	v_mul_f32_e32 v90, v90, v87
	v_mul_f32_e32 v87, v88, v87
	v_fma_f32 v87, v112, v87, v113
	v_cvt_pk_bf16_f32 v87, v87, s0
	ds_write_b16 v114, v87 offset:50768
	v_lshlrev_b32_e32 v87, 16, v86
	v_lshlrev_b32_e32 v86, 16, v85
	v_mul_f32_e32 v85, 0x3d372713, v86
	v_mul_f32_e32 v85, v85, v86
	v_mov_b32_e32 v88, v86
	v_fmac_f32_e32 v88, v85, v88
	v_mul_f32_e32 v85, 0x3f4c422a, v88
	v_add_f32_e32 v85, v85, v85
	v_mul_f32_e32 v85, 0xbfb8aa3b, v85
	v_exp_f32_e32 v88, v85
	v_mul_f32_e32 v85, 0x3d372713, v87
	v_mul_f32_e32 v85, v85, v87
	v_mov_b32_e32 v89, v87
	v_fmac_f32_e32 v89, v85, v89
	v_mul_f32_e32 v85, 0x3f4c422a, v89
	v_add_f32_e32 v85, v85, v85
	v_mul_f32_e32 v85, 0xbfb8aa3b, v85
	v_exp_f32_e32 v89, v85
	v_fma_f32 v90, v107, v90, v108
	v_cvt_pk_bf16_f32 v90, v90, s0
	ds_write_b16 v114, v90 offset:16976
	v_pk_add_f32 v[88:89], v[88:89], 1.0 op_sel_hi:[1,0]
	s_nop 0
	v_rcp_f32_e32 v89, v89
	v_rcp_f32_e32 v88, v88
	s_nop 0
	v_pk_mul_f32 v[86:87], v[88:89], v[86:87]
	s_nop 0
	v_add_f32_e32 v85, 0, v86
	v_add_f32_e32 v92, v85, v87
	v_lshlrev_b32_e32 v85, 16, v84
	v_lshlrev_b32_e32 v84, 16, v83
	v_mul_f32_e32 v83, 0x3d372713, v84
	v_mul_f32_e32 v83, v83, v84
	v_mov_b32_e32 v90, v84
	v_fmac_f32_e32 v90, v83, v90
	v_mul_f32_e32 v83, 0x3f4c422a, v90
	v_add_f32_e32 v83, v83, v83
	v_mul_f32_e32 v83, 0xbfb8aa3b, v83
	v_exp_f32_e32 v90, v83
	v_mul_f32_e32 v83, 0x3d372713, v85
	v_mul_f32_e32 v83, v83, v85
	v_mov_b32_e32 v91, v85
	v_fmac_f32_e32 v91, v83, v91
	v_mul_f32_e32 v83, 0x3f4c422a, v91
	v_add_f32_e32 v83, v83, v83
	v_mul_f32_e32 v83, 0xbfb8aa3b, v83
	v_exp_f32_e32 v91, v83
	v_pk_mul_f32 v[88:89], v[86:87], v[86:87]
	v_pk_add_f32 v[90:91], v[90:91], 1.0 op_sel_hi:[1,0]
	s_nop 0
	v_add_f32_e32 v88, v88, v89
	v_rcp_f32_e32 v91, v91
	v_rcp_f32_e32 v90, v90
	s_nop 0
	v_pk_mul_f32 v[84:85], v[90:91], v[84:85]
	s_nop 0
	v_add_f32_e32 v83, v92, v84
	v_add_f32_e32 v83, v83, v85
	v_pk_mul_f32 v[90:91], v[84:85], v[84:85]
	s_nop 0
	v_add_f32_dpp v83, v83, v83 quad_perm:[1,0,3,2] row_mask:0xf bank_mask:0xf bound_ctrl:1
	v_add_f32_e32 v88, v88, v90
	v_add_f32_e32 v88, v88, v91
	v_add_f32_dpp v83, v83, v83 quad_perm:[2,3,0,1] row_mask:0xf bank_mask:0xf bound_ctrl:1
	s_nop 1
	v_add_f32_dpp v83, v83, v83 row_half_mirror row_mask:0xf bank_mask:0xf bound_ctrl:1
	s_nop 1
	v_add_f32_dpp v83, v83, v83 row_mirror row_mask:0xf bank_mask:0xf bound_ctrl:1
	s_nop 0
	v_readlane_b32 s7, v83, 0
	v_readlane_b32 s5, v83, 16
	v_readlane_b32 s13, v83, 32
	v_readlane_b32 s9, v83, 48
	v_add_f32_dpp v83, v88, v88 quad_perm:[1,0,3,2] row_mask:0xf bank_mask:0xf bound_ctrl:1
	v_mov_b32_e32 v89, s5
	v_mov_b32_e32 v91, s9
	v_add_f32_dpp v83, v83, v83 quad_perm:[2,3,0,1] row_mask:0xf bank_mask:0xf bound_ctrl:1
	s_nop 1
	v_add_f32_dpp v83, v83, v83 row_half_mirror row_mask:0xf bank_mask:0xf bound_ctrl:1
	s_nop 1
	v_add_f32_dpp v83, v83, v83 row_mirror row_mask:0xf bank_mask:0xf bound_ctrl:1
	s_nop 0
	v_readlane_b32 s11, v83, 16
	v_readlane_b32 s14, v83, 48
	v_readlane_b32 s6, v83, 0
	v_readlane_b32 s12, v83, 32
	v_mov_b32_e32 v88, s11
	v_mov_b32_e32 v90, s14
	v_pk_add_f32 v[88:89], s[6:7], v[88:89]
	v_pk_add_f32 v[90:91], s[12:13], v[90:91]
	s_nop 0
	v_pk_add_f32 v[88:89], v[88:89], v[90:91]
	s_nop 0
	v_pk_mul_f32 v[88:89], v[88:89], s[20:21] op_sel_hi:[1,0]
	s_nop 0
	v_fma_f32 v83, -v89, v89, v88
	v_max_f32_e32 v83, 0, v83
	v_add_f32_e32 v83, 0x3727c5ac, v83
	v_cmp_gt_f32_e32 vcc, s18, v83
	v_mul_f32_e32 v88, 0x4b800000, v83
	v_sub_f32_e32 v86, v86, v89
	v_cndmask_b32_e32 v83, v83, v88, vcc
	v_rsq_f32_e32 v83, v83
	v_sub_f32_e32 v84, v84, v89
	v_mul_f32_e32 v88, 0x45800000, v83
	v_cndmask_b32_e32 v83, v83, v88, vcc
	v_mul_f32_e32 v86, v86, v83
	v_mul_f32_e32 v84, v84, v83
	v_fma_f32 v86, v67, v86, v106
	v_fma_f32 v84, v110, v84, v111
	v_cvt_pk_bf16_f32 v86, v86, s0
	v_cvt_pk_bf16_f32 v84, v84, s0
	ds_write_b16 v114, v86 offset:96
	v_sub_f32_e32 v86, v87, v89
	ds_write_b16 v114, v84 offset:33888
	v_sub_f32_e32 v84, v85, v89
	v_mul_f32_e32 v86, v86, v83
	v_mul_f32_e32 v83, v84, v83
	v_fma_f32 v83, v112, v83, v113
	v_cvt_pk_bf16_f32 v83, v83, s0
	ds_write_b16 v114, v83 offset:50784
	v_lshlrev_b32_e32 v83, 16, v82
	v_lshlrev_b32_e32 v82, 16, v81
	v_mul_f32_e32 v81, 0x3d372713, v82
	v_mul_f32_e32 v81, v81, v82
	v_mov_b32_e32 v84, v82
	v_fmac_f32_e32 v84, v81, v84
	v_mul_f32_e32 v81, 0x3f4c422a, v84
	v_add_f32_e32 v81, v81, v81
	v_mul_f32_e32 v81, 0xbfb8aa3b, v81
	v_exp_f32_e32 v84, v81
	v_mul_f32_e32 v81, 0x3d372713, v83
	v_mul_f32_e32 v81, v81, v83
	v_mov_b32_e32 v85, v83
	v_fmac_f32_e32 v85, v81, v85
	v_mul_f32_e32 v81, 0x3f4c422a, v85
	v_add_f32_e32 v81, v81, v81
	v_mul_f32_e32 v81, 0xbfb8aa3b, v81
	v_exp_f32_e32 v85, v81
	v_fma_f32 v86, v107, v86, v108
	v_cvt_pk_bf16_f32 v86, v86, s0
	ds_write_b16 v114, v86 offset:16992
	v_pk_add_f32 v[84:85], v[84:85], 1.0 op_sel_hi:[1,0]
	s_nop 0
	v_rcp_f32_e32 v85, v85
	v_rcp_f32_e32 v84, v84
	s_nop 0
	v_pk_mul_f32 v[82:83], v[84:85], v[82:83]
	s_nop 0
	v_add_f32_e32 v81, 0, v82
	v_add_f32_e32 v88, v81, v83
	v_lshlrev_b32_e32 v81, 16, v80
	v_lshlrev_b32_e32 v80, 16, v79
	v_mul_f32_e32 v79, 0x3d372713, v80
	v_mul_f32_e32 v79, v79, v80
	v_mov_b32_e32 v86, v80
	v_fmac_f32_e32 v86, v79, v86
	v_mul_f32_e32 v79, 0x3f4c422a, v86
	v_add_f32_e32 v79, v79, v79
	v_mul_f32_e32 v79, 0xbfb8aa3b, v79
	v_exp_f32_e32 v86, v79
	v_mul_f32_e32 v79, 0x3d372713, v81
	v_mul_f32_e32 v79, v79, v81
	v_mov_b32_e32 v87, v81
	v_fmac_f32_e32 v87, v79, v87
	v_mul_f32_e32 v79, 0x3f4c422a, v87
	v_add_f32_e32 v79, v79, v79
	v_mul_f32_e32 v79, 0xbfb8aa3b, v79
	v_exp_f32_e32 v87, v79
	v_pk_mul_f32 v[84:85], v[82:83], v[82:83]
	v_pk_add_f32 v[86:87], v[86:87], 1.0 op_sel_hi:[1,0]
	s_nop 0
	v_add_f32_e32 v84, v84, v85
	v_rcp_f32_e32 v87, v87
	v_rcp_f32_e32 v86, v86
	s_nop 0
	v_pk_mul_f32 v[80:81], v[86:87], v[80:81]
	s_nop 0
	v_add_f32_e32 v79, v88, v80
	v_add_f32_e32 v79, v79, v81
	v_pk_mul_f32 v[86:87], v[80:81], v[80:81]
	s_nop 0
	v_add_f32_dpp v79, v79, v79 quad_perm:[1,0,3,2] row_mask:0xf bank_mask:0xf bound_ctrl:1
	v_add_f32_e32 v84, v84, v86
	v_add_f32_e32 v84, v84, v87
	v_add_f32_dpp v79, v79, v79 quad_perm:[2,3,0,1] row_mask:0xf bank_mask:0xf bound_ctrl:1
	s_nop 1
	v_add_f32_dpp v79, v79, v79 row_half_mirror row_mask:0xf bank_mask:0xf bound_ctrl:1
	s_nop 1
	v_add_f32_dpp v79, v79, v79 row_mirror row_mask:0xf bank_mask:0xf bound_ctrl:1
	s_nop 0
	v_readlane_b32 s7, v79, 0
	v_readlane_b32 s5, v79, 16
	v_readlane_b32 s13, v79, 32
	v_readlane_b32 s9, v79, 48
	v_add_f32_dpp v79, v84, v84 quad_perm:[1,0,3,2] row_mask:0xf bank_mask:0xf bound_ctrl:1
	v_mov_b32_e32 v85, s5
	v_mov_b32_e32 v87, s9
	v_add_f32_dpp v79, v79, v79 quad_perm:[2,3,0,1] row_mask:0xf bank_mask:0xf bound_ctrl:1
	s_nop 1
	v_add_f32_dpp v79, v79, v79 row_half_mirror row_mask:0xf bank_mask:0xf bound_ctrl:1
	s_nop 1
	v_add_f32_dpp v79, v79, v79 row_mirror row_mask:0xf bank_mask:0xf bound_ctrl:1
	s_nop 0
	v_readlane_b32 s11, v79, 16
	v_readlane_b32 s14, v79, 48
	v_readlane_b32 s6, v79, 0
	v_readlane_b32 s12, v79, 32
	v_mov_b32_e32 v84, s11
	v_mov_b32_e32 v86, s14
	v_pk_add_f32 v[84:85], s[6:7], v[84:85]
	v_pk_add_f32 v[86:87], s[12:13], v[86:87]
	s_nop 0
	v_pk_add_f32 v[84:85], v[84:85], v[86:87]
	s_nop 0
	v_pk_mul_f32 v[84:85], v[84:85], s[20:21] op_sel_hi:[1,0]
	s_nop 0
	v_fma_f32 v79, -v85, v85, v84
	v_max_f32_e32 v79, 0, v79
	v_add_f32_e32 v79, 0x3727c5ac, v79
	v_cmp_gt_f32_e32 vcc, s18, v79
	v_mul_f32_e32 v84, 0x4b800000, v79
	v_sub_f32_e32 v82, v82, v85
	v_cndmask_b32_e32 v79, v79, v84, vcc
	v_rsq_f32_e32 v79, v79
	v_sub_f32_e32 v80, v80, v85
	v_mul_f32_e32 v84, 0x45800000, v79
	v_cndmask_b32_e32 v79, v79, v84, vcc
	v_mul_f32_e32 v82, v82, v79
	v_mul_f32_e32 v80, v80, v79
	v_fma_f32 v82, v67, v82, v106
	v_fma_f32 v80, v110, v80, v111
	v_cvt_pk_bf16_f32 v82, v82, s0
	v_cvt_pk_bf16_f32 v80, v80, s0
	ds_write_b16 v114, v82 offset:112
	v_sub_f32_e32 v82, v83, v85
	ds_write_b16 v114, v80 offset:33904
	v_sub_f32_e32 v80, v81, v85
	v_mul_f32_e32 v82, v82, v79
	v_mul_f32_e32 v79, v80, v79
	v_fma_f32 v79, v112, v79, v113
	v_cvt_pk_bf16_f32 v79, v79, s0
	ds_write_b16 v114, v79 offset:50800
	v_lshlrev_b32_e32 v79, 16, v78
	v_lshlrev_b32_e32 v78, 16, v77
	v_mul_f32_e32 v77, 0x3d372713, v78
	v_mul_f32_e32 v77, v77, v78
	v_mov_b32_e32 v80, v78
	v_fmac_f32_e32 v80, v77, v80
	v_mul_f32_e32 v77, 0x3f4c422a, v80
	v_add_f32_e32 v77, v77, v77
	v_mul_f32_e32 v77, 0xbfb8aa3b, v77
	v_exp_f32_e32 v80, v77
	v_mul_f32_e32 v77, 0x3d372713, v79
	v_mul_f32_e32 v77, v77, v79
	v_mov_b32_e32 v81, v79
	v_fmac_f32_e32 v81, v77, v81
	v_mul_f32_e32 v77, 0x3f4c422a, v81
	v_add_f32_e32 v77, v77, v77
	v_mul_f32_e32 v77, 0xbfb8aa3b, v77
	v_exp_f32_e32 v81, v77
	v_fma_f32 v82, v107, v82, v108
	v_cvt_pk_bf16_f32 v82, v82, s0
	ds_write_b16 v114, v82 offset:17008
	v_pk_add_f32 v[80:81], v[80:81], 1.0 op_sel_hi:[1,0]
	s_nop 0
	v_rcp_f32_e32 v81, v81
	v_mul_f32_e32 v82, 0x3d372713, v14
	v_mul_f32_e32 v82, v82, v14
	v_mov_b32_e32 v83, v14
	v_fmac_f32_e32 v83, v82, v83
	v_mul_f32_e32 v82, 0x3f4c422a, v83
	v_mul_f32_e32 v83, 0x3d372713, v15
	v_mul_f32_e32 v83, v83, v15
	v_mov_b32_e32 v84, v15
	v_fmac_f32_e32 v84, v83, v84
	v_mul_f32_e32 v83, 0x3f4c422a, v84
	v_add_f32_e32 v82, v82, v82
	v_add_f32_e32 v83, v83, v83
	v_mul_f32_e32 v82, 0xbfb8aa3b, v82
	v_mul_f32_e32 v83, 0xbfb8aa3b, v83
	v_exp_f32_e32 v82, v82
	v_exp_f32_e32 v83, v83
	v_rcp_f32_e32 v80, v80
	s_nop 0
	v_pk_mul_f32 v[78:79], v[80:81], v[78:79]
	v_pk_add_f32 v[82:83], v[82:83], 1.0 op_sel_hi:[1,0]
	s_nop 0
	v_add_f32_e32 v77, 0, v78
	v_add_f32_e32 v77, v77, v79
	v_pk_mul_f32 v[80:81], v[78:79], v[78:79]
	v_rcp_f32_e32 v83, v83
	v_add_f32_e32 v80, v80, v81
	v_rcp_f32_e32 v82, v82
	s_nop 0
	v_pk_mul_f32 v[14:15], v[82:83], v[14:15]
	s_nop 0
	v_add_f32_e32 v77, v77, v14
	v_add_f32_e32 v77, v77, v15
	v_pk_mul_f32 v[82:83], v[14:15], v[14:15]
	s_nop 0
	v_add_f32_dpp v77, v77, v77 quad_perm:[1,0,3,2] row_mask:0xf bank_mask:0xf bound_ctrl:1
	v_add_f32_e32 v80, v80, v82
	v_add_f32_e32 v80, v80, v83
	v_add_f32_dpp v77, v77, v77 quad_perm:[2,3,0,1] row_mask:0xf bank_mask:0xf bound_ctrl:1
	s_nop 1
	v_add_f32_dpp v77, v77, v77 row_half_mirror row_mask:0xf bank_mask:0xf bound_ctrl:1
	s_nop 1
	v_add_f32_dpp v77, v77, v77 row_mirror row_mask:0xf bank_mask:0xf bound_ctrl:1
	s_nop 0
	v_readlane_b32 s7, v77, 0
	v_readlane_b32 s5, v77, 16
	v_readlane_b32 s13, v77, 32
	v_readlane_b32 s9, v77, 48
	v_add_f32_dpp v77, v80, v80 quad_perm:[1,0,3,2] row_mask:0xf bank_mask:0xf bound_ctrl:1
	v_mov_b32_e32 v81, s5
	v_mov_b32_e32 v83, s9
	v_add_f32_dpp v77, v77, v77 quad_perm:[2,3,0,1] row_mask:0xf bank_mask:0xf bound_ctrl:1
	s_nop 1
	v_add_f32_dpp v77, v77, v77 row_half_mirror row_mask:0xf bank_mask:0xf bound_ctrl:1
	s_nop 1
	v_add_f32_dpp v77, v77, v77 row_mirror row_mask:0xf bank_mask:0xf bound_ctrl:1
	s_nop 0
	v_readlane_b32 s11, v77, 16
	v_readlane_b32 s14, v77, 48
	v_readlane_b32 s6, v77, 0
	v_readlane_b32 s12, v77, 32
	v_mov_b32_e32 v80, s11
	v_mov_b32_e32 v82, s14
	v_pk_add_f32 v[80:81], s[6:7], v[80:81]
	v_pk_add_f32 v[82:83], s[12:13], v[82:83]
	s_nop 0
	v_pk_add_f32 v[80:81], v[80:81], v[82:83]
	s_nop 0
	v_pk_mul_f32 v[80:81], v[80:81], s[20:21] op_sel_hi:[1,0]
	s_nop 0
	v_fma_f32 v77, -v81, v81, v80
	v_max_f32_e32 v77, 0, v77
	v_add_f32_e32 v77, 0x3727c5ac, v77
	v_cmp_gt_f32_e32 vcc, s18, v77
	v_mul_f32_e32 v80, 0x4b800000, v77
	v_sub_f32_e32 v14, v14, v81
	v_cndmask_b32_e32 v77, v77, v80, vcc
	v_rsq_f32_e32 v77, v77
	v_sub_f32_e32 v78, v78, v81
	v_mul_f32_e32 v80, 0x45800000, v77
	v_cndmask_b32_e32 v77, v77, v80, vcc
	v_mul_f32_e32 v14, v14, v77
	v_fma_f32 v14, v110, v14, v111
	v_cvt_pk_bf16_f32 v14, v14, s0
	ds_write_b16 v114, v14 offset:33920
	v_sub_f32_e32 v14, v15, v81
	v_mul_f32_e32 v14, v14, v77
	v_fma_f32 v14, v112, v14, v113
	v_cvt_pk_bf16_f32 v14, v14, s0
	v_mul_f32_e32 v78, v78, v77
	ds_write_b16 v114, v14 offset:50816
	v_mul_f32_e32 v14, 0x3d372713, v12
	v_fma_f32 v78, v67, v78, v106
	v_mul_f32_e32 v14, v14, v12
	v_mov_b32_e32 v15, v12
	v_cvt_pk_bf16_f32 v78, v78, s0
	v_fmac_f32_e32 v15, v14, v15
	ds_write_b16 v114, v78 offset:128
	v_sub_f32_e32 v78, v79, v81
	v_mul_f32_e32 v14, 0x3f4c422a, v15
	v_mul_f32_e32 v15, 0x3d372713, v13
	v_mul_f32_e32 v78, v78, v77
	v_mul_f32_e32 v15, v15, v13
	v_mov_b32_e32 v77, v13
	v_fmac_f32_e32 v77, v15, v77
	v_mul_f32_e32 v15, 0x3f4c422a, v77
	v_add_f32_e32 v14, v14, v14
	v_add_f32_e32 v15, v15, v15
	v_mul_f32_e32 v14, 0xbfb8aa3b, v14
	v_mul_f32_e32 v15, 0xbfb8aa3b, v15
	v_exp_f32_e32 v14, v14
	v_exp_f32_e32 v15, v15
	v_fma_f32 v78, v107, v78, v108
	v_cvt_pk_bf16_f32 v78, v78, s0
	ds_write_b16 v114, v78 offset:17024
	v_pk_add_f32 v[14:15], v[14:15], 1.0 op_sel_hi:[1,0]
	s_nop 0
	v_rcp_f32_e32 v15, v15
	v_mul_f32_e32 v78, 0x3d372713, v10
	v_mul_f32_e32 v78, v78, v10
	v_mov_b32_e32 v79, v10
	v_fmac_f32_e32 v79, v78, v79
	v_mul_f32_e32 v78, 0x3f4c422a, v79
	v_mul_f32_e32 v79, 0x3d372713, v11
	v_mul_f32_e32 v79, v79, v11
	v_mov_b32_e32 v80, v11
	v_fmac_f32_e32 v80, v79, v80
	v_mul_f32_e32 v79, 0x3f4c422a, v80
	v_add_f32_e32 v78, v78, v78
	v_add_f32_e32 v79, v79, v79
	v_mul_f32_e32 v78, 0xbfb8aa3b, v78
	v_mul_f32_e32 v79, 0xbfb8aa3b, v79
	v_exp_f32_e32 v78, v78
	v_exp_f32_e32 v79, v79
	v_rcp_f32_e32 v14, v14
	s_nop 0
	v_pk_mul_f32 v[12:13], v[14:15], v[12:13]
	v_pk_add_f32 v[78:79], v[78:79], 1.0 op_sel_hi:[1,0]
	s_nop 0
	v_add_f32_e32 v14, 0, v12
	v_add_f32_e32 v77, v14, v13
	v_pk_mul_f32 v[14:15], v[12:13], v[12:13]
	v_rcp_f32_e32 v79, v79
	v_add_f32_e32 v14, v14, v15
	v_rcp_f32_e32 v78, v78
	s_nop 0
	v_pk_mul_f32 v[10:11], v[78:79], v[10:11]
	v_lshlrev_b32_e32 v81, 16, v76
	v_pk_mul_f32 v[78:79], v[10:11], v[10:11]
	v_add_f32_e32 v77, v77, v10
	v_add_f32_e32 v14, v14, v78
	v_add_f32_e32 v77, v77, v11
	v_add_f32_e32 v14, v14, v79
	s_nop 0
	v_add_f32_dpp v15, v77, v77 quad_perm:[1,0,3,2] row_mask:0xf bank_mask:0xf bound_ctrl:1
	v_add_f32_dpp v14, v14, v14 quad_perm:[1,0,3,2] row_mask:0xf bank_mask:0xf bound_ctrl:1
	s_nop 0
	v_add_f32_dpp v15, v15, v15 quad_perm:[2,3,0,1] row_mask:0xf bank_mask:0xf bound_ctrl:1
	v_add_f32_dpp v14, v14, v14 quad_perm:[2,3,0,1] row_mask:0xf bank_mask:0xf bound_ctrl:1
	s_nop 0
	v_add_f32_dpp v15, v15, v15 row_half_mirror row_mask:0xf bank_mask:0xf bound_ctrl:1
	v_add_f32_dpp v14, v14, v14 row_half_mirror row_mask:0xf bank_mask:0xf bound_ctrl:1
	s_nop 0
	v_add_f32_dpp v15, v15, v15 row_mirror row_mask:0xf bank_mask:0xf bound_ctrl:1
	v_add_f32_dpp v14, v14, v14 row_mirror row_mask:0xf bank_mask:0xf bound_ctrl:1
	v_readlane_b32 s5, v15, 16
	v_readlane_b32 s9, v15, 48
	v_readlane_b32 s11, v14, 16
	v_readlane_b32 s14, v14, 48
	v_readlane_b32 s7, v15, 0
	v_readlane_b32 s13, v15, 32
	v_readlane_b32 s6, v14, 0
	v_readlane_b32 s12, v14, 32
	v_mov_b32_e32 v14, s11
	v_mov_b32_e32 v15, s5
	v_mov_b32_e32 v78, s14
	v_mov_b32_e32 v79, s9
	v_pk_add_f32 v[14:15], s[6:7], v[14:15]
	v_pk_add_f32 v[78:79], s[12:13], v[78:79]
	s_nop 0
	v_pk_add_f32 v[14:15], v[14:15], v[78:79]
	s_nop 0
	v_pk_mul_f32 v[14:15], v[14:15], s[20:21] op_sel_hi:[1,0]
	s_nop 0
	v_fma_f32 v14, -v15, v15, v14
	v_max_f32_e32 v14, 0, v14
	v_add_f32_e32 v14, 0x3727c5ac, v14
	v_cmp_gt_f32_e32 vcc, s18, v14
	v_mul_f32_e32 v77, 0x4b800000, v14
	v_sub_f32_e32 v12, v12, v15
	v_cndmask_b32_e32 v14, v14, v77, vcc
	v_rsq_f32_e32 v14, v14
	v_sub_f32_e32 v10, v10, v15
	v_sub_f32_e32 v11, v11, v15
	v_mul_f32_e32 v77, 0x45800000, v14
	v_cndmask_b32_e32 v14, v14, v77, vcc
	global_load_dword v77, v[0:1], off
	global_load_dword v78, v[2:3], off
	v_mul_f32_e32 v12, v12, v14
	v_mul_f32_e32 v80, v10, v14
	s_waitcnt vmcnt(0)
	v_fma_f32 v12, v77, v12, v78
	v_cvt_pk_bf16_f32 v12, v12, s0
	ds_write_b16 v114, v12 offset:144
	v_sub_f32_e32 v12, v13, v15
	v_mul_f32_e32 v79, v12, v14
	global_load_dword v12, v[0:1], off offset:256
	global_load_dword v13, v[2:3], off offset:256
	v_mul_f32_e32 v15, v11, v14
	s_waitcnt vmcnt(0)
	v_fma_f32 v79, v12, v79, v13
	v_cvt_pk_bf16_f32 v79, v79, s0
	ds_write_b16 v114, v79 offset:17040
	global_load_dword v10, v[0:1], off offset:512
	global_load_dword v79, v[2:3], off offset:512
	s_waitcnt vmcnt(0)
	v_fma_f32 v80, v10, v80, v79
	v_cvt_pk_bf16_f32 v80, v80, s0
	ds_write_b16 v114, v80 offset:33936
	global_load_dword v11, v[0:1], off offset:768
	global_load_dword v14, v[2:3], off offset:768
	v_lshlrev_b32_e32 v80, 16, v35
	v_mov_b32_e32 v35, v80
	s_waitcnt vmcnt(0)
	v_fma_f32 v15, v11, v15, v14
	v_cvt_pk_bf16_f32 v15, v15, s0
	ds_write_b16 v114, v15 offset:50832
	v_mul_f32_e32 v15, 0x3d372713, v80
	v_mul_f32_e32 v15, v15, v80
	v_fmac_f32_e32 v35, v15, v35
	v_mul_f32_e32 v15, 0x3f4c422a, v35
	v_add_f32_e32 v15, v15, v15
	v_mul_f32_e32 v15, 0xbfb8aa3b, v15
	v_exp_f32_e32 v82, v15
	v_mul_f32_e32 v15, 0x3d372713, v81
	v_mul_f32_e32 v15, v15, v81
	v_mov_b32_e32 v35, v81
	v_fmac_f32_e32 v35, v15, v35
	v_mul_f32_e32 v15, 0x3f4c422a, v35
	v_add_f32_e32 v15, v15, v15
	v_mul_f32_e32 v15, 0xbfb8aa3b, v15
	v_exp_f32_e32 v83, v15
	s_nop 0
	v_pk_add_f32 v[82:83], v[82:83], 1.0 op_sel_hi:[1,0]
	s_nop 0
	v_rcp_f32_e32 v83, v83
	v_lshlrev_b32_e32 v35, 16, v34
	v_lshlrev_b32_e32 v34, 16, v33
	v_mul_f32_e32 v33, 0x3d372713, v34
	v_mul_f32_e32 v33, v33, v34
	v_mov_b32_e32 v76, v34
	v_fmac_f32_e32 v76, v33, v76
	v_mul_f32_e32 v33, 0x3f4c422a, v76
	v_add_f32_e32 v33, v33, v33
	v_mul_f32_e32 v33, 0xbfb8aa3b, v33
	v_exp_f32_e32 v84, v33
	v_mul_f32_e32 v33, 0x3d372713, v35
	v_mul_f32_e32 v33, v33, v35
	v_mov_b32_e32 v76, v35
	v_fmac_f32_e32 v76, v33, v76
	v_mul_f32_e32 v33, 0x3f4c422a, v76
	v_add_f32_e32 v33, v33, v33
	v_mul_f32_e32 v33, 0xbfb8aa3b, v33
	v_exp_f32_e32 v85, v33
	v_rcp_f32_e32 v82, v82
	s_nop 0
	v_pk_mul_f32 v[80:81], v[82:83], v[80:81]
	v_pk_add_f32 v[84:85], v[84:85], 1.0 op_sel_hi:[1,0]
	s_nop 0
	v_add_f32_e32 v15, 0, v80
	v_add_f32_e32 v15, v15, v81
	v_pk_mul_f32 v[82:83], v[80:81], v[80:81]
	v_rcp_f32_e32 v85, v85
	v_rcp_f32_e32 v84, v84
	s_nop 0
	v_pk_mul_f32 v[34:35], v[84:85], v[34:35]
	v_add_f32_e32 v33, v82, v83
	v_add_f32_e32 v15, v15, v34
	v_add_f32_e32 v15, v15, v35
	v_pk_mul_f32 v[84:85], v[34:35], v[34:35]
	s_nop 0
	v_add_f32_dpp v15, v15, v15 quad_perm:[1,0,3,2] row_mask:0xf bank_mask:0xf bound_ctrl:1
	v_add_f32_e32 v33, v33, v84
	v_add_f32_e32 v33, v33, v85
	v_add_f32_dpp v15, v15, v15 quad_perm:[2,3,0,1] row_mask:0xf bank_mask:0xf bound_ctrl:1
	s_nop 1
	v_add_f32_dpp v15, v15, v15 row_half_mirror row_mask:0xf bank_mask:0xf bound_ctrl:1
	s_nop 1
	v_add_f32_dpp v15, v15, v15 row_mirror row_mask:0xf bank_mask:0xf bound_ctrl:1
	s_nop 0
	v_readlane_b32 s7, v15, 0
	v_readlane_b32 s5, v15, 16
	v_readlane_b32 s13, v15, 32
	v_readlane_b32 s9, v15, 48
	v_add_f32_dpp v15, v33, v33 quad_perm:[1,0,3,2] row_mask:0xf bank_mask:0xf bound_ctrl:1
	v_mov_b32_e32 v83, s5
	v_mov_b32_e32 v85, s9
	v_add_f32_dpp v15, v15, v15 quad_perm:[2,3,0,1] row_mask:0xf bank_mask:0xf bound_ctrl:1
	s_nop 1
	v_add_f32_dpp v15, v15, v15 row_half_mirror row_mask:0xf bank_mask:0xf bound_ctrl:1
	s_nop 1
	v_add_f32_dpp v15, v15, v15 row_mirror row_mask:0xf bank_mask:0xf bound_ctrl:1
	s_nop 0
	v_readlane_b32 s11, v15, 16
	v_readlane_b32 s14, v15, 48
	v_readlane_b32 s6, v15, 0
	v_readlane_b32 s12, v15, 32
	v_mov_b32_e32 v82, s11
	v_mov_b32_e32 v84, s14
	v_pk_add_f32 v[82:83], s[6:7], v[82:83]
	v_pk_add_f32 v[84:85], s[12:13], v[84:85]
	s_nop 0
	v_pk_add_f32 v[82:83], v[82:83], v[84:85]
	s_nop 0
	v_pk_mul_f32 v[82:83], v[82:83], s[20:21] op_sel_hi:[1,0]
	s_nop 0
	v_fma_f32 v15, -v83, v83, v82
	v_max_f32_e32 v15, 0, v15
	v_add_f32_e32 v15, 0x3727c5ac, v15
	v_cmp_gt_f32_e32 vcc, s18, v15
	v_mul_f32_e32 v33, 0x4b800000, v15
	s_nop 0
	v_cndmask_b32_e32 v15, v15, v33, vcc
	v_rsq_f32_e32 v15, v15
	s_nop 0
	v_mul_f32_e32 v33, 0x45800000, v15
	v_cndmask_b32_e32 v15, v15, v33, vcc
	v_sub_f32_e32 v33, v80, v83
	v_mul_f32_e32 v33, v33, v15
	v_fma_f32 v33, v77, v33, v78
	v_cvt_pk_bf16_f32 v33, v33, s0
	ds_write_b16 v114, v33 offset:160
	v_sub_f32_e32 v33, v81, v83
	v_mul_f32_e32 v33, v33, v15
	v_fma_f32 v33, v12, v33, v13
	v_cvt_pk_bf16_f32 v33, v33, s0
	ds_write_b16 v114, v33 offset:17056
	v_sub_f32_e32 v33, v34, v83
	v_mul_f32_e32 v33, v33, v15
	v_fma_f32 v33, v10, v33, v79
	v_cvt_pk_bf16_f32 v33, v33, s0
	ds_write_b16 v114, v33 offset:33952
	v_sub_f32_e32 v33, v35, v83
	v_mul_f32_e32 v15, v33, v15
	v_fma_f32 v15, v11, v15, v14
	v_cvt_pk_bf16_f32 v15, v15, s0
	v_lshlrev_b32_e32 v33, 16, v32
	v_lshlrev_b32_e32 v32, 16, v31
	ds_write_b16 v114, v15 offset:50848
	v_mul_f32_e32 v15, 0x3d372713, v32
	v_mul_f32_e32 v15, v15, v32
	v_mov_b32_e32 v31, v32
	v_fmac_f32_e32 v31, v15, v31
	v_mul_f32_e32 v15, 0x3f4c422a, v31
	v_add_f32_e32 v15, v15, v15
	v_mul_f32_e32 v15, 0xbfb8aa3b, v15
	v_exp_f32_e32 v34, v15
	v_mul_f32_e32 v15, 0x3d372713, v33
	v_mul_f32_e32 v15, v15, v33
	v_mov_b32_e32 v31, v33
	v_fmac_f32_e32 v31, v15, v31
	v_mul_f32_e32 v15, 0x3f4c422a, v31
	v_add_f32_e32 v15, v15, v15
	v_mul_f32_e32 v15, 0xbfb8aa3b, v15
	v_exp_f32_e32 v35, v15
	s_nop 0
	v_pk_add_f32 v[34:35], v[34:35], 1.0 op_sel_hi:[1,0]
	s_nop 0
	v_rcp_f32_e32 v35, v35
	v_lshlrev_b32_e32 v31, 16, v30
	v_lshlrev_b32_e32 v30, 16, v29
	v_mul_f32_e32 v29, 0x3d372713, v30
	v_mul_f32_e32 v29, v29, v30
	v_mov_b32_e32 v76, v30
	v_fmac_f32_e32 v76, v29, v76
	v_mul_f32_e32 v29, 0x3f4c422a, v76
	v_add_f32_e32 v29, v29, v29
	v_mul_f32_e32 v29, 0xbfb8aa3b, v29
	v_exp_f32_e32 v80, v29
	v_mul_f32_e32 v29, 0x3d372713, v31
	v_mul_f32_e32 v29, v29, v31
	v_mov_b32_e32 v76, v31
	v_fmac_f32_e32 v76, v29, v76
	v_mul_f32_e32 v29, 0x3f4c422a, v76
	v_add_f32_e32 v29, v29, v29
	v_mul_f32_e32 v29, 0xbfb8aa3b, v29
	v_exp_f32_e32 v81, v29
	v_rcp_f32_e32 v34, v34
	s_nop 0
	v_pk_mul_f32 v[32:33], v[34:35], v[32:33]
	v_pk_add_f32 v[80:81], v[80:81], 1.0 op_sel_hi:[1,0]
	s_nop 0
	v_add_f32_e32 v15, 0, v32
	v_add_f32_e32 v15, v15, v33
	v_pk_mul_f32 v[34:35], v[32:33], v[32:33]
	v_rcp_f32_e32 v81, v81
	v_rcp_f32_e32 v80, v80
	s_nop 0
	v_pk_mul_f32 v[30:31], v[80:81], v[30:31]
	v_add_f32_e32 v29, v34, v35
	v_add_f32_e32 v15, v15, v30
	v_add_f32_e32 v15, v15, v31
	v_pk_mul_f32 v[80:81], v[30:31], v[30:31]
	s_nop 0
	v_add_f32_dpp v15, v15, v15 quad_perm:[1,0,3,2] row_mask:0xf bank_mask:0xf bound_ctrl:1
	v_add_f32_e32 v29, v29, v80
	v_add_f32_e32 v29, v29, v81
	v_add_f32_dpp v15, v15, v15 quad_perm:[2,3,0,1] row_mask:0xf bank_mask:0xf bound_ctrl:1
	s_nop 1
	v_add_f32_dpp v15, v15, v15 row_half_mirror row_mask:0xf bank_mask:0xf bound_ctrl:1
	s_nop 1
	v_add_f32_dpp v15, v15, v15 row_mirror row_mask:0xf bank_mask:0xf bound_ctrl:1
	s_nop 0
	v_readlane_b32 s7, v15, 0
	v_readlane_b32 s5, v15, 16
	v_readlane_b32 s13, v15, 32
	v_readlane_b32 s9, v15, 48
	v_add_f32_dpp v15, v29, v29 quad_perm:[1,0,3,2] row_mask:0xf bank_mask:0xf bound_ctrl:1
	v_mov_b32_e32 v35, s5
	v_mov_b32_e32 v81, s9
	v_add_f32_dpp v15, v15, v15 quad_perm:[2,3,0,1] row_mask:0xf bank_mask:0xf bound_ctrl:1
	s_nop 1
	v_add_f32_dpp v15, v15, v15 row_half_mirror row_mask:0xf bank_mask:0xf bound_ctrl:1
	s_nop 1
	v_add_f32_dpp v15, v15, v15 row_mirror row_mask:0xf bank_mask:0xf bound_ctrl:1
	s_nop 0
	v_readlane_b32 s11, v15, 16
	v_readlane_b32 s14, v15, 48
	v_readlane_b32 s6, v15, 0
	v_readlane_b32 s12, v15, 32
	v_mov_b32_e32 v34, s11
	v_mov_b32_e32 v80, s14
	v_pk_add_f32 v[34:35], s[6:7], v[34:35]
	v_pk_add_f32 v[80:81], s[12:13], v[80:81]
	s_nop 0
	v_pk_add_f32 v[34:35], v[34:35], v[80:81]
	s_nop 0
	v_pk_mul_f32 v[34:35], v[34:35], s[20:21] op_sel_hi:[1,0]
	s_nop 0
	v_fma_f32 v15, -v35, v35, v34
	v_max_f32_e32 v15, 0, v15
	v_add_f32_e32 v15, 0x3727c5ac, v15
	v_cmp_gt_f32_e32 vcc, s18, v15
	v_mul_f32_e32 v29, 0x4b800000, v15
	s_nop 0
	v_cndmask_b32_e32 v15, v15, v29, vcc
	v_rsq_f32_e32 v15, v15
	s_nop 0
	v_mul_f32_e32 v29, 0x45800000, v15
	v_cndmask_b32_e32 v15, v15, v29, vcc
	v_sub_f32_e32 v29, v32, v35
	v_mul_f32_e32 v29, v29, v15
	v_fma_f32 v29, v77, v29, v78
	v_cvt_pk_bf16_f32 v29, v29, s0
	ds_write_b16 v114, v29 offset:176
	v_sub_f32_e32 v29, v33, v35
	v_mul_f32_e32 v29, v29, v15
	v_fma_f32 v29, v12, v29, v13
	v_cvt_pk_bf16_f32 v29, v29, s0
	ds_write_b16 v114, v29 offset:17072
	v_sub_f32_e32 v29, v30, v35
	v_mul_f32_e32 v29, v29, v15
	v_fma_f32 v29, v10, v29, v79
	v_cvt_pk_bf16_f32 v29, v29, s0
	ds_write_b16 v114, v29 offset:33968
	v_sub_f32_e32 v29, v31, v35
	v_mul_f32_e32 v15, v29, v15
	v_fma_f32 v15, v11, v15, v14
	v_cvt_pk_bf16_f32 v15, v15, s0
	v_lshlrev_b32_e32 v29, 16, v28
	v_lshlrev_b32_e32 v28, 16, v27
	ds_write_b16 v114, v15 offset:50864
	v_mul_f32_e32 v15, 0x3d372713, v28
	v_mul_f32_e32 v15, v15, v28
	v_mov_b32_e32 v27, v28
	v_fmac_f32_e32 v27, v15, v27
	v_mul_f32_e32 v15, 0x3f4c422a, v27
	v_add_f32_e32 v15, v15, v15
	v_mul_f32_e32 v15, 0xbfb8aa3b, v15
	v_exp_f32_e32 v30, v15
	v_mul_f32_e32 v15, 0x3d372713, v29
	v_mul_f32_e32 v15, v15, v29
	v_mov_b32_e32 v27, v29
	v_fmac_f32_e32 v27, v15, v27
	v_mul_f32_e32 v15, 0x3f4c422a, v27
	v_add_f32_e32 v15, v15, v15
	v_mul_f32_e32 v15, 0xbfb8aa3b, v15
	v_exp_f32_e32 v31, v15
	s_nop 0
	v_pk_add_f32 v[30:31], v[30:31], 1.0 op_sel_hi:[1,0]
	s_nop 0
	v_rcp_f32_e32 v31, v31
	v_lshlrev_b32_e32 v27, 16, v26
	v_lshlrev_b32_e32 v26, 16, v25
	v_mul_f32_e32 v25, 0x3d372713, v26
	v_mul_f32_e32 v25, v25, v26
	v_mov_b32_e32 v32, v26
	v_fmac_f32_e32 v32, v25, v32
	v_mul_f32_e32 v25, 0x3f4c422a, v32
	v_add_f32_e32 v25, v25, v25
	v_mul_f32_e32 v25, 0xbfb8aa3b, v25
	v_exp_f32_e32 v32, v25
	v_mul_f32_e32 v25, 0x3d372713, v27
	v_mul_f32_e32 v25, v25, v27
	v_mov_b32_e32 v33, v27
	v_fmac_f32_e32 v33, v25, v33
	v_mul_f32_e32 v25, 0x3f4c422a, v33
	v_add_f32_e32 v25, v25, v25
	v_mul_f32_e32 v25, 0xbfb8aa3b, v25
	v_exp_f32_e32 v33, v25
	v_rcp_f32_e32 v30, v30
	s_nop 0
	v_pk_mul_f32 v[28:29], v[30:31], v[28:29]
	v_pk_add_f32 v[32:33], v[32:33], 1.0 op_sel_hi:[1,0]
	s_nop 0
	v_add_f32_e32 v15, 0, v28
	v_add_f32_e32 v15, v15, v29
	v_pk_mul_f32 v[30:31], v[28:29], v[28:29]
	v_rcp_f32_e32 v33, v33
	v_rcp_f32_e32 v32, v32
	s_nop 0
	v_pk_mul_f32 v[26:27], v[32:33], v[26:27]
	v_add_f32_e32 v25, v30, v31
	v_add_f32_e32 v15, v15, v26
	v_add_f32_e32 v15, v15, v27
	v_pk_mul_f32 v[32:33], v[26:27], v[26:27]
	s_nop 0
	v_add_f32_dpp v15, v15, v15 quad_perm:[1,0,3,2] row_mask:0xf bank_mask:0xf bound_ctrl:1
	v_add_f32_e32 v25, v25, v32
	v_add_f32_e32 v25, v25, v33
	v_add_f32_dpp v15, v15, v15 quad_perm:[2,3,0,1] row_mask:0xf bank_mask:0xf bound_ctrl:1
	s_nop 1
	v_add_f32_dpp v15, v15, v15 row_half_mirror row_mask:0xf bank_mask:0xf bound_ctrl:1
	s_nop 1
	v_add_f32_dpp v15, v15, v15 row_mirror row_mask:0xf bank_mask:0xf bound_ctrl:1
	s_nop 0
	v_readlane_b32 s7, v15, 0
	v_readlane_b32 s5, v15, 16
	v_readlane_b32 s13, v15, 32
	v_readlane_b32 s9, v15, 48
	v_add_f32_dpp v15, v25, v25 quad_perm:[1,0,3,2] row_mask:0xf bank_mask:0xf bound_ctrl:1
	v_mov_b32_e32 v31, s5
	v_mov_b32_e32 v33, s9
	v_add_f32_dpp v15, v15, v15 quad_perm:[2,3,0,1] row_mask:0xf bank_mask:0xf bound_ctrl:1
	s_nop 1
	v_add_f32_dpp v15, v15, v15 row_half_mirror row_mask:0xf bank_mask:0xf bound_ctrl:1
	s_nop 1
	v_add_f32_dpp v15, v15, v15 row_mirror row_mask:0xf bank_mask:0xf bound_ctrl:1
	s_nop 0
	v_readlane_b32 s11, v15, 16
	v_readlane_b32 s14, v15, 48
	v_readlane_b32 s6, v15, 0
	v_readlane_b32 s12, v15, 32
	v_mov_b32_e32 v30, s11
	v_mov_b32_e32 v32, s14
	v_pk_add_f32 v[30:31], s[6:7], v[30:31]
	v_pk_add_f32 v[32:33], s[12:13], v[32:33]
	s_nop 0
	v_pk_add_f32 v[30:31], v[30:31], v[32:33]
	s_nop 0
	v_pk_mul_f32 v[30:31], v[30:31], s[20:21] op_sel_hi:[1,0]
	s_nop 0
	v_fma_f32 v15, -v31, v31, v30
	v_max_f32_e32 v15, 0, v15
	v_add_f32_e32 v15, 0x3727c5ac, v15
	v_cmp_gt_f32_e32 vcc, s18, v15
	v_mul_f32_e32 v25, 0x4b800000, v15
	s_nop 0
	v_cndmask_b32_e32 v15, v15, v25, vcc
	v_rsq_f32_e32 v15, v15
	s_nop 0
	v_mul_f32_e32 v25, 0x45800000, v15
	v_cndmask_b32_e32 v15, v15, v25, vcc
	v_sub_f32_e32 v25, v28, v31
	v_mul_f32_e32 v25, v25, v15
	v_fma_f32 v25, v77, v25, v78
	v_cvt_pk_bf16_f32 v25, v25, s0
	ds_write_b16 v114, v25 offset:192
	v_sub_f32_e32 v25, v29, v31
	v_mul_f32_e32 v25, v25, v15
	v_fma_f32 v25, v12, v25, v13
	v_cvt_pk_bf16_f32 v25, v25, s0
	ds_write_b16 v114, v25 offset:17088
	v_sub_f32_e32 v25, v26, v31
	v_mul_f32_e32 v25, v25, v15
	v_fma_f32 v25, v10, v25, v79
	v_cvt_pk_bf16_f32 v25, v25, s0
	ds_write_b16 v114, v25 offset:33984
	v_sub_f32_e32 v25, v27, v31
	v_mul_f32_e32 v15, v25, v15
	v_fma_f32 v15, v11, v15, v14
	v_cvt_pk_bf16_f32 v15, v15, s0
	v_lshlrev_b32_e32 v25, 16, v24
	v_lshlrev_b32_e32 v24, 16, v23
	ds_write_b16 v114, v15 offset:50880
	v_mul_f32_e32 v15, 0x3d372713, v24
	v_mul_f32_e32 v15, v15, v24
	v_mov_b32_e32 v23, v24
	v_fmac_f32_e32 v23, v15, v23
	v_mul_f32_e32 v15, 0x3f4c422a, v23
	v_add_f32_e32 v15, v15, v15
	v_mul_f32_e32 v15, 0xbfb8aa3b, v15
	v_exp_f32_e32 v26, v15
	v_mul_f32_e32 v15, 0x3d372713, v25
	v_mul_f32_e32 v15, v15, v25
	v_mov_b32_e32 v23, v25
	v_fmac_f32_e32 v23, v15, v23
	v_mul_f32_e32 v15, 0x3f4c422a, v23
	v_add_f32_e32 v15, v15, v15
	v_mul_f32_e32 v15, 0xbfb8aa3b, v15
	v_exp_f32_e32 v27, v15
	s_nop 0
	v_pk_add_f32 v[26:27], v[26:27], 1.0 op_sel_hi:[1,0]
	s_nop 0
	v_rcp_f32_e32 v27, v27
	v_lshlrev_b32_e32 v23, 16, v22
	v_lshlrev_b32_e32 v22, 16, v21
	v_mul_f32_e32 v21, 0x3d372713, v22
	v_mul_f32_e32 v21, v21, v22
	v_mov_b32_e32 v28, v22
	v_fmac_f32_e32 v28, v21, v28
	v_mul_f32_e32 v21, 0x3f4c422a, v28
	v_add_f32_e32 v21, v21, v21
	v_mul_f32_e32 v21, 0xbfb8aa3b, v21
	v_exp_f32_e32 v28, v21
	v_mul_f32_e32 v21, 0x3d372713, v23
	v_mul_f32_e32 v21, v21, v23
	v_mov_b32_e32 v29, v23
	v_fmac_f32_e32 v29, v21, v29
	v_mul_f32_e32 v21, 0x3f4c422a, v29
	v_add_f32_e32 v21, v21, v21
	v_mul_f32_e32 v21, 0xbfb8aa3b, v21
	v_exp_f32_e32 v29, v21
	v_rcp_f32_e32 v26, v26
	s_nop 0
	v_pk_mul_f32 v[24:25], v[26:27], v[24:25]
	v_pk_add_f32 v[28:29], v[28:29], 1.0 op_sel_hi:[1,0]
	s_nop 0
	v_add_f32_e32 v15, 0, v24
	v_add_f32_e32 v15, v15, v25
	v_pk_mul_f32 v[26:27], v[24:25], v[24:25]
	v_rcp_f32_e32 v29, v29
	v_rcp_f32_e32 v28, v28
	s_nop 0
	v_pk_mul_f32 v[22:23], v[28:29], v[22:23]
	v_add_f32_e32 v21, v26, v27
	v_add_f32_e32 v15, v15, v22
	v_add_f32_e32 v15, v15, v23
	v_pk_mul_f32 v[28:29], v[22:23], v[22:23]
	s_nop 0
	v_add_f32_dpp v15, v15, v15 quad_perm:[1,0,3,2] row_mask:0xf bank_mask:0xf bound_ctrl:1
	v_add_f32_e32 v21, v21, v28
	v_add_f32_e32 v21, v21, v29
	v_add_f32_dpp v15, v15, v15 quad_perm:[2,3,0,1] row_mask:0xf bank_mask:0xf bound_ctrl:1
	s_nop 1
	v_add_f32_dpp v15, v15, v15 row_half_mirror row_mask:0xf bank_mask:0xf bound_ctrl:1
	s_nop 1
	v_add_f32_dpp v15, v15, v15 row_mirror row_mask:0xf bank_mask:0xf bound_ctrl:1
	s_nop 0
	v_readlane_b32 s7, v15, 0
	v_readlane_b32 s5, v15, 16
	v_readlane_b32 s13, v15, 32
	v_readlane_b32 s9, v15, 48
	v_add_f32_dpp v15, v21, v21 quad_perm:[1,0,3,2] row_mask:0xf bank_mask:0xf bound_ctrl:1
	v_mov_b32_e32 v27, s5
	v_mov_b32_e32 v29, s9
	v_add_f32_dpp v15, v15, v15 quad_perm:[2,3,0,1] row_mask:0xf bank_mask:0xf bound_ctrl:1
	s_nop 1
	v_add_f32_dpp v15, v15, v15 row_half_mirror row_mask:0xf bank_mask:0xf bound_ctrl:1
	s_nop 1
	v_add_f32_dpp v15, v15, v15 row_mirror row_mask:0xf bank_mask:0xf bound_ctrl:1
	s_nop 0
	v_readlane_b32 s11, v15, 16
	v_readlane_b32 s14, v15, 48
	v_readlane_b32 s6, v15, 0
	v_readlane_b32 s12, v15, 32
	v_mov_b32_e32 v26, s11
	v_mov_b32_e32 v28, s14
	v_pk_add_f32 v[26:27], s[6:7], v[26:27]
	v_pk_add_f32 v[28:29], s[12:13], v[28:29]
	s_nop 0
	v_pk_add_f32 v[26:27], v[26:27], v[28:29]
	s_nop 0
	v_pk_mul_f32 v[26:27], v[26:27], s[20:21] op_sel_hi:[1,0]
	s_nop 0
	v_fma_f32 v15, -v27, v27, v26
	v_max_f32_e32 v15, 0, v15
	v_add_f32_e32 v15, 0x3727c5ac, v15
	v_cmp_gt_f32_e32 vcc, s18, v15
	v_mul_f32_e32 v21, 0x4b800000, v15
	s_nop 0
	v_cndmask_b32_e32 v15, v15, v21, vcc
	v_rsq_f32_e32 v15, v15
	s_nop 0
	v_mul_f32_e32 v21, 0x45800000, v15
	v_cndmask_b32_e32 v15, v15, v21, vcc
	v_sub_f32_e32 v21, v24, v27
	v_mul_f32_e32 v21, v21, v15
	v_fma_f32 v21, v77, v21, v78
	v_cvt_pk_bf16_f32 v21, v21, s0
	ds_write_b16 v114, v21 offset:208
	v_sub_f32_e32 v21, v25, v27
	v_mul_f32_e32 v21, v21, v15
	v_fma_f32 v21, v12, v21, v13
	v_cvt_pk_bf16_f32 v21, v21, s0
	ds_write_b16 v114, v21 offset:17104
	v_sub_f32_e32 v21, v22, v27
	v_mul_f32_e32 v21, v21, v15
	v_fma_f32 v21, v10, v21, v79
	v_cvt_pk_bf16_f32 v21, v21, s0
	ds_write_b16 v114, v21 offset:34000
	v_sub_f32_e32 v21, v23, v27
	v_mul_f32_e32 v15, v21, v15
	v_fma_f32 v15, v11, v15, v14
	v_cvt_pk_bf16_f32 v15, v15, s0
	v_lshlrev_b32_e32 v21, 16, v20
	v_lshlrev_b32_e32 v20, 16, v19
	ds_write_b16 v114, v15 offset:50896
	v_mul_f32_e32 v15, 0x3d372713, v20
	v_mul_f32_e32 v15, v15, v20
	v_mov_b32_e32 v19, v20
	v_fmac_f32_e32 v19, v15, v19
	v_mul_f32_e32 v15, 0x3f4c422a, v19
	v_add_f32_e32 v15, v15, v15
	v_mul_f32_e32 v15, 0xbfb8aa3b, v15
	v_exp_f32_e32 v22, v15
	v_mul_f32_e32 v15, 0x3d372713, v21
	v_mul_f32_e32 v15, v15, v21
	v_mov_b32_e32 v19, v21
	v_fmac_f32_e32 v19, v15, v19
	v_mul_f32_e32 v15, 0x3f4c422a, v19
	v_add_f32_e32 v15, v15, v15
	v_mul_f32_e32 v15, 0xbfb8aa3b, v15
	v_exp_f32_e32 v23, v15
	s_nop 0
	v_pk_add_f32 v[22:23], v[22:23], 1.0 op_sel_hi:[1,0]
	s_nop 0
	v_rcp_f32_e32 v23, v23
	v_lshlrev_b32_e32 v19, 16, v18
	v_lshlrev_b32_e32 v18, 16, v17
	v_mul_f32_e32 v17, 0x3d372713, v18
	v_mul_f32_e32 v17, v17, v18
	v_mov_b32_e32 v24, v18
	v_fmac_f32_e32 v24, v17, v24
	v_mul_f32_e32 v17, 0x3f4c422a, v24
	v_add_f32_e32 v17, v17, v17
	v_mul_f32_e32 v17, 0xbfb8aa3b, v17
	v_exp_f32_e32 v24, v17
	v_mul_f32_e32 v17, 0x3d372713, v19
	v_mul_f32_e32 v17, v17, v19
	v_mov_b32_e32 v25, v19
	v_fmac_f32_e32 v25, v17, v25
	v_mul_f32_e32 v17, 0x3f4c422a, v25
	v_add_f32_e32 v17, v17, v17
	v_mul_f32_e32 v17, 0xbfb8aa3b, v17
	v_exp_f32_e32 v25, v17
	v_rcp_f32_e32 v22, v22
	s_nop 0
	v_pk_mul_f32 v[20:21], v[22:23], v[20:21]
	v_pk_add_f32 v[24:25], v[24:25], 1.0 op_sel_hi:[1,0]
	s_nop 0
	v_add_f32_e32 v15, 0, v20
	v_add_f32_e32 v15, v15, v21
	v_pk_mul_f32 v[22:23], v[20:21], v[20:21]
	v_rcp_f32_e32 v25, v25
	v_rcp_f32_e32 v24, v24
	s_nop 0
	v_pk_mul_f32 v[18:19], v[24:25], v[18:19]
	v_add_f32_e32 v17, v22, v23
	v_add_f32_e32 v15, v15, v18
	v_add_f32_e32 v15, v15, v19
	v_pk_mul_f32 v[24:25], v[18:19], v[18:19]
	s_nop 0
	v_add_f32_dpp v15, v15, v15 quad_perm:[1,0,3,2] row_mask:0xf bank_mask:0xf bound_ctrl:1
	v_add_f32_e32 v17, v17, v24
	v_add_f32_e32 v17, v17, v25
	v_add_f32_dpp v15, v15, v15 quad_perm:[2,3,0,1] row_mask:0xf bank_mask:0xf bound_ctrl:1
	s_nop 1
	v_add_f32_dpp v15, v15, v15 row_half_mirror row_mask:0xf bank_mask:0xf bound_ctrl:1
	s_nop 1
	v_add_f32_dpp v15, v15, v15 row_mirror row_mask:0xf bank_mask:0xf bound_ctrl:1
	s_nop 0
	v_readlane_b32 s7, v15, 0
	v_readlane_b32 s5, v15, 16
	v_readlane_b32 s13, v15, 32
	v_readlane_b32 s9, v15, 48
	v_add_f32_dpp v15, v17, v17 quad_perm:[1,0,3,2] row_mask:0xf bank_mask:0xf bound_ctrl:1
	v_mov_b32_e32 v23, s5
	v_mov_b32_e32 v25, s9
	v_add_f32_dpp v15, v15, v15 quad_perm:[2,3,0,1] row_mask:0xf bank_mask:0xf bound_ctrl:1
	s_nop 1
	v_add_f32_dpp v15, v15, v15 row_half_mirror row_mask:0xf bank_mask:0xf bound_ctrl:1
	s_nop 1
	v_add_f32_dpp v15, v15, v15 row_mirror row_mask:0xf bank_mask:0xf bound_ctrl:1
	s_nop 0
	v_readlane_b32 s11, v15, 16
	v_readlane_b32 s14, v15, 48
	v_readlane_b32 s6, v15, 0
	v_readlane_b32 s12, v15, 32
	v_mov_b32_e32 v22, s11
	v_mov_b32_e32 v24, s14
	v_pk_add_f32 v[22:23], s[6:7], v[22:23]
	v_pk_add_f32 v[24:25], s[12:13], v[24:25]
	s_nop 0
	v_pk_add_f32 v[22:23], v[22:23], v[24:25]
	s_nop 0
	v_pk_mul_f32 v[22:23], v[22:23], s[20:21] op_sel_hi:[1,0]
	s_nop 0
	v_fma_f32 v15, -v23, v23, v22
	v_max_f32_e32 v15, 0, v15
	v_add_f32_e32 v15, 0x3727c5ac, v15
	v_cmp_gt_f32_e32 vcc, s18, v15
	v_mul_f32_e32 v17, 0x4b800000, v15
	s_nop 0
	v_cndmask_b32_e32 v15, v15, v17, vcc
	v_rsq_f32_e32 v15, v15
	s_nop 0
	v_mul_f32_e32 v17, 0x45800000, v15
	v_cndmask_b32_e32 v15, v15, v17, vcc
	v_sub_f32_e32 v17, v20, v23
	v_mul_f32_e32 v17, v17, v15
	v_fma_f32 v17, v77, v17, v78
	v_cvt_pk_bf16_f32 v17, v17, s0
	ds_write_b16 v114, v17 offset:224
	v_sub_f32_e32 v17, v21, v23
	v_mul_f32_e32 v17, v17, v15
	v_fma_f32 v17, v12, v17, v13
	v_cvt_pk_bf16_f32 v17, v17, s0
	ds_write_b16 v114, v17 offset:17120
	v_sub_f32_e32 v17, v18, v23
	v_mul_f32_e32 v17, v17, v15
	v_fma_f32 v17, v10, v17, v79
	v_cvt_pk_bf16_f32 v17, v17, s0
	ds_write_b16 v114, v17 offset:34016
	v_sub_f32_e32 v17, v19, v23
	v_mul_f32_e32 v15, v17, v15
	v_fma_f32 v15, v11, v15, v14
	v_lshlrev_b32_e32 v17, 16, v16
	v_lshlrev_b32_e32 v16, 16, v9
	v_cvt_pk_bf16_f32 v15, v15, s0
	v_mul_f32_e32 v9, 0x3d372713, v16
	ds_write_b16 v114, v15 offset:50912
	v_mul_f32_e32 v9, v9, v16
	v_mov_b32_e32 v15, v16
	v_fmac_f32_e32 v15, v9, v15
	v_mul_f32_e32 v9, 0x3f4c422a, v15
	v_add_f32_e32 v9, v9, v9
	v_mul_f32_e32 v9, 0xbfb8aa3b, v9
	v_exp_f32_e32 v18, v9
	v_mul_f32_e32 v9, 0x3d372713, v17
	v_mul_f32_e32 v9, v9, v17
	v_mov_b32_e32 v15, v17
	v_fmac_f32_e32 v15, v9, v15
	v_mul_f32_e32 v9, 0x3f4c422a, v15
	v_add_f32_e32 v9, v9, v9
	v_mul_f32_e32 v9, 0xbfb8aa3b, v9
	v_exp_f32_e32 v19, v9
	s_nop 0
	v_pk_add_f32 v[18:19], v[18:19], 1.0 op_sel_hi:[1,0]
	s_nop 0
	v_rcp_f32_e32 v19, v19
	v_lshlrev_b32_e32 v20, 16, v5
	v_mul_f32_e32 v5, 0x3d372713, v20
	v_lshlrev_b32_e32 v21, 16, v7
	v_mul_f32_e32 v5, v5, v20
	v_mov_b32_e32 v7, v20
	v_fmac_f32_e32 v7, v5, v7
	v_mul_f32_e32 v5, 0x3f4c422a, v7
	v_add_f32_e32 v5, v5, v5
	v_mul_f32_e32 v5, 0xbfb8aa3b, v5
	v_exp_f32_e32 v22, v5
	v_mul_f32_e32 v5, 0x3d372713, v21
	v_mul_f32_e32 v5, v5, v21
	v_mov_b32_e32 v7, v21
	v_fmac_f32_e32 v7, v5, v7
	v_mul_f32_e32 v5, 0x3f4c422a, v7
	v_add_f32_e32 v5, v5, v5
	v_mul_f32_e32 v5, 0xbfb8aa3b, v5
	v_exp_f32_e32 v23, v5
	v_rcp_f32_e32 v18, v18
	s_nop 0
	v_pk_mul_f32 v[16:17], v[18:19], v[16:17]
	v_pk_add_f32 v[22:23], v[22:23], 1.0 op_sel_hi:[1,0]
	s_nop 0
	v_add_f32_e32 v9, 0, v16
	v_add_f32_e32 v9, v9, v17
	v_pk_mul_f32 v[18:19], v[16:17], v[16:17]
	v_rcp_f32_e32 v23, v23
	v_rcp_f32_e32 v22, v22
	s_nop 0
	v_pk_mul_f32 v[20:21], v[22:23], v[20:21]
	v_add_f32_e32 v7, v18, v19
	v_add_f32_e32 v5, v9, v20
	v_add_f32_e32 v5, v5, v21
	v_pk_mul_f32 v[22:23], v[20:21], v[20:21]
	s_nop 0
	v_add_f32_dpp v5, v5, v5 quad_perm:[1,0,3,2] row_mask:0xf bank_mask:0xf bound_ctrl:1
	v_add_f32_e32 v7, v7, v22
	v_add_f32_e32 v7, v7, v23
	v_add_f32_dpp v5, v5, v5 quad_perm:[2,3,0,1] row_mask:0xf bank_mask:0xf bound_ctrl:1
	s_nop 1
	v_add_f32_dpp v5, v5, v5 row_half_mirror row_mask:0xf bank_mask:0xf bound_ctrl:1
	s_nop 1
	v_add_f32_dpp v5, v5, v5 row_mirror row_mask:0xf bank_mask:0xf bound_ctrl:1
	s_nop 0
	v_readlane_b32 s7, v5, 0
	v_readlane_b32 s5, v5, 16
	v_readlane_b32 s13, v5, 32
	v_readlane_b32 s9, v5, 48
	v_add_f32_dpp v5, v7, v7 quad_perm:[1,0,3,2] row_mask:0xf bank_mask:0xf bound_ctrl:1
	v_mov_b32_e32 v19, s5
	v_mov_b32_e32 v23, s9
	v_add_f32_dpp v5, v5, v5 quad_perm:[2,3,0,1] row_mask:0xf bank_mask:0xf bound_ctrl:1
	s_nop 1
	v_add_f32_dpp v5, v5, v5 row_half_mirror row_mask:0xf bank_mask:0xf bound_ctrl:1
	s_nop 1
	v_add_f32_dpp v5, v5, v5 row_mirror row_mask:0xf bank_mask:0xf bound_ctrl:1
	s_nop 0
	v_readlane_b32 s11, v5, 16
	v_readlane_b32 s14, v5, 48
	v_readlane_b32 s6, v5, 0
	v_readlane_b32 s12, v5, 32
	v_mov_b32_e32 v18, s11
	v_mov_b32_e32 v22, s14
	v_pk_add_f32 v[18:19], s[6:7], v[18:19]
	v_pk_add_f32 v[22:23], s[12:13], v[22:23]
	s_nop 0
	v_pk_add_f32 v[18:19], v[18:19], v[22:23]
	s_nop 0
	v_pk_mul_f32 v[18:19], v[18:19], s[20:21] op_sel_hi:[1,0]
	s_nop 0
	v_fma_f32 v5, -v19, v19, v18
	v_max_f32_e32 v5, 0, v5
	v_add_f32_e32 v5, 0x3727c5ac, v5
	v_cmp_gt_f32_e32 vcc, s18, v5
	v_mul_f32_e32 v7, 0x4b800000, v5
	s_nop 0
	v_cndmask_b32_e32 v5, v5, v7, vcc
	v_rsq_f32_e32 v5, v5
	s_nop 0
	v_mul_f32_e32 v7, 0x45800000, v5
	v_cndmask_b32_e32 v5, v5, v7, vcc
	v_sub_f32_e32 v7, v16, v19
	v_mul_f32_e32 v7, v7, v5
	v_fmac_f32_e32 v78, v77, v7
	v_cvt_pk_bf16_f32 v7, v78, s0
	ds_write_b16 v114, v7 offset:240
	v_sub_f32_e32 v7, v17, v19
	v_mul_f32_e32 v7, v7, v5
	v_fmac_f32_e32 v13, v12, v7
	v_cvt_pk_bf16_f32 v7, v13, s0
	ds_write_b16 v114, v7 offset:17136
	v_sub_f32_e32 v7, v20, v19
	v_mul_f32_e32 v7, v7, v5
	v_fmac_f32_e32 v79, v10, v7
	v_cvt_pk_bf16_f32 v7, v79, s0
	ds_write_b16 v114, v7 offset:34032
	v_sub_f32_e32 v7, v21, v19
	v_mul_f32_e32 v5, v7, v5
	v_fmac_f32_e32 v14, v11, v5
	v_cvt_pk_bf16_f32 v5, v14, s0
	ds_write_b16 v114, v5 offset:50928
	v_add_u32_e32 v114, 0x100, v114
	s_cbranch_scc1 .LBB0_603
.LBB0_604:
	v_readlane_b32 s4, v255, 29
	s_add_u32 s4, s0, s4
	v_or_b32_e32 v82, s10, v37
	s_addc_u32 s5, s1, 0
	v_lshlrev_b32_e32 v194, 4, v47
	v_or_b32_e32 v2, s3, v82
	v_lshl_add_u64 v[0:1], s[4:5], 0, v[194:195]
	s_mov_b64 s[4:5], 0x90a0000
	v_ashrrev_i32_e32 v3, 31, v2
	v_lshl_add_u64 v[76:77], v[0:1], 0, s[4:5]
	v_lshlrev_b64 v[2:3], 8, v[2:3]
	v_mov_b32_e32 v0, v192
	v_mov_b32_e32 v6, v192
	v_mov_b32_e32 v10, v192
	v_mov_b32_e32 v14, v192
	v_mov_b32_e32 v18, v192
	v_mov_b32_e32 v22, v192
	v_mov_b32_e32 v26, v192
	v_mov_b32_e32 v30, v192
	v_lshl_add_u64 v[2:3], v[76:77], 0, v[2:3]
	s_waitcnt vmcnt(0) lgkmcnt(0)
	s_barrier
	global_load_dwordx4 v[32:35], v[2:3], off
	v_or_b32_e32 v4, s2, v82
	v_ashrrev_i32_e32 v5, 31, v4
	v_lshlrev_b64 v[4:5], 8, v[4:5]
	v_lshl_add_u64 v[4:5], v[76:77], 0, v[4:5]
	global_load_dwordx4 v[78:81], v[4:5], off
	global_load_dwordx4 v[90:93], v[2:3], off offset:64
	v_or_b32_e32 v1, s8, v37
	s_movk_i32 s4, 0x108
	v_and_b32_e32 v2, 48, v57
	v_mul_lo_u32 v1, v1, s4
	v_add3_u32 v57, 0, v2, v1
	ds_read2_b64 v[86:89], v57 offset1:1
	v_mov_b32_e32 v1, v0
	v_add_u32_e32 v83, 0x1080, v57
	v_mov_b32_e32 v2, v0
	v_mov_b32_e32 v3, v0
	v_add_u32_e32 v84, 0x2100, v57
	v_add_u32_e32 v85, 0x3180, v57
	ds_read2_b64 v[94:97], v83 offset1:1
	ds_read2_b64 v[98:101], v84 offset1:1
	v_mov_b32_e32 v7, v6
	v_mov_b32_e32 v8, v6
	v_mov_b32_e32 v9, v6
	v_mov_b32_e32 v11, v10
	v_mov_b32_e32 v12, v10
	v_mov_b32_e32 v13, v10
	v_mov_b32_e32 v15, v14
	v_mov_b32_e32 v16, v14
	v_mov_b32_e32 v17, v14
	v_mov_b32_e32 v19, v18
	v_mov_b32_e32 v20, v18
	v_mov_b32_e32 v21, v18
	v_mov_b32_e32 v23, v22
	v_mov_b32_e32 v24, v22
	v_mov_b32_e32 v25, v22
	v_mov_b32_e32 v27, v26
	v_mov_b32_e32 v28, v26
	v_mov_b32_e32 v29, v26
	v_mov_b32_e32 v31, v30
	v_readlane_b32 s4, v253, 36
	s_waitcnt vmcnt(0) lgkmcnt(0)
	v_mfma_f32_16x16x32_bf16 v[110:113], v[86:89], v[78:81], v[18:21]
	v_or_b32_e32 v37, s4, v37
	s_mov_b64 s[4:5], 0x2040600
	v_mfma_f32_16x16x32_bf16 v[102:105], v[86:89], v[32:35], v[0:3]
	v_add_u32_e32 v86, 0x10c0, v57
	v_add_u32_e32 v87, 0x2140, v57
	v_add_u32_e32 v88, 0x31c0, v57
	ds_read2_b64 v[0:3], v85 offset1:1
	v_mfma_f32_16x16x32_bf16 v[6:9], v[94:97], v[32:35], v[6:9]
	ds_read2_b64 v[114:117], v87 offset1:1
	v_mfma_f32_16x16x32_bf16 v[10:13], v[98:101], v[32:35], v[10:13]
	s_waitcnt lgkmcnt(1)
	v_mfma_f32_16x16x32_bf16 v[14:17], v[0:3], v[32:35], v[14:17]
	v_mov_b32_e32 v32, v30
	v_mov_b32_e32 v33, v30
	v_mfma_f32_16x16x32_bf16 v[94:97], v[94:97], v[78:81], v[22:25]
	v_mfma_f32_16x16x32_bf16 v[98:101], v[98:101], v[78:81], v[26:29]
	v_mfma_f32_16x16x32_bf16 v[0:3], v[0:3], v[78:81], v[30:33]
	ds_read2_b64 v[78:81], v57 offset0:8 offset1:9
	s_waitcnt lgkmcnt(0)
	v_mfma_f32_16x16x32_bf16 v[28:31], v[78:81], v[90:93], v[102:105]
	s_nop 2
	ds_read2_b64 v[102:105], v86 offset1:1
	ds_read2_b64 v[32:35], v88 offset1:1
	s_waitcnt lgkmcnt(1)
	v_mfma_f32_16x16x32_bf16 v[24:27], v[102:105], v[90:93], v[6:9]
	v_mfma_f32_16x16x32_bf16 v[20:23], v[114:117], v[90:93], v[10:13]
	s_waitcnt lgkmcnt(0)
	v_mfma_f32_16x16x32_bf16 v[12:15], v[32:35], v[90:93], v[14:17]
	global_load_dwordx4 v[90:93], v[4:5], off offset:64
	v_lshlrev_b32_e32 v4, 2, v47
	s_waitcnt vmcnt(0) lgkmcnt(0)
	v_mfma_f32_16x16x32_bf16 v[8:11], v[102:105], v[90:93], v[94:97]
	s_nop 2
	v_lshlrev_b32_e32 v94, 16, v74
	v_mul_f32_e32 v47, 0x3d372713, v94
	v_mul_f32_e32 v47, v47, v94
	v_mov_b32_e32 v67, v94
	v_fmac_f32_e32 v67, v47, v67
	v_mul_f32_e32 v47, 0x3f4c422a, v67
	v_add_f32_e32 v47, v47, v47
	v_and_b32_e32 v95, 0xffff0000, v74
	v_mul_f32_e32 v47, 0xbfb8aa3b, v47
	v_mfma_f32_16x16x32_bf16 v[16:19], v[78:81], v[90:93], v[110:113]
	v_exp_f32_e32 v80, v47
	v_mul_f32_e32 v47, 0x3d372713, v95
	v_mul_f32_e32 v47, v47, v95
	v_mov_b32_e32 v67, v95
	v_fmac_f32_e32 v67, v47, v67
	v_mul_f32_e32 v47, 0x3f4c422a, v67
	v_add_f32_e32 v47, v47, v47
	v_mul_f32_e32 v47, 0xbfb8aa3b, v47
	v_exp_f32_e32 v81, v47
	v_mfma_f32_16x16x32_bf16 v[0:3], v[32:35], v[90:93], v[0:3]
	v_mov_b64_e32 v[32:33], s[0:1]
	v_or_b32_e32 v47, s3, v37
	v_pk_add_f32 v[34:35], v[80:81], 1.0 op_sel_hi:[1,0]
	v_mad_i64_i32 v[80:81], s[0:1], v47, s86, v[32:33]
	v_or_b32_e32 v78, s8, v4
	v_mfma_f32_16x16x32_bf16 v[4:7], v[114:117], v[90:93], v[98:101]
	v_lshl_add_u64 v[80:81], v[80:81], 0, s[4:5]
	v_rcp_f32_e32 v35, v35
	v_pk_add_f32 v[16:17], v[56:57], v[16:17] op_sel_hi:[0,1]
	v_lshlrev_b32_e32 v74, 16, v75
	v_mul_f32_e32 v67, 0x3d372713, v74
	v_mul_f32_e32 v67, v67, v74
	v_mov_b32_e32 v90, v74
	v_fmac_f32_e32 v90, v67, v90
	v_mul_f32_e32 v67, 0x3f4c422a, v90
	v_add_f32_e32 v67, v67, v67
	v_and_b32_e32 v75, 0xffff0000, v75
	v_mul_f32_e32 v67, 0xbfb8aa3b, v67
	v_exp_f32_e32 v90, v67
	v_mul_f32_e32 v67, 0x3d372713, v75
	v_mul_f32_e32 v67, v67, v75
	v_mov_b32_e32 v91, v75
	v_fmac_f32_e32 v91, v67, v91
	v_mul_f32_e32 v67, 0x3f4c422a, v91
	v_add_f32_e32 v67, v67, v67
	v_mul_f32_e32 v67, 0xbfb8aa3b, v67
	v_exp_f32_e32 v91, v67
	v_rcp_f32_e32 v34, v34
	s_nop 0
	v_pk_mul_f32 v[34:35], v[34:35], v[94:95]
	v_pk_add_f32 v[90:91], v[90:91], 1.0 op_sel_hi:[1,0]
	v_pk_add_f32 v[18:19], v[56:57], v[18:19] op_sel_hi:[0,1]
	v_pk_add_f32 v[8:9], v[56:57], v[8:9] op_sel_hi:[0,1]
	v_pk_add_f32 v[10:11], v[56:57], v[10:11] op_sel_hi:[0,1]
	v_pk_add_f32 v[4:5], v[56:57], v[4:5] op_sel_hi:[0,1]
	v_pk_add_f32 v[28:29], v[66:67], v[28:29] op_sel_hi:[0,1]
	v_pk_mul_f32 v[28:29], v[34:35], v[28:29]
	v_rcp_f32_e32 v35, v91
	v_pk_add_f32 v[6:7], v[56:57], v[6:7] op_sel_hi:[0,1]
	v_rcp_f32_e32 v34, v90
	s_nop 0
	v_pk_mul_f32 v[34:35], v[34:35], v[74:75]
	v_pk_add_f32 v[30:31], v[66:67], v[30:31] op_sel_hi:[0,1]
	v_pk_mul_f32 v[30:31], v[34:35], v[30:31]
	v_lshlrev_b32_e32 v34, 16, v72
	v_mul_f32_e32 v47, 0x3d372713, v34
	v_mul_f32_e32 v47, v47, v34
	v_mov_b32_e32 v67, v34
	v_fmac_f32_e32 v67, v47, v67
	v_mul_f32_e32 v47, 0x3f4c422a, v67
	v_add_f32_e32 v47, v47, v47
	v_and_b32_e32 v35, 0xffff0000, v72
	v_mul_f32_e32 v47, 0xbfb8aa3b, v47
	v_exp_f32_e32 v74, v47
	v_mul_f32_e32 v47, 0x3d372713, v35
	v_mul_f32_e32 v47, v47, v35
	v_mov_b32_e32 v67, v35
	v_fmac_f32_e32 v67, v47, v67
	v_mul_f32_e32 v47, 0x3f4c422a, v67
	v_add_f32_e32 v47, v47, v47
	v_mul_f32_e32 v47, 0xbfb8aa3b, v47
	v_exp_f32_e32 v75, v47
	v_cvt_pk_bf16_f32 v91, v30, v31
	v_ashrrev_i32_e32 v79, 31, v78
	v_cvt_pk_bf16_f32 v90, v28, v29
	v_pk_add_f32 v[30:31], v[74:75], 1.0 op_sel_hi:[1,0]
	v_lshlrev_b64 v[28:29], 1, v[78:79]
	v_lshl_add_u64 v[74:75], v[80:81], 0, v[28:29]
	global_store_dwordx2 v[74:75], v[90:91], off
	v_pk_add_f32 v[0:1], v[56:57], v[0:1] op_sel_hi:[0,1]
	v_rcp_f32_e32 v31, v31
	v_pk_add_f32 v[2:3], v[56:57], v[2:3] op_sel_hi:[0,1]
	v_lshlrev_b32_e32 v72, 16, v73
	v_mul_f32_e32 v74, 0x3d372713, v72
	v_mul_f32_e32 v74, v74, v72
	v_mov_b32_e32 v75, v72
	v_and_b32_e32 v73, 0xffff0000, v73
	v_fmac_f32_e32 v75, v74, v75
	v_mul_f32_e32 v74, 0x3f4c422a, v75
	v_mul_f32_e32 v75, 0x3d372713, v73
	v_mul_f32_e32 v75, v75, v73
	v_mov_b32_e32 v89, v73
	v_fmac_f32_e32 v89, v75, v89
	v_mul_f32_e32 v75, 0x3f4c422a, v89
	v_add_f32_e32 v74, v74, v74
	v_add_f32_e32 v75, v75, v75
	v_mul_f32_e32 v74, 0xbfb8aa3b, v74
	v_mul_f32_e32 v75, 0xbfb8aa3b, v75
	v_exp_f32_e32 v74, v74
	v_exp_f32_e32 v75, v75
	v_rcp_f32_e32 v30, v30
	s_nop 0
	v_pk_mul_f32 v[30:31], v[30:31], v[34:35]
	v_pk_add_f32 v[74:75], v[74:75], 1.0 op_sel_hi:[1,0]
	s_nop 0
	v_pk_add_f32 v[24:25], v[66:67], v[24:25] op_sel_hi:[0,1]
	v_pk_mul_f32 v[24:25], v[30:31], v[24:25]
	v_rcp_f32_e32 v31, v75
	v_rcp_f32_e32 v30, v74
	s_nop 0
	v_pk_mul_f32 v[30:31], v[30:31], v[72:73]
	v_pk_add_f32 v[26:27], v[66:67], v[26:27] op_sel_hi:[0,1]
	v_lshlrev_b32_e32 v34, 16, v70
	v_pk_mul_f32 v[26:27], v[30:31], v[26:27]
	v_mul_f32_e32 v31, 0x3d372713, v34
	v_mul_f32_e32 v31, v31, v34
	v_mov_b32_e32 v47, v34
	v_fmac_f32_e32 v47, v31, v47
	v_mul_f32_e32 v31, 0x3f4c422a, v47
	v_add_f32_e32 v31, v31, v31
	v_and_b32_e32 v35, 0xffff0000, v70
	v_mul_f32_e32 v31, 0xbfb8aa3b, v31
	v_exp_f32_e32 v72, v31
	v_mul_f32_e32 v31, 0x3d372713, v35
	v_mul_f32_e32 v31, v31, v35
	v_mov_b32_e32 v47, v35
	v_fmac_f32_e32 v47, v31, v47
	v_mul_f32_e32 v31, 0x3f4c422a, v47
	v_add_f32_e32 v31, v31, v31
	v_mul_f32_e32 v31, 0xbfb8aa3b, v31
	v_exp_f32_e32 v73, v31
	v_cvt_pk_bf16_f32 v24, v24, v25
	v_cvt_pk_bf16_f32 v25, v26, v27
	v_or_b32_e32 v30, 16, v78
	v_pk_add_f32 v[26:27], v[72:73], 1.0 op_sel_hi:[1,0]
	v_ashrrev_i32_e32 v31, 31, v30
	v_lshlrev_b64 v[30:31], 1, v[30:31]
	v_lshl_add_u64 v[72:73], v[80:81], 0, v[30:31]
	global_store_dwordx2 v[72:73], v[24:25], off
	v_rcp_f32_e32 v25, v27
	v_lshlrev_b32_e32 v70, 16, v71
	v_mul_f32_e32 v47, 0x3d372713, v70
	v_mul_f32_e32 v47, v47, v70
	v_mov_b32_e32 v67, v70
	v_fmac_f32_e32 v67, v47, v67
	v_mul_f32_e32 v47, 0x3f4c422a, v67
	v_add_f32_e32 v47, v47, v47
	v_and_b32_e32 v71, 0xffff0000, v71
	v_mul_f32_e32 v47, 0xbfb8aa3b, v47
	v_exp_f32_e32 v72, v47
	v_mul_f32_e32 v47, 0x3d372713, v71
	v_mul_f32_e32 v47, v47, v71
	v_mov_b32_e32 v67, v71
	v_fmac_f32_e32 v67, v47, v67
	v_mul_f32_e32 v47, 0x3f4c422a, v67
	v_add_f32_e32 v47, v47, v47
	v_mul_f32_e32 v47, 0xbfb8aa3b, v47
	v_exp_f32_e32 v73, v47
	v_rcp_f32_e32 v24, v26
	s_nop 0
	v_pk_mul_f32 v[24:25], v[24:25], v[34:35]
	v_pk_add_f32 v[26:27], v[72:73], 1.0 op_sel_hi:[1,0]
	s_nop 0
	v_pk_add_f32 v[20:21], v[66:67], v[20:21] op_sel_hi:[0,1]
	v_pk_mul_f32 v[20:21], v[24:25], v[20:21]
	v_rcp_f32_e32 v25, v27
	v_rcp_f32_e32 v24, v26
	s_nop 0
	v_pk_mul_f32 v[24:25], v[24:25], v[70:71]
	v_pk_add_f32 v[22:23], v[66:67], v[22:23] op_sel_hi:[0,1]
	v_lshlrev_b32_e32 v26, 16, v68
	v_pk_mul_f32 v[22:23], v[24:25], v[22:23]
	v_mul_f32_e32 v25, 0x3d372713, v26
	v_mul_f32_e32 v25, v25, v26
	v_mov_b32_e32 v34, v26
	v_fmac_f32_e32 v34, v25, v34
	v_mul_f32_e32 v25, 0x3f4c422a, v34
	v_add_f32_e32 v25, v25, v25
	v_and_b32_e32 v27, 0xffff0000, v68
	v_mul_f32_e32 v25, 0xbfb8aa3b, v25
	v_exp_f32_e32 v34, v25
	v_mul_f32_e32 v25, 0x3d372713, v27
	v_mul_f32_e32 v25, v25, v27
	v_mov_b32_e32 v35, v27
	v_fmac_f32_e32 v35, v25, v35
	v_mul_f32_e32 v25, 0x3f4c422a, v35
	v_add_f32_e32 v25, v25, v25
	v_mul_f32_e32 v25, 0xbfb8aa3b, v25
	v_exp_f32_e32 v35, v25
	v_cvt_pk_bf16_f32 v20, v20, v21
	v_cvt_pk_bf16_f32 v21, v22, v23
	v_or_b32_e32 v24, 32, v78
	v_pk_add_f32 v[22:23], v[34:35], 1.0 op_sel_hi:[1,0]
	v_ashrrev_i32_e32 v25, 31, v24
	v_lshlrev_b64 v[34:35], 1, v[24:25]
	v_lshl_add_u64 v[24:25], v[80:81], 0, v[34:35]
	global_store_dwordx2 v[24:25], v[20:21], off
	v_rcp_f32_e32 v21, v23
	v_lshlrev_b32_e32 v24, 16, v69
	v_mul_f32_e32 v67, 0x3d372713, v24
	v_mul_f32_e32 v67, v67, v24
	v_mov_b32_e32 v68, v24
	v_fmac_f32_e32 v68, v67, v68
	v_mul_f32_e32 v67, 0x3f4c422a, v68
	v_add_f32_e32 v67, v67, v67
	v_and_b32_e32 v25, 0xffff0000, v69
	v_mul_f32_e32 v67, 0xbfb8aa3b, v67
	v_exp_f32_e32 v68, v67
	v_mul_f32_e32 v67, 0x3d372713, v25
	v_mul_f32_e32 v67, v67, v25
	v_mov_b32_e32 v69, v25
	v_fmac_f32_e32 v69, v67, v69
	v_mul_f32_e32 v67, 0x3f4c422a, v69
	v_add_f32_e32 v67, v67, v67
	v_mul_f32_e32 v67, 0xbfb8aa3b, v67
	v_exp_f32_e32 v69, v67
	v_rcp_f32_e32 v20, v22
	s_nop 0
	v_pk_mul_f32 v[20:21], v[20:21], v[26:27]
	v_pk_add_f32 v[22:23], v[68:69], 1.0 op_sel_hi:[1,0]
	s_nop 0
	v_pk_add_f32 v[12:13], v[66:67], v[12:13] op_sel_hi:[0,1]
	v_pk_mul_f32 v[12:13], v[20:21], v[12:13]
	v_rcp_f32_e32 v21, v23
	v_rcp_f32_e32 v20, v22
	s_nop 0
	v_pk_mul_f32 v[20:21], v[20:21], v[24:25]
	v_pk_add_f32 v[14:15], v[66:67], v[14:15] op_sel_hi:[0,1]
	v_pk_mul_f32 v[14:15], v[20:21], v[14:15]
	v_or_b32_e32 v20, 48, v78
	v_cvt_pk_bf16_f32 v12, v12, v13
	v_cvt_pk_bf16_f32 v13, v14, v15
	v_ashrrev_i32_e32 v21, 31, v20
	v_lshlrev_b32_e32 v14, 16, v64
	v_lshlrev_b64 v[66:67], 1, v[20:21]
	v_mul_f32_e32 v20, 0x3d372713, v14
	v_mul_f32_e32 v20, v20, v14
	v_mov_b32_e32 v21, v14
	v_and_b32_e32 v15, 0xffff0000, v64
	v_fmac_f32_e32 v21, v20, v21
	v_mul_f32_e32 v20, 0x3f4c422a, v21
	v_mul_f32_e32 v21, 0x3d372713, v15
	v_mul_f32_e32 v21, v21, v15
	v_mov_b32_e32 v22, v15
	v_fmac_f32_e32 v22, v21, v22
	v_mul_f32_e32 v21, 0x3f4c422a, v22
	v_add_f32_e32 v20, v20, v20
	v_add_f32_e32 v21, v21, v21
	v_mul_f32_e32 v20, 0xbfb8aa3b, v20
	v_mul_f32_e32 v21, 0xbfb8aa3b, v21
	v_exp_f32_e32 v20, v20
	v_exp_f32_e32 v21, v21
	v_lshl_add_u64 v[22:23], v[80:81], 0, v[66:67]
	global_store_dwordx2 v[22:23], v[12:13], off
	v_or_b32_e32 v12, s2, v37
	v_pk_add_f32 v[20:21], v[20:21], 1.0 op_sel_hi:[1,0]
	v_mad_i64_i32 v[12:13], s[0:1], v12, s86, v[32:33]
	v_lshl_add_u64 v[12:13], v[12:13], 0, s[4:5]
	v_or_b32_e32 v37, 64, v37
	v_rcp_f32_e32 v21, v21
	v_lshlrev_b32_e32 v22, 16, v65
	v_mul_f32_e32 v24, 0x3d372713, v22
	v_mul_f32_e32 v24, v24, v22
	v_mov_b32_e32 v25, v22
	v_and_b32_e32 v23, 0xffff0000, v65
	v_fmac_f32_e32 v25, v24, v25
	v_mul_f32_e32 v24, 0x3f4c422a, v25
	v_mul_f32_e32 v25, 0x3d372713, v23
	v_mul_f32_e32 v25, v25, v23
	v_mov_b32_e32 v64, v23
	v_fmac_f32_e32 v64, v25, v64
	v_mul_f32_e32 v25, 0x3f4c422a, v64
	v_add_f32_e32 v24, v24, v24
	v_add_f32_e32 v25, v25, v25
	v_mul_f32_e32 v24, 0xbfb8aa3b, v24
	v_mul_f32_e32 v25, 0xbfb8aa3b, v25
	v_exp_f32_e32 v24, v24
	v_exp_f32_e32 v25, v25
	v_rcp_f32_e32 v20, v20
	s_nop 0
	v_pk_mul_f32 v[14:15], v[20:21], v[14:15]
	v_pk_add_f32 v[24:25], v[24:25], 1.0 op_sel_hi:[1,0]
	v_pk_mul_f32 v[14:15], v[14:15], v[16:17]
	s_nop 0
	v_cvt_pk_bf16_f32 v14, v14, v15
	v_add_u32_e32 v47, 0x1100, v57
	v_rcp_f32_e32 v17, v25
	v_rcp_f32_e32 v16, v24
	v_lshlrev_b32_e32 v20, 16, v62
	v_pk_mul_f32 v[16:17], v[16:17], v[22:23]
	v_mul_f32_e32 v22, 0x3d372713, v20
	v_mul_f32_e32 v22, v22, v20
	v_mov_b32_e32 v23, v20
	v_and_b32_e32 v21, 0xffff0000, v62
	v_fmac_f32_e32 v23, v22, v23
	v_mul_f32_e32 v22, 0x3f4c422a, v23
	v_mul_f32_e32 v23, 0x3d372713, v21
	v_mul_f32_e32 v23, v23, v21
	v_mov_b32_e32 v24, v21
	v_fmac_f32_e32 v24, v23, v24
	v_mul_f32_e32 v23, 0x3f4c422a, v24
	v_add_f32_e32 v22, v22, v22
	v_add_f32_e32 v23, v23, v23
	v_mul_f32_e32 v22, 0xbfb8aa3b, v22
	v_mul_f32_e32 v23, 0xbfb8aa3b, v23
	v_exp_f32_e32 v22, v22
	v_exp_f32_e32 v23, v23
	v_pk_mul_f32 v[16:17], v[16:17], v[18:19]
	v_mov_b32_e32 v62, v195
	v_cvt_pk_bf16_f32 v15, v16, v17
	v_pk_add_f32 v[18:19], v[22:23], 1.0 op_sel_hi:[1,0]
	v_lshl_add_u64 v[16:17], v[12:13], 0, v[28:29]
	global_store_dwordx2 v[16:17], v[14:15], off
	v_rcp_f32_e32 v15, v19
	v_lshlrev_b32_e32 v16, 16, v63
	v_mul_f32_e32 v22, 0x3d372713, v16
	v_mul_f32_e32 v22, v22, v16
	v_mov_b32_e32 v23, v16
	v_and_b32_e32 v17, 0xffff0000, v63
	v_fmac_f32_e32 v23, v22, v23
	v_mul_f32_e32 v22, 0x3f4c422a, v23
	v_mul_f32_e32 v23, 0x3d372713, v17
	v_mul_f32_e32 v23, v23, v17
	v_mov_b32_e32 v25, v17
	v_fmac_f32_e32 v25, v23, v25
	v_mul_f32_e32 v23, 0x3f4c422a, v25
	v_add_f32_e32 v22, v22, v22
	v_add_f32_e32 v23, v23, v23
	v_mul_f32_e32 v22, 0xbfb8aa3b, v22
	v_mul_f32_e32 v23, 0xbfb8aa3b, v23
	v_exp_f32_e32 v22, v22
	v_exp_f32_e32 v23, v23
	v_rcp_f32_e32 v14, v18
	s_nop 0
	v_pk_mul_f32 v[14:15], v[14:15], v[20:21]
	v_pk_add_f32 v[18:19], v[22:23], 1.0 op_sel_hi:[1,0]
	v_pk_mul_f32 v[8:9], v[14:15], v[8:9]
	s_nop 0
	v_cvt_pk_bf16_f32 v8, v8, v9
	v_mov_b32_e32 v24, v192
	v_rcp_f32_e32 v15, v19
	v_rcp_f32_e32 v14, v18
	s_nop 0
	v_pk_mul_f32 v[14:15], v[14:15], v[16:17]
	v_lshlrev_b32_e32 v16, 16, v60
	v_mul_f32_e32 v18, 0x3d372713, v16
	v_mul_f32_e32 v18, v18, v16
	v_mov_b32_e32 v19, v16
	v_and_b32_e32 v17, 0xffff0000, v60
	v_fmac_f32_e32 v19, v18, v19
	v_mul_f32_e32 v18, 0x3f4c422a, v19
	v_mul_f32_e32 v19, 0x3d372713, v17
	v_mul_f32_e32 v19, v19, v17
	v_mov_b32_e32 v20, v17
	v_fmac_f32_e32 v20, v19, v20
	v_mul_f32_e32 v19, 0x3f4c422a, v20
	v_add_f32_e32 v18, v18, v18
	v_add_f32_e32 v19, v19, v19
	v_mul_f32_e32 v18, 0xbfb8aa3b, v18
	v_mul_f32_e32 v19, 0xbfb8aa3b, v19
	v_exp_f32_e32 v18, v18
	v_exp_f32_e32 v19, v19
	v_pk_mul_f32 v[10:11], v[14:15], v[10:11]
	v_pk_add_f32 v[14:15], v[18:19], 1.0 op_sel_hi:[1,0]
	s_nop 0
	v_cvt_pk_bf16_f32 v9, v10, v11
	v_lshl_add_u64 v[10:11], v[12:13], 0, v[30:31]
	global_store_dwordx2 v[10:11], v[8:9], off
	v_rcp_f32_e32 v9, v15
	v_lshlrev_b32_e32 v10, 16, v61
	v_mul_f32_e32 v18, 0x3d372713, v10
	v_mul_f32_e32 v18, v18, v10
	v_mov_b32_e32 v19, v10
	v_and_b32_e32 v11, 0xffff0000, v61
	v_fmac_f32_e32 v19, v18, v19
	v_mul_f32_e32 v18, 0x3f4c422a, v19
	v_mul_f32_e32 v19, 0x3d372713, v11
	v_mul_f32_e32 v19, v19, v11
	v_mov_b32_e32 v21, v11
	v_fmac_f32_e32 v21, v19, v21
	v_mul_f32_e32 v19, 0x3f4c422a, v21
	v_add_f32_e32 v18, v18, v18
	v_add_f32_e32 v19, v19, v19
	v_mul_f32_e32 v18, 0xbfb8aa3b, v18
	v_mul_f32_e32 v19, 0xbfb8aa3b, v19
	v_exp_f32_e32 v18, v18
	v_exp_f32_e32 v19, v19
	v_rcp_f32_e32 v8, v14
	s_nop 0
	v_pk_mul_f32 v[8:9], v[8:9], v[16:17]
	v_pk_add_f32 v[14:15], v[18:19], 1.0 op_sel_hi:[1,0]
	v_pk_mul_f32 v[4:5], v[8:9], v[4:5]
	s_nop 0
	v_cvt_pk_bf16_f32 v4, v4, v5
	v_mov_b32_e32 v20, v192
	v_rcp_f32_e32 v9, v15
	v_rcp_f32_e32 v8, v14
	s_nop 0
	v_pk_mul_f32 v[8:9], v[8:9], v[10:11]
	v_lshlrev_b32_e32 v10, 16, v58
	v_mul_f32_e32 v14, 0x3d372713, v10
	v_mul_f32_e32 v14, v14, v10
	v_mov_b32_e32 v15, v10
	v_and_b32_e32 v11, 0xffff0000, v58
	v_fmac_f32_e32 v15, v14, v15
	v_mul_f32_e32 v14, 0x3f4c422a, v15
	v_mul_f32_e32 v15, 0x3d372713, v11
	v_mul_f32_e32 v15, v15, v11
	v_mov_b32_e32 v16, v11
	v_fmac_f32_e32 v16, v15, v16
	v_mul_f32_e32 v15, 0x3f4c422a, v16
	v_add_f32_e32 v14, v14, v14
	v_add_f32_e32 v15, v15, v15
	v_mul_f32_e32 v14, 0xbfb8aa3b, v14
	v_mul_f32_e32 v15, 0xbfb8aa3b, v15
	v_exp_f32_e32 v14, v14
	v_exp_f32_e32 v15, v15
	v_pk_mul_f32 v[6:7], v[8:9], v[6:7]
	v_mov_b32_e32 v58, v192
	v_cvt_pk_bf16_f32 v5, v6, v7
	v_pk_add_f32 v[8:9], v[14:15], 1.0 op_sel_hi:[1,0]
	v_lshl_add_u64 v[6:7], v[12:13], 0, v[34:35]
	global_store_dwordx2 v[6:7], v[4:5], off
	v_rcp_f32_e32 v5, v9
	v_lshlrev_b32_e32 v6, 16, v59
	v_mul_f32_e32 v14, 0x3d372713, v6
	v_mul_f32_e32 v14, v14, v6
	v_mov_b32_e32 v15, v6
	v_and_b32_e32 v7, 0xffff0000, v59
	v_fmac_f32_e32 v15, v14, v15
	v_mul_f32_e32 v14, 0x3f4c422a, v15
	v_mul_f32_e32 v15, 0x3d372713, v7
	v_mul_f32_e32 v15, v15, v7
	v_mov_b32_e32 v17, v7
	v_fmac_f32_e32 v17, v15, v17
	v_mul_f32_e32 v15, 0x3f4c422a, v17
	v_add_f32_e32 v14, v14, v14
	v_add_f32_e32 v15, v15, v15
	v_mul_f32_e32 v14, 0xbfb8aa3b, v14
	v_mul_f32_e32 v15, 0xbfb8aa3b, v15
	v_exp_f32_e32 v14, v14
	v_exp_f32_e32 v15, v15
	v_rcp_f32_e32 v4, v8
	s_nop 0
	v_pk_mul_f32 v[4:5], v[4:5], v[10:11]
	v_pk_add_f32 v[8:9], v[14:15], 1.0 op_sel_hi:[1,0]
	v_pk_mul_f32 v[0:1], v[4:5], v[0:1]
	s_nop 0
	v_cvt_pk_bf16_f32 v0, v0, v1
	v_mov_b32_e32 v16, v192
	v_rcp_f32_e32 v5, v9
	v_rcp_f32_e32 v4, v8
	s_nop 0
	v_pk_mul_f32 v[4:5], v[4:5], v[6:7]
	v_mov_b32_e32 v8, v192
	v_pk_mul_f32 v[2:3], v[4:5], v[2:3]
	v_or_b32_e32 v5, 64, v82
	v_cvt_pk_bf16_f32 v1, v2, v3
	v_lshl_add_u64 v[2:3], v[12:13], 0, v[66:67]
	global_store_dwordx2 v[2:3], v[0:1], off
	v_or_b32_e32 v0, s3, v5
	v_ashrrev_i32_e32 v1, 31, v0
	v_lshlrev_b64 v[0:1], 8, v[0:1]
	v_lshl_add_u64 v[2:3], v[76:77], 0, v[0:1]
	v_or_b32_e32 v0, s2, v5
	v_ashrrev_i32_e32 v1, 31, v0
	v_mov_b32_e32 v4, v192
	v_mov_b32_e32 v12, v192
	v_lshlrev_b64 v[0:1], 8, v[0:1]
	global_load_dwordx4 v[68:71], v[2:3], off
	v_lshl_add_u64 v[0:1], v[76:77], 0, v[0:1]
	global_load_dwordx4 v[72:75], v[0:1], off
	global_load_dwordx4 v[76:79], v[2:3], off offset:64
	ds_read2_b64 v[90:93], v57 offset1:1
	ds_read2_b64 v[80:83], v83 offset1:1
	ds_read2_b64 v[94:97], v84 offset1:1
	ds_read2_b64 v[98:101], v85 offset1:1
	v_mov_b32_e32 v9, v8
	v_mov_b32_e32 v5, v4
	v_mov_b32_e32 v6, v4
	v_mov_b32_e32 v7, v4
	v_mov_b32_e32 v10, v8
	v_mov_b32_e32 v11, v8
	v_mov_b32_e32 v13, v12
	v_mov_b32_e32 v14, v12
	v_mov_b32_e32 v15, v12
	v_mov_b32_e32 v17, v16
	v_mov_b32_e32 v18, v16
	v_mov_b32_e32 v19, v16
	v_mov_b32_e32 v21, v20
	v_mov_b32_e32 v22, v20
	v_mov_b32_e32 v23, v20
	v_mov_b32_e32 v25, v24
	v_mov_b32_e32 v26, v24
	v_mov_b32_e32 v27, v24
	v_mov_b32_e32 v59, v58
	v_mov_b32_e32 v60, v58
	v_mov_b32_e32 v61, v58
	v_mov_b32_e32 v63, v62
	v_mov_b32_e32 v64, v62
	v_mov_b32_e32 v65, v62
	s_waitcnt vmcnt(0) lgkmcnt(0)
	v_mfma_f32_16x16x32_bf16 v[4:7], v[90:93], v[68:71], v[4:7]
	v_mfma_f32_16x16x32_bf16 v[8:11], v[80:83], v[68:71], v[8:11]
	v_mfma_f32_16x16x32_bf16 v[12:15], v[94:97], v[68:71], v[12:15]
	v_mfma_f32_16x16x32_bf16 v[16:19], v[98:101], v[68:71], v[16:19]
	ds_read2_b64 v[68:71], v57 offset0:8 offset1:9
	v_mfma_f32_16x16x32_bf16 v[20:23], v[90:93], v[72:75], v[20:23]
	v_mfma_f32_16x16x32_bf16 v[24:27], v[80:83], v[72:75], v[24:27]
	ds_read2_b64 v[80:83], v87 offset1:1
	v_mfma_f32_16x16x32_bf16 v[58:61], v[94:97], v[72:75], v[58:61]
	v_mfma_f32_16x16x32_bf16 v[62:65], v[98:101], v[72:75], v[62:65]
	ds_read2_b64 v[72:75], v86 offset1:1
	ds_read2_b64 v[84:87], v88 offset1:1
	s_waitcnt lgkmcnt(3)
	v_mfma_f32_16x16x32_bf16 v[4:7], v[68:71], v[76:79], v[4:7]
	s_waitcnt lgkmcnt(1)
	v_mfma_f32_16x16x32_bf16 v[8:11], v[72:75], v[76:79], v[8:11]
	v_mfma_f32_16x16x32_bf16 v[12:15], v[80:83], v[76:79], v[12:15]
	s_waitcnt lgkmcnt(0)
	v_mfma_f32_16x16x32_bf16 v[16:19], v[84:87], v[76:79], v[16:19]
	global_load_dwordx4 v[76:79], v[0:1], off offset:64
	s_waitcnt vmcnt(0) lgkmcnt(0)
	v_mfma_f32_16x16x32_bf16 v[20:23], v[68:71], v[76:79], v[20:23]
	global_load_dwordx4 v[68:71], v[2:3], off offset:128
	v_mfma_f32_16x16x32_bf16 v[24:27], v[72:75], v[76:79], v[24:27]
	ds_read2_b64 v[72:75], v57 offset0:16 offset1:17
	v_mfma_f32_16x16x32_bf16 v[58:61], v[80:83], v[76:79], v[58:61]
	v_mfma_f32_16x16x32_bf16 v[62:65], v[84:87], v[76:79], v[62:65]
	ds_read2_b64 v[76:79], v47 offset1:1
	v_add_u32_e32 v47, 0x2180, v57
	ds_read2_b64 v[80:83], v47 offset1:1
	v_add_u32_e32 v47, 0x3200, v57
	ds_read2_b64 v[84:87], v47 offset1:1
	s_waitcnt vmcnt(0) lgkmcnt(0)
	v_mfma_f32_16x16x32_bf16 v[4:7], v[72:75], v[68:71], v[4:7]
	v_or_b32_e32 v47, s3, v37
	v_mfma_f32_16x16x32_bf16 v[8:11], v[76:79], v[68:71], v[8:11]
	v_mfma_f32_16x16x32_bf16 v[12:15], v[80:83], v[68:71], v[12:15]
	v_mfma_f32_16x16x32_bf16 v[16:19], v[84:87], v[68:71], v[16:19]
	global_load_dwordx4 v[68:71], v[0:1], off offset:128
	s_waitcnt vmcnt(0) lgkmcnt(0)
	v_mfma_f32_16x16x32_bf16 v[58:61], v[80:83], v[68:71], v[58:61]
	global_load_dwordx4 v[80:83], v[2:3], off offset:192
	v_add_u32_e32 v2, 0x1140, v57
	v_mfma_f32_16x16x32_bf16 v[72:75], v[72:75], v[68:71], v[20:23]
	v_mfma_f32_16x16x32_bf16 v[76:79], v[76:79], v[68:71], v[24:27]
	v_mfma_f32_16x16x32_bf16 v[62:65], v[84:87], v[68:71], v[62:65]
	ds_read2_b64 v[68:71], v57 offset0:24 offset1:25
	s_waitcnt vmcnt(0) lgkmcnt(0)
	v_mfma_f32_16x16x32_bf16 v[84:87], v[68:71], v[80:83], v[4:7]
	s_nop 2
	v_add_u32_e32 v6, 0x21c0, v57
	ds_read2_b64 v[2:5], v2 offset1:1
	ds_read2_b64 v[88:91], v6 offset1:1
	v_add_u32_e32 v6, 0x3240, v57
	ds_read2_b64 v[92:95], v6 offset1:1
	s_waitcnt lgkmcnt(2)
	v_mfma_f32_16x16x32_bf16 v[24:27], v[2:5], v[80:83], v[8:11]
	s_waitcnt lgkmcnt(1)
	v_mfma_f32_16x16x32_bf16 v[20:23], v[88:91], v[80:83], v[12:15]
	s_waitcnt lgkmcnt(0)
	v_mfma_f32_16x16x32_bf16 v[16:19], v[92:95], v[80:83], v[16:19]
	global_load_dwordx4 v[80:83], v[0:1], off offset:192
	s_waitcnt vmcnt(0) lgkmcnt(0)
	v_mfma_f32_16x16x32_bf16 v[8:11], v[2:5], v[80:83], v[76:79]
	s_nop 7
	v_pk_add_f32 v[8:9], v[36:37], v[8:9] op_sel_hi:[0,1]
	v_mfma_f32_16x16x32_bf16 v[4:7], v[88:91], v[80:83], v[58:61]
	v_add_f32_e64 v10, v36, v10
	v_add_f32_e64 v11, v36, v11
	s_nop 0
	v_lshlrev_b32_e32 v58, 16, v54
	v_mul_f32_e32 v0, 0x3d372713, v58
	v_mul_f32_e32 v0, v0, v58
	v_mov_b32_e32 v1, v58
	v_fmac_f32_e32 v1, v0, v1
	v_mul_f32_e32 v0, 0x3f4c422a, v1
	v_add_f32_e32 v0, v0, v0
	v_and_b32_e32 v59, 0xffff0000, v54
	v_mul_f32_e32 v0, 0xbfb8aa3b, v0
	v_exp_f32_e32 v56, v0
	v_mul_f32_e32 v0, 0x3d372713, v59
	v_mul_f32_e32 v0, v0, v59
	v_mov_b32_e32 v1, v59
	v_fmac_f32_e32 v1, v0, v1
	v_mul_f32_e32 v0, 0x3f4c422a, v1
	v_add_f32_e32 v0, v0, v0
	v_mul_f32_e32 v0, 0xbfb8aa3b, v0
	v_exp_f32_e32 v57, v0
	v_mfma_f32_16x16x32_bf16 v[0:3], v[92:95], v[80:83], v[62:65]
	v_add_f32_e64 v4, v36, v4
	v_add_f32_e64 v5, v36, v5
	v_pk_add_f32 v[6:7], v[36:37], v[6:7] op_sel_hi:[0,1]
	v_pk_add_f32 v[60:61], v[56:57], 1.0 op_sel_hi:[1,0]
	v_mad_i64_i32 v[56:57], s[0:1], v47, s86, v[32:33]
	v_mfma_f32_16x16x32_bf16 v[12:15], v[68:71], v[80:83], v[72:75]
	v_lshl_add_u64 v[56:57], v[56:57], 0, s[4:5]
	s_nop 0
	v_pk_add_f32 v[0:1], v[36:37], v[0:1] op_sel_hi:[0,1]
	v_rcp_f32_e32 v61, v61
	s_nop 3
	v_pk_add_f32 v[12:13], v[36:37], v[12:13] op_sel_hi:[0,1]
	v_lshlrev_b32_e32 v54, 16, v55
	v_mul_f32_e32 v62, 0x3d372713, v54
	v_mul_f32_e32 v62, v62, v54
	v_mov_b32_e32 v63, v54
	v_and_b32_e32 v55, 0xffff0000, v55
	v_fmac_f32_e32 v63, v62, v63
	v_mul_f32_e32 v62, 0x3f4c422a, v63
	v_mul_f32_e32 v63, 0x3d372713, v55
	v_mul_f32_e32 v63, v63, v55
	v_mov_b32_e32 v68, v55
	v_fmac_f32_e32 v68, v63, v68
	v_mul_f32_e32 v63, 0x3f4c422a, v68
	v_add_f32_e32 v62, v62, v62
	v_add_f32_e32 v63, v63, v63
	v_mul_f32_e32 v62, 0xbfb8aa3b, v62
	v_mul_f32_e32 v63, 0xbfb8aa3b, v63
	v_exp_f32_e32 v62, v62
	v_exp_f32_e32 v63, v63
	v_rcp_f32_e32 v60, v60
	s_nop 0
	v_pk_mul_f32 v[58:59], v[60:61], v[58:59]
	v_pk_add_f32 v[62:63], v[62:63], 1.0 op_sel_hi:[1,0]
	v_pk_add_f32 v[14:15], v[36:37], v[14:15] op_sel_hi:[0,1]
	v_pk_add_f32 v[60:61], v[46:47], v[84:85] op_sel_hi:[0,1]
	v_pk_mul_f32 v[58:59], v[58:59], v[60:61]
	v_pk_add_f32 v[2:3], v[36:37], v[2:3] op_sel_hi:[0,1]
	v_rcp_f32_e32 v61, v63
	v_cvt_pk_bf16_f32 v58, v58, v59
	v_rcp_f32_e32 v60, v62
	s_nop 0
	v_pk_mul_f32 v[54:55], v[60:61], v[54:55]
	v_lshlrev_b32_e32 v60, 16, v52
	v_mul_f32_e32 v47, 0x3d372713, v60
	v_and_b32_e32 v61, 0xffff0000, v52
	v_mul_f32_e32 v47, v47, v60
	v_mov_b32_e32 v52, v60
	v_fmac_f32_e32 v52, v47, v52
	v_mul_f32_e32 v47, 0x3f4c422a, v52
	v_add_f32_e32 v47, v47, v47
	v_mul_f32_e32 v47, 0xbfb8aa3b, v47
	v_exp_f32_e32 v62, v47
	v_mul_f32_e32 v47, 0x3d372713, v61
	v_mul_f32_e32 v47, v47, v61
	v_mov_b32_e32 v52, v61
	v_fmac_f32_e32 v52, v47, v52
	v_mul_f32_e32 v47, 0x3f4c422a, v52
	v_add_f32_e32 v47, v47, v47
	v_mul_f32_e32 v47, 0xbfb8aa3b, v47
	v_exp_f32_e32 v63, v47
	v_pk_add_f32 v[64:65], v[46:47], v[86:87] op_sel_hi:[0,1]
	v_pk_mul_f32 v[54:55], v[54:55], v[64:65]
	v_pk_add_f32 v[62:63], v[62:63], 1.0 op_sel_hi:[1,0]
	s_nop 0
	v_cvt_pk_bf16_f32 v59, v54, v55
	v_lshl_add_u64 v[54:55], v[56:57], 0, v[28:29]
	global_store_dwordx2 v[54:55], v[58:59], off
	v_rcp_f32_e32 v55, v63
	v_lshlrev_b32_e32 v52, 16, v53
	v_mul_f32_e32 v54, 0x3d372713, v52
	v_mul_f32_e32 v54, v54, v52
	v_mov_b32_e32 v58, v52
	v_fmac_f32_e32 v58, v54, v58
	v_mul_f32_e32 v54, 0x3f4c422a, v58
	v_add_f32_e32 v54, v54, v54
	v_and_b32_e32 v53, 0xffff0000, v53
	v_mul_f32_e32 v54, 0xbfb8aa3b, v54
	v_exp_f32_e32 v58, v54
	v_mul_f32_e32 v54, 0x3d372713, v53
	v_mul_f32_e32 v54, v54, v53
	v_mov_b32_e32 v59, v53
	v_fmac_f32_e32 v59, v54, v59
	v_mul_f32_e32 v54, 0x3f4c422a, v59
	v_add_f32_e32 v54, v54, v54
	v_mul_f32_e32 v54, 0xbfb8aa3b, v54
	v_exp_f32_e32 v59, v54
	v_rcp_f32_e32 v54, v62
	s_nop 0
	v_pk_mul_f32 v[54:55], v[54:55], v[60:61]
	v_pk_add_f32 v[58:59], v[58:59], 1.0 op_sel_hi:[1,0]
	s_nop 0
	v_pk_add_f32 v[24:25], v[46:47], v[24:25] op_sel_hi:[0,1]
	v_pk_mul_f32 v[24:25], v[54:55], v[24:25]
	v_rcp_f32_e32 v55, v59
	v_cvt_pk_bf16_f32 v24, v24, v25
	v_rcp_f32_e32 v54, v58
	s_nop 0
	v_pk_mul_f32 v[52:53], v[54:55], v[52:53]
	v_lshlrev_b32_e32 v54, 16, v50
	v_mul_f32_e32 v47, 0x3d372713, v54
	v_and_b32_e32 v55, 0xffff0000, v50
	v_mul_f32_e32 v47, v47, v54
	v_mov_b32_e32 v50, v54
	v_fmac_f32_e32 v50, v47, v50
	v_mul_f32_e32 v47, 0x3f4c422a, v50
	v_add_f32_e32 v47, v47, v47
	v_mul_f32_e32 v47, 0xbfb8aa3b, v47
	v_exp_f32_e32 v58, v47
	v_mul_f32_e32 v47, 0x3d372713, v55
	v_mul_f32_e32 v47, v47, v55
	v_mov_b32_e32 v50, v55
	v_fmac_f32_e32 v50, v47, v50
	v_mul_f32_e32 v47, 0x3f4c422a, v50
	v_add_f32_e32 v47, v47, v47
	v_mul_f32_e32 v47, 0xbfb8aa3b, v47
	v_exp_f32_e32 v59, v47
	v_pk_add_f32 v[26:27], v[46:47], v[26:27] op_sel_hi:[0,1]
	v_pk_mul_f32 v[26:27], v[52:53], v[26:27]
	v_pk_add_f32 v[52:53], v[58:59], 1.0 op_sel_hi:[1,0]
	s_nop 0
	v_cvt_pk_bf16_f32 v25, v26, v27
	v_lshl_add_u64 v[26:27], v[56:57], 0, v[30:31]
	global_store_dwordx2 v[26:27], v[24:25], off
	v_rcp_f32_e32 v25, v53
	v_lshlrev_b32_e32 v26, 16, v51
	v_mul_f32_e32 v50, 0x3d372713, v26
	v_and_b32_e32 v27, 0xffff0000, v51
	v_mul_f32_e32 v50, v50, v26
	v_mov_b32_e32 v51, v26
	v_fmac_f32_e32 v51, v50, v51
	v_mul_f32_e32 v50, 0x3f4c422a, v51
	v_mul_f32_e32 v51, 0x3d372713, v27
	v_mul_f32_e32 v51, v51, v27
	v_mov_b32_e32 v58, v27
	v_fmac_f32_e32 v58, v51, v58
	v_mul_f32_e32 v51, 0x3f4c422a, v58
	v_add_f32_e32 v50, v50, v50
	v_add_f32_e32 v51, v51, v51
	v_mul_f32_e32 v50, 0xbfb8aa3b, v50
	v_mul_f32_e32 v51, 0xbfb8aa3b, v51
	v_exp_f32_e32 v50, v50
	v_exp_f32_e32 v51, v51
	v_rcp_f32_e32 v24, v52
	s_nop 0
	v_pk_mul_f32 v[24:25], v[24:25], v[54:55]
	v_pk_add_f32 v[50:51], v[50:51], 1.0 op_sel_hi:[1,0]
	s_nop 0
	v_pk_add_f32 v[20:21], v[46:47], v[20:21] op_sel_hi:[0,1]
	v_pk_mul_f32 v[20:21], v[24:25], v[20:21]
	v_rcp_f32_e32 v25, v51
	v_cvt_pk_bf16_f32 v20, v20, v21
	v_rcp_f32_e32 v24, v50
	s_nop 0
	v_pk_mul_f32 v[24:25], v[24:25], v[26:27]
	v_lshlrev_b32_e32 v26, 16, v48
	v_mul_f32_e32 v47, 0x3d372713, v26
	v_and_b32_e32 v27, 0xffff0000, v48
	v_mul_f32_e32 v47, v47, v26
	v_mov_b32_e32 v48, v26
	v_fmac_f32_e32 v48, v47, v48
	v_mul_f32_e32 v47, 0x3f4c422a, v48
	v_add_f32_e32 v47, v47, v47
	v_mul_f32_e32 v47, 0xbfb8aa3b, v47
	v_exp_f32_e32 v50, v47
	v_mul_f32_e32 v47, 0x3d372713, v27
	v_mul_f32_e32 v47, v47, v27
	v_mov_b32_e32 v48, v27
	v_fmac_f32_e32 v48, v47, v48
	v_mul_f32_e32 v47, 0x3f4c422a, v48
	v_add_f32_e32 v47, v47, v47
	v_mul_f32_e32 v47, 0xbfb8aa3b, v47
	v_exp_f32_e32 v51, v47
	v_pk_add_f32 v[22:23], v[46:47], v[22:23] op_sel_hi:[0,1]
	v_pk_mul_f32 v[22:23], v[24:25], v[22:23]
	v_pk_add_f32 v[24:25], v[50:51], 1.0 op_sel_hi:[1,0]
	s_nop 0
	v_cvt_pk_bf16_f32 v21, v22, v23
	v_lshl_add_u64 v[22:23], v[56:57], 0, v[34:35]
	global_store_dwordx2 v[22:23], v[20:21], off
	v_rcp_f32_e32 v21, v25
	v_lshlrev_b32_e32 v22, 16, v49
	v_mul_f32_e32 v48, 0x3d372713, v22
	v_and_b32_e32 v23, 0xffff0000, v49
	v_mul_f32_e32 v48, v48, v22
	v_mov_b32_e32 v49, v22
	v_fmac_f32_e32 v49, v48, v49
	v_mul_f32_e32 v48, 0x3f4c422a, v49
	v_mul_f32_e32 v49, 0x3d372713, v23
	v_mul_f32_e32 v49, v49, v23
	v_mov_b32_e32 v50, v23
	v_fmac_f32_e32 v50, v49, v50
	v_mul_f32_e32 v49, 0x3f4c422a, v50
	v_add_f32_e32 v48, v48, v48
	v_add_f32_e32 v49, v49, v49
	v_mul_f32_e32 v48, 0xbfb8aa3b, v48
	v_mul_f32_e32 v49, 0xbfb8aa3b, v49
	v_exp_f32_e32 v48, v48
	v_exp_f32_e32 v49, v49
	v_rcp_f32_e32 v20, v24
	s_nop 0
	v_pk_mul_f32 v[20:21], v[20:21], v[26:27]
	v_pk_add_f32 v[24:25], v[48:49], 1.0 op_sel_hi:[1,0]
	s_nop 0
	v_pk_add_f32 v[16:17], v[46:47], v[16:17] op_sel_hi:[0,1]
	v_pk_mul_f32 v[16:17], v[20:21], v[16:17]
	v_rcp_f32_e32 v21, v25
	v_rcp_f32_e32 v20, v24
	s_nop 0
	v_pk_mul_f32 v[20:21], v[20:21], v[22:23]
	v_pk_add_f32 v[18:19], v[46:47], v[18:19] op_sel_hi:[0,1]
	v_pk_mul_f32 v[18:19], v[20:21], v[18:19]
	v_cvt_pk_bf16_f32 v16, v16, v17
	v_cvt_pk_bf16_f32 v17, v18, v19
	v_lshlrev_b32_e32 v18, 16, v44
	v_mul_f32_e32 v20, 0x3d372713, v18
	v_mul_f32_e32 v20, v20, v18
	v_mov_b32_e32 v21, v18
	v_and_b32_e32 v19, 0xffff0000, v44
	v_fmac_f32_e32 v21, v20, v21
	v_mul_f32_e32 v20, 0x3f4c422a, v21
	v_mul_f32_e32 v21, 0x3d372713, v19
	v_mul_f32_e32 v21, v21, v19
	v_mov_b32_e32 v22, v19
	v_fmac_f32_e32 v22, v21, v22
	v_mul_f32_e32 v21, 0x3f4c422a, v22
	v_add_f32_e32 v20, v20, v20
	v_add_f32_e32 v21, v21, v21
	v_mul_f32_e32 v20, 0xbfb8aa3b, v20
	v_mul_f32_e32 v21, 0xbfb8aa3b, v21
	v_exp_f32_e32 v20, v20
	v_exp_f32_e32 v21, v21
	v_lshl_add_u64 v[22:23], v[56:57], 0, v[66:67]
	global_store_dwordx2 v[22:23], v[16:17], off
	v_or_b32_e32 v16, s2, v37
	v_pk_add_f32 v[20:21], v[20:21], 1.0 op_sel_hi:[1,0]
	v_mad_i64_i32 v[16:17], s[0:1], v16, s86, v[32:33]
	v_lshl_add_u64 v[16:17], v[16:17], 0, s[4:5]
	v_rcp_f32_e32 v21, v21
	v_lshlrev_b32_e32 v22, 16, v45
	v_mul_f32_e32 v24, 0x3d372713, v22
	v_mul_f32_e32 v24, v24, v22
	v_mov_b32_e32 v25, v22
	v_and_b32_e32 v23, 0xffff0000, v45
	v_fmac_f32_e32 v25, v24, v25
	v_mul_f32_e32 v24, 0x3f4c422a, v25
	v_mul_f32_e32 v25, 0x3d372713, v23
	v_mul_f32_e32 v25, v25, v23
	v_mov_b32_e32 v33, v23
	v_fmac_f32_e32 v33, v25, v33
	v_mul_f32_e32 v25, 0x3f4c422a, v33
	v_add_f32_e32 v24, v24, v24
	v_add_f32_e32 v25, v25, v25
	v_mul_f32_e32 v24, 0xbfb8aa3b, v24
	v_mul_f32_e32 v25, 0xbfb8aa3b, v25
	v_exp_f32_e32 v24, v24
	v_exp_f32_e32 v25, v25
	v_rcp_f32_e32 v20, v20
	s_nop 0
	v_pk_mul_f32 v[18:19], v[20:21], v[18:19]
	v_pk_add_f32 v[24:25], v[24:25], 1.0 op_sel_hi:[1,0]
	v_pk_mul_f32 v[12:13], v[18:19], v[12:13]
	s_nop 0
	v_cvt_pk_bf16_f32 v12, v12, v13
	v_rcp_f32_e32 v19, v25
	v_rcp_f32_e32 v18, v24
	v_lshlrev_b32_e32 v20, 16, v42
	v_pk_mul_f32 v[18:19], v[18:19], v[22:23]
	v_mul_f32_e32 v22, 0x3d372713, v20
	v_mul_f32_e32 v22, v22, v20
	v_mov_b32_e32 v23, v20
	v_and_b32_e32 v21, 0xffff0000, v42
	v_fmac_f32_e32 v23, v22, v23
	v_mul_f32_e32 v22, 0x3f4c422a, v23
	v_mul_f32_e32 v23, 0x3d372713, v21
	v_mul_f32_e32 v23, v23, v21
	v_mov_b32_e32 v24, v21
	v_fmac_f32_e32 v24, v23, v24
	v_mul_f32_e32 v23, 0x3f4c422a, v24
	v_add_f32_e32 v22, v22, v22
	v_add_f32_e32 v23, v23, v23
	v_mul_f32_e32 v22, 0xbfb8aa3b, v22
	v_mul_f32_e32 v23, 0xbfb8aa3b, v23
	v_exp_f32_e32 v22, v22
	v_exp_f32_e32 v23, v23
	v_pk_mul_f32 v[14:15], v[18:19], v[14:15]
	v_pk_add_f32 v[18:19], v[22:23], 1.0 op_sel_hi:[1,0]
	s_nop 0
	v_cvt_pk_bf16_f32 v13, v14, v15
	v_lshl_add_u64 v[14:15], v[16:17], 0, v[28:29]
	global_store_dwordx2 v[14:15], v[12:13], off
	v_rcp_f32_e32 v13, v19
	v_lshlrev_b32_e32 v14, 16, v43
	v_mul_f32_e32 v22, 0x3d372713, v14
	v_mul_f32_e32 v22, v22, v14
	v_mov_b32_e32 v23, v14
	v_and_b32_e32 v15, 0xffff0000, v43
	v_fmac_f32_e32 v23, v22, v23
	v_mul_f32_e32 v22, 0x3f4c422a, v23
	v_mul_f32_e32 v23, 0x3d372713, v15
	v_mul_f32_e32 v23, v23, v15
	v_mov_b32_e32 v25, v15
	v_fmac_f32_e32 v25, v23, v25
	v_mul_f32_e32 v23, 0x3f4c422a, v25
	v_add_f32_e32 v22, v22, v22
	v_add_f32_e32 v23, v23, v23
	v_mul_f32_e32 v22, 0xbfb8aa3b, v22
	v_mul_f32_e32 v23, 0xbfb8aa3b, v23
	v_exp_f32_e32 v22, v22
	v_exp_f32_e32 v23, v23
	v_rcp_f32_e32 v12, v18
	s_nop 0
	v_pk_mul_f32 v[12:13], v[12:13], v[20:21]
	v_pk_add_f32 v[18:19], v[22:23], 1.0 op_sel_hi:[1,0]
	v_pk_mul_f32 v[8:9], v[12:13], v[8:9]
	s_nop 0
	v_cvt_pk_bf16_f32 v8, v8, v9
	v_rcp_f32_e32 v13, v19
	v_rcp_f32_e32 v12, v18
	s_nop 0
	v_pk_mul_f32 v[12:13], v[12:13], v[14:15]
	v_lshlrev_b32_e32 v14, 16, v40
	v_mul_f32_e32 v18, 0x3d372713, v14
	v_mul_f32_e32 v18, v18, v14
	v_mov_b32_e32 v19, v14
	v_and_b32_e32 v15, 0xffff0000, v40
	v_fmac_f32_e32 v19, v18, v19
	v_mul_f32_e32 v18, 0x3f4c422a, v19
	v_mul_f32_e32 v19, 0x3d372713, v15
	v_mul_f32_e32 v19, v19, v15
	v_mov_b32_e32 v20, v15
	v_fmac_f32_e32 v20, v19, v20
	v_mul_f32_e32 v19, 0x3f4c422a, v20
	v_add_f32_e32 v18, v18, v18
	v_add_f32_e32 v19, v19, v19
	v_mul_f32_e32 v18, 0xbfb8aa3b, v18
	v_mul_f32_e32 v19, 0xbfb8aa3b, v19
	v_exp_f32_e32 v18, v18
	v_exp_f32_e32 v19, v19
	v_pk_mul_f32 v[10:11], v[12:13], v[10:11]
	v_pk_add_f32 v[12:13], v[18:19], 1.0 op_sel_hi:[1,0]
	s_nop 0
	v_cvt_pk_bf16_f32 v9, v10, v11
	v_lshl_add_u64 v[10:11], v[16:17], 0, v[30:31]
	global_store_dwordx2 v[10:11], v[8:9], off
	v_rcp_f32_e32 v9, v13
	v_lshlrev_b32_e32 v10, 16, v41
	v_mul_f32_e32 v18, 0x3d372713, v10
	v_mul_f32_e32 v18, v18, v10
	v_mov_b32_e32 v19, v10
	v_and_b32_e32 v11, 0xffff0000, v41
	v_fmac_f32_e32 v19, v18, v19
	v_mul_f32_e32 v18, 0x3f4c422a, v19
	v_mul_f32_e32 v19, 0x3d372713, v11
	v_mul_f32_e32 v19, v19, v11
	v_mov_b32_e32 v21, v11
	v_fmac_f32_e32 v21, v19, v21
	v_mul_f32_e32 v19, 0x3f4c422a, v21
	v_add_f32_e32 v18, v18, v18
	v_add_f32_e32 v19, v19, v19
	v_mul_f32_e32 v18, 0xbfb8aa3b, v18
	v_mul_f32_e32 v19, 0xbfb8aa3b, v19
	v_exp_f32_e32 v18, v18
	v_exp_f32_e32 v19, v19
	v_rcp_f32_e32 v8, v12
	s_nop 0
	v_pk_mul_f32 v[8:9], v[8:9], v[14:15]
	v_pk_add_f32 v[12:13], v[18:19], 1.0 op_sel_hi:[1,0]
	v_pk_mul_f32 v[4:5], v[8:9], v[4:5]
	s_nop 0
	v_cvt_pk_bf16_f32 v4, v4, v5
	v_rcp_f32_e32 v9, v13
	v_rcp_f32_e32 v8, v12
	s_nop 0
	v_pk_mul_f32 v[8:9], v[8:9], v[10:11]
	v_lshlrev_b32_e32 v10, 16, v38
	v_mul_f32_e32 v12, 0x3d372713, v10
	v_mul_f32_e32 v12, v12, v10
	v_mov_b32_e32 v13, v10
	v_and_b32_e32 v11, 0xffff0000, v38
	v_fmac_f32_e32 v13, v12, v13
	v_mul_f32_e32 v12, 0x3f4c422a, v13
	v_mul_f32_e32 v13, 0x3d372713, v11
	v_mul_f32_e32 v13, v13, v11
	v_mov_b32_e32 v14, v11
	v_fmac_f32_e32 v14, v13, v14
	v_mul_f32_e32 v13, 0x3f4c422a, v14
	v_add_f32_e32 v12, v12, v12
	v_add_f32_e32 v13, v13, v13
	v_mul_f32_e32 v12, 0xbfb8aa3b, v12
	v_mul_f32_e32 v13, 0xbfb8aa3b, v13
	v_exp_f32_e32 v12, v12
	v_exp_f32_e32 v13, v13
	v_pk_mul_f32 v[6:7], v[8:9], v[6:7]
	v_pk_add_f32 v[8:9], v[12:13], 1.0 op_sel_hi:[1,0]
	s_nop 0
	v_cvt_pk_bf16_f32 v5, v6, v7
	v_lshl_add_u64 v[6:7], v[16:17], 0, v[34:35]
	global_store_dwordx2 v[6:7], v[4:5], off
	v_rcp_f32_e32 v5, v9
	v_lshlrev_b32_e32 v6, 16, v39
	v_mul_f32_e32 v12, 0x3d372713, v6
	v_mul_f32_e32 v12, v12, v6
	v_mov_b32_e32 v13, v6
	v_and_b32_e32 v7, 0xffff0000, v39
	v_fmac_f32_e32 v13, v12, v13
	v_mul_f32_e32 v12, 0x3f4c422a, v13
	v_mul_f32_e32 v13, 0x3d372713, v7
	v_mul_f32_e32 v13, v13, v7
	v_mov_b32_e32 v15, v7
	v_fmac_f32_e32 v15, v13, v15
	v_mul_f32_e32 v13, 0x3f4c422a, v15
	v_add_f32_e32 v12, v12, v12
	v_add_f32_e32 v13, v13, v13
	v_mul_f32_e32 v12, 0xbfb8aa3b, v12
	v_mul_f32_e32 v13, 0xbfb8aa3b, v13
	v_exp_f32_e32 v12, v12
	v_exp_f32_e32 v13, v13
	v_rcp_f32_e32 v4, v8
	s_nop 0
	v_pk_mul_f32 v[4:5], v[4:5], v[10:11]
	v_pk_add_f32 v[8:9], v[12:13], 1.0 op_sel_hi:[1,0]
	v_pk_mul_f32 v[0:1], v[4:5], v[0:1]
	s_nop 0
	v_cvt_pk_bf16_f32 v0, v0, v1
	v_rcp_f32_e32 v5, v9
	v_rcp_f32_e32 v4, v8
	s_nop 0
	v_pk_mul_f32 v[4:5], v[4:5], v[6:7]
	s_nop 0
	v_pk_mul_f32 v[2:3], v[4:5], v[2:3]
	s_nop 0
	v_cvt_pk_bf16_f32 v1, v2, v3
	v_lshl_add_u64 v[2:3], v[16:17], 0, v[66:67]
	global_store_dwordx2 v[2:3], v[0:1], off
	s_waitcnt lgkmcnt(0)
	s_barrier

.LBB0_670:
	s_add_i32 s12, s80, s8
	s_cmpk_lt_i32 s12, 0x4080
	s_cselect_b32 s70, s12, s8
	s_ashr_i32 s71, s70, 31
	s_lshl_b64 s[56:57], s[70:71], 10
	s_mul_i32 s3, s70, 0xc00
	s_mul_hi_i32 s2, s70, 0xc00
	s_add_u32 s80, s0, s3
	s_addc_u32 s81, s1, s2
	s_lshl_b64 s[4:5], s[70:71], 9
	s_add_i32 s11, s73, s8
	s_cmpk_lt_i32 s11, 0x4080
	s_cselect_b64 s[6:7], -1, 0
	s_and_b64 s[2:3], s[6:7], exec
	s_cselect_b32 s58, s11, s8
	s_ashr_i32 s59, s58, 31
	s_lshl_b64 s[82:83], s[58:59], 10
	s_mul_i32 s3, s58, 0xc00
	s_mul_hi_i32 s2, s58, 0xc00
	s_add_u32 s78, s0, s3
	v_readlane_b32 s38, v254, 4
	s_addc_u32 s79, s1, s2
	s_mul_i32 s2, s38, 24
	s_lshl_b64 s[62:63], s[58:59], 9
	s_add_i32 s10, s2, s8
	s_cmpk_lt_i32 s10, 0x4080
	s_cselect_b64 s[18:19], -1, 0
	s_and_b64 s[2:3], s[18:19], exec
	s_cselect_b32 s60, s10, s8
	s_ashr_i32 s61, s60, 31
	s_lshl_b64 s[92:93], s[60:61], 10
	s_mul_i32 s3, s60, 0xc00
	s_mul_hi_i32 s2, s60, 0xc00
	s_add_u32 s72, s0, s3
	s_addc_u32 s73, s1, s2
	s_lshl_b64 s[94:95], s[60:61], 9
	s_add_i32 s91, s76, s8
	s_cmpk_lt_i32 s91, 0x4080
	s_cselect_b64 s[16:17], -1, 0
	s_and_b64 s[2:3], s[16:17], exec
	s_cselect_b32 s66, s91, s8
	s_ashr_i32 s67, s66, 31
	s_lshl_b64 s[96:97], s[66:67], 10
	s_mul_i32 s3, s66, 0xc00
	s_mul_hi_i32 s2, s66, 0xc00
	s_add_u32 s76, s0, s3
	s_addc_u32 s77, s1, s2
	v_readlane_b32 s2, v254, 35
	s_lshl_b64 s[68:69], s[66:67], 9
	s_add_i32 s90, s2, s8
	s_cmpk_lt_i32 s90, 0x4080
	v_lshlrev_b32_e32 v194, 1, v40
	s_cselect_b64 s[14:15], -1, 0
	v_lshl_add_u64 v[10:11], s[80:81], 0, v[194:195]
	s_mov_b32 s65, 0xa890000
	s_and_b64 s[2:3], s[14:15], exec
	v_add_co_u32_e32 v10, vcc, s65, v10
	s_cselect_b32 s2, s90, s8
	s_nop 0
	v_addc_co_u32_e32 v11, vcc, 0, v11, vcc
	v_lshl_add_u64 v[18:19], s[78:79], 0, v[194:195]
	s_ashr_i32 s3, s2, 31
	v_lshl_add_u64 v[8:9], v[42:43], 0, s[56:57]
	v_add_co_u32_e32 v18, vcc, s65, v18
	s_lshl_b64 s[24:25], s[2:3], 10
	s_mul_i32 s13, s2, 0xc00
	v_lshl_add_u64 v[12:13], v[44:45], 0, s[4:5]
	v_lshl_add_u64 v[14:15], s[70:71], 4, v[46:47]
	v_lshl_add_u64 v[16:17], v[42:43], 0, s[82:83]
	v_addc_co_u32_e32 v19, vcc, 0, v19, vcc
	global_load_dwordx4 v[36:39], v[8:9], off
	global_load_dwordx2 v[106:107], v[10:11], off offset:1024
	global_load_dwordx2 v[104:105], v[12:13], off
	global_load_dword v102, v[14:15], off
	global_load_dwordx4 v[32:35], v[16:17], off
	global_load_dwordx2 v[100:101], v[18:19], off offset:1024
	v_lshl_add_u64 v[10:11], s[72:73], 0, v[194:195]
	s_mul_hi_i32 s9, s2, 0xc00
	s_add_u32 s28, s0, s13
	s_mul_i32 s89, s38, 48
	v_lshl_add_u64 v[20:21], v[44:45], 0, s[62:63]
	v_lshl_add_u64 v[8:9], s[58:59], 4, v[46:47]
	v_add_co_u32_e32 v10, vcc, s65, v10
	s_addc_u32 s29, s1, s9
	s_lshl_b64 s[26:27], s[2:3], 9
	s_add_i32 s89, s89, s8
	global_load_dwordx2 v[98:99], v[20:21], off
	global_load_dword v96, v[8:9], off
	v_lshl_add_u64 v[8:9], v[42:43], 0, s[92:93]
	v_addc_co_u32_e32 v11, vcc, 0, v11, vcc
	s_cmpk_lt_i32 s89, 0x4080
	global_load_dwordx4 v[28:31], v[8:9], off
	global_load_dwordx2 v[92:93], v[10:11], off offset:1024
	v_lshl_add_u64 v[8:9], v[44:45], 0, s[94:95]
	v_lshl_add_u64 v[10:11], s[60:61], 4, v[46:47]
	s_cselect_b64 s[20:21], -1, 0
	global_load_dwordx2 v[94:95], v[8:9], off
	global_load_dword v90, v[10:11], off
	v_lshl_add_u64 v[10:11], s[76:77], 0, v[194:195]
	v_writelane_b32 v255, s20, 29
	v_add_co_u32_e32 v10, vcc, s65, v10
	s_nop 0
	v_writelane_b32 v255, s21, 30
	s_and_b64 s[20:21], s[20:21], exec
	v_lshl_add_u64 v[8:9], v[42:43], 0, s[96:97]
	v_addc_co_u32_e32 v11, vcc, 0, v11, vcc
	v_lshl_add_u64 v[12:13], s[0:1], 0, v[50:51]
	s_cselect_b32 s22, s89, s8
	global_load_dwordx4 v[24:27], v[8:9], off
	global_load_dwordx2 v[84:85], v[10:11], off offset:1024
	v_lshl_add_u64 v[8:9], v[44:45], 0, s[68:69]
	v_lshl_add_u64 v[10:11], s[66:67], 4, v[46:47]
	v_lshl_add_u64 v[14:15], s[0:1], 0, v[52:53]
	global_load_dwordx2 v[112:113], v[12:13], off
	global_load_dwordx4 v[108:111], v[14:15], off
	global_load_dwordx2 v[88:89], v[8:9], off
	global_load_dword v86, v[10:11], off
	s_ashr_i32 s23, s22, 31
	s_lshl_b64 s[30:31], s[22:23], 10
	s_mul_i32 s13, s22, 0xc00
	s_mul_hi_i32 s9, s22, 0xc00
	s_add_u32 s36, s0, s13
	s_mul_i32 s42, s38, 56
	s_addc_u32 s37, s1, s9
	s_lshl_b64 s[34:35], s[22:23], 9
	s_add_i32 s42, s42, s8
	s_cmpk_lt_i32 s42, 0x4080
	s_cselect_b64 s[20:21], -1, 0
	v_writelane_b32 v255, s20, 41
	v_lshl_add_u64 v[10:11], s[28:29], 0, v[194:195]
	v_add_co_u32_e32 v10, vcc, s65, v10
	v_writelane_b32 v255, s21, 42
	s_and_b64 s[20:21], s[20:21], exec
	s_cselect_b32 s20, s42, s8
	s_ashr_i32 s21, s20, 31
	s_lshl_b64 s[38:39], s[20:21], 10
	s_mul_i32 s13, s20, 0xc00
	s_mul_hi_i32 s9, s20, 0xc00
	s_add_u32 s40, s0, s13
	s_addc_u32 s41, s1, s9
	v_readlane_b32 s9, v254, 6
	s_lshl_b64 s[56:57], s[20:21], 9
	s_add_i32 s9, s9, s8
	s_cmpk_lt_i32 s9, 0x4080
	v_lshl_add_u64 v[8:9], v[42:43], 0, s[24:25]
	v_addc_co_u32_e32 v11, vcc, 0, v11, vcc
	s_cselect_b64 s[4:5], -1, 0
	global_load_dwordx4 v[20:23], v[8:9], off
	global_load_dwordx2 v[82:83], v[10:11], off offset:1024
	v_lshl_add_u64 v[8:9], v[44:45], 0, s[26:27]
	v_lshl_add_u64 v[10:11], s[2:3], 4, v[46:47]
	s_and_b64 s[80:81], s[4:5], exec
	global_load_dwordx2 v[80:81], v[8:9], off
	global_load_dword v78, v[10:11], off
	v_lshl_add_u64 v[10:11], s[36:37], 0, v[194:195]
	s_cselect_b32 s80, s9, s8
	v_add_co_u32_e32 v10, vcc, s65, v10
	s_ashr_i32 s81, s80, 31
	v_lshl_add_u64 v[8:9], v[42:43], 0, s[30:31]
	v_addc_co_u32_e32 v11, vcc, 0, v11, vcc
	s_lshl_b64 s[70:71], s[80:81], 10
	s_mul_i32 s78, s80, 0xc00
	global_load_dwordx4 v[16:19], v[8:9], off
	global_load_dwordx2 v[76:77], v[10:11], off offset:1024
	v_lshl_add_u64 v[8:9], v[44:45], 0, s[34:35]
	v_lshl_add_u64 v[10:11], s[22:23], 4, v[46:47]
	s_mul_hi_i32 s13, s80, 0xc00
	s_add_u32 s78, s0, s78
	global_load_dwordx2 v[74:75], v[8:9], off
	global_load_dword v72, v[10:11], off
	v_lshl_add_u64 v[10:11], s[40:41], 0, v[194:195]
	s_addc_u32 s79, s1, s13
	s_lshl_b64 s[62:63], s[80:81], 9
	v_add_co_u32_e32 v10, vcc, s65, v10
	v_lshl_add_u64 v[8:9], v[42:43], 0, s[38:39]
	v_lshl_add_u64 v[12:13], v[44:45], 0, s[62:63]
	v_lshl_add_u64 v[14:15], s[80:81], 4, v[46:47]
	v_addc_co_u32_e32 v11, vcc, 0, v11, vcc
	v_lshl_add_u64 v[64:65], s[0:1], 0, v[56:57]
	v_lshl_add_u64 v[66:67], s[0:1], 0, v[54:55]
	global_load_dwordx2 v[62:63], v[12:13], off
	global_load_dword v60, v[14:15], off
	global_load_dword v114, v[64:65], off
	global_load_dwordx2 v[116:117], v[66:67], off
	s_nop 0
	global_load_dwordx4 v[12:15], v[8:9], off
	global_load_dwordx2 v[70:71], v[10:11], off offset:1024
	v_lshl_add_u64 v[8:9], v[44:45], 0, s[56:57]
	v_lshl_add_u64 v[10:11], s[20:21], 4, v[46:47]
	global_load_dwordx2 v[68:69], v[8:9], off
	global_load_dword v66, v[10:11], off
	v_lshl_add_u64 v[10:11], s[78:79], 0, v[194:195]
	v_add_co_u32_e32 v64, vcc, s65, v10
	v_lshl_add_u64 v[8:9], v[42:43], 0, s[70:71]
	s_nop 0
	v_addc_co_u32_e32 v65, vcc, 0, v11, vcc
	global_load_dwordx4 v[8:11], v[8:9], off
	s_nop 0
	global_load_dwordx2 v[64:65], v[64:65], off offset:1024
	s_waitcnt vmcnt(0) lgkmcnt(0)
	v_mov_b32_e32 v118, v109
	v_mov_b32_e32 v119, v110
	v_mov_b32_e32 v120, v108
	v_mov_b32_e32 v121, v111
	v_pk_add_f32 v[118:119], v[118:119], v[120:121]
	s_mov_b32 s13, 0x800000
	v_add_f32_e32 v61, v118, v119
	s_cmpk_gt_i32 s12, 0x407f
	s_nop 0
	v_add_f32_dpp v61, v61, v61 quad_perm:[1,0,3,2] row_mask:0xf bank_mask:0xf bound_ctrl:1
	s_nop 1
	v_add_f32_dpp v61, v61, v61 quad_perm:[2,3,0,1] row_mask:0xf bank_mask:0xf bound_ctrl:1
	s_nop 1
	v_add_f32_dpp v61, v61, v61 row_half_mirror row_mask:0xf bank_mask:0xf bound_ctrl:1
	s_nop 1
	v_add_f32_dpp v61, v61, v61 row_mirror row_mask:0xf bank_mask:0xf bound_ctrl:1
	v_fmamk_f32 v109, v61, 0xbc800000, v109
	v_fmamk_f32 v108, v61, 0xbc800000, v108
	v_fmamk_f32 v111, v61, 0xbc800000, v111
	v_fmac_f32_e32 v110, 0xbc800000, v61
	v_pk_mul_f32 v[118:119], v[110:111], v[110:111]
	v_pk_mul_f32 v[120:121], v[108:109], v[108:109]
	s_nop 0
	v_pk_mov_b32 v[122:123], v[120:121], v[118:119] op_sel:[1,0]
	v_mov_b32_e32 v121, v119
	v_pk_add_f32 v[118:119], v[122:123], v[120:121]
	v_lshlrev_b32_e32 v120, 16, v112
	v_add_f32_e32 v61, v118, v119
	v_and_b32_e32 v121, 0xffff0000, v112
	v_lshlrev_b32_e32 v112, 16, v113
	v_add_f32_dpp v61, v61, v61 quad_perm:[1,0,3,2] row_mask:0xf bank_mask:0xf bound_ctrl:1
	v_and_b32_e32 v113, 0xffff0000, v113
	v_lshlrev_b32_e32 v122, 16, v116
	v_add_f32_dpp v61, v61, v61 quad_perm:[2,3,0,1] row_mask:0xf bank_mask:0xf bound_ctrl:1
	v_and_b32_e32 v123, 0xffff0000, v116
	v_lshlrev_b32_e32 v116, 16, v117
	v_add_f32_dpp v61, v61, v61 row_half_mirror row_mask:0xf bank_mask:0xf bound_ctrl:1
	v_and_b32_e32 v117, 0xffff0000, v117
	s_nop 0
	v_add_f32_dpp v61, v61, v61 row_mirror row_mask:0xf bank_mask:0xf bound_ctrl:1
	v_fmamk_f32 v61, v61, 0x3c800000, v239
	v_mul_f32_e32 v67, 0x4b800000, v61
	v_cmp_gt_f32_e32 vcc, s13, v61
	s_nop 1
	v_cndmask_b32_e32 v61, v61, v67, vcc
	v_rsq_f32_e32 v61, v61
	s_nop 0
	v_mul_f32_e32 v67, 0x45800000, v61
	v_cndmask_b32_e32 v118, v61, v67, vcc
	v_pk_mul_f32 v[108:109], v[108:109], v[118:119] op_sel_hi:[1,0]
	v_pk_mul_f32 v[110:111], v[110:111], v[118:119] op_sel_hi:[1,0]
	v_pk_fma_f32 v[108:109], v[4:5], v[108:109], v[0:1]
	v_pk_fma_f32 v[110:111], v[6:7], v[110:111], v[2:3]
	v_pk_fma_f32 v[108:109], v[114:115], v[120:121], v[108:109] op_sel_hi:[0,1,1]
	v_pk_fma_f32 v[110:111], v[114:115], v[112:113], v[110:111] op_sel_hi:[0,1,1]
	v_pk_mul_f32 v[108:109], v[108:109], v[122:123]
	v_pk_mul_f32 v[110:111], v[110:111], v[116:117]
	v_cvt_pk_bf16_f32 v108, v108, v109
	v_cvt_pk_bf16_f32 v109, v110, v111
	v_lshl_add_u64 v[110:111], s[0:1], 0, v[48:49]
	global_store_dwordx2 v[110:111], v[108:109], off
	s_cbranch_scc1 .LBB0_672
	v_mov_b32_e32 v108, v37
	v_mov_b32_e32 v109, v38
	v_mov_b32_e32 v110, v36
	v_mov_b32_e32 v111, v39
	v_pk_add_f32 v[108:109], v[108:109], v[110:111]
	s_nop 0
	v_add_f32_e32 v61, v108, v109
	s_nop 1
	v_add_f32_dpp v61, v61, v61 quad_perm:[1,0,3,2] row_mask:0xf bank_mask:0xf bound_ctrl:1
	s_nop 1
	v_add_f32_dpp v61, v61, v61 quad_perm:[2,3,0,1] row_mask:0xf bank_mask:0xf bound_ctrl:1
	s_nop 1
	v_add_f32_dpp v61, v61, v61 row_half_mirror row_mask:0xf bank_mask:0xf bound_ctrl:1
	s_nop 1
	v_add_f32_dpp v61, v61, v61 row_mirror row_mask:0xf bank_mask:0xf bound_ctrl:1
	v_fmamk_f32 v37, v61, 0xbc800000, v37
	v_fmamk_f32 v36, v61, 0xbc800000, v36
	v_fmamk_f32 v39, v61, 0xbc800000, v39
	v_fmac_f32_e32 v38, 0xbc800000, v61
	v_pk_mul_f32 v[108:109], v[38:39], v[38:39]
	v_pk_mul_f32 v[110:111], v[36:37], v[36:37]
	s_nop 0
	v_pk_mov_b32 v[112:113], v[110:111], v[108:109] op_sel:[1,0]
	v_mov_b32_e32 v111, v109
	v_pk_add_f32 v[108:109], v[112:113], v[110:111]
	v_lshlrev_b32_e32 v110, 16, v106
	v_add_f32_e32 v61, v108, v109
	v_and_b32_e32 v111, 0xffff0000, v106
	v_lshlrev_b32_e32 v106, 16, v107
	v_add_f32_dpp v61, v61, v61 quad_perm:[1,0,3,2] row_mask:0xf bank_mask:0xf bound_ctrl:1
	v_and_b32_e32 v107, 0xffff0000, v107
	v_lshlrev_b32_e32 v112, 16, v104
	v_add_f32_dpp v61, v61, v61 quad_perm:[2,3,0,1] row_mask:0xf bank_mask:0xf bound_ctrl:1
	v_and_b32_e32 v113, 0xffff0000, v104
	v_lshlrev_b32_e32 v104, 16, v105
	v_add_f32_dpp v61, v61, v61 row_half_mirror row_mask:0xf bank_mask:0xf bound_ctrl:1
	v_and_b32_e32 v105, 0xffff0000, v105
	s_nop 0
	v_add_f32_dpp v61, v61, v61 row_mirror row_mask:0xf bank_mask:0xf bound_ctrl:1
	v_fmamk_f32 v61, v61, 0x3c800000, v239
	v_mul_f32_e32 v67, 0x4b800000, v61
	v_cmp_gt_f32_e32 vcc, s13, v61
	s_nop 1
	v_cndmask_b32_e32 v61, v61, v67, vcc
	v_rsq_f32_e32 v61, v61
	s_nop 0
	v_mul_f32_e32 v67, 0x45800000, v61
	v_cndmask_b32_e32 v108, v61, v67, vcc
	v_pk_mul_f32 v[36:37], v[36:37], v[108:109] op_sel_hi:[1,0]
	v_pk_mul_f32 v[38:39], v[38:39], v[108:109] op_sel_hi:[1,0]
	v_pk_fma_f32 v[36:37], v[4:5], v[36:37], v[0:1]
	v_pk_fma_f32 v[38:39], v[6:7], v[38:39], v[2:3]
	v_pk_fma_f32 v[36:37], v[102:103], v[110:111], v[36:37] op_sel_hi:[0,1,1]
	v_pk_fma_f32 v[38:39], v[102:103], v[106:107], v[38:39] op_sel_hi:[0,1,1]
	v_pk_mul_f32 v[36:37], v[36:37], v[112:113]
	v_pk_mul_f32 v[38:39], v[38:39], v[104:105]
	v_cvt_pk_bf16_f32 v36, v36, v37
	v_cvt_pk_bf16_f32 v37, v38, v39
	v_lshl_add_u64 v[38:39], s[0:1], 0, v[58:59]
	global_store_dwordx2 v[38:39], v[36:37], off
.LBB0_672:
	s_andn2_b64 vcc, exec, s[6:7]
	s_cbranch_vccnz .LBB0_674
	v_mov_b32_e32 v36, v33
	v_mov_b32_e32 v37, v34
	v_mov_b32_e32 v38, v32
	v_mov_b32_e32 v39, v35
	v_pk_add_f32 v[36:37], v[36:37], v[38:39]
	s_mul_hi_i32 s3, s11, 0x1400
	v_add_f32_e32 v36, v36, v37
	s_mulk_i32 s11, 0x1400
	s_add_u32 s2, s0, s11
	v_add_f32_dpp v36, v36, v36 quad_perm:[1,0,3,2] row_mask:0xf bank_mask:0xf bound_ctrl:1
	s_addc_u32 s3, s1, s3
	s_nop 0
	v_add_f32_dpp v36, v36, v36 quad_perm:[2,3,0,1] row_mask:0xf bank_mask:0xf bound_ctrl:1
	s_nop 1
	v_add_f32_dpp v36, v36, v36 row_half_mirror row_mask:0xf bank_mask:0xf bound_ctrl:1
	s_nop 1
	v_add_f32_dpp v36, v36, v36 row_mirror row_mask:0xf bank_mask:0xf bound_ctrl:1
	v_fmamk_f32 v33, v36, 0xbc800000, v33
	v_fmamk_f32 v32, v36, 0xbc800000, v32
	v_fmamk_f32 v35, v36, 0xbc800000, v35
	v_fmac_f32_e32 v34, 0xbc800000, v36
	v_pk_mul_f32 v[36:37], v[34:35], v[34:35]
	v_pk_mul_f32 v[38:39], v[32:33], v[32:33]
	s_nop 0
	v_pk_mov_b32 v[102:103], v[38:39], v[36:37] op_sel:[1,0]
	v_mov_b32_e32 v39, v37
	v_pk_add_f32 v[36:37], v[102:103], v[38:39]
	v_lshlrev_b32_e32 v38, 16, v100
	v_add_f32_e32 v36, v36, v37
	v_and_b32_e32 v39, 0xffff0000, v100
	v_lshlrev_b32_e32 v102, 16, v98
	v_add_f32_dpp v36, v36, v36 quad_perm:[1,0,3,2] row_mask:0xf bank_mask:0xf bound_ctrl:1
	v_and_b32_e32 v103, 0xffff0000, v98
	v_lshlrev_b32_e32 v98, 16, v99
	v_add_f32_dpp v36, v36, v36 quad_perm:[2,3,0,1] row_mask:0xf bank_mask:0xf bound_ctrl:1
	v_and_b32_e32 v99, 0xffff0000, v99
	s_nop 0
	v_add_f32_dpp v36, v36, v36 row_half_mirror row_mask:0xf bank_mask:0xf bound_ctrl:1
	s_nop 1
	v_add_f32_dpp v36, v36, v36 row_mirror row_mask:0xf bank_mask:0xf bound_ctrl:1
	v_fmamk_f32 v36, v36, 0x3c800000, v239
	v_mul_f32_e32 v37, 0x4b800000, v36
	v_cmp_gt_f32_e32 vcc, s13, v36
	s_nop 1
	v_cndmask_b32_e32 v36, v36, v37, vcc
	v_rsq_f32_e32 v36, v36
	s_nop 0
	v_mul_f32_e32 v37, 0x45800000, v36
	v_cndmask_b32_e32 v36, v36, v37, vcc
	v_pk_mul_f32 v[32:33], v[32:33], v[36:37] op_sel_hi:[1,0]
	v_pk_mul_f32 v[34:35], v[34:35], v[36:37] op_sel_hi:[1,0]
	v_pk_fma_f32 v[32:33], v[4:5], v[32:33], v[0:1]
	v_pk_fma_f32 v[34:35], v[6:7], v[34:35], v[2:3]
	v_pk_fma_f32 v[32:33], v[96:97], v[38:39], v[32:33] op_sel_hi:[0,1,1]
	v_lshlrev_b32_e32 v38, 16, v101
	v_and_b32_e32 v39, 0xffff0000, v101
	v_pk_fma_f32 v[34:35], v[96:97], v[38:39], v[34:35] op_sel_hi:[0,1,1]
	v_pk_mul_f32 v[32:33], v[32:33], v[102:103]
	v_pk_mul_f32 v[34:35], v[34:35], v[98:99]
	v_cvt_pk_bf16_f32 v32, v32, v33
	v_cvt_pk_bf16_f32 v33, v34, v35
	v_lshl_add_u64 v[34:35], s[2:3], 0, v[194:195]
	v_add_co_u32_e32 v34, vcc, 0x2040000, v34
	s_nop 1
	v_addc_co_u32_e32 v35, vcc, 0, v35, vcc
	global_store_dwordx2 v[34:35], v[32:33], off offset:512
.LBB0_674:
	s_andn2_b64 vcc, exec, s[18:19]
	v_readlane_b32 s80, v255, 16
	v_readlane_b32 s76, v255, 4
	v_readlane_b32 s73, v255, 5
	v_readlane_b32 s81, v255, 17
	s_cbranch_vccnz .LBB0_684
	v_mov_b32_e32 v32, v29
	v_mov_b32_e32 v33, v30
	v_mov_b32_e32 v34, v28
	v_mov_b32_e32 v35, v31
	v_pk_add_f32 v[32:33], v[32:33], v[34:35]
	s_mul_hi_i32 s3, s10, 0x1400
	v_add_f32_e32 v32, v32, v33
	s_mulk_i32 s10, 0x1400
	s_add_u32 s2, s0, s10
	v_add_f32_dpp v32, v32, v32 quad_perm:[1,0,3,2] row_mask:0xf bank_mask:0xf bound_ctrl:1
	s_addc_u32 s3, s1, s3
	s_nop 0
	v_add_f32_dpp v32, v32, v32 quad_perm:[2,3,0,1] row_mask:0xf bank_mask:0xf bound_ctrl:1
	s_nop 1
	v_add_f32_dpp v32, v32, v32 row_half_mirror row_mask:0xf bank_mask:0xf bound_ctrl:1
	s_nop 1
	v_add_f32_dpp v32, v32, v32 row_mirror row_mask:0xf bank_mask:0xf bound_ctrl:1
	v_fmamk_f32 v29, v32, 0xbc800000, v29
	v_fmamk_f32 v28, v32, 0xbc800000, v28
	v_fmamk_f32 v31, v32, 0xbc800000, v31
	v_fmac_f32_e32 v30, 0xbc800000, v32
	v_pk_mul_f32 v[32:33], v[30:31], v[30:31]
	v_pk_mul_f32 v[34:35], v[28:29], v[28:29]
	s_nop 0
	v_pk_mov_b32 v[36:37], v[34:35], v[32:33] op_sel:[1,0]
	v_mov_b32_e32 v35, v33
	v_pk_add_f32 v[32:33], v[36:37], v[34:35]
	v_lshlrev_b32_e32 v34, 16, v92
	v_add_f32_e32 v32, v32, v33
	v_and_b32_e32 v35, 0xffff0000, v92
	v_lshlrev_b32_e32 v36, 16, v94
	v_add_f32_dpp v32, v32, v32 quad_perm:[1,0,3,2] row_mask:0xf bank_mask:0xf bound_ctrl:1
	v_and_b32_e32 v37, 0xffff0000, v94
	s_nop 0
	v_add_f32_dpp v32, v32, v32 quad_perm:[2,3,0,1] row_mask:0xf bank_mask:0xf bound_ctrl:1
	s_nop 1
	v_add_f32_dpp v32, v32, v32 row_half_mirror row_mask:0xf bank_mask:0xf bound_ctrl:1
	s_nop 1
	v_add_f32_dpp v32, v32, v32 row_mirror row_mask:0xf bank_mask:0xf bound_ctrl:1
	v_fmamk_f32 v32, v32, 0x3c800000, v239
	v_mul_f32_e32 v33, 0x4b800000, v32
	v_cmp_gt_f32_e32 vcc, s13, v32
	s_nop 1
	v_cndmask_b32_e32 v32, v32, v33, vcc
	v_rsq_f32_e32 v32, v32
	s_nop 0
	v_mul_f32_e32 v33, 0x45800000, v32
	v_cndmask_b32_e32 v32, v32, v33, vcc
	v_pk_mul_f32 v[28:29], v[28:29], v[32:33] op_sel_hi:[1,0]
	v_pk_mul_f32 v[30:31], v[30:31], v[32:33] op_sel_hi:[1,0]
	v_pk_fma_f32 v[28:29], v[4:5], v[28:29], v[0:1]
	v_pk_fma_f32 v[30:31], v[6:7], v[30:31], v[2:3]
	v_pk_fma_f32 v[28:29], v[90:91], v[34:35], v[28:29] op_sel_hi:[0,1,1]
	v_lshlrev_b32_e32 v34, 16, v93
	v_and_b32_e32 v35, 0xffff0000, v93
	v_pk_mul_f32 v[28:29], v[28:29], v[36:37]
	v_lshlrev_b32_e32 v36, 16, v95
	v_and_b32_e32 v37, 0xffff0000, v95
	v_pk_fma_f32 v[30:31], v[90:91], v[34:35], v[30:31] op_sel_hi:[0,1,1]
	v_pk_mul_f32 v[30:31], v[30:31], v[36:37]
	v_cvt_pk_bf16_f32 v28, v28, v29
	v_cvt_pk_bf16_f32 v29, v30, v31
	v_lshl_add_u64 v[30:31], s[2:3], 0, v[194:195]
	v_add_co_u32_e32 v30, vcc, 0x2040000, v30
	s_nop 1
	v_addc_co_u32_e32 v31, vcc, 0, v31, vcc
	global_store_dwordx2 v[30:31], v[28:29], off offset:512
	s_andn2_b64 vcc, exec, s[16:17]
	s_cbranch_vccz .LBB0_685

.LBB0_677:
	v_mov_b32_e32 v24, v21
	v_mov_b32_e32 v25, v22
	v_mov_b32_e32 v26, v20
	v_mov_b32_e32 v27, v23
	v_pk_add_f32 v[24:25], v[24:25], v[26:27]
	s_mul_hi_i32 s3, s90, 0x1400
	v_add_f32_e32 v24, v24, v25
	s_mulk_i32 s90, 0x1400
	s_add_u32 s2, s0, s90
	v_add_f32_dpp v24, v24, v24 quad_perm:[1,0,3,2] row_mask:0xf bank_mask:0xf bound_ctrl:1
	s_addc_u32 s3, s1, s3
	s_nop 0
	v_add_f32_dpp v24, v24, v24 quad_perm:[2,3,0,1] row_mask:0xf bank_mask:0xf bound_ctrl:1
	s_nop 1
	v_add_f32_dpp v24, v24, v24 row_half_mirror row_mask:0xf bank_mask:0xf bound_ctrl:1
	s_nop 1
	v_add_f32_dpp v24, v24, v24 row_mirror row_mask:0xf bank_mask:0xf bound_ctrl:1
	v_fmamk_f32 v21, v24, 0xbc800000, v21
	v_fmamk_f32 v20, v24, 0xbc800000, v20
	v_fmamk_f32 v23, v24, 0xbc800000, v23
	v_fmac_f32_e32 v22, 0xbc800000, v24
	v_pk_mul_f32 v[24:25], v[22:23], v[22:23]
	v_pk_mul_f32 v[26:27], v[20:21], v[20:21]
	s_nop 0
	v_pk_mov_b32 v[28:29], v[26:27], v[24:25] op_sel:[1,0]
	v_mov_b32_e32 v27, v25
	v_pk_add_f32 v[24:25], v[28:29], v[26:27]
	v_lshlrev_b32_e32 v26, 16, v82
	v_add_f32_e32 v24, v24, v25
	v_and_b32_e32 v27, 0xffff0000, v82
	v_lshlrev_b32_e32 v28, 16, v80
	v_add_f32_dpp v24, v24, v24 quad_perm:[1,0,3,2] row_mask:0xf bank_mask:0xf bound_ctrl:1
	v_and_b32_e32 v29, 0xffff0000, v80
	s_nop 0
	v_add_f32_dpp v24, v24, v24 quad_perm:[2,3,0,1] row_mask:0xf bank_mask:0xf bound_ctrl:1
	s_nop 1
	v_add_f32_dpp v24, v24, v24 row_half_mirror row_mask:0xf bank_mask:0xf bound_ctrl:1
	s_nop 1
	v_add_f32_dpp v24, v24, v24 row_mirror row_mask:0xf bank_mask:0xf bound_ctrl:1
	v_fmamk_f32 v24, v24, 0x3c800000, v239
	v_mul_f32_e32 v25, 0x4b800000, v24
	v_cmp_gt_f32_e32 vcc, s13, v24
	s_nop 1
	v_cndmask_b32_e32 v24, v24, v25, vcc
	v_rsq_f32_e32 v24, v24
	s_nop 0
	v_mul_f32_e32 v25, 0x45800000, v24
	v_cndmask_b32_e32 v24, v24, v25, vcc
	v_pk_mul_f32 v[20:21], v[20:21], v[24:25] op_sel_hi:[1,0]
	v_pk_mul_f32 v[22:23], v[22:23], v[24:25] op_sel_hi:[1,0]
	v_pk_fma_f32 v[20:21], v[4:5], v[20:21], v[0:1]
	v_pk_fma_f32 v[22:23], v[6:7], v[22:23], v[2:3]
	v_pk_fma_f32 v[20:21], v[78:79], v[26:27], v[20:21] op_sel_hi:[0,1,1]
	v_lshlrev_b32_e32 v26, 16, v83
	v_and_b32_e32 v27, 0xffff0000, v83
	v_pk_mul_f32 v[20:21], v[20:21], v[28:29]
	v_lshlrev_b32_e32 v28, 16, v81
	v_and_b32_e32 v29, 0xffff0000, v81
	v_pk_fma_f32 v[22:23], v[78:79], v[26:27], v[22:23] op_sel_hi:[0,1,1]
	v_pk_mul_f32 v[22:23], v[22:23], v[28:29]
	v_cvt_pk_bf16_f32 v20, v20, v21
	v_cvt_pk_bf16_f32 v21, v22, v23
	v_lshl_add_u64 v[22:23], s[2:3], 0, v[194:195]
	v_add_co_u32_e32 v22, vcc, 0x2040000, v22
	s_nop 1
	v_addc_co_u32_e32 v23, vcc, 0, v23, vcc
	global_store_dwordx2 v[22:23], v[20:21], off offset:512
.LBB0_678:
	v_readlane_b32 s2, v255, 29
	v_readlane_b32 s3, v255, 30
	s_andn2_b64 vcc, exec, s[2:3]
	s_cbranch_vccnz .LBB0_680
	v_mov_b32_e32 v20, v17
	v_mov_b32_e32 v21, v18
	v_mov_b32_e32 v22, v16
	v_mov_b32_e32 v23, v19
	v_pk_add_f32 v[20:21], v[20:21], v[22:23]
	s_mul_hi_i32 s3, s89, 0x1400
	v_add_f32_e32 v20, v20, v21
	s_mulk_i32 s89, 0x1400
	s_add_u32 s2, s0, s89
	v_add_f32_dpp v20, v20, v20 quad_perm:[1,0,3,2] row_mask:0xf bank_mask:0xf bound_ctrl:1
	s_addc_u32 s3, s1, s3
	s_nop 0
	v_add_f32_dpp v20, v20, v20 quad_perm:[2,3,0,1] row_mask:0xf bank_mask:0xf bound_ctrl:1
	s_nop 1
	v_add_f32_dpp v20, v20, v20 row_half_mirror row_mask:0xf bank_mask:0xf bound_ctrl:1
	s_nop 1
	v_add_f32_dpp v20, v20, v20 row_mirror row_mask:0xf bank_mask:0xf bound_ctrl:1
	v_fmamk_f32 v17, v20, 0xbc800000, v17
	v_fmamk_f32 v16, v20, 0xbc800000, v16
	v_fmamk_f32 v19, v20, 0xbc800000, v19
	v_fmac_f32_e32 v18, 0xbc800000, v20
	v_pk_mul_f32 v[20:21], v[18:19], v[18:19]
	v_pk_mul_f32 v[22:23], v[16:17], v[16:17]
	s_nop 0
	v_pk_mov_b32 v[24:25], v[22:23], v[20:21] op_sel:[1,0]
	v_mov_b32_e32 v23, v21
	v_pk_add_f32 v[20:21], v[24:25], v[22:23]
	v_lshlrev_b32_e32 v22, 16, v76
	v_add_f32_e32 v20, v20, v21
	v_and_b32_e32 v23, 0xffff0000, v76
	v_lshlrev_b32_e32 v24, 16, v74
	v_add_f32_dpp v20, v20, v20 quad_perm:[1,0,3,2] row_mask:0xf bank_mask:0xf bound_ctrl:1
	v_and_b32_e32 v25, 0xffff0000, v74
	s_nop 0
	v_add_f32_dpp v20, v20, v20 quad_perm:[2,3,0,1] row_mask:0xf bank_mask:0xf bound_ctrl:1
	s_nop 1
	v_add_f32_dpp v20, v20, v20 row_half_mirror row_mask:0xf bank_mask:0xf bound_ctrl:1
	s_nop 1
	v_add_f32_dpp v20, v20, v20 row_mirror row_mask:0xf bank_mask:0xf bound_ctrl:1
	v_fmamk_f32 v20, v20, 0x3c800000, v239
	v_mul_f32_e32 v21, 0x4b800000, v20
	v_cmp_gt_f32_e32 vcc, s13, v20
	s_nop 1
	v_cndmask_b32_e32 v20, v20, v21, vcc
	v_rsq_f32_e32 v20, v20
	s_nop 0
	v_mul_f32_e32 v21, 0x45800000, v20
	v_cndmask_b32_e32 v20, v20, v21, vcc
	v_pk_mul_f32 v[16:17], v[16:17], v[20:21] op_sel_hi:[1,0]
	v_pk_mul_f32 v[18:19], v[18:19], v[20:21] op_sel_hi:[1,0]
	v_pk_fma_f32 v[16:17], v[4:5], v[16:17], v[0:1]
	v_pk_fma_f32 v[18:19], v[6:7], v[18:19], v[2:3]
	v_pk_fma_f32 v[16:17], v[72:73], v[22:23], v[16:17] op_sel_hi:[0,1,1]
	v_lshlrev_b32_e32 v22, 16, v77
	v_and_b32_e32 v23, 0xffff0000, v77
	v_pk_mul_f32 v[16:17], v[16:17], v[24:25]
	v_lshlrev_b32_e32 v24, 16, v75
	v_and_b32_e32 v25, 0xffff0000, v75
	v_pk_fma_f32 v[18:19], v[72:73], v[22:23], v[18:19] op_sel_hi:[0,1,1]
	v_pk_mul_f32 v[18:19], v[18:19], v[24:25]
	v_cvt_pk_bf16_f32 v16, v16, v17
	v_cvt_pk_bf16_f32 v17, v18, v19
	v_lshl_add_u64 v[18:19], s[2:3], 0, v[194:195]
	v_add_co_u32_e32 v18, vcc, 0x2040000, v18
	s_nop 1
	v_addc_co_u32_e32 v19, vcc, 0, v19, vcc
	global_store_dwordx2 v[18:19], v[16:17], off offset:512
.LBB0_680:
	v_readlane_b32 s2, v255, 41
	v_readlane_b32 s3, v255, 42
	s_andn2_b64 vcc, exec, s[2:3]
	s_cbranch_vccnz .LBB0_682
	v_mov_b32_e32 v16, v13
	v_mov_b32_e32 v17, v14
	v_mov_b32_e32 v18, v12
	v_mov_b32_e32 v19, v15
	v_pk_add_f32 v[16:17], v[16:17], v[18:19]
	s_mul_hi_i32 s3, s42, 0x1400
	v_add_f32_e32 v16, v16, v17
	s_mulk_i32 s42, 0x1400
	s_add_u32 s2, s0, s42
	v_add_f32_dpp v16, v16, v16 quad_perm:[1,0,3,2] row_mask:0xf bank_mask:0xf bound_ctrl:1
	s_addc_u32 s3, s1, s3
	s_nop 0
	v_add_f32_dpp v16, v16, v16 quad_perm:[2,3,0,1] row_mask:0xf bank_mask:0xf bound_ctrl:1
	s_nop 1
	v_add_f32_dpp v16, v16, v16 row_half_mirror row_mask:0xf bank_mask:0xf bound_ctrl:1
	s_nop 1
	v_add_f32_dpp v16, v16, v16 row_mirror row_mask:0xf bank_mask:0xf bound_ctrl:1
	v_fmamk_f32 v13, v16, 0xbc800000, v13
	v_fmamk_f32 v12, v16, 0xbc800000, v12
	v_fmamk_f32 v15, v16, 0xbc800000, v15
	v_fmac_f32_e32 v14, 0xbc800000, v16
	v_pk_mul_f32 v[16:17], v[14:15], v[14:15]
	v_pk_mul_f32 v[18:19], v[12:13], v[12:13]
	s_nop 0
	v_pk_mov_b32 v[20:21], v[18:19], v[16:17] op_sel:[1,0]
	v_mov_b32_e32 v19, v17
	v_pk_add_f32 v[16:17], v[20:21], v[18:19]
	v_lshlrev_b32_e32 v18, 16, v70
	v_add_f32_e32 v16, v16, v17
	v_and_b32_e32 v19, 0xffff0000, v70
	v_lshlrev_b32_e32 v20, 16, v68
	v_add_f32_dpp v16, v16, v16 quad_perm:[1,0,3,2] row_mask:0xf bank_mask:0xf bound_ctrl:1
	v_and_b32_e32 v21, 0xffff0000, v68
	s_nop 0
	v_add_f32_dpp v16, v16, v16 quad_perm:[2,3,0,1] row_mask:0xf bank_mask:0xf bound_ctrl:1
	s_nop 1
	v_add_f32_dpp v16, v16, v16 row_half_mirror row_mask:0xf bank_mask:0xf bound_ctrl:1
	s_nop 1
	v_add_f32_dpp v16, v16, v16 row_mirror row_mask:0xf bank_mask:0xf bound_ctrl:1
	v_fmamk_f32 v16, v16, 0x3c800000, v239
	v_mul_f32_e32 v17, 0x4b800000, v16
	v_cmp_gt_f32_e32 vcc, s13, v16
	s_nop 1
	v_cndmask_b32_e32 v16, v16, v17, vcc
	v_rsq_f32_e32 v16, v16
	s_nop 0
	v_mul_f32_e32 v17, 0x45800000, v16
	v_cndmask_b32_e32 v16, v16, v17, vcc
	v_pk_mul_f32 v[12:13], v[12:13], v[16:17] op_sel_hi:[1,0]
	v_pk_mul_f32 v[14:15], v[14:15], v[16:17] op_sel_hi:[1,0]
	v_pk_fma_f32 v[12:13], v[4:5], v[12:13], v[0:1]
	v_pk_fma_f32 v[14:15], v[6:7], v[14:15], v[2:3]
	v_pk_fma_f32 v[12:13], v[66:67], v[18:19], v[12:13] op_sel_hi:[0,1,1]
	v_lshlrev_b32_e32 v18, 16, v71
	v_and_b32_e32 v19, 0xffff0000, v71
	v_pk_mul_f32 v[12:13], v[12:13], v[20:21]
	v_lshlrev_b32_e32 v20, 16, v69
	v_and_b32_e32 v21, 0xffff0000, v69
	v_pk_fma_f32 v[14:15], v[66:67], v[18:19], v[14:15] op_sel_hi:[0,1,1]
	v_pk_mul_f32 v[14:15], v[14:15], v[20:21]
	v_cvt_pk_bf16_f32 v12, v12, v13
	v_cvt_pk_bf16_f32 v13, v14, v15
	v_lshl_add_u64 v[14:15], s[2:3], 0, v[194:195]
	v_add_co_u32_e32 v14, vcc, 0x2040000, v14
	s_nop 1
	v_addc_co_u32_e32 v15, vcc, 0, v15, vcc
	global_store_dwordx2 v[14:15], v[12:13], off offset:512
.LBB0_682:
	s_andn2_b64 vcc, exec, s[4:5]
	s_cbranch_vccnz .LBB0_669
	v_mov_b32_e32 v12, v9
	v_mov_b32_e32 v13, v10
	v_mov_b32_e32 v14, v8
	v_mov_b32_e32 v15, v11
	v_pk_add_f32 v[12:13], v[12:13], v[14:15]
	s_mul_hi_i32 s3, s9, 0x1400
	v_add_f32_e32 v12, v12, v13
	s_mulk_i32 s9, 0x1400
	s_add_u32 s2, s0, s9
	v_add_f32_dpp v12, v12, v12 quad_perm:[1,0,3,2] row_mask:0xf bank_mask:0xf bound_ctrl:1
	s_addc_u32 s3, s1, s3
	s_nop 0
	v_add_f32_dpp v12, v12, v12 quad_perm:[2,3,0,1] row_mask:0xf bank_mask:0xf bound_ctrl:1
	s_nop 1
	v_add_f32_dpp v12, v12, v12 row_half_mirror row_mask:0xf bank_mask:0xf bound_ctrl:1
	s_nop 1
	v_add_f32_dpp v12, v12, v12 row_mirror row_mask:0xf bank_mask:0xf bound_ctrl:1
	v_fmamk_f32 v9, v12, 0xbc800000, v9
	v_fmamk_f32 v8, v12, 0xbc800000, v8
	v_fmamk_f32 v11, v12, 0xbc800000, v11
	v_fmac_f32_e32 v10, 0xbc800000, v12
	v_pk_mul_f32 v[12:13], v[10:11], v[10:11]
	v_pk_mul_f32 v[14:15], v[8:9], v[8:9]
	s_nop 0
	v_pk_mov_b32 v[16:17], v[14:15], v[12:13] op_sel:[1,0]
	v_mov_b32_e32 v15, v13
	v_pk_add_f32 v[12:13], v[16:17], v[14:15]
	v_lshlrev_b32_e32 v14, 16, v64
	v_add_f32_e32 v12, v12, v13
	v_and_b32_e32 v15, 0xffff0000, v64
	v_lshlrev_b32_e32 v16, 16, v62
	v_add_f32_dpp v12, v12, v12 quad_perm:[1,0,3,2] row_mask:0xf bank_mask:0xf bound_ctrl:1
	v_and_b32_e32 v17, 0xffff0000, v62
	s_nop 0
	v_add_f32_dpp v12, v12, v12 quad_perm:[2,3,0,1] row_mask:0xf bank_mask:0xf bound_ctrl:1
	s_nop 1
	v_add_f32_dpp v12, v12, v12 row_half_mirror row_mask:0xf bank_mask:0xf bound_ctrl:1
	s_nop 1
	v_add_f32_dpp v12, v12, v12 row_mirror row_mask:0xf bank_mask:0xf bound_ctrl:1
	v_fmamk_f32 v12, v12, 0x3c800000, v239
	v_mul_f32_e32 v13, 0x4b800000, v12
	v_cmp_gt_f32_e32 vcc, s13, v12
	s_nop 1
	v_cndmask_b32_e32 v12, v12, v13, vcc
	v_rsq_f32_e32 v12, v12
	s_nop 0
	v_mul_f32_e32 v13, 0x45800000, v12
	v_cndmask_b32_e32 v12, v12, v13, vcc
	v_pk_mul_f32 v[8:9], v[8:9], v[12:13] op_sel_hi:[1,0]
	v_pk_mul_f32 v[10:11], v[10:11], v[12:13] op_sel_hi:[1,0]
	v_pk_fma_f32 v[8:9], v[4:5], v[8:9], v[0:1]
	v_pk_fma_f32 v[10:11], v[6:7], v[10:11], v[2:3]
	v_pk_fma_f32 v[8:9], v[60:61], v[14:15], v[8:9] op_sel_hi:[0,1,1]
	v_lshlrev_b32_e32 v14, 16, v65
	v_and_b32_e32 v15, 0xffff0000, v65
	v_pk_mul_f32 v[8:9], v[8:9], v[16:17]
	v_lshlrev_b32_e32 v16, 16, v63
	v_and_b32_e32 v17, 0xffff0000, v63
	v_pk_fma_f32 v[10:11], v[60:61], v[14:15], v[10:11] op_sel_hi:[0,1,1]
	v_pk_mul_f32 v[10:11], v[10:11], v[16:17]
	v_cvt_pk_bf16_f32 v8, v8, v9
	v_cvt_pk_bf16_f32 v9, v10, v11
	v_lshl_add_u64 v[10:11], s[2:3], 0, v[194:195]
	v_add_co_u32_e32 v10, vcc, 0x2040000, v10
	s_nop 1
	v_addc_co_u32_e32 v11, vcc, 0, v11, vcc
	global_store_dwordx2 v[10:11], v[8:9], off offset:512
	s_branch .LBB0_669

.LBB0_685:
	v_mov_b32_e32 v28, v25
	v_mov_b32_e32 v29, v26
	v_mov_b32_e32 v30, v24
	v_mov_b32_e32 v31, v27
	v_pk_add_f32 v[28:29], v[28:29], v[30:31]
	s_mul_hi_i32 s3, s91, 0x1400
	v_add_f32_e32 v28, v28, v29
	s_mulk_i32 s91, 0x1400
	s_add_u32 s2, s0, s91
	v_add_f32_dpp v28, v28, v28 quad_perm:[1,0,3,2] row_mask:0xf bank_mask:0xf bound_ctrl:1
	s_addc_u32 s3, s1, s3
	s_nop 0
	v_add_f32_dpp v28, v28, v28 quad_perm:[2,3,0,1] row_mask:0xf bank_mask:0xf bound_ctrl:1
	s_nop 1
	v_add_f32_dpp v28, v28, v28 row_half_mirror row_mask:0xf bank_mask:0xf bound_ctrl:1
	s_nop 1
	v_add_f32_dpp v28, v28, v28 row_mirror row_mask:0xf bank_mask:0xf bound_ctrl:1
	v_fmamk_f32 v25, v28, 0xbc800000, v25
	v_fmamk_f32 v24, v28, 0xbc800000, v24
	v_fmamk_f32 v27, v28, 0xbc800000, v27
	v_fmac_f32_e32 v26, 0xbc800000, v28
	v_pk_mul_f32 v[28:29], v[26:27], v[26:27]
	v_pk_mul_f32 v[30:31], v[24:25], v[24:25]
	s_nop 0
	v_pk_mov_b32 v[32:33], v[30:31], v[28:29] op_sel:[1,0]
	v_mov_b32_e32 v31, v29
	v_pk_add_f32 v[28:29], v[32:33], v[30:31]
	v_lshlrev_b32_e32 v30, 16, v84
	v_add_f32_e32 v28, v28, v29
	v_and_b32_e32 v31, 0xffff0000, v84
	v_lshlrev_b32_e32 v32, 16, v88
	v_add_f32_dpp v28, v28, v28 quad_perm:[1,0,3,2] row_mask:0xf bank_mask:0xf bound_ctrl:1
	v_and_b32_e32 v33, 0xffff0000, v88
	s_nop 0
	v_add_f32_dpp v28, v28, v28 quad_perm:[2,3,0,1] row_mask:0xf bank_mask:0xf bound_ctrl:1
	s_nop 1
	v_add_f32_dpp v28, v28, v28 row_half_mirror row_mask:0xf bank_mask:0xf bound_ctrl:1
	s_nop 1
	v_add_f32_dpp v28, v28, v28 row_mirror row_mask:0xf bank_mask:0xf bound_ctrl:1
	v_fmamk_f32 v28, v28, 0x3c800000, v239
	v_mul_f32_e32 v29, 0x4b800000, v28
	v_cmp_gt_f32_e32 vcc, s13, v28
	s_nop 1
	v_cndmask_b32_e32 v28, v28, v29, vcc
	v_rsq_f32_e32 v28, v28
	s_nop 0
	v_mul_f32_e32 v29, 0x45800000, v28
	v_cndmask_b32_e32 v28, v28, v29, vcc
	v_pk_mul_f32 v[24:25], v[24:25], v[28:29] op_sel_hi:[1,0]
	v_pk_mul_f32 v[26:27], v[26:27], v[28:29] op_sel_hi:[1,0]
	v_pk_fma_f32 v[24:25], v[4:5], v[24:25], v[0:1]
	v_pk_fma_f32 v[26:27], v[6:7], v[26:27], v[2:3]
	v_pk_fma_f32 v[24:25], v[86:87], v[30:31], v[24:25] op_sel_hi:[0,1,1]
	v_lshlrev_b32_e32 v30, 16, v85
	v_and_b32_e32 v31, 0xffff0000, v85
	v_pk_mul_f32 v[24:25], v[24:25], v[32:33]
	v_lshlrev_b32_e32 v32, 16, v89
	v_and_b32_e32 v33, 0xffff0000, v89
	v_pk_fma_f32 v[26:27], v[86:87], v[30:31], v[26:27] op_sel_hi:[0,1,1]
	v_pk_mul_f32 v[26:27], v[26:27], v[32:33]
	v_cvt_pk_bf16_f32 v24, v24, v25
	v_cvt_pk_bf16_f32 v25, v26, v27
	v_lshl_add_u64 v[26:27], s[2:3], 0, v[194:195]
	v_add_co_u32_e32 v26, vcc, 0x2040000, v26
	s_nop 1
	v_addc_co_u32_e32 v27, vcc, 0, v27, vcc
	global_store_dwordx2 v[26:27], v[24:25], off offset:512
	s_andn2_b64 vcc, exec, s[14:15]
	s_cbranch_vccz .LBB0_677
	s_branch .LBB0_678

.LBB0_763:
	s_add_u32 s0, s22, 0x100
	s_addc_u32 s1, s23, 0
	s_add_i32 s58, 0, 0x10000
	v_add_u32_e32 v140, s58, v246
	ds_read_b128 v[128:131], v140
	ds_read_b128 v[132:135], v140 offset:1024
	ds_read_b128 v[136:139], v140 offset:2048
	ds_read_b128 v[140:143], v140 offset:3072
	s_cmp_eq_u32 s57, 12
	s_cselect_b32 s7, s19, s1
	s_cselect_b32 s6, s18, s0
	s_cselect_b32 s3, s17, s56
	s_cselect_b32 s2, s40, s41
	v_lshl_add_u64 v[176:177], s[22:23], 0, v[214:215]
	s_add_i32 m0, s28, 0xc000
	ds_read_b128 v[144:147], v248
	ds_read_b128 v[148:151], v248 offset:1024
	ds_read_b128 v[152:155], v248 offset:2048
	ds_read_b128 v[156:159], v248 offset:3072
	ds_read_b128 v[160:163], v248 offset:4096
	ds_read_b128 v[164:167], v248 offset:5120
	ds_read_b128 v[168:171], v248 offset:6144
	ds_read_b128 v[172:175], v248 offset:7168
	global_load_lds_dwordx4 v[176:177], off
	v_lshl_add_u64 v[176:177], s[22:23], 0, v[212:213]
	s_add_i32 m0, s28, 0xe000
	s_nop 0
	global_load_lds_dwordx4 v[176:177], off
	s_waitcnt lgkmcnt(8)
	s_barrier
	s_waitcnt lgkmcnt(0)
	s_setprio 1
	s_waitcnt lgkmcnt(0)
	v_mfma_f32_16x16x32_bf16 v[124:127], v[128:131], v[144:147], v[124:127]
	v_mfma_f32_16x16x32_bf16 v[120:123], v[136:139], v[144:147], v[120:123]
	v_mfma_f32_16x16x32_bf16 v[100:103], v[128:131], v[152:155], v[100:103]
	v_mfma_f32_16x16x32_bf16 v[96:99], v[136:139], v[152:155], v[96:99]
	v_mfma_f32_16x16x32_bf16 v[84:87], v[128:131], v[160:163], v[84:87]
	v_mfma_f32_16x16x32_bf16 v[80:83], v[136:139], v[160:163], v[80:83]
	v_mfma_f32_16x16x32_bf16 v[68:71], v[128:131], v[168:171], v[68:71]
	v_mfma_f32_16x16x32_bf16 v[60:63], v[136:139], v[168:171], v[60:63]
	v_mfma_f32_16x16x32_bf16 v[124:127], v[132:135], v[148:151], v[124:127]
	v_mfma_f32_16x16x32_bf16 v[120:123], v[140:143], v[148:151], v[120:123]
	v_mfma_f32_16x16x32_bf16 v[100:103], v[132:135], v[156:159], v[100:103]
	v_mfma_f32_16x16x32_bf16 v[96:99], v[140:143], v[156:159], v[96:99]
	v_mfma_f32_16x16x32_bf16 v[84:87], v[132:135], v[164:167], v[84:87]
	v_mfma_f32_16x16x32_bf16 v[80:83], v[140:143], v[164:167], v[80:83]
	v_mfma_f32_16x16x32_bf16 v[68:71], v[132:135], v[172:175], v[68:71]
	v_mfma_f32_16x16x32_bf16 v[60:63], v[140:143], v[172:175], v[60:63]
	s_setprio 0
	s_barrier
	s_add_i32 s59, 0, 0x14000
	s_add_i32 s22, s58, s27
	v_add_u32_e32 v188, s59, v246
	v_lshl_add_u64 v[202:203], s[2:3], 0, v[194:195]
	s_mov_b32 m0, s22
	ds_read_b128 v[176:179], v188
	ds_read_b128 v[180:183], v188 offset:1024
	ds_read_b128 v[184:187], v188 offset:2048
	ds_read_b128 v[188:191], v188 offset:3072
	global_load_lds_dwordx4 v[202:203], off
	v_lshl_add_u64 v[216:217], s[2:3], 0, v[206:207]
	s_add_i32 m0, s22, 0x2000
	s_nop 0
	global_load_lds_dwordx4 v[216:217], off
	s_barrier
	s_waitcnt lgkmcnt(0)
	s_setprio 1
	s_waitcnt lgkmcnt(0)
	v_mfma_f32_16x16x32_bf16 v[116:119], v[176:179], v[144:147], v[116:119]
	v_mfma_f32_16x16x32_bf16 v[112:115], v[184:187], v[144:147], v[112:115]
	v_mfma_f32_16x16x32_bf16 v[108:111], v[176:179], v[152:155], v[108:111]
	v_mfma_f32_16x16x32_bf16 v[104:107], v[184:187], v[152:155], v[104:107]
	v_mfma_f32_16x16x32_bf16 v[92:95], v[176:179], v[160:163], v[92:95]
	v_mfma_f32_16x16x32_bf16 v[88:91], v[184:187], v[160:163], v[88:91]
	v_mfma_f32_16x16x32_bf16 v[76:79], v[176:179], v[168:171], v[76:79]
	v_mfma_f32_16x16x32_bf16 v[72:75], v[184:187], v[168:171], v[72:75]
	v_mfma_f32_16x16x32_bf16 v[116:119], v[180:183], v[148:151], v[116:119]
	v_mfma_f32_16x16x32_bf16 v[112:115], v[188:191], v[148:151], v[112:115]
	v_mfma_f32_16x16x32_bf16 v[108:111], v[180:183], v[156:159], v[108:111]
	v_mfma_f32_16x16x32_bf16 v[104:107], v[188:191], v[156:159], v[104:107]
	v_mfma_f32_16x16x32_bf16 v[92:95], v[180:183], v[164:167], v[92:95]
	v_mfma_f32_16x16x32_bf16 v[88:91], v[188:191], v[164:167], v[88:91]
	v_mfma_f32_16x16x32_bf16 v[76:79], v[180:183], v[172:175], v[76:79]
	v_mfma_f32_16x16x32_bf16 v[72:75], v[188:191], v[172:175], v[72:75]
	s_setprio 0
	s_mov_b32 m0, s28
	v_lshl_add_u64 v[218:219], s[6:7], 0, v[210:211]
	s_barrier
	ds_read_b128 v[144:147], v248 offset:16384
	ds_read_b128 v[148:151], v248 offset:17408
	ds_read_b128 v[152:155], v248 offset:18432
	ds_read_b128 v[156:159], v248 offset:19456
	ds_read_b128 v[160:163], v248 offset:20480
	ds_read_b128 v[164:167], v248 offset:21504
	ds_read_b128 v[168:171], v248 offset:22528
	ds_read_b128 v[172:175], v248 offset:23552
	global_load_lds_dwordx4 v[218:219], off
	v_lshl_add_u64 v[220:221], s[6:7], 0, v[208:209]
	s_mov_b32 m0, s29
	s_nop 0
	global_load_lds_dwordx4 v[220:221], off
	s_barrier
	s_waitcnt lgkmcnt(0)
	s_setprio 1
	s_waitcnt lgkmcnt(0)
	v_mfma_f32_16x16x32_bf16 v[52:55], v[128:131], v[144:147], v[52:55]
	v_mfma_f32_16x16x32_bf16 v[48:51], v[136:139], v[144:147], v[48:51]
	v_mfma_f32_16x16x32_bf16 v[36:39], v[128:131], v[152:155], v[36:39]
	v_mfma_f32_16x16x32_bf16 v[32:35], v[136:139], v[152:155], v[32:35]
	v_mfma_f32_16x16x32_bf16 v[20:23], v[128:131], v[160:163], v[20:23]
	v_mfma_f32_16x16x32_bf16 v[16:19], v[136:139], v[160:163], v[16:19]
	v_mfma_f32_16x16x32_bf16 v[4:7], v[128:131], v[168:171], v[4:7]
	v_mfma_f32_16x16x32_bf16 v[0:3], v[136:139], v[168:171], v[0:3]
	v_mfma_f32_16x16x32_bf16 v[52:55], v[132:135], v[148:151], v[52:55]
	v_mfma_f32_16x16x32_bf16 v[48:51], v[140:143], v[148:151], v[48:51]
	v_mfma_f32_16x16x32_bf16 v[36:39], v[132:135], v[156:159], v[36:39]
	v_mfma_f32_16x16x32_bf16 v[32:35], v[140:143], v[156:159], v[32:35]
	v_mfma_f32_16x16x32_bf16 v[20:23], v[132:135], v[164:167], v[20:23]
	v_mfma_f32_16x16x32_bf16 v[16:19], v[140:143], v[164:167], v[16:19]
	v_mfma_f32_16x16x32_bf16 v[4:7], v[132:135], v[172:175], v[4:7]
	v_mfma_f32_16x16x32_bf16 v[0:3], v[140:143], v[172:175], v[0:3]
	s_setprio 0
	s_barrier
	s_add_u32 s22, s2, 0x40000
	s_addc_u32 s23, s3, 0
	s_add_i32 s58, s59, s27
	v_lshl_add_u64 v[128:129], s[22:23], 0, v[194:195]
	s_mov_b32 m0, s58
	s_nop 0
	global_load_lds_dwordx4 v[128:129], off
	v_lshl_add_u64 v[128:129], s[22:23], 0, v[206:207]
	s_add_i32 m0, s58, 0x2000
	s_nop 0
	global_load_lds_dwordx4 v[128:129], off
	s_waitcnt vmcnt(6)
	s_barrier
	s_setprio 1
	v_mfma_f32_16x16x32_bf16 v[64:67], v[176:179], v[144:147], v[64:67]
	v_mfma_f32_16x16x32_bf16 v[56:59], v[184:187], v[144:147], v[56:59]
	v_mfma_f32_16x16x32_bf16 v[44:47], v[176:179], v[152:155], v[44:47]
	v_mfma_f32_16x16x32_bf16 v[40:43], v[184:187], v[152:155], v[40:43]
	v_mfma_f32_16x16x32_bf16 v[28:31], v[176:179], v[160:163], v[28:31]
	v_mfma_f32_16x16x32_bf16 v[24:27], v[184:187], v[160:163], v[24:27]
	v_mfma_f32_16x16x32_bf16 v[12:15], v[176:179], v[168:171], v[12:15]
	v_mfma_f32_16x16x32_bf16 v[8:11], v[184:187], v[168:171], v[8:11]
	v_mfma_f32_16x16x32_bf16 v[64:67], v[180:183], v[148:151], v[64:67]
	v_mfma_f32_16x16x32_bf16 v[56:59], v[188:191], v[148:151], v[56:59]
	v_mfma_f32_16x16x32_bf16 v[44:47], v[180:183], v[156:159], v[44:47]
	v_mfma_f32_16x16x32_bf16 v[40:43], v[188:191], v[156:159], v[40:43]
	v_mfma_f32_16x16x32_bf16 v[28:31], v[180:183], v[164:167], v[28:31]
	v_mfma_f32_16x16x32_bf16 v[24:27], v[188:191], v[164:167], v[24:27]
	v_mfma_f32_16x16x32_bf16 v[12:15], v[180:183], v[172:175], v[12:15]
	v_mfma_f32_16x16x32_bf16 v[8:11], v[188:191], v[172:175], v[8:11]
	s_setprio 0
	s_add_i32 s22, 0, 0x18000
	v_add_u32_e32 v140, s22, v246
	s_barrier
	ds_read_b128 v[128:131], v140
	ds_read_b128 v[132:135], v140 offset:1024
	ds_read_b128 v[136:139], v140 offset:2048
	ds_read_b128 v[140:143], v140 offset:3072
	s_add_u32 s6, s6, 0xa0000
	s_addc_u32 s7, s7, 0
	s_mov_b32 m0, s30
	v_lshl_add_u64 v[176:177], s[6:7], 0, v[210:211]
	ds_read_b128 v[144:147], v248 offset:32768
	ds_read_b128 v[148:151], v248 offset:33792
	ds_read_b128 v[152:155], v248 offset:34816
	ds_read_b128 v[156:159], v248 offset:35840
	ds_read_b128 v[160:163], v248 offset:36864
	ds_read_b128 v[164:167], v248 offset:37888
	ds_read_b128 v[168:171], v248 offset:38912
	ds_read_b128 v[172:175], v248 offset:39936
	global_load_lds_dwordx4 v[176:177], off
	v_lshl_add_u64 v[176:177], s[6:7], 0, v[208:209]
	s_mov_b32 m0, s31
	s_nop 0
	global_load_lds_dwordx4 v[176:177], off
	s_waitcnt lgkmcnt(8)
	s_barrier
	s_waitcnt lgkmcnt(0)
	s_setprio 1
	s_waitcnt lgkmcnt(0)
	v_mfma_f32_16x16x32_bf16 v[124:127], v[128:131], v[144:147], v[124:127]
	v_mfma_f32_16x16x32_bf16 v[120:123], v[136:139], v[144:147], v[120:123]
	v_mfma_f32_16x16x32_bf16 v[100:103], v[128:131], v[152:155], v[100:103]
	v_mfma_f32_16x16x32_bf16 v[96:99], v[136:139], v[152:155], v[96:99]
	v_mfma_f32_16x16x32_bf16 v[84:87], v[128:131], v[160:163], v[84:87]
	v_mfma_f32_16x16x32_bf16 v[80:83], v[136:139], v[160:163], v[80:83]
	v_mfma_f32_16x16x32_bf16 v[68:71], v[128:131], v[168:171], v[68:71]
	v_mfma_f32_16x16x32_bf16 v[60:63], v[136:139], v[168:171], v[60:63]
	v_mfma_f32_16x16x32_bf16 v[124:127], v[132:135], v[148:151], v[124:127]
	v_mfma_f32_16x16x32_bf16 v[120:123], v[140:143], v[148:151], v[120:123]
	v_mfma_f32_16x16x32_bf16 v[100:103], v[132:135], v[156:159], v[100:103]
	v_mfma_f32_16x16x32_bf16 v[96:99], v[140:143], v[156:159], v[96:99]
	v_mfma_f32_16x16x32_bf16 v[84:87], v[132:135], v[164:167], v[84:87]
	v_mfma_f32_16x16x32_bf16 v[80:83], v[140:143], v[164:167], v[80:83]
	v_mfma_f32_16x16x32_bf16 v[68:71], v[132:135], v[172:175], v[68:71]
	v_mfma_f32_16x16x32_bf16 v[60:63], v[140:143], v[172:175], v[60:63]
	s_setprio 0
	s_barrier
	s_add_i32 s6, 0, 0x1c000
	s_add_i32 s7, s22, s27
	v_add_u32_e32 v188, s6, v246
	v_lshl_add_u64 v[202:203], v[202:203], 0, s[70:71]
	s_mov_b32 m0, s7
	ds_read_b128 v[176:179], v188
	ds_read_b128 v[180:183], v188 offset:1024
	ds_read_b128 v[184:187], v188 offset:2048
	ds_read_b128 v[188:191], v188 offset:3072
	global_load_lds_dwordx4 v[202:203], off
	v_lshl_add_u64 v[202:203], v[216:217], 0, s[70:71]
	s_add_i32 m0, s7, 0x2000
	s_nop 0
	global_load_lds_dwordx4 v[202:203], off
	s_barrier
	s_waitcnt lgkmcnt(0)
	s_setprio 1
	s_waitcnt lgkmcnt(0)
	v_mfma_f32_16x16x32_bf16 v[116:119], v[176:179], v[144:147], v[116:119]
	v_mfma_f32_16x16x32_bf16 v[112:115], v[184:187], v[144:147], v[112:115]
	v_mfma_f32_16x16x32_bf16 v[108:111], v[176:179], v[152:155], v[108:111]
	v_mfma_f32_16x16x32_bf16 v[104:107], v[184:187], v[152:155], v[104:107]
	v_mfma_f32_16x16x32_bf16 v[92:95], v[176:179], v[160:163], v[92:95]
	v_mfma_f32_16x16x32_bf16 v[88:91], v[184:187], v[160:163], v[88:91]
	v_mfma_f32_16x16x32_bf16 v[76:79], v[176:179], v[168:171], v[76:79]
	v_mfma_f32_16x16x32_bf16 v[72:75], v[184:187], v[168:171], v[72:75]
	v_mfma_f32_16x16x32_bf16 v[116:119], v[180:183], v[148:151], v[116:119]
	v_mfma_f32_16x16x32_bf16 v[112:115], v[188:191], v[148:151], v[112:115]
	v_mfma_f32_16x16x32_bf16 v[108:111], v[180:183], v[156:159], v[108:111]
	v_mfma_f32_16x16x32_bf16 v[104:107], v[188:191], v[156:159], v[104:107]
	v_mfma_f32_16x16x32_bf16 v[92:95], v[180:183], v[164:167], v[92:95]
	v_mfma_f32_16x16x32_bf16 v[88:91], v[188:191], v[164:167], v[88:91]
	v_mfma_f32_16x16x32_bf16 v[76:79], v[180:183], v[172:175], v[76:79]
	v_mfma_f32_16x16x32_bf16 v[72:75], v[188:191], v[172:175], v[72:75]
	s_setprio 0
	s_mov_b32 m0, s34
	v_lshl_add_u64 v[202:203], v[218:219], 0, s[70:71]
	s_barrier
	ds_read_b128 v[144:147], v248 offset:49152
	ds_read_b128 v[148:151], v248 offset:50176
	ds_read_b128 v[152:155], v248 offset:51200
	ds_read_b128 v[156:159], v248 offset:52224
	ds_read_b128 v[160:163], v248 offset:53248
	ds_read_b128 v[164:167], v248 offset:54272
	ds_read_b128 v[168:171], v248 offset:55296
	ds_read_b128 v[172:175], v248 offset:56320
	global_load_lds_dwordx4 v[202:203], off
	v_lshl_add_u64 v[202:203], v[220:221], 0, s[70:71]
	s_mov_b32 m0, s35
	s_nop 0
	global_load_lds_dwordx4 v[202:203], off
	s_barrier
	s_waitcnt lgkmcnt(0)
	s_setprio 1
	s_waitcnt lgkmcnt(0)
	v_mfma_f32_16x16x32_bf16 v[52:55], v[128:131], v[144:147], v[52:55]
	v_mfma_f32_16x16x32_bf16 v[48:51], v[136:139], v[144:147], v[48:51]
	v_mfma_f32_16x16x32_bf16 v[36:39], v[128:131], v[152:155], v[36:39]
	v_mfma_f32_16x16x32_bf16 v[32:35], v[136:139], v[152:155], v[32:35]
	v_mfma_f32_16x16x32_bf16 v[20:23], v[128:131], v[160:163], v[20:23]
	v_mfma_f32_16x16x32_bf16 v[16:19], v[136:139], v[160:163], v[16:19]
	v_mfma_f32_16x16x32_bf16 v[4:7], v[128:131], v[168:171], v[4:7]
	v_mfma_f32_16x16x32_bf16 v[0:3], v[136:139], v[168:171], v[0:3]
	v_mfma_f32_16x16x32_bf16 v[52:55], v[132:135], v[148:151], v[52:55]
	v_mfma_f32_16x16x32_bf16 v[48:51], v[140:143], v[148:151], v[48:51]
	v_mfma_f32_16x16x32_bf16 v[36:39], v[132:135], v[156:159], v[36:39]
	v_mfma_f32_16x16x32_bf16 v[32:35], v[140:143], v[156:159], v[32:35]
	v_mfma_f32_16x16x32_bf16 v[20:23], v[132:135], v[164:167], v[20:23]
	v_mfma_f32_16x16x32_bf16 v[16:19], v[140:143], v[164:167], v[16:19]
	v_mfma_f32_16x16x32_bf16 v[4:7], v[132:135], v[172:175], v[4:7]
	v_mfma_f32_16x16x32_bf16 v[0:3], v[140:143], v[172:175], v[0:3]
	s_setprio 0
	s_barrier
	s_add_u32 s2, s2, 0x40080
	s_addc_u32 s3, s3, 0
	s_add_i32 s6, s6, s27
	v_lshl_add_u64 v[128:129], s[2:3], 0, v[194:195]
	s_mov_b32 m0, s6
	s_nop 0
	global_load_lds_dwordx4 v[128:129], off
	v_lshl_add_u64 v[128:129], s[2:3], 0, v[206:207]
	s_add_i32 m0, s6, 0x2000
	s_nop 0
	global_load_lds_dwordx4 v[128:129], off
	s_waitcnt vmcnt(6)
	s_barrier
	s_setprio 1
	v_mfma_f32_16x16x32_bf16 v[64:67], v[176:179], v[144:147], v[64:67]
	v_mfma_f32_16x16x32_bf16 v[56:59], v[184:187], v[144:147], v[56:59]
	v_mfma_f32_16x16x32_bf16 v[44:47], v[176:179], v[152:155], v[44:47]
	v_mfma_f32_16x16x32_bf16 v[40:43], v[184:187], v[152:155], v[40:43]
	v_mfma_f32_16x16x32_bf16 v[28:31], v[176:179], v[160:163], v[28:31]
	v_mfma_f32_16x16x32_bf16 v[24:27], v[184:187], v[160:163], v[24:27]
	v_mfma_f32_16x16x32_bf16 v[12:15], v[176:179], v[168:171], v[12:15]
	v_mfma_f32_16x16x32_bf16 v[8:11], v[184:187], v[168:171], v[8:11]
	v_mfma_f32_16x16x32_bf16 v[64:67], v[180:183], v[148:151], v[64:67]
	v_mfma_f32_16x16x32_bf16 v[56:59], v[188:191], v[148:151], v[56:59]
	v_mfma_f32_16x16x32_bf16 v[44:47], v[180:183], v[156:159], v[44:47]
	v_mfma_f32_16x16x32_bf16 v[40:43], v[188:191], v[156:159], v[40:43]
	v_mfma_f32_16x16x32_bf16 v[28:31], v[180:183], v[164:167], v[28:31]
	v_mfma_f32_16x16x32_bf16 v[24:27], v[188:191], v[164:167], v[24:27]
	v_mfma_f32_16x16x32_bf16 v[12:15], v[180:183], v[172:175], v[12:15]
	v_mfma_f32_16x16x32_bf16 v[8:11], v[188:191], v[172:175], v[8:11]
	s_setprio 0
	s_add_i32 s57, s57, 2
	s_add_u32 s41, s41, 0x100
	s_addc_u32 s56, s56, 0
	s_cmp_gt_u32 s57, 13
	s_mov_b64 s[22:23], s[0:1]
	s_barrier
	s_cbranch_scc0 .LBB0_763
	v_lshl_or_b32 v216, s38, 8, v247
	v_lshl_add_u32 v232, s39, 8, v196
	v_ashrrev_i32_e32 v217, 31, v216
	v_lshlrev_b64 v[234:235], 1, v[216:217]
	v_ashrrev_i32_e32 v233, 31, v232
	v_lshl_add_u64 v[128:129], s[12:13], 0, v[234:235]
	v_lshlrev_b64 v[202:203], 11, v[232:233]
	v_lshl_add_u64 v[130:131], v[128:129], 0, v[202:203]
	global_load_dwordx4 v[188:191], v[130:131], off
	global_load_dwordx4 v[184:187], v[130:131], off offset:256
	v_or_b32_e32 v130, 16, v232
	v_ashrrev_i32_e32 v131, 31, v130
	v_lshlrev_b64 v[230:231], 11, v[130:131]
	v_lshl_add_u64 v[130:131], v[128:129], 0, v[230:231]
	global_load_dwordx4 v[180:183], v[130:131], off
	global_load_dwordx4 v[176:179], v[130:131], off offset:256
	v_or_b32_e32 v130, 32, v232
	v_ashrrev_i32_e32 v131, 31, v130
	v_lshlrev_b64 v[228:229], 11, v[130:131]
	v_lshl_add_u64 v[130:131], v[128:129], 0, v[228:229]
	global_load_dwordx4 v[172:175], v[130:131], off
	global_load_dwordx4 v[168:171], v[130:131], off offset:256
	v_or_b32_e32 v130, 48, v232
	v_ashrrev_i32_e32 v131, 31, v130
	s_mov_b64 s[0:1], 0x40000
	v_lshlrev_b64 v[226:227], 11, v[130:131]
	v_lshl_add_u64 v[224:225], v[202:203], 0, s[0:1]
	s_mov_b64 s[0:1], 0x48000
	v_lshl_add_u64 v[130:131], v[128:129], 0, v[226:227]
	v_lshl_add_u64 v[222:223], v[202:203], 0, s[0:1]
	s_mov_b64 s[0:1], 0x50000
	global_load_dwordx4 v[164:167], v[130:131], off
	global_load_dwordx4 v[160:163], v[130:131], off offset:256
	v_lshl_add_u64 v[130:131], v[128:129], 0, v[224:225]
	v_lshl_add_u64 v[220:221], v[202:203], 0, s[0:1]
	s_mov_b64 s[0:1], 0x58000
	global_load_dwordx4 v[156:159], v[130:131], off
	global_load_dwordx4 v[152:155], v[130:131], off offset:256
	v_lshl_add_u64 v[130:131], v[128:129], 0, v[222:223]
	v_lshl_add_u64 v[218:219], v[202:203], 0, s[0:1]
	global_load_dwordx4 v[148:151], v[130:131], off
	global_load_dwordx4 v[144:147], v[130:131], off offset:256
	v_lshl_add_u64 v[130:131], v[128:129], 0, v[220:221]
	v_lshl_add_u64 v[128:129], v[128:129], 0, v[218:219]
	global_load_dwordx4 v[140:143], v[130:131], off
	global_load_dwordx4 v[136:139], v[130:131], off offset:256
	global_load_dwordx4 v[132:135], v[128:129], off
	s_nop 0
	global_load_dwordx4 v[128:131], v[128:129], off offset:256
	v_lshl_add_u64 v[202:203], s[12:13], 0, v[202:203]
	v_lshl_add_u64 v[234:235], v[202:203], 0, v[234:235]
	v_and_b32_e32 v250, 64, v243
	v_xor_b32_e32 v249, 16, v243
	v_add_u32_e32 v250, 64, v250
	v_cmp_lt_i32_e32 vcc, v249, v250
	v_xor_b32_e32 v251, 32, v243
	s_waitcnt vmcnt(0) lgkmcnt(0)
	v_lshlrev_b32_e32 v202, 16, v188
	v_and_b32_e32 v203, 0xffff0000, v188
	v_lshlrev_b32_e32 v188, 16, v189
	v_and_b32_e32 v189, 0xffff0000, v189
	v_pk_add_f32 v[124:125], v[124:125], v[202:203]
	v_pk_add_f32 v[126:127], v[126:127], v[188:189]
	v_cvt_pk_bf16_f32 v124, v124, v125
	v_cvt_pk_bf16_f32 v125, v126, v127
	v_lshlrev_b32_e32 v126, 16, v190
	v_and_b32_e32 v127, 0xffff0000, v190
	v_pk_add_f32 v[120:121], v[120:121], v[126:127]
	v_cndmask_b32_e32 v249, v243, v249, vcc
	v_cvt_pk_bf16_f32 v126, v120, v121
	v_lshlrev_b32_e32 v120, 16, v191
	v_and_b32_e32 v121, 0xffff0000, v191
	v_pk_add_f32 v[120:121], v[122:123], v[120:121]
	v_lshlrev_b32_e32 v122, 16, v125
	v_cvt_pk_bf16_f32 v127, v120, v121
	v_and_b32_e32 v121, 0xffff0000, v124
	v_lshlrev_b32_e32 v120, 16, v124
	v_mul_f32_e32 v188, v121, v121
	v_fmac_f32_e32 v188, v120, v120
	v_lshlrev_b32_e32 v120, 16, v184
	v_and_b32_e32 v121, 0xffff0000, v184
	v_pk_add_f32 v[116:117], v[116:117], v[120:121]
	v_lshlrev_b32_e32 v120, 16, v185
	v_and_b32_e32 v121, 0xffff0000, v185
	v_and_b32_e32 v123, 0xffff0000, v125
	v_fmac_f32_e32 v188, v122, v122
	v_pk_add_f32 v[118:119], v[118:119], v[120:121]
	global_store_dwordx4 v[234:235], v[124:127], off
	v_fmac_f32_e32 v188, v123, v123
	v_cvt_pk_bf16_f32 v116, v116, v117
	v_lshlrev_b32_e32 v124, 16, v126
	v_cvt_pk_bf16_f32 v117, v118, v119
	v_lshlrev_b32_e32 v118, 16, v186
	v_and_b32_e32 v119, 0xffff0000, v186
	v_and_b32_e32 v125, 0xffff0000, v126
	v_fmac_f32_e32 v188, v124, v124
	v_pk_add_f32 v[112:113], v[112:113], v[118:119]
	v_lshlrev_b32_e32 v126, 16, v127
	v_fmac_f32_e32 v188, v125, v125
	v_cvt_pk_bf16_f32 v118, v112, v113
	v_lshlrev_b32_e32 v112, 16, v187
	v_and_b32_e32 v113, 0xffff0000, v187
	v_and_b32_e32 v127, 0xffff0000, v127
	v_fmac_f32_e32 v188, v126, v126
	v_pk_add_f32 v[112:113], v[114:115], v[112:113]
	v_fmac_f32_e32 v188, v127, v127
	v_cvt_pk_bf16_f32 v119, v112, v113
	v_lshlrev_b32_e32 v112, 16, v116
	v_and_b32_e32 v113, 0xffff0000, v116
	v_fmac_f32_e32 v188, v112, v112
	v_lshlrev_b32_e32 v114, 16, v117
	v_fmac_f32_e32 v188, v113, v113
	v_and_b32_e32 v115, 0xffff0000, v117
	v_fmac_f32_e32 v188, v114, v114
	global_store_dwordx4 v[234:235], v[116:119], off offset:256
	v_fmac_f32_e32 v188, v115, v115
	v_lshlrev_b32_e32 v249, 2, v249
	v_lshlrev_b32_e32 v116, 16, v118
	v_and_b32_e32 v117, 0xffff0000, v118
	v_fmac_f32_e32 v188, v116, v116
	v_lshlrev_b32_e32 v118, 16, v119
	v_fmac_f32_e32 v188, v117, v117
	v_and_b32_e32 v119, 0xffff0000, v119
	v_fmac_f32_e32 v188, v118, v118
	v_fmac_f32_e32 v188, v119, v119
	ds_bpermute_b32 v112, v249, v188
	v_cmp_lt_i32_e32 vcc, v251, v250
	s_waitcnt lgkmcnt(0)
	v_add_f32_e32 v114, v188, v112
	v_cndmask_b32_e32 v250, v243, v251, vcc
	v_lshlrev_b32_e32 v250, 2, v250
	ds_bpermute_b32 v115, v250, v114
	v_lshl_add_u64 v[112:113], v[232:233], 3, s[14:15]
	s_and_saveexec_b64 s[0:1], s[8:9]
	s_mov_b32 s6, 0x4b800000
	s_cbranch_execz .LBB0_766
	s_waitcnt lgkmcnt(0)
	v_add_f32_e32 v114, v114, v115
	v_fma_f32 v114, v114, s6, 0.5
	v_trunc_f32_e32 v114, v114
	v_mul_f32_e32 v115, 0x2f800000, v114
	v_floor_f32_e32 v115, v115
	v_fmac_f32_e32 v114, 0xcf800000, v115
	v_cvt_u32_f32_e32 v114, v114
	v_cvt_u32_f32_e32 v115, v115
	global_atomic_add_x2 v[112:113], v[114:115], off
.LBB0_766:
	s_or_b64 exec, exec, s[0:1]
	v_lshlrev_b32_e32 v114, 16, v180
	s_waitcnt lgkmcnt(0)
	v_and_b32_e32 v115, 0xffff0000, v180
	v_pk_add_f32 v[100:101], v[100:101], v[114:115]
	v_lshlrev_b32_e32 v114, 16, v181
	v_and_b32_e32 v115, 0xffff0000, v181
	v_pk_add_f32 v[102:103], v[102:103], v[114:115]
	v_cvt_pk_bf16_f32 v100, v100, v101
	v_cvt_pk_bf16_f32 v101, v102, v103
	v_lshlrev_b32_e32 v102, 16, v182
	v_and_b32_e32 v103, 0xffff0000, v182
	v_pk_add_f32 v[96:97], v[96:97], v[102:103]
	s_nop 0
	v_cvt_pk_bf16_f32 v102, v96, v97
	v_lshlrev_b32_e32 v96, 16, v183
	v_and_b32_e32 v97, 0xffff0000, v183
	v_pk_add_f32 v[96:97], v[98:99], v[96:97]
	v_lshlrev_b32_e32 v98, 16, v101
	v_cvt_pk_bf16_f32 v103, v96, v97
	v_and_b32_e32 v97, 0xffff0000, v100
	v_lshlrev_b32_e32 v96, 16, v100
	v_mul_f32_e32 v118, v97, v97
	v_fmac_f32_e32 v118, v96, v96
	v_lshlrev_b32_e32 v96, 16, v176
	v_and_b32_e32 v97, 0xffff0000, v176
	v_pk_add_f32 v[96:97], v[108:109], v[96:97]
	v_and_b32_e32 v99, 0xffff0000, v101
	v_cvt_pk_bf16_f32 v108, v96, v97
	v_lshlrev_b32_e32 v96, 16, v177
	v_and_b32_e32 v97, 0xffff0000, v177
	v_fmac_f32_e32 v118, v98, v98
	v_pk_add_f32 v[96:97], v[110:111], v[96:97]
	v_lshlrev_b32_e32 v114, 16, v102
	v_fmac_f32_e32 v118, v99, v99
	v_cvt_pk_bf16_f32 v109, v96, v97
	v_lshlrev_b32_e32 v96, 16, v178
	v_and_b32_e32 v97, 0xffff0000, v178
	v_and_b32_e32 v115, 0xffff0000, v102
	v_fmac_f32_e32 v118, v114, v114
	v_pk_add_f32 v[96:97], v[104:105], v[96:97]
	v_lshlrev_b32_e32 v116, 16, v103
	v_fmac_f32_e32 v118, v115, v115
	v_cvt_pk_bf16_f32 v110, v96, v97
	v_lshlrev_b32_e32 v96, 16, v179
	v_and_b32_e32 v97, 0xffff0000, v179
	v_and_b32_e32 v117, 0xffff0000, v103
	v_fmac_f32_e32 v118, v116, v116
	v_pk_add_f32 v[96:97], v[106:107], v[96:97]
	v_fmac_f32_e32 v118, v117, v117
	v_cvt_pk_bf16_f32 v111, v96, v97
	v_lshlrev_b32_e32 v96, 16, v108
	v_and_b32_e32 v97, 0xffff0000, v108
	v_fmac_f32_e32 v118, v96, v96
	v_lshlrev_b32_e32 v98, 16, v109
	v_fmac_f32_e32 v118, v97, v97
	v_and_b32_e32 v99, 0xffff0000, v109
	v_fmac_f32_e32 v118, v98, v98
	v_lshlrev_b32_e32 v104, 16, v110
	v_fmac_f32_e32 v118, v99, v99
	v_and_b32_e32 v105, 0xffff0000, v110
	v_fmac_f32_e32 v118, v104, v104
	v_lshlrev_b32_e32 v106, 16, v111
	v_fmac_f32_e32 v118, v105, v105
	v_and_b32_e32 v107, 0xffff0000, v111
	v_fmac_f32_e32 v118, v106, v106
	v_fmac_f32_e32 v118, v107, v107
	ds_bpermute_b32 v96, v249, v118
	v_lshl_add_u64 v[98:99], s[12:13], 0, v[230:231]
	v_lshl_add_u64 v[98:99], v[216:217], 1, v[98:99]
	global_store_dwordx4 v[98:99], v[100:103], off
	global_store_dwordx4 v[98:99], v[108:111], off offset:256
	s_waitcnt lgkmcnt(0)
	v_add_f32_e32 v96, v118, v96
	ds_bpermute_b32 v97, v250, v96
	s_and_saveexec_b64 s[0:1], s[8:9]
	s_cbranch_execz .LBB0_768
	s_waitcnt lgkmcnt(0)
	v_add_f32_e32 v96, v96, v97
	v_fma_f32 v96, v96, s6, 0.5
	v_trunc_f32_e32 v96, v96
	v_mul_f32_e32 v97, 0x2f800000, v96
	v_floor_f32_e32 v97, v97
	v_fmac_f32_e32 v96, 0xcf800000, v97
	v_cvt_u32_f32_e32 v96, v96
	v_cvt_u32_f32_e32 v97, v97
	global_atomic_add_x2 v[112:113], v[96:97], off offset:128
.LBB0_768:
	s_or_b64 exec, exec, s[0:1]
	v_lshlrev_b32_e32 v96, 16, v172
	s_waitcnt lgkmcnt(0)
	v_and_b32_e32 v97, 0xffff0000, v172
	v_pk_add_f32 v[84:85], v[84:85], v[96:97]
	v_lshlrev_b32_e32 v96, 16, v173
	v_and_b32_e32 v97, 0xffff0000, v173
	v_pk_add_f32 v[86:87], v[86:87], v[96:97]
	v_cvt_pk_bf16_f32 v84, v84, v85
	v_cvt_pk_bf16_f32 v85, v86, v87
	v_lshlrev_b32_e32 v86, 16, v174
	v_and_b32_e32 v87, 0xffff0000, v174
	v_pk_add_f32 v[80:81], v[80:81], v[86:87]
	s_nop 0
	v_cvt_pk_bf16_f32 v86, v80, v81
	v_lshlrev_b32_e32 v80, 16, v175
	v_and_b32_e32 v81, 0xffff0000, v175
	v_pk_add_f32 v[80:81], v[82:83], v[80:81]
	v_lshlrev_b32_e32 v82, 16, v85
	v_cvt_pk_bf16_f32 v87, v80, v81
	v_and_b32_e32 v81, 0xffff0000, v84
	v_lshlrev_b32_e32 v80, 16, v84
	v_mul_f32_e32 v100, v81, v81
	v_fmac_f32_e32 v100, v80, v80
	v_lshlrev_b32_e32 v80, 16, v168
	v_and_b32_e32 v81, 0xffff0000, v168
	v_pk_add_f32 v[80:81], v[92:93], v[80:81]
	v_and_b32_e32 v83, 0xffff0000, v85
	v_cvt_pk_bf16_f32 v92, v80, v81
	v_lshlrev_b32_e32 v80, 16, v169
	v_and_b32_e32 v81, 0xffff0000, v169
	v_fmac_f32_e32 v100, v82, v82
	v_pk_add_f32 v[80:81], v[94:95], v[80:81]
	v_lshlrev_b32_e32 v96, 16, v86
	v_fmac_f32_e32 v100, v83, v83
	v_cvt_pk_bf16_f32 v93, v80, v81
	v_lshlrev_b32_e32 v80, 16, v170
	v_and_b32_e32 v81, 0xffff0000, v170
	v_and_b32_e32 v97, 0xffff0000, v86
	v_fmac_f32_e32 v100, v96, v96
	v_pk_add_f32 v[80:81], v[88:89], v[80:81]
	v_lshlrev_b32_e32 v98, 16, v87
	v_fmac_f32_e32 v100, v97, v97
	v_cvt_pk_bf16_f32 v94, v80, v81
	v_lshlrev_b32_e32 v80, 16, v171
	v_and_b32_e32 v81, 0xffff0000, v171
	v_and_b32_e32 v99, 0xffff0000, v87
	v_fmac_f32_e32 v100, v98, v98
	v_pk_add_f32 v[80:81], v[90:91], v[80:81]
	v_fmac_f32_e32 v100, v99, v99
	v_cvt_pk_bf16_f32 v95, v80, v81
	v_lshlrev_b32_e32 v80, 16, v92
	v_and_b32_e32 v81, 0xffff0000, v92
	v_fmac_f32_e32 v100, v80, v80
	v_lshlrev_b32_e32 v82, 16, v93
	v_fmac_f32_e32 v100, v81, v81
	v_and_b32_e32 v83, 0xffff0000, v93
	v_fmac_f32_e32 v100, v82, v82
	v_lshlrev_b32_e32 v88, 16, v94
	v_fmac_f32_e32 v100, v83, v83
	v_and_b32_e32 v89, 0xffff0000, v94
	v_fmac_f32_e32 v100, v88, v88
	v_lshlrev_b32_e32 v90, 16, v95
	v_fmac_f32_e32 v100, v89, v89
	v_and_b32_e32 v91, 0xffff0000, v95
	v_fmac_f32_e32 v100, v90, v90
	v_fmac_f32_e32 v100, v91, v91
	ds_bpermute_b32 v80, v249, v100
	v_lshl_add_u64 v[82:83], s[12:13], 0, v[228:229]
	v_lshl_add_u64 v[82:83], v[216:217], 1, v[82:83]
	global_store_dwordx4 v[82:83], v[84:87], off
	global_store_dwordx4 v[82:83], v[92:95], off offset:256
	s_waitcnt lgkmcnt(0)
	v_add_f32_e32 v80, v100, v80
	ds_bpermute_b32 v81, v250, v80
	s_and_saveexec_b64 s[0:1], s[8:9]
	s_cbranch_execz .LBB0_770
	s_waitcnt lgkmcnt(0)
	v_add_f32_e32 v80, v80, v81
	v_fma_f32 v80, v80, s6, 0.5
	v_trunc_f32_e32 v80, v80
	v_mul_f32_e32 v81, 0x2f800000, v80
	v_floor_f32_e32 v81, v81
	v_fmac_f32_e32 v80, 0xcf800000, v81
	v_cvt_u32_f32_e32 v80, v80
	v_cvt_u32_f32_e32 v81, v81
	global_atomic_add_x2 v[112:113], v[80:81], off offset:256
.LBB0_770:
	s_or_b64 exec, exec, s[0:1]
	v_lshlrev_b32_e32 v80, 16, v164
	s_waitcnt lgkmcnt(0)
	v_and_b32_e32 v81, 0xffff0000, v164
	v_pk_add_f32 v[68:69], v[68:69], v[80:81]
	v_lshlrev_b32_e32 v80, 16, v165
	v_and_b32_e32 v81, 0xffff0000, v165
	v_pk_add_f32 v[70:71], v[70:71], v[80:81]
	v_cvt_pk_bf16_f32 v68, v68, v69
	v_cvt_pk_bf16_f32 v69, v70, v71
	v_lshlrev_b32_e32 v70, 16, v166
	v_and_b32_e32 v71, 0xffff0000, v166
	v_pk_add_f32 v[60:61], v[60:61], v[70:71]
	s_nop 0
	v_cvt_pk_bf16_f32 v70, v60, v61
	v_lshlrev_b32_e32 v60, 16, v167
	v_and_b32_e32 v61, 0xffff0000, v167
	v_pk_add_f32 v[60:61], v[62:63], v[60:61]
	v_lshlrev_b32_e32 v62, 16, v69
	v_cvt_pk_bf16_f32 v71, v60, v61
	v_and_b32_e32 v61, 0xffff0000, v68
	v_lshlrev_b32_e32 v60, 16, v68
	v_mul_f32_e32 v84, v61, v61
	v_fmac_f32_e32 v84, v60, v60
	v_lshlrev_b32_e32 v60, 16, v160
	v_and_b32_e32 v61, 0xffff0000, v160
	v_pk_add_f32 v[60:61], v[76:77], v[60:61]
	v_and_b32_e32 v63, 0xffff0000, v69
	v_cvt_pk_bf16_f32 v76, v60, v61
	v_lshlrev_b32_e32 v60, 16, v161
	v_and_b32_e32 v61, 0xffff0000, v161
	v_fmac_f32_e32 v84, v62, v62
	v_pk_add_f32 v[60:61], v[78:79], v[60:61]
	v_lshlrev_b32_e32 v80, 16, v70
	v_fmac_f32_e32 v84, v63, v63
	v_cvt_pk_bf16_f32 v77, v60, v61
	v_lshlrev_b32_e32 v60, 16, v162
	v_and_b32_e32 v61, 0xffff0000, v162
	v_and_b32_e32 v81, 0xffff0000, v70
	v_fmac_f32_e32 v84, v80, v80
	v_pk_add_f32 v[60:61], v[72:73], v[60:61]
	v_lshlrev_b32_e32 v82, 16, v71
	v_fmac_f32_e32 v84, v81, v81
	v_cvt_pk_bf16_f32 v78, v60, v61
	v_lshlrev_b32_e32 v60, 16, v163
	v_and_b32_e32 v61, 0xffff0000, v163
	v_and_b32_e32 v83, 0xffff0000, v71
	v_fmac_f32_e32 v84, v82, v82
	v_pk_add_f32 v[60:61], v[74:75], v[60:61]
	v_fmac_f32_e32 v84, v83, v83
	v_cvt_pk_bf16_f32 v79, v60, v61
	v_lshlrev_b32_e32 v60, 16, v76
	v_and_b32_e32 v61, 0xffff0000, v76
	v_fmac_f32_e32 v84, v60, v60
	v_lshlrev_b32_e32 v62, 16, v77
	v_fmac_f32_e32 v84, v61, v61
	v_and_b32_e32 v63, 0xffff0000, v77
	v_fmac_f32_e32 v84, v62, v62
	v_lshlrev_b32_e32 v72, 16, v78
	v_fmac_f32_e32 v84, v63, v63
	v_and_b32_e32 v73, 0xffff0000, v78
	v_fmac_f32_e32 v84, v72, v72
	v_lshlrev_b32_e32 v74, 16, v79
	v_fmac_f32_e32 v84, v73, v73
	v_and_b32_e32 v75, 0xffff0000, v79
	v_fmac_f32_e32 v84, v74, v74
	v_fmac_f32_e32 v84, v75, v75
	ds_bpermute_b32 v60, v249, v84
	v_lshl_add_u64 v[62:63], s[12:13], 0, v[226:227]
	v_lshl_add_u64 v[62:63], v[216:217], 1, v[62:63]
	global_store_dwordx4 v[62:63], v[68:71], off
	global_store_dwordx4 v[62:63], v[76:79], off offset:256
	s_waitcnt lgkmcnt(0)
	v_add_f32_e32 v60, v84, v60
	ds_bpermute_b32 v61, v250, v60
	s_and_saveexec_b64 s[0:1], s[8:9]
	s_cbranch_execz .LBB0_772
	s_waitcnt lgkmcnt(0)
	v_add_f32_e32 v60, v60, v61
	v_fma_f32 v60, v60, s6, 0.5
	v_trunc_f32_e32 v60, v60
	v_mul_f32_e32 v61, 0x2f800000, v60
	v_floor_f32_e32 v61, v61
	v_fmac_f32_e32 v60, 0xcf800000, v61
	v_cvt_u32_f32_e32 v60, v60
	v_cvt_u32_f32_e32 v61, v61
	global_atomic_add_x2 v[112:113], v[60:61], off offset:384
.LBB0_772:
	s_or_b64 exec, exec, s[0:1]
	v_lshlrev_b32_e32 v60, 16, v156
	s_waitcnt lgkmcnt(0)
	v_and_b32_e32 v61, 0xffff0000, v156
	v_pk_add_f32 v[52:53], v[52:53], v[60:61]
	v_lshlrev_b32_e32 v60, 16, v157
	v_and_b32_e32 v61, 0xffff0000, v157
	v_pk_add_f32 v[54:55], v[54:55], v[60:61]
	v_cvt_pk_bf16_f32 v52, v52, v53
	v_cvt_pk_bf16_f32 v53, v54, v55
	v_lshlrev_b32_e32 v54, 16, v158
	v_and_b32_e32 v55, 0xffff0000, v158
	v_pk_add_f32 v[48:49], v[48:49], v[54:55]
	s_nop 0
	v_cvt_pk_bf16_f32 v54, v48, v49
	v_lshlrev_b32_e32 v48, 16, v159
	v_and_b32_e32 v49, 0xffff0000, v159
	v_pk_add_f32 v[48:49], v[50:51], v[48:49]
	v_lshlrev_b32_e32 v50, 16, v53
	v_cvt_pk_bf16_f32 v55, v48, v49
	v_and_b32_e32 v49, 0xffff0000, v52
	v_lshlrev_b32_e32 v48, 16, v52
	v_mul_f32_e32 v68, v49, v49
	v_fmac_f32_e32 v68, v48, v48
	v_and_b32_e32 v51, 0xffff0000, v53
	v_fmac_f32_e32 v68, v50, v50
	v_lshlrev_b32_e32 v48, 16, v152
	v_and_b32_e32 v49, 0xffff0000, v152
	v_lshlrev_b32_e32 v60, 16, v54
	v_fmac_f32_e32 v68, v51, v51
	v_pk_add_f32 v[48:49], v[64:65], v[48:49]
	v_fmac_f32_e32 v68, v60, v60
	v_cvt_pk_bf16_f32 v60, v48, v49
	v_lshlrev_b32_e32 v48, 16, v153
	v_and_b32_e32 v49, 0xffff0000, v153
	v_and_b32_e32 v61, 0xffff0000, v54
	v_pk_add_f32 v[48:49], v[66:67], v[48:49]
	v_fmac_f32_e32 v68, v61, v61
	v_cvt_pk_bf16_f32 v61, v48, v49
	v_lshlrev_b32_e32 v48, 16, v154
	v_and_b32_e32 v49, 0xffff0000, v154
	v_lshlrev_b32_e32 v62, 16, v55
	v_pk_add_f32 v[48:49], v[56:57], v[48:49]
	v_fmac_f32_e32 v68, v62, v62
	v_cvt_pk_bf16_f32 v62, v48, v49
	v_lshlrev_b32_e32 v48, 16, v155
	v_and_b32_e32 v49, 0xffff0000, v155
	v_and_b32_e32 v63, 0xffff0000, v55
	v_pk_add_f32 v[48:49], v[58:59], v[48:49]
	v_fmac_f32_e32 v68, v63, v63
	v_cvt_pk_bf16_f32 v63, v48, v49
	v_lshlrev_b32_e32 v48, 16, v60
	v_and_b32_e32 v49, 0xffff0000, v60
	v_fmac_f32_e32 v68, v48, v48
	v_lshlrev_b32_e32 v50, 16, v61
	v_fmac_f32_e32 v68, v49, v49
	v_and_b32_e32 v51, 0xffff0000, v61
	v_fmac_f32_e32 v68, v50, v50
	v_lshlrev_b32_e32 v56, 16, v62
	v_fmac_f32_e32 v68, v51, v51
	v_and_b32_e32 v57, 0xffff0000, v62
	v_fmac_f32_e32 v68, v56, v56
	v_lshlrev_b32_e32 v58, 16, v63
	v_fmac_f32_e32 v68, v57, v57
	v_and_b32_e32 v59, 0xffff0000, v63
	v_fmac_f32_e32 v68, v58, v58
	v_fmac_f32_e32 v68, v59, v59
	ds_bpermute_b32 v48, v249, v68
	v_lshl_add_u64 v[50:51], s[12:13], 0, v[224:225]
	v_lshl_add_u64 v[50:51], v[216:217], 1, v[50:51]
	global_store_dwordx4 v[50:51], v[52:55], off
	global_store_dwordx4 v[50:51], v[60:63], off offset:256
	s_waitcnt lgkmcnt(0)
	v_add_f32_e32 v48, v68, v48
	ds_bpermute_b32 v49, v250, v48
	s_and_saveexec_b64 s[0:1], s[8:9]
	s_cbranch_execz .LBB0_774
	s_waitcnt lgkmcnt(0)
	v_add_f32_e32 v48, v48, v49
	v_fma_f32 v48, v48, s6, 0.5
	v_trunc_f32_e32 v48, v48
	v_mul_f32_e32 v49, 0x2f800000, v48
	v_floor_f32_e32 v49, v49
	v_fmac_f32_e32 v48, 0xcf800000, v49
	v_cvt_u32_f32_e32 v48, v48
	v_cvt_u32_f32_e32 v49, v49
	global_atomic_add_x2 v[112:113], v[48:49], off offset:1024
.LBB0_774:
	s_or_b64 exec, exec, s[0:1]
	v_lshlrev_b32_e32 v48, 16, v148
	s_waitcnt lgkmcnt(0)
	v_and_b32_e32 v49, 0xffff0000, v148
	v_pk_add_f32 v[36:37], v[36:37], v[48:49]
	v_lshlrev_b32_e32 v48, 16, v149
	v_and_b32_e32 v49, 0xffff0000, v149
	v_pk_add_f32 v[38:39], v[38:39], v[48:49]
	v_cvt_pk_bf16_f32 v36, v36, v37
	v_cvt_pk_bf16_f32 v37, v38, v39
	v_lshlrev_b32_e32 v38, 16, v150
	v_and_b32_e32 v39, 0xffff0000, v150
	v_pk_add_f32 v[32:33], v[32:33], v[38:39]
	s_nop 0
	v_cvt_pk_bf16_f32 v38, v32, v33
	v_lshlrev_b32_e32 v32, 16, v151
	v_and_b32_e32 v33, 0xffff0000, v151
	v_pk_add_f32 v[32:33], v[34:35], v[32:33]
	v_lshlrev_b32_e32 v34, 16, v37
	v_cvt_pk_bf16_f32 v39, v32, v33
	v_and_b32_e32 v33, 0xffff0000, v36
	v_lshlrev_b32_e32 v32, 16, v36
	v_mul_f32_e32 v52, v33, v33
	v_fmac_f32_e32 v52, v32, v32
	v_lshlrev_b32_e32 v32, 16, v144
	v_and_b32_e32 v33, 0xffff0000, v144
	v_pk_add_f32 v[32:33], v[44:45], v[32:33]
	v_and_b32_e32 v35, 0xffff0000, v37
	v_cvt_pk_bf16_f32 v44, v32, v33
	v_lshlrev_b32_e32 v32, 16, v145
	v_and_b32_e32 v33, 0xffff0000, v145
	v_fmac_f32_e32 v52, v34, v34
	v_pk_add_f32 v[32:33], v[46:47], v[32:33]
	v_lshlrev_b32_e32 v48, 16, v38
	v_fmac_f32_e32 v52, v35, v35
	v_cvt_pk_bf16_f32 v45, v32, v33
	v_lshlrev_b32_e32 v32, 16, v146
	v_and_b32_e32 v33, 0xffff0000, v146
	v_and_b32_e32 v49, 0xffff0000, v38
	v_fmac_f32_e32 v52, v48, v48
	v_pk_add_f32 v[32:33], v[40:41], v[32:33]
	v_lshlrev_b32_e32 v50, 16, v39
	v_fmac_f32_e32 v52, v49, v49
	v_cvt_pk_bf16_f32 v46, v32, v33
	v_lshlrev_b32_e32 v32, 16, v147
	v_and_b32_e32 v33, 0xffff0000, v147
	v_and_b32_e32 v51, 0xffff0000, v39
	v_fmac_f32_e32 v52, v50, v50
	v_pk_add_f32 v[32:33], v[42:43], v[32:33]
	v_fmac_f32_e32 v52, v51, v51
	v_cvt_pk_bf16_f32 v47, v32, v33
	v_lshlrev_b32_e32 v32, 16, v44
	v_and_b32_e32 v33, 0xffff0000, v44
	v_fmac_f32_e32 v52, v32, v32
	v_lshlrev_b32_e32 v34, 16, v45
	v_fmac_f32_e32 v52, v33, v33
	v_and_b32_e32 v35, 0xffff0000, v45
	v_fmac_f32_e32 v52, v34, v34
	v_lshlrev_b32_e32 v40, 16, v46
	v_fmac_f32_e32 v52, v35, v35
	v_and_b32_e32 v41, 0xffff0000, v46
	v_fmac_f32_e32 v52, v40, v40
	v_lshlrev_b32_e32 v42, 16, v47
	v_fmac_f32_e32 v52, v41, v41
	v_and_b32_e32 v43, 0xffff0000, v47
	v_fmac_f32_e32 v52, v42, v42
	v_fmac_f32_e32 v52, v43, v43
	ds_bpermute_b32 v32, v249, v52
	v_lshl_add_u64 v[34:35], s[12:13], 0, v[222:223]
	v_lshl_add_u64 v[34:35], v[216:217], 1, v[34:35]
	global_store_dwordx4 v[34:35], v[36:39], off
	global_store_dwordx4 v[34:35], v[44:47], off offset:256
	s_waitcnt lgkmcnt(0)
	v_add_f32_e32 v32, v52, v32
	ds_bpermute_b32 v33, v250, v32
	s_and_saveexec_b64 s[0:1], s[8:9]
	s_cbranch_execz .LBB0_776
	s_waitcnt lgkmcnt(0)
	v_add_f32_e32 v32, v32, v33
	v_fma_f32 v32, v32, s6, 0.5
	v_trunc_f32_e32 v32, v32
	v_mul_f32_e32 v33, 0x2f800000, v32
	v_floor_f32_e32 v33, v33
	v_fmac_f32_e32 v32, 0xcf800000, v33
	v_cvt_u32_f32_e32 v32, v32
	v_cvt_u32_f32_e32 v33, v33
	global_atomic_add_x2 v[112:113], v[32:33], off offset:1152
.LBB0_776:
	s_or_b64 exec, exec, s[0:1]
	v_lshlrev_b32_e32 v32, 16, v140
	s_waitcnt lgkmcnt(0)
	v_and_b32_e32 v33, 0xffff0000, v140
	v_pk_add_f32 v[20:21], v[20:21], v[32:33]
	v_lshlrev_b32_e32 v32, 16, v141
	v_and_b32_e32 v33, 0xffff0000, v141
	v_pk_add_f32 v[22:23], v[22:23], v[32:33]
	v_cvt_pk_bf16_f32 v20, v20, v21
	v_cvt_pk_bf16_f32 v21, v22, v23
	v_lshlrev_b32_e32 v22, 16, v142
	v_and_b32_e32 v23, 0xffff0000, v142
	v_pk_add_f32 v[16:17], v[16:17], v[22:23]
	s_nop 0
	v_cvt_pk_bf16_f32 v22, v16, v17
	v_lshlrev_b32_e32 v16, 16, v143
	v_and_b32_e32 v17, 0xffff0000, v143
	v_pk_add_f32 v[16:17], v[18:19], v[16:17]
	v_lshlrev_b32_e32 v18, 16, v21
	v_cvt_pk_bf16_f32 v23, v16, v17
	v_and_b32_e32 v17, 0xffff0000, v20
	v_lshlrev_b32_e32 v16, 16, v20
	v_mul_f32_e32 v36, v17, v17
	v_fmac_f32_e32 v36, v16, v16
	v_lshlrev_b32_e32 v16, 16, v136
	v_and_b32_e32 v17, 0xffff0000, v136
	v_pk_add_f32 v[16:17], v[28:29], v[16:17]
	v_and_b32_e32 v19, 0xffff0000, v21
	v_cvt_pk_bf16_f32 v28, v16, v17
	v_lshlrev_b32_e32 v16, 16, v137
	v_and_b32_e32 v17, 0xffff0000, v137
	v_fmac_f32_e32 v36, v18, v18
	v_pk_add_f32 v[16:17], v[30:31], v[16:17]
	v_lshlrev_b32_e32 v32, 16, v22
	v_fmac_f32_e32 v36, v19, v19
	v_cvt_pk_bf16_f32 v29, v16, v17
	v_lshlrev_b32_e32 v16, 16, v138
	v_and_b32_e32 v17, 0xffff0000, v138
	v_and_b32_e32 v33, 0xffff0000, v22
	v_fmac_f32_e32 v36, v32, v32
	v_pk_add_f32 v[16:17], v[24:25], v[16:17]
	v_lshlrev_b32_e32 v34, 16, v23
	v_fmac_f32_e32 v36, v33, v33
	v_cvt_pk_bf16_f32 v30, v16, v17
	v_lshlrev_b32_e32 v16, 16, v139
	v_and_b32_e32 v17, 0xffff0000, v139
	v_and_b32_e32 v35, 0xffff0000, v23
	v_fmac_f32_e32 v36, v34, v34
	v_pk_add_f32 v[16:17], v[26:27], v[16:17]
	v_fmac_f32_e32 v36, v35, v35
	v_cvt_pk_bf16_f32 v31, v16, v17
	v_lshlrev_b32_e32 v16, 16, v28
	v_and_b32_e32 v17, 0xffff0000, v28
	v_fmac_f32_e32 v36, v16, v16
	v_lshlrev_b32_e32 v18, 16, v29
	v_fmac_f32_e32 v36, v17, v17
	v_and_b32_e32 v19, 0xffff0000, v29
	v_fmac_f32_e32 v36, v18, v18
	v_lshlrev_b32_e32 v24, 16, v30
	v_fmac_f32_e32 v36, v19, v19
	v_and_b32_e32 v25, 0xffff0000, v30
	v_fmac_f32_e32 v36, v24, v24
	v_lshlrev_b32_e32 v26, 16, v31
	v_fmac_f32_e32 v36, v25, v25
	v_and_b32_e32 v27, 0xffff0000, v31
	v_fmac_f32_e32 v36, v26, v26
	v_fmac_f32_e32 v36, v27, v27
	ds_bpermute_b32 v16, v249, v36
	v_lshl_add_u64 v[18:19], s[12:13], 0, v[220:221]
	v_lshl_add_u64 v[18:19], v[216:217], 1, v[18:19]
	global_store_dwordx4 v[18:19], v[20:23], off
	global_store_dwordx4 v[18:19], v[28:31], off offset:256
	s_waitcnt lgkmcnt(0)
	v_add_f32_e32 v16, v36, v16
	ds_bpermute_b32 v17, v250, v16
	s_and_saveexec_b64 s[0:1], s[8:9]
	s_cbranch_execz .LBB0_778
	s_waitcnt lgkmcnt(0)
	v_add_f32_e32 v16, v16, v17
	v_fma_f32 v16, v16, s6, 0.5
	v_trunc_f32_e32 v16, v16
	v_mul_f32_e32 v17, 0x2f800000, v16
	v_floor_f32_e32 v17, v17
	v_fmac_f32_e32 v16, 0xcf800000, v17
	v_cvt_u32_f32_e32 v16, v16
	v_cvt_u32_f32_e32 v17, v17
	global_atomic_add_x2 v[112:113], v[16:17], off offset:1280
.LBB0_778:
	s_or_b64 exec, exec, s[0:1]
	v_lshlrev_b32_e32 v18, 16, v132
	v_and_b32_e32 v19, 0xffff0000, v132
	v_pk_add_f32 v[4:5], v[4:5], v[18:19]
	v_lshlrev_b32_e32 v18, 16, v133
	v_and_b32_e32 v19, 0xffff0000, v133
	v_pk_add_f32 v[6:7], v[6:7], v[18:19]
	v_cvt_pk_bf16_f32 v4, v4, v5
	v_cvt_pk_bf16_f32 v5, v6, v7
	v_lshlrev_b32_e32 v6, 16, v134
	v_and_b32_e32 v7, 0xffff0000, v134
	v_pk_add_f32 v[0:1], v[0:1], v[6:7]
	s_waitcnt lgkmcnt(0)
	v_lshl_add_u64 v[16:17], s[12:13], 0, v[218:219]
	v_cvt_pk_bf16_f32 v6, v0, v1
	v_lshlrev_b32_e32 v0, 16, v135
	v_and_b32_e32 v1, 0xffff0000, v135
	v_pk_add_f32 v[0:1], v[2:3], v[0:1]
	v_lshlrev_b32_e32 v2, 16, v5
	v_cvt_pk_bf16_f32 v7, v0, v1
	v_and_b32_e32 v1, 0xffff0000, v4
	v_lshlrev_b32_e32 v0, 16, v4
	v_mul_f32_e32 v18, v1, v1
	v_fmac_f32_e32 v18, v0, v0
	v_lshl_add_u64 v[16:17], v[216:217], 1, v[16:17]
	v_and_b32_e32 v3, 0xffff0000, v5
	v_fmac_f32_e32 v18, v2, v2
	global_store_dwordx4 v[16:17], v[4:7], off
	v_fmac_f32_e32 v18, v3, v3
	v_lshlrev_b32_e32 v0, 16, v128
	v_lshlrev_b32_e32 v4, 16, v6
	v_and_b32_e32 v1, 0xffff0000, v128
	v_lshlrev_b32_e32 v2, 16, v129
	v_and_b32_e32 v3, 0xffff0000, v129
	v_and_b32_e32 v5, 0xffff0000, v6
	v_fmac_f32_e32 v18, v4, v4
	v_pk_add_f32 v[0:1], v[12:13], v[0:1]
	v_pk_add_f32 v[2:3], v[14:15], v[2:3]
	v_lshlrev_b32_e32 v6, 16, v7
	v_fmac_f32_e32 v18, v5, v5
	v_cvt_pk_bf16_f32 v0, v0, v1
	v_cvt_pk_bf16_f32 v1, v2, v3
	v_lshlrev_b32_e32 v2, 16, v130
	v_and_b32_e32 v3, 0xffff0000, v130
	v_lshlrev_b32_e32 v4, 16, v131
	v_and_b32_e32 v5, 0xffff0000, v131
	v_and_b32_e32 v7, 0xffff0000, v7
	v_fmac_f32_e32 v18, v6, v6
	v_pk_add_f32 v[2:3], v[8:9], v[2:3]
	v_pk_add_f32 v[4:5], v[10:11], v[4:5]
	v_fmac_f32_e32 v18, v7, v7
	v_cvt_pk_bf16_f32 v2, v2, v3
	v_cvt_pk_bf16_f32 v3, v4, v5
	v_lshlrev_b32_e32 v4, 16, v0
	global_store_dwordx4 v[16:17], v[0:3], off offset:256
	v_fmac_f32_e32 v18, v4, v4
	v_lshlrev_b32_e32 v5, 16, v1
	v_and_b32_e32 v0, 0xffff0000, v0
	v_fmac_f32_e32 v18, v0, v0
	v_and_b32_e32 v1, 0xffff0000, v1
	v_fmac_f32_e32 v18, v5, v5
	v_lshlrev_b32_e32 v6, 16, v2
	v_fmac_f32_e32 v18, v1, v1
	v_and_b32_e32 v2, 0xffff0000, v2
	v_fmac_f32_e32 v18, v6, v6
	v_lshlrev_b32_e32 v7, 16, v3
	v_fmac_f32_e32 v18, v2, v2
	v_and_b32_e32 v3, 0xffff0000, v3
	v_fmac_f32_e32 v18, v7, v7
	v_fmac_f32_e32 v18, v3, v3
	ds_bpermute_b32 v0, v249, v18
	s_waitcnt lgkmcnt(0)
	v_add_f32_e32 v0, v18, v0
	ds_bpermute_b32 v1, v250, v0
	s_and_saveexec_b64 s[0:1], s[8:9]
	s_cbranch_execz .LBB0_780
	s_waitcnt lgkmcnt(0)
	v_add_f32_e32 v0, v0, v1
	v_fma_f32 v0, v0, s6, 0.5
	v_trunc_f32_e32 v0, v0
	v_mul_f32_e32 v1, 0x2f800000, v0
	v_floor_f32_e32 v1, v1
	v_fmac_f32_e32 v0, 0xcf800000, v1
	v_cvt_u32_f32_e32 v0, v0
	v_cvt_u32_f32_e32 v1, v1
	global_atomic_add_x2 v[112:113], v[0:1], off offset:1408

.LBB0_789:
	s_and_b32 s2, s13, 0x70
	v_or_b32_e32 v5, s2, v12
	v_mul_u32_u24_e32 v6, 0xa00, v5
	s_and_b32 s6, s14, 0xffffffe0
	v_lshlrev_b32_e32 v194, 1, v6
	v_or_b32_e32 v6, s6, v12
	v_ashrrev_i32_e32 v7, 31, v6
	v_lshlrev_b64 v[8:9], 11, v[6:7]
	v_lshl_add_u64 v[34:35], v[2:3], 0, v[8:9]
	v_or_b32_e32 v14, 16, v6
	global_load_dwordx4 v[6:9], v[34:35], off
	v_ashrrev_i32_e32 v15, 31, v14
	v_lshl_add_u64 v[10:11], v[0:1], 0, v[194:195]
	v_lshlrev_b64 v[14:15], 11, v[14:15]
	v_lshl_add_u64 v[36:37], v[2:3], 0, v[14:15]
	global_load_dwordx4 v[14:17], v[10:11], off
	global_load_dwordx4 v[18:21], v[36:37], off
	global_load_dwordx4 v[22:25], v[34:35], off offset:64
	global_load_dwordx4 v[26:29], v[10:11], off offset:64
	s_andn2_b64 vcc, exec, s[4:5]
	s_waitcnt vmcnt(0) lgkmcnt(0)
	v_mfma_f32_16x16x32_bf16 v[6:9], v[6:9], v[14:17], 0
	v_mfma_f32_16x16x32_bf16 v[14:17], v[18:21], v[14:17], 0
	global_load_dwordx4 v[18:21], v[36:37], off offset:64
	v_mfma_f32_16x16x32_bf16 v[6:9], v[22:25], v[26:29], v[6:9]
	global_load_dwordx4 v[22:25], v[34:35], off offset:128
	global_load_dwordx4 v[30:33], v[10:11], off offset:128
	s_waitcnt vmcnt(0) lgkmcnt(0)
	v_mfma_f32_16x16x32_bf16 v[14:17], v[18:21], v[26:29], v[14:17]
	global_load_dwordx4 v[18:21], v[36:37], off offset:128
	v_mfma_f32_16x16x32_bf16 v[6:9], v[22:25], v[30:33], v[6:9]
	global_load_dwordx4 v[22:25], v[34:35], off offset:192
	global_load_dwordx4 v[26:29], v[36:37], off offset:192
	s_waitcnt vmcnt(0) lgkmcnt(0)
	v_mfma_f32_16x16x32_bf16 v[14:17], v[18:21], v[30:33], v[14:17]
	global_load_dwordx4 v[18:21], v[10:11], off offset:192
	v_add_u32_e32 v10, s12, v13
	s_waitcnt vmcnt(0) lgkmcnt(0)
	v_mfma_f32_16x16x32_bf16 v[6:9], v[22:25], v[18:21], v[6:9]
	v_mfma_f32_16x16x32_bf16 v[14:17], v[26:29], v[18:21], v[14:17]
	s_nop 6
	ds_write_b128 v10, v[6:9]
	ds_write_b128 v10, v[14:17] offset:16
	s_waitcnt lgkmcnt(0)
	s_barrier
	s_cbranch_vccnz .LBB0_788
	v_add_u32_e32 v24, 0, v13
	ds_read_b128 v[6:9], v24
	ds_read_b128 v[14:17], v24 offset:16
	s_ashr_i32 s7, s6, 31
	s_waitcnt lgkmcnt(1)
	v_pk_add_f32 v[10:11], v[8:9], 0 op_sel_hi:[1,0]
	v_pk_add_f32 v[18:19], v[6:7], 0 op_sel_hi:[1,0]
	ds_read_b128 v[6:9], v24 offset:2048
	s_waitcnt lgkmcnt(1)
	v_pk_add_f32 v[16:17], v[16:17], 0 op_sel_hi:[1,0]
	v_pk_add_f32 v[14:15], v[14:15], 0 op_sel_hi:[1,0]
	s_waitcnt lgkmcnt(0)
	v_pk_add_f32 v[10:11], v[10:11], v[8:9]
	v_pk_add_f32 v[18:19], v[18:19], v[6:7]
	ds_read_b128 v[6:9], v24 offset:2064
	s_waitcnt lgkmcnt(0)
	v_pk_add_f32 v[16:17], v[16:17], v[8:9]
	v_pk_add_f32 v[14:15], v[14:15], v[6:7]
	ds_read_b128 v[6:9], v24 offset:4096
	s_waitcnt lgkmcnt(0)
	v_pk_add_f32 v[10:11], v[10:11], v[8:9]
	v_pk_add_f32 v[18:19], v[18:19], v[6:7]
	ds_read_b128 v[6:9], v24 offset:4112
	s_waitcnt lgkmcnt(0)
	v_pk_add_f32 v[16:17], v[16:17], v[8:9]
	v_pk_add_f32 v[14:15], v[14:15], v[6:7]
	ds_read_b128 v[6:9], v24 offset:6144
	s_waitcnt lgkmcnt(0)
	v_pk_add_f32 v[10:11], v[10:11], v[8:9]
	v_pk_add_f32 v[18:19], v[18:19], v[6:7]
	ds_read_b128 v[6:9], v24 offset:6160
	s_waitcnt lgkmcnt(0)
	v_pk_add_f32 v[16:17], v[16:17], v[8:9]
	v_pk_add_f32 v[14:15], v[14:15], v[6:7]
	ds_read_b128 v[6:9], v24 offset:8192
	s_waitcnt lgkmcnt(0)
	v_pk_add_f32 v[10:11], v[10:11], v[8:9]
	v_pk_add_f32 v[18:19], v[18:19], v[6:7]
	ds_read_b128 v[6:9], v24 offset:8208
	s_waitcnt lgkmcnt(0)
	v_pk_add_f32 v[16:17], v[16:17], v[8:9]
	v_pk_add_f32 v[14:15], v[14:15], v[6:7]
	ds_read_b128 v[6:9], v24 offset:10240
	s_waitcnt lgkmcnt(0)
	v_pk_add_f32 v[10:11], v[10:11], v[8:9]
	v_pk_add_f32 v[18:19], v[18:19], v[6:7]
	ds_read_b128 v[6:9], v24 offset:10256
	s_waitcnt lgkmcnt(0)
	v_pk_add_f32 v[16:17], v[16:17], v[8:9]
	v_pk_add_f32 v[14:15], v[14:15], v[6:7]
	ds_read_b128 v[6:9], v24 offset:12288
	s_waitcnt lgkmcnt(0)
	v_pk_add_f32 v[10:11], v[10:11], v[8:9]
	v_pk_add_f32 v[18:19], v[18:19], v[6:7]
	ds_read_b128 v[6:9], v24 offset:12304
	s_waitcnt lgkmcnt(0)
	v_pk_add_f32 v[20:21], v[16:17], v[8:9]
	v_pk_add_f32 v[22:23], v[14:15], v[6:7]
	ds_read_b128 v[6:9], v24 offset:14336
	ds_read_b128 v[14:17], v24 offset:14352
	s_waitcnt lgkmcnt(1)
	v_pk_add_f32 v[8:9], v[10:11], v[8:9]
	s_waitcnt lgkmcnt(0)
	v_pk_add_f32 v[10:11], v[22:23], v[14:15]
	v_or_b32_e32 v14, 0x4000, v5
	v_lshlrev_b32_e32 v194, 11, v14
	v_pk_add_f32 v[18:19], v[18:19], v[6:7]
	v_pk_add_f32 v[6:7], v[20:21], v[16:17]
	v_lshl_add_u64 v[16:17], s[0:1], 0, v[194:195]
	v_lshl_add_u64 v[16:17], s[6:7], 1, v[16:17]
	v_mov_b32_e32 v5, v195
	v_lshl_add_u64 v[16:17], v[16:17], 0, v[4:5]
	global_load_dwordx2 v[20:21], v[16:17], off
	global_load_dwordx2 v[22:23], v[16:17], off offset:32
	s_waitcnt vmcnt(0) lgkmcnt(0)
	v_lshlrev_b32_e32 v24, 16, v20
	v_and_b32_e32 v25, 0xffff0000, v20
	v_lshlrev_b32_e32 v20, 16, v21
	v_and_b32_e32 v21, 0xffff0000, v21
	v_pk_add_f32 v[18:19], v[18:19], v[24:25]
	v_pk_add_f32 v[8:9], v[8:9], v[20:21]
	v_cvt_pk_bf16_f32 v18, v18, v19
	v_cvt_pk_bf16_f32 v19, v8, v9
	v_lshlrev_b32_e32 v8, 16, v22
	v_and_b32_e32 v9, 0xffff0000, v22
	v_pk_add_f32 v[8:9], v[10:11], v[8:9]
	v_lshlrev_b32_e32 v10, 16, v23
	v_and_b32_e32 v11, 0xffff0000, v23
	v_pk_add_f32 v[6:7], v[6:7], v[10:11]
	v_cvt_pk_bf16_f32 v8, v8, v9
	v_cvt_pk_bf16_f32 v9, v6, v7
	v_and_b32_e32 v6, 0xffff0000, v18
	v_lshlrev_b32_e32 v5, 16, v18
	v_and_b32_e32 v10, 0xffff0000, v19
	v_mul_f32_e32 v6, v6, v6
	v_lshlrev_b32_e32 v7, 16, v19
	v_fmac_f32_e32 v6, v5, v5
	v_mul_f32_e32 v5, v10, v10
	global_store_dwordx2 v[16:17], v[18:19], off
	global_store_dwordx2 v[16:17], v[8:9], off offset:32
	v_lshlrev_b32_e32 v11, 16, v8
	v_and_b32_e32 v8, 0xffff0000, v8
	v_fmac_f32_e32 v5, v7, v7
	v_add_f32_e32 v5, v6, v5
	v_mul_f32_e32 v6, v8, v8
	v_lshlrev_b32_e32 v15, 16, v9
	v_and_b32_e32 v9, 0xffff0000, v9
	v_fmac_f32_e32 v6, v11, v11
	v_add_f32_e32 v5, v5, v6
	v_mul_f32_e32 v6, v9, v9
	v_fmac_f32_e32 v6, v15, v15
	v_and_b32_e32 v7, 64, v243
	v_add_f32_e32 v5, v6, v5
	v_xor_b32_e32 v6, 16, v243
	v_add_u32_e32 v7, 64, v7
	v_cmp_lt_i32_e32 vcc, v6, v7
	s_nop 1
	v_cndmask_b32_e32 v6, v243, v6, vcc
	v_lshlrev_b32_e32 v6, 2, v6
	ds_bpermute_b32 v6, v6, v5
	s_waitcnt lgkmcnt(0)
	v_add_f32_e32 v5, v5, v6
	v_xor_b32_e32 v6, 32, v243
	v_cmp_lt_i32_e32 vcc, v6, v7
	s_nop 1
	v_cndmask_b32_e32 v6, v243, v6, vcc
	v_lshlrev_b32_e32 v6, 2, v6
	ds_bpermute_b32 v6, v6, v5
	s_and_saveexec_b64 s[2:3], s[8:9]
	s_cbranch_execz .LBB0_787
	s_waitcnt lgkmcnt(0)
	v_add_f32_e32 v5, v5, v6
	s_mov_b32 s6, 0x4b800000
	v_fma_f32 v5, v5, s6, 0.5
	v_trunc_f32_e32 v5, v5
	v_mul_f32_e32 v6, 0x2f800000, v5
	v_floor_f32_e32 v7, v6
	v_fmac_f32_e32 v5, 0xcf800000, v7
	v_cvt_u32_f32_e32 v6, v5
	v_cvt_u32_f32_e32 v7, v7
	v_lshlrev_b32_e32 v194, 3, v14
	v_lshl_add_u64 v[8:9], s[10:11], 0, v[194:195]
	global_atomic_add_x2 v[8:9], v[6:7], off
	s_branch .LBB0_787

.LBB0_862:
	s_add_u32 s2, s6, 0xfffc0080
	s_addc_u32 s3, s7, -1
	s_add_i32 s56, 0, 0x10000
	v_add_u32_e32 v150, s56, v159
	ds_read_b128 v[138:141], v150
	ds_read_b128 v[142:145], v150 offset:1024
	ds_read_b128 v[146:149], v150 offset:2048
	ds_read_b128 v[150:153], v150 offset:3072
	s_cmp_eq_u32 s41, 12
	s_cselect_b32 s21, s17, s3
	s_cselect_b32 s20, s39, s2
	s_cselect_b32 s3, s15, s23
	s_cselect_b32 s2, s40, s22
	v_lshl_add_u64 v[154:155], s[6:7], 0, v[136:137]
	s_add_i32 m0, s28, 0xc000
	ds_read_b128 v[162:165], v161
	ds_read_b128 v[166:169], v161 offset:1024
	ds_read_b128 v[170:173], v161 offset:2048
	ds_read_b128 v[174:177], v161 offset:3072
	ds_read_b128 v[178:181], v161 offset:4096
	ds_read_b128 v[182:185], v161 offset:5120
	ds_read_b128 v[186:189], v161 offset:6144
	ds_read_b128 v[206:209], v161 offset:7168
	global_load_lds_dwordx4 v[154:155], off
	v_lshl_add_u64 v[154:155], s[6:7], 0, v[134:135]
	s_add_i32 m0, s28, 0xe000
	s_nop 0
	global_load_lds_dwordx4 v[154:155], off
	s_waitcnt lgkmcnt(8)
	s_barrier
	s_waitcnt lgkmcnt(0)
	s_setprio 1
	s_waitcnt lgkmcnt(0)
	v_mfma_f32_16x16x32_bf16 v[120:123], v[138:141], v[162:165], v[120:123]
	v_mfma_f32_16x16x32_bf16 v[112:115], v[146:149], v[162:165], v[112:115]
	v_mfma_f32_16x16x32_bf16 v[104:107], v[138:141], v[170:173], v[104:107]
	v_mfma_f32_16x16x32_bf16 v[96:99], v[146:149], v[170:173], v[96:99]
	v_mfma_f32_16x16x32_bf16 v[88:91], v[138:141], v[178:181], v[88:91]
	v_mfma_f32_16x16x32_bf16 v[80:83], v[146:149], v[178:181], v[80:83]
	v_mfma_f32_16x16x32_bf16 v[72:75], v[138:141], v[186:189], v[72:75]
	v_mfma_f32_16x16x32_bf16 v[64:67], v[146:149], v[186:189], v[64:67]
	v_mfma_f32_16x16x32_bf16 v[120:123], v[142:145], v[166:169], v[120:123]
	v_mfma_f32_16x16x32_bf16 v[112:115], v[150:153], v[166:169], v[112:115]
	v_mfma_f32_16x16x32_bf16 v[104:107], v[142:145], v[174:177], v[104:107]
	v_mfma_f32_16x16x32_bf16 v[96:99], v[150:153], v[174:177], v[96:99]
	v_mfma_f32_16x16x32_bf16 v[88:91], v[142:145], v[182:185], v[88:91]
	v_mfma_f32_16x16x32_bf16 v[80:83], v[150:153], v[182:185], v[80:83]
	v_mfma_f32_16x16x32_bf16 v[72:75], v[142:145], v[206:209], v[72:75]
	v_mfma_f32_16x16x32_bf16 v[64:67], v[150:153], v[206:209], v[64:67]
	s_setprio 0
	s_barrier
	s_add_i32 s58, 0, 0x14000
	v_add_u32_e32 v154, s58, v159
	s_add_i32 s56, s56, s27
	ds_read_b128 v[210:213], v154
	ds_read_b128 v[214:217], v154 offset:1024
	ds_read_b128 v[218:221], v154 offset:2048
	ds_read_b128 v[222:225], v154 offset:3072
	v_lshl_add_u64 v[154:155], s[2:3], 0, v[194:195]
	s_mov_b32 m0, s56
	v_lshl_add_u64 v[190:191], s[2:3], 0, v[128:129]
	global_load_lds_dwordx4 v[154:155], off
	s_add_i32 m0, s56, 0x2000
	s_nop 0
	global_load_lds_dwordx4 v[190:191], off
	s_barrier
	s_waitcnt lgkmcnt(0)
	s_setprio 1
	s_waitcnt lgkmcnt(0)
	v_mfma_f32_16x16x32_bf16 v[124:127], v[210:213], v[162:165], v[124:127]
	v_mfma_f32_16x16x32_bf16 v[116:119], v[218:221], v[162:165], v[116:119]
	v_mfma_f32_16x16x32_bf16 v[108:111], v[210:213], v[170:173], v[108:111]
	v_mfma_f32_16x16x32_bf16 v[100:103], v[218:221], v[170:173], v[100:103]
	v_mfma_f32_16x16x32_bf16 v[92:95], v[210:213], v[178:181], v[92:95]
	v_mfma_f32_16x16x32_bf16 v[84:87], v[218:221], v[178:181], v[84:87]
	v_mfma_f32_16x16x32_bf16 v[76:79], v[210:213], v[186:189], v[76:79]
	v_mfma_f32_16x16x32_bf16 v[68:71], v[218:221], v[186:189], v[68:71]
	v_mfma_f32_16x16x32_bf16 v[124:127], v[214:217], v[166:169], v[124:127]
	v_mfma_f32_16x16x32_bf16 v[116:119], v[222:225], v[166:169], v[116:119]
	v_mfma_f32_16x16x32_bf16 v[108:111], v[214:217], v[174:177], v[108:111]
	v_mfma_f32_16x16x32_bf16 v[100:103], v[222:225], v[174:177], v[100:103]
	v_mfma_f32_16x16x32_bf16 v[92:95], v[214:217], v[182:185], v[92:95]
	v_mfma_f32_16x16x32_bf16 v[84:87], v[222:225], v[182:185], v[84:87]
	v_mfma_f32_16x16x32_bf16 v[76:79], v[214:217], v[206:209], v[76:79]
	v_mfma_f32_16x16x32_bf16 v[68:71], v[222:225], v[206:209], v[68:71]
	s_setprio 0
	s_mov_b32 m0, s28
	v_lshl_add_u64 v[202:203], s[20:21], 0, v[132:133]
	s_barrier
	ds_read_b128 v[162:165], v161 offset:16384
	ds_read_b128 v[166:169], v161 offset:17408
	ds_read_b128 v[170:173], v161 offset:18432
	ds_read_b128 v[174:177], v161 offset:19456
	ds_read_b128 v[178:181], v161 offset:20480
	ds_read_b128 v[182:185], v161 offset:21504
	ds_read_b128 v[186:189], v161 offset:22528
	ds_read_b128 v[206:209], v161 offset:23552
	global_load_lds_dwordx4 v[202:203], off
	v_lshl_add_u64 v[226:227], s[20:21], 0, v[130:131]
	s_mov_b32 m0, s29
	s_nop 0
	global_load_lds_dwordx4 v[226:227], off
	s_barrier
	s_waitcnt lgkmcnt(0)
	s_setprio 1
	s_waitcnt lgkmcnt(0)
	v_mfma_f32_16x16x32_bf16 v[56:59], v[138:141], v[162:165], v[56:59]
	v_mfma_f32_16x16x32_bf16 v[48:51], v[146:149], v[162:165], v[48:51]
	v_mfma_f32_16x16x32_bf16 v[40:43], v[138:141], v[170:173], v[40:43]
	v_mfma_f32_16x16x32_bf16 v[32:35], v[146:149], v[170:173], v[32:35]
	v_mfma_f32_16x16x32_bf16 v[24:27], v[138:141], v[178:181], v[24:27]
	v_mfma_f32_16x16x32_bf16 v[16:19], v[146:149], v[178:181], v[16:19]
	v_mfma_f32_16x16x32_bf16 v[8:11], v[138:141], v[186:189], v[8:11]
	v_mfma_f32_16x16x32_bf16 v[0:3], v[146:149], v[186:189], v[0:3]
	v_mfma_f32_16x16x32_bf16 v[56:59], v[142:145], v[166:169], v[56:59]
	v_mfma_f32_16x16x32_bf16 v[48:51], v[150:153], v[166:169], v[48:51]
	v_mfma_f32_16x16x32_bf16 v[40:43], v[142:145], v[174:177], v[40:43]
	v_mfma_f32_16x16x32_bf16 v[32:35], v[150:153], v[174:177], v[32:35]
	v_mfma_f32_16x16x32_bf16 v[24:27], v[142:145], v[182:185], v[24:27]
	v_mfma_f32_16x16x32_bf16 v[16:19], v[150:153], v[182:185], v[16:19]
	v_mfma_f32_16x16x32_bf16 v[8:11], v[142:145], v[206:209], v[8:11]
	v_mfma_f32_16x16x32_bf16 v[0:3], v[150:153], v[206:209], v[0:3]
	s_setprio 0
	s_barrier
	s_add_u32 s56, s2, 0x40000
	s_addc_u32 s57, s3, 0
	s_add_i32 s58, s58, s27
	v_lshl_add_u64 v[138:139], s[56:57], 0, v[194:195]
	s_mov_b32 m0, s58
	s_nop 0
	global_load_lds_dwordx4 v[138:139], off
	v_lshl_add_u64 v[138:139], s[56:57], 0, v[128:129]
	s_add_i32 m0, s58, 0x2000
	s_nop 0
	global_load_lds_dwordx4 v[138:139], off
	s_waitcnt vmcnt(6)
	s_barrier
	s_setprio 1
	v_mfma_f32_16x16x32_bf16 v[60:63], v[210:213], v[162:165], v[60:63]
	v_mfma_f32_16x16x32_bf16 v[52:55], v[218:221], v[162:165], v[52:55]
	v_mfma_f32_16x16x32_bf16 v[44:47], v[210:213], v[170:173], v[44:47]
	v_mfma_f32_16x16x32_bf16 v[36:39], v[218:221], v[170:173], v[36:39]
	v_mfma_f32_16x16x32_bf16 v[28:31], v[210:213], v[178:181], v[28:31]
	v_mfma_f32_16x16x32_bf16 v[20:23], v[218:221], v[178:181], v[20:23]
	v_mfma_f32_16x16x32_bf16 v[12:15], v[210:213], v[186:189], v[12:15]
	v_mfma_f32_16x16x32_bf16 v[4:7], v[218:221], v[186:189], v[4:7]
	v_mfma_f32_16x16x32_bf16 v[60:63], v[214:217], v[166:169], v[60:63]
	v_mfma_f32_16x16x32_bf16 v[52:55], v[222:225], v[166:169], v[52:55]
	v_mfma_f32_16x16x32_bf16 v[44:47], v[214:217], v[174:177], v[44:47]
	v_mfma_f32_16x16x32_bf16 v[36:39], v[222:225], v[174:177], v[36:39]
	v_mfma_f32_16x16x32_bf16 v[28:31], v[214:217], v[182:185], v[28:31]
	v_mfma_f32_16x16x32_bf16 v[20:23], v[222:225], v[182:185], v[20:23]
	v_mfma_f32_16x16x32_bf16 v[12:15], v[214:217], v[206:209], v[12:15]
	v_mfma_f32_16x16x32_bf16 v[4:7], v[222:225], v[206:209], v[4:7]
	s_setprio 0
	s_add_i32 s56, 0, 0x18000
	v_add_u32_e32 v150, s56, v159
	s_barrier
	ds_read_b128 v[138:141], v150
	ds_read_b128 v[142:145], v150 offset:1024
	ds_read_b128 v[146:149], v150 offset:2048
	ds_read_b128 v[150:153], v150 offset:3072
	s_add_u32 s20, s20, 0x40000
	s_addc_u32 s21, s21, 0
	s_mov_b32 m0, s30
	v_lshl_add_u64 v[210:211], s[20:21], 0, v[132:133]
	ds_read_b128 v[162:165], v161 offset:32768
	ds_read_b128 v[166:169], v161 offset:33792
	ds_read_b128 v[170:173], v161 offset:34816
	ds_read_b128 v[174:177], v161 offset:35840
	ds_read_b128 v[178:181], v161 offset:36864
	ds_read_b128 v[182:185], v161 offset:37888
	ds_read_b128 v[186:189], v161 offset:38912
	ds_read_b128 v[206:209], v161 offset:39936
	global_load_lds_dwordx4 v[210:211], off
	v_lshl_add_u64 v[210:211], s[20:21], 0, v[130:131]
	s_mov_b32 m0, s31
	s_nop 0
	global_load_lds_dwordx4 v[210:211], off
	s_waitcnt lgkmcnt(8)
	s_barrier
	s_waitcnt lgkmcnt(0)
	s_setprio 1
	s_waitcnt lgkmcnt(0)
	v_mfma_f32_16x16x32_bf16 v[120:123], v[138:141], v[162:165], v[120:123]
	v_mfma_f32_16x16x32_bf16 v[112:115], v[146:149], v[162:165], v[112:115]
	v_mfma_f32_16x16x32_bf16 v[104:107], v[138:141], v[170:173], v[104:107]
	v_mfma_f32_16x16x32_bf16 v[96:99], v[146:149], v[170:173], v[96:99]
	v_mfma_f32_16x16x32_bf16 v[88:91], v[138:141], v[178:181], v[88:91]
	v_mfma_f32_16x16x32_bf16 v[80:83], v[146:149], v[178:181], v[80:83]
	v_mfma_f32_16x16x32_bf16 v[72:75], v[138:141], v[186:189], v[72:75]
	v_mfma_f32_16x16x32_bf16 v[64:67], v[146:149], v[186:189], v[64:67]
	v_mfma_f32_16x16x32_bf16 v[120:123], v[142:145], v[166:169], v[120:123]
	v_mfma_f32_16x16x32_bf16 v[112:115], v[150:153], v[166:169], v[112:115]
	v_mfma_f32_16x16x32_bf16 v[104:107], v[142:145], v[174:177], v[104:107]
	v_mfma_f32_16x16x32_bf16 v[96:99], v[150:153], v[174:177], v[96:99]
	v_mfma_f32_16x16x32_bf16 v[88:91], v[142:145], v[182:185], v[88:91]
	v_mfma_f32_16x16x32_bf16 v[80:83], v[150:153], v[182:185], v[80:83]
	v_mfma_f32_16x16x32_bf16 v[72:75], v[142:145], v[206:209], v[72:75]
	v_mfma_f32_16x16x32_bf16 v[64:67], v[150:153], v[206:209], v[64:67]
	s_setprio 0
	s_barrier
	s_add_i32 s20, 0, 0x1c000
	s_add_i32 s21, s56, s27
	v_add_u32_e32 v156, s20, v159
	v_lshl_add_u64 v[154:155], v[154:155], 0, s[70:71]
	s_mov_b32 m0, s21
	ds_read_b128 v[210:213], v156
	ds_read_b128 v[214:217], v156 offset:1024
	ds_read_b128 v[218:221], v156 offset:2048
	ds_read_b128 v[222:225], v156 offset:3072
	global_load_lds_dwordx4 v[154:155], off
	v_lshl_add_u64 v[154:155], v[190:191], 0, s[70:71]
	s_add_i32 m0, s21, 0x2000
	s_nop 0
	global_load_lds_dwordx4 v[154:155], off
	s_barrier
	s_waitcnt lgkmcnt(0)
	s_setprio 1
	s_waitcnt lgkmcnt(0)
	v_mfma_f32_16x16x32_bf16 v[124:127], v[210:213], v[162:165], v[124:127]
	v_mfma_f32_16x16x32_bf16 v[116:119], v[218:221], v[162:165], v[116:119]
	v_mfma_f32_16x16x32_bf16 v[108:111], v[210:213], v[170:173], v[108:111]
	v_mfma_f32_16x16x32_bf16 v[100:103], v[218:221], v[170:173], v[100:103]
	v_mfma_f32_16x16x32_bf16 v[92:95], v[210:213], v[178:181], v[92:95]
	v_mfma_f32_16x16x32_bf16 v[84:87], v[218:221], v[178:181], v[84:87]
	v_mfma_f32_16x16x32_bf16 v[76:79], v[210:213], v[186:189], v[76:79]
	v_mfma_f32_16x16x32_bf16 v[68:71], v[218:221], v[186:189], v[68:71]
	v_mfma_f32_16x16x32_bf16 v[124:127], v[214:217], v[166:169], v[124:127]
	v_mfma_f32_16x16x32_bf16 v[116:119], v[222:225], v[166:169], v[116:119]
	v_mfma_f32_16x16x32_bf16 v[108:111], v[214:217], v[174:177], v[108:111]
	v_mfma_f32_16x16x32_bf16 v[100:103], v[222:225], v[174:177], v[100:103]
	v_mfma_f32_16x16x32_bf16 v[92:95], v[214:217], v[182:185], v[92:95]
	v_mfma_f32_16x16x32_bf16 v[84:87], v[222:225], v[182:185], v[84:87]
	v_mfma_f32_16x16x32_bf16 v[76:79], v[214:217], v[206:209], v[76:79]
	v_mfma_f32_16x16x32_bf16 v[68:71], v[222:225], v[206:209], v[68:71]
	s_setprio 0
	s_mov_b32 m0, s34
	v_lshl_add_u64 v[154:155], v[202:203], 0, s[70:71]
	s_barrier
	ds_read_b128 v[162:165], v161 offset:49152
	ds_read_b128 v[166:169], v161 offset:50176
	ds_read_b128 v[170:173], v161 offset:51200
	ds_read_b128 v[174:177], v161 offset:52224
	ds_read_b128 v[178:181], v161 offset:53248
	ds_read_b128 v[182:185], v161 offset:54272
	ds_read_b128 v[186:189], v161 offset:55296
	ds_read_b128 v[206:209], v161 offset:56320
	global_load_lds_dwordx4 v[154:155], off
	v_lshl_add_u64 v[154:155], v[226:227], 0, s[70:71]
	s_mov_b32 m0, s35
	s_nop 0
	global_load_lds_dwordx4 v[154:155], off
	s_barrier
	s_waitcnt lgkmcnt(0)
	s_setprio 1
	s_waitcnt lgkmcnt(0)
	v_mfma_f32_16x16x32_bf16 v[56:59], v[138:141], v[162:165], v[56:59]
	v_mfma_f32_16x16x32_bf16 v[48:51], v[146:149], v[162:165], v[48:51]
	v_mfma_f32_16x16x32_bf16 v[40:43], v[138:141], v[170:173], v[40:43]
	v_mfma_f32_16x16x32_bf16 v[32:35], v[146:149], v[170:173], v[32:35]
	v_mfma_f32_16x16x32_bf16 v[24:27], v[138:141], v[178:181], v[24:27]
	v_mfma_f32_16x16x32_bf16 v[16:19], v[146:149], v[178:181], v[16:19]
	v_mfma_f32_16x16x32_bf16 v[8:11], v[138:141], v[186:189], v[8:11]
	v_mfma_f32_16x16x32_bf16 v[0:3], v[146:149], v[186:189], v[0:3]
	v_mfma_f32_16x16x32_bf16 v[56:59], v[142:145], v[166:169], v[56:59]
	v_mfma_f32_16x16x32_bf16 v[48:51], v[150:153], v[166:169], v[48:51]
	v_mfma_f32_16x16x32_bf16 v[40:43], v[142:145], v[174:177], v[40:43]
	v_mfma_f32_16x16x32_bf16 v[32:35], v[150:153], v[174:177], v[32:35]
	v_mfma_f32_16x16x32_bf16 v[24:27], v[142:145], v[182:185], v[24:27]
	v_mfma_f32_16x16x32_bf16 v[16:19], v[150:153], v[182:185], v[16:19]
	v_mfma_f32_16x16x32_bf16 v[8:11], v[142:145], v[206:209], v[8:11]
	v_mfma_f32_16x16x32_bf16 v[0:3], v[150:153], v[206:209], v[0:3]
	s_setprio 0
	s_barrier
	s_add_u32 s2, s2, 0x40080
	s_addc_u32 s3, s3, 0
	s_add_i32 s20, s20, s27
	v_lshl_add_u64 v[138:139], s[2:3], 0, v[194:195]
	s_mov_b32 m0, s20
	s_nop 0
	global_load_lds_dwordx4 v[138:139], off
	v_lshl_add_u64 v[138:139], s[2:3], 0, v[128:129]
	s_add_i32 m0, s20, 0x2000
	s_nop 0
	global_load_lds_dwordx4 v[138:139], off
	s_waitcnt vmcnt(6)
	s_barrier
	s_setprio 1
	v_mfma_f32_16x16x32_bf16 v[60:63], v[210:213], v[162:165], v[60:63]
	v_mfma_f32_16x16x32_bf16 v[52:55], v[218:221], v[162:165], v[52:55]
	v_mfma_f32_16x16x32_bf16 v[44:47], v[210:213], v[170:173], v[44:47]
	v_mfma_f32_16x16x32_bf16 v[36:39], v[218:221], v[170:173], v[36:39]
	v_mfma_f32_16x16x32_bf16 v[28:31], v[210:213], v[178:181], v[28:31]
	v_mfma_f32_16x16x32_bf16 v[20:23], v[218:221], v[178:181], v[20:23]
	v_mfma_f32_16x16x32_bf16 v[12:15], v[210:213], v[186:189], v[12:15]
	v_mfma_f32_16x16x32_bf16 v[4:7], v[218:221], v[186:189], v[4:7]
	v_mfma_f32_16x16x32_bf16 v[60:63], v[214:217], v[166:169], v[60:63]
	v_mfma_f32_16x16x32_bf16 v[52:55], v[222:225], v[166:169], v[52:55]
	v_mfma_f32_16x16x32_bf16 v[44:47], v[214:217], v[174:177], v[44:47]
	v_mfma_f32_16x16x32_bf16 v[36:39], v[222:225], v[174:177], v[36:39]
	v_mfma_f32_16x16x32_bf16 v[28:31], v[214:217], v[182:185], v[28:31]
	v_mfma_f32_16x16x32_bf16 v[20:23], v[222:225], v[182:185], v[20:23]
	v_mfma_f32_16x16x32_bf16 v[12:15], v[214:217], v[206:209], v[12:15]
	v_mfma_f32_16x16x32_bf16 v[4:7], v[222:225], v[206:209], v[4:7]
	s_setprio 0
	s_add_i32 s41, s41, 2
	s_add_u32 s22, s22, 0x100
	s_addc_u32 s23, s23, 0
	s_add_u32 s6, s6, 0x100
	s_addc_u32 s7, s7, 0
	s_cmp_gt_u32 s41, 13
	s_barrier
	s_cbranch_scc0 .LBB0_862
	v_lshl_add_u32 v138, s38, 8, v158
	v_ashrrev_i32_e32 v139, 31, v138
	v_lshl_add_u64 v[140:141], v[138:139], 3, s[12:13]
	global_load_dwordx2 v[162:163], v[140:141], off
	global_load_dwordx2 v[152:153], v[140:141], off offset:128
	global_load_dwordx2 v[150:151], v[140:141], off offset:256
	global_load_dwordx2 v[148:149], v[140:141], off offset:384
	s_mov_b32 s20, 0x800000
	v_lshl_or_b32 v154, s37, 7, v160
	v_ashrrev_i32_e32 v155, 31, v154
	s_movk_i32 s6, 0x1600
	global_load_dwordx2 v[146:147], v[140:141], off offset:1024
	global_load_dwordx2 v[144:145], v[140:141], off offset:1152
	global_load_dwordx2 v[142:143], v[140:141], off offset:1280
	s_nop 0
	global_load_dwordx2 v[140:141], v[140:141], off offset:1408
	v_add_u32_e32 v139, 0x80, v138
	s_waitcnt vmcnt(0) lgkmcnt(0)
	v_ffbh_u32_e32 v156, v163
	v_min_u32_e32 v156, 32, v156
	v_lshlrev_b64 v[162:163], v156, v[162:163]
	v_min_u32_e32 v162, 1, v162
	v_or_b32_e32 v162, v163, v162
	v_cvt_f32_u32_e32 v162, v162
	v_sub_u32_e32 v156, 32, v156
	v_ldexp_f32 v156, v162, v156
	v_fmamk_f32 v156, v156, 0x2e800000, v236
	v_cmp_gt_f32_e32 vcc, s20, v156
	v_mul_f32_e32 v162, 0x4b800000, v156
	s_nop 0
	v_cndmask_b32_e32 v156, v156, v162, vcc
	v_rsq_f32_e32 v156, v156
	s_nop 0
	v_mul_f32_e32 v162, 0x45800000, v156
	v_cndmask_b32_e32 v156, v156, v162, vcc
	v_pk_mul_f32 v[120:121], v[120:121], v[156:157] op_sel_hi:[1,0]
	v_pk_mul_f32 v[124:125], v[124:125], v[156:157] op_sel_hi:[1,0]
	v_mul_f32_e32 v162, 0xbfb8aa3b, v120
	v_mul_f32_e32 v163, 0xbfb8aa3b, v121
	v_exp_f32_e32 v162, v162
	v_exp_f32_e32 v163, v163
	v_pk_mul_f32 v[122:123], v[122:123], v[156:157] op_sel_hi:[1,0]
	v_pk_mul_f32 v[112:113], v[112:113], v[156:157] op_sel_hi:[1,0]
	v_pk_mul_f32 v[126:127], v[126:127], v[156:157] op_sel_hi:[1,0]
	v_pk_add_f32 v[162:163], v[162:163], 1.0 op_sel_hi:[1,0]
	v_pk_mul_f32 v[116:117], v[116:117], v[156:157] op_sel_hi:[1,0]
	v_pk_mul_f32 v[114:115], v[114:115], v[156:157] op_sel_hi:[1,0]
	v_pk_mul_f32 v[118:119], v[118:119], v[156:157] op_sel_hi:[1,0]
	v_rcp_f32_e32 v163, v163
	v_rcp_f32_e32 v162, v162
	s_nop 0
	v_pk_mul_f32 v[120:121], v[120:121], v[162:163]
	s_nop 0
	v_pk_mul_f32 v[120:121], v[124:125], v[120:121]
	v_mul_f32_e32 v124, 0xbfb8aa3b, v122
	v_mul_f32_e32 v125, 0xbfb8aa3b, v123
	v_exp_f32_e32 v124, v124
	v_exp_f32_e32 v125, v125
	s_nop 0
	v_pk_add_f32 v[124:125], v[124:125], 1.0 op_sel_hi:[1,0]
	s_nop 0
	v_rcp_f32_e32 v125, v125
	v_rcp_f32_e32 v124, v124
	s_nop 0
	v_pk_mul_f32 v[122:123], v[122:123], v[124:125]
	v_mul_f32_e32 v124, 0xbfb8aa3b, v112
	v_mul_f32_e32 v125, 0xbfb8aa3b, v113
	v_exp_f32_e32 v124, v124
	v_exp_f32_e32 v125, v125
	v_pk_mul_f32 v[122:123], v[126:127], v[122:123]
	v_pk_add_f32 v[124:125], v[124:125], 1.0 op_sel_hi:[1,0]
	s_nop 0
	v_rcp_f32_e32 v125, v125
	v_rcp_f32_e32 v124, v124
	s_nop 0
	v_pk_mul_f32 v[112:113], v[112:113], v[124:125]
	s_nop 0
	v_pk_mul_f32 v[112:113], v[116:117], v[112:113]
	v_mul_f32_e32 v116, 0xbfb8aa3b, v114
	v_mul_f32_e32 v117, 0xbfb8aa3b, v115
	v_exp_f32_e32 v116, v116
	v_exp_f32_e32 v117, v117
	s_nop 0
	v_pk_add_f32 v[116:117], v[116:117], 1.0 op_sel_hi:[1,0]
	s_nop 0
	v_rcp_f32_e32 v117, v117
	v_rcp_f32_e32 v116, v116
	s_nop 0
	v_pk_mul_f32 v[114:115], v[114:115], v[116:117]
	v_cvt_pk_bf16_f32 v116, v120, v121
	v_pk_mul_f32 v[114:115], v[118:119], v[114:115]
	v_cvt_pk_bf16_f32 v118, v112, v113
	v_mov_b64_e32 v[112:113], s[10:11]
	v_cvt_pk_bf16_f32 v119, v114, v115
	v_mad_i64_i32 v[120:121], s[2:3], v138, s6, v[112:113]
	v_lshlrev_b64 v[114:115], 1, v[154:155]
	v_cvt_pk_bf16_f32 v117, v122, v123
	v_lshl_add_u64 v[120:121], v[120:121], 0, v[114:115]
	global_store_dwordx4 v[120:121], v[116:119], off
	s_nop 1
	v_ffbh_u32_e32 v116, v153
	v_min_u32_e32 v118, 32, v116
	v_lshlrev_b64 v[116:117], v118, v[152:153]
	v_min_u32_e32 v116, 1, v116
	v_or_b32_e32 v116, v117, v116
	v_cvt_f32_u32_e32 v116, v116
	v_sub_u32_e32 v117, 32, v118
	v_ldexp_f32 v116, v116, v117
	v_fmamk_f32 v116, v116, 0x2e800000, v236
	v_cmp_gt_f32_e32 vcc, s20, v116
	v_mul_f32_e32 v117, 0x4b800000, v116
	s_nop 0
	v_cndmask_b32_e32 v116, v116, v117, vcc
	v_rsq_f32_e32 v116, v116
	s_nop 0
	v_mul_f32_e32 v117, 0x45800000, v116
	v_cndmask_b32_e32 v116, v116, v117, vcc
	v_pk_mul_f32 v[104:105], v[104:105], v[116:117] op_sel_hi:[1,0]
	s_nop 0
	v_mul_f32_e32 v117, 0xbfb8aa3b, v104
	v_exp_f32_e32 v118, v117
	v_pk_mul_f32 v[108:109], v[108:109], v[116:117] op_sel_hi:[1,0]
	v_mul_f32_e32 v117, 0xbfb8aa3b, v105
	v_exp_f32_e32 v119, v117
	s_nop 0
	v_pk_add_f32 v[118:119], v[118:119], 1.0 op_sel_hi:[1,0]
	s_nop 0
	v_rcp_f32_e32 v119, v119
	v_rcp_f32_e32 v118, v118
	s_nop 0
	v_pk_mul_f32 v[104:105], v[104:105], v[118:119]
	v_pk_mul_f32 v[106:107], v[106:107], v[116:117] op_sel_hi:[1,0]
	v_pk_mul_f32 v[104:105], v[108:109], v[104:105]
	v_mul_f32_e32 v108, 0xbfb8aa3b, v106
	v_mul_f32_e32 v109, 0xbfb8aa3b, v107
	v_exp_f32_e32 v108, v108
	v_exp_f32_e32 v109, v109
	v_pk_mul_f32 v[110:111], v[110:111], v[116:117] op_sel_hi:[1,0]
	v_pk_add_f32 v[108:109], v[108:109], 1.0 op_sel_hi:[1,0]
	s_nop 0
	v_rcp_f32_e32 v109, v109
	v_rcp_f32_e32 v108, v108
	v_pk_mul_f32 v[96:97], v[96:97], v[116:117] op_sel_hi:[1,0]
	v_pk_mul_f32 v[106:107], v[106:107], v[108:109]
	v_mul_f32_e32 v108, 0xbfb8aa3b, v96
	v_mul_f32_e32 v109, 0xbfb8aa3b, v97
	v_exp_f32_e32 v108, v108
	v_exp_f32_e32 v109, v109
	v_pk_mul_f32 v[106:107], v[110:111], v[106:107]
	v_pk_mul_f32 v[100:101], v[100:101], v[116:117] op_sel_hi:[1,0]
	v_pk_add_f32 v[108:109], v[108:109], 1.0 op_sel_hi:[1,0]
	s_nop 0
	v_rcp_f32_e32 v109, v109
	v_rcp_f32_e32 v108, v108
	s_nop 0
	v_pk_mul_f32 v[96:97], v[96:97], v[108:109]
	v_pk_mul_f32 v[102:103], v[102:103], v[116:117] op_sel_hi:[1,0]
	v_pk_mul_f32 v[100:101], v[100:101], v[96:97]
	v_pk_mul_f32 v[96:97], v[98:99], v[116:117] op_sel_hi:[1,0]
	s_nop 0
	v_mul_f32_e32 v98, 0xbfb8aa3b, v96
	v_mul_f32_e32 v99, 0xbfb8aa3b, v97
	v_exp_f32_e32 v98, v98
	v_exp_f32_e32 v99, v99
	s_nop 0
	v_pk_add_f32 v[98:99], v[98:99], 1.0 op_sel_hi:[1,0]
	s_nop 0
	v_rcp_f32_e32 v99, v99
	v_rcp_f32_e32 v98, v98
	s_nop 0
	v_pk_mul_f32 v[96:97], v[96:97], v[98:99]
	v_or_b32_e32 v108, 16, v138
	v_pk_mul_f32 v[102:103], v[102:103], v[96:97]
	v_cvt_pk_bf16_f32 v98, v100, v101
	v_mad_i64_i32 v[100:101], s[2:3], v108, s6, v[112:113]
	v_cvt_pk_bf16_f32 v96, v104, v105
	v_cvt_pk_bf16_f32 v97, v106, v107
	v_cvt_pk_bf16_f32 v99, v102, v103
	v_lshl_add_u64 v[100:101], v[100:101], 0, v[114:115]
	global_store_dwordx4 v[100:101], v[96:99], off
	s_nop 1
	v_ffbh_u32_e32 v96, v151
	v_min_u32_e32 v98, 32, v96
	v_lshlrev_b64 v[96:97], v98, v[150:151]
	v_min_u32_e32 v96, 1, v96
	v_or_b32_e32 v96, v97, v96
	v_cvt_f32_u32_e32 v96, v96
	v_sub_u32_e32 v97, 32, v98
	v_ldexp_f32 v96, v96, v97
	v_fmamk_f32 v96, v96, 0x2e800000, v236
	v_cmp_gt_f32_e32 vcc, s20, v96
	v_mul_f32_e32 v97, 0x4b800000, v96
	s_nop 0
	v_cndmask_b32_e32 v96, v96, v97, vcc
	v_rsq_f32_e32 v96, v96
	s_nop 0
	v_mul_f32_e32 v97, 0x45800000, v96
	v_cndmask_b32_e32 v96, v96, v97, vcc
	v_pk_mul_f32 v[88:89], v[88:89], v[96:97] op_sel_hi:[1,0]
	s_nop 0
	v_mul_f32_e32 v97, 0xbfb8aa3b, v88
	v_exp_f32_e32 v98, v97
	v_pk_mul_f32 v[92:93], v[92:93], v[96:97] op_sel_hi:[1,0]
	v_mul_f32_e32 v97, 0xbfb8aa3b, v89
	v_exp_f32_e32 v99, v97
	s_nop 0
	v_pk_add_f32 v[98:99], v[98:99], 1.0 op_sel_hi:[1,0]
	s_nop 0
	v_rcp_f32_e32 v99, v99
	v_rcp_f32_e32 v98, v98
	s_nop 0
	v_pk_mul_f32 v[88:89], v[88:89], v[98:99]
	v_pk_mul_f32 v[90:91], v[90:91], v[96:97] op_sel_hi:[1,0]
	v_pk_mul_f32 v[88:89], v[92:93], v[88:89]
	v_mul_f32_e32 v92, 0xbfb8aa3b, v90
	v_mul_f32_e32 v93, 0xbfb8aa3b, v91
	v_exp_f32_e32 v92, v92
	v_exp_f32_e32 v93, v93
	v_pk_mul_f32 v[94:95], v[94:95], v[96:97] op_sel_hi:[1,0]
	v_pk_add_f32 v[92:93], v[92:93], 1.0 op_sel_hi:[1,0]
	s_nop 0
	v_rcp_f32_e32 v93, v93
	v_rcp_f32_e32 v92, v92
	v_pk_mul_f32 v[80:81], v[80:81], v[96:97] op_sel_hi:[1,0]
	v_pk_mul_f32 v[90:91], v[90:91], v[92:93]
	v_mul_f32_e32 v92, 0xbfb8aa3b, v80
	v_mul_f32_e32 v93, 0xbfb8aa3b, v81
	v_exp_f32_e32 v92, v92
	v_exp_f32_e32 v93, v93
	v_pk_mul_f32 v[90:91], v[94:95], v[90:91]
	v_pk_mul_f32 v[84:85], v[84:85], v[96:97] op_sel_hi:[1,0]
	v_pk_add_f32 v[92:93], v[92:93], 1.0 op_sel_hi:[1,0]
	s_nop 0
	v_rcp_f32_e32 v93, v93
	v_rcp_f32_e32 v92, v92
	s_nop 0
	v_pk_mul_f32 v[80:81], v[80:81], v[92:93]
	v_pk_mul_f32 v[86:87], v[86:87], v[96:97] op_sel_hi:[1,0]
	v_pk_mul_f32 v[84:85], v[84:85], v[80:81]
	v_pk_mul_f32 v[80:81], v[82:83], v[96:97] op_sel_hi:[1,0]
	s_nop 0
	v_mul_f32_e32 v82, 0xbfb8aa3b, v80
	v_mul_f32_e32 v83, 0xbfb8aa3b, v81
	v_exp_f32_e32 v82, v82
	v_exp_f32_e32 v83, v83
	s_nop 0
	v_pk_add_f32 v[82:83], v[82:83], 1.0 op_sel_hi:[1,0]
	s_nop 0
	v_rcp_f32_e32 v83, v83
	v_rcp_f32_e32 v82, v82
	s_nop 0
	v_pk_mul_f32 v[80:81], v[80:81], v[82:83]
	v_or_b32_e32 v92, 32, v138
	v_pk_mul_f32 v[86:87], v[86:87], v[80:81]
	v_cvt_pk_bf16_f32 v82, v84, v85
	v_mad_i64_i32 v[84:85], s[2:3], v92, s6, v[112:113]
	v_cvt_pk_bf16_f32 v80, v88, v89
	v_cvt_pk_bf16_f32 v81, v90, v91
	v_cvt_pk_bf16_f32 v83, v86, v87
	v_lshl_add_u64 v[84:85], v[84:85], 0, v[114:115]
	global_store_dwordx4 v[84:85], v[80:83], off
	s_nop 1
	v_ffbh_u32_e32 v80, v149
	v_min_u32_e32 v82, 32, v80
	v_lshlrev_b64 v[80:81], v82, v[148:149]
	v_min_u32_e32 v80, 1, v80
	v_or_b32_e32 v80, v81, v80
	v_cvt_f32_u32_e32 v80, v80
	v_sub_u32_e32 v81, 32, v82
	v_ldexp_f32 v80, v80, v81
	v_fmamk_f32 v80, v80, 0x2e800000, v236
	v_cmp_gt_f32_e32 vcc, s20, v80
	v_mul_f32_e32 v81, 0x4b800000, v80
	s_nop 0
	v_cndmask_b32_e32 v80, v80, v81, vcc
	v_rsq_f32_e32 v80, v80
	s_nop 0
	v_mul_f32_e32 v81, 0x45800000, v80
	v_cndmask_b32_e32 v80, v80, v81, vcc
	v_pk_mul_f32 v[72:73], v[72:73], v[80:81] op_sel_hi:[1,0]
	s_nop 0
	v_mul_f32_e32 v81, 0xbfb8aa3b, v72
	v_exp_f32_e32 v82, v81
	v_pk_mul_f32 v[76:77], v[76:77], v[80:81] op_sel_hi:[1,0]
	v_mul_f32_e32 v81, 0xbfb8aa3b, v73
	v_exp_f32_e32 v83, v81
	s_nop 0
	v_pk_add_f32 v[82:83], v[82:83], 1.0 op_sel_hi:[1,0]
	s_nop 0
	v_rcp_f32_e32 v83, v83
	v_rcp_f32_e32 v82, v82
	s_nop 0
	v_pk_mul_f32 v[72:73], v[72:73], v[82:83]
	v_pk_mul_f32 v[74:75], v[74:75], v[80:81] op_sel_hi:[1,0]
	v_pk_mul_f32 v[72:73], v[76:77], v[72:73]
	v_mul_f32_e32 v76, 0xbfb8aa3b, v74
	v_mul_f32_e32 v77, 0xbfb8aa3b, v75
	v_exp_f32_e32 v76, v76
	v_exp_f32_e32 v77, v77
	v_pk_mul_f32 v[78:79], v[78:79], v[80:81] op_sel_hi:[1,0]
	v_pk_add_f32 v[76:77], v[76:77], 1.0 op_sel_hi:[1,0]
	s_nop 0
	v_rcp_f32_e32 v77, v77
	v_rcp_f32_e32 v76, v76
	v_pk_mul_f32 v[64:65], v[64:65], v[80:81] op_sel_hi:[1,0]
	v_pk_mul_f32 v[74:75], v[74:75], v[76:77]
	v_mul_f32_e32 v76, 0xbfb8aa3b, v64
	v_mul_f32_e32 v77, 0xbfb8aa3b, v65
	v_exp_f32_e32 v76, v76
	v_exp_f32_e32 v77, v77
	v_pk_mul_f32 v[74:75], v[78:79], v[74:75]
	v_pk_mul_f32 v[68:69], v[68:69], v[80:81] op_sel_hi:[1,0]
	v_pk_add_f32 v[76:77], v[76:77], 1.0 op_sel_hi:[1,0]
	s_nop 0
	v_rcp_f32_e32 v77, v77
	v_rcp_f32_e32 v76, v76
	s_nop 0
	v_pk_mul_f32 v[64:65], v[64:65], v[76:77]
	v_pk_mul_f32 v[70:71], v[70:71], v[80:81] op_sel_hi:[1,0]
	v_pk_mul_f32 v[68:69], v[68:69], v[64:65]
	v_pk_mul_f32 v[64:65], v[66:67], v[80:81] op_sel_hi:[1,0]
	s_nop 0
	v_mul_f32_e32 v66, 0xbfb8aa3b, v64
	v_mul_f32_e32 v67, 0xbfb8aa3b, v65
	v_exp_f32_e32 v66, v66
	v_exp_f32_e32 v67, v67
	s_nop 0
	v_pk_add_f32 v[66:67], v[66:67], 1.0 op_sel_hi:[1,0]
	s_nop 0
	v_rcp_f32_e32 v67, v67
	v_rcp_f32_e32 v66, v66
	s_nop 0
	v_pk_mul_f32 v[64:65], v[64:65], v[66:67]
	v_or_b32_e32 v76, 48, v138
	v_pk_mul_f32 v[70:71], v[70:71], v[64:65]
	v_cvt_pk_bf16_f32 v66, v68, v69
	v_mad_i64_i32 v[68:69], s[2:3], v76, s6, v[112:113]
	v_cvt_pk_bf16_f32 v64, v72, v73
	v_cvt_pk_bf16_f32 v65, v74, v75
	v_cvt_pk_bf16_f32 v67, v70, v71
	v_lshl_add_u64 v[68:69], v[68:69], 0, v[114:115]
	global_store_dwordx4 v[68:69], v[64:67], off
	s_nop 1
	v_ffbh_u32_e32 v64, v147
	v_min_u32_e32 v66, 32, v64
	v_lshlrev_b64 v[64:65], v66, v[146:147]
	v_min_u32_e32 v64, 1, v64
	v_or_b32_e32 v64, v65, v64
	v_cvt_f32_u32_e32 v64, v64
	v_sub_u32_e32 v65, 32, v66
	v_ldexp_f32 v64, v64, v65
	v_fmamk_f32 v64, v64, 0x2e800000, v236
	v_cmp_gt_f32_e32 vcc, s20, v64
	v_mul_f32_e32 v65, 0x4b800000, v64
	s_nop 0
	v_cndmask_b32_e32 v64, v64, v65, vcc
	v_rsq_f32_e32 v64, v64
	s_nop 0
	v_mul_f32_e32 v65, 0x45800000, v64
	v_cndmask_b32_e32 v64, v64, v65, vcc
	v_pk_mul_f32 v[56:57], v[56:57], v[64:65] op_sel_hi:[1,0]
	s_nop 0
	v_mul_f32_e32 v65, 0xbfb8aa3b, v56
	v_exp_f32_e32 v66, v65
	v_pk_mul_f32 v[60:61], v[60:61], v[64:65] op_sel_hi:[1,0]
	v_mul_f32_e32 v65, 0xbfb8aa3b, v57
	v_exp_f32_e32 v67, v65
	s_nop 0
	v_pk_add_f32 v[66:67], v[66:67], 1.0 op_sel_hi:[1,0]
	s_nop 0
	v_rcp_f32_e32 v67, v67
	v_rcp_f32_e32 v66, v66
	s_nop 0
	v_pk_mul_f32 v[56:57], v[56:57], v[66:67]
	v_pk_mul_f32 v[58:59], v[58:59], v[64:65] op_sel_hi:[1,0]
	v_pk_mul_f32 v[56:57], v[60:61], v[56:57]
	v_mul_f32_e32 v60, 0xbfb8aa3b, v58
	v_mul_f32_e32 v61, 0xbfb8aa3b, v59
	v_exp_f32_e32 v60, v60
	v_exp_f32_e32 v61, v61
	v_pk_mul_f32 v[62:63], v[62:63], v[64:65] op_sel_hi:[1,0]
	v_pk_add_f32 v[60:61], v[60:61], 1.0 op_sel_hi:[1,0]
	s_nop 0
	v_rcp_f32_e32 v61, v61
	v_rcp_f32_e32 v60, v60
	v_pk_mul_f32 v[48:49], v[48:49], v[64:65] op_sel_hi:[1,0]
	v_pk_mul_f32 v[58:59], v[58:59], v[60:61]
	v_mul_f32_e32 v60, 0xbfb8aa3b, v48
	v_mul_f32_e32 v61, 0xbfb8aa3b, v49
	v_exp_f32_e32 v60, v60
	v_exp_f32_e32 v61, v61
	v_pk_mul_f32 v[58:59], v[62:63], v[58:59]
	v_pk_mul_f32 v[52:53], v[52:53], v[64:65] op_sel_hi:[1,0]
	v_pk_add_f32 v[60:61], v[60:61], 1.0 op_sel_hi:[1,0]
	s_nop 0
	v_rcp_f32_e32 v61, v61
	v_rcp_f32_e32 v60, v60
	s_nop 0
	v_pk_mul_f32 v[48:49], v[48:49], v[60:61]
	v_pk_mul_f32 v[54:55], v[54:55], v[64:65] op_sel_hi:[1,0]
	v_pk_mul_f32 v[52:53], v[52:53], v[48:49]
	v_pk_mul_f32 v[48:49], v[50:51], v[64:65] op_sel_hi:[1,0]
	s_nop 0
	v_mul_f32_e32 v50, 0xbfb8aa3b, v48
	v_mul_f32_e32 v51, 0xbfb8aa3b, v49
	v_exp_f32_e32 v50, v50
	v_exp_f32_e32 v51, v51
	s_nop 0
	v_pk_add_f32 v[50:51], v[50:51], 1.0 op_sel_hi:[1,0]
	s_nop 0
	v_rcp_f32_e32 v51, v51
	v_rcp_f32_e32 v50, v50
	s_nop 0
	v_pk_mul_f32 v[48:49], v[48:49], v[50:51]
	v_cvt_pk_bf16_f32 v50, v52, v53
	v_pk_mul_f32 v[54:55], v[54:55], v[48:49]
	v_mad_i64_i32 v[52:53], s[2:3], v139, s6, v[112:113]
	v_cvt_pk_bf16_f32 v48, v56, v57
	v_cvt_pk_bf16_f32 v49, v58, v59
	v_cvt_pk_bf16_f32 v51, v54, v55
	v_lshl_add_u64 v[52:53], v[52:53], 0, v[114:115]
	global_store_dwordx4 v[52:53], v[48:51], off
	s_nop 1
	v_ffbh_u32_e32 v48, v145
	v_min_u32_e32 v50, 32, v48
	v_lshlrev_b64 v[48:49], v50, v[144:145]
	v_min_u32_e32 v48, 1, v48
	v_or_b32_e32 v48, v49, v48
	v_cvt_f32_u32_e32 v48, v48
	v_sub_u32_e32 v49, 32, v50
	v_ldexp_f32 v48, v48, v49
	v_fmamk_f32 v48, v48, 0x2e800000, v236
	v_cmp_gt_f32_e32 vcc, s20, v48
	v_mul_f32_e32 v49, 0x4b800000, v48
	s_nop 0
	v_cndmask_b32_e32 v48, v48, v49, vcc
	v_rsq_f32_e32 v48, v48
	s_nop 0
	v_mul_f32_e32 v49, 0x45800000, v48
	v_cndmask_b32_e32 v48, v48, v49, vcc
	v_pk_mul_f32 v[40:41], v[40:41], v[48:49] op_sel_hi:[1,0]
	s_nop 0
	v_mul_f32_e32 v49, 0xbfb8aa3b, v40
	v_exp_f32_e32 v50, v49
	v_pk_mul_f32 v[44:45], v[44:45], v[48:49] op_sel_hi:[1,0]
	v_mul_f32_e32 v49, 0xbfb8aa3b, v41
	v_exp_f32_e32 v51, v49
	s_nop 0
	v_pk_add_f32 v[50:51], v[50:51], 1.0 op_sel_hi:[1,0]
	s_nop 0
	v_rcp_f32_e32 v51, v51
	v_rcp_f32_e32 v50, v50
	s_nop 0
	v_pk_mul_f32 v[40:41], v[40:41], v[50:51]
	v_pk_mul_f32 v[42:43], v[42:43], v[48:49] op_sel_hi:[1,0]
	v_pk_mul_f32 v[40:41], v[44:45], v[40:41]
	v_mul_f32_e32 v44, 0xbfb8aa3b, v42
	v_mul_f32_e32 v45, 0xbfb8aa3b, v43
	v_exp_f32_e32 v44, v44
	v_exp_f32_e32 v45, v45
	v_pk_mul_f32 v[46:47], v[46:47], v[48:49] op_sel_hi:[1,0]
	v_pk_add_f32 v[44:45], v[44:45], 1.0 op_sel_hi:[1,0]
	s_nop 0
	v_rcp_f32_e32 v45, v45
	v_rcp_f32_e32 v44, v44
	v_pk_mul_f32 v[32:33], v[32:33], v[48:49] op_sel_hi:[1,0]
	v_pk_mul_f32 v[42:43], v[42:43], v[44:45]
	v_mul_f32_e32 v44, 0xbfb8aa3b, v32
	v_mul_f32_e32 v45, 0xbfb8aa3b, v33
	v_exp_f32_e32 v44, v44
	v_exp_f32_e32 v45, v45
	v_pk_mul_f32 v[42:43], v[46:47], v[42:43]
	v_pk_mul_f32 v[36:37], v[36:37], v[48:49] op_sel_hi:[1,0]
	v_pk_add_f32 v[44:45], v[44:45], 1.0 op_sel_hi:[1,0]
	s_nop 0
	v_rcp_f32_e32 v45, v45
	v_rcp_f32_e32 v44, v44
	s_nop 0
	v_pk_mul_f32 v[32:33], v[32:33], v[44:45]
	v_pk_mul_f32 v[38:39], v[38:39], v[48:49] op_sel_hi:[1,0]
	v_pk_mul_f32 v[36:37], v[36:37], v[32:33]
	v_pk_mul_f32 v[32:33], v[34:35], v[48:49] op_sel_hi:[1,0]
	s_nop 0
	v_mul_f32_e32 v34, 0xbfb8aa3b, v32
	v_mul_f32_e32 v35, 0xbfb8aa3b, v33
	v_exp_f32_e32 v34, v34
	v_exp_f32_e32 v35, v35
	s_nop 0
	v_pk_add_f32 v[34:35], v[34:35], 1.0 op_sel_hi:[1,0]
	s_nop 0
	v_rcp_f32_e32 v35, v35
	v_rcp_f32_e32 v34, v34
	s_nop 0
	v_pk_mul_f32 v[32:33], v[32:33], v[34:35]
	v_add_u32_e32 v44, 0x90, v138
	v_pk_mul_f32 v[38:39], v[38:39], v[32:33]
	v_cvt_pk_bf16_f32 v34, v36, v37
	v_mad_i64_i32 v[36:37], s[2:3], v44, s6, v[112:113]
	v_cvt_pk_bf16_f32 v32, v40, v41
	v_cvt_pk_bf16_f32 v33, v42, v43
	v_cvt_pk_bf16_f32 v35, v38, v39
	v_lshl_add_u64 v[36:37], v[36:37], 0, v[114:115]
	global_store_dwordx4 v[36:37], v[32:35], off
	s_nop 1
	v_ffbh_u32_e32 v32, v143
	v_min_u32_e32 v34, 32, v32
	v_lshlrev_b64 v[32:33], v34, v[142:143]
	v_min_u32_e32 v32, 1, v32
	v_or_b32_e32 v32, v33, v32
	v_cvt_f32_u32_e32 v32, v32
	v_sub_u32_e32 v33, 32, v34
	v_ldexp_f32 v32, v32, v33
	v_fmamk_f32 v32, v32, 0x2e800000, v236
	v_cmp_gt_f32_e32 vcc, s20, v32
	v_mul_f32_e32 v33, 0x4b800000, v32
	s_nop 0
	v_cndmask_b32_e32 v32, v32, v33, vcc
	v_rsq_f32_e32 v32, v32
	s_nop 0
	v_mul_f32_e32 v33, 0x45800000, v32
	v_cndmask_b32_e32 v32, v32, v33, vcc
	v_pk_mul_f32 v[24:25], v[24:25], v[32:33] op_sel_hi:[1,0]
	s_nop 0
	v_mul_f32_e32 v33, 0xbfb8aa3b, v24
	v_exp_f32_e32 v34, v33
	v_pk_mul_f32 v[28:29], v[28:29], v[32:33] op_sel_hi:[1,0]
	v_mul_f32_e32 v33, 0xbfb8aa3b, v25
	v_exp_f32_e32 v35, v33
	s_nop 0
	v_pk_add_f32 v[34:35], v[34:35], 1.0 op_sel_hi:[1,0]
	s_nop 0
	v_rcp_f32_e32 v35, v35
	v_rcp_f32_e32 v34, v34
	s_nop 0
	v_pk_mul_f32 v[24:25], v[24:25], v[34:35]
	v_pk_mul_f32 v[26:27], v[26:27], v[32:33] op_sel_hi:[1,0]
	v_pk_mul_f32 v[24:25], v[28:29], v[24:25]
	v_mul_f32_e32 v28, 0xbfb8aa3b, v26
	v_mul_f32_e32 v29, 0xbfb8aa3b, v27
	v_exp_f32_e32 v28, v28
	v_exp_f32_e32 v29, v29
	v_pk_mul_f32 v[30:31], v[30:31], v[32:33] op_sel_hi:[1,0]
	v_pk_add_f32 v[28:29], v[28:29], 1.0 op_sel_hi:[1,0]
	s_nop 0
	v_rcp_f32_e32 v29, v29
	v_rcp_f32_e32 v28, v28
	v_pk_mul_f32 v[16:17], v[16:17], v[32:33] op_sel_hi:[1,0]
	v_pk_mul_f32 v[26:27], v[26:27], v[28:29]
	v_mul_f32_e32 v28, 0xbfb8aa3b, v16
	v_mul_f32_e32 v29, 0xbfb8aa3b, v17
	v_exp_f32_e32 v28, v28
	v_exp_f32_e32 v29, v29
	v_pk_mul_f32 v[26:27], v[30:31], v[26:27]
	v_pk_mul_f32 v[20:21], v[20:21], v[32:33] op_sel_hi:[1,0]
	v_pk_add_f32 v[28:29], v[28:29], 1.0 op_sel_hi:[1,0]
	s_nop 0
	v_rcp_f32_e32 v29, v29
	v_rcp_f32_e32 v28, v28
	s_nop 0
	v_pk_mul_f32 v[16:17], v[16:17], v[28:29]
	v_pk_mul_f32 v[22:23], v[22:23], v[32:33] op_sel_hi:[1,0]
	v_pk_mul_f32 v[20:21], v[20:21], v[16:17]
	v_pk_mul_f32 v[16:17], v[18:19], v[32:33] op_sel_hi:[1,0]
	s_nop 0
	v_mul_f32_e32 v18, 0xbfb8aa3b, v16
	v_mul_f32_e32 v19, 0xbfb8aa3b, v17
	v_exp_f32_e32 v18, v18
	v_exp_f32_e32 v19, v19
	s_nop 0
	v_pk_add_f32 v[18:19], v[18:19], 1.0 op_sel_hi:[1,0]
	s_nop 0
	v_rcp_f32_e32 v19, v19
	v_rcp_f32_e32 v18, v18
	s_nop 0
	v_pk_mul_f32 v[16:17], v[16:17], v[18:19]
	v_add_u32_e32 v28, 0xa0, v138
	v_pk_mul_f32 v[22:23], v[22:23], v[16:17]
	v_cvt_pk_bf16_f32 v18, v20, v21
	v_mad_i64_i32 v[20:21], s[2:3], v28, s6, v[112:113]
	v_cvt_pk_bf16_f32 v16, v24, v25
	v_cvt_pk_bf16_f32 v17, v26, v27
	v_cvt_pk_bf16_f32 v19, v22, v23
	v_lshl_add_u64 v[20:21], v[20:21], 0, v[114:115]
	global_store_dwordx4 v[20:21], v[16:19], off
	s_nop 1
	v_ffbh_u32_e32 v16, v141
	v_min_u32_e32 v18, 32, v16
	v_lshlrev_b64 v[16:17], v18, v[140:141]
	v_min_u32_e32 v16, 1, v16
	v_or_b32_e32 v16, v17, v16
	v_cvt_f32_u32_e32 v16, v16
	v_sub_u32_e32 v17, 32, v18
	v_ldexp_f32 v16, v16, v17
	v_fmamk_f32 v16, v16, 0x2e800000, v236
	v_cmp_gt_f32_e32 vcc, s20, v16
	v_mul_f32_e32 v17, 0x4b800000, v16
	s_nop 0
	v_cndmask_b32_e32 v16, v16, v17, vcc
	v_rsq_f32_e32 v16, v16
	s_nop 0
	v_mul_f32_e32 v17, 0x45800000, v16
	v_cndmask_b32_e32 v16, v16, v17, vcc
	v_pk_mul_f32 v[8:9], v[8:9], v[16:17] op_sel_hi:[1,0]
	s_nop 0
	v_mul_f32_e32 v17, 0xbfb8aa3b, v8
	v_exp_f32_e32 v18, v17
	v_pk_mul_f32 v[12:13], v[12:13], v[16:17] op_sel_hi:[1,0]
	v_mul_f32_e32 v17, 0xbfb8aa3b, v9
	v_exp_f32_e32 v19, v17
	s_nop 0
	v_pk_add_f32 v[18:19], v[18:19], 1.0 op_sel_hi:[1,0]
	s_nop 0
	v_rcp_f32_e32 v19, v19
	v_rcp_f32_e32 v18, v18
	s_nop 0
	v_pk_mul_f32 v[8:9], v[8:9], v[18:19]
	v_pk_mul_f32 v[10:11], v[10:11], v[16:17] op_sel_hi:[1,0]
	v_pk_mul_f32 v[8:9], v[12:13], v[8:9]
	v_mul_f32_e32 v12, 0xbfb8aa3b, v10
	v_mul_f32_e32 v13, 0xbfb8aa3b, v11
	v_exp_f32_e32 v12, v12
	v_exp_f32_e32 v13, v13
	v_pk_mul_f32 v[14:15], v[14:15], v[16:17] op_sel_hi:[1,0]
	v_pk_add_f32 v[12:13], v[12:13], 1.0 op_sel_hi:[1,0]
	s_nop 0
	v_rcp_f32_e32 v13, v13
	v_rcp_f32_e32 v12, v12
	v_pk_mul_f32 v[0:1], v[0:1], v[16:17] op_sel_hi:[1,0]
	v_pk_mul_f32 v[10:11], v[10:11], v[12:13]
	v_mul_f32_e32 v12, 0xbfb8aa3b, v0
	v_mul_f32_e32 v13, 0xbfb8aa3b, v1
	v_exp_f32_e32 v12, v12
	v_exp_f32_e32 v13, v13
	v_pk_mul_f32 v[10:11], v[14:15], v[10:11]
	v_pk_mul_f32 v[4:5], v[4:5], v[16:17] op_sel_hi:[1,0]
	v_pk_add_f32 v[12:13], v[12:13], 1.0 op_sel_hi:[1,0]
	s_nop 0
	v_rcp_f32_e32 v13, v13
	v_rcp_f32_e32 v12, v12
	s_nop 0
	v_pk_mul_f32 v[0:1], v[0:1], v[12:13]
	v_pk_mul_f32 v[6:7], v[6:7], v[16:17] op_sel_hi:[1,0]
	v_pk_mul_f32 v[4:5], v[4:5], v[0:1]
	v_pk_mul_f32 v[0:1], v[2:3], v[16:17] op_sel_hi:[1,0]
	s_nop 0
	v_mul_f32_e32 v2, 0xbfb8aa3b, v0
	v_mul_f32_e32 v3, 0xbfb8aa3b, v1
	v_exp_f32_e32 v2, v2
	v_exp_f32_e32 v3, v3
	s_nop 0
	v_pk_add_f32 v[2:3], v[2:3], 1.0 op_sel_hi:[1,0]
	s_nop 0
	v_rcp_f32_e32 v3, v3
	v_rcp_f32_e32 v2, v2
	s_nop 0
	v_pk_mul_f32 v[0:1], v[0:1], v[2:3]
	v_add_u32_e32 v12, 0xb0, v138
	v_pk_mul_f32 v[6:7], v[6:7], v[0:1]
	v_cvt_pk_bf16_f32 v2, v4, v5
	v_mad_i64_i32 v[4:5], s[2:3], v12, s6, v[112:113]
	v_cvt_pk_bf16_f32 v0, v8, v9
	v_cvt_pk_bf16_f32 v1, v10, v11
	v_cvt_pk_bf16_f32 v3, v6, v7
	v_lshl_add_u64 v[4:5], v[4:5], 0, v[114:115]
	s_mov_b64 s[2:3], -1
	s_andn2_b64 vcc, exec, s[8:9]
	global_store_dwordx4 v[4:5], v[0:3], off
	s_cbranch_vccnz .LBB0_858
	v_mov_b32_e32 v120, v192
	v_mov_b32_e32 v112, v192
	v_mov_b32_e32 v104, v192
	v_mov_b32_e32 v96, v192
	v_mov_b32_e32 v88, v192
	v_mov_b32_e32 v80, v192
	v_mov_b32_e32 v72, v192
	v_mov_b32_e32 v64, v192
	v_mov_b32_e32 v124, v192
	v_mov_b32_e32 v116, v192
	v_mov_b32_e32 v108, v192
	v_mov_b32_e32 v100, v192
	v_mov_b32_e32 v92, v192
	v_mov_b32_e32 v84, v192
	v_mov_b32_e32 v76, v192
	v_mov_b32_e32 v68, v192
	v_mov_b32_e32 v56, v192
	v_mov_b32_e32 v48, v192
	v_mov_b32_e32 v40, v192
	v_mov_b32_e32 v32, v192
	v_mov_b32_e32 v24, v192
	v_mov_b32_e32 v16, v192
	v_mov_b32_e32 v8, v192
	v_mov_b32_e32 v0, v192
	v_mov_b32_e32 v60, v192
	v_mov_b32_e32 v52, v192
	v_mov_b32_e32 v44, v192
	v_mov_b32_e32 v36, v192
	v_mov_b32_e32 v28, v192
	v_mov_b32_e32 v20, v192
	v_mov_b32_e32 v12, v192
	v_mov_b32_e32 v4, v195
	s_nop 0
	v_mov_b32_e32 v121, v120
	v_mov_b32_e32 v122, v120
	v_mov_b32_e32 v123, v120
	v_mov_b32_e32 v113, v112
	v_mov_b32_e32 v114, v112
	v_mov_b32_e32 v115, v112
	v_mov_b32_e32 v105, v104
	v_mov_b32_e32 v106, v104
	v_mov_b32_e32 v107, v104
	v_mov_b32_e32 v97, v96
	v_mov_b32_e32 v98, v96
	v_mov_b32_e32 v99, v96
	v_mov_b32_e32 v89, v88
	v_mov_b32_e32 v90, v88
	v_mov_b32_e32 v91, v88
	v_mov_b32_e32 v81, v80
	v_mov_b32_e32 v82, v80
	v_mov_b32_e32 v83, v80
	s_nop 0
	v_mov_b32_e32 v73, v72
	v_mov_b32_e32 v74, v72
	v_mov_b32_e32 v75, v72
	v_mov_b32_e32 v65, v64
	v_mov_b32_e32 v66, v64
	v_mov_b32_e32 v67, v64
	v_mov_b32_e32 v125, v124
	v_mov_b32_e32 v126, v124
	v_mov_b32_e32 v127, v124
	v_mov_b32_e32 v117, v116
	v_mov_b32_e32 v118, v116
	v_mov_b32_e32 v119, v116
	v_mov_b32_e32 v109, v108
	v_mov_b32_e32 v110, v108
	v_mov_b32_e32 v111, v108
	v_mov_b32_e32 v101, v100
	v_mov_b32_e32 v102, v100
	v_mov_b32_e32 v103, v100
	s_nop 0
	v_mov_b32_e32 v93, v92
	v_mov_b32_e32 v94, v92
	v_mov_b32_e32 v95, v92
	v_mov_b32_e32 v85, v84
	v_mov_b32_e32 v86, v84
	v_mov_b32_e32 v87, v84
	v_mov_b32_e32 v77, v76
	v_mov_b32_e32 v78, v76
	v_mov_b32_e32 v79, v76
	v_mov_b32_e32 v69, v68
	v_mov_b32_e32 v70, v68
	v_mov_b32_e32 v71, v68
	v_mov_b32_e32 v57, v56
	v_mov_b32_e32 v58, v56
	v_mov_b32_e32 v59, v56
	v_mov_b32_e32 v49, v48
	v_mov_b32_e32 v50, v48
	v_mov_b32_e32 v51, v48
	s_nop 0
	v_mov_b32_e32 v41, v40
	v_mov_b32_e32 v42, v40
	v_mov_b32_e32 v43, v40
	v_mov_b32_e32 v33, v32
	v_mov_b32_e32 v34, v32
	v_mov_b32_e32 v35, v32
	v_mov_b32_e32 v25, v24
	v_mov_b32_e32 v26, v24
	v_mov_b32_e32 v27, v24
	v_mov_b32_e32 v17, v16
	v_mov_b32_e32 v18, v16
	v_mov_b32_e32 v19, v16
	v_mov_b32_e32 v9, v8
	v_mov_b32_e32 v10, v8
	v_mov_b32_e32 v11, v8
	v_mov_b32_e32 v1, v0
	v_mov_b32_e32 v2, v0
	v_mov_b32_e32 v3, v0
	s_nop 0
	v_mov_b32_e32 v61, v60
	v_mov_b32_e32 v62, v60
	v_mov_b32_e32 v63, v60
	v_mov_b32_e32 v53, v52
	v_mov_b32_e32 v54, v52
	v_mov_b32_e32 v55, v52
	v_mov_b32_e32 v45, v44
	v_mov_b32_e32 v46, v44
	v_mov_b32_e32 v47, v44
	v_mov_b32_e32 v37, v36
	v_mov_b32_e32 v38, v36
	v_mov_b32_e32 v39, v36
	v_mov_b32_e32 v29, v28
	v_mov_b32_e32 v30, v28
	v_mov_b32_e32 v31, v28
	v_mov_b32_e32 v21, v20
	v_mov_b32_e32 v22, v20
	v_mov_b32_e32 v23, v20
	s_mov_b64 s[2:3], 0
	v_mov_b32_e32 v13, v12
	v_mov_b32_e32 v14, v12
	v_mov_b32_e32 v15, v12
	v_mov_b32_e32 v5, v4
	v_mov_b32_e32 v6, v4
	v_mov_b32_e32 v7, v4
	s_branch .LBB0_858

.LBB0_871:
	s_ashr_i32 s1, s3, 3
	s_and_b32 s0, s6, 0x70
	v_or_b32_e32 v6, s0, v12
	s_lshl_b32 s0, s1, 4
	s_lshl_b32 s1, s1, 5
	s_and_b32 s7, s1, 0xffffff00
	s_and_b32 s8, s0, 0x70
	s_or_b32 s7, s8, s7
	v_lshlrev_b32_e32 v194, 11, v6
	v_or_b32_e32 v13, 0x4000, v6
	v_or_b32_e32 v6, s7, v12
	v_ashrrev_i32_e32 v7, 31, v6
	v_or_b32_e32 v22, 0x80, v6
	v_lshlrev_b64 v[6:7], 11, v[6:7]
	v_lshl_add_u64 v[78:79], v[0:1], 0, v[194:195]
	v_ashrrev_i32_e32 v23, 31, v22
	v_lshl_add_u64 v[8:9], v[2:3], 0, v[6:7]
	global_load_dwordx4 v[14:17], v[78:79], off
	global_load_dwordx4 v[18:21], v[78:79], off offset:64
	v_lshlrev_b64 v[6:7], 11, v[22:23]
	global_load_dwordx4 v[22:25], v[8:9], off
	v_lshl_add_u64 v[6:7], v[2:3], 0, v[6:7]
	global_load_dwordx4 v[26:29], v[8:9], off offset:64
	global_load_dwordx4 v[30:33], v[6:7], off
	global_load_dwordx4 v[34:37], v[6:7], off offset:64
	v_lshlrev_b32_e32 v194, 3, v13
	v_mul_u32_u24_e32 v13, 0xb00, v13
	s_ashr_i32 s1, s0, 31
	v_mov_b32_e32 v5, v195
	s_add_i32 s3, s3, s80
	s_add_i32 s6, s6, s64
	s_cmpk_gt_i32 s3, 0x57f
	s_waitcnt vmcnt(0) lgkmcnt(0)
	v_mfma_f32_16x16x32_bf16 v[22:25], v[22:25], v[14:17], 0
	v_mfma_f32_16x16x32_bf16 v[14:17], v[30:33], v[14:17], 0
	global_load_dwordx4 v[30:33], v[78:79], off offset:128
	global_load_dwordx4 v[38:41], v[78:79], off offset:192
	v_mfma_f32_16x16x32_bf16 v[22:25], v[26:29], v[18:21], v[22:25]
	global_load_dwordx4 v[26:29], v[8:9], off offset:128
	global_load_dwordx4 v[42:45], v[8:9], off offset:192
	v_mfma_f32_16x16x32_bf16 v[14:17], v[34:37], v[18:21], v[14:17]
	global_load_dwordx4 v[18:21], v[6:7], off offset:128
	s_waitcnt vmcnt(0) lgkmcnt(0)
	v_mfma_f32_16x16x32_bf16 v[22:25], v[26:29], v[30:33], v[22:25]
	global_load_dwordx4 v[26:29], v[6:7], off offset:192
	v_mfma_f32_16x16x32_bf16 v[14:17], v[18:21], v[30:33], v[14:17]
	global_load_dwordx4 v[18:21], v[78:79], off offset:256
	global_load_dwordx4 v[30:33], v[78:79], off offset:320
	v_mfma_f32_16x16x32_bf16 v[22:25], v[42:45], v[38:41], v[22:25]
	global_load_dwordx4 v[34:37], v[8:9], off offset:256
	global_load_dwordx4 v[42:45], v[8:9], off offset:320
	s_waitcnt vmcnt(0) lgkmcnt(0)
	v_mfma_f32_16x16x32_bf16 v[14:17], v[26:29], v[38:41], v[14:17]
	global_load_dwordx4 v[26:29], v[6:7], off offset:256
	v_mfma_f32_16x16x32_bf16 v[22:25], v[34:37], v[18:21], v[22:25]
	global_load_dwordx4 v[34:37], v[6:7], off offset:320
	v_mfma_f32_16x16x32_bf16 v[22:25], v[42:45], v[30:33], v[22:25]
	s_waitcnt vmcnt(0) lgkmcnt(0)
	v_mfma_f32_16x16x32_bf16 v[14:17], v[26:29], v[18:21], v[14:17]
	global_load_dwordx4 v[18:21], v[78:79], off offset:384
	global_load_dwordx4 v[26:29], v[78:79], off offset:448
	global_load_dwordx4 v[38:41], v[78:79], off offset:512
	global_load_dwordx4 v[42:45], v[8:9], off offset:384
	global_load_dwordx4 v[46:49], v[8:9], off offset:448
	v_mfma_f32_16x16x32_bf16 v[14:17], v[34:37], v[30:33], v[14:17]
	global_load_dwordx4 v[30:33], v[6:7], off offset:384
	global_load_dwordx4 v[34:37], v[6:7], off offset:448
	s_waitcnt vmcnt(0) lgkmcnt(0)
	v_mfma_f32_16x16x32_bf16 v[22:25], v[42:45], v[18:21], v[22:25]
	v_mfma_f32_16x16x32_bf16 v[14:17], v[30:33], v[18:21], v[14:17]
	global_load_dwordx4 v[18:21], v[78:79], off offset:576
	global_load_dwordx4 v[30:33], v[78:79], off offset:640
	global_load_dwordx4 v[42:45], v[78:79], off offset:704
	v_mfma_f32_16x16x32_bf16 v[22:25], v[46:49], v[26:29], v[22:25]
	global_load_dwordx4 v[46:49], v[8:9], off offset:512
	global_load_dwordx4 v[50:53], v[8:9], off offset:576
	v_mfma_f32_16x16x32_bf16 v[14:17], v[34:37], v[26:29], v[14:17]
	global_load_dwordx4 v[26:29], v[6:7], off offset:512
	global_load_dwordx4 v[34:37], v[6:7], off offset:576
	s_waitcnt vmcnt(0) lgkmcnt(0)
	v_mfma_f32_16x16x32_bf16 v[22:25], v[46:49], v[38:41], v[22:25]
	v_mfma_f32_16x16x32_bf16 v[14:17], v[26:29], v[38:41], v[14:17]
	global_load_dwordx4 v[26:29], v[78:79], off offset:768
	global_load_dwordx4 v[38:41], v[78:79], off offset:832
	global_load_dwordx4 v[46:49], v[78:79], off offset:896
	v_mfma_f32_16x16x32_bf16 v[22:25], v[50:53], v[18:21], v[22:25]
	global_load_dwordx4 v[50:53], v[8:9], off offset:640
	global_load_dwordx4 v[54:57], v[8:9], off offset:704
	v_mfma_f32_16x16x32_bf16 v[14:17], v[34:37], v[18:21], v[14:17]
	global_load_dwordx4 v[18:21], v[6:7], off offset:640
	global_load_dwordx4 v[34:37], v[6:7], off offset:704
	s_waitcnt vmcnt(0) lgkmcnt(0)
	v_mfma_f32_16x16x32_bf16 v[22:25], v[50:53], v[30:33], v[22:25]
	v_mfma_f32_16x16x32_bf16 v[14:17], v[18:21], v[30:33], v[14:17]
	global_load_dwordx4 v[18:21], v[78:79], off offset:960
	global_load_dwordx4 v[30:33], v[78:79], off offset:1024
	global_load_dwordx4 v[50:53], v[78:79], off offset:1088
	v_mfma_f32_16x16x32_bf16 v[22:25], v[54:57], v[42:45], v[22:25]
	global_load_dwordx4 v[54:57], v[8:9], off offset:768
	global_load_dwordx4 v[58:61], v[8:9], off offset:832
	v_mfma_f32_16x16x32_bf16 v[14:17], v[34:37], v[42:45], v[14:17]
	global_load_dwordx4 v[34:37], v[6:7], off offset:768
	global_load_dwordx4 v[42:45], v[6:7], off offset:832
	s_waitcnt vmcnt(0) lgkmcnt(0)
	v_mfma_f32_16x16x32_bf16 v[22:25], v[54:57], v[26:29], v[22:25]
	v_mfma_f32_16x16x32_bf16 v[14:17], v[34:37], v[26:29], v[14:17]
	global_load_dwordx4 v[26:29], v[78:79], off offset:1152
	global_load_dwordx4 v[34:37], v[78:79], off offset:1216
	global_load_dwordx4 v[54:57], v[78:79], off offset:1280
	v_mfma_f32_16x16x32_bf16 v[22:25], v[58:61], v[38:41], v[22:25]
	global_load_dwordx4 v[58:61], v[8:9], off offset:896
	global_load_dwordx4 v[62:65], v[8:9], off offset:960
	v_mfma_f32_16x16x32_bf16 v[14:17], v[42:45], v[38:41], v[14:17]
	global_load_dwordx4 v[38:41], v[6:7], off offset:896
	global_load_dwordx4 v[42:45], v[6:7], off offset:960
	s_waitcnt vmcnt(0) lgkmcnt(0)
	v_mfma_f32_16x16x32_bf16 v[22:25], v[58:61], v[46:49], v[22:25]
	v_mfma_f32_16x16x32_bf16 v[14:17], v[38:41], v[46:49], v[14:17]
	global_load_dwordx4 v[38:41], v[78:79], off offset:1344
	global_load_dwordx4 v[46:49], v[78:79], off offset:1408
	global_load_dwordx4 v[58:61], v[78:79], off offset:1472
	v_mfma_f32_16x16x32_bf16 v[22:25], v[62:65], v[18:21], v[22:25]
	global_load_dwordx4 v[62:65], v[8:9], off offset:1024
	global_load_dwordx4 v[66:69], v[8:9], off offset:1088
	v_mfma_f32_16x16x32_bf16 v[14:17], v[42:45], v[18:21], v[14:17]
	global_load_dwordx4 v[18:21], v[6:7], off offset:1024
	global_load_dwordx4 v[42:45], v[6:7], off offset:1088
	s_waitcnt vmcnt(0) lgkmcnt(0)
	v_mfma_f32_16x16x32_bf16 v[22:25], v[62:65], v[30:33], v[22:25]
	v_mfma_f32_16x16x32_bf16 v[14:17], v[18:21], v[30:33], v[14:17]
	global_load_dwordx4 v[18:21], v[78:79], off offset:1536
	global_load_dwordx4 v[30:33], v[78:79], off offset:1600
	global_load_dwordx4 v[62:65], v[78:79], off offset:1664
	v_mfma_f32_16x16x32_bf16 v[22:25], v[66:69], v[50:53], v[22:25]
	global_load_dwordx4 v[66:69], v[8:9], off offset:1152
	global_load_dwordx4 v[70:73], v[8:9], off offset:1216
	v_mfma_f32_16x16x32_bf16 v[14:17], v[42:45], v[50:53], v[14:17]
	global_load_dwordx4 v[42:45], v[6:7], off offset:1152
	global_load_dwordx4 v[50:53], v[6:7], off offset:1216
	s_waitcnt vmcnt(0) lgkmcnt(0)
	v_mfma_f32_16x16x32_bf16 v[22:25], v[66:69], v[26:29], v[22:25]
	v_mfma_f32_16x16x32_bf16 v[14:17], v[42:45], v[26:29], v[14:17]
	global_load_dwordx4 v[26:29], v[78:79], off offset:1728
	global_load_dwordx4 v[42:45], v[78:79], off offset:1792
	global_load_dwordx4 v[66:69], v[78:79], off offset:1856
	v_mfma_f32_16x16x32_bf16 v[22:25], v[70:73], v[34:37], v[22:25]
	global_load_dwordx4 v[70:73], v[8:9], off offset:1280
	global_load_dwordx4 v[74:77], v[8:9], off offset:1344
	v_mfma_f32_16x16x32_bf16 v[14:17], v[50:53], v[34:37], v[14:17]
	global_load_dwordx4 v[34:37], v[6:7], off offset:1280
	global_load_dwordx4 v[50:53], v[6:7], off offset:1344
	s_waitcnt vmcnt(0) lgkmcnt(0)
	v_mfma_f32_16x16x32_bf16 v[22:25], v[70:73], v[54:57], v[22:25]
	v_mfma_f32_16x16x32_bf16 v[14:17], v[34:37], v[54:57], v[14:17]
	global_load_dwordx4 v[34:37], v[78:79], off offset:1920
	global_load_dwordx4 v[54:57], v[78:79], off offset:1984
	v_lshl_add_u64 v[78:79], s[14:15], 0, v[194:195]
	v_lshlrev_b32_e32 v194, 1, v13
	v_mfma_f32_16x16x32_bf16 v[22:25], v[74:77], v[38:41], v[22:25]
	global_load_dwordx4 v[70:73], v[8:9], off offset:1408
	global_load_dwordx4 v[74:77], v[8:9], off offset:1472
	v_mfma_f32_16x16x32_bf16 v[14:17], v[50:53], v[38:41], v[14:17]
	global_load_dwordx4 v[38:41], v[6:7], off offset:1408
	global_load_dwordx4 v[50:53], v[6:7], off offset:1472
	s_waitcnt vmcnt(0) lgkmcnt(0)
	v_mfma_f32_16x16x32_bf16 v[22:25], v[70:73], v[46:49], v[22:25]
	global_load_dwordx2 v[70:71], v[78:79], off
	v_mfma_f32_16x16x32_bf16 v[14:17], v[38:41], v[46:49], v[14:17]
	global_load_dwordx4 v[38:41], v[8:9], off offset:1536
	global_load_dwordx4 v[46:49], v[8:9], off offset:1600
	v_mfma_f32_16x16x32_bf16 v[14:17], v[50:53], v[58:61], v[14:17]
	global_load_dwordx4 v[50:53], v[6:7], off offset:1536
	v_mfma_f32_16x16x32_bf16 v[22:25], v[74:77], v[58:61], v[22:25]
	s_waitcnt vmcnt(0) lgkmcnt(0)
	v_mfma_f32_16x16x32_bf16 v[22:25], v[38:41], v[18:21], v[22:25]
	global_load_dwordx4 v[38:41], v[6:7], off offset:1600
	v_mfma_f32_16x16x32_bf16 v[14:17], v[50:53], v[18:21], v[14:17]
	v_lshl_add_u64 v[18:19], s[12:13], 0, v[194:195]
	v_lshl_add_u64 v[18:19], s[0:1], 1, v[18:19]
	v_lshl_add_u64 v[72:73], v[18:19], 0, v[4:5]
	v_mfma_f32_16x16x32_bf16 v[18:21], v[46:49], v[30:33], v[22:25]
	s_nop 2
	global_load_dwordx4 v[22:25], v[8:9], off offset:1664
	global_load_dwordx4 v[46:49], v[8:9], off offset:1728
	global_load_dwordx4 v[50:53], v[8:9], off offset:1792
	v_ffbh_u32_e32 v5, v71
	v_min_u32_e32 v5, 32, v5
	s_waitcnt vmcnt(0) lgkmcnt(0)
	v_mfma_f32_16x16x32_bf16 v[14:17], v[38:41], v[30:33], v[14:17]
	global_load_dwordx4 v[30:33], v[6:7], off offset:1664
	v_mfma_f32_16x16x32_bf16 v[18:21], v[22:25], v[62:65], v[18:21]
	global_load_dwordx4 v[22:25], v[6:7], off offset:1728
	v_mfma_f32_16x16x32_bf16 v[18:21], v[46:49], v[26:29], v[18:21]
	v_mfma_f32_16x16x32_bf16 v[18:21], v[50:53], v[42:45], v[18:21]
	s_waitcnt vmcnt(0) lgkmcnt(0)
	v_mfma_f32_16x16x32_bf16 v[14:17], v[30:33], v[62:65], v[14:17]
	global_load_dwordx4 v[30:33], v[8:9], off offset:1856
	global_load_dwordx4 v[38:41], v[8:9], off offset:1920
	global_load_dwordx4 v[58:61], v[8:9], off offset:1984
	global_load_dwordx4 v[46:49], v[6:7], off offset:1792
	v_mfma_f32_16x16x32_bf16 v[14:17], v[22:25], v[26:29], v[14:17]
	global_load_dwordx4 v[22:25], v[6:7], off offset:1856
	global_load_dwordx4 v[26:29], v[6:7], off offset:1920
	s_nop 0
	global_load_dwordx4 v[6:9], v[6:7], off offset:1984
	s_waitcnt vmcnt(0) lgkmcnt(0)
	v_mfma_f32_16x16x32_bf16 v[18:21], v[30:33], v[66:69], v[18:21]
	v_lshlrev_b64 v[30:31], v5, v[70:71]
	v_min_u32_e32 v13, 1, v30
	v_or_b32_e32 v13, v31, v13
	v_cvt_f32_u32_e32 v13, v13
	v_mfma_f32_16x16x32_bf16 v[14:17], v[46:49], v[42:45], v[14:17]
	v_sub_u32_e32 v5, 32, v5
	v_ldexp_f32 v5, v13, v5
	v_fmamk_f32 v5, v5, 0x2e800000, v236
	v_mfma_f32_16x16x32_bf16 v[14:17], v[22:25], v[66:69], v[14:17]
	v_mul_f32_e32 v13, 0x4b800000, v5
	v_cmp_gt_f32_e32 vcc, s20, v5
	v_mfma_f32_16x16x32_bf16 v[18:21], v[38:41], v[34:37], v[18:21]
	s_nop 0
	v_cndmask_b32_e32 v5, v5, v13, vcc
	v_rsq_f32_e32 v5, v5
	v_mfma_f32_16x16x32_bf16 v[14:17], v[26:29], v[34:37], v[14:17]
	v_mul_f32_e32 v13, 0x45800000, v5
	v_cndmask_b32_e32 v22, v5, v13, vcc
	v_mfma_f32_16x16x32_bf16 v[18:21], v[58:61], v[54:57], v[18:21]
	v_mfma_f32_16x16x32_bf16 v[6:9], v[6:9], v[54:57], v[14:17]
	s_nop 6
	v_mul_f32_e64 v14, v18, v22
	v_mul_f32_e64 v15, v19, v22
	v_pk_mul_f32 v[16:17], v[20:21], v[22:23] op_sel_hi:[1,0]
	v_mul_f32_e32 v5, 0xbfb8aa3b, v14
	v_mul_f32_e32 v13, 0xbfb8aa3b, v15
	v_exp_f32_e32 v18, v5
	v_exp_f32_e32 v19, v13
	v_mul_f32_e32 v20, 0xbfb8aa3b, v16
	v_mul_f32_e32 v21, 0xbfb8aa3b, v17
	v_exp_f32_e32 v20, v20
	v_exp_f32_e32 v21, v21
	v_pk_add_f32 v[18:19], v[18:19], 1.0 op_sel_hi:[1,0]
	v_pk_mul_f32 v[6:7], v[6:7], v[22:23] op_sel_hi:[1,0]
	v_pk_mul_f32 v[8:9], v[8:9], v[22:23] op_sel_hi:[1,0]
	v_pk_add_f32 v[20:21], v[20:21], 1.0 op_sel_hi:[1,0]
	v_div_scale_f32 v22, s[0:1], v18, v18, 1.0
	v_div_scale_f32 v24, s[8:9], v21, v21, 1.0
	v_rcp_f32_e32 v29, v22
	v_div_scale_f32 v26, s[10:11], v20, v20, 1.0
	v_rcp_f32_e32 v30, v24
	v_rcp_f32_e32 v31, v26
	v_fma_f32 v33, -v22, v29, 1.0
	v_div_scale_f32 v23, s[0:1], 1.0, v18, 1.0
	v_fma_f32 v34, -v24, v30, 1.0
	v_fmac_f32_e32 v29, v33, v29
	v_div_scale_f32 v25, s[8:9], 1.0, v21, 1.0
	v_fma_f32 v35, -v26, v31, 1.0
	v_fmac_f32_e32 v30, v34, v30
	v_mul_f32_e32 v33, v23, v29
	v_div_scale_f32 v27, s[10:11], 1.0, v20, 1.0
	v_fmac_f32_e32 v31, v35, v31
	v_mul_f32_e32 v34, v25, v30
	v_fma_f32 v37, -v22, v33, v23
	v_mul_f32_e32 v35, v27, v31
	v_fma_f32 v38, -v24, v34, v25
	v_fmac_f32_e32 v33, v37, v29
	v_fma_f32 v39, -v26, v35, v27
	v_fmac_f32_e32 v34, v38, v30
	v_fma_f32 v13, -v22, v33, v23
	s_mov_b64 vcc, s[0:1]
	v_fmac_f32_e32 v35, v39, v31
	v_fma_f32 v22, -v24, v34, v25
	v_rcp_f32_e32 v19, v19
	v_div_fmas_f32 v5, v13, v29, v33
	s_mov_b64 vcc, s[8:9]
	v_fma_f32 v23, -v26, v35, v27
	v_div_fixup_f32 v18, v5, v18, 1.0
	v_div_fmas_f32 v5, v22, v30, v34
	s_mov_b64 vcc, s[10:11]
	v_pk_mul_f32 v[14:15], v[14:15], v[18:19]
	v_div_fixup_f32 v19, v5, v21, 1.0
	v_div_fmas_f32 v5, v23, v31, v35
	v_div_fixup_f32 v18, v5, v20, 1.0
	v_pk_mul_f32 v[6:7], v[6:7], v[14:15]
	v_pk_mul_f32 v[14:15], v[16:17], v[18:19]
	v_cvt_pk_bf16_f32 v6, v6, v7
	v_pk_mul_f32 v[8:9], v[8:9], v[14:15]
	s_nop 0
	v_cvt_pk_bf16_f32 v7, v8, v9
	global_store_dwordx2 v[72:73], v[6:7], off
	s_cbranch_scc0 .LBB0_871

.LBB0_877:
	s_ashr_i32 s1, s2, 3
	s_and_b32 s0, s3, 0x70
	v_or_b32_e32 v6, s0, v11
	s_lshl_b32 s0, s1, 4
	s_lshl_b32 s1, s1, 5
	s_and_b32 s4, s1, 0xffffff00
	s_and_b32 s5, s0, 0x70
	s_or_b32 s4, s5, s4
	v_lshlrev_b32_e32 v194, 11, v6
	v_or_b32_e32 v10, 0x4000, v6
	v_or_b32_e32 v6, s4, v11
	v_ashrrev_i32_e32 v7, 31, v6
	v_or_b32_e32 v20, 0x80, v6
	v_lshlrev_b64 v[6:7], 11, v[6:7]
	v_lshl_add_u64 v[76:77], v[0:1], 0, v[194:195]
	v_ashrrev_i32_e32 v21, 31, v20
	v_lshl_add_u64 v[8:9], v[2:3], 0, v[6:7]
	global_load_dwordx4 v[12:15], v[76:77], off
	global_load_dwordx4 v[16:19], v[76:77], off offset:64
	v_lshlrev_b64 v[6:7], 11, v[20:21]
	global_load_dwordx4 v[20:23], v[8:9], off
	v_lshl_add_u64 v[6:7], v[2:3], 0, v[6:7]
	global_load_dwordx4 v[24:27], v[8:9], off offset:64
	global_load_dwordx4 v[28:31], v[6:7], off
	global_load_dwordx4 v[32:35], v[6:7], off offset:64
	v_lshlrev_b32_e32 v194, 3, v10
	v_mul_u32_u24_e32 v10, 0xb00, v10
	s_ashr_i32 s1, s0, 31
	v_mov_b32_e32 v5, v195
	s_add_i32 s2, s2, s18
	s_add_i32 s3, s3, s19
	s_cmpk_gt_i32 s2, 0x57f
	s_waitcnt vmcnt(0) lgkmcnt(0)
	v_mfma_f32_16x16x32_bf16 v[20:23], v[20:23], v[12:15], 0
	v_mfma_f32_16x16x32_bf16 v[12:15], v[28:31], v[12:15], 0
	global_load_dwordx4 v[28:31], v[76:77], off offset:128
	global_load_dwordx4 v[36:39], v[76:77], off offset:192
	v_mfma_f32_16x16x32_bf16 v[20:23], v[24:27], v[16:19], v[20:23]
	global_load_dwordx4 v[24:27], v[8:9], off offset:128
	global_load_dwordx4 v[40:43], v[8:9], off offset:192
	v_mfma_f32_16x16x32_bf16 v[12:15], v[32:35], v[16:19], v[12:15]
	global_load_dwordx4 v[16:19], v[6:7], off offset:128
	s_waitcnt vmcnt(0) lgkmcnt(0)
	v_mfma_f32_16x16x32_bf16 v[20:23], v[24:27], v[28:31], v[20:23]
	global_load_dwordx4 v[24:27], v[6:7], off offset:192
	v_mfma_f32_16x16x32_bf16 v[12:15], v[16:19], v[28:31], v[12:15]
	global_load_dwordx4 v[16:19], v[76:77], off offset:256
	global_load_dwordx4 v[28:31], v[76:77], off offset:320
	v_mfma_f32_16x16x32_bf16 v[20:23], v[40:43], v[36:39], v[20:23]
	global_load_dwordx4 v[32:35], v[8:9], off offset:256
	global_load_dwordx4 v[40:43], v[8:9], off offset:320
	s_waitcnt vmcnt(0) lgkmcnt(0)
	v_mfma_f32_16x16x32_bf16 v[12:15], v[24:27], v[36:39], v[12:15]
	global_load_dwordx4 v[24:27], v[6:7], off offset:256
	v_mfma_f32_16x16x32_bf16 v[20:23], v[32:35], v[16:19], v[20:23]
	global_load_dwordx4 v[32:35], v[6:7], off offset:320
	v_mfma_f32_16x16x32_bf16 v[20:23], v[40:43], v[28:31], v[20:23]
	s_waitcnt vmcnt(0) lgkmcnt(0)
	v_mfma_f32_16x16x32_bf16 v[12:15], v[24:27], v[16:19], v[12:15]
	global_load_dwordx4 v[16:19], v[76:77], off offset:384
	global_load_dwordx4 v[24:27], v[76:77], off offset:448
	global_load_dwordx4 v[36:39], v[76:77], off offset:512
	global_load_dwordx4 v[40:43], v[8:9], off offset:384
	global_load_dwordx4 v[44:47], v[8:9], off offset:448
	v_mfma_f32_16x16x32_bf16 v[12:15], v[32:35], v[28:31], v[12:15]
	global_load_dwordx4 v[28:31], v[6:7], off offset:384
	global_load_dwordx4 v[32:35], v[6:7], off offset:448
	s_waitcnt vmcnt(0) lgkmcnt(0)
	v_mfma_f32_16x16x32_bf16 v[20:23], v[40:43], v[16:19], v[20:23]
	v_mfma_f32_16x16x32_bf16 v[12:15], v[28:31], v[16:19], v[12:15]
	global_load_dwordx4 v[16:19], v[76:77], off offset:576
	global_load_dwordx4 v[28:31], v[76:77], off offset:640
	global_load_dwordx4 v[40:43], v[76:77], off offset:704
	v_mfma_f32_16x16x32_bf16 v[20:23], v[44:47], v[24:27], v[20:23]
	global_load_dwordx4 v[44:47], v[8:9], off offset:512
	global_load_dwordx4 v[48:51], v[8:9], off offset:576
	v_mfma_f32_16x16x32_bf16 v[12:15], v[32:35], v[24:27], v[12:15]
	global_load_dwordx4 v[24:27], v[6:7], off offset:512
	global_load_dwordx4 v[32:35], v[6:7], off offset:576
	s_waitcnt vmcnt(0) lgkmcnt(0)
	v_mfma_f32_16x16x32_bf16 v[20:23], v[44:47], v[36:39], v[20:23]
	v_mfma_f32_16x16x32_bf16 v[12:15], v[24:27], v[36:39], v[12:15]
	global_load_dwordx4 v[24:27], v[76:77], off offset:768
	global_load_dwordx4 v[36:39], v[76:77], off offset:832
	global_load_dwordx4 v[44:47], v[76:77], off offset:896
	v_mfma_f32_16x16x32_bf16 v[20:23], v[48:51], v[16:19], v[20:23]
	global_load_dwordx4 v[48:51], v[8:9], off offset:640
	global_load_dwordx4 v[52:55], v[8:9], off offset:704
	v_mfma_f32_16x16x32_bf16 v[12:15], v[32:35], v[16:19], v[12:15]
	global_load_dwordx4 v[16:19], v[6:7], off offset:640
	global_load_dwordx4 v[32:35], v[6:7], off offset:704
	s_waitcnt vmcnt(0) lgkmcnt(0)
	v_mfma_f32_16x16x32_bf16 v[20:23], v[48:51], v[28:31], v[20:23]
	v_mfma_f32_16x16x32_bf16 v[12:15], v[16:19], v[28:31], v[12:15]
	global_load_dwordx4 v[16:19], v[76:77], off offset:960
	global_load_dwordx4 v[28:31], v[76:77], off offset:1024
	global_load_dwordx4 v[48:51], v[76:77], off offset:1088
	v_mfma_f32_16x16x32_bf16 v[20:23], v[52:55], v[40:43], v[20:23]
	global_load_dwordx4 v[52:55], v[8:9], off offset:768
	global_load_dwordx4 v[56:59], v[8:9], off offset:832
	v_mfma_f32_16x16x32_bf16 v[12:15], v[32:35], v[40:43], v[12:15]
	global_load_dwordx4 v[32:35], v[6:7], off offset:768
	global_load_dwordx4 v[40:43], v[6:7], off offset:832
	s_waitcnt vmcnt(0) lgkmcnt(0)
	v_mfma_f32_16x16x32_bf16 v[20:23], v[52:55], v[24:27], v[20:23]
	v_mfma_f32_16x16x32_bf16 v[12:15], v[32:35], v[24:27], v[12:15]
	global_load_dwordx4 v[24:27], v[76:77], off offset:1152
	global_load_dwordx4 v[32:35], v[76:77], off offset:1216
	global_load_dwordx4 v[52:55], v[76:77], off offset:1280
	v_mfma_f32_16x16x32_bf16 v[20:23], v[56:59], v[36:39], v[20:23]
	global_load_dwordx4 v[56:59], v[8:9], off offset:896
	global_load_dwordx4 v[60:63], v[8:9], off offset:960
	v_mfma_f32_16x16x32_bf16 v[12:15], v[40:43], v[36:39], v[12:15]
	global_load_dwordx4 v[36:39], v[6:7], off offset:896
	global_load_dwordx4 v[40:43], v[6:7], off offset:960
	s_waitcnt vmcnt(0) lgkmcnt(0)
	v_mfma_f32_16x16x32_bf16 v[20:23], v[56:59], v[44:47], v[20:23]
	v_mfma_f32_16x16x32_bf16 v[12:15], v[36:39], v[44:47], v[12:15]
	global_load_dwordx4 v[36:39], v[76:77], off offset:1344
	global_load_dwordx4 v[44:47], v[76:77], off offset:1408
	global_load_dwordx4 v[56:59], v[76:77], off offset:1472
	v_mfma_f32_16x16x32_bf16 v[20:23], v[60:63], v[16:19], v[20:23]
	global_load_dwordx4 v[60:63], v[8:9], off offset:1024
	global_load_dwordx4 v[64:67], v[8:9], off offset:1088
	v_mfma_f32_16x16x32_bf16 v[12:15], v[40:43], v[16:19], v[12:15]
	global_load_dwordx4 v[16:19], v[6:7], off offset:1024
	global_load_dwordx4 v[40:43], v[6:7], off offset:1088
	s_waitcnt vmcnt(0) lgkmcnt(0)
	v_mfma_f32_16x16x32_bf16 v[20:23], v[60:63], v[28:31], v[20:23]
	v_mfma_f32_16x16x32_bf16 v[12:15], v[16:19], v[28:31], v[12:15]
	global_load_dwordx4 v[16:19], v[76:77], off offset:1536
	global_load_dwordx4 v[28:31], v[76:77], off offset:1600
	global_load_dwordx4 v[60:63], v[76:77], off offset:1664
	v_mfma_f32_16x16x32_bf16 v[20:23], v[64:67], v[48:51], v[20:23]
	global_load_dwordx4 v[64:67], v[8:9], off offset:1152
	global_load_dwordx4 v[68:71], v[8:9], off offset:1216
	v_mfma_f32_16x16x32_bf16 v[12:15], v[40:43], v[48:51], v[12:15]
	global_load_dwordx4 v[40:43], v[6:7], off offset:1152
	global_load_dwordx4 v[48:51], v[6:7], off offset:1216
	s_waitcnt vmcnt(0) lgkmcnt(0)
	v_mfma_f32_16x16x32_bf16 v[20:23], v[64:67], v[24:27], v[20:23]
	v_mfma_f32_16x16x32_bf16 v[12:15], v[40:43], v[24:27], v[12:15]
	global_load_dwordx4 v[24:27], v[76:77], off offset:1728
	global_load_dwordx4 v[40:43], v[76:77], off offset:1792
	global_load_dwordx4 v[64:67], v[76:77], off offset:1856
	v_mfma_f32_16x16x32_bf16 v[20:23], v[68:71], v[32:35], v[20:23]
	global_load_dwordx4 v[68:71], v[8:9], off offset:1280
	global_load_dwordx4 v[72:75], v[8:9], off offset:1344
	v_mfma_f32_16x16x32_bf16 v[12:15], v[48:51], v[32:35], v[12:15]
	global_load_dwordx4 v[32:35], v[6:7], off offset:1280
	global_load_dwordx4 v[48:51], v[6:7], off offset:1344
	s_waitcnt vmcnt(0) lgkmcnt(0)
	v_mfma_f32_16x16x32_bf16 v[20:23], v[68:71], v[52:55], v[20:23]
	v_mfma_f32_16x16x32_bf16 v[12:15], v[32:35], v[52:55], v[12:15]
	global_load_dwordx4 v[32:35], v[76:77], off offset:1920
	global_load_dwordx4 v[52:55], v[76:77], off offset:1984
	v_lshl_add_u64 v[76:77], s[14:15], 0, v[194:195]
	v_lshlrev_b32_e32 v194, 1, v10
	v_mfma_f32_16x16x32_bf16 v[20:23], v[72:75], v[36:39], v[20:23]
	global_load_dwordx4 v[68:71], v[8:9], off offset:1408
	global_load_dwordx4 v[72:75], v[8:9], off offset:1472
	v_mfma_f32_16x16x32_bf16 v[12:15], v[48:51], v[36:39], v[12:15]
	global_load_dwordx4 v[36:39], v[6:7], off offset:1408
	global_load_dwordx4 v[48:51], v[6:7], off offset:1472
	s_waitcnt vmcnt(0) lgkmcnt(0)
	v_mfma_f32_16x16x32_bf16 v[20:23], v[68:71], v[44:47], v[20:23]
	global_load_dwordx2 v[68:69], v[76:77], off
	v_mfma_f32_16x16x32_bf16 v[12:15], v[36:39], v[44:47], v[12:15]
	global_load_dwordx4 v[36:39], v[8:9], off offset:1536
	global_load_dwordx4 v[44:47], v[8:9], off offset:1600
	v_mfma_f32_16x16x32_bf16 v[12:15], v[48:51], v[56:59], v[12:15]
	global_load_dwordx4 v[48:51], v[6:7], off offset:1536
	v_mfma_f32_16x16x32_bf16 v[20:23], v[72:75], v[56:59], v[20:23]
	s_waitcnt vmcnt(0) lgkmcnt(0)
	v_mfma_f32_16x16x32_bf16 v[20:23], v[36:39], v[16:19], v[20:23]
	global_load_dwordx4 v[36:39], v[6:7], off offset:1600
	v_mfma_f32_16x16x32_bf16 v[12:15], v[48:51], v[16:19], v[12:15]
	v_lshl_add_u64 v[16:17], s[12:13], 0, v[194:195]
	v_lshl_add_u64 v[16:17], s[0:1], 1, v[16:17]
	v_lshl_add_u64 v[70:71], v[16:17], 0, v[4:5]
	v_mfma_f32_16x16x32_bf16 v[16:19], v[44:47], v[28:31], v[20:23]
	s_nop 2
	global_load_dwordx4 v[20:23], v[8:9], off offset:1664
	global_load_dwordx4 v[44:47], v[8:9], off offset:1728
	global_load_dwordx4 v[48:51], v[8:9], off offset:1792
	v_ffbh_u32_e32 v5, v69
	v_min_u32_e32 v5, 32, v5
	s_waitcnt vmcnt(0) lgkmcnt(0)
	v_mfma_f32_16x16x32_bf16 v[12:15], v[36:39], v[28:31], v[12:15]
	global_load_dwordx4 v[28:31], v[6:7], off offset:1664
	v_mfma_f32_16x16x32_bf16 v[16:19], v[20:23], v[60:63], v[16:19]
	global_load_dwordx4 v[20:23], v[6:7], off offset:1728
	v_mfma_f32_16x16x32_bf16 v[16:19], v[44:47], v[24:27], v[16:19]
	v_mfma_f32_16x16x32_bf16 v[16:19], v[48:51], v[40:43], v[16:19]
	s_waitcnt vmcnt(0) lgkmcnt(0)
	v_mfma_f32_16x16x32_bf16 v[12:15], v[28:31], v[60:63], v[12:15]
	global_load_dwordx4 v[28:31], v[8:9], off offset:1856
	global_load_dwordx4 v[36:39], v[8:9], off offset:1920
	global_load_dwordx4 v[56:59], v[8:9], off offset:1984
	global_load_dwordx4 v[44:47], v[6:7], off offset:1792
	v_mfma_f32_16x16x32_bf16 v[12:15], v[20:23], v[24:27], v[12:15]
	global_load_dwordx4 v[20:23], v[6:7], off offset:1856
	global_load_dwordx4 v[24:27], v[6:7], off offset:1920
	s_nop 0
	global_load_dwordx4 v[6:9], v[6:7], off offset:1984
	s_waitcnt vmcnt(0) lgkmcnt(0)
	v_mfma_f32_16x16x32_bf16 v[16:19], v[28:31], v[64:67], v[16:19]
	v_lshlrev_b64 v[28:29], v5, v[68:69]
	v_min_u32_e32 v10, 1, v28
	v_or_b32_e32 v10, v29, v10
	v_cvt_f32_u32_e32 v10, v10
	v_mfma_f32_16x16x32_bf16 v[12:15], v[44:47], v[40:43], v[12:15]
	v_sub_u32_e32 v5, 32, v5
	v_ldexp_f32 v5, v10, v5
	v_fmamk_f32 v5, v5, 0x2e800000, v236
	v_mfma_f32_16x16x32_bf16 v[12:15], v[20:23], v[64:67], v[12:15]
	v_mul_f32_e32 v10, 0x4b800000, v5
	v_cmp_gt_f32_e32 vcc, s20, v5
	v_mfma_f32_16x16x32_bf16 v[16:19], v[36:39], v[32:35], v[16:19]
	s_nop 0
	v_cndmask_b32_e32 v5, v5, v10, vcc
	v_rsq_f32_e32 v5, v5
	v_mfma_f32_16x16x32_bf16 v[12:15], v[24:27], v[32:35], v[12:15]
	v_mul_f32_e32 v10, 0x45800000, v5
	v_cndmask_b32_e32 v10, v5, v10, vcc
	v_mfma_f32_16x16x32_bf16 v[16:19], v[56:59], v[52:55], v[16:19]
	v_mfma_f32_16x16x32_bf16 v[6:9], v[6:9], v[52:55], v[12:15]
	s_nop 6
	v_mul_f32_e64 v12, v16, v10
	v_mul_f32_e64 v13, v17, v10
	v_pk_mul_f32 v[14:15], v[18:19], v[10:11] op_sel_hi:[1,0]
	v_mul_f32_e32 v5, 0xbfb8aa3b, v12
	v_mul_f32_e32 v17, 0xbfb8aa3b, v13
	v_exp_f32_e32 v16, v5
	v_exp_f32_e32 v17, v17
	v_pk_mul_f32 v[6:7], v[6:7], v[10:11] op_sel_hi:[1,0]
	v_mul_f32_e32 v18, 0xbfb8aa3b, v14
	v_pk_mul_f32 v[8:9], v[8:9], v[10:11] op_sel_hi:[1,0]
	v_mul_f32_e32 v10, 0xbfb8aa3b, v15
	v_exp_f32_e32 v18, v18
	v_exp_f32_e32 v19, v10
	v_pk_add_f32 v[16:17], v[16:17], 1.0 op_sel_hi:[1,0]
	v_pk_add_f32 v[18:19], v[18:19], 1.0 op_sel_hi:[1,0]
	v_div_scale_f32 v20, s[0:1], v16, v16, 1.0
	v_div_scale_f32 v22, s[4:5], v19, v19, 1.0
	v_rcp_f32_e32 v27, v20
	v_div_scale_f32 v24, s[4:5], v18, v18, 1.0
	v_rcp_f32_e32 v28, v22
	v_rcp_f32_e32 v29, v24
	v_fma_f32 v31, -v20, v27, 1.0
	v_div_scale_f32 v21, s[0:1], 1.0, v16, 1.0
	v_fma_f32 v32, -v22, v28, 1.0
	v_fmac_f32_e32 v27, v31, v27
	v_div_scale_f32 v23, s[8:9], 1.0, v19, 1.0
	v_fma_f32 v33, -v24, v29, 1.0
	v_fmac_f32_e32 v28, v32, v28
	v_mul_f32_e32 v31, v21, v27
	v_div_scale_f32 v25, s[10:11], 1.0, v18, 1.0
	v_fmac_f32_e32 v29, v33, v29
	v_mul_f32_e32 v32, v23, v28
	v_fma_f32 v35, -v20, v31, v21
	v_mul_f32_e32 v33, v25, v29
	v_fma_f32 v36, -v22, v32, v23
	v_fmac_f32_e32 v31, v35, v27
	v_fma_f32 v37, -v24, v33, v25
	v_fmac_f32_e32 v32, v36, v28
	v_fma_f32 v10, -v20, v31, v21
	s_mov_b64 vcc, s[0:1]
	v_fmac_f32_e32 v33, v37, v29
	v_fma_f32 v20, -v22, v32, v23
	v_rcp_f32_e32 v17, v17
	v_div_fmas_f32 v5, v10, v27, v31
	s_mov_b64 vcc, s[8:9]
	v_fma_f32 v21, -v24, v33, v25
	v_div_fixup_f32 v16, v5, v16, 1.0
	v_div_fmas_f32 v5, v20, v28, v32
	s_mov_b64 vcc, s[10:11]
	v_pk_mul_f32 v[12:13], v[12:13], v[16:17]
	v_div_fixup_f32 v17, v5, v19, 1.0
	v_div_fmas_f32 v5, v21, v29, v33
	v_div_fixup_f32 v16, v5, v18, 1.0
	v_pk_mul_f32 v[6:7], v[6:7], v[12:13]
	v_pk_mul_f32 v[12:13], v[14:15], v[16:17]
	v_cvt_pk_bf16_f32 v6, v6, v7
	v_pk_mul_f32 v[8:9], v[8:9], v[12:13]
	s_nop 0
	v_cvt_pk_bf16_f32 v7, v8, v9
	global_store_dwordx2 v[70:71], v[6:7], off
	s_cbranch_scc0 .LBB0_877

.LBB0_908:
	ds_read2_b32 v[22:23], v21 offset1:65
	ds_read2_b32 v[24:25], v21 offset0:130 offset1:195
	v_add_u32_e32 v15, 0x400, v21
	ds_read2_b32 v[26:27], v15 offset0:4 offset1:69
	ds_read2_b32 v[28:29], v15 offset0:134 offset1:199
	v_mov_b32_e32 v15, v195
	s_waitcnt lgkmcnt(3)
	v_cvt_pk_bf16_f32 v22, v22, v23
	s_waitcnt lgkmcnt(2)
	v_cvt_pk_bf16_f32 v23, v24, v25
	s_waitcnt lgkmcnt(1)
	v_cvt_pk_bf16_f32 v24, v26, v27
	v_mad_u64_u32 v[26:27], s[2:3], s28, v12, 0
	s_waitcnt lgkmcnt(0)
	v_cvt_pk_bf16_f32 v25, v28, v29
	v_mov_b32_e32 v28, v27
	v_mad_u64_u32 v[28:29], s[2:3], s28, v13, v[28:29]
	v_mov_b32_e32 v27, v28
	v_lshl_add_u64 v[26:27], v[26:27], 1, s[4:5]
	v_lshl_add_u64 v[26:27], v[26:27], 0, v[14:15]
	s_add_i32 s59, s59, s60
	s_add_i32 s61, s61, s62
	s_and_b64 vcc, exec, s[6:7]
	s_mov_b32 s28, s42
	s_mov_b64 s[4:5], s[8:9]
	global_store_dwordx4 v[26:27], v[22:25], off
	s_waitcnt lgkmcnt(0)
	s_barrier
	s_cbranch_vccnz .LBB0_930

.LBB0_961:
	ds_read2_b32 v[20:21], v19 offset1:65
	ds_read2_b32 v[22:23], v19 offset0:130 offset1:195
	v_add_u32_e32 v15, 0x400, v19
	ds_read2_b32 v[24:25], v15 offset0:4 offset1:69
	ds_read2_b32 v[26:27], v15 offset0:134 offset1:199
	v_mov_b32_e32 v15, v195
	s_waitcnt lgkmcnt(3)
	v_cvt_pk_bf16_f32 v20, v20, v21
	s_waitcnt lgkmcnt(2)
	v_cvt_pk_bf16_f32 v21, v22, v23
	s_waitcnt lgkmcnt(1)
	v_cvt_pk_bf16_f32 v22, v24, v25
	v_mad_u64_u32 v[24:25], s[2:3], s62, v12, 0
	s_waitcnt lgkmcnt(0)
	v_cvt_pk_bf16_f32 v23, v26, v27
	v_mov_b32_e32 v26, v25
	v_mad_u64_u32 v[26:27], s[2:3], s62, v13, v[26:27]
	v_mov_b32_e32 v25, v26
	v_lshl_add_u64 v[24:25], v[24:25], 1, s[0:1]
	v_lshl_add_u64 v[24:25], v[24:25], 0, v[14:15]
	s_add_i32 s57, s57, s58
	s_add_i32 s59, s59, s60
	s_and_b64 vcc, exec, s[4:5]
	s_mov_b32 s62, s42
	s_mov_b64 s[0:1], s[6:7]
	global_store_dwordx4 v[24:25], v[20:23], off
	s_waitcnt lgkmcnt(0)
	s_barrier
	s_cbranch_vccnz .LBB0_983

.LBB0_1062:
	s_add_u32 s18, s16, 0x100
	s_addc_u32 s19, s17, 0
	s_add_i32 s56, 0, 0x10000
	v_add_u32_e32 v140, s56, v246
	ds_read_b128 v[128:131], v140
	ds_read_b128 v[132:135], v140 offset:1024
	ds_read_b128 v[136:139], v140 offset:2048
	ds_read_b128 v[140:143], v140 offset:3072
	s_cmp_eq_u32 s41, 40
	s_cselect_b32 s21, s1, s19
	s_cselect_b32 s20, s0, s18
	s_cselect_b32 s3, s15, s40
	s_cselect_b32 s2, s14, s39
	v_lshl_add_u64 v[176:177], s[16:17], 0, v[214:215]
	s_add_i32 m0, s26, 0xc000
	ds_read_b128 v[144:147], v248
	ds_read_b128 v[148:151], v248 offset:1024
	ds_read_b128 v[152:155], v248 offset:2048
	ds_read_b128 v[156:159], v248 offset:3072
	ds_read_b128 v[160:163], v248 offset:4096
	ds_read_b128 v[164:167], v248 offset:5120
	ds_read_b128 v[168:171], v248 offset:6144
	ds_read_b128 v[172:175], v248 offset:7168
	global_load_lds_dwordx4 v[176:177], off
	v_lshl_add_u64 v[176:177], s[16:17], 0, v[212:213]
	s_add_i32 m0, s26, 0xe000
	s_nop 0
	global_load_lds_dwordx4 v[176:177], off
	s_waitcnt lgkmcnt(8)
	s_barrier
	s_waitcnt lgkmcnt(0)
	s_setprio 1
	s_waitcnt lgkmcnt(0)
	v_mfma_f32_16x16x32_bf16 v[124:127], v[128:131], v[144:147], v[124:127]
	v_mfma_f32_16x16x32_bf16 v[120:123], v[136:139], v[144:147], v[120:123]
	v_mfma_f32_16x16x32_bf16 v[100:103], v[128:131], v[152:155], v[100:103]
	v_mfma_f32_16x16x32_bf16 v[96:99], v[136:139], v[152:155], v[96:99]
	v_mfma_f32_16x16x32_bf16 v[84:87], v[128:131], v[160:163], v[84:87]
	v_mfma_f32_16x16x32_bf16 v[80:83], v[136:139], v[160:163], v[80:83]
	v_mfma_f32_16x16x32_bf16 v[68:71], v[128:131], v[168:171], v[68:71]
	v_mfma_f32_16x16x32_bf16 v[60:63], v[136:139], v[168:171], v[60:63]
	v_mfma_f32_16x16x32_bf16 v[124:127], v[132:135], v[148:151], v[124:127]
	v_mfma_f32_16x16x32_bf16 v[120:123], v[140:143], v[148:151], v[120:123]
	v_mfma_f32_16x16x32_bf16 v[100:103], v[132:135], v[156:159], v[100:103]
	v_mfma_f32_16x16x32_bf16 v[96:99], v[140:143], v[156:159], v[96:99]
	v_mfma_f32_16x16x32_bf16 v[84:87], v[132:135], v[164:167], v[84:87]
	v_mfma_f32_16x16x32_bf16 v[80:83], v[140:143], v[164:167], v[80:83]
	v_mfma_f32_16x16x32_bf16 v[68:71], v[132:135], v[172:175], v[68:71]
	v_mfma_f32_16x16x32_bf16 v[60:63], v[140:143], v[172:175], v[60:63]
	s_setprio 0
	s_barrier
	s_add_i32 s57, 0, 0x14000
	s_add_i32 s16, s56, s25
	v_add_u32_e32 v188, s57, v246
	v_lshl_add_u64 v[202:203], s[2:3], 0, v[194:195]
	s_mov_b32 m0, s16
	ds_read_b128 v[176:179], v188
	ds_read_b128 v[180:183], v188 offset:1024
	ds_read_b128 v[184:187], v188 offset:2048
	ds_read_b128 v[188:191], v188 offset:3072
	global_load_lds_dwordx4 v[202:203], off
	v_lshl_add_u64 v[216:217], s[2:3], 0, v[206:207]
	s_add_i32 m0, s16, 0x2000
	s_nop 0
	global_load_lds_dwordx4 v[216:217], off
	s_barrier
	s_waitcnt lgkmcnt(0)
	s_setprio 1
	s_waitcnt lgkmcnt(0)
	v_mfma_f32_16x16x32_bf16 v[116:119], v[176:179], v[144:147], v[116:119]
	v_mfma_f32_16x16x32_bf16 v[112:115], v[184:187], v[144:147], v[112:115]
	v_mfma_f32_16x16x32_bf16 v[108:111], v[176:179], v[152:155], v[108:111]
	v_mfma_f32_16x16x32_bf16 v[104:107], v[184:187], v[152:155], v[104:107]
	v_mfma_f32_16x16x32_bf16 v[92:95], v[176:179], v[160:163], v[92:95]
	v_mfma_f32_16x16x32_bf16 v[88:91], v[184:187], v[160:163], v[88:91]
	v_mfma_f32_16x16x32_bf16 v[76:79], v[176:179], v[168:171], v[76:79]
	v_mfma_f32_16x16x32_bf16 v[72:75], v[184:187], v[168:171], v[72:75]
	v_mfma_f32_16x16x32_bf16 v[116:119], v[180:183], v[148:151], v[116:119]
	v_mfma_f32_16x16x32_bf16 v[112:115], v[188:191], v[148:151], v[112:115]
	v_mfma_f32_16x16x32_bf16 v[108:111], v[180:183], v[156:159], v[108:111]
	v_mfma_f32_16x16x32_bf16 v[104:107], v[188:191], v[156:159], v[104:107]
	v_mfma_f32_16x16x32_bf16 v[92:95], v[180:183], v[164:167], v[92:95]
	v_mfma_f32_16x16x32_bf16 v[88:91], v[188:191], v[164:167], v[88:91]
	v_mfma_f32_16x16x32_bf16 v[76:79], v[180:183], v[172:175], v[76:79]
	v_mfma_f32_16x16x32_bf16 v[72:75], v[188:191], v[172:175], v[72:75]
	s_setprio 0
	s_mov_b32 m0, s26
	v_lshl_add_u64 v[218:219], s[20:21], 0, v[210:211]
	s_barrier
	ds_read_b128 v[144:147], v248 offset:16384
	ds_read_b128 v[148:151], v248 offset:17408
	ds_read_b128 v[152:155], v248 offset:18432
	ds_read_b128 v[156:159], v248 offset:19456
	ds_read_b128 v[160:163], v248 offset:20480
	ds_read_b128 v[164:167], v248 offset:21504
	ds_read_b128 v[168:171], v248 offset:22528
	ds_read_b128 v[172:175], v248 offset:23552
	global_load_lds_dwordx4 v[218:219], off
	v_lshl_add_u64 v[220:221], s[20:21], 0, v[208:209]
	s_mov_b32 m0, s27
	s_nop 0
	global_load_lds_dwordx4 v[220:221], off
	s_barrier
	s_waitcnt lgkmcnt(0)
	s_setprio 1
	s_waitcnt lgkmcnt(0)
	v_mfma_f32_16x16x32_bf16 v[52:55], v[128:131], v[144:147], v[52:55]
	v_mfma_f32_16x16x32_bf16 v[48:51], v[136:139], v[144:147], v[48:51]
	v_mfma_f32_16x16x32_bf16 v[36:39], v[128:131], v[152:155], v[36:39]
	v_mfma_f32_16x16x32_bf16 v[32:35], v[136:139], v[152:155], v[32:35]
	v_mfma_f32_16x16x32_bf16 v[20:23], v[128:131], v[160:163], v[20:23]
	v_mfma_f32_16x16x32_bf16 v[16:19], v[136:139], v[160:163], v[16:19]
	v_mfma_f32_16x16x32_bf16 v[4:7], v[128:131], v[168:171], v[4:7]
	v_mfma_f32_16x16x32_bf16 v[0:3], v[136:139], v[168:171], v[0:3]
	v_mfma_f32_16x16x32_bf16 v[52:55], v[132:135], v[148:151], v[52:55]
	v_mfma_f32_16x16x32_bf16 v[48:51], v[140:143], v[148:151], v[48:51]
	v_mfma_f32_16x16x32_bf16 v[36:39], v[132:135], v[156:159], v[36:39]
	v_mfma_f32_16x16x32_bf16 v[32:35], v[140:143], v[156:159], v[32:35]
	v_mfma_f32_16x16x32_bf16 v[20:23], v[132:135], v[164:167], v[20:23]
	v_mfma_f32_16x16x32_bf16 v[16:19], v[140:143], v[164:167], v[16:19]
	v_mfma_f32_16x16x32_bf16 v[4:7], v[132:135], v[172:175], v[4:7]
	v_mfma_f32_16x16x32_bf16 v[0:3], v[140:143], v[172:175], v[0:3]
	s_setprio 0
	s_barrier
	s_add_u32 s16, s2, 0xb0000
	s_addc_u32 s17, s3, 0
	s_add_i32 s56, s57, s25
	v_lshl_add_u64 v[128:129], s[16:17], 0, v[194:195]
	s_mov_b32 m0, s56
	s_nop 0
	global_load_lds_dwordx4 v[128:129], off
	v_lshl_add_u64 v[128:129], s[16:17], 0, v[206:207]
	s_add_i32 m0, s56, 0x2000
	s_nop 0
	global_load_lds_dwordx4 v[128:129], off
	s_waitcnt vmcnt(6)
	s_barrier
	s_setprio 1
	v_mfma_f32_16x16x32_bf16 v[64:67], v[176:179], v[144:147], v[64:67]
	v_mfma_f32_16x16x32_bf16 v[56:59], v[184:187], v[144:147], v[56:59]
	v_mfma_f32_16x16x32_bf16 v[44:47], v[176:179], v[152:155], v[44:47]
	v_mfma_f32_16x16x32_bf16 v[40:43], v[184:187], v[152:155], v[40:43]
	v_mfma_f32_16x16x32_bf16 v[28:31], v[176:179], v[160:163], v[28:31]
	v_mfma_f32_16x16x32_bf16 v[24:27], v[184:187], v[160:163], v[24:27]
	v_mfma_f32_16x16x32_bf16 v[12:15], v[176:179], v[168:171], v[12:15]
	v_mfma_f32_16x16x32_bf16 v[8:11], v[184:187], v[168:171], v[8:11]
	v_mfma_f32_16x16x32_bf16 v[64:67], v[180:183], v[148:151], v[64:67]
	v_mfma_f32_16x16x32_bf16 v[56:59], v[188:191], v[148:151], v[56:59]
	v_mfma_f32_16x16x32_bf16 v[44:47], v[180:183], v[156:159], v[44:47]
	v_mfma_f32_16x16x32_bf16 v[40:43], v[188:191], v[156:159], v[40:43]
	v_mfma_f32_16x16x32_bf16 v[28:31], v[180:183], v[164:167], v[28:31]
	v_mfma_f32_16x16x32_bf16 v[24:27], v[188:191], v[164:167], v[24:27]
	v_mfma_f32_16x16x32_bf16 v[12:15], v[180:183], v[172:175], v[12:15]
	v_mfma_f32_16x16x32_bf16 v[8:11], v[188:191], v[172:175], v[8:11]
	s_setprio 0
	s_add_i32 s56, 0, 0x18000
	v_add_u32_e32 v140, s56, v246
	s_barrier
	ds_read_b128 v[128:131], v140
	ds_read_b128 v[132:135], v140 offset:1024
	ds_read_b128 v[136:139], v140 offset:2048
	ds_read_b128 v[140:143], v140 offset:3072
	s_add_u32 s16, s20, 0xb0000
	s_addc_u32 s17, s21, 0
	s_mov_b32 m0, s28
	v_lshl_add_u64 v[176:177], s[16:17], 0, v[210:211]
	ds_read_b128 v[144:147], v248 offset:32768
	ds_read_b128 v[148:151], v248 offset:33792
	ds_read_b128 v[152:155], v248 offset:34816
	ds_read_b128 v[156:159], v248 offset:35840
	ds_read_b128 v[160:163], v248 offset:36864
	ds_read_b128 v[164:167], v248 offset:37888
	ds_read_b128 v[168:171], v248 offset:38912
	ds_read_b128 v[172:175], v248 offset:39936
	global_load_lds_dwordx4 v[176:177], off
	v_lshl_add_u64 v[176:177], s[16:17], 0, v[208:209]
	s_mov_b32 m0, s29
	s_nop 0
	global_load_lds_dwordx4 v[176:177], off
	s_waitcnt lgkmcnt(8)
	s_barrier
	s_waitcnt lgkmcnt(0)
	s_setprio 1
	s_waitcnt lgkmcnt(0)
	v_mfma_f32_16x16x32_bf16 v[124:127], v[128:131], v[144:147], v[124:127]
	v_mfma_f32_16x16x32_bf16 v[120:123], v[136:139], v[144:147], v[120:123]
	v_mfma_f32_16x16x32_bf16 v[100:103], v[128:131], v[152:155], v[100:103]
	v_mfma_f32_16x16x32_bf16 v[96:99], v[136:139], v[152:155], v[96:99]
	v_mfma_f32_16x16x32_bf16 v[84:87], v[128:131], v[160:163], v[84:87]
	v_mfma_f32_16x16x32_bf16 v[80:83], v[136:139], v[160:163], v[80:83]
	v_mfma_f32_16x16x32_bf16 v[68:71], v[128:131], v[168:171], v[68:71]
	v_mfma_f32_16x16x32_bf16 v[60:63], v[136:139], v[168:171], v[60:63]
	v_mfma_f32_16x16x32_bf16 v[124:127], v[132:135], v[148:151], v[124:127]
	v_mfma_f32_16x16x32_bf16 v[120:123], v[140:143], v[148:151], v[120:123]
	v_mfma_f32_16x16x32_bf16 v[100:103], v[132:135], v[156:159], v[100:103]
	v_mfma_f32_16x16x32_bf16 v[96:99], v[140:143], v[156:159], v[96:99]
	v_mfma_f32_16x16x32_bf16 v[84:87], v[132:135], v[164:167], v[84:87]
	v_mfma_f32_16x16x32_bf16 v[80:83], v[140:143], v[164:167], v[80:83]
	v_mfma_f32_16x16x32_bf16 v[68:71], v[132:135], v[172:175], v[68:71]
	v_mfma_f32_16x16x32_bf16 v[60:63], v[140:143], v[172:175], v[60:63]
	s_setprio 0
	s_barrier
	s_add_i32 s16, 0, 0x1c000
	s_add_i32 s17, s56, s25
	v_add_u32_e32 v188, s16, v246
	v_lshl_add_u64 v[202:203], v[202:203], 0, s[70:71]
	s_mov_b32 m0, s17
	ds_read_b128 v[176:179], v188
	ds_read_b128 v[180:183], v188 offset:1024
	ds_read_b128 v[184:187], v188 offset:2048
	ds_read_b128 v[188:191], v188 offset:3072
	global_load_lds_dwordx4 v[202:203], off
	v_lshl_add_u64 v[202:203], v[216:217], 0, s[70:71]
	s_add_i32 m0, s17, 0x2000
	s_nop 0
	global_load_lds_dwordx4 v[202:203], off
	s_barrier
	s_waitcnt lgkmcnt(0)
	s_setprio 1
	s_waitcnt lgkmcnt(0)
	v_mfma_f32_16x16x32_bf16 v[116:119], v[176:179], v[144:147], v[116:119]
	v_mfma_f32_16x16x32_bf16 v[112:115], v[184:187], v[144:147], v[112:115]
	v_mfma_f32_16x16x32_bf16 v[108:111], v[176:179], v[152:155], v[108:111]
	v_mfma_f32_16x16x32_bf16 v[104:107], v[184:187], v[152:155], v[104:107]
	v_mfma_f32_16x16x32_bf16 v[92:95], v[176:179], v[160:163], v[92:95]
	v_mfma_f32_16x16x32_bf16 v[88:91], v[184:187], v[160:163], v[88:91]
	v_mfma_f32_16x16x32_bf16 v[76:79], v[176:179], v[168:171], v[76:79]
	v_mfma_f32_16x16x32_bf16 v[72:75], v[184:187], v[168:171], v[72:75]
	v_mfma_f32_16x16x32_bf16 v[116:119], v[180:183], v[148:151], v[116:119]
	v_mfma_f32_16x16x32_bf16 v[112:115], v[188:191], v[148:151], v[112:115]
	v_mfma_f32_16x16x32_bf16 v[108:111], v[180:183], v[156:159], v[108:111]
	v_mfma_f32_16x16x32_bf16 v[104:107], v[188:191], v[156:159], v[104:107]
	v_mfma_f32_16x16x32_bf16 v[92:95], v[180:183], v[164:167], v[92:95]
	v_mfma_f32_16x16x32_bf16 v[88:91], v[188:191], v[164:167], v[88:91]
	v_mfma_f32_16x16x32_bf16 v[76:79], v[180:183], v[172:175], v[76:79]
	v_mfma_f32_16x16x32_bf16 v[72:75], v[188:191], v[172:175], v[72:75]
	s_setprio 0
	s_mov_b32 m0, s30
	v_lshl_add_u64 v[202:203], v[218:219], 0, s[70:71]
	s_barrier
	ds_read_b128 v[144:147], v248 offset:49152
	ds_read_b128 v[148:151], v248 offset:50176
	ds_read_b128 v[152:155], v248 offset:51200
	ds_read_b128 v[156:159], v248 offset:52224
	ds_read_b128 v[160:163], v248 offset:53248
	ds_read_b128 v[164:167], v248 offset:54272
	ds_read_b128 v[168:171], v248 offset:55296
	ds_read_b128 v[172:175], v248 offset:56320
	global_load_lds_dwordx4 v[202:203], off
	v_lshl_add_u64 v[202:203], v[220:221], 0, s[70:71]
	s_mov_b32 m0, s31
	s_nop 0
	global_load_lds_dwordx4 v[202:203], off
	s_barrier
	s_waitcnt lgkmcnt(0)
	s_setprio 1
	s_waitcnt lgkmcnt(0)
	v_mfma_f32_16x16x32_bf16 v[52:55], v[128:131], v[144:147], v[52:55]
	v_mfma_f32_16x16x32_bf16 v[48:51], v[136:139], v[144:147], v[48:51]
	v_mfma_f32_16x16x32_bf16 v[36:39], v[128:131], v[152:155], v[36:39]
	v_mfma_f32_16x16x32_bf16 v[32:35], v[136:139], v[152:155], v[32:35]
	v_mfma_f32_16x16x32_bf16 v[20:23], v[128:131], v[160:163], v[20:23]
	v_mfma_f32_16x16x32_bf16 v[16:19], v[136:139], v[160:163], v[16:19]
	v_mfma_f32_16x16x32_bf16 v[4:7], v[128:131], v[168:171], v[4:7]
	v_mfma_f32_16x16x32_bf16 v[0:3], v[136:139], v[168:171], v[0:3]
	v_mfma_f32_16x16x32_bf16 v[52:55], v[132:135], v[148:151], v[52:55]
	v_mfma_f32_16x16x32_bf16 v[48:51], v[140:143], v[148:151], v[48:51]
	v_mfma_f32_16x16x32_bf16 v[36:39], v[132:135], v[156:159], v[36:39]
	v_mfma_f32_16x16x32_bf16 v[32:35], v[140:143], v[156:159], v[32:35]
	v_mfma_f32_16x16x32_bf16 v[20:23], v[132:135], v[164:167], v[20:23]
	v_mfma_f32_16x16x32_bf16 v[16:19], v[140:143], v[164:167], v[16:19]
	v_mfma_f32_16x16x32_bf16 v[4:7], v[132:135], v[172:175], v[4:7]
	v_mfma_f32_16x16x32_bf16 v[0:3], v[140:143], v[172:175], v[0:3]
	s_setprio 0
	s_barrier
	s_add_u32 s2, s2, 0xb0080
	s_addc_u32 s3, s3, 0
	s_add_i32 s16, s16, s25
	v_lshl_add_u64 v[128:129], s[2:3], 0, v[194:195]
	s_mov_b32 m0, s16
	s_nop 0
	global_load_lds_dwordx4 v[128:129], off
	v_lshl_add_u64 v[128:129], s[2:3], 0, v[206:207]
	s_add_i32 m0, s16, 0x2000
	s_nop 0
	global_load_lds_dwordx4 v[128:129], off
	s_waitcnt vmcnt(6)
	s_barrier
	s_setprio 1
	v_mfma_f32_16x16x32_bf16 v[64:67], v[176:179], v[144:147], v[64:67]
	v_mfma_f32_16x16x32_bf16 v[56:59], v[184:187], v[144:147], v[56:59]
	v_mfma_f32_16x16x32_bf16 v[44:47], v[176:179], v[152:155], v[44:47]
	v_mfma_f32_16x16x32_bf16 v[40:43], v[184:187], v[152:155], v[40:43]
	v_mfma_f32_16x16x32_bf16 v[28:31], v[176:179], v[160:163], v[28:31]
	v_mfma_f32_16x16x32_bf16 v[24:27], v[184:187], v[160:163], v[24:27]
	v_mfma_f32_16x16x32_bf16 v[12:15], v[176:179], v[168:171], v[12:15]
	v_mfma_f32_16x16x32_bf16 v[8:11], v[184:187], v[168:171], v[8:11]
	v_mfma_f32_16x16x32_bf16 v[64:67], v[180:183], v[148:151], v[64:67]
	v_mfma_f32_16x16x32_bf16 v[56:59], v[188:191], v[148:151], v[56:59]
	v_mfma_f32_16x16x32_bf16 v[44:47], v[180:183], v[156:159], v[44:47]
	v_mfma_f32_16x16x32_bf16 v[40:43], v[188:191], v[156:159], v[40:43]
	v_mfma_f32_16x16x32_bf16 v[28:31], v[180:183], v[164:167], v[28:31]
	v_mfma_f32_16x16x32_bf16 v[24:27], v[188:191], v[164:167], v[24:27]
	v_mfma_f32_16x16x32_bf16 v[12:15], v[180:183], v[172:175], v[12:15]
	v_mfma_f32_16x16x32_bf16 v[8:11], v[188:191], v[172:175], v[8:11]
	s_setprio 0
	s_add_i32 s41, s41, 2
	s_add_u32 s39, s39, 0x100
	s_addc_u32 s40, s40, 0
	s_cmp_gt_u32 s41, 41
	s_mov_b64 s[16:17], s[18:19]
	s_barrier
	s_cbranch_scc0 .LBB0_1062
	v_lshl_or_b32 v216, s37, 8, v247
	v_lshl_add_u32 v232, s38, 8, v196
	v_ashrrev_i32_e32 v217, 31, v216
	v_lshlrev_b64 v[202:203], 1, v[216:217]
	v_ashrrev_i32_e32 v233, 31, v232
	v_lshl_add_u64 v[128:129], s[10:11], 0, v[202:203]
	v_lshlrev_b64 v[234:235], 11, v[232:233]
	v_lshl_add_u64 v[130:131], v[128:129], 0, v[234:235]
	global_load_dwordx4 v[188:191], v[130:131], off
	global_load_dwordx4 v[184:187], v[130:131], off offset:256
	v_or_b32_e32 v130, 16, v232
	v_ashrrev_i32_e32 v131, 31, v130
	v_lshlrev_b64 v[230:231], 11, v[130:131]
	v_lshl_add_u64 v[130:131], v[128:129], 0, v[230:231]
	global_load_dwordx4 v[180:183], v[130:131], off
	global_load_dwordx4 v[176:179], v[130:131], off offset:256
	v_or_b32_e32 v130, 32, v232
	v_ashrrev_i32_e32 v131, 31, v130
	v_lshlrev_b64 v[228:229], 11, v[130:131]
	v_lshl_add_u64 v[130:131], v[128:129], 0, v[228:229]
	global_load_dwordx4 v[172:175], v[130:131], off
	global_load_dwordx4 v[168:171], v[130:131], off offset:256
	v_or_b32_e32 v130, 48, v232
	v_ashrrev_i32_e32 v131, 31, v130
	s_mov_b64 s[2:3], 0x40000
	v_lshlrev_b64 v[226:227], 11, v[130:131]
	v_lshl_add_u64 v[224:225], v[234:235], 0, s[2:3]
	s_mov_b64 s[2:3], 0x48000
	v_lshl_add_u64 v[130:131], v[128:129], 0, v[226:227]
	v_lshl_add_u64 v[222:223], v[234:235], 0, s[2:3]
	s_mov_b64 s[2:3], 0x50000
	global_load_dwordx4 v[164:167], v[130:131], off
	global_load_dwordx4 v[160:163], v[130:131], off offset:256
	v_lshl_add_u64 v[130:131], v[128:129], 0, v[224:225]
	v_lshl_add_u64 v[220:221], v[234:235], 0, s[2:3]
	s_mov_b64 s[2:3], 0x58000
	global_load_dwordx4 v[156:159], v[130:131], off
	global_load_dwordx4 v[152:155], v[130:131], off offset:256
	v_lshl_add_u64 v[130:131], v[128:129], 0, v[222:223]
	v_lshl_add_u64 v[218:219], v[234:235], 0, s[2:3]
	global_load_dwordx4 v[148:151], v[130:131], off
	global_load_dwordx4 v[144:147], v[130:131], off offset:256
	v_lshl_add_u64 v[130:131], v[128:129], 0, v[220:221]
	v_lshl_add_u64 v[128:129], v[128:129], 0, v[218:219]
	global_load_dwordx4 v[140:143], v[130:131], off
	global_load_dwordx4 v[136:139], v[130:131], off offset:256
	global_load_dwordx4 v[132:135], v[128:129], off
	s_nop 0
	global_load_dwordx4 v[128:131], v[128:129], off offset:256
	v_lshl_add_u64 v[234:235], s[10:11], 0, v[234:235]
	v_lshl_add_u64 v[234:235], v[234:235], 0, v[202:203]
	v_and_b32_e32 v250, 64, v243
	v_xor_b32_e32 v249, 16, v243
	v_add_u32_e32 v250, 64, v250
	v_cmp_lt_i32_e32 vcc, v249, v250
	v_xor_b32_e32 v251, 32, v243
	s_waitcnt vmcnt(0) lgkmcnt(0)
	v_lshlrev_b32_e32 v202, 16, v188
	v_and_b32_e32 v203, 0xffff0000, v188
	v_lshlrev_b32_e32 v188, 16, v189
	v_and_b32_e32 v189, 0xffff0000, v189
	v_pk_add_f32 v[124:125], v[124:125], v[202:203]
	v_pk_add_f32 v[126:127], v[126:127], v[188:189]
	v_cvt_pk_bf16_f32 v124, v124, v125
	v_cvt_pk_bf16_f32 v125, v126, v127
	v_lshlrev_b32_e32 v126, 16, v190
	v_and_b32_e32 v127, 0xffff0000, v190
	v_pk_add_f32 v[120:121], v[120:121], v[126:127]
	v_cndmask_b32_e32 v249, v243, v249, vcc
	v_cvt_pk_bf16_f32 v126, v120, v121
	v_lshlrev_b32_e32 v120, 16, v191
	v_and_b32_e32 v121, 0xffff0000, v191
	v_pk_add_f32 v[120:121], v[122:123], v[120:121]
	v_lshlrev_b32_e32 v122, 16, v125
	v_cvt_pk_bf16_f32 v127, v120, v121
	v_and_b32_e32 v121, 0xffff0000, v124
	v_lshlrev_b32_e32 v120, 16, v124
	v_mul_f32_e32 v188, v121, v121
	v_fmac_f32_e32 v188, v120, v120
	v_lshlrev_b32_e32 v120, 16, v184
	v_and_b32_e32 v121, 0xffff0000, v184
	v_pk_add_f32 v[116:117], v[116:117], v[120:121]
	v_lshlrev_b32_e32 v120, 16, v185
	v_and_b32_e32 v121, 0xffff0000, v185
	v_and_b32_e32 v123, 0xffff0000, v125
	v_fmac_f32_e32 v188, v122, v122
	v_pk_add_f32 v[118:119], v[118:119], v[120:121]
	global_store_dwordx4 v[234:235], v[124:127], off
	v_fmac_f32_e32 v188, v123, v123
	v_cvt_pk_bf16_f32 v116, v116, v117
	v_lshlrev_b32_e32 v124, 16, v126
	v_cvt_pk_bf16_f32 v117, v118, v119
	v_lshlrev_b32_e32 v118, 16, v186
	v_and_b32_e32 v119, 0xffff0000, v186
	v_and_b32_e32 v125, 0xffff0000, v126
	v_fmac_f32_e32 v188, v124, v124
	v_pk_add_f32 v[112:113], v[112:113], v[118:119]
	v_lshlrev_b32_e32 v126, 16, v127
	v_fmac_f32_e32 v188, v125, v125
	v_cvt_pk_bf16_f32 v118, v112, v113
	v_lshlrev_b32_e32 v112, 16, v187
	v_and_b32_e32 v113, 0xffff0000, v187
	v_and_b32_e32 v127, 0xffff0000, v127
	v_fmac_f32_e32 v188, v126, v126
	v_pk_add_f32 v[112:113], v[114:115], v[112:113]
	v_fmac_f32_e32 v188, v127, v127
	v_cvt_pk_bf16_f32 v119, v112, v113
	v_lshlrev_b32_e32 v112, 16, v116
	v_and_b32_e32 v113, 0xffff0000, v116
	v_fmac_f32_e32 v188, v112, v112
	v_lshlrev_b32_e32 v114, 16, v117
	v_fmac_f32_e32 v188, v113, v113
	v_and_b32_e32 v115, 0xffff0000, v117
	v_fmac_f32_e32 v188, v114, v114
	global_store_dwordx4 v[234:235], v[116:119], off offset:256
	v_fmac_f32_e32 v188, v115, v115
	v_lshlrev_b32_e32 v249, 2, v249
	v_lshlrev_b32_e32 v116, 16, v118
	v_and_b32_e32 v117, 0xffff0000, v118
	v_fmac_f32_e32 v188, v116, v116
	v_lshlrev_b32_e32 v118, 16, v119
	v_fmac_f32_e32 v188, v117, v117
	v_and_b32_e32 v119, 0xffff0000, v119
	v_fmac_f32_e32 v188, v118, v118
	v_fmac_f32_e32 v188, v119, v119
	ds_bpermute_b32 v112, v249, v188
	v_cmp_lt_i32_e32 vcc, v251, v250
	s_waitcnt lgkmcnt(0)
	v_add_f32_e32 v114, v188, v112
	v_cndmask_b32_e32 v250, v243, v251, vcc
	v_lshlrev_b32_e32 v250, 2, v250
	ds_bpermute_b32 v115, v250, v114
	v_lshl_add_u64 v[112:113], v[232:233], 3, s[12:13]
	s_and_saveexec_b64 s[2:3], s[6:7]
	s_mov_b32 s18, 0x4b800000
	s_cbranch_execz .LBB0_1065
	s_waitcnt lgkmcnt(0)
	v_add_f32_e32 v114, v114, v115
	v_fma_f32 v114, v114, s18, 0.5
	v_trunc_f32_e32 v114, v114
	v_mul_f32_e32 v115, 0x2f800000, v114
	v_floor_f32_e32 v115, v115
	v_fmac_f32_e32 v114, 0xcf800000, v115
	v_cvt_u32_f32_e32 v114, v114
	v_cvt_u32_f32_e32 v115, v115
	global_atomic_add_x2 v[112:113], v[114:115], off
.LBB0_1065:
	s_or_b64 exec, exec, s[2:3]
	v_lshlrev_b32_e32 v114, 16, v180
	s_waitcnt lgkmcnt(0)
	v_and_b32_e32 v115, 0xffff0000, v180
	v_pk_add_f32 v[100:101], v[100:101], v[114:115]
	v_lshlrev_b32_e32 v114, 16, v181
	v_and_b32_e32 v115, 0xffff0000, v181
	v_pk_add_f32 v[102:103], v[102:103], v[114:115]
	v_cvt_pk_bf16_f32 v100, v100, v101
	v_cvt_pk_bf16_f32 v101, v102, v103
	v_lshlrev_b32_e32 v102, 16, v182
	v_and_b32_e32 v103, 0xffff0000, v182
	v_pk_add_f32 v[96:97], v[96:97], v[102:103]
	s_nop 0
	v_cvt_pk_bf16_f32 v102, v96, v97
	v_lshlrev_b32_e32 v96, 16, v183
	v_and_b32_e32 v97, 0xffff0000, v183
	v_pk_add_f32 v[96:97], v[98:99], v[96:97]
	v_lshlrev_b32_e32 v98, 16, v101
	v_cvt_pk_bf16_f32 v103, v96, v97
	v_and_b32_e32 v97, 0xffff0000, v100
	v_lshlrev_b32_e32 v96, 16, v100
	v_mul_f32_e32 v118, v97, v97
	v_fmac_f32_e32 v118, v96, v96
	v_lshlrev_b32_e32 v96, 16, v176
	v_and_b32_e32 v97, 0xffff0000, v176
	v_pk_add_f32 v[96:97], v[108:109], v[96:97]
	v_and_b32_e32 v99, 0xffff0000, v101
	v_cvt_pk_bf16_f32 v108, v96, v97
	v_lshlrev_b32_e32 v96, 16, v177
	v_and_b32_e32 v97, 0xffff0000, v177
	v_fmac_f32_e32 v118, v98, v98
	v_pk_add_f32 v[96:97], v[110:111], v[96:97]
	v_lshlrev_b32_e32 v114, 16, v102
	v_fmac_f32_e32 v118, v99, v99
	v_cvt_pk_bf16_f32 v109, v96, v97
	v_lshlrev_b32_e32 v96, 16, v178
	v_and_b32_e32 v97, 0xffff0000, v178
	v_and_b32_e32 v115, 0xffff0000, v102
	v_fmac_f32_e32 v118, v114, v114
	v_pk_add_f32 v[96:97], v[104:105], v[96:97]
	v_lshlrev_b32_e32 v116, 16, v103
	v_fmac_f32_e32 v118, v115, v115
	v_cvt_pk_bf16_f32 v110, v96, v97
	v_lshlrev_b32_e32 v96, 16, v179
	v_and_b32_e32 v97, 0xffff0000, v179
	v_and_b32_e32 v117, 0xffff0000, v103
	v_fmac_f32_e32 v118, v116, v116
	v_pk_add_f32 v[96:97], v[106:107], v[96:97]
	v_fmac_f32_e32 v118, v117, v117
	v_cvt_pk_bf16_f32 v111, v96, v97
	v_lshlrev_b32_e32 v96, 16, v108
	v_and_b32_e32 v97, 0xffff0000, v108
	v_fmac_f32_e32 v118, v96, v96
	v_lshlrev_b32_e32 v98, 16, v109
	v_fmac_f32_e32 v118, v97, v97
	v_and_b32_e32 v99, 0xffff0000, v109
	v_fmac_f32_e32 v118, v98, v98
	v_lshlrev_b32_e32 v104, 16, v110
	v_fmac_f32_e32 v118, v99, v99
	v_and_b32_e32 v105, 0xffff0000, v110
	v_fmac_f32_e32 v118, v104, v104
	v_lshlrev_b32_e32 v106, 16, v111
	v_fmac_f32_e32 v118, v105, v105
	v_and_b32_e32 v107, 0xffff0000, v111
	v_fmac_f32_e32 v118, v106, v106
	v_fmac_f32_e32 v118, v107, v107
	ds_bpermute_b32 v96, v249, v118
	v_lshl_add_u64 v[98:99], s[10:11], 0, v[230:231]
	v_lshl_add_u64 v[98:99], v[216:217], 1, v[98:99]
	global_store_dwordx4 v[98:99], v[100:103], off
	global_store_dwordx4 v[98:99], v[108:111], off offset:256
	s_waitcnt lgkmcnt(0)
	v_add_f32_e32 v96, v118, v96
	ds_bpermute_b32 v97, v250, v96
	s_and_saveexec_b64 s[2:3], s[6:7]
	s_cbranch_execz .LBB0_1067
	s_waitcnt lgkmcnt(0)
	v_add_f32_e32 v96, v96, v97
	v_fma_f32 v96, v96, s18, 0.5
	v_trunc_f32_e32 v96, v96
	v_mul_f32_e32 v97, 0x2f800000, v96
	v_floor_f32_e32 v97, v97
	v_fmac_f32_e32 v96, 0xcf800000, v97
	v_cvt_u32_f32_e32 v96, v96
	v_cvt_u32_f32_e32 v97, v97
	global_atomic_add_x2 v[112:113], v[96:97], off offset:128
.LBB0_1067:
	s_or_b64 exec, exec, s[2:3]
	v_lshlrev_b32_e32 v96, 16, v172
	s_waitcnt lgkmcnt(0)
	v_and_b32_e32 v97, 0xffff0000, v172
	v_pk_add_f32 v[84:85], v[84:85], v[96:97]
	v_lshlrev_b32_e32 v96, 16, v173
	v_and_b32_e32 v97, 0xffff0000, v173
	v_pk_add_f32 v[86:87], v[86:87], v[96:97]
	v_cvt_pk_bf16_f32 v84, v84, v85
	v_cvt_pk_bf16_f32 v85, v86, v87
	v_lshlrev_b32_e32 v86, 16, v174
	v_and_b32_e32 v87, 0xffff0000, v174
	v_pk_add_f32 v[80:81], v[80:81], v[86:87]
	s_nop 0
	v_cvt_pk_bf16_f32 v86, v80, v81
	v_lshlrev_b32_e32 v80, 16, v175
	v_and_b32_e32 v81, 0xffff0000, v175
	v_pk_add_f32 v[80:81], v[82:83], v[80:81]
	v_lshlrev_b32_e32 v82, 16, v85
	v_cvt_pk_bf16_f32 v87, v80, v81
	v_and_b32_e32 v81, 0xffff0000, v84
	v_lshlrev_b32_e32 v80, 16, v84
	v_mul_f32_e32 v100, v81, v81
	v_fmac_f32_e32 v100, v80, v80
	v_lshlrev_b32_e32 v80, 16, v168
	v_and_b32_e32 v81, 0xffff0000, v168
	v_pk_add_f32 v[80:81], v[92:93], v[80:81]
	v_and_b32_e32 v83, 0xffff0000, v85
	v_cvt_pk_bf16_f32 v92, v80, v81
	v_lshlrev_b32_e32 v80, 16, v169
	v_and_b32_e32 v81, 0xffff0000, v169
	v_fmac_f32_e32 v100, v82, v82
	v_pk_add_f32 v[80:81], v[94:95], v[80:81]
	v_lshlrev_b32_e32 v96, 16, v86
	v_fmac_f32_e32 v100, v83, v83
	v_cvt_pk_bf16_f32 v93, v80, v81
	v_lshlrev_b32_e32 v80, 16, v170
	v_and_b32_e32 v81, 0xffff0000, v170
	v_and_b32_e32 v97, 0xffff0000, v86
	v_fmac_f32_e32 v100, v96, v96
	v_pk_add_f32 v[80:81], v[88:89], v[80:81]
	v_lshlrev_b32_e32 v98, 16, v87
	v_fmac_f32_e32 v100, v97, v97
	v_cvt_pk_bf16_f32 v94, v80, v81
	v_lshlrev_b32_e32 v80, 16, v171
	v_and_b32_e32 v81, 0xffff0000, v171
	v_and_b32_e32 v99, 0xffff0000, v87
	v_fmac_f32_e32 v100, v98, v98
	v_pk_add_f32 v[80:81], v[90:91], v[80:81]
	v_fmac_f32_e32 v100, v99, v99
	v_cvt_pk_bf16_f32 v95, v80, v81
	v_lshlrev_b32_e32 v80, 16, v92
	v_and_b32_e32 v81, 0xffff0000, v92
	v_fmac_f32_e32 v100, v80, v80
	v_lshlrev_b32_e32 v82, 16, v93
	v_fmac_f32_e32 v100, v81, v81
	v_and_b32_e32 v83, 0xffff0000, v93
	v_fmac_f32_e32 v100, v82, v82
	v_lshlrev_b32_e32 v88, 16, v94
	v_fmac_f32_e32 v100, v83, v83
	v_and_b32_e32 v89, 0xffff0000, v94
	v_fmac_f32_e32 v100, v88, v88
	v_lshlrev_b32_e32 v90, 16, v95
	v_fmac_f32_e32 v100, v89, v89
	v_and_b32_e32 v91, 0xffff0000, v95
	v_fmac_f32_e32 v100, v90, v90
	v_fmac_f32_e32 v100, v91, v91
	ds_bpermute_b32 v80, v249, v100
	v_lshl_add_u64 v[82:83], s[10:11], 0, v[228:229]
	v_lshl_add_u64 v[82:83], v[216:217], 1, v[82:83]
	global_store_dwordx4 v[82:83], v[84:87], off
	global_store_dwordx4 v[82:83], v[92:95], off offset:256
	s_waitcnt lgkmcnt(0)
	v_add_f32_e32 v80, v100, v80
	ds_bpermute_b32 v81, v250, v80
	s_and_saveexec_b64 s[2:3], s[6:7]
	s_cbranch_execz .LBB0_1069
	s_waitcnt lgkmcnt(0)
	v_add_f32_e32 v80, v80, v81
	v_fma_f32 v80, v80, s18, 0.5
	v_trunc_f32_e32 v80, v80
	v_mul_f32_e32 v81, 0x2f800000, v80
	v_floor_f32_e32 v81, v81
	v_fmac_f32_e32 v80, 0xcf800000, v81
	v_cvt_u32_f32_e32 v80, v80
	v_cvt_u32_f32_e32 v81, v81
	global_atomic_add_x2 v[112:113], v[80:81], off offset:256
.LBB0_1069:
	s_or_b64 exec, exec, s[2:3]
	v_lshlrev_b32_e32 v80, 16, v164
	s_waitcnt lgkmcnt(0)
	v_and_b32_e32 v81, 0xffff0000, v164
	v_pk_add_f32 v[68:69], v[68:69], v[80:81]
	v_lshlrev_b32_e32 v80, 16, v165
	v_and_b32_e32 v81, 0xffff0000, v165
	v_pk_add_f32 v[70:71], v[70:71], v[80:81]
	v_cvt_pk_bf16_f32 v68, v68, v69
	v_cvt_pk_bf16_f32 v69, v70, v71
	v_lshlrev_b32_e32 v70, 16, v166
	v_and_b32_e32 v71, 0xffff0000, v166
	v_pk_add_f32 v[60:61], v[60:61], v[70:71]
	s_nop 0
	v_cvt_pk_bf16_f32 v70, v60, v61
	v_lshlrev_b32_e32 v60, 16, v167
	v_and_b32_e32 v61, 0xffff0000, v167
	v_pk_add_f32 v[60:61], v[62:63], v[60:61]
	v_lshlrev_b32_e32 v62, 16, v69
	v_cvt_pk_bf16_f32 v71, v60, v61
	v_and_b32_e32 v61, 0xffff0000, v68
	v_lshlrev_b32_e32 v60, 16, v68
	v_mul_f32_e32 v84, v61, v61
	v_fmac_f32_e32 v84, v60, v60
	v_lshlrev_b32_e32 v60, 16, v160
	v_and_b32_e32 v61, 0xffff0000, v160
	v_pk_add_f32 v[60:61], v[76:77], v[60:61]
	v_and_b32_e32 v63, 0xffff0000, v69
	v_cvt_pk_bf16_f32 v76, v60, v61
	v_lshlrev_b32_e32 v60, 16, v161
	v_and_b32_e32 v61, 0xffff0000, v161
	v_fmac_f32_e32 v84, v62, v62
	v_pk_add_f32 v[60:61], v[78:79], v[60:61]
	v_lshlrev_b32_e32 v80, 16, v70
	v_fmac_f32_e32 v84, v63, v63
	v_cvt_pk_bf16_f32 v77, v60, v61
	v_lshlrev_b32_e32 v60, 16, v162
	v_and_b32_e32 v61, 0xffff0000, v162
	v_and_b32_e32 v81, 0xffff0000, v70
	v_fmac_f32_e32 v84, v80, v80
	v_pk_add_f32 v[60:61], v[72:73], v[60:61]
	v_lshlrev_b32_e32 v82, 16, v71
	v_fmac_f32_e32 v84, v81, v81
	v_cvt_pk_bf16_f32 v78, v60, v61
	v_lshlrev_b32_e32 v60, 16, v163
	v_and_b32_e32 v61, 0xffff0000, v163
	v_and_b32_e32 v83, 0xffff0000, v71
	v_fmac_f32_e32 v84, v82, v82
	v_pk_add_f32 v[60:61], v[74:75], v[60:61]
	v_fmac_f32_e32 v84, v83, v83
	v_cvt_pk_bf16_f32 v79, v60, v61
	v_lshlrev_b32_e32 v60, 16, v76
	v_and_b32_e32 v61, 0xffff0000, v76
	v_fmac_f32_e32 v84, v60, v60
	v_lshlrev_b32_e32 v62, 16, v77
	v_fmac_f32_e32 v84, v61, v61
	v_and_b32_e32 v63, 0xffff0000, v77
	v_fmac_f32_e32 v84, v62, v62
	v_lshlrev_b32_e32 v72, 16, v78
	v_fmac_f32_e32 v84, v63, v63
	v_and_b32_e32 v73, 0xffff0000, v78
	v_fmac_f32_e32 v84, v72, v72
	v_lshlrev_b32_e32 v74, 16, v79
	v_fmac_f32_e32 v84, v73, v73
	v_and_b32_e32 v75, 0xffff0000, v79
	v_fmac_f32_e32 v84, v74, v74
	v_fmac_f32_e32 v84, v75, v75
	ds_bpermute_b32 v60, v249, v84
	v_lshl_add_u64 v[62:63], s[10:11], 0, v[226:227]
	v_lshl_add_u64 v[62:63], v[216:217], 1, v[62:63]
	global_store_dwordx4 v[62:63], v[68:71], off
	global_store_dwordx4 v[62:63], v[76:79], off offset:256
	s_waitcnt lgkmcnt(0)
	v_add_f32_e32 v60, v84, v60
	ds_bpermute_b32 v61, v250, v60
	s_and_saveexec_b64 s[2:3], s[6:7]
	s_mov_b32 s20, 0x800000
	s_cbranch_execz .LBB0_1071
	s_waitcnt lgkmcnt(0)
	v_add_f32_e32 v60, v60, v61
	v_fma_f32 v60, v60, s18, 0.5
	v_trunc_f32_e32 v60, v60
	v_mul_f32_e32 v61, 0x2f800000, v60
	v_floor_f32_e32 v61, v61
	v_fmac_f32_e32 v60, 0xcf800000, v61
	v_cvt_u32_f32_e32 v60, v60
	v_cvt_u32_f32_e32 v61, v61
	global_atomic_add_x2 v[112:113], v[60:61], off offset:384
.LBB0_1071:
	s_or_b64 exec, exec, s[2:3]
	v_lshlrev_b32_e32 v60, 16, v156
	s_waitcnt lgkmcnt(0)
	v_and_b32_e32 v61, 0xffff0000, v156
	v_pk_add_f32 v[52:53], v[52:53], v[60:61]
	v_lshlrev_b32_e32 v60, 16, v157
	v_and_b32_e32 v61, 0xffff0000, v157
	v_pk_add_f32 v[54:55], v[54:55], v[60:61]
	v_cvt_pk_bf16_f32 v52, v52, v53
	v_cvt_pk_bf16_f32 v53, v54, v55
	v_lshlrev_b32_e32 v54, 16, v158
	v_and_b32_e32 v55, 0xffff0000, v158
	v_pk_add_f32 v[48:49], v[48:49], v[54:55]
	s_nop 0
	v_cvt_pk_bf16_f32 v54, v48, v49
	v_lshlrev_b32_e32 v48, 16, v159
	v_and_b32_e32 v49, 0xffff0000, v159
	v_pk_add_f32 v[48:49], v[50:51], v[48:49]
	v_lshlrev_b32_e32 v50, 16, v53
	v_cvt_pk_bf16_f32 v55, v48, v49
	v_and_b32_e32 v49, 0xffff0000, v52
	v_lshlrev_b32_e32 v48, 16, v52
	v_mul_f32_e32 v68, v49, v49
	v_fmac_f32_e32 v68, v48, v48
	v_and_b32_e32 v51, 0xffff0000, v53
	v_fmac_f32_e32 v68, v50, v50
	v_lshlrev_b32_e32 v48, 16, v152
	v_and_b32_e32 v49, 0xffff0000, v152
	v_lshlrev_b32_e32 v60, 16, v54
	v_fmac_f32_e32 v68, v51, v51
	v_pk_add_f32 v[48:49], v[64:65], v[48:49]
	v_fmac_f32_e32 v68, v60, v60
	v_cvt_pk_bf16_f32 v60, v48, v49
	v_lshlrev_b32_e32 v48, 16, v153
	v_and_b32_e32 v49, 0xffff0000, v153
	v_and_b32_e32 v61, 0xffff0000, v54
	v_pk_add_f32 v[48:49], v[66:67], v[48:49]
	v_fmac_f32_e32 v68, v61, v61
	v_cvt_pk_bf16_f32 v61, v48, v49
	v_lshlrev_b32_e32 v48, 16, v154
	v_and_b32_e32 v49, 0xffff0000, v154
	v_lshlrev_b32_e32 v62, 16, v55
	v_pk_add_f32 v[48:49], v[56:57], v[48:49]
	v_fmac_f32_e32 v68, v62, v62
	v_cvt_pk_bf16_f32 v62, v48, v49
	v_lshlrev_b32_e32 v48, 16, v155
	v_and_b32_e32 v49, 0xffff0000, v155
	v_and_b32_e32 v63, 0xffff0000, v55
	v_pk_add_f32 v[48:49], v[58:59], v[48:49]
	v_fmac_f32_e32 v68, v63, v63
	v_cvt_pk_bf16_f32 v63, v48, v49
	v_lshlrev_b32_e32 v48, 16, v60
	v_and_b32_e32 v49, 0xffff0000, v60
	v_fmac_f32_e32 v68, v48, v48
	v_lshlrev_b32_e32 v50, 16, v61
	v_fmac_f32_e32 v68, v49, v49
	v_and_b32_e32 v51, 0xffff0000, v61
	v_fmac_f32_e32 v68, v50, v50
	v_lshlrev_b32_e32 v56, 16, v62
	v_fmac_f32_e32 v68, v51, v51
	v_and_b32_e32 v57, 0xffff0000, v62
	v_fmac_f32_e32 v68, v56, v56
	v_lshlrev_b32_e32 v58, 16, v63
	v_fmac_f32_e32 v68, v57, v57
	v_and_b32_e32 v59, 0xffff0000, v63
	v_fmac_f32_e32 v68, v58, v58
	v_fmac_f32_e32 v68, v59, v59
	ds_bpermute_b32 v48, v249, v68
	v_lshl_add_u64 v[50:51], s[10:11], 0, v[224:225]
	v_lshl_add_u64 v[50:51], v[216:217], 1, v[50:51]
	global_store_dwordx4 v[50:51], v[52:55], off
	global_store_dwordx4 v[50:51], v[60:63], off offset:256
	s_waitcnt lgkmcnt(0)
	v_add_f32_e32 v48, v68, v48
	ds_bpermute_b32 v49, v250, v48
	s_and_saveexec_b64 s[2:3], s[6:7]
	s_cbranch_execz .LBB0_1073
	s_waitcnt lgkmcnt(0)
	v_add_f32_e32 v48, v48, v49
	v_fma_f32 v48, v48, s18, 0.5
	v_trunc_f32_e32 v48, v48
	v_mul_f32_e32 v49, 0x2f800000, v48
	v_floor_f32_e32 v49, v49
	v_fmac_f32_e32 v48, 0xcf800000, v49
	v_cvt_u32_f32_e32 v48, v48
	v_cvt_u32_f32_e32 v49, v49
	global_atomic_add_x2 v[112:113], v[48:49], off offset:1024
.LBB0_1073:
	s_or_b64 exec, exec, s[2:3]
	v_lshlrev_b32_e32 v48, 16, v148
	s_waitcnt lgkmcnt(0)
	v_and_b32_e32 v49, 0xffff0000, v148
	v_pk_add_f32 v[36:37], v[36:37], v[48:49]
	v_lshlrev_b32_e32 v48, 16, v149
	v_and_b32_e32 v49, 0xffff0000, v149
	v_pk_add_f32 v[38:39], v[38:39], v[48:49]
	v_cvt_pk_bf16_f32 v36, v36, v37
	v_cvt_pk_bf16_f32 v37, v38, v39
	v_lshlrev_b32_e32 v38, 16, v150
	v_and_b32_e32 v39, 0xffff0000, v150
	v_pk_add_f32 v[32:33], v[32:33], v[38:39]
	s_nop 0
	v_cvt_pk_bf16_f32 v38, v32, v33
	v_lshlrev_b32_e32 v32, 16, v151
	v_and_b32_e32 v33, 0xffff0000, v151
	v_pk_add_f32 v[32:33], v[34:35], v[32:33]
	v_lshlrev_b32_e32 v34, 16, v37
	v_cvt_pk_bf16_f32 v39, v32, v33
	v_and_b32_e32 v33, 0xffff0000, v36
	v_lshlrev_b32_e32 v32, 16, v36
	v_mul_f32_e32 v52, v33, v33
	v_fmac_f32_e32 v52, v32, v32
	v_lshlrev_b32_e32 v32, 16, v144
	v_and_b32_e32 v33, 0xffff0000, v144
	v_pk_add_f32 v[32:33], v[44:45], v[32:33]
	v_and_b32_e32 v35, 0xffff0000, v37
	v_cvt_pk_bf16_f32 v44, v32, v33
	v_lshlrev_b32_e32 v32, 16, v145
	v_and_b32_e32 v33, 0xffff0000, v145
	v_fmac_f32_e32 v52, v34, v34
	v_pk_add_f32 v[32:33], v[46:47], v[32:33]
	v_lshlrev_b32_e32 v48, 16, v38
	v_fmac_f32_e32 v52, v35, v35
	v_cvt_pk_bf16_f32 v45, v32, v33
	v_lshlrev_b32_e32 v32, 16, v146
	v_and_b32_e32 v33, 0xffff0000, v146
	v_and_b32_e32 v49, 0xffff0000, v38
	v_fmac_f32_e32 v52, v48, v48
	v_pk_add_f32 v[32:33], v[40:41], v[32:33]
	v_lshlrev_b32_e32 v50, 16, v39
	v_fmac_f32_e32 v52, v49, v49
	v_cvt_pk_bf16_f32 v46, v32, v33
	v_lshlrev_b32_e32 v32, 16, v147
	v_and_b32_e32 v33, 0xffff0000, v147
	v_and_b32_e32 v51, 0xffff0000, v39
	v_fmac_f32_e32 v52, v50, v50
	v_pk_add_f32 v[32:33], v[42:43], v[32:33]
	v_fmac_f32_e32 v52, v51, v51
	v_cvt_pk_bf16_f32 v47, v32, v33
	v_lshlrev_b32_e32 v32, 16, v44
	v_and_b32_e32 v33, 0xffff0000, v44
	v_fmac_f32_e32 v52, v32, v32
	v_lshlrev_b32_e32 v34, 16, v45
	v_fmac_f32_e32 v52, v33, v33
	v_and_b32_e32 v35, 0xffff0000, v45
	v_fmac_f32_e32 v52, v34, v34
	v_lshlrev_b32_e32 v40, 16, v46
	v_fmac_f32_e32 v52, v35, v35
	v_and_b32_e32 v41, 0xffff0000, v46
	v_fmac_f32_e32 v52, v40, v40
	v_lshlrev_b32_e32 v42, 16, v47
	v_fmac_f32_e32 v52, v41, v41
	v_and_b32_e32 v43, 0xffff0000, v47
	v_fmac_f32_e32 v52, v42, v42
	v_fmac_f32_e32 v52, v43, v43
	ds_bpermute_b32 v32, v249, v52
	v_lshl_add_u64 v[34:35], s[10:11], 0, v[222:223]
	v_lshl_add_u64 v[34:35], v[216:217], 1, v[34:35]
	global_store_dwordx4 v[34:35], v[36:39], off
	global_store_dwordx4 v[34:35], v[44:47], off offset:256
	s_waitcnt lgkmcnt(0)
	v_add_f32_e32 v32, v52, v32
	ds_bpermute_b32 v33, v250, v32
	s_and_saveexec_b64 s[2:3], s[6:7]
	s_cbranch_execz .LBB0_1075
	s_waitcnt lgkmcnt(0)
	v_add_f32_e32 v32, v32, v33
	v_fma_f32 v32, v32, s18, 0.5
	v_trunc_f32_e32 v32, v32
	v_mul_f32_e32 v33, 0x2f800000, v32
	v_floor_f32_e32 v33, v33
	v_fmac_f32_e32 v32, 0xcf800000, v33
	v_cvt_u32_f32_e32 v32, v32
	v_cvt_u32_f32_e32 v33, v33
	global_atomic_add_x2 v[112:113], v[32:33], off offset:1152
.LBB0_1075:
	s_or_b64 exec, exec, s[2:3]
	v_lshlrev_b32_e32 v32, 16, v140
	s_waitcnt lgkmcnt(0)
	v_and_b32_e32 v33, 0xffff0000, v140
	v_pk_add_f32 v[20:21], v[20:21], v[32:33]
	v_lshlrev_b32_e32 v32, 16, v141
	v_and_b32_e32 v33, 0xffff0000, v141
	v_pk_add_f32 v[22:23], v[22:23], v[32:33]
	v_cvt_pk_bf16_f32 v20, v20, v21
	v_cvt_pk_bf16_f32 v21, v22, v23
	v_lshlrev_b32_e32 v22, 16, v142
	v_and_b32_e32 v23, 0xffff0000, v142
	v_pk_add_f32 v[16:17], v[16:17], v[22:23]
	s_nop 0
	v_cvt_pk_bf16_f32 v22, v16, v17
	v_lshlrev_b32_e32 v16, 16, v143
	v_and_b32_e32 v17, 0xffff0000, v143
	v_pk_add_f32 v[16:17], v[18:19], v[16:17]
	v_lshlrev_b32_e32 v18, 16, v21
	v_cvt_pk_bf16_f32 v23, v16, v17
	v_and_b32_e32 v17, 0xffff0000, v20
	v_lshlrev_b32_e32 v16, 16, v20
	v_mul_f32_e32 v36, v17, v17
	v_fmac_f32_e32 v36, v16, v16
	v_lshlrev_b32_e32 v16, 16, v136
	v_and_b32_e32 v17, 0xffff0000, v136
	v_pk_add_f32 v[16:17], v[28:29], v[16:17]
	v_and_b32_e32 v19, 0xffff0000, v21
	v_cvt_pk_bf16_f32 v28, v16, v17
	v_lshlrev_b32_e32 v16, 16, v137
	v_and_b32_e32 v17, 0xffff0000, v137
	v_fmac_f32_e32 v36, v18, v18
	v_pk_add_f32 v[16:17], v[30:31], v[16:17]
	v_lshlrev_b32_e32 v32, 16, v22
	v_fmac_f32_e32 v36, v19, v19
	v_cvt_pk_bf16_f32 v29, v16, v17
	v_lshlrev_b32_e32 v16, 16, v138
	v_and_b32_e32 v17, 0xffff0000, v138
	v_and_b32_e32 v33, 0xffff0000, v22
	v_fmac_f32_e32 v36, v32, v32
	v_pk_add_f32 v[16:17], v[24:25], v[16:17]
	v_lshlrev_b32_e32 v34, 16, v23
	v_fmac_f32_e32 v36, v33, v33
	v_cvt_pk_bf16_f32 v30, v16, v17
	v_lshlrev_b32_e32 v16, 16, v139
	v_and_b32_e32 v17, 0xffff0000, v139
	v_and_b32_e32 v35, 0xffff0000, v23
	v_fmac_f32_e32 v36, v34, v34
	v_pk_add_f32 v[16:17], v[26:27], v[16:17]
	v_fmac_f32_e32 v36, v35, v35
	v_cvt_pk_bf16_f32 v31, v16, v17
	v_lshlrev_b32_e32 v16, 16, v28
	v_and_b32_e32 v17, 0xffff0000, v28
	v_fmac_f32_e32 v36, v16, v16
	v_lshlrev_b32_e32 v18, 16, v29
	v_fmac_f32_e32 v36, v17, v17
	v_and_b32_e32 v19, 0xffff0000, v29
	v_fmac_f32_e32 v36, v18, v18
	v_lshlrev_b32_e32 v24, 16, v30
	v_fmac_f32_e32 v36, v19, v19
	v_and_b32_e32 v25, 0xffff0000, v30
	v_fmac_f32_e32 v36, v24, v24
	v_lshlrev_b32_e32 v26, 16, v31
	v_fmac_f32_e32 v36, v25, v25
	v_and_b32_e32 v27, 0xffff0000, v31
	v_fmac_f32_e32 v36, v26, v26
	v_fmac_f32_e32 v36, v27, v27
	ds_bpermute_b32 v16, v249, v36
	v_lshl_add_u64 v[18:19], s[10:11], 0, v[220:221]
	v_lshl_add_u64 v[18:19], v[216:217], 1, v[18:19]
	global_store_dwordx4 v[18:19], v[20:23], off
	global_store_dwordx4 v[18:19], v[28:31], off offset:256
	s_waitcnt lgkmcnt(0)
	v_add_f32_e32 v16, v36, v16
	ds_bpermute_b32 v17, v250, v16
	s_and_saveexec_b64 s[2:3], s[6:7]
	s_cbranch_execz .LBB0_1077
	s_waitcnt lgkmcnt(0)
	v_add_f32_e32 v16, v16, v17
	v_fma_f32 v16, v16, s18, 0.5
	v_trunc_f32_e32 v16, v16
	v_mul_f32_e32 v17, 0x2f800000, v16
	v_floor_f32_e32 v17, v17
	v_fmac_f32_e32 v16, 0xcf800000, v17
	v_cvt_u32_f32_e32 v16, v16
	v_cvt_u32_f32_e32 v17, v17
	global_atomic_add_x2 v[112:113], v[16:17], off offset:1280
.LBB0_1077:
	s_or_b64 exec, exec, s[2:3]
	v_lshlrev_b32_e32 v18, 16, v132
	v_and_b32_e32 v19, 0xffff0000, v132
	v_pk_add_f32 v[4:5], v[4:5], v[18:19]
	v_lshlrev_b32_e32 v18, 16, v133
	v_and_b32_e32 v19, 0xffff0000, v133
	v_pk_add_f32 v[6:7], v[6:7], v[18:19]
	v_cvt_pk_bf16_f32 v4, v4, v5
	v_cvt_pk_bf16_f32 v5, v6, v7
	v_lshlrev_b32_e32 v6, 16, v134
	v_and_b32_e32 v7, 0xffff0000, v134
	v_pk_add_f32 v[0:1], v[0:1], v[6:7]
	s_waitcnt lgkmcnt(0)
	v_lshl_add_u64 v[16:17], s[10:11], 0, v[218:219]
	v_cvt_pk_bf16_f32 v6, v0, v1
	v_lshlrev_b32_e32 v0, 16, v135
	v_and_b32_e32 v1, 0xffff0000, v135
	v_pk_add_f32 v[0:1], v[2:3], v[0:1]
	v_lshlrev_b32_e32 v2, 16, v5
	v_cvt_pk_bf16_f32 v7, v0, v1
	v_and_b32_e32 v1, 0xffff0000, v4
	v_lshlrev_b32_e32 v0, 16, v4
	v_mul_f32_e32 v18, v1, v1
	v_fmac_f32_e32 v18, v0, v0
	v_lshl_add_u64 v[16:17], v[216:217], 1, v[16:17]
	v_and_b32_e32 v3, 0xffff0000, v5
	v_fmac_f32_e32 v18, v2, v2
	global_store_dwordx4 v[16:17], v[4:7], off
	v_fmac_f32_e32 v18, v3, v3
	v_lshlrev_b32_e32 v0, 16, v128
	v_lshlrev_b32_e32 v4, 16, v6
	v_and_b32_e32 v1, 0xffff0000, v128
	v_lshlrev_b32_e32 v2, 16, v129
	v_and_b32_e32 v3, 0xffff0000, v129
	v_and_b32_e32 v5, 0xffff0000, v6
	v_fmac_f32_e32 v18, v4, v4
	v_pk_add_f32 v[0:1], v[12:13], v[0:1]
	v_pk_add_f32 v[2:3], v[14:15], v[2:3]
	v_lshlrev_b32_e32 v6, 16, v7
	v_fmac_f32_e32 v18, v5, v5
	v_cvt_pk_bf16_f32 v0, v0, v1
	v_cvt_pk_bf16_f32 v1, v2, v3
	v_lshlrev_b32_e32 v2, 16, v130
	v_and_b32_e32 v3, 0xffff0000, v130
	v_lshlrev_b32_e32 v4, 16, v131
	v_and_b32_e32 v5, 0xffff0000, v131
	v_and_b32_e32 v7, 0xffff0000, v7
	v_fmac_f32_e32 v18, v6, v6
	v_pk_add_f32 v[2:3], v[8:9], v[2:3]
	v_pk_add_f32 v[4:5], v[10:11], v[4:5]
	v_fmac_f32_e32 v18, v7, v7
	v_cvt_pk_bf16_f32 v2, v2, v3
	v_cvt_pk_bf16_f32 v3, v4, v5
	v_lshlrev_b32_e32 v4, 16, v0
	global_store_dwordx4 v[16:17], v[0:3], off offset:256
	v_fmac_f32_e32 v18, v4, v4
	v_lshlrev_b32_e32 v5, 16, v1
	v_and_b32_e32 v0, 0xffff0000, v0
	v_fmac_f32_e32 v18, v0, v0
	v_and_b32_e32 v1, 0xffff0000, v1
	v_fmac_f32_e32 v18, v5, v5
	v_lshlrev_b32_e32 v6, 16, v2
	v_fmac_f32_e32 v18, v1, v1
	v_and_b32_e32 v2, 0xffff0000, v2
	v_fmac_f32_e32 v18, v6, v6
	v_lshlrev_b32_e32 v7, 16, v3
	v_fmac_f32_e32 v18, v2, v2
	v_and_b32_e32 v3, 0xffff0000, v3
	v_fmac_f32_e32 v18, v7, v7
	v_fmac_f32_e32 v18, v3, v3
	ds_bpermute_b32 v0, v249, v18
	s_waitcnt lgkmcnt(0)
	v_add_f32_e32 v0, v18, v0
	ds_bpermute_b32 v1, v250, v0
	s_and_saveexec_b64 s[2:3], s[6:7]
	s_cbranch_execz .LBB0_1079
	s_waitcnt lgkmcnt(0)
	v_add_f32_e32 v0, v0, v1
	v_fma_f32 v0, v0, s18, 0.5
	v_trunc_f32_e32 v0, v0
	v_mul_f32_e32 v1, 0x2f800000, v0
	v_floor_f32_e32 v1, v1
	v_fmac_f32_e32 v0, 0xcf800000, v1
	v_cvt_u32_f32_e32 v0, v0
	v_cvt_u32_f32_e32 v1, v1
	global_atomic_add_x2 v[112:113], v[0:1], off offset:1408

.LBB0_1088:
	s_and_b32 s10, s14, 0xffffffe0
	s_and_b32 s2, s13, 0x70
	v_or_b32_e32 v8, s10, v12
	s_movk_i32 s11, 0x1600
	v_or_b32_e32 v5, s2, v12
	v_mad_i64_i32 v[10:11], s[2:3], v8, s11, v[2:3]
	global_load_dwordx4 v[14:17], v[10:11], off
	v_mul_u32_u24_e32 v6, 0xb00, v5
	v_or_b32_e32 v8, 16, v8
	v_lshlrev_b32_e32 v194, 1, v6
	v_mad_i64_i32 v[8:9], s[2:3], v8, s11, v[2:3]
	v_lshl_add_u64 v[6:7], v[0:1], 0, v[194:195]
	global_load_dwordx4 v[18:21], v[8:9], off
	global_load_dwordx4 v[22:25], v[6:7], off
	global_load_dwordx4 v[26:29], v[10:11], off offset:64
	global_load_dwordx4 v[30:33], v[8:9], off offset:64
	s_andn2_b64 vcc, exec, s[8:9]
	s_waitcnt vmcnt(0) lgkmcnt(0)
	v_mfma_f32_16x16x32_bf16 v[18:21], v[18:21], v[22:25], 0
	v_mfma_f32_16x16x32_bf16 v[14:17], v[14:17], v[22:25], 0
	global_load_dwordx4 v[22:25], v[6:7], off offset:64
	s_waitcnt vmcnt(0) lgkmcnt(0)
	v_mfma_f32_16x16x32_bf16 v[14:17], v[26:29], v[22:25], v[14:17]
	global_load_dwordx4 v[26:29], v[10:11], off offset:128
	global_load_dwordx4 v[34:37], v[8:9], off offset:128
	v_mfma_f32_16x16x32_bf16 v[18:21], v[30:33], v[22:25], v[18:21]
	global_load_dwordx4 v[22:25], v[6:7], off offset:128
	s_waitcnt vmcnt(0) lgkmcnt(0)
	v_mfma_f32_16x16x32_bf16 v[14:17], v[26:29], v[22:25], v[14:17]
	global_load_dwordx4 v[26:29], v[10:11], off offset:192
	global_load_dwordx4 v[30:33], v[8:9], off offset:192
	v_mfma_f32_16x16x32_bf16 v[18:21], v[34:37], v[22:25], v[18:21]
	global_load_dwordx4 v[22:25], v[6:7], off offset:192
	s_waitcnt vmcnt(0) lgkmcnt(0)
	v_mfma_f32_16x16x32_bf16 v[14:17], v[26:29], v[22:25], v[14:17]
	global_load_dwordx4 v[26:29], v[10:11], off offset:256
	global_load_dwordx4 v[34:37], v[8:9], off offset:256
	v_mfma_f32_16x16x32_bf16 v[18:21], v[30:33], v[22:25], v[18:21]
	global_load_dwordx4 v[22:25], v[6:7], off offset:256
	s_waitcnt vmcnt(0) lgkmcnt(0)
	v_mfma_f32_16x16x32_bf16 v[14:17], v[26:29], v[22:25], v[14:17]
	global_load_dwordx4 v[26:29], v[10:11], off offset:320
	global_load_dwordx4 v[30:33], v[8:9], off offset:320
	v_mfma_f32_16x16x32_bf16 v[18:21], v[34:37], v[22:25], v[18:21]
	global_load_dwordx4 v[22:25], v[6:7], off offset:320
	s_waitcnt vmcnt(0) lgkmcnt(0)
	v_mfma_f32_16x16x32_bf16 v[14:17], v[26:29], v[22:25], v[14:17]
	global_load_dwordx4 v[26:29], v[10:11], off offset:384
	global_load_dwordx4 v[34:37], v[8:9], off offset:384
	v_mfma_f32_16x16x32_bf16 v[18:21], v[30:33], v[22:25], v[18:21]
	global_load_dwordx4 v[22:25], v[6:7], off offset:384
	s_waitcnt vmcnt(0) lgkmcnt(0)
	v_mfma_f32_16x16x32_bf16 v[14:17], v[26:29], v[22:25], v[14:17]
	global_load_dwordx4 v[26:29], v[10:11], off offset:448
	global_load_dwordx4 v[30:33], v[8:9], off offset:448
	v_mfma_f32_16x16x32_bf16 v[18:21], v[34:37], v[22:25], v[18:21]
	global_load_dwordx4 v[22:25], v[6:7], off offset:448
	s_waitcnt vmcnt(0) lgkmcnt(0)
	v_mfma_f32_16x16x32_bf16 v[14:17], v[26:29], v[22:25], v[14:17]
	global_load_dwordx4 v[26:29], v[10:11], off offset:512
	global_load_dwordx4 v[34:37], v[8:9], off offset:512
	v_mfma_f32_16x16x32_bf16 v[18:21], v[30:33], v[22:25], v[18:21]
	global_load_dwordx4 v[22:25], v[6:7], off offset:512
	s_waitcnt vmcnt(0) lgkmcnt(0)
	v_mfma_f32_16x16x32_bf16 v[14:17], v[26:29], v[22:25], v[14:17]
	global_load_dwordx4 v[26:29], v[10:11], off offset:576
	global_load_dwordx4 v[30:33], v[8:9], off offset:576
	v_mfma_f32_16x16x32_bf16 v[18:21], v[34:37], v[22:25], v[18:21]
	global_load_dwordx4 v[22:25], v[6:7], off offset:576
	s_waitcnt vmcnt(0) lgkmcnt(0)
	v_mfma_f32_16x16x32_bf16 v[14:17], v[26:29], v[22:25], v[14:17]
	global_load_dwordx4 v[26:29], v[10:11], off offset:640
	s_nop 0
	global_load_dwordx4 v[8:11], v[8:9], off offset:640
	v_mfma_f32_16x16x32_bf16 v[18:21], v[30:33], v[22:25], v[18:21]
	global_load_dwordx4 v[22:25], v[6:7], off offset:640
	v_add_u32_e32 v30, s12, v13
	s_waitcnt vmcnt(0) lgkmcnt(0)
	v_mfma_f32_16x16x32_bf16 v[14:17], v[26:29], v[22:25], v[14:17]
	v_mfma_f32_16x16x32_bf16 v[6:9], v[8:11], v[22:25], v[18:21]
	s_nop 6
	ds_write_b128 v30, v[14:17]
	ds_write_b128 v30, v[6:9] offset:16
	s_waitcnt lgkmcnt(0)
	s_barrier
	s_cbranch_vccnz .LBB0_1087
	v_add_u32_e32 v24, 0, v13
	ds_read_b128 v[6:9], v24
	ds_read_b128 v[14:17], v24 offset:16
	s_ashr_i32 s11, s10, 31
	s_waitcnt lgkmcnt(1)
	v_pk_add_f32 v[10:11], v[8:9], 0 op_sel_hi:[1,0]
	v_pk_add_f32 v[18:19], v[6:7], 0 op_sel_hi:[1,0]
	ds_read_b128 v[6:9], v24 offset:2048
	s_waitcnt lgkmcnt(1)
	v_pk_add_f32 v[16:17], v[16:17], 0 op_sel_hi:[1,0]
	v_pk_add_f32 v[14:15], v[14:15], 0 op_sel_hi:[1,0]
	s_waitcnt lgkmcnt(0)
	v_pk_add_f32 v[10:11], v[10:11], v[8:9]
	v_pk_add_f32 v[18:19], v[18:19], v[6:7]
	ds_read_b128 v[6:9], v24 offset:2064
	s_waitcnt lgkmcnt(0)
	v_pk_add_f32 v[16:17], v[16:17], v[8:9]
	v_pk_add_f32 v[14:15], v[14:15], v[6:7]
	ds_read_b128 v[6:9], v24 offset:4096
	s_waitcnt lgkmcnt(0)
	v_pk_add_f32 v[10:11], v[10:11], v[8:9]
	v_pk_add_f32 v[18:19], v[18:19], v[6:7]
	ds_read_b128 v[6:9], v24 offset:4112
	s_waitcnt lgkmcnt(0)
	v_pk_add_f32 v[16:17], v[16:17], v[8:9]
	v_pk_add_f32 v[14:15], v[14:15], v[6:7]
	ds_read_b128 v[6:9], v24 offset:6144
	s_waitcnt lgkmcnt(0)
	v_pk_add_f32 v[10:11], v[10:11], v[8:9]
	v_pk_add_f32 v[18:19], v[18:19], v[6:7]
	ds_read_b128 v[6:9], v24 offset:6160
	s_waitcnt lgkmcnt(0)
	v_pk_add_f32 v[16:17], v[16:17], v[8:9]
	v_pk_add_f32 v[14:15], v[14:15], v[6:7]
	ds_read_b128 v[6:9], v24 offset:8192
	s_waitcnt lgkmcnt(0)
	v_pk_add_f32 v[10:11], v[10:11], v[8:9]
	v_pk_add_f32 v[18:19], v[18:19], v[6:7]
	ds_read_b128 v[6:9], v24 offset:8208
	s_waitcnt lgkmcnt(0)
	v_pk_add_f32 v[16:17], v[16:17], v[8:9]
	v_pk_add_f32 v[14:15], v[14:15], v[6:7]
	ds_read_b128 v[6:9], v24 offset:10240
	s_waitcnt lgkmcnt(0)
	v_pk_add_f32 v[10:11], v[10:11], v[8:9]
	v_pk_add_f32 v[18:19], v[18:19], v[6:7]
	ds_read_b128 v[6:9], v24 offset:10256
	s_waitcnt lgkmcnt(0)
	v_pk_add_f32 v[16:17], v[16:17], v[8:9]
	v_pk_add_f32 v[14:15], v[14:15], v[6:7]
	ds_read_b128 v[6:9], v24 offset:12288
	s_waitcnt lgkmcnt(0)
	v_pk_add_f32 v[10:11], v[10:11], v[8:9]
	v_pk_add_f32 v[18:19], v[18:19], v[6:7]
	ds_read_b128 v[6:9], v24 offset:12304
	s_waitcnt lgkmcnt(0)
	v_pk_add_f32 v[20:21], v[16:17], v[8:9]
	v_pk_add_f32 v[22:23], v[14:15], v[6:7]
	ds_read_b128 v[6:9], v24 offset:14336
	ds_read_b128 v[14:17], v24 offset:14352
	s_waitcnt lgkmcnt(1)
	v_pk_add_f32 v[8:9], v[10:11], v[8:9]
	s_waitcnt lgkmcnt(0)
	v_pk_add_f32 v[10:11], v[22:23], v[14:15]
	v_or_b32_e32 v14, 0x4000, v5
	v_lshlrev_b32_e32 v194, 11, v14
	v_pk_add_f32 v[18:19], v[18:19], v[6:7]
	v_pk_add_f32 v[6:7], v[20:21], v[16:17]
	v_lshl_add_u64 v[16:17], s[0:1], 0, v[194:195]
	v_lshl_add_u64 v[16:17], s[10:11], 1, v[16:17]
	v_mov_b32_e32 v5, v195
	v_lshl_add_u64 v[16:17], v[16:17], 0, v[4:5]
	global_load_dwordx2 v[20:21], v[16:17], off
	global_load_dwordx2 v[22:23], v[16:17], off offset:32
	s_waitcnt vmcnt(0) lgkmcnt(0)
	v_lshlrev_b32_e32 v24, 16, v20
	v_and_b32_e32 v25, 0xffff0000, v20
	v_lshlrev_b32_e32 v20, 16, v21
	v_and_b32_e32 v21, 0xffff0000, v21
	v_pk_add_f32 v[18:19], v[18:19], v[24:25]
	v_pk_add_f32 v[8:9], v[8:9], v[20:21]
	v_cvt_pk_bf16_f32 v18, v18, v19
	v_cvt_pk_bf16_f32 v19, v8, v9
	v_lshlrev_b32_e32 v8, 16, v22
	v_and_b32_e32 v9, 0xffff0000, v22
	v_pk_add_f32 v[8:9], v[10:11], v[8:9]
	v_lshlrev_b32_e32 v10, 16, v23
	v_and_b32_e32 v11, 0xffff0000, v23
	v_pk_add_f32 v[6:7], v[6:7], v[10:11]
	v_cvt_pk_bf16_f32 v8, v8, v9
	v_cvt_pk_bf16_f32 v9, v6, v7
	v_and_b32_e32 v6, 0xffff0000, v18
	v_lshlrev_b32_e32 v5, 16, v18
	v_and_b32_e32 v10, 0xffff0000, v19
	v_mul_f32_e32 v6, v6, v6
	v_lshlrev_b32_e32 v7, 16, v19
	v_fmac_f32_e32 v6, v5, v5
	v_mul_f32_e32 v5, v10, v10
	global_store_dwordx2 v[16:17], v[18:19], off
	global_store_dwordx2 v[16:17], v[8:9], off offset:32
	v_lshlrev_b32_e32 v11, 16, v8
	v_and_b32_e32 v8, 0xffff0000, v8
	v_fmac_f32_e32 v5, v7, v7
	v_add_f32_e32 v5, v6, v5
	v_mul_f32_e32 v6, v8, v8
	v_lshlrev_b32_e32 v15, 16, v9
	v_and_b32_e32 v9, 0xffff0000, v9
	v_fmac_f32_e32 v6, v11, v11
	v_add_f32_e32 v5, v5, v6
	v_mul_f32_e32 v6, v9, v9
	v_fmac_f32_e32 v6, v15, v15
	v_and_b32_e32 v7, 64, v243
	v_add_f32_e32 v5, v6, v5
	v_xor_b32_e32 v6, 16, v243
	v_add_u32_e32 v7, 64, v7
	v_cmp_lt_i32_e32 vcc, v6, v7
	s_nop 1
	v_cndmask_b32_e32 v6, v243, v6, vcc
	v_lshlrev_b32_e32 v6, 2, v6
	ds_bpermute_b32 v6, v6, v5
	s_waitcnt lgkmcnt(0)
	v_add_f32_e32 v5, v5, v6
	v_xor_b32_e32 v6, 32, v243
	v_cmp_lt_i32_e32 vcc, v6, v7
	s_nop 1
	v_cndmask_b32_e32 v6, v243, v6, vcc
	v_lshlrev_b32_e32 v6, 2, v6
	ds_bpermute_b32 v6, v6, v5
	s_and_saveexec_b64 s[2:3], s[4:5]
	s_cbranch_execz .LBB0_1086
	s_waitcnt lgkmcnt(0)
	v_add_f32_e32 v5, v5, v6
	s_mov_b32 s10, 0x4b800000
	v_fma_f32 v5, v5, s10, 0.5
	v_trunc_f32_e32 v5, v5
	v_mul_f32_e32 v6, 0x2f800000, v5
	v_floor_f32_e32 v7, v6
	v_fmac_f32_e32 v5, 0xcf800000, v7
	v_cvt_u32_f32_e32 v6, v5
	v_cvt_u32_f32_e32 v7, v7
	v_lshlrev_b32_e32 v194, 3, v14
	v_lshl_add_u64 v[8:9], s[6:7], 0, v[194:195]
	global_atomic_add_x2 v[8:9], v[6:7], off
	s_branch .LBB0_1086

.LBB0_1154:
	s_add_i32 s14, s80, s0
	s_cmpk_lt_i32 s14, 0x4080
	s_cselect_b32 s2, s14, s0
	s_ashr_i32 s3, s2, 31
	s_lshl_b64 s[4:5], s[2:3], 3
	s_add_u32 s7, s78, s4
	s_addc_u32 s11, s79, s5
	s_lshl_b64 s[16:17], s[2:3], 11
	s_add_i32 s10, s73, s0
	s_cmpk_lt_i32 s10, 0x4080
	s_cselect_b64 s[12:13], -1, 0
	s_and_b64 s[2:3], s[12:13], exec
	s_cselect_b32 s2, s10, s0
	s_ashr_i32 s3, s2, 31
	s_lshl_b64 s[4:5], s[2:3], 3
	s_add_u32 s15, s78, s4
	v_readlane_b32 s1, v252, 1
	s_addc_u32 s30, s79, s5
	s_lshl_b64 s[18:19], s[2:3], 11
	s_add_i32 s6, s1, s0
	s_cmpk_lt_i32 s6, 0x4080
	s_cselect_b64 s[8:9], -1, 0
	s_and_b64 s[2:3], s[8:9], exec
	s_cselect_b32 s2, s6, s0
	s_ashr_i32 s3, s2, 31
	s_lshl_b64 s[4:5], s[2:3], 3
	s_add_u32 s31, s78, s4
	s_addc_u32 s33, s79, s5
	s_lshl_b64 s[20:21], s[2:3], 11
	s_add_i32 s2, s76, s0
	s_cmpk_lt_i32 s2, 0x4080
	s_cselect_b64 s[4:5], -1, 0
	s_and_b64 s[22:23], s[4:5], exec
	s_cselect_b32 s22, s2, s0
	s_ashr_i32 s23, s22, 31
	s_lshl_b64 s[26:27], s[22:23], 3
	s_add_u32 s3, s78, s26
	s_addc_u32 s34, s79, s27
	s_ashr_i32 s1, s0, 31
	s_lshl_b64 s[22:23], s[22:23], 11
	s_lshl_b64 s[26:27], s[0:1], 11
	s_lshl_b64 s[28:29], s[0:1], 3
	s_add_u32 s28, s78, s28
	v_lshl_add_u64 v[20:21], v[16:17], 0, s[26:27]
	s_addc_u32 s29, s79, s29
	global_load_dwordx2 v[70:71], v[20:21], off offset:1536
	global_load_dwordx2 v[72:73], v[20:21], off offset:1024
	global_load_dwordx2 v[62:63], v[20:21], off offset:512
	global_load_dwordx2 v[64:65], v[20:21], off
	v_mov_b32_e32 v20, s28
	v_mov_b32_e32 v21, s29
	v_add_co_u32_e32 v20, vcc, s24, v20
	v_lshl_add_u64 v[22:23], v[16:17], 0, s[16:17]
	s_nop 0
	v_addc_co_u32_e32 v21, vcc, 0, v21, vcc
	global_load_dwordx2 v[66:67], v[20:21], off offset:2048
	v_mov_b32_e32 v20, s7
	v_mov_b32_e32 v21, s11
	v_add_co_u32_e32 v20, vcc, s24, v20
	v_lshl_add_u64 v[24:25], v[16:17], 0, s[18:19]
	s_nop 0
	v_addc_co_u32_e32 v21, vcc, 0, v21, vcc
	global_load_dwordx2 v[58:59], v[20:21], off offset:2048
	global_load_dwordx2 v[56:57], v[22:23], off
	global_load_dwordx2 v[54:55], v[22:23], off offset:512
	global_load_dwordx2 v[52:53], v[22:23], off offset:1024
	v_mov_b32_e32 v20, s15
	v_mov_b32_e32 v21, s30
	v_add_co_u32_e32 v20, vcc, s24, v20
	v_lshl_add_u64 v[68:69], v[16:17], 0, s[20:21]
	s_nop 0
	v_addc_co_u32_e32 v21, vcc, 0, v21, vcc
	global_load_dwordx2 v[50:51], v[22:23], off offset:1536
	global_load_dwordx2 v[48:49], v[20:21], off offset:2048
	global_load_dwordx2 v[46:47], v[24:25], off
	global_load_dwordx2 v[44:45], v[24:25], off offset:512
	v_mov_b32_e32 v20, s31
	v_mov_b32_e32 v21, s33
	v_add_co_u32_e32 v20, vcc, s24, v20
	v_lshl_add_u64 v[76:77], v[16:17], 0, s[22:23]
	s_nop 0
	v_addc_co_u32_e32 v21, vcc, 0, v21, vcc
	global_load_dwordx2 v[42:43], v[24:25], off offset:1024
	global_load_dwordx2 v[40:41], v[24:25], off offset:1536
	global_load_dwordx2 v[38:39], v[20:21], off offset:2048
	global_load_dwordx2 v[36:37], v[68:69], off
	v_mov_b32_e32 v20, s3
	v_mov_b32_e32 v21, s34
	v_add_co_u32_e32 v74, vcc, s24, v20
	s_lshl_b64 s[16:17], s[0:1], 12
	s_nop 0
	v_addc_co_u32_e32 v75, vcc, 0, v21, vcc
	global_load_dwordx2 v[26:27], v[76:77], off
	global_load_dwordx2 v[24:25], v[76:77], off offset:512
	global_load_dwordx2 v[22:23], v[76:77], off offset:1024
	global_load_dwordx2 v[20:21], v[76:77], off offset:1536
	global_load_dwordx2 v[34:35], v[68:69], off offset:512
	global_load_dwordx2 v[32:33], v[68:69], off offset:1024
	global_load_dwordx2 v[30:31], v[68:69], off offset:1536
	global_load_dwordx2 v[28:29], v[74:75], off offset:2048
	v_lshl_add_u64 v[74:75], v[18:19], 0, s[16:17]
	s_cmpk_gt_i32 s14, 0x407f
	s_waitcnt vmcnt(0) lgkmcnt(0)
	v_lshlrev_b32_e32 v68, 16, v64
	v_and_b32_e32 v69, 0xffff0000, v64
	v_lshlrev_b32_e32 v64, 16, v65
	v_and_b32_e32 v65, 0xffff0000, v65
	v_ffbh_u32_e32 v61, v67
	v_min_u32_e32 v61, 32, v61
	v_lshlrev_b64 v[66:67], v61, v[66:67]
	v_min_u32_e32 v66, 1, v66
	v_or_b32_e32 v66, v67, v66
	v_cvt_f32_u32_e32 v67, v66
	v_sub_u32_e32 v61, 32, v61
	v_lshlrev_b32_e32 v66, 16, v62
	v_ldexp_f32 v61, v67, v61
	v_fmamk_f32 v61, v61, 0x2e800000, v60
	v_mul_f32_e32 v67, 0x4b800000, v61
	v_cmp_gt_f32_e32 vcc, s25, v61
	s_nop 1
	v_cndmask_b32_e32 v61, v61, v67, vcc
	v_rsq_f32_e32 v61, v61
	v_and_b32_e32 v67, 0xffff0000, v62
	v_lshlrev_b32_e32 v62, 16, v63
	v_and_b32_e32 v63, 0xffff0000, v63
	v_mul_f32_e32 v76, 0x45800000, v61
	v_cndmask_b32_e32 v76, v61, v76, vcc
	v_pk_mul_f32 v[68:69], v[76:77], v[68:69] op_sel_hi:[0,1]
	v_pk_mul_f32 v[64:65], v[76:77], v[64:65] op_sel_hi:[0,1]
	v_pk_mul_f32 v[66:67], v[76:77], v[66:67] op_sel_hi:[0,1]
	v_pk_mul_f32 v[78:79], v[76:77], v[62:63] op_sel_hi:[0,1]
	v_pk_mul_f32 v[62:63], v[12:13], v[68:69]
	v_pk_mul_f32 v[64:65], v[14:15], v[64:65]
	v_pk_mul_f32 v[66:67], v[8:9], v[66:67]
	v_pk_mul_f32 v[68:69], v[10:11], v[78:79]
	global_store_dwordx4 v[74:75], v[62:65], off
	global_store_dwordx4 v[74:75], v[66:69], off offset:1024
	s_nop 0
	v_lshlrev_b32_e32 v62, 16, v72
	v_and_b32_e32 v63, 0xffff0000, v72
	v_lshlrev_b32_e32 v64, 16, v73
	v_and_b32_e32 v65, 0xffff0000, v73
	v_pk_mul_f32 v[62:63], v[76:77], v[62:63] op_sel_hi:[0,1]
	v_pk_mul_f32 v[64:65], v[76:77], v[64:65] op_sel_hi:[0,1]
	v_pk_mul_f32 v[62:63], v[4:5], v[62:63]
	v_pk_mul_f32 v[64:65], v[6:7], v[64:65]
	global_store_dwordx4 v[74:75], v[62:65], off offset:2048
	s_nop 1
	v_lshlrev_b32_e32 v62, 16, v70
	v_and_b32_e32 v63, 0xffff0000, v70
	v_lshlrev_b32_e32 v64, 16, v71
	v_and_b32_e32 v65, 0xffff0000, v71
	v_pk_mul_f32 v[62:63], v[76:77], v[62:63] op_sel_hi:[0,1]
	v_pk_mul_f32 v[64:65], v[76:77], v[64:65] op_sel_hi:[0,1]
	v_pk_mul_f32 v[62:63], v[0:1], v[62:63]
	v_pk_mul_f32 v[64:65], v[2:3], v[64:65]
	global_store_dwordx4 v[74:75], v[62:65], off offset:3072
	s_cbranch_scc1 .LBB0_1158
	v_ffbh_u32_e32 v61, v59
	v_min_u32_e32 v61, 32, v61
	v_lshlrev_b64 v[58:59], v61, v[58:59]
	v_min_u32_e32 v58, 1, v58
	v_or_b32_e32 v58, v59, v58
	v_cvt_f32_u32_e32 v58, v58
	v_sub_u32_e32 v59, 32, v61
	s_ashr_i32 s15, s14, 31
	s_lshl_b64 s[14:15], s[14:15], 12
	v_ldexp_f32 v58, v58, v59
	v_fmamk_f32 v58, v58, 0x2e800000, v60
	v_mul_f32_e32 v59, 0x4b800000, v58
	v_cmp_gt_f32_e32 vcc, s25, v58
	v_lshl_add_u64 v[66:67], v[18:19], 0, s[14:15]
	s_nop 0
	v_cndmask_b32_e32 v58, v58, v59, vcc
	v_rsq_f32_e32 v59, v58
	v_lshlrev_b32_e32 v58, 16, v56
	v_mul_f32_e32 v61, 0x45800000, v59
	v_cndmask_b32_e32 v68, v59, v61, vcc
	v_and_b32_e32 v59, 0xffff0000, v56
	v_lshlrev_b32_e32 v56, 16, v57
	v_and_b32_e32 v57, 0xffff0000, v57
	v_pk_mul_f32 v[56:57], v[68:69], v[56:57] op_sel_hi:[0,1]
	v_pk_mul_f32 v[64:65], v[14:15], v[56:57]
	v_lshlrev_b32_e32 v56, 16, v54
	v_and_b32_e32 v57, 0xffff0000, v54
	v_lshlrev_b32_e32 v54, 16, v55
	v_and_b32_e32 v55, 0xffff0000, v55
	v_pk_mul_f32 v[58:59], v[68:69], v[58:59] op_sel_hi:[0,1]
	v_pk_mul_f32 v[54:55], v[68:69], v[54:55] op_sel_hi:[0,1]
	v_pk_mul_f32 v[62:63], v[12:13], v[58:59]
	v_pk_mul_f32 v[56:57], v[68:69], v[56:57] op_sel_hi:[0,1]
	v_pk_mul_f32 v[58:59], v[10:11], v[54:55]
	v_lshlrev_b32_e32 v54, 16, v52
	v_and_b32_e32 v55, 0xffff0000, v52
	v_lshlrev_b32_e32 v52, 16, v53
	v_and_b32_e32 v53, 0xffff0000, v53
	v_pk_mul_f32 v[56:57], v[8:9], v[56:57]
	v_pk_mul_f32 v[52:53], v[68:69], v[52:53] op_sel_hi:[0,1]
	global_store_dwordx4 v[66:67], v[56:59], off offset:1024
	v_pk_mul_f32 v[54:55], v[68:69], v[54:55] op_sel_hi:[0,1]
	v_pk_mul_f32 v[54:55], v[4:5], v[54:55]
	v_pk_mul_f32 v[56:57], v[6:7], v[52:53]
	v_lshlrev_b32_e32 v52, 16, v50
	v_and_b32_e32 v53, 0xffff0000, v50
	v_lshlrev_b32_e32 v50, 16, v51
	v_and_b32_e32 v51, 0xffff0000, v51
	v_pk_mul_f32 v[52:53], v[68:69], v[52:53] op_sel_hi:[0,1]
	v_pk_mul_f32 v[50:51], v[68:69], v[50:51] op_sel_hi:[0,1]
	global_store_dwordx4 v[66:67], v[54:57], off offset:2048
	v_pk_mul_f32 v[52:53], v[0:1], v[52:53]
	global_store_dwordx4 v[66:67], v[62:65], off
	v_pk_mul_f32 v[54:55], v[2:3], v[50:51]
	global_store_dwordx4 v[66:67], v[52:55], off offset:3072
	s_andn2_b64 vcc, exec, s[12:13]
	s_cbranch_vccz .LBB0_1159
